# GEMM loops: phase-6 B-fragment ds_reads also addressed off the persistent base with immediates (second per-iteration v_add_u32 removed); on top of v33
# baseline (speedup 1.0000x reference)
; #define PG8_STAGE(bufoff, gbase, voff) do { _Pragma("unroll") for (int _i = 0; _i < 2; ++_i) \
;         __builtin_amdgcn_global_load_lds((const unsigned*)((const char*)(gbase) + (voff)[_i]), (LAS unsigned*)(lds + (bufoff) + ldsw + _i * 8192), 16, 0, 0); } while (0)
; #define PG8_LDA(dst, b, h) do { _Pragma("unroll") for (int m = 0; m < 4; ++m) _Pragma("unroll") for (int k = 0; k < 2; ++k) dst[m][k] = *(const LAS bf16x8*)(lds + PG8_SA(b, h) + aoff + m * 2048 + k * 1024); } while (0)
; #define PG8_LDB(dst, b, h) do { _Pragma("unroll") for (int n = 0; n < 2; ++n) _Pragma("unroll") for (int k = 0; k < 2; ++k) dst[n][k] = *(const LAS bf16x8*)(lds + PG8_SB(b, h) + boff + n * 2048 + k * 1024); } while (0)
; #define PG8_MMA(ai, bj, At, Bt) do { __builtin_amdgcn_s_setprio(1); _Pragma("unroll") for (int m = 0; m < 4; ++m) _Pragma("unroll") for (int n = 0; n < 2; ++n) _Pragma("unroll") for (int k = 0; k < 2; ++k) \
;         acc[ai][bj][m][n] = __builtin_amdgcn_mfma_f32_16x16x32_bf16(Bt[n][k], At[m][k], acc[ai][bj][m][n], 0, 0, 0); __builtin_amdgcn_s_setprio(0); } while (0)
; #define PG8_WAIT_L(n) asm volatile("s_waitcnt lgkmcnt(" #n ")" ::: "memory")
; template <class Epi, class Sched>
; __device__ __forceinline__ void gemm_phase(LAS unsigned char* lds, const Gemm g, const Sched& S, const Epi& E) {
;     ...
;     for (;;) {
;         const bool has_next = S.next(ui + 1, nxt);
;         const char* nA = has_next ? (const char*)g.A + (size_t)nxt.pm * tstep : cA; const char* nB = has_next ? (const char*)g.Bt + (size_t)nxt.pn * tstep : cB;
;         for (int t = 0; t < nt; t += 2) {
;             const bool last = (t == nt - 2);
;             const char* a1 = cA + (size_t)(t + 1) * kstep;
;             const char* a2 = last ? nA : cA + (size_t)(t + 2) * kstep; const char* b2 = last ? nB : cB + (size_t)(t + 2) * kstep;
;             const char* a3 = a2 + kstep; const char* b3 = b2 + kstep;
;             PG8_LDB(B0, 0, 0); PG8_SCHED; PG8_LDA(At, 0, 0); PG8_STAGE(PG8_SA(1, 1), a1 + hstep, voffA);
;             PG8_WAIT_L(8); PG8_BAR; PG8_WAIT_L(0); PG8_MMA(0, 0, At, B0); PG8_BAR; PG8_SCHED;
;             PG8_LDB(B1, 0, 1); PG8_STAGE(PG8_SB(0, 0), b2, voffB);
;             PG8_BAR; PG8_WAIT_L(0); PG8_MMA(0, 1, At, B1); PG8_BAR;
;             PG8_LDA(At, 0, 1); PG8_STAGE(PG8_SA(0, 0), a2, voffA);
;             PG8_BAR; PG8_WAIT_L(0); PG8_MMA(1, 0, At, B0); PG8_BAR; PG8_SCHED;
.LBB0_234:
	s_ashr_i32 s7, s6, 31
	v_cmp_lt_i64_e32 vcc, s[8:9], v[140:141]
	s_lshl_b64 s[8:9], s[6:7], 19
	s_add_u32 s8, s96, s8
	s_addc_u32 s9, s97, s9
	s_and_b64 s[10:11], vcc, exec
	s_cselect_b32 s7, s9, s15
	s_cselect_b32 s44, s8, s14
	s_ashr_i32 s5, s4, 31
	s_lshl_b64 s[10:11], s[4:5], 19
	s_add_u32 s10, s72, s10
	s_addc_u32 s11, s73, s11
	s_and_b64 s[16:17], vcc, exec
	s_cselect_b32 s5, s11, s19
	s_cselect_b32 s45, s10, s18
	s_add_u32 s14, s14, 0x40080
	s_addc_u32 s15, s15, 0
	s_add_u32 s46, s18, 0x100
	s_addc_u32 s47, s19, 0
	s_mov_b32 s48, -2
	ds_read_b128 v[150:153], v147
	ds_read_b128 v[154:157], v147 offset:1024
	ds_read_b128 v[158:161], v147 offset:2048
	ds_read_b128 v[162:165], v147 offset:3072
	s_add_u32 s16, s14, 0xfffc0080
	s_addc_u32 s17, s15, -1
	s_cmp_eq_u32 s48, 12
	s_cselect_b32 s23, s7, s17
	s_cselect_b32 s22, s44, s16
	s_cselect_b32 s19, s5, s47
	s_cselect_b32 s18, s45, s46
	s_add_i32 m0, s13, 0xc000
	ds_read_b128 v[166:169], v148
	ds_read_b128 v[170:173], v148 offset:1024
	ds_read_b128 v[174:177], v148 offset:2048
	ds_read_b128 v[178:181], v148 offset:3072
	ds_read_b128 v[182:185], v148 offset:4096
	ds_read_b128 v[186:189], v148 offset:5120
	ds_read_b128 v[190:193], v148 offset:6144
	ds_read_b128 v[194:197], v148 offset:7168
	global_load_lds_dwordx4 v136, s[14:15]
	s_add_i32 m0, s13, 0xe000
	s_nop 0
	global_load_lds_dwordx4 v138, s[14:15]
	s_waitcnt lgkmcnt(8)
	s_waitcnt vmcnt(8)
	s_setprio 1
	s_barrier
	s_waitcnt lgkmcnt(0)
	v_mfma_f32_16x16x32_bf16 v[124:127], v[150:153], v[166:169], 0
	v_mfma_f32_16x16x32_bf16 v[116:119], v[158:161], v[166:169], 0
	v_mfma_f32_16x16x32_bf16 v[108:111], v[150:153], v[174:177], 0
	v_mfma_f32_16x16x32_bf16 v[100:103], v[158:161], v[174:177], 0
	v_mfma_f32_16x16x32_bf16 v[92:95], v[150:153], v[182:185], 0
	v_mfma_f32_16x16x32_bf16 v[84:87], v[158:161], v[182:185], 0
	v_mfma_f32_16x16x32_bf16 v[76:79], v[150:153], v[190:193], 0
	v_mfma_f32_16x16x32_bf16 v[68:71], v[158:161], v[190:193], 0
	v_mfma_f32_16x16x32_bf16 v[124:127], v[154:157], v[170:173], v[124:127]
	v_mfma_f32_16x16x32_bf16 v[116:119], v[162:165], v[170:173], v[116:119]
	v_mfma_f32_16x16x32_bf16 v[108:111], v[154:157], v[178:181], v[108:111]
	v_mfma_f32_16x16x32_bf16 v[100:103], v[162:165], v[178:181], v[100:103]
	v_mfma_f32_16x16x32_bf16 v[92:95], v[154:157], v[186:189], v[92:95]
	v_mfma_f32_16x16x32_bf16 v[84:87], v[162:165], v[186:189], v[84:87]
	v_mfma_f32_16x16x32_bf16 v[76:79], v[154:157], v[194:197], v[76:79]
	v_mfma_f32_16x16x32_bf16 v[68:71], v[162:165], v[194:197], v[68:71]
	s_barrier
	s_setprio 0
	s_add_i32 s16, s40, s25
	s_mov_b32 m0, s16
	ds_read_b128 v[202:205], v149
	ds_read_b128 v[206:209], v149 offset:1024
	ds_read_b128 v[210:213], v149 offset:2048
	ds_read_b128 v[214:217], v149 offset:3072
	global_load_lds_dwordx4 v132, s[18:19]
	s_add_i32 m0, s16, 0x2000
	s_nop 0
	global_load_lds_dwordx4 v128, s[18:19]
	s_waitcnt vmcnt(8)
	s_setprio 1
	s_barrier
	s_waitcnt lgkmcnt(0)
	v_mfma_f32_16x16x32_bf16 v[120:123], v[202:205], v[166:169], 0
	v_mfma_f32_16x16x32_bf16 v[112:115], v[210:213], v[166:169], 0
	v_mfma_f32_16x16x32_bf16 v[104:107], v[202:205], v[174:177], 0
	v_mfma_f32_16x16x32_bf16 v[96:99], v[210:213], v[174:177], 0
	v_mfma_f32_16x16x32_bf16 v[88:91], v[202:205], v[182:185], 0
	v_mfma_f32_16x16x32_bf16 v[80:83], v[210:213], v[182:185], 0
	v_mfma_f32_16x16x32_bf16 v[72:75], v[202:205], v[190:193], 0
	v_mfma_f32_16x16x32_bf16 v[64:67], v[210:213], v[190:193], 0
	v_mfma_f32_16x16x32_bf16 v[120:123], v[206:209], v[170:173], v[120:123]
	v_mfma_f32_16x16x32_bf16 v[112:115], v[214:217], v[170:173], v[112:115]
	v_mfma_f32_16x16x32_bf16 v[104:107], v[206:209], v[178:181], v[104:107]
	v_mfma_f32_16x16x32_bf16 v[96:99], v[214:217], v[178:181], v[96:99]
	v_mfma_f32_16x16x32_bf16 v[88:91], v[206:209], v[186:189], v[88:91]
	v_mfma_f32_16x16x32_bf16 v[80:83], v[214:217], v[186:189], v[80:83]
	v_mfma_f32_16x16x32_bf16 v[72:75], v[206:209], v[194:197], v[72:75]
	v_mfma_f32_16x16x32_bf16 v[64:67], v[214:217], v[194:197], v[64:67]
	s_barrier
	s_setprio 0
	s_mov_b32 m0, s13
	ds_read_b128 v[166:169], v148 offset:16384
	ds_read_b128 v[170:173], v148 offset:17408
	ds_read_b128 v[174:177], v148 offset:18432
	ds_read_b128 v[178:181], v148 offset:19456
	ds_read_b128 v[182:185], v148 offset:20480
	ds_read_b128 v[186:189], v148 offset:21504
	ds_read_b128 v[190:193], v148 offset:22528
	ds_read_b128 v[194:197], v148 offset:23552
	global_load_lds_dwordx4 v134, s[22:23]
	s_mov_b32 m0, s28
	s_nop 0
	global_load_lds_dwordx4 v130, s[22:23]
	s_setprio 1
	s_barrier
	s_waitcnt lgkmcnt(0)
	v_mfma_f32_16x16x32_bf16 v[60:63], v[150:153], v[166:169], 0
	v_mfma_f32_16x16x32_bf16 v[56:59], v[158:161], v[166:169], 0
	v_mfma_f32_16x16x32_bf16 v[44:47], v[150:153], v[174:177], 0
	v_mfma_f32_16x16x32_bf16 v[40:43], v[158:161], v[174:177], 0
	v_mfma_f32_16x16x32_bf16 v[28:31], v[150:153], v[182:185], 0
	v_mfma_f32_16x16x32_bf16 v[24:27], v[158:161], v[182:185], 0
	v_mfma_f32_16x16x32_bf16 v[12:15], v[150:153], v[190:193], 0
	v_mfma_f32_16x16x32_bf16 v[8:11], v[158:161], v[190:193], 0
	v_mfma_f32_16x16x32_bf16 v[60:63], v[154:157], v[170:173], v[60:63]
	v_mfma_f32_16x16x32_bf16 v[56:59], v[162:165], v[170:173], v[56:59]
	v_mfma_f32_16x16x32_bf16 v[44:47], v[154:157], v[178:181], v[44:47]
	v_mfma_f32_16x16x32_bf16 v[40:43], v[162:165], v[178:181], v[40:43]
	v_mfma_f32_16x16x32_bf16 v[28:31], v[154:157], v[186:189], v[28:31]
	v_mfma_f32_16x16x32_bf16 v[24:27], v[162:165], v[186:189], v[24:27]
	v_mfma_f32_16x16x32_bf16 v[12:15], v[154:157], v[194:197], v[12:15]
	v_mfma_f32_16x16x32_bf16 v[8:11], v[162:165], v[194:197], v[8:11]
	s_barrier
; #define PG8_STAGE(bufoff, gbase, voff) do { _Pragma("unroll") for (int _i = 0; _i < 2; ++_i) \
;         __builtin_amdgcn_global_load_lds((const unsigned*)((const char*)(gbase) + (voff)[_i]), (LAS unsigned*)(lds + (bufoff) + ldsw + _i * 8192), 16, 0, 0); } while (0)
; #define PG8_LDA(dst, b, h) do { _Pragma("unroll") for (int m = 0; m < 4; ++m) _Pragma("unroll") for (int k = 0; k < 2; ++k) dst[m][k] = *(const LAS bf16x8*)(lds + PG8_SA(b, h) + aoff + m * 2048 + k * 1024); } while (0)
; #define PG8_LDB(dst, b, h) do { _Pragma("unroll") for (int n = 0; n < 2; ++n) _Pragma("unroll") for (int k = 0; k < 2; ++k) dst[n][k] = *(const LAS bf16x8*)(lds + PG8_SB(b, h) + boff + n * 2048 + k * 1024); } while (0)
; #define PG8_MMA(ai, bj, At, Bt) do { __builtin_amdgcn_s_setprio(1); _Pragma("unroll") for (int m = 0; m < 4; ++m) _Pragma("unroll") for (int n = 0; n < 2; ++n) _Pragma("unroll") for (int k = 0; k < 2; ++k) \
;         acc[ai][bj][m][n] = __builtin_amdgcn_mfma_f32_16x16x32_bf16(Bt[n][k], At[m][k], acc[ai][bj][m][n], 0, 0, 0); __builtin_amdgcn_s_setprio(0); } while (0)
; #define PG8_WAIT_V(n) asm volatile("s_waitcnt vmcnt(" #n ")" ::: "memory")
; #define PG8_WAIT_L(n) asm volatile("s_waitcnt lgkmcnt(" #n ")" ::: "memory")
; #define PG8_BAR __builtin_amdgcn_s_barrier()
; #define PG8_SCHED __builtin_amdgcn_sched_barrier(0)
; template <class Epi, class Sched>
; __device__ __forceinline__ void gemm_phase(LAS unsigned char* lds, const Gemm g, const Sched& S, const Epi& E) {
;     ...
;             PG8_STAGE(PG8_SB(0, 1), b2 + hstep, voffB);
;             PG8_WAIT_V(6); PG8_BAR; PG8_MMA(1, 1, At, B1); PG8_BAR;
;             PG8_LDB(B0, 1, 0); PG8_SCHED; PG8_LDA(At, 1, 0); PG8_STAGE(PG8_SA(0, 1), a2 + hstep, voffA);
;             PG8_WAIT_L(8); PG8_BAR; PG8_WAIT_L(0); PG8_MMA(0, 0, At, B0); PG8_BAR; PG8_SCHED;
;             PG8_LDB(B1, 1, 1); PG8_STAGE(PG8_SB(1, 0), b3, voffB);
;             PG8_BAR; PG8_WAIT_L(0); PG8_MMA(0, 1, At, B1); PG8_BAR;
;             PG8_LDA(At, 1, 1); PG8_STAGE(PG8_SA(1, 0), a3, voffA);
	s_setprio 0
	s_add_u32 s16, s18, 0x40000
	s_addc_u32 s17, s19, 0
	s_add_i32 s20, s41, s25
	s_mov_b32 m0, s20
	s_nop 0
	global_load_lds_dwordx4 v132, s[16:17]
	s_add_i32 m0, s20, 0x2000
	s_nop 0
	global_load_lds_dwordx4 v128, s[16:17]
	s_add_u32 s16, s22, 0x40000
	s_addc_u32 s17, s23, 0
	s_mov_b32 m0, s29
	s_nop 0
	global_load_lds_dwordx4 v134, s[16:17]
	s_mov_b32 m0, s33
	s_nop 0
	global_load_lds_dwordx4 v130, s[16:17]
	s_waitcnt vmcnt(10)
	s_setprio 1
	s_barrier
	v_mfma_f32_16x16x32_bf16 v[52:55], v[202:205], v[166:169], 0
	v_mfma_f32_16x16x32_bf16 v[48:51], v[210:213], v[166:169], 0
	v_mfma_f32_16x16x32_bf16 v[36:39], v[202:205], v[174:177], 0
	v_mfma_f32_16x16x32_bf16 v[32:35], v[210:213], v[174:177], 0
	v_mfma_f32_16x16x32_bf16 v[20:23], v[202:205], v[182:185], 0
	v_mfma_f32_16x16x32_bf16 v[16:19], v[210:213], v[182:185], 0
	v_mfma_f32_16x16x32_bf16 v[4:7], v[202:205], v[190:193], 0
	v_mfma_f32_16x16x32_bf16 v[0:3], v[210:213], v[190:193], 0
	v_mfma_f32_16x16x32_bf16 v[52:55], v[206:209], v[170:173], v[52:55]
	v_mfma_f32_16x16x32_bf16 v[48:51], v[214:217], v[170:173], v[48:51]
	v_mfma_f32_16x16x32_bf16 v[36:39], v[206:209], v[178:181], v[36:39]
	v_mfma_f32_16x16x32_bf16 v[32:35], v[214:217], v[178:181], v[32:35]
	v_mfma_f32_16x16x32_bf16 v[20:23], v[206:209], v[186:189], v[20:23]
	v_mfma_f32_16x16x32_bf16 v[16:19], v[214:217], v[186:189], v[16:19]
	v_mfma_f32_16x16x32_bf16 v[4:7], v[206:209], v[194:197], v[4:7]
	v_mfma_f32_16x16x32_bf16 v[0:3], v[214:217], v[194:197], v[0:3]
	s_barrier
	s_setprio 0
	s_add_i32 s20, 0, 0x18000
	ds_read_b128 v[150:153], v149 offset:16384
	ds_read_b128 v[154:157], v149 offset:17408
	ds_read_b128 v[158:161], v149 offset:18432
	ds_read_b128 v[162:165], v149 offset:19456
	ds_read_b128 v[166:169], v148 offset:32768
	ds_read_b128 v[170:173], v148 offset:33792
	ds_read_b128 v[174:177], v148 offset:34816
	ds_read_b128 v[178:181], v148 offset:35840
	ds_read_b128 v[182:185], v148 offset:36864
	ds_read_b128 v[186:189], v148 offset:37888
	ds_read_b128 v[190:193], v148 offset:38912
	ds_read_b128 v[194:197], v148 offset:39936
	s_waitcnt lgkmcnt(8)
	s_waitcnt vmcnt(8)
	s_setprio 1
	s_barrier
	s_waitcnt lgkmcnt(0)
	v_mfma_f32_16x16x32_bf16 v[124:127], v[150:153], v[166:169], v[124:127]
	v_mfma_f32_16x16x32_bf16 v[116:119], v[158:161], v[166:169], v[116:119]
	v_mfma_f32_16x16x32_bf16 v[108:111], v[150:153], v[174:177], v[108:111]
	v_mfma_f32_16x16x32_bf16 v[100:103], v[158:161], v[174:177], v[100:103]
	v_mfma_f32_16x16x32_bf16 v[92:95], v[150:153], v[182:185], v[92:95]
	v_mfma_f32_16x16x32_bf16 v[84:87], v[158:161], v[182:185], v[84:87]
	v_mfma_f32_16x16x32_bf16 v[76:79], v[150:153], v[190:193], v[76:79]
	v_mfma_f32_16x16x32_bf16 v[68:71], v[158:161], v[190:193], v[68:71]
	v_mfma_f32_16x16x32_bf16 v[124:127], v[154:157], v[170:173], v[124:127]
	v_mfma_f32_16x16x32_bf16 v[116:119], v[162:165], v[170:173], v[116:119]
	v_mfma_f32_16x16x32_bf16 v[108:111], v[154:157], v[178:181], v[108:111]
	v_mfma_f32_16x16x32_bf16 v[100:103], v[162:165], v[178:181], v[100:103]
	v_mfma_f32_16x16x32_bf16 v[92:95], v[154:157], v[186:189], v[92:95]
	v_mfma_f32_16x16x32_bf16 v[84:87], v[162:165], v[186:189], v[84:87]
	v_mfma_f32_16x16x32_bf16 v[76:79], v[154:157], v[194:197], v[76:79]
	v_mfma_f32_16x16x32_bf16 v[68:71], v[162:165], v[194:197], v[68:71]
	s_barrier
	s_setprio 0
	s_add_i32 s21, 0, 0x1c000
	s_add_i32 s16, s20, s25
	s_add_u32 s0, s18, 0x80
	s_addc_u32 s1, s19, 0
	s_mov_b32 m0, s16
	ds_read_b128 v[202:205], v149 offset:32768
	ds_read_b128 v[206:209], v149 offset:33792
	ds_read_b128 v[210:213], v149 offset:34816
	ds_read_b128 v[214:217], v149 offset:35840
	global_load_lds_dwordx4 v132, s[0:1]
	s_add_i32 m0, s16, 0x2000
	s_nop 0
	global_load_lds_dwordx4 v128, s[0:1]
	s_waitcnt vmcnt(8)
	s_setprio 1
	s_barrier
	s_waitcnt lgkmcnt(0)
	v_mfma_f32_16x16x32_bf16 v[120:123], v[202:205], v[166:169], v[120:123]
	v_mfma_f32_16x16x32_bf16 v[112:115], v[210:213], v[166:169], v[112:115]
	v_mfma_f32_16x16x32_bf16 v[104:107], v[202:205], v[174:177], v[104:107]
	v_mfma_f32_16x16x32_bf16 v[96:99], v[210:213], v[174:177], v[96:99]
	v_mfma_f32_16x16x32_bf16 v[88:91], v[202:205], v[182:185], v[88:91]
	v_mfma_f32_16x16x32_bf16 v[80:83], v[210:213], v[182:185], v[80:83]
	v_mfma_f32_16x16x32_bf16 v[72:75], v[202:205], v[190:193], v[72:75]
	v_mfma_f32_16x16x32_bf16 v[64:67], v[210:213], v[190:193], v[64:67]
	v_mfma_f32_16x16x32_bf16 v[120:123], v[206:209], v[170:173], v[120:123]
	v_mfma_f32_16x16x32_bf16 v[112:115], v[214:217], v[170:173], v[112:115]
	v_mfma_f32_16x16x32_bf16 v[104:107], v[206:209], v[178:181], v[104:107]
	v_mfma_f32_16x16x32_bf16 v[96:99], v[214:217], v[178:181], v[96:99]
	v_mfma_f32_16x16x32_bf16 v[88:91], v[206:209], v[186:189], v[88:91]
	v_mfma_f32_16x16x32_bf16 v[80:83], v[214:217], v[186:189], v[80:83]
	v_mfma_f32_16x16x32_bf16 v[72:75], v[206:209], v[194:197], v[72:75]
	v_mfma_f32_16x16x32_bf16 v[64:67], v[214:217], v[194:197], v[64:67]
	s_barrier
	s_setprio 0
	s_mov_b32 m0, s36
	s_add_u32 s0, s22, 0x80
	s_addc_u32 s1, s23, 0
	ds_read_b128 v[166:169], v148 offset:49152
	ds_read_b128 v[170:173], v148 offset:50176
	ds_read_b128 v[174:177], v148 offset:51200
	ds_read_b128 v[178:181], v148 offset:52224
	ds_read_b128 v[182:185], v148 offset:53248
	ds_read_b128 v[186:189], v148 offset:54272
	ds_read_b128 v[190:193], v148 offset:55296
	ds_read_b128 v[194:197], v148 offset:56320
	global_load_lds_dwordx4 v134, s[0:1]
	s_mov_b32 m0, s37
	s_nop 0
	global_load_lds_dwordx4 v130, s[0:1]
	s_setprio 1
	s_barrier
; #define PG8_STAGE(bufoff, gbase, voff) do { _Pragma("unroll") for (int _i = 0; _i < 2; ++_i) \
;         __builtin_amdgcn_global_load_lds((const unsigned*)((const char*)(gbase) + (voff)[_i]), (LAS unsigned*)(lds + (bufoff) + ldsw + _i * 8192), 16, 0, 0); } while (0)
; #define PG8_LDA(dst, b, h) do { _Pragma("unroll") for (int m = 0; m < 4; ++m) _Pragma("unroll") for (int k = 0; k < 2; ++k) dst[m][k] = *(const LAS bf16x8*)(lds + PG8_SA(b, h) + aoff + m * 2048 + k * 1024); } while (0)
; #define PG8_LDB(dst, b, h) do { _Pragma("unroll") for (int n = 0; n < 2; ++n) _Pragma("unroll") for (int k = 0; k < 2; ++k) dst[n][k] = *(const LAS bf16x8*)(lds + PG8_SB(b, h) + boff + n * 2048 + k * 1024); } while (0)
; #define PG8_WAIT_V(n) asm volatile("s_waitcnt vmcnt(" #n ")" ::: "memory")
; #define PG8_WAIT_L(n) asm volatile("s_waitcnt lgkmcnt(" #n ")" ::: "memory")
; #define PG8_BAR __builtin_amdgcn_s_barrier()
; #define PG8_SCHED __builtin_amdgcn_sched_barrier(0)
; template <class Epi, class Sched>
; __device__ __forceinline__ void gemm_phase(LAS unsigned char* lds, const Gemm g, const Sched& S, const Epi& E) {
;     ...
;             PG8_LDB(B0, 0, 0); PG8_SCHED; PG8_LDA(At, 0, 0); PG8_STAGE(PG8_SA(1, 1), a1 + hstep, voffA);
;             PG8_WAIT_L(8); PG8_BAR; PG8_WAIT_L(0); PG8_MMA(0, 0, At, B0); PG8_BAR; PG8_SCHED;
;             PG8_LDB(B1, 0, 1); PG8_STAGE(PG8_SB(0, 0), b2, voffB);
;             PG8_BAR; PG8_WAIT_L(0); PG8_MMA(0, 1, At, B1); PG8_BAR;
;             PG8_LDA(At, 0, 1); PG8_STAGE(PG8_SA(0, 0), a2, voffA);
;             PG8_BAR; PG8_WAIT_L(0); PG8_MMA(1, 0, At, B0); PG8_BAR; PG8_SCHED;
;             PG8_STAGE(PG8_SB(0, 1), b2 + hstep, voffB);
;             PG8_WAIT_V(6); PG8_BAR; PG8_MMA(1, 1, At, B1); PG8_BAR;
;             PG8_LDB(B0, 1, 0); PG8_SCHED; PG8_LDA(At, 1, 0); PG8_STAGE(PG8_SA(0, 1), a2 + hstep, voffA);
;             PG8_WAIT_L(8); PG8_BAR; PG8_WAIT_L(0); PG8_MMA(0, 0, At, B0); PG8_BAR; PG8_SCHED;
;             PG8_LDB(B1, 1, 1); PG8_STAGE(PG8_SB(1, 0), b3, voffB);
;             PG8_BAR; PG8_WAIT_L(0); PG8_MMA(0, 1, At, B1); PG8_BAR;
;             PG8_LDA(At, 1, 1); PG8_STAGE(PG8_SA(1, 0), a3, voffA);
;             PG8_BAR; PG8_WAIT_L(0); PG8_MMA(1, 0, At, B0); PG8_BAR; PG8_SCHED;
;             PG8_STAGE(PG8_SB(1, 1), b3 + hstep, voffB);
;             PG8_WAIT_V(6); PG8_BAR; PG8_MMA(1, 1, At, B1); PG8_BAR;
	s_waitcnt lgkmcnt(0)
	v_mfma_f32_16x16x32_bf16 v[60:63], v[150:153], v[166:169], v[60:63]
	v_mfma_f32_16x16x32_bf16 v[56:59], v[158:161], v[166:169], v[56:59]
	v_mfma_f32_16x16x32_bf16 v[44:47], v[150:153], v[174:177], v[44:47]
	v_mfma_f32_16x16x32_bf16 v[40:43], v[158:161], v[174:177], v[40:43]
	v_mfma_f32_16x16x32_bf16 v[28:31], v[150:153], v[182:185], v[28:31]
	v_mfma_f32_16x16x32_bf16 v[24:27], v[158:161], v[182:185], v[24:27]
	v_mfma_f32_16x16x32_bf16 v[12:15], v[150:153], v[190:193], v[12:15]
	v_mfma_f32_16x16x32_bf16 v[8:11], v[158:161], v[190:193], v[8:11]
	v_mfma_f32_16x16x32_bf16 v[60:63], v[154:157], v[170:173], v[60:63]
	v_mfma_f32_16x16x32_bf16 v[56:59], v[162:165], v[170:173], v[56:59]
	v_mfma_f32_16x16x32_bf16 v[44:47], v[154:157], v[178:181], v[44:47]
	v_mfma_f32_16x16x32_bf16 v[40:43], v[162:165], v[178:181], v[40:43]
	v_mfma_f32_16x16x32_bf16 v[28:31], v[154:157], v[186:189], v[28:31]
	v_mfma_f32_16x16x32_bf16 v[24:27], v[162:165], v[186:189], v[24:27]
	v_mfma_f32_16x16x32_bf16 v[12:15], v[154:157], v[194:197], v[12:15]
	v_mfma_f32_16x16x32_bf16 v[8:11], v[162:165], v[194:197], v[8:11]
	s_barrier
	s_setprio 0
	s_add_u32 s16, s18, 0x40080
	s_addc_u32 s17, s19, 0
	s_add_i32 s18, s21, s25
	s_mov_b32 m0, s18
	s_nop 0
	global_load_lds_dwordx4 v132, s[16:17]
	s_add_i32 m0, s18, 0x2000
	s_nop 0
	global_load_lds_dwordx4 v128, s[16:17]
	s_waitcnt vmcnt(8)
	s_setprio 1
	s_barrier
	v_mfma_f32_16x16x32_bf16 v[52:55], v[202:205], v[166:169], v[52:55]
	v_mfma_f32_16x16x32_bf16 v[48:51], v[210:213], v[166:169], v[48:51]
	v_mfma_f32_16x16x32_bf16 v[36:39], v[202:205], v[174:177], v[36:39]
	v_mfma_f32_16x16x32_bf16 v[32:35], v[210:213], v[174:177], v[32:35]
	v_mfma_f32_16x16x32_bf16 v[20:23], v[202:205], v[182:185], v[20:23]
	v_mfma_f32_16x16x32_bf16 v[16:19], v[210:213], v[182:185], v[16:19]
	v_mfma_f32_16x16x32_bf16 v[4:7], v[202:205], v[190:193], v[4:7]
	v_mfma_f32_16x16x32_bf16 v[0:3], v[210:213], v[190:193], v[0:3]
	v_mfma_f32_16x16x32_bf16 v[52:55], v[206:209], v[170:173], v[52:55]
	v_mfma_f32_16x16x32_bf16 v[48:51], v[214:217], v[170:173], v[48:51]
	v_mfma_f32_16x16x32_bf16 v[36:39], v[206:209], v[178:181], v[36:39]
	v_mfma_f32_16x16x32_bf16 v[32:35], v[214:217], v[178:181], v[32:35]
	v_mfma_f32_16x16x32_bf16 v[20:23], v[206:209], v[186:189], v[20:23]
	v_mfma_f32_16x16x32_bf16 v[16:19], v[214:217], v[186:189], v[16:19]
	v_mfma_f32_16x16x32_bf16 v[4:7], v[206:209], v[194:197], v[4:7]
	v_mfma_f32_16x16x32_bf16 v[0:3], v[214:217], v[194:197], v[0:3]
	s_barrier
	s_setprio 0
	s_add_i32 s48, s48, 2
	s_add_u32 s14, s14, 0x100
	s_addc_u32 s15, s15, 0
	s_add_u32 s46, s46, 0x100
	s_addc_u32 s47, s47, 0
	s_cmp_gt_u32 s48, 13
.LBB0_235:
	ds_read_b128 v[150:153], v147
	ds_read_b128 v[154:157], v147 offset:1024
	ds_read_b128 v[158:161], v147 offset:2048
	ds_read_b128 v[162:165], v147 offset:3072
	s_add_u32 s16, s14, 0xfffc0080
	s_addc_u32 s17, s15, -1
	s_cmp_eq_u32 s48, 12
	s_cselect_b32 s23, s7, s17
	s_cselect_b32 s22, s44, s16
	s_cselect_b32 s19, s5, s47
	s_cselect_b32 s18, s45, s46
	s_add_i32 m0, s13, 0xc000
	ds_read_b128 v[166:169], v148
	ds_read_b128 v[170:173], v148 offset:1024
	ds_read_b128 v[174:177], v148 offset:2048
	ds_read_b128 v[178:181], v148 offset:3072
	ds_read_b128 v[182:185], v148 offset:4096
	ds_read_b128 v[186:189], v148 offset:5120
	ds_read_b128 v[190:193], v148 offset:6144
	ds_read_b128 v[194:197], v148 offset:7168
	global_load_lds_dwordx4 v136, s[14:15]
	s_add_i32 m0, s13, 0xe000
	s_nop 0
	global_load_lds_dwordx4 v138, s[14:15]
	s_waitcnt lgkmcnt(8)
	s_waitcnt vmcnt(8)
	s_setprio 1
	s_barrier
	s_waitcnt lgkmcnt(0)
	v_mfma_f32_16x16x32_bf16 v[124:127], v[150:153], v[166:169], v[124:127]
	v_mfma_f32_16x16x32_bf16 v[116:119], v[158:161], v[166:169], v[116:119]
	v_mfma_f32_16x16x32_bf16 v[108:111], v[150:153], v[174:177], v[108:111]
	v_mfma_f32_16x16x32_bf16 v[100:103], v[158:161], v[174:177], v[100:103]
	v_mfma_f32_16x16x32_bf16 v[92:95], v[150:153], v[182:185], v[92:95]
	v_mfma_f32_16x16x32_bf16 v[84:87], v[158:161], v[182:185], v[84:87]
	v_mfma_f32_16x16x32_bf16 v[76:79], v[150:153], v[190:193], v[76:79]
	v_mfma_f32_16x16x32_bf16 v[68:71], v[158:161], v[190:193], v[68:71]
	v_mfma_f32_16x16x32_bf16 v[124:127], v[154:157], v[170:173], v[124:127]
	v_mfma_f32_16x16x32_bf16 v[116:119], v[162:165], v[170:173], v[116:119]
	v_mfma_f32_16x16x32_bf16 v[108:111], v[154:157], v[178:181], v[108:111]
	v_mfma_f32_16x16x32_bf16 v[100:103], v[162:165], v[178:181], v[100:103]
	v_mfma_f32_16x16x32_bf16 v[92:95], v[154:157], v[186:189], v[92:95]
	v_mfma_f32_16x16x32_bf16 v[84:87], v[162:165], v[186:189], v[84:87]
	v_mfma_f32_16x16x32_bf16 v[76:79], v[154:157], v[194:197], v[76:79]
	v_mfma_f32_16x16x32_bf16 v[68:71], v[162:165], v[194:197], v[68:71]
	s_barrier
	s_setprio 0
	s_add_i32 s16, s40, s25
	s_mov_b32 m0, s16
	ds_read_b128 v[202:205], v149
	ds_read_b128 v[206:209], v149 offset:1024
	ds_read_b128 v[210:213], v149 offset:2048
	ds_read_b128 v[214:217], v149 offset:3072
	global_load_lds_dwordx4 v132, s[18:19]
	s_add_i32 m0, s16, 0x2000
	s_nop 0
	global_load_lds_dwordx4 v128, s[18:19]
	s_waitcnt vmcnt(8)
	s_setprio 1
	s_barrier
; #define PG8_STAGE(bufoff, gbase, voff) do { _Pragma("unroll") for (int _i = 0; _i < 2; ++_i) \
;         __builtin_amdgcn_global_load_lds((const unsigned*)((const char*)(gbase) + (voff)[_i]), (LAS unsigned*)(lds + (bufoff) + ldsw + _i * 8192), 16, 0, 0); } while (0)
; #define PG8_LDA(dst, b, h) do { _Pragma("unroll") for (int m = 0; m < 4; ++m) _Pragma("unroll") for (int k = 0; k < 2; ++k) dst[m][k] = *(const LAS bf16x8*)(lds + PG8_SA(b, h) + aoff + m * 2048 + k * 1024); } while (0)
; #define PG8_LDB(dst, b, h) do { _Pragma("unroll") for (int n = 0; n < 2; ++n) _Pragma("unroll") for (int k = 0; k < 2; ++k) dst[n][k] = *(const LAS bf16x8*)(lds + PG8_SB(b, h) + boff + n * 2048 + k * 1024); } while (0)
; #define PG8_MMA(ai, bj, At, Bt) do { __builtin_amdgcn_s_setprio(1); _Pragma("unroll") for (int m = 0; m < 4; ++m) _Pragma("unroll") for (int n = 0; n < 2; ++n) _Pragma("unroll") for (int k = 0; k < 2; ++k) \
;         acc[ai][bj][m][n] = __builtin_amdgcn_mfma_f32_16x16x32_bf16(Bt[n][k], At[m][k], acc[ai][bj][m][n], 0, 0, 0); __builtin_amdgcn_s_setprio(0); } while (0)
; #define PG8_WAIT_V(n) asm volatile("s_waitcnt vmcnt(" #n ")" ::: "memory")
; #define PG8_WAIT_L(n) asm volatile("s_waitcnt lgkmcnt(" #n ")" ::: "memory")
; #define PG8_BAR __builtin_amdgcn_s_barrier()
; #define PG8_SCHED __builtin_amdgcn_sched_barrier(0)
; template <class Epi, class Sched>
; __device__ __forceinline__ void gemm_phase(LAS unsigned char* lds, const Gemm g, const Sched& S, const Epi& E) {
;     ...
;             PG8_BAR; PG8_WAIT_L(0); PG8_MMA(0, 1, At, B1); PG8_BAR;
;             PG8_LDA(At, 0, 1); PG8_STAGE(PG8_SA(0, 0), a2, voffA);
;             PG8_BAR; PG8_WAIT_L(0); PG8_MMA(1, 0, At, B0); PG8_BAR; PG8_SCHED;
;             PG8_STAGE(PG8_SB(0, 1), b2 + hstep, voffB);
;             PG8_WAIT_V(6); PG8_BAR; PG8_MMA(1, 1, At, B1); PG8_BAR;
;             PG8_LDB(B0, 1, 0); PG8_SCHED; PG8_LDA(At, 1, 0); PG8_STAGE(PG8_SA(0, 1), a2 + hstep, voffA);
;             PG8_WAIT_L(8); PG8_BAR; PG8_WAIT_L(0); PG8_MMA(0, 0, At, B0); PG8_BAR; PG8_SCHED;
	s_waitcnt lgkmcnt(0)
	v_mfma_f32_16x16x32_bf16 v[120:123], v[202:205], v[166:169], v[120:123]
	v_mfma_f32_16x16x32_bf16 v[112:115], v[210:213], v[166:169], v[112:115]
	v_mfma_f32_16x16x32_bf16 v[104:107], v[202:205], v[174:177], v[104:107]
	v_mfma_f32_16x16x32_bf16 v[96:99], v[210:213], v[174:177], v[96:99]
	v_mfma_f32_16x16x32_bf16 v[88:91], v[202:205], v[182:185], v[88:91]
	v_mfma_f32_16x16x32_bf16 v[80:83], v[210:213], v[182:185], v[80:83]
	v_mfma_f32_16x16x32_bf16 v[72:75], v[202:205], v[190:193], v[72:75]
	v_mfma_f32_16x16x32_bf16 v[64:67], v[210:213], v[190:193], v[64:67]
	v_mfma_f32_16x16x32_bf16 v[120:123], v[206:209], v[170:173], v[120:123]
	v_mfma_f32_16x16x32_bf16 v[112:115], v[214:217], v[170:173], v[112:115]
	v_mfma_f32_16x16x32_bf16 v[104:107], v[206:209], v[178:181], v[104:107]
	v_mfma_f32_16x16x32_bf16 v[96:99], v[214:217], v[178:181], v[96:99]
	v_mfma_f32_16x16x32_bf16 v[88:91], v[206:209], v[186:189], v[88:91]
	v_mfma_f32_16x16x32_bf16 v[80:83], v[214:217], v[186:189], v[80:83]
	v_mfma_f32_16x16x32_bf16 v[72:75], v[206:209], v[194:197], v[72:75]
	v_mfma_f32_16x16x32_bf16 v[64:67], v[214:217], v[194:197], v[64:67]
	s_barrier
	s_setprio 0
	s_mov_b32 m0, s13
	ds_read_b128 v[166:169], v148 offset:16384
	ds_read_b128 v[170:173], v148 offset:17408
	ds_read_b128 v[174:177], v148 offset:18432
	ds_read_b128 v[178:181], v148 offset:19456
	ds_read_b128 v[182:185], v148 offset:20480
	ds_read_b128 v[186:189], v148 offset:21504
	ds_read_b128 v[190:193], v148 offset:22528
	ds_read_b128 v[194:197], v148 offset:23552
	global_load_lds_dwordx4 v134, s[22:23]
	s_mov_b32 m0, s28
	s_nop 0
	global_load_lds_dwordx4 v130, s[22:23]
	s_setprio 1
	s_barrier
	s_waitcnt lgkmcnt(0)
	v_mfma_f32_16x16x32_bf16 v[60:63], v[150:153], v[166:169], v[60:63]
	v_mfma_f32_16x16x32_bf16 v[56:59], v[158:161], v[166:169], v[56:59]
	v_mfma_f32_16x16x32_bf16 v[44:47], v[150:153], v[174:177], v[44:47]
	v_mfma_f32_16x16x32_bf16 v[40:43], v[158:161], v[174:177], v[40:43]
	v_mfma_f32_16x16x32_bf16 v[28:31], v[150:153], v[182:185], v[28:31]
	v_mfma_f32_16x16x32_bf16 v[24:27], v[158:161], v[182:185], v[24:27]
	v_mfma_f32_16x16x32_bf16 v[12:15], v[150:153], v[190:193], v[12:15]
	v_mfma_f32_16x16x32_bf16 v[8:11], v[158:161], v[190:193], v[8:11]
	v_mfma_f32_16x16x32_bf16 v[60:63], v[154:157], v[170:173], v[60:63]
	v_mfma_f32_16x16x32_bf16 v[56:59], v[162:165], v[170:173], v[56:59]
	v_mfma_f32_16x16x32_bf16 v[44:47], v[154:157], v[178:181], v[44:47]
	v_mfma_f32_16x16x32_bf16 v[40:43], v[162:165], v[178:181], v[40:43]
	v_mfma_f32_16x16x32_bf16 v[28:31], v[154:157], v[186:189], v[28:31]
	v_mfma_f32_16x16x32_bf16 v[24:27], v[162:165], v[186:189], v[24:27]
	v_mfma_f32_16x16x32_bf16 v[12:15], v[154:157], v[194:197], v[12:15]
	v_mfma_f32_16x16x32_bf16 v[8:11], v[162:165], v[194:197], v[8:11]
	s_barrier
	s_setprio 0
	s_add_u32 s16, s18, 0x40000
	s_addc_u32 s17, s19, 0
	s_add_i32 s20, s41, s25
	s_mov_b32 m0, s20
	s_nop 0
	global_load_lds_dwordx4 v132, s[16:17]
	s_add_i32 m0, s20, 0x2000
	s_nop 0
	global_load_lds_dwordx4 v128, s[16:17]
	s_add_u32 s16, s22, 0x40000
	s_addc_u32 s17, s23, 0
	s_mov_b32 m0, s29
	s_nop 0
	global_load_lds_dwordx4 v134, s[16:17]
	s_mov_b32 m0, s33
	s_nop 0
	global_load_lds_dwordx4 v130, s[16:17]
	s_waitcnt vmcnt(10)
	s_setprio 1
	s_barrier
	v_mfma_f32_16x16x32_bf16 v[52:55], v[202:205], v[166:169], v[52:55]
	v_mfma_f32_16x16x32_bf16 v[48:51], v[210:213], v[166:169], v[48:51]
	v_mfma_f32_16x16x32_bf16 v[36:39], v[202:205], v[174:177], v[36:39]
	v_mfma_f32_16x16x32_bf16 v[32:35], v[210:213], v[174:177], v[32:35]
	v_mfma_f32_16x16x32_bf16 v[20:23], v[202:205], v[182:185], v[20:23]
	v_mfma_f32_16x16x32_bf16 v[16:19], v[210:213], v[182:185], v[16:19]
	v_mfma_f32_16x16x32_bf16 v[4:7], v[202:205], v[190:193], v[4:7]
	v_mfma_f32_16x16x32_bf16 v[0:3], v[210:213], v[190:193], v[0:3]
	v_mfma_f32_16x16x32_bf16 v[52:55], v[206:209], v[170:173], v[52:55]
	v_mfma_f32_16x16x32_bf16 v[48:51], v[214:217], v[170:173], v[48:51]
	v_mfma_f32_16x16x32_bf16 v[36:39], v[206:209], v[178:181], v[36:39]
	v_mfma_f32_16x16x32_bf16 v[32:35], v[214:217], v[178:181], v[32:35]
	v_mfma_f32_16x16x32_bf16 v[20:23], v[206:209], v[186:189], v[20:23]
	v_mfma_f32_16x16x32_bf16 v[16:19], v[214:217], v[186:189], v[16:19]
	v_mfma_f32_16x16x32_bf16 v[4:7], v[206:209], v[194:197], v[4:7]
	v_mfma_f32_16x16x32_bf16 v[0:3], v[214:217], v[194:197], v[0:3]
	s_barrier
	s_setprio 0
	s_add_i32 s20, 0, 0x18000
	ds_read_b128 v[150:153], v149 offset:16384
	ds_read_b128 v[154:157], v149 offset:17408
	ds_read_b128 v[158:161], v149 offset:18432
	ds_read_b128 v[162:165], v149 offset:19456
	ds_read_b128 v[166:169], v148 offset:32768
	ds_read_b128 v[170:173], v148 offset:33792
	ds_read_b128 v[174:177], v148 offset:34816
	ds_read_b128 v[178:181], v148 offset:35840
	ds_read_b128 v[182:185], v148 offset:36864
	ds_read_b128 v[186:189], v148 offset:37888
	ds_read_b128 v[190:193], v148 offset:38912
	ds_read_b128 v[194:197], v148 offset:39936
	s_waitcnt lgkmcnt(8)
	s_waitcnt vmcnt(8)
	s_setprio 1
	s_barrier
; #define PG8_STAGE(bufoff, gbase, voff) do { _Pragma("unroll") for (int _i = 0; _i < 2; ++_i) \
;         __builtin_amdgcn_global_load_lds((const unsigned*)((const char*)(gbase) + (voff)[_i]), (LAS unsigned*)(lds + (bufoff) + ldsw + _i * 8192), 16, 0, 0); } while (0)
; #define PG8_LDA(dst, b, h) do { _Pragma("unroll") for (int m = 0; m < 4; ++m) _Pragma("unroll") for (int k = 0; k < 2; ++k) dst[m][k] = *(const LAS bf16x8*)(lds + PG8_SA(b, h) + aoff + m * 2048 + k * 1024); } while (0)
; #define PG8_LDB(dst, b, h) do { _Pragma("unroll") for (int n = 0; n < 2; ++n) _Pragma("unroll") for (int k = 0; k < 2; ++k) dst[n][k] = *(const LAS bf16x8*)(lds + PG8_SB(b, h) + boff + n * 2048 + k * 1024); } while (0)
; #define PG8_MMA(ai, bj, At, Bt) do { __builtin_amdgcn_s_setprio(1); _Pragma("unroll") for (int m = 0; m < 4; ++m) _Pragma("unroll") for (int n = 0; n < 2; ++n) _Pragma("unroll") for (int k = 0; k < 2; ++k) \
;         acc[ai][bj][m][n] = __builtin_amdgcn_mfma_f32_16x16x32_bf16(Bt[n][k], At[m][k], acc[ai][bj][m][n], 0, 0, 0); __builtin_amdgcn_s_setprio(0); } while (0)
; #define PG8_WAIT_V(n) asm volatile("s_waitcnt vmcnt(" #n ")" ::: "memory")
; #define PG8_WAIT_L(n) asm volatile("s_waitcnt lgkmcnt(" #n ")" ::: "memory")
; #define PG8_BAR __builtin_amdgcn_s_barrier()
; #define PG8_SCHED __builtin_amdgcn_sched_barrier(0)
; template <class Epi, class Sched>
; __device__ __forceinline__ void gemm_phase(LAS unsigned char* lds, const Gemm g, const Sched& S, const Epi& E) {
;     ...
;             PG8_WAIT_L(8); PG8_BAR; PG8_WAIT_L(0); PG8_MMA(0, 0, At, B0); PG8_BAR; PG8_SCHED;
;             PG8_LDB(B1, 1, 1); PG8_STAGE(PG8_SB(1, 0), b3, voffB);
;             PG8_BAR; PG8_WAIT_L(0); PG8_MMA(0, 1, At, B1); PG8_BAR;
;             PG8_LDA(At, 1, 1); PG8_STAGE(PG8_SA(1, 0), a3, voffA);
;             PG8_BAR; PG8_WAIT_L(0); PG8_MMA(1, 0, At, B0); PG8_BAR; PG8_SCHED;
;             PG8_STAGE(PG8_SB(1, 1), b3 + hstep, voffB);
;             PG8_WAIT_V(6); PG8_BAR; PG8_MMA(1, 1, At, B1); PG8_BAR;
	s_waitcnt lgkmcnt(0)
	v_mfma_f32_16x16x32_bf16 v[124:127], v[150:153], v[166:169], v[124:127]
	v_mfma_f32_16x16x32_bf16 v[116:119], v[158:161], v[166:169], v[116:119]
	v_mfma_f32_16x16x32_bf16 v[108:111], v[150:153], v[174:177], v[108:111]
	v_mfma_f32_16x16x32_bf16 v[100:103], v[158:161], v[174:177], v[100:103]
	v_mfma_f32_16x16x32_bf16 v[92:95], v[150:153], v[182:185], v[92:95]
	v_mfma_f32_16x16x32_bf16 v[84:87], v[158:161], v[182:185], v[84:87]
	v_mfma_f32_16x16x32_bf16 v[76:79], v[150:153], v[190:193], v[76:79]
	v_mfma_f32_16x16x32_bf16 v[68:71], v[158:161], v[190:193], v[68:71]
	v_mfma_f32_16x16x32_bf16 v[124:127], v[154:157], v[170:173], v[124:127]
	v_mfma_f32_16x16x32_bf16 v[116:119], v[162:165], v[170:173], v[116:119]
	v_mfma_f32_16x16x32_bf16 v[108:111], v[154:157], v[178:181], v[108:111]
	v_mfma_f32_16x16x32_bf16 v[100:103], v[162:165], v[178:181], v[100:103]
	v_mfma_f32_16x16x32_bf16 v[92:95], v[154:157], v[186:189], v[92:95]
	v_mfma_f32_16x16x32_bf16 v[84:87], v[162:165], v[186:189], v[84:87]
	v_mfma_f32_16x16x32_bf16 v[76:79], v[154:157], v[194:197], v[76:79]
	v_mfma_f32_16x16x32_bf16 v[68:71], v[162:165], v[194:197], v[68:71]
	s_barrier
	s_setprio 0
	s_add_i32 s21, 0, 0x1c000
	s_add_i32 s16, s20, s25
	s_add_u32 s0, s18, 0x80
	s_addc_u32 s1, s19, 0
	s_mov_b32 m0, s16
	ds_read_b128 v[202:205], v149 offset:32768
	ds_read_b128 v[206:209], v149 offset:33792
	ds_read_b128 v[210:213], v149 offset:34816
	ds_read_b128 v[214:217], v149 offset:35840
	global_load_lds_dwordx4 v132, s[0:1]
	s_add_i32 m0, s16, 0x2000
	s_nop 0
	global_load_lds_dwordx4 v128, s[0:1]
	s_waitcnt vmcnt(8)
	s_setprio 1
	s_barrier
	s_waitcnt lgkmcnt(0)
	v_mfma_f32_16x16x32_bf16 v[120:123], v[202:205], v[166:169], v[120:123]
	v_mfma_f32_16x16x32_bf16 v[112:115], v[210:213], v[166:169], v[112:115]
	v_mfma_f32_16x16x32_bf16 v[104:107], v[202:205], v[174:177], v[104:107]
	v_mfma_f32_16x16x32_bf16 v[96:99], v[210:213], v[174:177], v[96:99]
	v_mfma_f32_16x16x32_bf16 v[88:91], v[202:205], v[182:185], v[88:91]
	v_mfma_f32_16x16x32_bf16 v[80:83], v[210:213], v[182:185], v[80:83]
	v_mfma_f32_16x16x32_bf16 v[72:75], v[202:205], v[190:193], v[72:75]
	v_mfma_f32_16x16x32_bf16 v[64:67], v[210:213], v[190:193], v[64:67]
	v_mfma_f32_16x16x32_bf16 v[120:123], v[206:209], v[170:173], v[120:123]
	v_mfma_f32_16x16x32_bf16 v[112:115], v[214:217], v[170:173], v[112:115]
	v_mfma_f32_16x16x32_bf16 v[104:107], v[206:209], v[178:181], v[104:107]
	v_mfma_f32_16x16x32_bf16 v[96:99], v[214:217], v[178:181], v[96:99]
	v_mfma_f32_16x16x32_bf16 v[88:91], v[206:209], v[186:189], v[88:91]
	v_mfma_f32_16x16x32_bf16 v[80:83], v[214:217], v[186:189], v[80:83]
	v_mfma_f32_16x16x32_bf16 v[72:75], v[206:209], v[194:197], v[72:75]
	v_mfma_f32_16x16x32_bf16 v[64:67], v[214:217], v[194:197], v[64:67]
	s_barrier
	s_setprio 0
	s_mov_b32 m0, s36
	s_add_u32 s0, s22, 0x80
	s_addc_u32 s1, s23, 0
	ds_read_b128 v[166:169], v148 offset:49152
	ds_read_b128 v[170:173], v148 offset:50176
	ds_read_b128 v[174:177], v148 offset:51200
	ds_read_b128 v[178:181], v148 offset:52224
	ds_read_b128 v[182:185], v148 offset:53248
	ds_read_b128 v[186:189], v148 offset:54272
	ds_read_b128 v[190:193], v148 offset:55296
	ds_read_b128 v[194:197], v148 offset:56320
	global_load_lds_dwordx4 v134, s[0:1]
	s_mov_b32 m0, s37
	s_nop 0
	global_load_lds_dwordx4 v130, s[0:1]
	s_setprio 1
	s_barrier
	s_waitcnt lgkmcnt(0)
	v_mfma_f32_16x16x32_bf16 v[60:63], v[150:153], v[166:169], v[60:63]
	v_mfma_f32_16x16x32_bf16 v[56:59], v[158:161], v[166:169], v[56:59]
	v_mfma_f32_16x16x32_bf16 v[44:47], v[150:153], v[174:177], v[44:47]
	v_mfma_f32_16x16x32_bf16 v[40:43], v[158:161], v[174:177], v[40:43]
	v_mfma_f32_16x16x32_bf16 v[28:31], v[150:153], v[182:185], v[28:31]
	v_mfma_f32_16x16x32_bf16 v[24:27], v[158:161], v[182:185], v[24:27]
	v_mfma_f32_16x16x32_bf16 v[12:15], v[150:153], v[190:193], v[12:15]
	v_mfma_f32_16x16x32_bf16 v[8:11], v[158:161], v[190:193], v[8:11]
	v_mfma_f32_16x16x32_bf16 v[60:63], v[154:157], v[170:173], v[60:63]
	v_mfma_f32_16x16x32_bf16 v[56:59], v[162:165], v[170:173], v[56:59]
	v_mfma_f32_16x16x32_bf16 v[44:47], v[154:157], v[178:181], v[44:47]
	v_mfma_f32_16x16x32_bf16 v[40:43], v[162:165], v[178:181], v[40:43]
	v_mfma_f32_16x16x32_bf16 v[28:31], v[154:157], v[186:189], v[28:31]
	v_mfma_f32_16x16x32_bf16 v[24:27], v[162:165], v[186:189], v[24:27]
	v_mfma_f32_16x16x32_bf16 v[12:15], v[154:157], v[194:197], v[12:15]
	v_mfma_f32_16x16x32_bf16 v[8:11], v[162:165], v[194:197], v[8:11]
	s_barrier
	s_setprio 0
	s_add_u32 s16, s18, 0x40080
	s_addc_u32 s17, s19, 0
	s_add_i32 s18, s21, s25
	s_mov_b32 m0, s18
	s_nop 0
	global_load_lds_dwordx4 v132, s[16:17]
	s_add_i32 m0, s18, 0x2000
	s_nop 0
	global_load_lds_dwordx4 v128, s[16:17]
	s_waitcnt vmcnt(8)
	s_setprio 1
	s_barrier
	v_mfma_f32_16x16x32_bf16 v[52:55], v[202:205], v[166:169], v[52:55]
	v_mfma_f32_16x16x32_bf16 v[48:51], v[210:213], v[166:169], v[48:51]
	v_mfma_f32_16x16x32_bf16 v[36:39], v[202:205], v[174:177], v[36:39]
	v_mfma_f32_16x16x32_bf16 v[32:35], v[210:213], v[174:177], v[32:35]
	v_mfma_f32_16x16x32_bf16 v[20:23], v[202:205], v[182:185], v[20:23]
	v_mfma_f32_16x16x32_bf16 v[16:19], v[210:213], v[182:185], v[16:19]
	v_mfma_f32_16x16x32_bf16 v[4:7], v[202:205], v[190:193], v[4:7]
	v_mfma_f32_16x16x32_bf16 v[0:3], v[210:213], v[190:193], v[0:3]
	v_mfma_f32_16x16x32_bf16 v[52:55], v[206:209], v[170:173], v[52:55]
	v_mfma_f32_16x16x32_bf16 v[48:51], v[214:217], v[170:173], v[48:51]
	v_mfma_f32_16x16x32_bf16 v[36:39], v[206:209], v[178:181], v[36:39]
	v_mfma_f32_16x16x32_bf16 v[32:35], v[214:217], v[178:181], v[32:35]
	v_mfma_f32_16x16x32_bf16 v[20:23], v[206:209], v[186:189], v[20:23]
	v_mfma_f32_16x16x32_bf16 v[16:19], v[214:217], v[186:189], v[16:19]
	v_mfma_f32_16x16x32_bf16 v[4:7], v[206:209], v[194:197], v[4:7]
	v_mfma_f32_16x16x32_bf16 v[0:3], v[214:217], v[194:197], v[0:3]
	s_setprio 0
	s_add_i32 s48, s48, 2
	s_add_u32 s14, s14, 0x100
	s_addc_u32 s15, s15, 0
	s_add_u32 s46, s46, 0x100
	s_addc_u32 s47, s47, 0
	s_cmp_gt_u32 s48, 13
	s_cbranch_scc1 .Lconc_last_g0
	s_barrier
	s_branch .LBB0_235

; #define PG8_STAGE(bufoff, gbase, voff) do { _Pragma("unroll") for (int _i = 0; _i < 2; ++_i) \
;         __builtin_amdgcn_global_load_lds((const unsigned*)((const char*)(gbase) + (voff)[_i]), (LAS unsigned*)(lds + (bufoff) + ldsw + _i * 8192), 16, 0, 0); } while (0)
; #define PG8_LDA(dst, b, h) do { _Pragma("unroll") for (int m = 0; m < 4; ++m) _Pragma("unroll") for (int k = 0; k < 2; ++k) dst[m][k] = *(const LAS bf16x8*)(lds + PG8_SA(b, h) + aoff + m * 2048 + k * 1024); } while (0)
; #define PG8_LDB(dst, b, h) do { _Pragma("unroll") for (int n = 0; n < 2; ++n) _Pragma("unroll") for (int k = 0; k < 2; ++k) dst[n][k] = *(const LAS bf16x8*)(lds + PG8_SB(b, h) + boff + n * 2048 + k * 1024); } while (0)
; #define PG8_MMA(ai, bj, At, Bt) do { __builtin_amdgcn_s_setprio(1); _Pragma("unroll") for (int m = 0; m < 4; ++m) _Pragma("unroll") for (int n = 0; n < 2; ++n) _Pragma("unroll") for (int k = 0; k < 2; ++k) \
;         acc[ai][bj][m][n] = __builtin_amdgcn_mfma_f32_16x16x32_bf16(Bt[n][k], At[m][k], acc[ai][bj][m][n], 0, 0, 0); __builtin_amdgcn_s_setprio(0); } while (0)
; template <class Epi, class Sched>
; __device__ __forceinline__ void gemm_phase(LAS unsigned char* lds, const Gemm g, const Sched& S, const Epi& E) {
;     ...
;         const char* nA = has_next ? (const char*)g.A + (size_t)nxt.pm * tstep : cA; const char* nB = has_next ? (const char*)g.Bt + (size_t)nxt.pn * tstep : cB;
;         for (int t = 0; t < nt; t += 2) {
;             const bool last = (t == nt - 2);
;             const char* a1 = cA + (size_t)(t + 1) * kstep;
;             const char* a2 = last ? nA : cA + (size_t)(t + 2) * kstep; const char* b2 = last ? nB : cB + (size_t)(t + 2) * kstep;
;             const char* a3 = a2 + kstep; const char* b3 = b2 + kstep;
;             PG8_LDB(B0, 0, 0); PG8_SCHED; PG8_LDA(At, 0, 0); PG8_STAGE(PG8_SA(1, 1), a1 + hstep, voffA);
;             PG8_WAIT_L(8); PG8_BAR; PG8_WAIT_L(0); PG8_MMA(0, 0, At, B0); PG8_BAR; PG8_SCHED;
;             PG8_LDB(B1, 0, 1); PG8_STAGE(PG8_SB(0, 0), b2, voffB);
;             PG8_BAR; PG8_WAIT_L(0); PG8_MMA(0, 1, At, B1); PG8_BAR;
;             PG8_LDA(At, 0, 1); PG8_STAGE(PG8_SA(0, 0), a2, voffA);
;             PG8_BAR; PG8_WAIT_L(0); PG8_MMA(1, 0, At, B0); PG8_BAR; PG8_SCHED;
;             PG8_STAGE(PG8_SB(0, 1), b2 + hstep, voffB);
;             PG8_WAIT_V(6); PG8_BAR; PG8_MMA(1, 1, At, B1); PG8_BAR;
.LBB0_304:
	s_add_u32 s0, s28, 0x100
	s_addc_u32 s67, s29, 0
	s_mov_b32 s68, -2
	ds_read_b128 v[144:147], v165
	ds_read_b128 v[148:151], v165 offset:1024
	ds_read_b128 v[152:155], v165 offset:2048
	ds_read_b128 v[156:159], v165 offset:3072
	s_add_u32 s28, s26, 0x100
	s_addc_u32 s29, s27, 0
	s_cmp_eq_u32 s68, 40
	s_cselect_b32 s37, s5, s29
	s_cselect_b32 s36, s4, s28
	s_cselect_b32 s35, s7, s67
	s_cselect_b32 s34, s6, s0
	v_lshl_add_u64 v[160:161], s[26:27], 0, v[136:137]
	s_add_i32 m0, s42, 0xc000
	ds_read_b128 v[168:171], v166
	ds_read_b128 v[172:175], v166 offset:1024
	ds_read_b128 v[176:179], v166 offset:2048
	ds_read_b128 v[180:183], v166 offset:3072
	ds_read_b128 v[184:187], v166 offset:4096
	ds_read_b128 v[188:191], v166 offset:5120
	ds_read_b128 v[192:195], v166 offset:6144
	ds_read_b128 v[196:199], v166 offset:7168
	global_load_lds_dwordx4 v[160:161], off
	v_lshl_add_u64 v[160:161], s[26:27], 0, v[138:139]
	s_add_i32 m0, s42, 0xe000
	s_nop 0
	global_load_lds_dwordx4 v[160:161], off
	s_waitcnt lgkmcnt(8)
	s_waitcnt vmcnt(8)
	s_setprio 1
	s_barrier
	s_waitcnt lgkmcnt(0)
	v_mfma_f32_16x16x32_bf16 v[124:127], v[144:147], v[168:171], 0
	v_mfma_f32_16x16x32_bf16 v[120:123], v[152:155], v[168:171], 0
	v_mfma_f32_16x16x32_bf16 v[116:119], v[144:147], v[176:179], 0
	v_mfma_f32_16x16x32_bf16 v[104:107], v[152:155], v[176:179], 0
	v_mfma_f32_16x16x32_bf16 v[96:99], v[144:147], v[184:187], 0
	v_mfma_f32_16x16x32_bf16 v[88:91], v[152:155], v[184:187], 0
	v_mfma_f32_16x16x32_bf16 v[80:83], v[144:147], v[192:195], 0
	v_mfma_f32_16x16x32_bf16 v[72:75], v[152:155], v[192:195], 0
	v_mfma_f32_16x16x32_bf16 v[124:127], v[148:151], v[172:175], v[124:127]
	v_mfma_f32_16x16x32_bf16 v[120:123], v[156:159], v[172:175], v[120:123]
	v_mfma_f32_16x16x32_bf16 v[116:119], v[148:151], v[180:183], v[116:119]
	v_mfma_f32_16x16x32_bf16 v[104:107], v[156:159], v[180:183], v[104:107]
	v_mfma_f32_16x16x32_bf16 v[96:99], v[148:151], v[188:191], v[96:99]
	v_mfma_f32_16x16x32_bf16 v[88:91], v[156:159], v[188:191], v[88:91]
	v_mfma_f32_16x16x32_bf16 v[80:83], v[148:151], v[196:199], v[80:83]
	v_mfma_f32_16x16x32_bf16 v[72:75], v[156:159], v[196:199], v[72:75]
	s_barrier
	s_setprio 0
	s_add_i32 s16, s58, s40
	s_mov_b32 m0, s16
	ds_read_b128 v[202:205], v167
	ds_read_b128 v[206:209], v167 offset:1024
	ds_read_b128 v[210:213], v167 offset:2048
	ds_read_b128 v[214:217], v167 offset:3072
	global_load_lds_dwordx4 v132, s[34:35]
	s_add_i32 m0, s16, 0x2000
	s_nop 0
	global_load_lds_dwordx4 v128, s[34:35]
	s_waitcnt vmcnt(8)
	s_setprio 1
	s_barrier
	s_waitcnt lgkmcnt(0)
	v_mfma_f32_16x16x32_bf16 v[112:115], v[202:205], v[168:171], 0
	v_mfma_f32_16x16x32_bf16 v[108:111], v[210:213], v[168:171], 0
	v_mfma_f32_16x16x32_bf16 v[100:103], v[202:205], v[176:179], 0
	v_mfma_f32_16x16x32_bf16 v[92:95], v[210:213], v[176:179], 0
	v_mfma_f32_16x16x32_bf16 v[84:87], v[202:205], v[184:187], 0
	v_mfma_f32_16x16x32_bf16 v[76:79], v[210:213], v[184:187], 0
	v_mfma_f32_16x16x32_bf16 v[68:71], v[202:205], v[192:195], 0
	v_mfma_f32_16x16x32_bf16 v[64:67], v[210:213], v[192:195], 0
	v_mfma_f32_16x16x32_bf16 v[112:115], v[206:209], v[172:175], v[112:115]
	v_mfma_f32_16x16x32_bf16 v[108:111], v[214:217], v[172:175], v[108:111]
	v_mfma_f32_16x16x32_bf16 v[100:103], v[206:209], v[180:183], v[100:103]
	v_mfma_f32_16x16x32_bf16 v[92:95], v[214:217], v[180:183], v[92:95]
	v_mfma_f32_16x16x32_bf16 v[84:87], v[206:209], v[188:191], v[84:87]
	v_mfma_f32_16x16x32_bf16 v[76:79], v[214:217], v[188:191], v[76:79]
	v_mfma_f32_16x16x32_bf16 v[68:71], v[206:209], v[196:199], v[68:71]
	v_mfma_f32_16x16x32_bf16 v[64:67], v[214:217], v[196:199], v[64:67]
	s_barrier
	s_setprio 0
	s_mov_b32 m0, s42
	ds_read_b128 v[168:171], v166 offset:16384
	ds_read_b128 v[172:175], v166 offset:17408
	ds_read_b128 v[176:179], v166 offset:18432
	ds_read_b128 v[180:183], v166 offset:19456
	ds_read_b128 v[184:187], v166 offset:20480
	ds_read_b128 v[188:191], v166 offset:21504
	ds_read_b128 v[192:195], v166 offset:22528
	ds_read_b128 v[196:199], v166 offset:23552
	global_load_lds_dwordx4 v134, s[36:37]
	s_mov_b32 m0, s43
	s_nop 0
	global_load_lds_dwordx4 v130, s[36:37]
	s_setprio 1
	s_barrier
	s_waitcnt lgkmcnt(0)
	v_mfma_f32_16x16x32_bf16 v[60:63], v[144:147], v[168:171], 0
	v_mfma_f32_16x16x32_bf16 v[56:59], v[152:155], v[168:171], 0
	v_mfma_f32_16x16x32_bf16 v[48:51], v[144:147], v[176:179], 0
	v_mfma_f32_16x16x32_bf16 v[40:43], v[152:155], v[176:179], 0
	v_mfma_f32_16x16x32_bf16 v[32:35], v[144:147], v[184:187], 0
	v_mfma_f32_16x16x32_bf16 v[24:27], v[152:155], v[184:187], 0
	v_mfma_f32_16x16x32_bf16 v[16:19], v[144:147], v[192:195], 0
	v_mfma_f32_16x16x32_bf16 v[8:11], v[152:155], v[192:195], 0
	v_mfma_f32_16x16x32_bf16 v[60:63], v[148:151], v[172:175], v[60:63]
	v_mfma_f32_16x16x32_bf16 v[56:59], v[156:159], v[172:175], v[56:59]
	v_mfma_f32_16x16x32_bf16 v[48:51], v[148:151], v[180:183], v[48:51]
	v_mfma_f32_16x16x32_bf16 v[40:43], v[156:159], v[180:183], v[40:43]
	v_mfma_f32_16x16x32_bf16 v[32:35], v[148:151], v[188:191], v[32:35]
	v_mfma_f32_16x16x32_bf16 v[24:27], v[156:159], v[188:191], v[24:27]
	v_mfma_f32_16x16x32_bf16 v[16:19], v[148:151], v[196:199], v[16:19]
	v_mfma_f32_16x16x32_bf16 v[8:11], v[156:159], v[196:199], v[8:11]
	s_barrier
	s_setprio 0
	s_add_u32 s16, s34, 0xb0000
	s_addc_u32 s17, s35, 0
	s_add_i32 s20, s59, s40
	s_mov_b32 m0, s20
	s_nop 0
	global_load_lds_dwordx4 v132, s[16:17]
	s_add_i32 m0, s20, 0x2000
	s_nop 0
	global_load_lds_dwordx4 v128, s[16:17]
	s_add_u32 s16, s36, 0xb0000
	s_addc_u32 s17, s37, 0
	s_mov_b32 m0, s44
	s_nop 0
	global_load_lds_dwordx4 v134, s[16:17]
	s_mov_b32 m0, s45
	s_nop 0
	global_load_lds_dwordx4 v130, s[16:17]
	s_waitcnt vmcnt(10)
	s_setprio 1
	s_barrier
; #define PG8_STAGE(bufoff, gbase, voff) do { _Pragma("unroll") for (int _i = 0; _i < 2; ++_i) \
;         __builtin_amdgcn_global_load_lds((const unsigned*)((const char*)(gbase) + (voff)[_i]), (LAS unsigned*)(lds + (bufoff) + ldsw + _i * 8192), 16, 0, 0); } while (0)
; #define PG8_LDA(dst, b, h) do { _Pragma("unroll") for (int m = 0; m < 4; ++m) _Pragma("unroll") for (int k = 0; k < 2; ++k) dst[m][k] = *(const LAS bf16x8*)(lds + PG8_SA(b, h) + aoff + m * 2048 + k * 1024); } while (0)
; #define PG8_LDB(dst, b, h) do { _Pragma("unroll") for (int n = 0; n < 2; ++n) _Pragma("unroll") for (int k = 0; k < 2; ++k) dst[n][k] = *(const LAS bf16x8*)(lds + PG8_SB(b, h) + boff + n * 2048 + k * 1024); } while (0)
; #define PG8_MMA(ai, bj, At, Bt) do { __builtin_amdgcn_s_setprio(1); _Pragma("unroll") for (int m = 0; m < 4; ++m) _Pragma("unroll") for (int n = 0; n < 2; ++n) _Pragma("unroll") for (int k = 0; k < 2; ++k) \
;         acc[ai][bj][m][n] = __builtin_amdgcn_mfma_f32_16x16x32_bf16(Bt[n][k], At[m][k], acc[ai][bj][m][n], 0, 0, 0); __builtin_amdgcn_s_setprio(0); } while (0)
; #define PG8_WAIT_V(n) asm volatile("s_waitcnt vmcnt(" #n ")" ::: "memory")
; #define PG8_WAIT_L(n) asm volatile("s_waitcnt lgkmcnt(" #n ")" ::: "memory")
; #define PG8_BAR __builtin_amdgcn_s_barrier()
; #define PG8_SCHED __builtin_amdgcn_sched_barrier(0)
; template <class Epi, class Sched>
; __device__ __forceinline__ void gemm_phase(LAS unsigned char* lds, const Gemm g, const Sched& S, const Epi& E) {
;     ...
;             PG8_WAIT_V(6); PG8_BAR; PG8_MMA(1, 1, At, B1); PG8_BAR;
;             PG8_LDB(B0, 1, 0); PG8_SCHED; PG8_LDA(At, 1, 0); PG8_STAGE(PG8_SA(0, 1), a2 + hstep, voffA);
;             PG8_WAIT_L(8); PG8_BAR; PG8_WAIT_L(0); PG8_MMA(0, 0, At, B0); PG8_BAR; PG8_SCHED;
;             PG8_LDB(B1, 1, 1); PG8_STAGE(PG8_SB(1, 0), b3, voffB);
;             PG8_BAR; PG8_WAIT_L(0); PG8_MMA(0, 1, At, B1); PG8_BAR;
;             PG8_LDA(At, 1, 1); PG8_STAGE(PG8_SA(1, 0), a3, voffA);
	v_mfma_f32_16x16x32_bf16 v[52:55], v[202:205], v[168:171], 0
	v_mfma_f32_16x16x32_bf16 v[44:47], v[210:213], v[168:171], 0
	v_mfma_f32_16x16x32_bf16 v[36:39], v[202:205], v[176:179], 0
	v_mfma_f32_16x16x32_bf16 v[28:31], v[210:213], v[176:179], 0
	v_mfma_f32_16x16x32_bf16 v[20:23], v[202:205], v[184:187], 0
	v_mfma_f32_16x16x32_bf16 v[12:15], v[210:213], v[184:187], 0
	v_mfma_f32_16x16x32_bf16 v[4:7], v[202:205], v[192:195], 0
	v_mfma_f32_16x16x32_bf16 v[0:3], v[210:213], v[192:195], 0
	v_mfma_f32_16x16x32_bf16 v[52:55], v[206:209], v[172:175], v[52:55]
	v_mfma_f32_16x16x32_bf16 v[44:47], v[214:217], v[172:175], v[44:47]
	v_mfma_f32_16x16x32_bf16 v[36:39], v[206:209], v[180:183], v[36:39]
	v_mfma_f32_16x16x32_bf16 v[28:31], v[214:217], v[180:183], v[28:31]
	v_mfma_f32_16x16x32_bf16 v[20:23], v[206:209], v[188:191], v[20:23]
	v_mfma_f32_16x16x32_bf16 v[12:15], v[214:217], v[188:191], v[12:15]
	v_mfma_f32_16x16x32_bf16 v[4:7], v[206:209], v[196:199], v[4:7]
	v_mfma_f32_16x16x32_bf16 v[0:3], v[214:217], v[196:199], v[0:3]
	s_barrier
	s_setprio 0
	s_add_i32 s20, 0, 0x18000
	ds_read_b128 v[144:147], v167 offset:16384
	ds_read_b128 v[148:151], v167 offset:17408
	ds_read_b128 v[152:155], v167 offset:18432
	ds_read_b128 v[156:159], v167 offset:19456
	ds_read_b128 v[168:171], v166 offset:32768
	ds_read_b128 v[172:175], v166 offset:33792
	ds_read_b128 v[176:179], v166 offset:34816
	ds_read_b128 v[180:183], v166 offset:35840
	ds_read_b128 v[184:187], v166 offset:36864
	ds_read_b128 v[188:191], v166 offset:37888
	ds_read_b128 v[192:195], v166 offset:38912
	ds_read_b128 v[196:199], v166 offset:39936
	s_waitcnt lgkmcnt(8)
	s_waitcnt vmcnt(8)
	s_setprio 1
	s_barrier
	s_waitcnt lgkmcnt(0)
	v_mfma_f32_16x16x32_bf16 v[124:127], v[144:147], v[168:171], v[124:127]
	v_mfma_f32_16x16x32_bf16 v[120:123], v[152:155], v[168:171], v[120:123]
	v_mfma_f32_16x16x32_bf16 v[116:119], v[144:147], v[176:179], v[116:119]
	v_mfma_f32_16x16x32_bf16 v[104:107], v[152:155], v[176:179], v[104:107]
	v_mfma_f32_16x16x32_bf16 v[96:99], v[144:147], v[184:187], v[96:99]
	v_mfma_f32_16x16x32_bf16 v[88:91], v[152:155], v[184:187], v[88:91]
	v_mfma_f32_16x16x32_bf16 v[80:83], v[144:147], v[192:195], v[80:83]
	v_mfma_f32_16x16x32_bf16 v[72:75], v[152:155], v[192:195], v[72:75]
	v_mfma_f32_16x16x32_bf16 v[124:127], v[148:151], v[172:175], v[124:127]
	v_mfma_f32_16x16x32_bf16 v[120:123], v[156:159], v[172:175], v[120:123]
	v_mfma_f32_16x16x32_bf16 v[116:119], v[148:151], v[180:183], v[116:119]
	v_mfma_f32_16x16x32_bf16 v[104:107], v[156:159], v[180:183], v[104:107]
	v_mfma_f32_16x16x32_bf16 v[96:99], v[148:151], v[188:191], v[96:99]
	v_mfma_f32_16x16x32_bf16 v[88:91], v[156:159], v[188:191], v[88:91]
	v_mfma_f32_16x16x32_bf16 v[80:83], v[148:151], v[196:199], v[80:83]
	v_mfma_f32_16x16x32_bf16 v[72:75], v[156:159], v[196:199], v[72:75]
	s_barrier
	s_setprio 0
	s_add_i32 s21, 0, 0x1c000
	s_add_i32 s16, s20, s40
	s_add_u32 s8, s34, 0x80
	s_addc_u32 s9, s35, 0
	s_mov_b32 m0, s16
	ds_read_b128 v[202:205], v167 offset:32768
	ds_read_b128 v[206:209], v167 offset:33792
	ds_read_b128 v[210:213], v167 offset:34816
	ds_read_b128 v[214:217], v167 offset:35840
	global_load_lds_dwordx4 v132, s[8:9]
	s_add_i32 m0, s16, 0x2000
	s_nop 0
	global_load_lds_dwordx4 v128, s[8:9]
	s_waitcnt vmcnt(8)
	s_setprio 1
	s_barrier
	s_waitcnt lgkmcnt(0)
	v_mfma_f32_16x16x32_bf16 v[112:115], v[202:205], v[168:171], v[112:115]
	v_mfma_f32_16x16x32_bf16 v[108:111], v[210:213], v[168:171], v[108:111]
	v_mfma_f32_16x16x32_bf16 v[100:103], v[202:205], v[176:179], v[100:103]
	v_mfma_f32_16x16x32_bf16 v[92:95], v[210:213], v[176:179], v[92:95]
	v_mfma_f32_16x16x32_bf16 v[84:87], v[202:205], v[184:187], v[84:87]
	v_mfma_f32_16x16x32_bf16 v[76:79], v[210:213], v[184:187], v[76:79]
	v_mfma_f32_16x16x32_bf16 v[68:71], v[202:205], v[192:195], v[68:71]
	v_mfma_f32_16x16x32_bf16 v[64:67], v[210:213], v[192:195], v[64:67]
	v_mfma_f32_16x16x32_bf16 v[112:115], v[206:209], v[172:175], v[112:115]
	v_mfma_f32_16x16x32_bf16 v[108:111], v[214:217], v[172:175], v[108:111]
	v_mfma_f32_16x16x32_bf16 v[100:103], v[206:209], v[180:183], v[100:103]
	v_mfma_f32_16x16x32_bf16 v[92:95], v[214:217], v[180:183], v[92:95]
	v_mfma_f32_16x16x32_bf16 v[84:87], v[206:209], v[188:191], v[84:87]
	v_mfma_f32_16x16x32_bf16 v[76:79], v[214:217], v[188:191], v[76:79]
	v_mfma_f32_16x16x32_bf16 v[68:71], v[206:209], v[196:199], v[68:71]
	v_mfma_f32_16x16x32_bf16 v[64:67], v[214:217], v[196:199], v[64:67]
	s_barrier
	s_setprio 0
	s_mov_b32 m0, s52
	s_add_u32 s8, s36, 0x80
	s_addc_u32 s9, s37, 0
	ds_read_b128 v[168:171], v166 offset:49152
	ds_read_b128 v[172:175], v166 offset:50176
	ds_read_b128 v[176:179], v166 offset:51200
	ds_read_b128 v[180:183], v166 offset:52224
	ds_read_b128 v[184:187], v166 offset:53248
	ds_read_b128 v[188:191], v166 offset:54272
	ds_read_b128 v[192:195], v166 offset:55296
	ds_read_b128 v[196:199], v166 offset:56320
	global_load_lds_dwordx4 v134, s[8:9]
	s_mov_b32 m0, s53
	s_nop 0
	global_load_lds_dwordx4 v130, s[8:9]
	s_setprio 1
	s_barrier
	s_waitcnt lgkmcnt(0)
	v_mfma_f32_16x16x32_bf16 v[60:63], v[144:147], v[168:171], v[60:63]
	v_mfma_f32_16x16x32_bf16 v[56:59], v[152:155], v[168:171], v[56:59]
	v_mfma_f32_16x16x32_bf16 v[48:51], v[144:147], v[176:179], v[48:51]
	v_mfma_f32_16x16x32_bf16 v[40:43], v[152:155], v[176:179], v[40:43]
	v_mfma_f32_16x16x32_bf16 v[32:35], v[144:147], v[184:187], v[32:35]
	v_mfma_f32_16x16x32_bf16 v[24:27], v[152:155], v[184:187], v[24:27]
	v_mfma_f32_16x16x32_bf16 v[16:19], v[144:147], v[192:195], v[16:19]
	v_mfma_f32_16x16x32_bf16 v[8:11], v[152:155], v[192:195], v[8:11]
	v_mfma_f32_16x16x32_bf16 v[60:63], v[148:151], v[172:175], v[60:63]
	v_mfma_f32_16x16x32_bf16 v[56:59], v[156:159], v[172:175], v[56:59]
	v_mfma_f32_16x16x32_bf16 v[48:51], v[148:151], v[180:183], v[48:51]
	v_mfma_f32_16x16x32_bf16 v[40:43], v[156:159], v[180:183], v[40:43]
	v_mfma_f32_16x16x32_bf16 v[32:35], v[148:151], v[188:191], v[32:35]
	v_mfma_f32_16x16x32_bf16 v[24:27], v[156:159], v[188:191], v[24:27]
	v_mfma_f32_16x16x32_bf16 v[16:19], v[148:151], v[196:199], v[16:19]
	v_mfma_f32_16x16x32_bf16 v[8:11], v[156:159], v[196:199], v[8:11]
	s_barrier
; #define PG8_STAGE(bufoff, gbase, voff) do { _Pragma("unroll") for (int _i = 0; _i < 2; ++_i) \
;         __builtin_amdgcn_global_load_lds((const unsigned*)((const char*)(gbase) + (voff)[_i]), (LAS unsigned*)(lds + (bufoff) + ldsw + _i * 8192), 16, 0, 0); } while (0)
; #define PG8_LDA(dst, b, h) do { _Pragma("unroll") for (int m = 0; m < 4; ++m) _Pragma("unroll") for (int k = 0; k < 2; ++k) dst[m][k] = *(const LAS bf16x8*)(lds + PG8_SA(b, h) + aoff + m * 2048 + k * 1024); } while (0)
; #define PG8_LDB(dst, b, h) do { _Pragma("unroll") for (int n = 0; n < 2; ++n) _Pragma("unroll") for (int k = 0; k < 2; ++k) dst[n][k] = *(const LAS bf16x8*)(lds + PG8_SB(b, h) + boff + n * 2048 + k * 1024); } while (0)
; #define PG8_WAIT_V(n) asm volatile("s_waitcnt vmcnt(" #n ")" ::: "memory")
; #define PG8_WAIT_L(n) asm volatile("s_waitcnt lgkmcnt(" #n ")" ::: "memory")
; #define PG8_BAR __builtin_amdgcn_s_barrier()
; #define PG8_SCHED __builtin_amdgcn_sched_barrier(0)
; template <class Epi, class Sched>
; __device__ __forceinline__ void gemm_phase(LAS unsigned char* lds, const Gemm g, const Sched& S, const Epi& E) {
;     ...
;             PG8_LDB(B0, 0, 0); PG8_SCHED; PG8_LDA(At, 0, 0); PG8_STAGE(PG8_SA(1, 1), a1 + hstep, voffA);
;             PG8_WAIT_L(8); PG8_BAR; PG8_WAIT_L(0); PG8_MMA(0, 0, At, B0); PG8_BAR; PG8_SCHED;
;             PG8_LDB(B1, 0, 1); PG8_STAGE(PG8_SB(0, 0), b2, voffB);
;             PG8_BAR; PG8_WAIT_L(0); PG8_MMA(0, 1, At, B1); PG8_BAR;
;             PG8_LDA(At, 0, 1); PG8_STAGE(PG8_SA(0, 0), a2, voffA);
;             PG8_BAR; PG8_WAIT_L(0); PG8_MMA(1, 0, At, B0); PG8_BAR; PG8_SCHED;
;             PG8_STAGE(PG8_SB(0, 1), b2 + hstep, voffB);
;             PG8_WAIT_V(6); PG8_BAR; PG8_MMA(1, 1, At, B1); PG8_BAR;
;             PG8_LDB(B0, 1, 0); PG8_SCHED; PG8_LDA(At, 1, 0); PG8_STAGE(PG8_SA(0, 1), a2 + hstep, voffA);
;             PG8_WAIT_L(8); PG8_BAR; PG8_WAIT_L(0); PG8_MMA(0, 0, At, B0); PG8_BAR; PG8_SCHED;
;             PG8_LDB(B1, 1, 1); PG8_STAGE(PG8_SB(1, 0), b3, voffB);
;             PG8_BAR; PG8_WAIT_L(0); PG8_MMA(0, 1, At, B1); PG8_BAR;
;             PG8_LDA(At, 1, 1); PG8_STAGE(PG8_SA(1, 0), a3, voffA);
;             PG8_BAR; PG8_WAIT_L(0); PG8_MMA(1, 0, At, B0); PG8_BAR; PG8_SCHED;
;             PG8_STAGE(PG8_SB(1, 1), b3 + hstep, voffB);
;             PG8_WAIT_V(6); PG8_BAR; PG8_MMA(1, 1, At, B1); PG8_BAR;
	s_setprio 0
	s_add_u32 s16, s34, 0xb0080
	s_addc_u32 s17, s35, 0
	s_add_i32 s20, s21, s40
	s_mov_b32 m0, s20
	s_nop 0
	global_load_lds_dwordx4 v132, s[16:17]
	s_add_i32 m0, s20, 0x2000
	s_nop 0
	global_load_lds_dwordx4 v128, s[16:17]
	s_waitcnt vmcnt(8)
	s_setprio 1
	s_barrier
	v_mfma_f32_16x16x32_bf16 v[52:55], v[202:205], v[168:171], v[52:55]
	v_mfma_f32_16x16x32_bf16 v[44:47], v[210:213], v[168:171], v[44:47]
	v_mfma_f32_16x16x32_bf16 v[36:39], v[202:205], v[176:179], v[36:39]
	v_mfma_f32_16x16x32_bf16 v[28:31], v[210:213], v[176:179], v[28:31]
	v_mfma_f32_16x16x32_bf16 v[20:23], v[202:205], v[184:187], v[20:23]
	v_mfma_f32_16x16x32_bf16 v[12:15], v[210:213], v[184:187], v[12:15]
	v_mfma_f32_16x16x32_bf16 v[4:7], v[202:205], v[192:195], v[4:7]
	v_mfma_f32_16x16x32_bf16 v[0:3], v[210:213], v[192:195], v[0:3]
	v_mfma_f32_16x16x32_bf16 v[52:55], v[206:209], v[172:175], v[52:55]
	v_mfma_f32_16x16x32_bf16 v[44:47], v[214:217], v[172:175], v[44:47]
	v_mfma_f32_16x16x32_bf16 v[36:39], v[206:209], v[180:183], v[36:39]
	v_mfma_f32_16x16x32_bf16 v[28:31], v[214:217], v[180:183], v[28:31]
	v_mfma_f32_16x16x32_bf16 v[20:23], v[206:209], v[188:191], v[20:23]
	v_mfma_f32_16x16x32_bf16 v[12:15], v[214:217], v[188:191], v[12:15]
	v_mfma_f32_16x16x32_bf16 v[4:7], v[206:209], v[196:199], v[4:7]
	v_mfma_f32_16x16x32_bf16 v[0:3], v[214:217], v[196:199], v[0:3]
	s_barrier
	s_setprio 0
	s_add_i32 s68, s68, 2
	s_add_u32 s0, s0, 0x100
	s_addc_u32 s67, s67, 0
	s_cmp_gt_u32 s68, 41
	s_mov_b64 s[26:27], s[28:29]
.LBB0_305:
	ds_read_b128 v[144:147], v165
	ds_read_b128 v[148:151], v165 offset:1024
	ds_read_b128 v[152:155], v165 offset:2048
	ds_read_b128 v[156:159], v165 offset:3072
	s_add_u32 s28, s26, 0x100
	s_addc_u32 s29, s27, 0
	s_cmp_eq_u32 s68, 40
	s_cselect_b32 s37, s5, s29
	s_cselect_b32 s36, s4, s28
	s_cselect_b32 s35, s7, s67
	s_cselect_b32 s34, s6, s0
	v_lshl_add_u64 v[160:161], s[26:27], 0, v[136:137]
	s_add_i32 m0, s42, 0xc000
	ds_read_b128 v[168:171], v166
	ds_read_b128 v[172:175], v166 offset:1024
	ds_read_b128 v[176:179], v166 offset:2048
	ds_read_b128 v[180:183], v166 offset:3072
	ds_read_b128 v[184:187], v166 offset:4096
	ds_read_b128 v[188:191], v166 offset:5120
	ds_read_b128 v[192:195], v166 offset:6144
	ds_read_b128 v[196:199], v166 offset:7168
	global_load_lds_dwordx4 v[160:161], off
	v_lshl_add_u64 v[160:161], s[26:27], 0, v[138:139]
	s_add_i32 m0, s42, 0xe000
	s_nop 0
	global_load_lds_dwordx4 v[160:161], off
	s_waitcnt lgkmcnt(8)
	s_waitcnt vmcnt(8)
	s_setprio 1
	s_barrier
	s_waitcnt lgkmcnt(0)
	v_mfma_f32_16x16x32_bf16 v[124:127], v[144:147], v[168:171], v[124:127]
	v_mfma_f32_16x16x32_bf16 v[120:123], v[152:155], v[168:171], v[120:123]
	v_mfma_f32_16x16x32_bf16 v[116:119], v[144:147], v[176:179], v[116:119]
	v_mfma_f32_16x16x32_bf16 v[104:107], v[152:155], v[176:179], v[104:107]
	v_mfma_f32_16x16x32_bf16 v[96:99], v[144:147], v[184:187], v[96:99]
	v_mfma_f32_16x16x32_bf16 v[88:91], v[152:155], v[184:187], v[88:91]
	v_mfma_f32_16x16x32_bf16 v[80:83], v[144:147], v[192:195], v[80:83]
	v_mfma_f32_16x16x32_bf16 v[72:75], v[152:155], v[192:195], v[72:75]
	v_mfma_f32_16x16x32_bf16 v[124:127], v[148:151], v[172:175], v[124:127]
	v_mfma_f32_16x16x32_bf16 v[120:123], v[156:159], v[172:175], v[120:123]
	v_mfma_f32_16x16x32_bf16 v[116:119], v[148:151], v[180:183], v[116:119]
	v_mfma_f32_16x16x32_bf16 v[104:107], v[156:159], v[180:183], v[104:107]
	v_mfma_f32_16x16x32_bf16 v[96:99], v[148:151], v[188:191], v[96:99]
	v_mfma_f32_16x16x32_bf16 v[88:91], v[156:159], v[188:191], v[88:91]
	v_mfma_f32_16x16x32_bf16 v[80:83], v[148:151], v[196:199], v[80:83]
	v_mfma_f32_16x16x32_bf16 v[72:75], v[156:159], v[196:199], v[72:75]
	s_barrier
	s_setprio 0
	s_add_i32 s16, s58, s40
	s_mov_b32 m0, s16
	ds_read_b128 v[202:205], v167
	ds_read_b128 v[206:209], v167 offset:1024
	ds_read_b128 v[210:213], v167 offset:2048
	ds_read_b128 v[214:217], v167 offset:3072
	global_load_lds_dwordx4 v132, s[34:35]
	s_add_i32 m0, s16, 0x2000
	s_nop 0
	global_load_lds_dwordx4 v128, s[34:35]
	s_waitcnt vmcnt(8)
	s_setprio 1
	s_barrier
	s_waitcnt lgkmcnt(0)
	v_mfma_f32_16x16x32_bf16 v[112:115], v[202:205], v[168:171], v[112:115]
	v_mfma_f32_16x16x32_bf16 v[108:111], v[210:213], v[168:171], v[108:111]
	v_mfma_f32_16x16x32_bf16 v[100:103], v[202:205], v[176:179], v[100:103]
	v_mfma_f32_16x16x32_bf16 v[92:95], v[210:213], v[176:179], v[92:95]
	v_mfma_f32_16x16x32_bf16 v[84:87], v[202:205], v[184:187], v[84:87]
	v_mfma_f32_16x16x32_bf16 v[76:79], v[210:213], v[184:187], v[76:79]
	v_mfma_f32_16x16x32_bf16 v[68:71], v[202:205], v[192:195], v[68:71]
	v_mfma_f32_16x16x32_bf16 v[64:67], v[210:213], v[192:195], v[64:67]
	v_mfma_f32_16x16x32_bf16 v[112:115], v[206:209], v[172:175], v[112:115]
	v_mfma_f32_16x16x32_bf16 v[108:111], v[214:217], v[172:175], v[108:111]
	v_mfma_f32_16x16x32_bf16 v[100:103], v[206:209], v[180:183], v[100:103]
	v_mfma_f32_16x16x32_bf16 v[92:95], v[214:217], v[180:183], v[92:95]
	v_mfma_f32_16x16x32_bf16 v[84:87], v[206:209], v[188:191], v[84:87]
	v_mfma_f32_16x16x32_bf16 v[76:79], v[214:217], v[188:191], v[76:79]
	v_mfma_f32_16x16x32_bf16 v[68:71], v[206:209], v[196:199], v[68:71]
	v_mfma_f32_16x16x32_bf16 v[64:67], v[214:217], v[196:199], v[64:67]
	s_barrier
	s_setprio 0
	s_mov_b32 m0, s42
	ds_read_b128 v[168:171], v166 offset:16384
	ds_read_b128 v[172:175], v166 offset:17408
	ds_read_b128 v[176:179], v166 offset:18432
	ds_read_b128 v[180:183], v166 offset:19456
	ds_read_b128 v[184:187], v166 offset:20480
	ds_read_b128 v[188:191], v166 offset:21504
	ds_read_b128 v[192:195], v166 offset:22528
	ds_read_b128 v[196:199], v166 offset:23552
	global_load_lds_dwordx4 v134, s[36:37]
	s_mov_b32 m0, s43
	s_nop 0
	global_load_lds_dwordx4 v130, s[36:37]
	s_setprio 1
	s_barrier
; #define PG8_STAGE(bufoff, gbase, voff) do { _Pragma("unroll") for (int _i = 0; _i < 2; ++_i) \
;         __builtin_amdgcn_global_load_lds((const unsigned*)((const char*)(gbase) + (voff)[_i]), (LAS unsigned*)(lds + (bufoff) + ldsw + _i * 8192), 16, 0, 0); } while (0)
; #define PG8_LDA(dst, b, h) do { _Pragma("unroll") for (int m = 0; m < 4; ++m) _Pragma("unroll") for (int k = 0; k < 2; ++k) dst[m][k] = *(const LAS bf16x8*)(lds + PG8_SA(b, h) + aoff + m * 2048 + k * 1024); } while (0)
; #define PG8_LDB(dst, b, h) do { _Pragma("unroll") for (int n = 0; n < 2; ++n) _Pragma("unroll") for (int k = 0; k < 2; ++k) dst[n][k] = *(const LAS bf16x8*)(lds + PG8_SB(b, h) + boff + n * 2048 + k * 1024); } while (0)
; #define PG8_MMA(ai, bj, At, Bt) do { __builtin_amdgcn_s_setprio(1); _Pragma("unroll") for (int m = 0; m < 4; ++m) _Pragma("unroll") for (int n = 0; n < 2; ++n) _Pragma("unroll") for (int k = 0; k < 2; ++k) \
;         acc[ai][bj][m][n] = __builtin_amdgcn_mfma_f32_16x16x32_bf16(Bt[n][k], At[m][k], acc[ai][bj][m][n], 0, 0, 0); __builtin_amdgcn_s_setprio(0); } while (0)
; #define PG8_WAIT_V(n) asm volatile("s_waitcnt vmcnt(" #n ")" ::: "memory")
; #define PG8_WAIT_L(n) asm volatile("s_waitcnt lgkmcnt(" #n ")" ::: "memory")
; #define PG8_BAR __builtin_amdgcn_s_barrier()
; #define PG8_SCHED __builtin_amdgcn_sched_barrier(0)
; template <class Epi, class Sched>
; __device__ __forceinline__ void gemm_phase(LAS unsigned char* lds, const Gemm g, const Sched& S, const Epi& E) {
;     ...
;             PG8_BAR; PG8_WAIT_L(0); PG8_MMA(0, 1, At, B1); PG8_BAR;
;             PG8_LDA(At, 0, 1); PG8_STAGE(PG8_SA(0, 0), a2, voffA);
;             PG8_BAR; PG8_WAIT_L(0); PG8_MMA(1, 0, At, B0); PG8_BAR; PG8_SCHED;
;             PG8_STAGE(PG8_SB(0, 1), b2 + hstep, voffB);
;             PG8_WAIT_V(6); PG8_BAR; PG8_MMA(1, 1, At, B1); PG8_BAR;
;             PG8_LDB(B0, 1, 0); PG8_SCHED; PG8_LDA(At, 1, 0); PG8_STAGE(PG8_SA(0, 1), a2 + hstep, voffA);
;             PG8_WAIT_L(8); PG8_BAR; PG8_WAIT_L(0); PG8_MMA(0, 0, At, B0); PG8_BAR; PG8_SCHED;
	s_waitcnt lgkmcnt(0)
	v_mfma_f32_16x16x32_bf16 v[60:63], v[144:147], v[168:171], v[60:63]
	v_mfma_f32_16x16x32_bf16 v[56:59], v[152:155], v[168:171], v[56:59]
	v_mfma_f32_16x16x32_bf16 v[48:51], v[144:147], v[176:179], v[48:51]
	v_mfma_f32_16x16x32_bf16 v[40:43], v[152:155], v[176:179], v[40:43]
	v_mfma_f32_16x16x32_bf16 v[32:35], v[144:147], v[184:187], v[32:35]
	v_mfma_f32_16x16x32_bf16 v[24:27], v[152:155], v[184:187], v[24:27]
	v_mfma_f32_16x16x32_bf16 v[16:19], v[144:147], v[192:195], v[16:19]
	v_mfma_f32_16x16x32_bf16 v[8:11], v[152:155], v[192:195], v[8:11]
	v_mfma_f32_16x16x32_bf16 v[60:63], v[148:151], v[172:175], v[60:63]
	v_mfma_f32_16x16x32_bf16 v[56:59], v[156:159], v[172:175], v[56:59]
	v_mfma_f32_16x16x32_bf16 v[48:51], v[148:151], v[180:183], v[48:51]
	v_mfma_f32_16x16x32_bf16 v[40:43], v[156:159], v[180:183], v[40:43]
	v_mfma_f32_16x16x32_bf16 v[32:35], v[148:151], v[188:191], v[32:35]
	v_mfma_f32_16x16x32_bf16 v[24:27], v[156:159], v[188:191], v[24:27]
	v_mfma_f32_16x16x32_bf16 v[16:19], v[148:151], v[196:199], v[16:19]
	v_mfma_f32_16x16x32_bf16 v[8:11], v[156:159], v[196:199], v[8:11]
	s_barrier
	s_setprio 0
	s_add_u32 s16, s34, 0xb0000
	s_addc_u32 s17, s35, 0
	s_add_i32 s20, s59, s40
	s_mov_b32 m0, s20
	s_nop 0
	global_load_lds_dwordx4 v132, s[16:17]
	s_add_i32 m0, s20, 0x2000
	s_nop 0
	global_load_lds_dwordx4 v128, s[16:17]
	s_add_u32 s16, s36, 0xb0000
	s_addc_u32 s17, s37, 0
	s_mov_b32 m0, s44
	s_nop 0
	global_load_lds_dwordx4 v134, s[16:17]
	s_mov_b32 m0, s45
	s_nop 0
	global_load_lds_dwordx4 v130, s[16:17]
	s_waitcnt vmcnt(10)
	s_setprio 1
	s_barrier
	v_mfma_f32_16x16x32_bf16 v[52:55], v[202:205], v[168:171], v[52:55]
	v_mfma_f32_16x16x32_bf16 v[44:47], v[210:213], v[168:171], v[44:47]
	v_mfma_f32_16x16x32_bf16 v[36:39], v[202:205], v[176:179], v[36:39]
	v_mfma_f32_16x16x32_bf16 v[28:31], v[210:213], v[176:179], v[28:31]
	v_mfma_f32_16x16x32_bf16 v[20:23], v[202:205], v[184:187], v[20:23]
	v_mfma_f32_16x16x32_bf16 v[12:15], v[210:213], v[184:187], v[12:15]
	v_mfma_f32_16x16x32_bf16 v[4:7], v[202:205], v[192:195], v[4:7]
	v_mfma_f32_16x16x32_bf16 v[0:3], v[210:213], v[192:195], v[0:3]
	v_mfma_f32_16x16x32_bf16 v[52:55], v[206:209], v[172:175], v[52:55]
	v_mfma_f32_16x16x32_bf16 v[44:47], v[214:217], v[172:175], v[44:47]
	v_mfma_f32_16x16x32_bf16 v[36:39], v[206:209], v[180:183], v[36:39]
	v_mfma_f32_16x16x32_bf16 v[28:31], v[214:217], v[180:183], v[28:31]
	v_mfma_f32_16x16x32_bf16 v[20:23], v[206:209], v[188:191], v[20:23]
	v_mfma_f32_16x16x32_bf16 v[12:15], v[214:217], v[188:191], v[12:15]
	v_mfma_f32_16x16x32_bf16 v[4:7], v[206:209], v[196:199], v[4:7]
	v_mfma_f32_16x16x32_bf16 v[0:3], v[214:217], v[196:199], v[0:3]
	s_barrier
	s_setprio 0
	s_add_i32 s20, 0, 0x18000
	ds_read_b128 v[144:147], v167 offset:16384
	ds_read_b128 v[148:151], v167 offset:17408
	ds_read_b128 v[152:155], v167 offset:18432
	ds_read_b128 v[156:159], v167 offset:19456
	ds_read_b128 v[168:171], v166 offset:32768
	ds_read_b128 v[172:175], v166 offset:33792
	ds_read_b128 v[176:179], v166 offset:34816
	ds_read_b128 v[180:183], v166 offset:35840
	ds_read_b128 v[184:187], v166 offset:36864
	ds_read_b128 v[188:191], v166 offset:37888
	ds_read_b128 v[192:195], v166 offset:38912
	ds_read_b128 v[196:199], v166 offset:39936
	s_waitcnt lgkmcnt(8)
	s_waitcnt vmcnt(8)
	s_setprio 1
	s_barrier
	s_waitcnt lgkmcnt(0)
	v_mfma_f32_16x16x32_bf16 v[124:127], v[144:147], v[168:171], v[124:127]
	v_mfma_f32_16x16x32_bf16 v[120:123], v[152:155], v[168:171], v[120:123]
	v_mfma_f32_16x16x32_bf16 v[116:119], v[144:147], v[176:179], v[116:119]
	v_mfma_f32_16x16x32_bf16 v[104:107], v[152:155], v[176:179], v[104:107]
	v_mfma_f32_16x16x32_bf16 v[96:99], v[144:147], v[184:187], v[96:99]
	v_mfma_f32_16x16x32_bf16 v[88:91], v[152:155], v[184:187], v[88:91]
	v_mfma_f32_16x16x32_bf16 v[80:83], v[144:147], v[192:195], v[80:83]
	v_mfma_f32_16x16x32_bf16 v[72:75], v[152:155], v[192:195], v[72:75]
	v_mfma_f32_16x16x32_bf16 v[124:127], v[148:151], v[172:175], v[124:127]
	v_mfma_f32_16x16x32_bf16 v[120:123], v[156:159], v[172:175], v[120:123]
	v_mfma_f32_16x16x32_bf16 v[116:119], v[148:151], v[180:183], v[116:119]
	v_mfma_f32_16x16x32_bf16 v[104:107], v[156:159], v[180:183], v[104:107]
	v_mfma_f32_16x16x32_bf16 v[96:99], v[148:151], v[188:191], v[96:99]
	v_mfma_f32_16x16x32_bf16 v[88:91], v[156:159], v[188:191], v[88:91]
	v_mfma_f32_16x16x32_bf16 v[80:83], v[148:151], v[196:199], v[80:83]
	v_mfma_f32_16x16x32_bf16 v[72:75], v[156:159], v[196:199], v[72:75]
	s_barrier
	s_setprio 0
	s_add_i32 s21, 0, 0x1c000
	s_add_i32 s16, s20, s40
	s_add_u32 s8, s34, 0x80
	s_addc_u32 s9, s35, 0
	s_mov_b32 m0, s16
	ds_read_b128 v[202:205], v167 offset:32768
	ds_read_b128 v[206:209], v167 offset:33792
	ds_read_b128 v[210:213], v167 offset:34816
	ds_read_b128 v[214:217], v167 offset:35840
	global_load_lds_dwordx4 v132, s[8:9]
	s_add_i32 m0, s16, 0x2000
	s_nop 0
	global_load_lds_dwordx4 v128, s[8:9]
	s_waitcnt vmcnt(8)
	s_setprio 1
	s_barrier
; #define PG8_STAGE(bufoff, gbase, voff) do { _Pragma("unroll") for (int _i = 0; _i < 2; ++_i) \
;         __builtin_amdgcn_global_load_lds((const unsigned*)((const char*)(gbase) + (voff)[_i]), (LAS unsigned*)(lds + (bufoff) + ldsw + _i * 8192), 16, 0, 0); } while (0)
; #define PG8_LDA(dst, b, h) do { _Pragma("unroll") for (int m = 0; m < 4; ++m) _Pragma("unroll") for (int k = 0; k < 2; ++k) dst[m][k] = *(const LAS bf16x8*)(lds + PG8_SA(b, h) + aoff + m * 2048 + k * 1024); } while (0)
; #define PG8_LDB(dst, b, h) do { _Pragma("unroll") for (int n = 0; n < 2; ++n) _Pragma("unroll") for (int k = 0; k < 2; ++k) dst[n][k] = *(const LAS bf16x8*)(lds + PG8_SB(b, h) + boff + n * 2048 + k * 1024); } while (0)
; #define PG8_MMA(ai, bj, At, Bt) do { __builtin_amdgcn_s_setprio(1); _Pragma("unroll") for (int m = 0; m < 4; ++m) _Pragma("unroll") for (int n = 0; n < 2; ++n) _Pragma("unroll") for (int k = 0; k < 2; ++k) \
;         acc[ai][bj][m][n] = __builtin_amdgcn_mfma_f32_16x16x32_bf16(Bt[n][k], At[m][k], acc[ai][bj][m][n], 0, 0, 0); __builtin_amdgcn_s_setprio(0); } while (0)
; #define PG8_WAIT_V(n) asm volatile("s_waitcnt vmcnt(" #n ")" ::: "memory")
; #define PG8_WAIT_L(n) asm volatile("s_waitcnt lgkmcnt(" #n ")" ::: "memory")
; #define PG8_BAR __builtin_amdgcn_s_barrier()
; template <class Epi, class Sched>
; __device__ __forceinline__ void gemm_phase(LAS unsigned char* lds, const Gemm g, const Sched& S, const Epi& E) {
;     ...
;             PG8_WAIT_L(8); PG8_BAR; PG8_WAIT_L(0); PG8_MMA(0, 0, At, B0); PG8_BAR; PG8_SCHED;
;             PG8_LDB(B1, 1, 1); PG8_STAGE(PG8_SB(1, 0), b3, voffB);
;             PG8_BAR; PG8_WAIT_L(0); PG8_MMA(0, 1, At, B1); PG8_BAR;
;             PG8_LDA(At, 1, 1); PG8_STAGE(PG8_SA(1, 0), a3, voffA);
;             PG8_BAR; PG8_WAIT_L(0); PG8_MMA(1, 0, At, B0); PG8_BAR; PG8_SCHED;
;             PG8_STAGE(PG8_SB(1, 1), b3 + hstep, voffB);
;             PG8_WAIT_V(6); PG8_BAR; PG8_MMA(1, 1, At, B1); PG8_BAR;
;         }
;         E(acc, cur, wr, wc, fr, fq);
;         if (!has_next) break;
;     __device__ __forceinline__ void operator()(const AccT& acc, const Unit& u, int wr, int wc, int fr, int fq) const {
;     ...
;         const int rowt = u.pm * 256; const bool isc = rowt >= MX; const int b = isc ? 32 : (rowt >> 11);
;         const float* res = isc ? res_c + (size_t)(rowt - MX) * DM : res_x + (size_t)rowt * DM; bf16_t* out = hb + (size_t)rowt * DM;
	s_waitcnt lgkmcnt(0)
	v_mfma_f32_16x16x32_bf16 v[112:115], v[202:205], v[168:171], v[112:115]
	v_mfma_f32_16x16x32_bf16 v[108:111], v[210:213], v[168:171], v[108:111]
	v_mfma_f32_16x16x32_bf16 v[100:103], v[202:205], v[176:179], v[100:103]
	v_mfma_f32_16x16x32_bf16 v[92:95], v[210:213], v[176:179], v[92:95]
	v_mfma_f32_16x16x32_bf16 v[84:87], v[202:205], v[184:187], v[84:87]
	v_mfma_f32_16x16x32_bf16 v[76:79], v[210:213], v[184:187], v[76:79]
	v_mfma_f32_16x16x32_bf16 v[68:71], v[202:205], v[192:195], v[68:71]
	v_mfma_f32_16x16x32_bf16 v[64:67], v[210:213], v[192:195], v[64:67]
	v_mfma_f32_16x16x32_bf16 v[112:115], v[206:209], v[172:175], v[112:115]
	v_mfma_f32_16x16x32_bf16 v[108:111], v[214:217], v[172:175], v[108:111]
	v_mfma_f32_16x16x32_bf16 v[100:103], v[206:209], v[180:183], v[100:103]
	v_mfma_f32_16x16x32_bf16 v[92:95], v[214:217], v[180:183], v[92:95]
	v_mfma_f32_16x16x32_bf16 v[84:87], v[206:209], v[188:191], v[84:87]
	v_mfma_f32_16x16x32_bf16 v[76:79], v[214:217], v[188:191], v[76:79]
	v_mfma_f32_16x16x32_bf16 v[68:71], v[206:209], v[196:199], v[68:71]
	v_mfma_f32_16x16x32_bf16 v[64:67], v[214:217], v[196:199], v[64:67]
	s_barrier
	s_setprio 0
	s_mov_b32 m0, s52
	s_add_u32 s8, s36, 0x80
	s_addc_u32 s9, s37, 0
	ds_read_b128 v[168:171], v166 offset:49152
	ds_read_b128 v[172:175], v166 offset:50176
	ds_read_b128 v[176:179], v166 offset:51200
	ds_read_b128 v[180:183], v166 offset:52224
	ds_read_b128 v[184:187], v166 offset:53248
	ds_read_b128 v[188:191], v166 offset:54272
	ds_read_b128 v[192:195], v166 offset:55296
	ds_read_b128 v[196:199], v166 offset:56320
	global_load_lds_dwordx4 v134, s[8:9]
	s_mov_b32 m0, s53
	s_nop 0
	global_load_lds_dwordx4 v130, s[8:9]
	s_setprio 1
	s_barrier
	s_waitcnt lgkmcnt(0)
	v_mfma_f32_16x16x32_bf16 v[60:63], v[144:147], v[168:171], v[60:63]
	v_mfma_f32_16x16x32_bf16 v[56:59], v[152:155], v[168:171], v[56:59]
	v_mfma_f32_16x16x32_bf16 v[48:51], v[144:147], v[176:179], v[48:51]
	v_mfma_f32_16x16x32_bf16 v[40:43], v[152:155], v[176:179], v[40:43]
	v_mfma_f32_16x16x32_bf16 v[32:35], v[144:147], v[184:187], v[32:35]
	v_mfma_f32_16x16x32_bf16 v[24:27], v[152:155], v[184:187], v[24:27]
	v_mfma_f32_16x16x32_bf16 v[16:19], v[144:147], v[192:195], v[16:19]
	v_mfma_f32_16x16x32_bf16 v[8:11], v[152:155], v[192:195], v[8:11]
	v_mfma_f32_16x16x32_bf16 v[60:63], v[148:151], v[172:175], v[60:63]
	v_mfma_f32_16x16x32_bf16 v[56:59], v[156:159], v[172:175], v[56:59]
	v_mfma_f32_16x16x32_bf16 v[48:51], v[148:151], v[180:183], v[48:51]
	v_mfma_f32_16x16x32_bf16 v[40:43], v[156:159], v[180:183], v[40:43]
	v_mfma_f32_16x16x32_bf16 v[32:35], v[148:151], v[188:191], v[32:35]
	v_mfma_f32_16x16x32_bf16 v[24:27], v[156:159], v[188:191], v[24:27]
	v_mfma_f32_16x16x32_bf16 v[16:19], v[148:151], v[196:199], v[16:19]
	v_mfma_f32_16x16x32_bf16 v[8:11], v[156:159], v[196:199], v[8:11]
	s_barrier
	s_setprio 0
	s_add_u32 s16, s34, 0xb0080
	s_addc_u32 s17, s35, 0
	s_add_i32 s20, s21, s40
	s_mov_b32 m0, s20
	s_nop 0
	global_load_lds_dwordx4 v132, s[16:17]
	s_add_i32 m0, s20, 0x2000
	s_nop 0
	global_load_lds_dwordx4 v128, s[16:17]
	s_waitcnt vmcnt(8)
	s_setprio 1
	s_barrier
	v_mfma_f32_16x16x32_bf16 v[52:55], v[202:205], v[168:171], v[52:55]
	v_mfma_f32_16x16x32_bf16 v[44:47], v[210:213], v[168:171], v[44:47]
	v_mfma_f32_16x16x32_bf16 v[36:39], v[202:205], v[176:179], v[36:39]
	v_mfma_f32_16x16x32_bf16 v[28:31], v[210:213], v[176:179], v[28:31]
	v_mfma_f32_16x16x32_bf16 v[20:23], v[202:205], v[184:187], v[20:23]
	v_mfma_f32_16x16x32_bf16 v[12:15], v[210:213], v[184:187], v[12:15]
	v_mfma_f32_16x16x32_bf16 v[4:7], v[202:205], v[192:195], v[4:7]
	v_mfma_f32_16x16x32_bf16 v[0:3], v[210:213], v[192:195], v[0:3]
	v_mfma_f32_16x16x32_bf16 v[52:55], v[206:209], v[172:175], v[52:55]
	v_mfma_f32_16x16x32_bf16 v[44:47], v[214:217], v[172:175], v[44:47]
	v_mfma_f32_16x16x32_bf16 v[36:39], v[206:209], v[180:183], v[36:39]
	v_mfma_f32_16x16x32_bf16 v[28:31], v[214:217], v[180:183], v[28:31]
	v_mfma_f32_16x16x32_bf16 v[20:23], v[206:209], v[188:191], v[20:23]
	v_mfma_f32_16x16x32_bf16 v[12:15], v[214:217], v[188:191], v[12:15]
	v_mfma_f32_16x16x32_bf16 v[4:7], v[206:209], v[196:199], v[4:7]
	v_mfma_f32_16x16x32_bf16 v[0:3], v[214:217], v[196:199], v[0:3]
	s_barrier
	s_setprio 0
	s_add_i32 s68, s68, 2
	s_add_u32 s0, s0, 0x100
	s_addc_u32 s67, s67, 0
	s_cmp_gt_u32 s68, 41
	s_mov_b64 s[26:27], s[28:29]
	s_cbranch_scc0 .LBB0_305
	s_lshl_b32 s0, s66, 8
	v_mov_b32_e32 v145, v163
	v_mov_b32_e32 v144, v162
	s_cmpk_lt_i32 s66, 0x100
	s_cbranch_scc0 .LBB0_308
	s_ashr_i32 s29, s0, 31
	s_mov_b32 s28, s0
	s_lshl_b64 s[16:17], s[28:29], 12
	v_readlane_b32 s80, v254, 23
	v_readlane_b32 s81, v254, 24
	s_add_u32 s26, s80, s16
	v_readlane_b32 s82, v254, 25
	v_readlane_b32 s83, v254, 26
	v_readlane_b32 s84, v254, 27
	v_readlane_b32 s85, v254, 28
	v_readlane_b32 s86, v254, 29
	v_readlane_b32 s87, v254, 30
	v_readlane_b32 s88, v254, 31
	v_readlane_b32 s89, v254, 32
	v_readlane_b32 s90, v254, 33
	v_readlane_b32 s91, v254, 34
	v_readlane_b32 s92, v254, 35
	v_readlane_b32 s93, v254, 36
	v_readlane_b32 s94, v254, 37
	v_readlane_b32 s95, v254, 38
	s_addc_u32 s27, s81, s17
	s_cbranch_execnz .LBB0_297
	s_branch .LBB0_296

; #define PG8_STAGE(bufoff, gbase, voff) do { _Pragma("unroll") for (int _i = 0; _i < 2; ++_i) \
;         __builtin_amdgcn_global_load_lds((const unsigned*)((const char*)(gbase) + (voff)[_i]), (LAS unsigned*)(lds + (bufoff) + ldsw + _i * 8192), 16, 0, 0); } while (0)
; #define PG8_LDA(dst, b, h) do { _Pragma("unroll") for (int m = 0; m < 4; ++m) _Pragma("unroll") for (int k = 0; k < 2; ++k) dst[m][k] = *(const LAS bf16x8*)(lds + PG8_SA(b, h) + aoff + m * 2048 + k * 1024); } while (0)
; #define PG8_LDB(dst, b, h) do { _Pragma("unroll") for (int n = 0; n < 2; ++n) _Pragma("unroll") for (int k = 0; k < 2; ++k) dst[n][k] = *(const LAS bf16x8*)(lds + PG8_SB(b, h) + boff + n * 2048 + k * 1024); } while (0)
; #define PG8_MMA(ai, bj, At, Bt) do { __builtin_amdgcn_s_setprio(1); _Pragma("unroll") for (int m = 0; m < 4; ++m) _Pragma("unroll") for (int n = 0; n < 2; ++n) _Pragma("unroll") for (int k = 0; k < 2; ++k) \
;         acc[ai][bj][m][n] = __builtin_amdgcn_mfma_f32_16x16x32_bf16(Bt[n][k], At[m][k], acc[ai][bj][m][n], 0, 0, 0); __builtin_amdgcn_s_setprio(0); } while (0)
; #define PG8_WAIT_L(n) asm volatile("s_waitcnt lgkmcnt(" #n ")" ::: "memory")
; #define PG8_BAR __builtin_amdgcn_s_barrier()
; template <class Epi, class Sched>
; __device__ __forceinline__ void gemm_phase(LAS unsigned char* lds, const Gemm g, const Sched& S, const Epi& E) {
;     ...
;         const char* nA = has_next ? (const char*)g.A + (size_t)nxt.pm * tstep : cA; const char* nB = has_next ? (const char*)g.Bt + (size_t)nxt.pn * tstep : cB;
;         for (int t = 0; t < nt; t += 2) {
;             const bool last = (t == nt - 2);
;             const char* a1 = cA + (size_t)(t + 1) * kstep;
;             const char* a2 = last ? nA : cA + (size_t)(t + 2) * kstep; const char* b2 = last ? nB : cB + (size_t)(t + 2) * kstep;
;             const char* a3 = a2 + kstep; const char* b3 = b2 + kstep;
;             PG8_LDB(B0, 0, 0); PG8_SCHED; PG8_LDA(At, 0, 0); PG8_STAGE(PG8_SA(1, 1), a1 + hstep, voffA);
;             PG8_WAIT_L(8); PG8_BAR; PG8_WAIT_L(0); PG8_MMA(0, 0, At, B0); PG8_BAR; PG8_SCHED;
;             PG8_LDB(B1, 0, 1); PG8_STAGE(PG8_SB(0, 0), b2, voffB);
;             PG8_BAR; PG8_WAIT_L(0); PG8_MMA(0, 1, At, B1); PG8_BAR;
;             PG8_LDA(At, 0, 1); PG8_STAGE(PG8_SA(0, 0), a2, voffA);
;             PG8_BAR; PG8_WAIT_L(0); PG8_MMA(1, 0, At, B0); PG8_BAR; PG8_SCHED;
.LBB0_577:
	s_ashr_i32 s21, s20, 31
	v_cmp_lt_i64_e32 vcc, s[22:23], v[156:157]
	s_lshl_b64 s[22:23], s[20:21], 19
	s_add_u32 s22, s96, s22
	s_addc_u32 s23, s97, s23
	s_and_b64 s[24:25], vcc, exec
	s_cselect_b32 s5, s23, s7
	s_cselect_b32 s21, s22, s6
	s_ashr_i32 s19, s18, 31
	s_lshl_b64 s[24:25], s[18:19], 19
	s_add_u32 s24, s31, s24
	s_addc_u32 s25, s33, s25
	s_and_b64 s[28:29], vcc, exec
	s_cselect_b32 s19, s25, s27
	s_cselect_b32 s53, s24, s26
	s_add_u32 s6, s6, 0x40080
	s_addc_u32 s7, s7, 0
	s_add_u32 s54, s26, 0x100
	s_addc_u32 s55, s27, 0
	s_mov_b32 s56, -2
	s_waitcnt lgkmcnt(0)
	ds_read_b128 v[128:131], v167
	ds_read_b128 v[132:135], v167 offset:1024
	ds_read_b128 v[136:139], v167 offset:2048
	ds_read_b128 v[160:163], v167 offset:3072
	s_add_u32 s26, s6, 0xfffc0080
	s_addc_u32 s27, s7, -1
	s_cmp_eq_u32 s56, 12
	s_cselect_b32 s29, s5, s27
	s_cselect_b32 s28, s21, s26
	s_cselect_b32 s27, s19, s55
	s_cselect_b32 s26, s53, s54
	s_add_i32 m0, s37, 0xc000
	ds_read_b128 v[170:173], v168
	ds_read_b128 v[174:177], v168 offset:1024
	ds_read_b128 v[178:181], v168 offset:2048
	ds_read_b128 v[182:185], v168 offset:3072
	ds_read_b128 v[186:189], v168 offset:4096
	ds_read_b128 v[190:193], v168 offset:5120
	ds_read_b128 v[194:197], v168 offset:6144
	ds_read_b128 v[202:205], v168 offset:7168
	global_load_lds_dwordx4 v152, s[6:7]
	s_add_i32 m0, s37, 0xe000
	s_nop 0
	global_load_lds_dwordx4 v154, s[6:7]
	s_waitcnt lgkmcnt(8)
	s_waitcnt vmcnt(8)
	s_setprio 1
	s_barrier
	s_waitcnt lgkmcnt(0)
	v_mfma_f32_16x16x32_bf16 v[124:127], v[128:131], v[170:173], 0
	v_mfma_f32_16x16x32_bf16 v[120:123], v[136:139], v[170:173], 0
	v_mfma_f32_16x16x32_bf16 v[108:111], v[128:131], v[178:181], 0
	v_mfma_f32_16x16x32_bf16 v[104:107], v[136:139], v[178:181], 0
	v_mfma_f32_16x16x32_bf16 v[92:95], v[128:131], v[186:189], 0
	v_mfma_f32_16x16x32_bf16 v[88:91], v[136:139], v[186:189], 0
	v_mfma_f32_16x16x32_bf16 v[76:79], v[128:131], v[194:197], 0
	v_mfma_f32_16x16x32_bf16 v[72:75], v[136:139], v[194:197], 0
	v_mfma_f32_16x16x32_bf16 v[124:127], v[132:135], v[174:177], v[124:127]
	v_mfma_f32_16x16x32_bf16 v[120:123], v[160:163], v[174:177], v[120:123]
	v_mfma_f32_16x16x32_bf16 v[108:111], v[132:135], v[182:185], v[108:111]
	v_mfma_f32_16x16x32_bf16 v[104:107], v[160:163], v[182:185], v[104:107]
	v_mfma_f32_16x16x32_bf16 v[92:95], v[132:135], v[190:193], v[92:95]
	v_mfma_f32_16x16x32_bf16 v[88:91], v[160:163], v[190:193], v[88:91]
	v_mfma_f32_16x16x32_bf16 v[76:79], v[132:135], v[202:205], v[76:79]
	v_mfma_f32_16x16x32_bf16 v[72:75], v[160:163], v[202:205], v[72:75]
	s_barrier
	s_setprio 0
	s_add_i32 s57, s48, s34
	s_mov_b32 m0, s57
	ds_read_b128 v[206:209], v169
	ds_read_b128 v[210:213], v169 offset:1024
	ds_read_b128 v[214:217], v169 offset:2048
	ds_read_b128 v[218:221], v169 offset:3072
	global_load_lds_dwordx4 v146, s[26:27]
	s_add_i32 m0, s57, 0x2000
	s_nop 0
	global_load_lds_dwordx4 v142, s[26:27]
	s_waitcnt vmcnt(8)
	s_setprio 1
	s_barrier
	s_waitcnt lgkmcnt(0)
	v_mfma_f32_16x16x32_bf16 v[116:119], v[206:209], v[170:173], 0
	v_mfma_f32_16x16x32_bf16 v[112:115], v[214:217], v[170:173], 0
	v_mfma_f32_16x16x32_bf16 v[100:103], v[206:209], v[178:181], 0
	v_mfma_f32_16x16x32_bf16 v[96:99], v[214:217], v[178:181], 0
	v_mfma_f32_16x16x32_bf16 v[84:87], v[206:209], v[186:189], 0
	v_mfma_f32_16x16x32_bf16 v[80:83], v[214:217], v[186:189], 0
	v_mfma_f32_16x16x32_bf16 v[68:71], v[206:209], v[194:197], 0
	v_mfma_f32_16x16x32_bf16 v[64:67], v[214:217], v[194:197], 0
	v_mfma_f32_16x16x32_bf16 v[116:119], v[210:213], v[174:177], v[116:119]
	v_mfma_f32_16x16x32_bf16 v[112:115], v[218:221], v[174:177], v[112:115]
	v_mfma_f32_16x16x32_bf16 v[100:103], v[210:213], v[182:185], v[100:103]
	v_mfma_f32_16x16x32_bf16 v[96:99], v[218:221], v[182:185], v[96:99]
	v_mfma_f32_16x16x32_bf16 v[84:87], v[210:213], v[190:193], v[84:87]
	v_mfma_f32_16x16x32_bf16 v[80:83], v[218:221], v[190:193], v[80:83]
	v_mfma_f32_16x16x32_bf16 v[68:71], v[210:213], v[202:205], v[68:71]
	v_mfma_f32_16x16x32_bf16 v[64:67], v[218:221], v[202:205], v[64:67]
	s_barrier
	s_setprio 0
	s_mov_b32 m0, s37
	v_lshl_add_u64 v[222:223], s[28:29], 0, v[148:149]
	ds_read_b128 v[170:173], v168 offset:16384
	ds_read_b128 v[174:177], v168 offset:17408
	ds_read_b128 v[178:181], v168 offset:18432
	ds_read_b128 v[182:185], v168 offset:19456
	ds_read_b128 v[186:189], v168 offset:20480
	ds_read_b128 v[190:193], v168 offset:21504
	ds_read_b128 v[194:197], v168 offset:22528
	ds_read_b128 v[202:205], v168 offset:23552
	global_load_lds_dwordx4 v148, s[28:29]
	v_lshl_add_u64 v[224:225], s[28:29], 0, v[144:145]
	s_mov_b32 m0, s38
	s_nop 0
	global_load_lds_dwordx4 v144, s[28:29]
	s_setprio 1
	s_barrier
	s_waitcnt lgkmcnt(0)
	v_mfma_f32_16x16x32_bf16 v[60:63], v[128:131], v[170:173], 0
	v_mfma_f32_16x16x32_bf16 v[56:59], v[136:139], v[170:173], 0
	v_mfma_f32_16x16x32_bf16 v[44:47], v[128:131], v[178:181], 0
	v_mfma_f32_16x16x32_bf16 v[40:43], v[136:139], v[178:181], 0
	v_mfma_f32_16x16x32_bf16 v[28:31], v[128:131], v[186:189], 0
	v_mfma_f32_16x16x32_bf16 v[24:27], v[136:139], v[186:189], 0
	v_mfma_f32_16x16x32_bf16 v[12:15], v[128:131], v[194:197], 0
	v_mfma_f32_16x16x32_bf16 v[8:11], v[136:139], v[194:197], 0
	v_mfma_f32_16x16x32_bf16 v[60:63], v[132:135], v[174:177], v[60:63]
	v_mfma_f32_16x16x32_bf16 v[56:59], v[160:163], v[174:177], v[56:59]
	v_mfma_f32_16x16x32_bf16 v[44:47], v[132:135], v[182:185], v[44:47]
	v_mfma_f32_16x16x32_bf16 v[40:43], v[160:163], v[182:185], v[40:43]
	v_mfma_f32_16x16x32_bf16 v[28:31], v[132:135], v[190:193], v[28:31]
	v_mfma_f32_16x16x32_bf16 v[24:27], v[160:163], v[190:193], v[24:27]
	v_mfma_f32_16x16x32_bf16 v[12:15], v[132:135], v[202:205], v[12:15]
	v_mfma_f32_16x16x32_bf16 v[8:11], v[160:163], v[202:205], v[8:11]
	s_barrier
; #define PG8_STAGE(bufoff, gbase, voff) do { _Pragma("unroll") for (int _i = 0; _i < 2; ++_i) \
;         __builtin_amdgcn_global_load_lds((const unsigned*)((const char*)(gbase) + (voff)[_i]), (LAS unsigned*)(lds + (bufoff) + ldsw + _i * 8192), 16, 0, 0); } while (0)
; #define PG8_LDA(dst, b, h) do { _Pragma("unroll") for (int m = 0; m < 4; ++m) _Pragma("unroll") for (int k = 0; k < 2; ++k) dst[m][k] = *(const LAS bf16x8*)(lds + PG8_SA(b, h) + aoff + m * 2048 + k * 1024); } while (0)
; #define PG8_LDB(dst, b, h) do { _Pragma("unroll") for (int n = 0; n < 2; ++n) _Pragma("unroll") for (int k = 0; k < 2; ++k) dst[n][k] = *(const LAS bf16x8*)(lds + PG8_SB(b, h) + boff + n * 2048 + k * 1024); } while (0)
; #define PG8_MMA(ai, bj, At, Bt) do { __builtin_amdgcn_s_setprio(1); _Pragma("unroll") for (int m = 0; m < 4; ++m) _Pragma("unroll") for (int n = 0; n < 2; ++n) _Pragma("unroll") for (int k = 0; k < 2; ++k) \
;         acc[ai][bj][m][n] = __builtin_amdgcn_mfma_f32_16x16x32_bf16(Bt[n][k], At[m][k], acc[ai][bj][m][n], 0, 0, 0); __builtin_amdgcn_s_setprio(0); } while (0)
; #define PG8_WAIT_V(n) asm volatile("s_waitcnt vmcnt(" #n ")" ::: "memory")
; #define PG8_WAIT_L(n) asm volatile("s_waitcnt lgkmcnt(" #n ")" ::: "memory")
; #define PG8_BAR __builtin_amdgcn_s_barrier()
; #define PG8_SCHED __builtin_amdgcn_sched_barrier(0)
; template <class Epi, class Sched>
; __device__ __forceinline__ void gemm_phase(LAS unsigned char* lds, const Gemm g, const Sched& S, const Epi& E) {
;     ...
;             PG8_STAGE(PG8_SB(0, 1), b2 + hstep, voffB);
;             PG8_WAIT_V(6); PG8_BAR; PG8_MMA(1, 1, At, B1); PG8_BAR;
;             PG8_LDB(B0, 1, 0); PG8_SCHED; PG8_LDA(At, 1, 0); PG8_STAGE(PG8_SA(0, 1), a2 + hstep, voffA);
;             PG8_WAIT_L(8); PG8_BAR; PG8_WAIT_L(0); PG8_MMA(0, 0, At, B0); PG8_BAR; PG8_SCHED;
;             PG8_LDB(B1, 1, 1); PG8_STAGE(PG8_SB(1, 0), b3, voffB);
;             PG8_BAR; PG8_WAIT_L(0); PG8_MMA(0, 1, At, B1); PG8_BAR;
;             PG8_LDA(At, 1, 1); PG8_STAGE(PG8_SA(1, 0), a3, voffA);
	s_setprio 0
	s_add_u32 s58, s26, 0x40000
	s_addc_u32 s59, s27, 0
	s_add_i32 s57, s49, s34
	s_mov_b32 m0, s57
	s_nop 0
	global_load_lds_dwordx4 v146, s[58:59]
	s_add_i32 m0, s57, 0x2000
	s_nop 0
	global_load_lds_dwordx4 v142, s[58:59]
	s_add_u32 s28, s28, 0x40000
	s_addc_u32 s29, s29, 0
	s_mov_b32 m0, s39
	s_nop 0
	global_load_lds_dwordx4 v148, s[28:29]
	s_mov_b32 m0, s40
	s_nop 0
	global_load_lds_dwordx4 v144, s[28:29]
	s_waitcnt vmcnt(10)
	s_setprio 1
	s_barrier
	v_mfma_f32_16x16x32_bf16 v[52:55], v[206:209], v[170:173], 0
	v_mfma_f32_16x16x32_bf16 v[48:51], v[214:217], v[170:173], 0
	v_mfma_f32_16x16x32_bf16 v[36:39], v[206:209], v[178:181], 0
	v_mfma_f32_16x16x32_bf16 v[32:35], v[214:217], v[178:181], 0
	v_mfma_f32_16x16x32_bf16 v[20:23], v[206:209], v[186:189], 0
	v_mfma_f32_16x16x32_bf16 v[16:19], v[214:217], v[186:189], 0
	v_mfma_f32_16x16x32_bf16 v[4:7], v[206:209], v[194:197], 0
	v_mfma_f32_16x16x32_bf16 v[0:3], v[214:217], v[194:197], 0
	v_mfma_f32_16x16x32_bf16 v[52:55], v[210:213], v[174:177], v[52:55]
	v_mfma_f32_16x16x32_bf16 v[48:51], v[218:221], v[174:177], v[48:51]
	v_mfma_f32_16x16x32_bf16 v[36:39], v[210:213], v[182:185], v[36:39]
	v_mfma_f32_16x16x32_bf16 v[32:35], v[218:221], v[182:185], v[32:35]
	v_mfma_f32_16x16x32_bf16 v[20:23], v[210:213], v[190:193], v[20:23]
	v_mfma_f32_16x16x32_bf16 v[16:19], v[218:221], v[190:193], v[16:19]
	v_mfma_f32_16x16x32_bf16 v[4:7], v[210:213], v[202:205], v[4:7]
	v_mfma_f32_16x16x32_bf16 v[0:3], v[218:221], v[202:205], v[0:3]
	s_barrier
	s_setprio 0
	s_add_i32 s57, 0, 0x18000
	ds_read_b128 v[128:131], v169 offset:16384
	ds_read_b128 v[132:135], v169 offset:17408
	ds_read_b128 v[136:139], v169 offset:18432
	ds_read_b128 v[160:163], v169 offset:19456
	ds_read_b128 v[170:173], v168 offset:32768
	ds_read_b128 v[174:177], v168 offset:33792
	ds_read_b128 v[178:181], v168 offset:34816
	ds_read_b128 v[182:185], v168 offset:35840
	ds_read_b128 v[186:189], v168 offset:36864
	ds_read_b128 v[190:193], v168 offset:37888
	ds_read_b128 v[194:197], v168 offset:38912
	ds_read_b128 v[202:205], v168 offset:39936
	s_waitcnt lgkmcnt(8)
	s_waitcnt vmcnt(8)
	s_setprio 1
	s_barrier
	s_waitcnt lgkmcnt(0)
	v_mfma_f32_16x16x32_bf16 v[124:127], v[128:131], v[170:173], v[124:127]
	v_mfma_f32_16x16x32_bf16 v[120:123], v[136:139], v[170:173], v[120:123]
	v_mfma_f32_16x16x32_bf16 v[108:111], v[128:131], v[178:181], v[108:111]
	v_mfma_f32_16x16x32_bf16 v[104:107], v[136:139], v[178:181], v[104:107]
	v_mfma_f32_16x16x32_bf16 v[92:95], v[128:131], v[186:189], v[92:95]
	v_mfma_f32_16x16x32_bf16 v[88:91], v[136:139], v[186:189], v[88:91]
	v_mfma_f32_16x16x32_bf16 v[76:79], v[128:131], v[194:197], v[76:79]
	v_mfma_f32_16x16x32_bf16 v[72:75], v[136:139], v[194:197], v[72:75]
	v_mfma_f32_16x16x32_bf16 v[124:127], v[132:135], v[174:177], v[124:127]
	v_mfma_f32_16x16x32_bf16 v[120:123], v[160:163], v[174:177], v[120:123]
	v_mfma_f32_16x16x32_bf16 v[108:111], v[132:135], v[182:185], v[108:111]
	v_mfma_f32_16x16x32_bf16 v[104:107], v[160:163], v[182:185], v[104:107]
	v_mfma_f32_16x16x32_bf16 v[92:95], v[132:135], v[190:193], v[92:95]
	v_mfma_f32_16x16x32_bf16 v[88:91], v[160:163], v[190:193], v[88:91]
	v_mfma_f32_16x16x32_bf16 v[76:79], v[132:135], v[202:205], v[76:79]
	v_mfma_f32_16x16x32_bf16 v[72:75], v[160:163], v[202:205], v[72:75]
	s_barrier
	s_setprio 0
	s_add_i32 s28, 0, 0x1c000
	s_add_i32 s29, s57, s34
	s_add_u32 s0, s26, 0x80
	s_addc_u32 s1, s27, 0
	s_mov_b32 m0, s29
	ds_read_b128 v[206:209], v169 offset:32768
	ds_read_b128 v[210:213], v169 offset:33792
	ds_read_b128 v[214:217], v169 offset:34816
	ds_read_b128 v[218:221], v169 offset:35840
	global_load_lds_dwordx4 v146, s[0:1]
	s_add_i32 m0, s29, 0x2000
	s_nop 0
	global_load_lds_dwordx4 v142, s[0:1]
	s_waitcnt vmcnt(8)
	s_setprio 1
	s_barrier
	s_waitcnt lgkmcnt(0)
	v_mfma_f32_16x16x32_bf16 v[116:119], v[206:209], v[170:173], v[116:119]
	v_mfma_f32_16x16x32_bf16 v[112:115], v[214:217], v[170:173], v[112:115]
	v_mfma_f32_16x16x32_bf16 v[100:103], v[206:209], v[178:181], v[100:103]
	v_mfma_f32_16x16x32_bf16 v[96:99], v[214:217], v[178:181], v[96:99]
	v_mfma_f32_16x16x32_bf16 v[84:87], v[206:209], v[186:189], v[84:87]
	v_mfma_f32_16x16x32_bf16 v[80:83], v[214:217], v[186:189], v[80:83]
	v_mfma_f32_16x16x32_bf16 v[68:71], v[206:209], v[194:197], v[68:71]
	v_mfma_f32_16x16x32_bf16 v[64:67], v[214:217], v[194:197], v[64:67]
	v_mfma_f32_16x16x32_bf16 v[116:119], v[210:213], v[174:177], v[116:119]
	v_mfma_f32_16x16x32_bf16 v[112:115], v[218:221], v[174:177], v[112:115]
	v_mfma_f32_16x16x32_bf16 v[100:103], v[210:213], v[182:185], v[100:103]
	v_mfma_f32_16x16x32_bf16 v[96:99], v[218:221], v[182:185], v[96:99]
	v_mfma_f32_16x16x32_bf16 v[84:87], v[210:213], v[190:193], v[84:87]
	v_mfma_f32_16x16x32_bf16 v[80:83], v[218:221], v[190:193], v[80:83]
	v_mfma_f32_16x16x32_bf16 v[68:71], v[210:213], v[202:205], v[68:71]
	v_mfma_f32_16x16x32_bf16 v[64:67], v[218:221], v[202:205], v[64:67]
	s_barrier
	s_setprio 0
	s_mov_b32 m0, s44
	s_mov_b64 s[0:1], 0x80
	v_lshl_add_u64 v[140:141], v[222:223], 0, s[0:1]
	ds_read_b128 v[170:173], v168 offset:49152
	ds_read_b128 v[174:177], v168 offset:50176
	ds_read_b128 v[178:181], v168 offset:51200
	ds_read_b128 v[182:185], v168 offset:52224
	ds_read_b128 v[186:189], v168 offset:53248
	ds_read_b128 v[190:193], v168 offset:54272
	ds_read_b128 v[194:197], v168 offset:55296
	ds_read_b128 v[202:205], v168 offset:56320
	global_load_lds_dwordx4 v[140:141], off
	v_lshl_add_u64 v[140:141], v[224:225], 0, s[0:1]
	s_mov_b32 m0, s45
	s_nop 0
	global_load_lds_dwordx4 v[140:141], off
	s_setprio 1
	s_barrier
; #define PG8_STAGE(bufoff, gbase, voff) do { _Pragma("unroll") for (int _i = 0; _i < 2; ++_i) \
;         __builtin_amdgcn_global_load_lds((const unsigned*)((const char*)(gbase) + (voff)[_i]), (LAS unsigned*)(lds + (bufoff) + ldsw + _i * 8192), 16, 0, 0); } while (0)
; #define PG8_LDA(dst, b, h) do { _Pragma("unroll") for (int m = 0; m < 4; ++m) _Pragma("unroll") for (int k = 0; k < 2; ++k) dst[m][k] = *(const LAS bf16x8*)(lds + PG8_SA(b, h) + aoff + m * 2048 + k * 1024); } while (0)
; #define PG8_LDB(dst, b, h) do { _Pragma("unroll") for (int n = 0; n < 2; ++n) _Pragma("unroll") for (int k = 0; k < 2; ++k) dst[n][k] = *(const LAS bf16x8*)(lds + PG8_SB(b, h) + boff + n * 2048 + k * 1024); } while (0)
; #define PG8_WAIT_V(n) asm volatile("s_waitcnt vmcnt(" #n ")" ::: "memory")
; #define PG8_WAIT_L(n) asm volatile("s_waitcnt lgkmcnt(" #n ")" ::: "memory")
; #define PG8_BAR __builtin_amdgcn_s_barrier()
; #define PG8_SCHED __builtin_amdgcn_sched_barrier(0)
; template <class Epi, class Sched>
; __device__ __forceinline__ void gemm_phase(LAS unsigned char* lds, const Gemm g, const Sched& S, const Epi& E) {
;     ...
;             PG8_LDB(B0, 0, 0); PG8_SCHED; PG8_LDA(At, 0, 0); PG8_STAGE(PG8_SA(1, 1), a1 + hstep, voffA);
;             PG8_WAIT_L(8); PG8_BAR; PG8_WAIT_L(0); PG8_MMA(0, 0, At, B0); PG8_BAR; PG8_SCHED;
;             PG8_LDB(B1, 0, 1); PG8_STAGE(PG8_SB(0, 0), b2, voffB);
;             PG8_BAR; PG8_WAIT_L(0); PG8_MMA(0, 1, At, B1); PG8_BAR;
;             PG8_LDA(At, 0, 1); PG8_STAGE(PG8_SA(0, 0), a2, voffA);
;             PG8_BAR; PG8_WAIT_L(0); PG8_MMA(1, 0, At, B0); PG8_BAR; PG8_SCHED;
;             PG8_STAGE(PG8_SB(0, 1), b2 + hstep, voffB);
;             PG8_WAIT_V(6); PG8_BAR; PG8_MMA(1, 1, At, B1); PG8_BAR;
;             PG8_LDB(B0, 1, 0); PG8_SCHED; PG8_LDA(At, 1, 0); PG8_STAGE(PG8_SA(0, 1), a2 + hstep, voffA);
;             PG8_WAIT_L(8); PG8_BAR; PG8_WAIT_L(0); PG8_MMA(0, 0, At, B0); PG8_BAR; PG8_SCHED;
;             PG8_LDB(B1, 1, 1); PG8_STAGE(PG8_SB(1, 0), b3, voffB);
;             PG8_BAR; PG8_WAIT_L(0); PG8_MMA(0, 1, At, B1); PG8_BAR;
;             PG8_LDA(At, 1, 1); PG8_STAGE(PG8_SA(1, 0), a3, voffA);
;             PG8_BAR; PG8_WAIT_L(0); PG8_MMA(1, 0, At, B0); PG8_BAR; PG8_SCHED;
;             PG8_STAGE(PG8_SB(1, 1), b3 + hstep, voffB);
;             PG8_WAIT_V(6); PG8_BAR; PG8_MMA(1, 1, At, B1); PG8_BAR;
	s_waitcnt lgkmcnt(0)
	v_mfma_f32_16x16x32_bf16 v[60:63], v[128:131], v[170:173], v[60:63]
	v_mfma_f32_16x16x32_bf16 v[56:59], v[136:139], v[170:173], v[56:59]
	v_mfma_f32_16x16x32_bf16 v[44:47], v[128:131], v[178:181], v[44:47]
	v_mfma_f32_16x16x32_bf16 v[40:43], v[136:139], v[178:181], v[40:43]
	v_mfma_f32_16x16x32_bf16 v[28:31], v[128:131], v[186:189], v[28:31]
	v_mfma_f32_16x16x32_bf16 v[24:27], v[136:139], v[186:189], v[24:27]
	v_mfma_f32_16x16x32_bf16 v[12:15], v[128:131], v[194:197], v[12:15]
	v_mfma_f32_16x16x32_bf16 v[8:11], v[136:139], v[194:197], v[8:11]
	v_mfma_f32_16x16x32_bf16 v[60:63], v[132:135], v[174:177], v[60:63]
	v_mfma_f32_16x16x32_bf16 v[56:59], v[160:163], v[174:177], v[56:59]
	v_mfma_f32_16x16x32_bf16 v[44:47], v[132:135], v[182:185], v[44:47]
	v_mfma_f32_16x16x32_bf16 v[40:43], v[160:163], v[182:185], v[40:43]
	v_mfma_f32_16x16x32_bf16 v[28:31], v[132:135], v[190:193], v[28:31]
	v_mfma_f32_16x16x32_bf16 v[24:27], v[160:163], v[190:193], v[24:27]
	v_mfma_f32_16x16x32_bf16 v[12:15], v[132:135], v[202:205], v[12:15]
	v_mfma_f32_16x16x32_bf16 v[8:11], v[160:163], v[202:205], v[8:11]
	s_barrier
	s_setprio 0
	s_add_u32 s26, s26, 0x40080
	s_addc_u32 s27, s27, 0
	s_add_i32 s28, s28, s34
	s_mov_b32 m0, s28
	s_nop 0
	global_load_lds_dwordx4 v146, s[26:27]
	s_add_i32 m0, s28, 0x2000
	s_nop 0
	global_load_lds_dwordx4 v142, s[26:27]
	s_waitcnt vmcnt(8)
	s_setprio 1
	s_barrier
	v_mfma_f32_16x16x32_bf16 v[52:55], v[206:209], v[170:173], v[52:55]
	v_mfma_f32_16x16x32_bf16 v[48:51], v[214:217], v[170:173], v[48:51]
	v_mfma_f32_16x16x32_bf16 v[36:39], v[206:209], v[178:181], v[36:39]
	v_mfma_f32_16x16x32_bf16 v[32:35], v[214:217], v[178:181], v[32:35]
	v_mfma_f32_16x16x32_bf16 v[20:23], v[206:209], v[186:189], v[20:23]
	v_mfma_f32_16x16x32_bf16 v[16:19], v[214:217], v[186:189], v[16:19]
	v_mfma_f32_16x16x32_bf16 v[4:7], v[206:209], v[194:197], v[4:7]
	v_mfma_f32_16x16x32_bf16 v[0:3], v[214:217], v[194:197], v[0:3]
	v_mfma_f32_16x16x32_bf16 v[52:55], v[210:213], v[174:177], v[52:55]
	v_mfma_f32_16x16x32_bf16 v[48:51], v[218:221], v[174:177], v[48:51]
	v_mfma_f32_16x16x32_bf16 v[36:39], v[210:213], v[182:185], v[36:39]
	v_mfma_f32_16x16x32_bf16 v[32:35], v[218:221], v[182:185], v[32:35]
	v_mfma_f32_16x16x32_bf16 v[20:23], v[210:213], v[190:193], v[20:23]
	v_mfma_f32_16x16x32_bf16 v[16:19], v[218:221], v[190:193], v[16:19]
	v_mfma_f32_16x16x32_bf16 v[4:7], v[210:213], v[202:205], v[4:7]
	v_mfma_f32_16x16x32_bf16 v[0:3], v[218:221], v[202:205], v[0:3]
	s_barrier
	s_setprio 0
	s_add_i32 s56, s56, 2
	s_add_u32 s6, s6, 0x100
	s_addc_u32 s7, s7, 0
	s_add_u32 s54, s54, 0x100
	s_addc_u32 s55, s55, 0
	s_cmp_gt_u32 s56, 13
.LBB0_578:
	ds_read_b128 v[128:131], v167
	ds_read_b128 v[132:135], v167 offset:1024
	ds_read_b128 v[136:139], v167 offset:2048
	ds_read_b128 v[160:163], v167 offset:3072
	s_add_u32 s26, s6, 0xfffc0080
	s_addc_u32 s27, s7, -1
	s_cmp_eq_u32 s56, 12
	s_cselect_b32 s29, s5, s27
	s_cselect_b32 s28, s21, s26
	s_cselect_b32 s27, s19, s55
	s_cselect_b32 s26, s53, s54
	s_add_i32 m0, s37, 0xc000
	ds_read_b128 v[170:173], v168
	ds_read_b128 v[174:177], v168 offset:1024
	ds_read_b128 v[178:181], v168 offset:2048
	ds_read_b128 v[182:185], v168 offset:3072
	ds_read_b128 v[186:189], v168 offset:4096
	ds_read_b128 v[190:193], v168 offset:5120
	ds_read_b128 v[194:197], v168 offset:6144
	ds_read_b128 v[202:205], v168 offset:7168
	global_load_lds_dwordx4 v152, s[6:7]
	s_add_i32 m0, s37, 0xe000
	s_nop 0
	global_load_lds_dwordx4 v154, s[6:7]
	s_waitcnt lgkmcnt(8)
	s_waitcnt vmcnt(8)
	s_setprio 1
	s_barrier
	s_waitcnt lgkmcnt(0)
	v_mfma_f32_16x16x32_bf16 v[124:127], v[128:131], v[170:173], v[124:127]
	v_mfma_f32_16x16x32_bf16 v[120:123], v[136:139], v[170:173], v[120:123]
	v_mfma_f32_16x16x32_bf16 v[108:111], v[128:131], v[178:181], v[108:111]
	v_mfma_f32_16x16x32_bf16 v[104:107], v[136:139], v[178:181], v[104:107]
	v_mfma_f32_16x16x32_bf16 v[92:95], v[128:131], v[186:189], v[92:95]
	v_mfma_f32_16x16x32_bf16 v[88:91], v[136:139], v[186:189], v[88:91]
	v_mfma_f32_16x16x32_bf16 v[76:79], v[128:131], v[194:197], v[76:79]
	v_mfma_f32_16x16x32_bf16 v[72:75], v[136:139], v[194:197], v[72:75]
	v_mfma_f32_16x16x32_bf16 v[124:127], v[132:135], v[174:177], v[124:127]
	v_mfma_f32_16x16x32_bf16 v[120:123], v[160:163], v[174:177], v[120:123]
	v_mfma_f32_16x16x32_bf16 v[108:111], v[132:135], v[182:185], v[108:111]
	v_mfma_f32_16x16x32_bf16 v[104:107], v[160:163], v[182:185], v[104:107]
	v_mfma_f32_16x16x32_bf16 v[92:95], v[132:135], v[190:193], v[92:95]
	v_mfma_f32_16x16x32_bf16 v[88:91], v[160:163], v[190:193], v[88:91]
	v_mfma_f32_16x16x32_bf16 v[76:79], v[132:135], v[202:205], v[76:79]
	v_mfma_f32_16x16x32_bf16 v[72:75], v[160:163], v[202:205], v[72:75]
	s_barrier
	s_setprio 0
	s_add_i32 s57, s48, s34
	s_mov_b32 m0, s57
	ds_read_b128 v[206:209], v169
	ds_read_b128 v[210:213], v169 offset:1024
	ds_read_b128 v[214:217], v169 offset:2048
	ds_read_b128 v[218:221], v169 offset:3072
	global_load_lds_dwordx4 v146, s[26:27]
	s_add_i32 m0, s57, 0x2000
	s_nop 0
	global_load_lds_dwordx4 v142, s[26:27]
	s_waitcnt vmcnt(8)
	s_setprio 1
	s_barrier
; #define PG8_STAGE(bufoff, gbase, voff) do { _Pragma("unroll") for (int _i = 0; _i < 2; ++_i) \
;         __builtin_amdgcn_global_load_lds((const unsigned*)((const char*)(gbase) + (voff)[_i]), (LAS unsigned*)(lds + (bufoff) + ldsw + _i * 8192), 16, 0, 0); } while (0)
; #define PG8_LDA(dst, b, h) do { _Pragma("unroll") for (int m = 0; m < 4; ++m) _Pragma("unroll") for (int k = 0; k < 2; ++k) dst[m][k] = *(const LAS bf16x8*)(lds + PG8_SA(b, h) + aoff + m * 2048 + k * 1024); } while (0)
; #define PG8_LDB(dst, b, h) do { _Pragma("unroll") for (int n = 0; n < 2; ++n) _Pragma("unroll") for (int k = 0; k < 2; ++k) dst[n][k] = *(const LAS bf16x8*)(lds + PG8_SB(b, h) + boff + n * 2048 + k * 1024); } while (0)
; #define PG8_MMA(ai, bj, At, Bt) do { __builtin_amdgcn_s_setprio(1); _Pragma("unroll") for (int m = 0; m < 4; ++m) _Pragma("unroll") for (int n = 0; n < 2; ++n) _Pragma("unroll") for (int k = 0; k < 2; ++k) \
;         acc[ai][bj][m][n] = __builtin_amdgcn_mfma_f32_16x16x32_bf16(Bt[n][k], At[m][k], acc[ai][bj][m][n], 0, 0, 0); __builtin_amdgcn_s_setprio(0); } while (0)
; #define PG8_WAIT_V(n) asm volatile("s_waitcnt vmcnt(" #n ")" ::: "memory")
; #define PG8_WAIT_L(n) asm volatile("s_waitcnt lgkmcnt(" #n ")" ::: "memory")
; #define PG8_BAR __builtin_amdgcn_s_barrier()
; #define PG8_SCHED __builtin_amdgcn_sched_barrier(0)
; template <class Epi, class Sched>
; __device__ __forceinline__ void gemm_phase(LAS unsigned char* lds, const Gemm g, const Sched& S, const Epi& E) {
;     ...
;             PG8_BAR; PG8_WAIT_L(0); PG8_MMA(0, 1, At, B1); PG8_BAR;
;             PG8_LDA(At, 0, 1); PG8_STAGE(PG8_SA(0, 0), a2, voffA);
;             PG8_BAR; PG8_WAIT_L(0); PG8_MMA(1, 0, At, B0); PG8_BAR; PG8_SCHED;
;             PG8_STAGE(PG8_SB(0, 1), b2 + hstep, voffB);
;             PG8_WAIT_V(6); PG8_BAR; PG8_MMA(1, 1, At, B1); PG8_BAR;
;             PG8_LDB(B0, 1, 0); PG8_SCHED; PG8_LDA(At, 1, 0); PG8_STAGE(PG8_SA(0, 1), a2 + hstep, voffA);
;             PG8_WAIT_L(8); PG8_BAR; PG8_WAIT_L(0); PG8_MMA(0, 0, At, B0); PG8_BAR; PG8_SCHED;
	s_waitcnt lgkmcnt(0)
	v_mfma_f32_16x16x32_bf16 v[116:119], v[206:209], v[170:173], v[116:119]
	v_mfma_f32_16x16x32_bf16 v[112:115], v[214:217], v[170:173], v[112:115]
	v_mfma_f32_16x16x32_bf16 v[100:103], v[206:209], v[178:181], v[100:103]
	v_mfma_f32_16x16x32_bf16 v[96:99], v[214:217], v[178:181], v[96:99]
	v_mfma_f32_16x16x32_bf16 v[84:87], v[206:209], v[186:189], v[84:87]
	v_mfma_f32_16x16x32_bf16 v[80:83], v[214:217], v[186:189], v[80:83]
	v_mfma_f32_16x16x32_bf16 v[68:71], v[206:209], v[194:197], v[68:71]
	v_mfma_f32_16x16x32_bf16 v[64:67], v[214:217], v[194:197], v[64:67]
	v_mfma_f32_16x16x32_bf16 v[116:119], v[210:213], v[174:177], v[116:119]
	v_mfma_f32_16x16x32_bf16 v[112:115], v[218:221], v[174:177], v[112:115]
	v_mfma_f32_16x16x32_bf16 v[100:103], v[210:213], v[182:185], v[100:103]
	v_mfma_f32_16x16x32_bf16 v[96:99], v[218:221], v[182:185], v[96:99]
	v_mfma_f32_16x16x32_bf16 v[84:87], v[210:213], v[190:193], v[84:87]
	v_mfma_f32_16x16x32_bf16 v[80:83], v[218:221], v[190:193], v[80:83]
	v_mfma_f32_16x16x32_bf16 v[68:71], v[210:213], v[202:205], v[68:71]
	v_mfma_f32_16x16x32_bf16 v[64:67], v[218:221], v[202:205], v[64:67]
	s_barrier
	s_setprio 0
	s_mov_b32 m0, s37
	v_lshl_add_u64 v[222:223], s[28:29], 0, v[148:149]
	ds_read_b128 v[170:173], v168 offset:16384
	ds_read_b128 v[174:177], v168 offset:17408
	ds_read_b128 v[178:181], v168 offset:18432
	ds_read_b128 v[182:185], v168 offset:19456
	ds_read_b128 v[186:189], v168 offset:20480
	ds_read_b128 v[190:193], v168 offset:21504
	ds_read_b128 v[194:197], v168 offset:22528
	ds_read_b128 v[202:205], v168 offset:23552
	global_load_lds_dwordx4 v148, s[28:29]
	v_lshl_add_u64 v[224:225], s[28:29], 0, v[144:145]
	s_mov_b32 m0, s38
	s_nop 0
	global_load_lds_dwordx4 v144, s[28:29]
	s_setprio 1
	s_barrier
	s_waitcnt lgkmcnt(0)
	v_mfma_f32_16x16x32_bf16 v[60:63], v[128:131], v[170:173], v[60:63]
	v_mfma_f32_16x16x32_bf16 v[56:59], v[136:139], v[170:173], v[56:59]
	v_mfma_f32_16x16x32_bf16 v[44:47], v[128:131], v[178:181], v[44:47]
	v_mfma_f32_16x16x32_bf16 v[40:43], v[136:139], v[178:181], v[40:43]
	v_mfma_f32_16x16x32_bf16 v[28:31], v[128:131], v[186:189], v[28:31]
	v_mfma_f32_16x16x32_bf16 v[24:27], v[136:139], v[186:189], v[24:27]
	v_mfma_f32_16x16x32_bf16 v[12:15], v[128:131], v[194:197], v[12:15]
	v_mfma_f32_16x16x32_bf16 v[8:11], v[136:139], v[194:197], v[8:11]
	v_mfma_f32_16x16x32_bf16 v[60:63], v[132:135], v[174:177], v[60:63]
	v_mfma_f32_16x16x32_bf16 v[56:59], v[160:163], v[174:177], v[56:59]
	v_mfma_f32_16x16x32_bf16 v[44:47], v[132:135], v[182:185], v[44:47]
	v_mfma_f32_16x16x32_bf16 v[40:43], v[160:163], v[182:185], v[40:43]
	v_mfma_f32_16x16x32_bf16 v[28:31], v[132:135], v[190:193], v[28:31]
	v_mfma_f32_16x16x32_bf16 v[24:27], v[160:163], v[190:193], v[24:27]
	v_mfma_f32_16x16x32_bf16 v[12:15], v[132:135], v[202:205], v[12:15]
	v_mfma_f32_16x16x32_bf16 v[8:11], v[160:163], v[202:205], v[8:11]
	s_barrier
	s_setprio 0
	s_add_u32 s58, s26, 0x40000
	s_addc_u32 s59, s27, 0
	s_add_i32 s57, s49, s34
	s_mov_b32 m0, s57
	s_nop 0
	global_load_lds_dwordx4 v146, s[58:59]
	s_add_i32 m0, s57, 0x2000
	s_nop 0
	global_load_lds_dwordx4 v142, s[58:59]
	s_add_u32 s28, s28, 0x40000
	s_addc_u32 s29, s29, 0
	s_mov_b32 m0, s39
	s_nop 0
	global_load_lds_dwordx4 v148, s[28:29]
	s_mov_b32 m0, s40
	s_nop 0
	global_load_lds_dwordx4 v144, s[28:29]
	s_waitcnt vmcnt(10)
	s_setprio 1
	s_barrier
	v_mfma_f32_16x16x32_bf16 v[52:55], v[206:209], v[170:173], v[52:55]
	v_mfma_f32_16x16x32_bf16 v[48:51], v[214:217], v[170:173], v[48:51]
	v_mfma_f32_16x16x32_bf16 v[36:39], v[206:209], v[178:181], v[36:39]
	v_mfma_f32_16x16x32_bf16 v[32:35], v[214:217], v[178:181], v[32:35]
	v_mfma_f32_16x16x32_bf16 v[20:23], v[206:209], v[186:189], v[20:23]
	v_mfma_f32_16x16x32_bf16 v[16:19], v[214:217], v[186:189], v[16:19]
	v_mfma_f32_16x16x32_bf16 v[4:7], v[206:209], v[194:197], v[4:7]
	v_mfma_f32_16x16x32_bf16 v[0:3], v[214:217], v[194:197], v[0:3]
	v_mfma_f32_16x16x32_bf16 v[52:55], v[210:213], v[174:177], v[52:55]
	v_mfma_f32_16x16x32_bf16 v[48:51], v[218:221], v[174:177], v[48:51]
	v_mfma_f32_16x16x32_bf16 v[36:39], v[210:213], v[182:185], v[36:39]
	v_mfma_f32_16x16x32_bf16 v[32:35], v[218:221], v[182:185], v[32:35]
	v_mfma_f32_16x16x32_bf16 v[20:23], v[210:213], v[190:193], v[20:23]
	v_mfma_f32_16x16x32_bf16 v[16:19], v[218:221], v[190:193], v[16:19]
	v_mfma_f32_16x16x32_bf16 v[4:7], v[210:213], v[202:205], v[4:7]
	v_mfma_f32_16x16x32_bf16 v[0:3], v[218:221], v[202:205], v[0:3]
	s_barrier
	s_setprio 0
	s_add_i32 s57, 0, 0x18000
	ds_read_b128 v[128:131], v169 offset:16384
	ds_read_b128 v[132:135], v169 offset:17408
	ds_read_b128 v[136:139], v169 offset:18432
	ds_read_b128 v[160:163], v169 offset:19456
	ds_read_b128 v[170:173], v168 offset:32768
	ds_read_b128 v[174:177], v168 offset:33792
	ds_read_b128 v[178:181], v168 offset:34816
	ds_read_b128 v[182:185], v168 offset:35840
	ds_read_b128 v[186:189], v168 offset:36864
	ds_read_b128 v[190:193], v168 offset:37888
	ds_read_b128 v[194:197], v168 offset:38912
	ds_read_b128 v[202:205], v168 offset:39936
	s_waitcnt lgkmcnt(8)
	s_waitcnt vmcnt(8)
	s_setprio 1
	s_barrier
; #define PG8_STAGE(bufoff, gbase, voff) do { _Pragma("unroll") for (int _i = 0; _i < 2; ++_i) \
;         __builtin_amdgcn_global_load_lds((const unsigned*)((const char*)(gbase) + (voff)[_i]), (LAS unsigned*)(lds + (bufoff) + ldsw + _i * 8192), 16, 0, 0); } while (0)
; #define PG8_LDA(dst, b, h) do { _Pragma("unroll") for (int m = 0; m < 4; ++m) _Pragma("unroll") for (int k = 0; k < 2; ++k) dst[m][k] = *(const LAS bf16x8*)(lds + PG8_SA(b, h) + aoff + m * 2048 + k * 1024); } while (0)
; #define PG8_LDB(dst, b, h) do { _Pragma("unroll") for (int n = 0; n < 2; ++n) _Pragma("unroll") for (int k = 0; k < 2; ++k) dst[n][k] = *(const LAS bf16x8*)(lds + PG8_SB(b, h) + boff + n * 2048 + k * 1024); } while (0)
; #define PG8_MMA(ai, bj, At, Bt) do { __builtin_amdgcn_s_setprio(1); _Pragma("unroll") for (int m = 0; m < 4; ++m) _Pragma("unroll") for (int n = 0; n < 2; ++n) _Pragma("unroll") for (int k = 0; k < 2; ++k) \
;         acc[ai][bj][m][n] = __builtin_amdgcn_mfma_f32_16x16x32_bf16(Bt[n][k], At[m][k], acc[ai][bj][m][n], 0, 0, 0); __builtin_amdgcn_s_setprio(0); } while (0)
; #define PG8_WAIT_L(n) asm volatile("s_waitcnt lgkmcnt(" #n ")" ::: "memory")
; #define PG8_BAR __builtin_amdgcn_s_barrier()
; #define PG8_SCHED __builtin_amdgcn_sched_barrier(0)
; template <class Epi, class Sched>
; __device__ __forceinline__ void gemm_phase(LAS unsigned char* lds, const Gemm g, const Sched& S, const Epi& E) {
;     ...
;             PG8_WAIT_L(8); PG8_BAR; PG8_WAIT_L(0); PG8_MMA(0, 0, At, B0); PG8_BAR; PG8_SCHED;
;             PG8_LDB(B1, 1, 1); PG8_STAGE(PG8_SB(1, 0), b3, voffB);
;             PG8_BAR; PG8_WAIT_L(0); PG8_MMA(0, 1, At, B1); PG8_BAR;
;             PG8_LDA(At, 1, 1); PG8_STAGE(PG8_SA(1, 0), a3, voffA);
	s_waitcnt lgkmcnt(0)
	v_mfma_f32_16x16x32_bf16 v[124:127], v[128:131], v[170:173], v[124:127]
	v_mfma_f32_16x16x32_bf16 v[120:123], v[136:139], v[170:173], v[120:123]
	v_mfma_f32_16x16x32_bf16 v[108:111], v[128:131], v[178:181], v[108:111]
	v_mfma_f32_16x16x32_bf16 v[104:107], v[136:139], v[178:181], v[104:107]
	v_mfma_f32_16x16x32_bf16 v[92:95], v[128:131], v[186:189], v[92:95]
	v_mfma_f32_16x16x32_bf16 v[88:91], v[136:139], v[186:189], v[88:91]
	v_mfma_f32_16x16x32_bf16 v[76:79], v[128:131], v[194:197], v[76:79]
	v_mfma_f32_16x16x32_bf16 v[72:75], v[136:139], v[194:197], v[72:75]
	v_mfma_f32_16x16x32_bf16 v[124:127], v[132:135], v[174:177], v[124:127]
	v_mfma_f32_16x16x32_bf16 v[120:123], v[160:163], v[174:177], v[120:123]
	v_mfma_f32_16x16x32_bf16 v[108:111], v[132:135], v[182:185], v[108:111]
	v_mfma_f32_16x16x32_bf16 v[104:107], v[160:163], v[182:185], v[104:107]
	v_mfma_f32_16x16x32_bf16 v[92:95], v[132:135], v[190:193], v[92:95]
	v_mfma_f32_16x16x32_bf16 v[88:91], v[160:163], v[190:193], v[88:91]
	v_mfma_f32_16x16x32_bf16 v[76:79], v[132:135], v[202:205], v[76:79]
	v_mfma_f32_16x16x32_bf16 v[72:75], v[160:163], v[202:205], v[72:75]
	s_barrier
	s_setprio 0
	s_add_i32 s28, 0, 0x1c000
	s_add_i32 s29, s57, s34
	s_add_u32 s0, s26, 0x80
	s_addc_u32 s1, s27, 0
	s_mov_b32 m0, s29
	ds_read_b128 v[206:209], v169 offset:32768
	ds_read_b128 v[210:213], v169 offset:33792
	ds_read_b128 v[214:217], v169 offset:34816
	ds_read_b128 v[218:221], v169 offset:35840
	global_load_lds_dwordx4 v146, s[0:1]
	s_add_i32 m0, s29, 0x2000
	s_nop 0
	global_load_lds_dwordx4 v142, s[0:1]
	s_waitcnt vmcnt(8)
	s_setprio 1
	s_barrier
	s_waitcnt lgkmcnt(0)
	v_mfma_f32_16x16x32_bf16 v[116:119], v[206:209], v[170:173], v[116:119]
	v_mfma_f32_16x16x32_bf16 v[112:115], v[214:217], v[170:173], v[112:115]
	v_mfma_f32_16x16x32_bf16 v[100:103], v[206:209], v[178:181], v[100:103]
	v_mfma_f32_16x16x32_bf16 v[96:99], v[214:217], v[178:181], v[96:99]
	v_mfma_f32_16x16x32_bf16 v[84:87], v[206:209], v[186:189], v[84:87]
	v_mfma_f32_16x16x32_bf16 v[80:83], v[214:217], v[186:189], v[80:83]
	v_mfma_f32_16x16x32_bf16 v[68:71], v[206:209], v[194:197], v[68:71]
	v_mfma_f32_16x16x32_bf16 v[64:67], v[214:217], v[194:197], v[64:67]
	v_mfma_f32_16x16x32_bf16 v[116:119], v[210:213], v[174:177], v[116:119]
	v_mfma_f32_16x16x32_bf16 v[112:115], v[218:221], v[174:177], v[112:115]
	v_mfma_f32_16x16x32_bf16 v[100:103], v[210:213], v[182:185], v[100:103]
	v_mfma_f32_16x16x32_bf16 v[96:99], v[218:221], v[182:185], v[96:99]
	v_mfma_f32_16x16x32_bf16 v[84:87], v[210:213], v[190:193], v[84:87]
	v_mfma_f32_16x16x32_bf16 v[80:83], v[218:221], v[190:193], v[80:83]
	v_mfma_f32_16x16x32_bf16 v[68:71], v[210:213], v[202:205], v[68:71]
	v_mfma_f32_16x16x32_bf16 v[64:67], v[218:221], v[202:205], v[64:67]
	s_barrier
	s_setprio 0
	s_mov_b32 m0, s44
	s_mov_b64 s[0:1], 0x80
	v_lshl_add_u64 v[140:141], v[222:223], 0, s[0:1]
	ds_read_b128 v[170:173], v168 offset:49152
	ds_read_b128 v[174:177], v168 offset:50176
	ds_read_b128 v[178:181], v168 offset:51200
	ds_read_b128 v[182:185], v168 offset:52224
	ds_read_b128 v[186:189], v168 offset:53248
	ds_read_b128 v[190:193], v168 offset:54272
	ds_read_b128 v[194:197], v168 offset:55296
	ds_read_b128 v[202:205], v168 offset:56320
	global_load_lds_dwordx4 v[140:141], off
	v_lshl_add_u64 v[140:141], v[224:225], 0, s[0:1]
	s_mov_b32 m0, s45
	s_nop 0
	global_load_lds_dwordx4 v[140:141], off
	s_setprio 1
	s_barrier
; #define PG8_STAGE(bufoff, gbase, voff) do { _Pragma("unroll") for (int _i = 0; _i < 2; ++_i) \
;         __builtin_amdgcn_global_load_lds((const unsigned*)((const char*)(gbase) + (voff)[_i]), (LAS unsigned*)(lds + (bufoff) + ldsw + _i * 8192), 16, 0, 0); } while (0)
; #define PG8_MMA(ai, bj, At, Bt) do { __builtin_amdgcn_s_setprio(1); _Pragma("unroll") for (int m = 0; m < 4; ++m) _Pragma("unroll") for (int n = 0; n < 2; ++n) _Pragma("unroll") for (int k = 0; k < 2; ++k) \
;         acc[ai][bj][m][n] = __builtin_amdgcn_mfma_f32_16x16x32_bf16(Bt[n][k], At[m][k], acc[ai][bj][m][n], 0, 0, 0); __builtin_amdgcn_s_setprio(0); } while (0)
; #define PG8_WAIT_V(n) asm volatile("s_waitcnt vmcnt(" #n ")" ::: "memory")
; #define PG8_WAIT_L(n) asm volatile("s_waitcnt lgkmcnt(" #n ")" ::: "memory")
; #define PG8_BAR __builtin_amdgcn_s_barrier()
; #define PG8_SCHED __builtin_amdgcn_sched_barrier(0)
; template <class Epi, class Sched>
; __device__ __forceinline__ void gemm_phase(LAS unsigned char* lds, const Gemm g, const Sched& S, const Epi& E) {
;     ...
;             PG8_BAR; PG8_WAIT_L(0); PG8_MMA(1, 0, At, B0); PG8_BAR; PG8_SCHED;
;             PG8_STAGE(PG8_SB(1, 1), b3 + hstep, voffB);
;             PG8_WAIT_V(6); PG8_BAR; PG8_MMA(1, 1, At, B1); PG8_BAR;
;         }
;         E(acc, cur, wr, wc, fr, fq);
;     __device__ __forceinline__ void operator()(const AccT& acc, const Unit& u, int wr, int wc, int fr, int fq) const {
;     ...
;         const int row0 = u.pm * 256 + wr * 64 + fr, col0 = u.pn * 256 + wc * 32 + 8 * fq;
;         const bool rope = u.pn < 2;
;         const int i = 4 * (wc & 1) + fq;
; #pragma unroll
;         for (int ai = 0; ai < 2; ++ai)
; #pragma unroll
;             for (int m = 0; m < 4; ++m) {
;                 const int row = row0 + ai * 128 + m * 16;
;                 f32x4 cs = {1.f, 1.f, 1.f, 1.f}, sn = {0.f, 0.f, 0.f, 0.f};
;                 if (rope) { const int t = row & 2047; const int pos = (i < 4) ? (t >> 6) : (t & 63);
;                     cs = *(const f32x4*)(ropeA + pos * 16 + ((4 * i) & 15)); sn = *(const f32x4*)(ropeA + 1024 + pos * 16 + ((4 * i) & 15)); }
	s_waitcnt lgkmcnt(0)
	v_mfma_f32_16x16x32_bf16 v[60:63], v[128:131], v[170:173], v[60:63]
	v_mfma_f32_16x16x32_bf16 v[56:59], v[136:139], v[170:173], v[56:59]
	v_mfma_f32_16x16x32_bf16 v[44:47], v[128:131], v[178:181], v[44:47]
	v_mfma_f32_16x16x32_bf16 v[40:43], v[136:139], v[178:181], v[40:43]
	v_mfma_f32_16x16x32_bf16 v[28:31], v[128:131], v[186:189], v[28:31]
	v_mfma_f32_16x16x32_bf16 v[24:27], v[136:139], v[186:189], v[24:27]
	v_mfma_f32_16x16x32_bf16 v[12:15], v[128:131], v[194:197], v[12:15]
	v_mfma_f32_16x16x32_bf16 v[8:11], v[136:139], v[194:197], v[8:11]
	v_mfma_f32_16x16x32_bf16 v[60:63], v[132:135], v[174:177], v[60:63]
	v_mfma_f32_16x16x32_bf16 v[56:59], v[160:163], v[174:177], v[56:59]
	v_mfma_f32_16x16x32_bf16 v[44:47], v[132:135], v[182:185], v[44:47]
	v_mfma_f32_16x16x32_bf16 v[40:43], v[160:163], v[182:185], v[40:43]
	v_mfma_f32_16x16x32_bf16 v[28:31], v[132:135], v[190:193], v[28:31]
	v_mfma_f32_16x16x32_bf16 v[24:27], v[160:163], v[190:193], v[24:27]
	v_mfma_f32_16x16x32_bf16 v[12:15], v[132:135], v[202:205], v[12:15]
	v_mfma_f32_16x16x32_bf16 v[8:11], v[160:163], v[202:205], v[8:11]
	s_barrier
	s_setprio 0
	s_add_u32 s26, s26, 0x40080
	s_addc_u32 s27, s27, 0
	s_add_i32 s28, s28, s34
	s_mov_b32 m0, s28
	s_nop 0
	global_load_lds_dwordx4 v146, s[26:27]
	s_add_i32 m0, s28, 0x2000
	s_nop 0
	global_load_lds_dwordx4 v142, s[26:27]
	s_waitcnt vmcnt(8)
	s_setprio 1
	s_barrier
	v_mfma_f32_16x16x32_bf16 v[52:55], v[206:209], v[170:173], v[52:55]
	v_mfma_f32_16x16x32_bf16 v[48:51], v[214:217], v[170:173], v[48:51]
	v_mfma_f32_16x16x32_bf16 v[36:39], v[206:209], v[178:181], v[36:39]
	v_mfma_f32_16x16x32_bf16 v[32:35], v[214:217], v[178:181], v[32:35]
	v_mfma_f32_16x16x32_bf16 v[20:23], v[206:209], v[186:189], v[20:23]
	v_mfma_f32_16x16x32_bf16 v[16:19], v[214:217], v[186:189], v[16:19]
	v_mfma_f32_16x16x32_bf16 v[4:7], v[206:209], v[194:197], v[4:7]
	v_mfma_f32_16x16x32_bf16 v[0:3], v[214:217], v[194:197], v[0:3]
	v_mfma_f32_16x16x32_bf16 v[52:55], v[210:213], v[174:177], v[52:55]
	v_mfma_f32_16x16x32_bf16 v[48:51], v[218:221], v[174:177], v[48:51]
	v_mfma_f32_16x16x32_bf16 v[36:39], v[210:213], v[182:185], v[36:39]
	v_mfma_f32_16x16x32_bf16 v[32:35], v[218:221], v[182:185], v[32:35]
	v_mfma_f32_16x16x32_bf16 v[20:23], v[210:213], v[190:193], v[20:23]
	v_mfma_f32_16x16x32_bf16 v[16:19], v[218:221], v[190:193], v[16:19]
	v_mfma_f32_16x16x32_bf16 v[4:7], v[210:213], v[202:205], v[4:7]
	v_mfma_f32_16x16x32_bf16 v[0:3], v[218:221], v[202:205], v[0:3]
	s_barrier
	s_setprio 0
	s_add_i32 s56, s56, 2
	s_add_u32 s6, s6, 0x100
	s_addc_u32 s7, s7, 0
	s_add_u32 s54, s54, 0x100
	s_addc_u32 s55, s55, 0
	s_cmp_gt_u32 s56, 13
	s_cbranch_scc0 .LBB0_578
	v_mov_b32_e32 v129, v165
	v_mov_b32_e32 v173, v164
	s_lshl_b32 s4, s4, 8
	s_add_i32 s4, s4, s42
	v_add_u32_e32 v128, s46, v129
	v_add_u32_e32 v170, s4, v173
	v_cmp_gt_i32_e64 s[4:5], 4, v128
	v_lshlrev_b32_e32 v128, 2, v128
	s_cmp_lt_i32 s52, 2
	v_and_b32_e32 v130, 12, v128
	s_cselect_b64 s[26:27], -1, 0
	s_cmp_gt_i32 s52, 1
	v_and_b32_e32 v172, 63, v173
	v_mov_b32_e32 v128, 1.0
	v_mov_b32_e32 v132, 0
	v_lshlrev_b32_e32 v162, 2, v130
	v_mov_b32_e32 v134, 0
	v_mov_b32_e32 v135, 0
	v_mov_b32_e32 v136, 0
	v_mov_b32_e32 v137, 0
	v_mov_b32_e32 v138, 1.0
	v_mov_b32_e32 v139, 1.0
	v_mov_b32_e32 v140, 1.0
	v_mov_b32_e32 v141, 1.0
	s_cbranch_scc1 .LBB0_581
	v_bfe_u32 v130, v170, 6, 5
	v_cndmask_b32_e64 v130, v172, v130, s[4:5]
	v_lshlrev_b32_e32 v150, 6, v130
	v_lshl_add_u64 v[130:131], s[16:17], 0, v[150:151]
	v_mov_b32_e32 v163, v151
	v_lshl_add_u64 v[134:135], s[8:9], 0, v[150:151]
	v_lshl_add_u64 v[130:131], v[130:131], 0, v[162:163]
	v_lshl_add_u64 v[134:135], v[134:135], 0, v[162:163]
	global_load_dwordx4 v[138:141], v[130:131], off
	s_nop 0
	global_load_dwordx4 v[134:137], v[134:135], off
	s_waitcnt vmcnt(0)

; #define PG8_STAGE(bufoff, gbase, voff) do { _Pragma("unroll") for (int _i = 0; _i < 2; ++_i) \
;         __builtin_amdgcn_global_load_lds((const unsigned*)((const char*)(gbase) + (voff)[_i]), (LAS unsigned*)(lds + (bufoff) + ldsw + _i * 8192), 16, 0, 0); } while (0)
; #define PG8_LDA(dst, b, h) do { _Pragma("unroll") for (int m = 0; m < 4; ++m) _Pragma("unroll") for (int k = 0; k < 2; ++k) dst[m][k] = *(const LAS bf16x8*)(lds + PG8_SA(b, h) + aoff + m * 2048 + k * 1024); } while (0)
; #define PG8_LDB(dst, b, h) do { _Pragma("unroll") for (int n = 0; n < 2; ++n) _Pragma("unroll") for (int k = 0; k < 2; ++k) dst[n][k] = *(const LAS bf16x8*)(lds + PG8_SB(b, h) + boff + n * 2048 + k * 1024); } while (0)
; #define PG8_MMA(ai, bj, At, Bt) do { __builtin_amdgcn_s_setprio(1); _Pragma("unroll") for (int m = 0; m < 4; ++m) _Pragma("unroll") for (int n = 0; n < 2; ++n) _Pragma("unroll") for (int k = 0; k < 2; ++k) \
;         acc[ai][bj][m][n] = __builtin_amdgcn_mfma_f32_16x16x32_bf16(Bt[n][k], At[m][k], acc[ai][bj][m][n], 0, 0, 0); __builtin_amdgcn_s_setprio(0); } while (0)
; #define PG8_WAIT_L(n) asm volatile("s_waitcnt lgkmcnt(" #n ")" ::: "memory")
; #define PG8_BAR __builtin_amdgcn_s_barrier()
; template <class Epi, class Sched>
; __device__ __forceinline__ void gemm_phase(LAS unsigned char* lds, const Gemm g, const Sched& S, const Epi& E) {
;     ...
;         const char* nA = has_next ? (const char*)g.A + (size_t)nxt.pm * tstep : cA; const char* nB = has_next ? (const char*)g.Bt + (size_t)nxt.pn * tstep : cB;
;         for (int t = 0; t < nt; t += 2) {
;             const bool last = (t == nt - 2);
;             const char* a1 = cA + (size_t)(t + 1) * kstep;
;             const char* a2 = last ? nA : cA + (size_t)(t + 2) * kstep; const char* b2 = last ? nB : cB + (size_t)(t + 2) * kstep;
;             const char* a3 = a2 + kstep; const char* b3 = b2 + kstep;
;             PG8_LDB(B0, 0, 0); PG8_SCHED; PG8_LDA(At, 0, 0); PG8_STAGE(PG8_SA(1, 1), a1 + hstep, voffA);
;             PG8_WAIT_L(8); PG8_BAR; PG8_WAIT_L(0); PG8_MMA(0, 0, At, B0); PG8_BAR; PG8_SCHED;
;             PG8_LDB(B1, 0, 1); PG8_STAGE(PG8_SB(0, 0), b2, voffB);
;             PG8_BAR; PG8_WAIT_L(0); PG8_MMA(0, 1, At, B1); PG8_BAR;
;             PG8_LDA(At, 0, 1); PG8_STAGE(PG8_SA(0, 0), a2, voffA);
;             PG8_BAR; PG8_WAIT_L(0); PG8_MMA(1, 0, At, B0); PG8_BAR; PG8_SCHED;
.LBB0_612:
	s_ashr_i32 s35, s34, 31
	v_cmp_lt_i64_e32 vcc, s[6:7], v[142:143]
	s_lshl_b64 s[6:7], s[34:35], 19
	s_add_u32 s36, s40, s6
	s_addc_u32 s37, s41, s7
	s_and_b64 s[6:7], vcc, exec
	s_cselect_b32 s8, s37, s1
	s_cselect_b32 s9, s36, s0
	s_ashr_i32 s31, s30, 31
	s_lshl_b64 s[6:7], s[30:31], 19
	s_add_u32 s38, s96, s6
	s_addc_u32 s39, s97, s7
	s_and_b64 s[6:7], vcc, exec
	s_cselect_b32 s31, s39, s5
	s_cselect_b32 s35, s38, s4
	s_add_u32 s0, s0, 0x40080
	s_addc_u32 s1, s1, 0
	s_add_u32 s65, s4, 0x100
	s_addc_u32 s66, s5, 0
	s_mov_b32 s67, -2
	s_waitcnt lgkmcnt(0)
	ds_read_b128 v[146:149], v171
	ds_read_b128 v[150:153], v171 offset:1024
	ds_read_b128 v[154:157], v171 offset:2048
	ds_read_b128 v[158:161], v171 offset:3072
	s_add_u32 s4, s0, 0xfffc0080
	s_addc_u32 s5, s1, -1
	s_cmp_eq_u32 s67, 12
	s_cselect_b32 s7, s8, s5
	s_cselect_b32 s6, s9, s4
	s_cselect_b32 s5, s31, s66
	s_cselect_b32 s4, s35, s65
	s_add_i32 m0, s45, 0xc000
	ds_read_b128 v[162:165], v172
	ds_read_b128 v[178:181], v172 offset:1024
	ds_read_b128 v[182:185], v172 offset:2048
	ds_read_b128 v[186:189], v172 offset:3072
	ds_read_b128 v[190:193], v172 offset:4096
	ds_read_b128 v[194:197], v172 offset:5120
	ds_read_b128 v[202:205], v172 offset:6144
	ds_read_b128 v[206:209], v172 offset:7168
	global_load_lds_dwordx4 v138, s[0:1]
	s_add_i32 m0, s45, 0xe000
	s_nop 0
	global_load_lds_dwordx4 v140, s[0:1]
	s_waitcnt lgkmcnt(8)
	s_waitcnt vmcnt(8)
	s_setprio 1
	s_barrier
	s_waitcnt lgkmcnt(0)
	v_mfma_f32_16x16x32_bf16 v[124:127], v[146:149], v[162:165], 0
	v_mfma_f32_16x16x32_bf16 v[120:123], v[154:157], v[162:165], 0
	v_mfma_f32_16x16x32_bf16 v[108:111], v[146:149], v[182:185], 0
	v_mfma_f32_16x16x32_bf16 v[104:107], v[154:157], v[182:185], 0
	v_mfma_f32_16x16x32_bf16 v[92:95], v[146:149], v[190:193], 0
	v_mfma_f32_16x16x32_bf16 v[88:91], v[154:157], v[190:193], 0
	v_mfma_f32_16x16x32_bf16 v[76:79], v[146:149], v[202:205], 0
	v_mfma_f32_16x16x32_bf16 v[72:75], v[154:157], v[202:205], 0
	v_mfma_f32_16x16x32_bf16 v[124:127], v[150:153], v[178:181], v[124:127]
	v_mfma_f32_16x16x32_bf16 v[120:123], v[158:161], v[178:181], v[120:123]
	v_mfma_f32_16x16x32_bf16 v[108:111], v[150:153], v[186:189], v[108:111]
	v_mfma_f32_16x16x32_bf16 v[104:107], v[158:161], v[186:189], v[104:107]
	v_mfma_f32_16x16x32_bf16 v[92:95], v[150:153], v[194:197], v[92:95]
	v_mfma_f32_16x16x32_bf16 v[88:91], v[158:161], v[194:197], v[88:91]
	v_mfma_f32_16x16x32_bf16 v[76:79], v[150:153], v[206:209], v[76:79]
	v_mfma_f32_16x16x32_bf16 v[72:75], v[158:161], v[206:209], v[72:75]
	s_barrier
	s_setprio 0
	s_add_i32 s68, s57, s44
	s_mov_b32 m0, s68
	ds_read_b128 v[210:213], v173
	ds_read_b128 v[214:217], v173 offset:1024
	ds_read_b128 v[218:221], v173 offset:2048
	ds_read_b128 v[222:225], v173 offset:3072
	global_load_lds_dwordx4 v130, s[4:5]
	s_add_i32 m0, s68, 0x2000
	s_nop 0
	global_load_lds_dwordx4 v134, s[4:5]
	s_waitcnt vmcnt(8)
	s_setprio 1
	s_barrier
	s_waitcnt lgkmcnt(0)
	v_mfma_f32_16x16x32_bf16 v[116:119], v[210:213], v[162:165], 0
	v_mfma_f32_16x16x32_bf16 v[112:115], v[218:221], v[162:165], 0
	v_mfma_f32_16x16x32_bf16 v[100:103], v[210:213], v[182:185], 0
	v_mfma_f32_16x16x32_bf16 v[96:99], v[218:221], v[182:185], 0
	v_mfma_f32_16x16x32_bf16 v[84:87], v[210:213], v[190:193], 0
	v_mfma_f32_16x16x32_bf16 v[80:83], v[218:221], v[190:193], 0
	v_mfma_f32_16x16x32_bf16 v[68:71], v[210:213], v[202:205], 0
	v_mfma_f32_16x16x32_bf16 v[64:67], v[218:221], v[202:205], 0
	v_mfma_f32_16x16x32_bf16 v[116:119], v[214:217], v[178:181], v[116:119]
	v_mfma_f32_16x16x32_bf16 v[112:115], v[222:225], v[178:181], v[112:115]
	v_mfma_f32_16x16x32_bf16 v[100:103], v[214:217], v[186:189], v[100:103]
	v_mfma_f32_16x16x32_bf16 v[96:99], v[222:225], v[186:189], v[96:99]
	v_mfma_f32_16x16x32_bf16 v[84:87], v[214:217], v[194:197], v[84:87]
	v_mfma_f32_16x16x32_bf16 v[80:83], v[222:225], v[194:197], v[80:83]
	v_mfma_f32_16x16x32_bf16 v[68:71], v[214:217], v[206:209], v[68:71]
	v_mfma_f32_16x16x32_bf16 v[64:67], v[222:225], v[206:209], v[64:67]
	s_barrier
	s_setprio 0
	s_mov_b32 m0, s45
	v_lshl_add_u64 v[226:227], s[6:7], 0, v[128:129]
	ds_read_b128 v[162:165], v172 offset:16384
	ds_read_b128 v[178:181], v172 offset:17408
	ds_read_b128 v[182:185], v172 offset:18432
	ds_read_b128 v[186:189], v172 offset:19456
	ds_read_b128 v[190:193], v172 offset:20480
	ds_read_b128 v[194:197], v172 offset:21504
	ds_read_b128 v[202:205], v172 offset:22528
	ds_read_b128 v[206:209], v172 offset:23552
	global_load_lds_dwordx4 v128, s[6:7]
	v_lshl_add_u64 v[228:229], s[6:7], 0, v[132:133]
	s_mov_b32 m0, s46
	s_nop 0
	global_load_lds_dwordx4 v132, s[6:7]
	s_setprio 1
	s_barrier
	s_waitcnt lgkmcnt(0)
	v_mfma_f32_16x16x32_bf16 v[60:63], v[146:149], v[162:165], 0
	v_mfma_f32_16x16x32_bf16 v[56:59], v[154:157], v[162:165], 0
	v_mfma_f32_16x16x32_bf16 v[44:47], v[146:149], v[182:185], 0
	v_mfma_f32_16x16x32_bf16 v[40:43], v[154:157], v[182:185], 0
	v_mfma_f32_16x16x32_bf16 v[28:31], v[146:149], v[190:193], 0
	v_mfma_f32_16x16x32_bf16 v[24:27], v[154:157], v[190:193], 0
	v_mfma_f32_16x16x32_bf16 v[12:15], v[146:149], v[202:205], 0
	v_mfma_f32_16x16x32_bf16 v[8:11], v[154:157], v[202:205], 0
	v_mfma_f32_16x16x32_bf16 v[60:63], v[150:153], v[178:181], v[60:63]
	v_mfma_f32_16x16x32_bf16 v[56:59], v[158:161], v[178:181], v[56:59]
	v_mfma_f32_16x16x32_bf16 v[44:47], v[150:153], v[186:189], v[44:47]
	v_mfma_f32_16x16x32_bf16 v[40:43], v[158:161], v[186:189], v[40:43]
	v_mfma_f32_16x16x32_bf16 v[28:31], v[150:153], v[194:197], v[28:31]
	v_mfma_f32_16x16x32_bf16 v[24:27], v[158:161], v[194:197], v[24:27]
	v_mfma_f32_16x16x32_bf16 v[12:15], v[150:153], v[206:209], v[12:15]
	v_mfma_f32_16x16x32_bf16 v[8:11], v[158:161], v[206:209], v[8:11]
	s_barrier
; #define PG8_STAGE(bufoff, gbase, voff) do { _Pragma("unroll") for (int _i = 0; _i < 2; ++_i) \
;         __builtin_amdgcn_global_load_lds((const unsigned*)((const char*)(gbase) + (voff)[_i]), (LAS unsigned*)(lds + (bufoff) + ldsw + _i * 8192), 16, 0, 0); } while (0)
; #define PG8_LDA(dst, b, h) do { _Pragma("unroll") for (int m = 0; m < 4; ++m) _Pragma("unroll") for (int k = 0; k < 2; ++k) dst[m][k] = *(const LAS bf16x8*)(lds + PG8_SA(b, h) + aoff + m * 2048 + k * 1024); } while (0)
; #define PG8_LDB(dst, b, h) do { _Pragma("unroll") for (int n = 0; n < 2; ++n) _Pragma("unroll") for (int k = 0; k < 2; ++k) dst[n][k] = *(const LAS bf16x8*)(lds + PG8_SB(b, h) + boff + n * 2048 + k * 1024); } while (0)
; #define PG8_WAIT_V(n) asm volatile("s_waitcnt vmcnt(" #n ")" ::: "memory")
; #define PG8_WAIT_L(n) asm volatile("s_waitcnt lgkmcnt(" #n ")" ::: "memory")
; #define PG8_BAR __builtin_amdgcn_s_barrier()
; #define PG8_SCHED __builtin_amdgcn_sched_barrier(0)
; template <class Epi, class Sched>
; __device__ __forceinline__ void gemm_phase(LAS unsigned char* lds, const Gemm g, const Sched& S, const Epi& E) {
;     ...
;             PG8_LDB(B0, 0, 0); PG8_SCHED; PG8_LDA(At, 0, 0); PG8_STAGE(PG8_SA(1, 1), a1 + hstep, voffA);
;             PG8_WAIT_L(8); PG8_BAR; PG8_WAIT_L(0); PG8_MMA(0, 0, At, B0); PG8_BAR; PG8_SCHED;
;             PG8_LDB(B1, 0, 1); PG8_STAGE(PG8_SB(0, 0), b2, voffB);
;             PG8_BAR; PG8_WAIT_L(0); PG8_MMA(0, 1, At, B1); PG8_BAR;
;             PG8_LDA(At, 0, 1); PG8_STAGE(PG8_SA(0, 0), a2, voffA);
;             PG8_BAR; PG8_WAIT_L(0); PG8_MMA(1, 0, At, B0); PG8_BAR; PG8_SCHED;
;             PG8_STAGE(PG8_SB(0, 1), b2 + hstep, voffB);
;             PG8_WAIT_V(6); PG8_BAR; PG8_MMA(1, 1, At, B1); PG8_BAR;
;             PG8_LDB(B0, 1, 0); PG8_SCHED; PG8_LDA(At, 1, 0); PG8_STAGE(PG8_SA(0, 1), a2 + hstep, voffA);
;             PG8_WAIT_L(8); PG8_BAR; PG8_WAIT_L(0); PG8_MMA(0, 0, At, B0); PG8_BAR; PG8_SCHED;
;             PG8_LDB(B1, 1, 1); PG8_STAGE(PG8_SB(1, 0), b3, voffB);
;             PG8_BAR; PG8_WAIT_L(0); PG8_MMA(0, 1, At, B1); PG8_BAR;
;             PG8_LDA(At, 1, 1); PG8_STAGE(PG8_SA(1, 0), a3, voffA);
;             PG8_BAR; PG8_WAIT_L(0); PG8_MMA(1, 0, At, B0); PG8_BAR; PG8_SCHED;
;             PG8_STAGE(PG8_SB(1, 1), b3 + hstep, voffB);
;             PG8_WAIT_V(6); PG8_BAR; PG8_MMA(1, 1, At, B1); PG8_BAR;
	s_setprio 0
	s_add_u32 s68, s4, 0x40000
	s_addc_u32 s69, s5, 0
	s_add_i32 s70, s58, s44
	s_mov_b32 m0, s70
	s_nop 0
	global_load_lds_dwordx4 v130, s[68:69]
	s_add_i32 m0, s70, 0x2000
	s_nop 0
	global_load_lds_dwordx4 v134, s[68:69]
	s_add_u32 s6, s6, 0x40000
	s_addc_u32 s7, s7, 0
	s_mov_b32 m0, s47
	s_nop 0
	global_load_lds_dwordx4 v128, s[6:7]
	s_mov_b32 m0, s48
	s_nop 0
	global_load_lds_dwordx4 v132, s[6:7]
	s_waitcnt vmcnt(10)
	s_setprio 1
	s_barrier
	v_mfma_f32_16x16x32_bf16 v[52:55], v[210:213], v[162:165], 0
	v_mfma_f32_16x16x32_bf16 v[48:51], v[218:221], v[162:165], 0
	v_mfma_f32_16x16x32_bf16 v[36:39], v[210:213], v[182:185], 0
	v_mfma_f32_16x16x32_bf16 v[32:35], v[218:221], v[182:185], 0
	v_mfma_f32_16x16x32_bf16 v[20:23], v[210:213], v[190:193], 0
	v_mfma_f32_16x16x32_bf16 v[16:19], v[218:221], v[190:193], 0
	v_mfma_f32_16x16x32_bf16 v[4:7], v[210:213], v[202:205], 0
	v_mfma_f32_16x16x32_bf16 v[0:3], v[218:221], v[202:205], 0
	v_mfma_f32_16x16x32_bf16 v[52:55], v[214:217], v[178:181], v[52:55]
	v_mfma_f32_16x16x32_bf16 v[48:51], v[222:225], v[178:181], v[48:51]
	v_mfma_f32_16x16x32_bf16 v[36:39], v[214:217], v[186:189], v[36:39]
	v_mfma_f32_16x16x32_bf16 v[32:35], v[222:225], v[186:189], v[32:35]
	v_mfma_f32_16x16x32_bf16 v[20:23], v[214:217], v[194:197], v[20:23]
	v_mfma_f32_16x16x32_bf16 v[16:19], v[222:225], v[194:197], v[16:19]
	v_mfma_f32_16x16x32_bf16 v[4:7], v[214:217], v[206:209], v[4:7]
	v_mfma_f32_16x16x32_bf16 v[0:3], v[222:225], v[206:209], v[0:3]
	s_barrier
	s_setprio 0
	s_add_i32 s68, 0, 0x18000
	ds_read_b128 v[146:149], v173 offset:16384
	ds_read_b128 v[150:153], v173 offset:17408
	ds_read_b128 v[154:157], v173 offset:18432
	ds_read_b128 v[158:161], v173 offset:19456
	ds_read_b128 v[162:165], v172 offset:32768
	ds_read_b128 v[178:181], v172 offset:33792
	ds_read_b128 v[182:185], v172 offset:34816
	ds_read_b128 v[186:189], v172 offset:35840
	ds_read_b128 v[190:193], v172 offset:36864
	ds_read_b128 v[194:197], v172 offset:37888
	ds_read_b128 v[202:205], v172 offset:38912
	ds_read_b128 v[206:209], v172 offset:39936
	s_waitcnt lgkmcnt(8)
	s_waitcnt vmcnt(8)
	s_setprio 1
	s_barrier
	s_waitcnt lgkmcnt(0)
	v_mfma_f32_16x16x32_bf16 v[124:127], v[146:149], v[162:165], v[124:127]
	v_mfma_f32_16x16x32_bf16 v[120:123], v[154:157], v[162:165], v[120:123]
	v_mfma_f32_16x16x32_bf16 v[108:111], v[146:149], v[182:185], v[108:111]
	v_mfma_f32_16x16x32_bf16 v[104:107], v[154:157], v[182:185], v[104:107]
	v_mfma_f32_16x16x32_bf16 v[92:95], v[146:149], v[190:193], v[92:95]
	v_mfma_f32_16x16x32_bf16 v[88:91], v[154:157], v[190:193], v[88:91]
	v_mfma_f32_16x16x32_bf16 v[76:79], v[146:149], v[202:205], v[76:79]
	v_mfma_f32_16x16x32_bf16 v[72:75], v[154:157], v[202:205], v[72:75]
	v_mfma_f32_16x16x32_bf16 v[124:127], v[150:153], v[178:181], v[124:127]
	v_mfma_f32_16x16x32_bf16 v[120:123], v[158:161], v[178:181], v[120:123]
	v_mfma_f32_16x16x32_bf16 v[108:111], v[150:153], v[186:189], v[108:111]
	v_mfma_f32_16x16x32_bf16 v[104:107], v[158:161], v[186:189], v[104:107]
	v_mfma_f32_16x16x32_bf16 v[92:95], v[150:153], v[194:197], v[92:95]
	v_mfma_f32_16x16x32_bf16 v[88:91], v[158:161], v[194:197], v[88:91]
	v_mfma_f32_16x16x32_bf16 v[76:79], v[150:153], v[206:209], v[76:79]
	v_mfma_f32_16x16x32_bf16 v[72:75], v[158:161], v[206:209], v[72:75]
	s_barrier
	s_setprio 0
	s_add_i32 s6, 0, 0x1c000
	s_add_i32 s7, s68, s44
	s_add_u32 s20, s4, 0x80
	s_addc_u32 s21, s5, 0
	s_mov_b32 m0, s7
	ds_read_b128 v[210:213], v173 offset:32768
	ds_read_b128 v[214:217], v173 offset:33792
	ds_read_b128 v[218:221], v173 offset:34816
	ds_read_b128 v[222:225], v173 offset:35840
	global_load_lds_dwordx4 v130, s[20:21]
	s_add_i32 m0, s7, 0x2000
	s_nop 0
	global_load_lds_dwordx4 v134, s[20:21]
	s_waitcnt vmcnt(8)
	s_setprio 1
	s_barrier
	s_waitcnt lgkmcnt(0)
	v_mfma_f32_16x16x32_bf16 v[116:119], v[210:213], v[162:165], v[116:119]
	v_mfma_f32_16x16x32_bf16 v[112:115], v[218:221], v[162:165], v[112:115]
	v_mfma_f32_16x16x32_bf16 v[100:103], v[210:213], v[182:185], v[100:103]
	v_mfma_f32_16x16x32_bf16 v[96:99], v[218:221], v[182:185], v[96:99]
	v_mfma_f32_16x16x32_bf16 v[84:87], v[210:213], v[190:193], v[84:87]
	v_mfma_f32_16x16x32_bf16 v[80:83], v[218:221], v[190:193], v[80:83]
	v_mfma_f32_16x16x32_bf16 v[68:71], v[210:213], v[202:205], v[68:71]
	v_mfma_f32_16x16x32_bf16 v[64:67], v[218:221], v[202:205], v[64:67]
	v_mfma_f32_16x16x32_bf16 v[116:119], v[214:217], v[178:181], v[116:119]
	v_mfma_f32_16x16x32_bf16 v[112:115], v[222:225], v[178:181], v[112:115]
	v_mfma_f32_16x16x32_bf16 v[100:103], v[214:217], v[186:189], v[100:103]
	v_mfma_f32_16x16x32_bf16 v[96:99], v[222:225], v[186:189], v[96:99]
	v_mfma_f32_16x16x32_bf16 v[84:87], v[214:217], v[194:197], v[84:87]
	v_mfma_f32_16x16x32_bf16 v[80:83], v[222:225], v[194:197], v[80:83]
	v_mfma_f32_16x16x32_bf16 v[68:71], v[214:217], v[206:209], v[68:71]
	v_mfma_f32_16x16x32_bf16 v[64:67], v[222:225], v[206:209], v[64:67]
	s_barrier
	s_setprio 0
	s_mov_b32 m0, s54
	s_mov_b64 s[20:21], 0x80
	v_lshl_add_u64 v[166:167], v[226:227], 0, s[20:21]
	ds_read_b128 v[162:165], v172 offset:49152
	ds_read_b128 v[178:181], v172 offset:50176
	ds_read_b128 v[182:185], v172 offset:51200
	ds_read_b128 v[186:189], v172 offset:52224
	ds_read_b128 v[190:193], v172 offset:53248
	ds_read_b128 v[194:197], v172 offset:54272
	ds_read_b128 v[202:205], v172 offset:55296
	ds_read_b128 v[206:209], v172 offset:56320
	global_load_lds_dwordx4 v[166:167], off
	v_lshl_add_u64 v[166:167], v[228:229], 0, s[20:21]
	s_mov_b32 m0, s55
	s_nop 0
	global_load_lds_dwordx4 v[166:167], off
	s_setprio 1
	s_barrier
; #define PG8_STAGE(bufoff, gbase, voff) do { _Pragma("unroll") for (int _i = 0; _i < 2; ++_i) \
;         __builtin_amdgcn_global_load_lds((const unsigned*)((const char*)(gbase) + (voff)[_i]), (LAS unsigned*)(lds + (bufoff) + ldsw + _i * 8192), 16, 0, 0); } while (0)
; #define PG8_LDA(dst, b, h) do { _Pragma("unroll") for (int m = 0; m < 4; ++m) _Pragma("unroll") for (int k = 0; k < 2; ++k) dst[m][k] = *(const LAS bf16x8*)(lds + PG8_SA(b, h) + aoff + m * 2048 + k * 1024); } while (0)
; #define PG8_WAIT_V(n) asm volatile("s_waitcnt vmcnt(" #n ")" ::: "memory")
; #define PG8_WAIT_L(n) asm volatile("s_waitcnt lgkmcnt(" #n ")" ::: "memory")
; template <class Epi, class Sched>
; __device__ __forceinline__ void gemm_phase(LAS unsigned char* lds, const Gemm g, const Sched& S, const Epi& E) {
;     ...
;         for (int t = 0; t < nt; t += 2) {
;             const bool last = (t == nt - 2);
;             const char* a1 = cA + (size_t)(t + 1) * kstep;
;             const char* a2 = last ? nA : cA + (size_t)(t + 2) * kstep; const char* b2 = last ? nB : cB + (size_t)(t + 2) * kstep;
;             const char* a3 = a2 + kstep; const char* b3 = b2 + kstep;
;             PG8_LDB(B0, 0, 0); PG8_SCHED; PG8_LDA(At, 0, 0); PG8_STAGE(PG8_SA(1, 1), a1 + hstep, voffA);
;             PG8_WAIT_L(8); PG8_BAR; PG8_WAIT_L(0); PG8_MMA(0, 0, At, B0); PG8_BAR; PG8_SCHED;
;             PG8_LDB(B1, 0, 1); PG8_STAGE(PG8_SB(0, 0), b2, voffB);
;             PG8_BAR; PG8_WAIT_L(0); PG8_MMA(0, 1, At, B1); PG8_BAR;
;             PG8_LDA(At, 0, 1); PG8_STAGE(PG8_SA(0, 0), a2, voffA);
;             PG8_BAR; PG8_WAIT_L(0); PG8_MMA(1, 0, At, B0); PG8_BAR; PG8_SCHED;
;             PG8_STAGE(PG8_SB(0, 1), b2 + hstep, voffB);
;             PG8_WAIT_V(6); PG8_BAR; PG8_MMA(1, 1, At, B1); PG8_BAR;
;             PG8_LDB(B0, 1, 0); PG8_SCHED; PG8_LDA(At, 1, 0); PG8_STAGE(PG8_SA(0, 1), a2 + hstep, voffA);
;             PG8_WAIT_L(8); PG8_BAR; PG8_WAIT_L(0); PG8_MMA(0, 0, At, B0); PG8_BAR; PG8_SCHED;
;             PG8_LDB(B1, 1, 1); PG8_STAGE(PG8_SB(1, 0), b3, voffB);
;             PG8_BAR; PG8_WAIT_L(0); PG8_MMA(0, 1, At, B1); PG8_BAR;
;             PG8_LDA(At, 1, 1); PG8_STAGE(PG8_SA(1, 0), a3, voffA);
;             PG8_BAR; PG8_WAIT_L(0); PG8_MMA(1, 0, At, B0); PG8_BAR; PG8_SCHED;
;             PG8_STAGE(PG8_SB(1, 1), b3 + hstep, voffB);
;             PG8_WAIT_V(6); PG8_BAR; PG8_MMA(1, 1, At, B1); PG8_BAR;
	s_waitcnt lgkmcnt(0)
	v_mfma_f32_16x16x32_bf16 v[60:63], v[146:149], v[162:165], v[60:63]
	v_mfma_f32_16x16x32_bf16 v[56:59], v[154:157], v[162:165], v[56:59]
	v_mfma_f32_16x16x32_bf16 v[44:47], v[146:149], v[182:185], v[44:47]
	v_mfma_f32_16x16x32_bf16 v[40:43], v[154:157], v[182:185], v[40:43]
	v_mfma_f32_16x16x32_bf16 v[28:31], v[146:149], v[190:193], v[28:31]
	v_mfma_f32_16x16x32_bf16 v[24:27], v[154:157], v[190:193], v[24:27]
	v_mfma_f32_16x16x32_bf16 v[12:15], v[146:149], v[202:205], v[12:15]
	v_mfma_f32_16x16x32_bf16 v[8:11], v[154:157], v[202:205], v[8:11]
	v_mfma_f32_16x16x32_bf16 v[60:63], v[150:153], v[178:181], v[60:63]
	v_mfma_f32_16x16x32_bf16 v[56:59], v[158:161], v[178:181], v[56:59]
	v_mfma_f32_16x16x32_bf16 v[44:47], v[150:153], v[186:189], v[44:47]
	v_mfma_f32_16x16x32_bf16 v[40:43], v[158:161], v[186:189], v[40:43]
	v_mfma_f32_16x16x32_bf16 v[28:31], v[150:153], v[194:197], v[28:31]
	v_mfma_f32_16x16x32_bf16 v[24:27], v[158:161], v[194:197], v[24:27]
	v_mfma_f32_16x16x32_bf16 v[12:15], v[150:153], v[206:209], v[12:15]
	v_mfma_f32_16x16x32_bf16 v[8:11], v[158:161], v[206:209], v[8:11]
	s_barrier
	s_setprio 0
	s_add_u32 s4, s4, 0x40080
	s_addc_u32 s5, s5, 0
	s_add_i32 s6, s6, s44
	s_mov_b32 m0, s6
	s_nop 0
	global_load_lds_dwordx4 v130, s[4:5]
	s_add_i32 m0, s6, 0x2000
	s_nop 0
	global_load_lds_dwordx4 v134, s[4:5]
	s_waitcnt vmcnt(8)
	s_setprio 1
	s_barrier
	v_mfma_f32_16x16x32_bf16 v[52:55], v[210:213], v[162:165], v[52:55]
	v_mfma_f32_16x16x32_bf16 v[48:51], v[218:221], v[162:165], v[48:51]
	v_mfma_f32_16x16x32_bf16 v[36:39], v[210:213], v[182:185], v[36:39]
	v_mfma_f32_16x16x32_bf16 v[32:35], v[218:221], v[182:185], v[32:35]
	v_mfma_f32_16x16x32_bf16 v[20:23], v[210:213], v[190:193], v[20:23]
	v_mfma_f32_16x16x32_bf16 v[16:19], v[218:221], v[190:193], v[16:19]
	v_mfma_f32_16x16x32_bf16 v[4:7], v[210:213], v[202:205], v[4:7]
	v_mfma_f32_16x16x32_bf16 v[0:3], v[218:221], v[202:205], v[0:3]
	v_mfma_f32_16x16x32_bf16 v[52:55], v[214:217], v[178:181], v[52:55]
	v_mfma_f32_16x16x32_bf16 v[48:51], v[222:225], v[178:181], v[48:51]
	v_mfma_f32_16x16x32_bf16 v[36:39], v[214:217], v[186:189], v[36:39]
	v_mfma_f32_16x16x32_bf16 v[32:35], v[222:225], v[186:189], v[32:35]
	v_mfma_f32_16x16x32_bf16 v[20:23], v[214:217], v[194:197], v[20:23]
	v_mfma_f32_16x16x32_bf16 v[16:19], v[222:225], v[194:197], v[16:19]
	v_mfma_f32_16x16x32_bf16 v[4:7], v[214:217], v[206:209], v[4:7]
	v_mfma_f32_16x16x32_bf16 v[0:3], v[222:225], v[206:209], v[0:3]
	s_barrier
	s_setprio 0
	s_add_i32 s67, s67, 2
	s_add_u32 s0, s0, 0x100
	s_addc_u32 s1, s1, 0
	s_add_u32 s65, s65, 0x100
	s_addc_u32 s66, s66, 0
	s_cmp_gt_u32 s67, 13
.LBB0_613:
	ds_read_b128 v[146:149], v171
	ds_read_b128 v[150:153], v171 offset:1024
	ds_read_b128 v[154:157], v171 offset:2048
	ds_read_b128 v[158:161], v171 offset:3072
	s_add_u32 s4, s0, 0xfffc0080
	s_addc_u32 s5, s1, -1
	s_cmp_eq_u32 s67, 12
	s_cselect_b32 s7, s8, s5
	s_cselect_b32 s6, s9, s4
	s_cselect_b32 s5, s31, s66
	s_cselect_b32 s4, s35, s65
	s_add_i32 m0, s45, 0xc000
	ds_read_b128 v[162:165], v172
	ds_read_b128 v[178:181], v172 offset:1024
	ds_read_b128 v[182:185], v172 offset:2048
	ds_read_b128 v[186:189], v172 offset:3072
	ds_read_b128 v[190:193], v172 offset:4096
	ds_read_b128 v[194:197], v172 offset:5120
	ds_read_b128 v[202:205], v172 offset:6144
	ds_read_b128 v[206:209], v172 offset:7168
	global_load_lds_dwordx4 v138, s[0:1]
	s_add_i32 m0, s45, 0xe000
	s_nop 0
	global_load_lds_dwordx4 v140, s[0:1]
	s_waitcnt lgkmcnt(8)
	s_waitcnt vmcnt(8)
	s_setprio 1
	s_barrier
	s_waitcnt lgkmcnt(0)
	v_mfma_f32_16x16x32_bf16 v[124:127], v[146:149], v[162:165], v[124:127]
	v_mfma_f32_16x16x32_bf16 v[120:123], v[154:157], v[162:165], v[120:123]
	v_mfma_f32_16x16x32_bf16 v[108:111], v[146:149], v[182:185], v[108:111]
	v_mfma_f32_16x16x32_bf16 v[104:107], v[154:157], v[182:185], v[104:107]
	v_mfma_f32_16x16x32_bf16 v[92:95], v[146:149], v[190:193], v[92:95]
	v_mfma_f32_16x16x32_bf16 v[88:91], v[154:157], v[190:193], v[88:91]
	v_mfma_f32_16x16x32_bf16 v[76:79], v[146:149], v[202:205], v[76:79]
	v_mfma_f32_16x16x32_bf16 v[72:75], v[154:157], v[202:205], v[72:75]
	v_mfma_f32_16x16x32_bf16 v[124:127], v[150:153], v[178:181], v[124:127]
	v_mfma_f32_16x16x32_bf16 v[120:123], v[158:161], v[178:181], v[120:123]
	v_mfma_f32_16x16x32_bf16 v[108:111], v[150:153], v[186:189], v[108:111]
	v_mfma_f32_16x16x32_bf16 v[104:107], v[158:161], v[186:189], v[104:107]
	v_mfma_f32_16x16x32_bf16 v[92:95], v[150:153], v[194:197], v[92:95]
	v_mfma_f32_16x16x32_bf16 v[88:91], v[158:161], v[194:197], v[88:91]
	v_mfma_f32_16x16x32_bf16 v[76:79], v[150:153], v[206:209], v[76:79]
	v_mfma_f32_16x16x32_bf16 v[72:75], v[158:161], v[206:209], v[72:75]
	s_barrier
	s_setprio 0
	s_add_i32 s68, s57, s44
	s_mov_b32 m0, s68
	ds_read_b128 v[210:213], v173
	ds_read_b128 v[214:217], v173 offset:1024
	ds_read_b128 v[218:221], v173 offset:2048
	ds_read_b128 v[222:225], v173 offset:3072
	global_load_lds_dwordx4 v130, s[4:5]
	s_add_i32 m0, s68, 0x2000
	s_nop 0
	global_load_lds_dwordx4 v134, s[4:5]
	s_waitcnt vmcnt(8)
	s_setprio 1
	s_barrier
; #define PG8_STAGE(bufoff, gbase, voff) do { _Pragma("unroll") for (int _i = 0; _i < 2; ++_i) \
;         __builtin_amdgcn_global_load_lds((const unsigned*)((const char*)(gbase) + (voff)[_i]), (LAS unsigned*)(lds + (bufoff) + ldsw + _i * 8192), 16, 0, 0); } while (0)
; #define PG8_LDA(dst, b, h) do { _Pragma("unroll") for (int m = 0; m < 4; ++m) _Pragma("unroll") for (int k = 0; k < 2; ++k) dst[m][k] = *(const LAS bf16x8*)(lds + PG8_SA(b, h) + aoff + m * 2048 + k * 1024); } while (0)
; #define PG8_LDB(dst, b, h) do { _Pragma("unroll") for (int n = 0; n < 2; ++n) _Pragma("unroll") for (int k = 0; k < 2; ++k) dst[n][k] = *(const LAS bf16x8*)(lds + PG8_SB(b, h) + boff + n * 2048 + k * 1024); } while (0)
; #define PG8_WAIT_V(n) asm volatile("s_waitcnt vmcnt(" #n ")" ::: "memory")
; #define PG8_WAIT_L(n) asm volatile("s_waitcnt lgkmcnt(" #n ")" ::: "memory")
; #define PG8_BAR __builtin_amdgcn_s_barrier()
; #define PG8_SCHED __builtin_amdgcn_sched_barrier(0)
; template <class Epi, class Sched>
; __device__ __forceinline__ void gemm_phase(LAS unsigned char* lds, const Gemm g, const Sched& S, const Epi& E) {
;     ...
;             PG8_LDB(B0, 0, 0); PG8_SCHED; PG8_LDA(At, 0, 0); PG8_STAGE(PG8_SA(1, 1), a1 + hstep, voffA);
;             PG8_WAIT_L(8); PG8_BAR; PG8_WAIT_L(0); PG8_MMA(0, 0, At, B0); PG8_BAR; PG8_SCHED;
;             PG8_LDB(B1, 0, 1); PG8_STAGE(PG8_SB(0, 0), b2, voffB);
;             PG8_BAR; PG8_WAIT_L(0); PG8_MMA(0, 1, At, B1); PG8_BAR;
;             PG8_LDA(At, 0, 1); PG8_STAGE(PG8_SA(0, 0), a2, voffA);
;             PG8_BAR; PG8_WAIT_L(0); PG8_MMA(1, 0, At, B0); PG8_BAR; PG8_SCHED;
;             PG8_STAGE(PG8_SB(0, 1), b2 + hstep, voffB);
;             PG8_WAIT_V(6); PG8_BAR; PG8_MMA(1, 1, At, B1); PG8_BAR;
;             PG8_LDB(B0, 1, 0); PG8_SCHED; PG8_LDA(At, 1, 0); PG8_STAGE(PG8_SA(0, 1), a2 + hstep, voffA);
;             PG8_WAIT_L(8); PG8_BAR; PG8_WAIT_L(0); PG8_MMA(0, 0, At, B0); PG8_BAR; PG8_SCHED;
;             PG8_LDB(B1, 1, 1); PG8_STAGE(PG8_SB(1, 0), b3, voffB);
;             PG8_BAR; PG8_WAIT_L(0); PG8_MMA(0, 1, At, B1); PG8_BAR;
;             PG8_LDA(At, 1, 1); PG8_STAGE(PG8_SA(1, 0), a3, voffA);
;             PG8_BAR; PG8_WAIT_L(0); PG8_MMA(1, 0, At, B0); PG8_BAR; PG8_SCHED;
;             PG8_STAGE(PG8_SB(1, 1), b3 + hstep, voffB);
;             PG8_WAIT_V(6); PG8_BAR; PG8_MMA(1, 1, At, B1); PG8_BAR;
	s_waitcnt lgkmcnt(0)
	v_mfma_f32_16x16x32_bf16 v[116:119], v[210:213], v[162:165], v[116:119]
	v_mfma_f32_16x16x32_bf16 v[112:115], v[218:221], v[162:165], v[112:115]
	v_mfma_f32_16x16x32_bf16 v[100:103], v[210:213], v[182:185], v[100:103]
	v_mfma_f32_16x16x32_bf16 v[96:99], v[218:221], v[182:185], v[96:99]
	v_mfma_f32_16x16x32_bf16 v[84:87], v[210:213], v[190:193], v[84:87]
	v_mfma_f32_16x16x32_bf16 v[80:83], v[218:221], v[190:193], v[80:83]
	v_mfma_f32_16x16x32_bf16 v[68:71], v[210:213], v[202:205], v[68:71]
	v_mfma_f32_16x16x32_bf16 v[64:67], v[218:221], v[202:205], v[64:67]
	v_mfma_f32_16x16x32_bf16 v[116:119], v[214:217], v[178:181], v[116:119]
	v_mfma_f32_16x16x32_bf16 v[112:115], v[222:225], v[178:181], v[112:115]
	v_mfma_f32_16x16x32_bf16 v[100:103], v[214:217], v[186:189], v[100:103]
	v_mfma_f32_16x16x32_bf16 v[96:99], v[222:225], v[186:189], v[96:99]
	v_mfma_f32_16x16x32_bf16 v[84:87], v[214:217], v[194:197], v[84:87]
	v_mfma_f32_16x16x32_bf16 v[80:83], v[222:225], v[194:197], v[80:83]
	v_mfma_f32_16x16x32_bf16 v[68:71], v[214:217], v[206:209], v[68:71]
	v_mfma_f32_16x16x32_bf16 v[64:67], v[222:225], v[206:209], v[64:67]
	s_barrier
	s_setprio 0
	s_mov_b32 m0, s45
	v_lshl_add_u64 v[226:227], s[6:7], 0, v[128:129]
	ds_read_b128 v[162:165], v172 offset:16384
	ds_read_b128 v[178:181], v172 offset:17408
	ds_read_b128 v[182:185], v172 offset:18432
	ds_read_b128 v[186:189], v172 offset:19456
	ds_read_b128 v[190:193], v172 offset:20480
	ds_read_b128 v[194:197], v172 offset:21504
	ds_read_b128 v[202:205], v172 offset:22528
	ds_read_b128 v[206:209], v172 offset:23552
	global_load_lds_dwordx4 v128, s[6:7]
	v_lshl_add_u64 v[228:229], s[6:7], 0, v[132:133]
	s_mov_b32 m0, s46
	s_nop 0
	global_load_lds_dwordx4 v132, s[6:7]
	s_setprio 1
	s_barrier
	s_waitcnt lgkmcnt(0)
	v_mfma_f32_16x16x32_bf16 v[60:63], v[146:149], v[162:165], v[60:63]
	v_mfma_f32_16x16x32_bf16 v[56:59], v[154:157], v[162:165], v[56:59]
	v_mfma_f32_16x16x32_bf16 v[44:47], v[146:149], v[182:185], v[44:47]
	v_mfma_f32_16x16x32_bf16 v[40:43], v[154:157], v[182:185], v[40:43]
	v_mfma_f32_16x16x32_bf16 v[28:31], v[146:149], v[190:193], v[28:31]
	v_mfma_f32_16x16x32_bf16 v[24:27], v[154:157], v[190:193], v[24:27]
	v_mfma_f32_16x16x32_bf16 v[12:15], v[146:149], v[202:205], v[12:15]
	v_mfma_f32_16x16x32_bf16 v[8:11], v[154:157], v[202:205], v[8:11]
	v_mfma_f32_16x16x32_bf16 v[60:63], v[150:153], v[178:181], v[60:63]
	v_mfma_f32_16x16x32_bf16 v[56:59], v[158:161], v[178:181], v[56:59]
	v_mfma_f32_16x16x32_bf16 v[44:47], v[150:153], v[186:189], v[44:47]
	v_mfma_f32_16x16x32_bf16 v[40:43], v[158:161], v[186:189], v[40:43]
	v_mfma_f32_16x16x32_bf16 v[28:31], v[150:153], v[194:197], v[28:31]
	v_mfma_f32_16x16x32_bf16 v[24:27], v[158:161], v[194:197], v[24:27]
	v_mfma_f32_16x16x32_bf16 v[12:15], v[150:153], v[206:209], v[12:15]
	v_mfma_f32_16x16x32_bf16 v[8:11], v[158:161], v[206:209], v[8:11]
	s_barrier
	s_setprio 0
	s_add_u32 s68, s4, 0x40000
	s_addc_u32 s69, s5, 0
	s_add_i32 s70, s58, s44
	s_mov_b32 m0, s70
	s_nop 0
	global_load_lds_dwordx4 v130, s[68:69]
	s_add_i32 m0, s70, 0x2000
	s_nop 0
	global_load_lds_dwordx4 v134, s[68:69]
	s_add_u32 s6, s6, 0x40000
	s_addc_u32 s7, s7, 0
	s_mov_b32 m0, s47
	s_nop 0
	global_load_lds_dwordx4 v128, s[6:7]
	s_mov_b32 m0, s48
	s_nop 0
	global_load_lds_dwordx4 v132, s[6:7]
	s_waitcnt vmcnt(10)
	s_setprio 1
	s_barrier
	v_mfma_f32_16x16x32_bf16 v[52:55], v[210:213], v[162:165], v[52:55]
	v_mfma_f32_16x16x32_bf16 v[48:51], v[218:221], v[162:165], v[48:51]
	v_mfma_f32_16x16x32_bf16 v[36:39], v[210:213], v[182:185], v[36:39]
	v_mfma_f32_16x16x32_bf16 v[32:35], v[218:221], v[182:185], v[32:35]
	v_mfma_f32_16x16x32_bf16 v[20:23], v[210:213], v[190:193], v[20:23]
	v_mfma_f32_16x16x32_bf16 v[16:19], v[218:221], v[190:193], v[16:19]
	v_mfma_f32_16x16x32_bf16 v[4:7], v[210:213], v[202:205], v[4:7]
	v_mfma_f32_16x16x32_bf16 v[0:3], v[218:221], v[202:205], v[0:3]
	v_mfma_f32_16x16x32_bf16 v[52:55], v[214:217], v[178:181], v[52:55]
	v_mfma_f32_16x16x32_bf16 v[48:51], v[222:225], v[178:181], v[48:51]
	v_mfma_f32_16x16x32_bf16 v[36:39], v[214:217], v[186:189], v[36:39]
	v_mfma_f32_16x16x32_bf16 v[32:35], v[222:225], v[186:189], v[32:35]
	v_mfma_f32_16x16x32_bf16 v[20:23], v[214:217], v[194:197], v[20:23]
	v_mfma_f32_16x16x32_bf16 v[16:19], v[222:225], v[194:197], v[16:19]
	v_mfma_f32_16x16x32_bf16 v[4:7], v[214:217], v[206:209], v[4:7]
	v_mfma_f32_16x16x32_bf16 v[0:3], v[222:225], v[206:209], v[0:3]
	s_barrier
	s_setprio 0
	s_add_i32 s68, 0, 0x18000
	ds_read_b128 v[146:149], v173 offset:16384
	ds_read_b128 v[150:153], v173 offset:17408
	ds_read_b128 v[154:157], v173 offset:18432
	ds_read_b128 v[158:161], v173 offset:19456
	ds_read_b128 v[162:165], v172 offset:32768
	ds_read_b128 v[178:181], v172 offset:33792
	ds_read_b128 v[182:185], v172 offset:34816
	ds_read_b128 v[186:189], v172 offset:35840
	ds_read_b128 v[190:193], v172 offset:36864
	ds_read_b128 v[194:197], v172 offset:37888
	ds_read_b128 v[202:205], v172 offset:38912
	ds_read_b128 v[206:209], v172 offset:39936
	s_waitcnt lgkmcnt(8)
	s_waitcnt vmcnt(8)
	s_setprio 1
	s_barrier
; #define PG8_STAGE(bufoff, gbase, voff) do { _Pragma("unroll") for (int _i = 0; _i < 2; ++_i) \
;         __builtin_amdgcn_global_load_lds((const unsigned*)((const char*)(gbase) + (voff)[_i]), (LAS unsigned*)(lds + (bufoff) + ldsw + _i * 8192), 16, 0, 0); } while (0)
; #define PG8_LDA(dst, b, h) do { _Pragma("unroll") for (int m = 0; m < 4; ++m) _Pragma("unroll") for (int k = 0; k < 2; ++k) dst[m][k] = *(const LAS bf16x8*)(lds + PG8_SA(b, h) + aoff + m * 2048 + k * 1024); } while (0)
; #define PG8_LDB(dst, b, h) do { _Pragma("unroll") for (int n = 0; n < 2; ++n) _Pragma("unroll") for (int k = 0; k < 2; ++k) dst[n][k] = *(const LAS bf16x8*)(lds + PG8_SB(b, h) + boff + n * 2048 + k * 1024); } while (0)
; #define PG8_WAIT_V(n) asm volatile("s_waitcnt vmcnt(" #n ")" ::: "memory")
; #define PG8_WAIT_L(n) asm volatile("s_waitcnt lgkmcnt(" #n ")" ::: "memory")
; #define PG8_BAR __builtin_amdgcn_s_barrier()
; #define PG8_SCHED __builtin_amdgcn_sched_barrier(0)
; template <class Epi, class Sched>
; __device__ __forceinline__ void gemm_phase(LAS unsigned char* lds, const Gemm g, const Sched& S, const Epi& E) {
;     ...
;             PG8_LDB(B0, 0, 0); PG8_SCHED; PG8_LDA(At, 0, 0); PG8_STAGE(PG8_SA(1, 1), a1 + hstep, voffA);
;             PG8_WAIT_L(8); PG8_BAR; PG8_WAIT_L(0); PG8_MMA(0, 0, At, B0); PG8_BAR; PG8_SCHED;
;             PG8_LDB(B1, 0, 1); PG8_STAGE(PG8_SB(0, 0), b2, voffB);
;             PG8_BAR; PG8_WAIT_L(0); PG8_MMA(0, 1, At, B1); PG8_BAR;
;             PG8_LDA(At, 0, 1); PG8_STAGE(PG8_SA(0, 0), a2, voffA);
;             PG8_BAR; PG8_WAIT_L(0); PG8_MMA(1, 0, At, B0); PG8_BAR; PG8_SCHED;
;             PG8_STAGE(PG8_SB(0, 1), b2 + hstep, voffB);
;             PG8_WAIT_V(6); PG8_BAR; PG8_MMA(1, 1, At, B1); PG8_BAR;
;             PG8_LDB(B0, 1, 0); PG8_SCHED; PG8_LDA(At, 1, 0); PG8_STAGE(PG8_SA(0, 1), a2 + hstep, voffA);
;             PG8_WAIT_L(8); PG8_BAR; PG8_WAIT_L(0); PG8_MMA(0, 0, At, B0); PG8_BAR; PG8_SCHED;
;             PG8_LDB(B1, 1, 1); PG8_STAGE(PG8_SB(1, 0), b3, voffB);
;             PG8_BAR; PG8_WAIT_L(0); PG8_MMA(0, 1, At, B1); PG8_BAR;
;             PG8_LDA(At, 1, 1); PG8_STAGE(PG8_SA(1, 0), a3, voffA);
;             PG8_BAR; PG8_WAIT_L(0); PG8_MMA(1, 0, At, B0); PG8_BAR; PG8_SCHED;
;             PG8_STAGE(PG8_SB(1, 1), b3 + hstep, voffB);
;             PG8_WAIT_V(6); PG8_BAR; PG8_MMA(1, 1, At, B1); PG8_BAR;
	s_waitcnt lgkmcnt(0)
	v_mfma_f32_16x16x32_bf16 v[124:127], v[146:149], v[162:165], v[124:127]
	v_mfma_f32_16x16x32_bf16 v[120:123], v[154:157], v[162:165], v[120:123]
	v_mfma_f32_16x16x32_bf16 v[108:111], v[146:149], v[182:185], v[108:111]
	v_mfma_f32_16x16x32_bf16 v[104:107], v[154:157], v[182:185], v[104:107]
	v_mfma_f32_16x16x32_bf16 v[92:95], v[146:149], v[190:193], v[92:95]
	v_mfma_f32_16x16x32_bf16 v[88:91], v[154:157], v[190:193], v[88:91]
	v_mfma_f32_16x16x32_bf16 v[76:79], v[146:149], v[202:205], v[76:79]
	v_mfma_f32_16x16x32_bf16 v[72:75], v[154:157], v[202:205], v[72:75]
	v_mfma_f32_16x16x32_bf16 v[124:127], v[150:153], v[178:181], v[124:127]
	v_mfma_f32_16x16x32_bf16 v[120:123], v[158:161], v[178:181], v[120:123]
	v_mfma_f32_16x16x32_bf16 v[108:111], v[150:153], v[186:189], v[108:111]
	v_mfma_f32_16x16x32_bf16 v[104:107], v[158:161], v[186:189], v[104:107]
	v_mfma_f32_16x16x32_bf16 v[92:95], v[150:153], v[194:197], v[92:95]
	v_mfma_f32_16x16x32_bf16 v[88:91], v[158:161], v[194:197], v[88:91]
	v_mfma_f32_16x16x32_bf16 v[76:79], v[150:153], v[206:209], v[76:79]
	v_mfma_f32_16x16x32_bf16 v[72:75], v[158:161], v[206:209], v[72:75]
	s_barrier
	s_setprio 0
	s_add_i32 s6, 0, 0x1c000
	s_add_i32 s7, s68, s44
	s_add_u32 s20, s4, 0x80
	s_addc_u32 s21, s5, 0
	s_mov_b32 m0, s7
	ds_read_b128 v[210:213], v173 offset:32768
	ds_read_b128 v[214:217], v173 offset:33792
	ds_read_b128 v[218:221], v173 offset:34816
	ds_read_b128 v[222:225], v173 offset:35840
	global_load_lds_dwordx4 v130, s[20:21]
	s_add_i32 m0, s7, 0x2000
	s_nop 0
	global_load_lds_dwordx4 v134, s[20:21]
	s_waitcnt vmcnt(8)
	s_setprio 1
	s_barrier
	s_waitcnt lgkmcnt(0)
	v_mfma_f32_16x16x32_bf16 v[116:119], v[210:213], v[162:165], v[116:119]
	v_mfma_f32_16x16x32_bf16 v[112:115], v[218:221], v[162:165], v[112:115]
	v_mfma_f32_16x16x32_bf16 v[100:103], v[210:213], v[182:185], v[100:103]
	v_mfma_f32_16x16x32_bf16 v[96:99], v[218:221], v[182:185], v[96:99]
	v_mfma_f32_16x16x32_bf16 v[84:87], v[210:213], v[190:193], v[84:87]
	v_mfma_f32_16x16x32_bf16 v[80:83], v[218:221], v[190:193], v[80:83]
	v_mfma_f32_16x16x32_bf16 v[68:71], v[210:213], v[202:205], v[68:71]
	v_mfma_f32_16x16x32_bf16 v[64:67], v[218:221], v[202:205], v[64:67]
	v_mfma_f32_16x16x32_bf16 v[116:119], v[214:217], v[178:181], v[116:119]
	v_mfma_f32_16x16x32_bf16 v[112:115], v[222:225], v[178:181], v[112:115]
	v_mfma_f32_16x16x32_bf16 v[100:103], v[214:217], v[186:189], v[100:103]
	v_mfma_f32_16x16x32_bf16 v[96:99], v[222:225], v[186:189], v[96:99]
	v_mfma_f32_16x16x32_bf16 v[84:87], v[214:217], v[194:197], v[84:87]
	v_mfma_f32_16x16x32_bf16 v[80:83], v[222:225], v[194:197], v[80:83]
	v_mfma_f32_16x16x32_bf16 v[68:71], v[214:217], v[206:209], v[68:71]
	v_mfma_f32_16x16x32_bf16 v[64:67], v[222:225], v[206:209], v[64:67]
	s_barrier
	s_setprio 0
	s_mov_b32 m0, s54
	s_mov_b64 s[20:21], 0x80
	v_lshl_add_u64 v[166:167], v[226:227], 0, s[20:21]
	ds_read_b128 v[162:165], v172 offset:49152
	ds_read_b128 v[178:181], v172 offset:50176
	ds_read_b128 v[182:185], v172 offset:51200
	ds_read_b128 v[186:189], v172 offset:52224
	ds_read_b128 v[190:193], v172 offset:53248
	ds_read_b128 v[194:197], v172 offset:54272
	ds_read_b128 v[202:205], v172 offset:55296
	ds_read_b128 v[206:209], v172 offset:56320
	global_load_lds_dwordx4 v[166:167], off
	v_lshl_add_u64 v[166:167], v[228:229], 0, s[20:21]
	s_mov_b32 m0, s55
	s_nop 0
	global_load_lds_dwordx4 v[166:167], off
	s_setprio 1
	s_barrier
	s_waitcnt lgkmcnt(0)
	v_mfma_f32_16x16x32_bf16 v[60:63], v[146:149], v[162:165], v[60:63]
	v_mfma_f32_16x16x32_bf16 v[56:59], v[154:157], v[162:165], v[56:59]
	v_mfma_f32_16x16x32_bf16 v[44:47], v[146:149], v[182:185], v[44:47]
	v_mfma_f32_16x16x32_bf16 v[40:43], v[154:157], v[182:185], v[40:43]
	v_mfma_f32_16x16x32_bf16 v[28:31], v[146:149], v[190:193], v[28:31]
	v_mfma_f32_16x16x32_bf16 v[24:27], v[154:157], v[190:193], v[24:27]
	v_mfma_f32_16x16x32_bf16 v[12:15], v[146:149], v[202:205], v[12:15]
	v_mfma_f32_16x16x32_bf16 v[8:11], v[154:157], v[202:205], v[8:11]
	v_mfma_f32_16x16x32_bf16 v[60:63], v[150:153], v[178:181], v[60:63]
	v_mfma_f32_16x16x32_bf16 v[56:59], v[158:161], v[178:181], v[56:59]
	v_mfma_f32_16x16x32_bf16 v[44:47], v[150:153], v[186:189], v[44:47]
	v_mfma_f32_16x16x32_bf16 v[40:43], v[158:161], v[186:189], v[40:43]
	v_mfma_f32_16x16x32_bf16 v[28:31], v[150:153], v[194:197], v[28:31]
	v_mfma_f32_16x16x32_bf16 v[24:27], v[158:161], v[194:197], v[24:27]
	v_mfma_f32_16x16x32_bf16 v[12:15], v[150:153], v[206:209], v[12:15]
	v_mfma_f32_16x16x32_bf16 v[8:11], v[158:161], v[206:209], v[8:11]
	s_barrier
	s_setprio 0
	s_add_u32 s4, s4, 0x40080
	s_addc_u32 s5, s5, 0
	s_add_i32 s6, s6, s44
	s_mov_b32 m0, s6
	s_nop 0
	global_load_lds_dwordx4 v130, s[4:5]
	s_add_i32 m0, s6, 0x2000
	s_nop 0
	global_load_lds_dwordx4 v134, s[4:5]
	s_waitcnt vmcnt(8)
	s_setprio 1
	s_barrier
	v_mfma_f32_16x16x32_bf16 v[52:55], v[210:213], v[162:165], v[52:55]
	v_mfma_f32_16x16x32_bf16 v[48:51], v[218:221], v[162:165], v[48:51]
	v_mfma_f32_16x16x32_bf16 v[36:39], v[210:213], v[182:185], v[36:39]
	v_mfma_f32_16x16x32_bf16 v[32:35], v[218:221], v[182:185], v[32:35]
	v_mfma_f32_16x16x32_bf16 v[20:23], v[210:213], v[190:193], v[20:23]
	v_mfma_f32_16x16x32_bf16 v[16:19], v[218:221], v[190:193], v[16:19]
	v_mfma_f32_16x16x32_bf16 v[4:7], v[210:213], v[202:205], v[4:7]
	v_mfma_f32_16x16x32_bf16 v[0:3], v[218:221], v[202:205], v[0:3]
	v_mfma_f32_16x16x32_bf16 v[52:55], v[214:217], v[178:181], v[52:55]
	v_mfma_f32_16x16x32_bf16 v[48:51], v[222:225], v[178:181], v[48:51]
	v_mfma_f32_16x16x32_bf16 v[36:39], v[214:217], v[186:189], v[36:39]
	v_mfma_f32_16x16x32_bf16 v[32:35], v[222:225], v[186:189], v[32:35]
	v_mfma_f32_16x16x32_bf16 v[20:23], v[214:217], v[194:197], v[20:23]
	v_mfma_f32_16x16x32_bf16 v[16:19], v[222:225], v[194:197], v[16:19]
	v_mfma_f32_16x16x32_bf16 v[4:7], v[214:217], v[206:209], v[4:7]
	v_mfma_f32_16x16x32_bf16 v[0:3], v[222:225], v[206:209], v[0:3]
	s_barrier
;     __device__ __forceinline__ void operator()(const AccT& acc, const Unit& u, int wr, int wc, int fr, int fq) const {
;         asm volatile("" : "+v"(fr), "+v"(fq));
;         const int rbase = wr * 64 + fr;
;         const int tb = u.pn * 256 + wc * 32 + 8 * fq;
;         const int o0 = wc * 32 + 8 * fq;
;         const int j = fr & 3; const float sgn = ((fr >> 2) & 1) ? 1.0f : -1.0f;
; #pragma unroll
;         for (int ai = 0; ai < 2; ++ai) {
;             const int hh = 2 * ai + wr;
;             const float l2f = lgd[hh] * 1.4426950408889634f, l2b = lgd[4 + hh] * 1.4426950408889634f;
;             const float zf0 = exp2f((float)(127 - o0) * l2f), zfs = exp2f(-l2f), zb0 = exp2f((float)o0 * l2b), zbs = exp2f(l2b);
; #pragma unroll
;             for (int m = 0; m < 4; ++m) {
;                 const int r = rbase + ai * 128 + m * 16;
;                 const int d = 4 * (2 * m + (fr >> 3)) + j;
; #pragma unroll
;                 for (int bj = 0; bj < 2; ++bj) {
;                     const int t0 = tb + bj * 128;
;                     float v[8];
; #pragma unroll
;                     for (int jj = 0; jj < 4; ++jj) { v[jj] = acc[ai][bj][m][0][jj]; v[4 + jj] = acc[ai][bj][m][1][jj]; }
;                     if constexpr (ROPE) {
;                         const int t = t0 & 2047;
; #pragma unroll
;                         for (int hf = 0; hf < 2; ++hf) {
;                             f32x4 cs, sn;
;                             if (m < 2) { const float c1 = ropeA[(t >> 6) * 16 + d], s1 = ropeA[1024 + (t >> 6) * 16 + d]; cs = (f32x4){c1, c1, c1, c1}; sn = (f32x4){s1, s1, s1, s1}; }
;                             else { const float* cb = ropeA + 2048 + (d - 16) * 64 + (t & 63) + 4 * hf; cs = *(const f32x4*)(cb); sn = *(const f32x4*)(cb + 1024); }
; #pragma unroll
;                             for (int jj = 0; jj < 4; ++jj) { const float pr = __shfl_xor(v[4 * hf + jj], 4); v[4 * hf + jj] = v[4 * hf + jj] * cs[jj] + sgn * pr * sn[jj]; }
;                             __builtin_amdgcn_sched_barrier(0);
;                         }
;                     }
;                     float zf[8], zb[8]; zf[0] = zf0; zb[0] = zb0;
; #pragma unroll
;                     for (int jj = 1; jj < 8; ++jj) { zf[jj] = zf[jj - 1] * zfs; zb[jj] = zb[jj - 1] * zbs; }
;                     u32x4 wf, wb;
	s_setprio 0
	s_add_i32 s67, s67, 2
	s_add_u32 s0, s0, 0x100
	s_addc_u32 s1, s1, 0
	s_add_u32 s65, s65, 0x100
	s_addc_u32 s66, s66, 0
	s_cmp_gt_u32 s67, 13
	s_cbranch_scc0 .LBB0_613
	v_mov_b32_e32 v136, v169
	v_mov_b32_e32 v150, v168
	s_lshl_b32 s0, s33, 8
	global_load_dword v154, v137, s[22:23]
	global_load_dword v155, v137, s[22:23] offset:16
	s_or_b32 s0, s0, s53
	v_lshlrev_b32_e32 v151, 3, v136
	v_ashrrev_i32_e32 v136, 1, v150
	v_add_u32_e32 v162, s0, v151
	v_bfi_b32 v136, -4, v136, v150
	v_lshrrev_b32_e32 v146, 2, v162
	v_add_u32_e32 v192, 0x400, v136
	v_and_b32_e32 v187, 0x1f0, v146
	v_add_u32_e32 v146, v192, v187
	v_add_u32_e32 v148, v187, v136
	v_ashrrev_i32_e32 v147, 31, v146
	v_ashrrev_i32_e32 v149, 31, v148
	v_lshl_add_u64 v[146:147], v[146:147], 2, s[16:17]
	v_lshl_add_u64 v[148:149], v[148:149], 2, s[16:17]
	global_load_dword v153, v[146:147], off
	global_load_dword v166, v[148:149], off
	v_and_b32_e32 v157, 64, v174
	v_xor_b32_e32 v156, 4, v174
	v_add_u32_e32 v157, 64, v157
	v_cmp_lt_i32_e32 vcc, v156, v157
	v_mov_b32_e32 v152, v124
	v_add_u32_e32 v151, s53, v151
	v_cndmask_b32_e32 v156, v174, v156, vcc
	v_lshlrev_b32_e32 v177, 2, v156
	ds_bpermute_b32 v124, v177, v124
	v_sub_u32_e32 v156, 0x7f, v151
	v_add_u32_e32 v164, s52, v150
	v_and_b32_e32 v150, 4, v150
	v_cvt_f32_i32_e32 v179, v156
	v_cvt_f32_i32_e32 v178, v151
	v_cmp_eq_u32_e32 vcc, 0, v150
	ds_bpermute_b32 v157, v177, v125
	ds_bpermute_b32 v158, v177, v127
	s_waitcnt lgkmcnt(0)
	v_cndmask_b32_e64 v167, v124, -v124, vcc
	ds_bpermute_b32 v151, v177, v126
	v_ashrrev_i32_e32 v165, 31, v164
	v_and_b32_e32 v186, 56, v162
	s_waitcnt lgkmcnt(0)
	v_cndmask_b32_e64 v151, v151, -v151, vcc
	s_waitcnt vmcnt(0)
	v_mul_f32_e32 v124, 0x3fb8aa3b, v154
	v_mul_f32_e32 v150, 0x3fb8aa3b, v155
	v_cmp_lt_f32_e64 s[4:5], s60, v124
	v_mul_f32_e32 v156, v124, v179
	v_cmp_gt_f32_e64 s[6:7], s59, v150
	v_cndmask_b32_e64 v159, 0, v176, s[4:5]
	v_mul_f32_e32 v160, v150, v178
	v_cndmask_b32_e64 v161, 0, v176, s[6:7]
	v_cmp_gt_f32_e64 s[8:9], s59, v156
	v_fmac_f32_e32 v159, 0xbfb8aa3b, v154
	s_and_b64 s[0:1], s[4:5], exec
	v_cmp_gt_f32_e64 s[4:5], s59, v160
	v_fmac_f32_e32 v161, 0x3fb8aa3b, v155
	v_cndmask_b32_e64 v154, 0, v176, s[8:9]
	v_exp_f32_e32 v155, v159
	v_cndmask_b32_e64 v159, 0, v176, s[4:5]
	v_fmac_f32_e32 v154, v124, v179
	v_fmac_f32_e32 v159, v150, v178
	v_exp_f32_e32 v150, v154
	v_cndmask_b32_e64 v156, 0, v175, s[8:9]
	s_cselect_b32 s8, 0xffffffc0, 0
	v_exp_f32_e32 v161, v161
	v_exp_f32_e32 v159, v159
	v_ldexp_f32 v163, v155, s8
	v_pk_mul_f32 v[154:155], v[152:153], v[166:167]
	v_cndmask_b32_e64 v167, v157, -v157, vcc
	v_mov_b32_e32 v152, v125
	s_and_b64 s[0:1], s[6:7], exec
	v_add_f32_e32 v190, v154, v155
	v_pk_mul_f32 v[154:155], v[152:153], v[166:167]
	v_cndmask_b32_e64 v167, v158, -v158, vcc
	v_mov_b32_e32 v152, v127
	v_cndmask_b32_e64 v160, 0, v175, s[4:5]
	s_cselect_b32 s0, 0xffffffc0, 0
	v_ldexp_f32 v180, v150, v156
	v_add_f32_e32 v191, v154, v155
	v_pk_mul_f32 v[154:155], v[152:153], v[166:167]
	v_ldexp_f32 v124, v161, s0
	v_mul_f32_e32 v161, v126, v166
	v_ldexp_f32 v150, v159, v160
	v_mul_f32_e32 v181, v163, v180
	v_add_f32_e32 v193, v154, v155
	global_load_dword v188, v[148:149], off
	global_load_dword v157, v[146:147], off
	ds_bpermute_b32 v127, v177, v121
	v_mov_b32_e32 v156, v121
	ds_bpermute_b32 v121, v177, v123
	ds_bpermute_b32 v125, v177, v120
	ds_bpermute_b32 v152, v177, v122
	s_waitcnt lgkmcnt(3)
	v_cndmask_b32_e64 v189, v127, -v127, vcc
	s_waitcnt lgkmcnt(1)
	v_cndmask_b32_e64 v158, v125, -v125, vcc
	s_waitcnt lgkmcnt(0)
	v_cndmask_b32_e64 v127, v152, -v152, vcc
	s_waitcnt vmcnt(1)
	v_mul_f32_e32 v159, v120, v188
	s_waitcnt vmcnt(0)
	v_pk_mul_f32 v[154:155], v[156:157], v[188:189]
	v_cndmask_b32_e64 v189, v121, -v121, vcc
	v_mov_b32_e32 v156, v123
	v_add_f32_e32 v121, v154, v155
	v_pk_mul_f32 v[154:155], v[156:157], v[188:189]
	s_nop 0
	v_add_f32_e32 v123, v154, v155
	v_mov_b32_e32 v125, v153
	v_pk_mul_f32 v[152:153], v[124:125], v[150:151]
	v_mov_b32_e32 v125, v161
	v_pk_mul_f32 v[154:155], v[124:125], v[152:153]
	v_mov_b32_e32 v125, v157
	v_mov_b32_e32 v155, v158
	v_pk_mul_f32 v[156:157], v[124:125], v[154:155]
	v_mov_b32_e32 v158, v124
	v_pk_mul_f32 v[158:159], v[158:159], v[156:157]
	v_mul_f32_e32 v167, v163, v181
	v_mov_b32_e32 v159, v127
	v_mul_f32_e32 v183, v163, v167
	v_pk_mul_f32 v[160:161], v[124:125], v[158:159]
	v_mul_f32_e32 v182, v163, v183
	v_mul_f32_e32 v151, v124, v160
	v_mul_f32_e32 v185, v163, v182
	v_mul_f32_e32 v155, v124, v151
	v_mul_f32_e32 v124, v180, v190
	v_mul_f32_e32 v125, v181, v191
	v_fma_f32 v153, v126, v166, v153
	v_mul_f32_e32 v184, v163, v185
	v_cvt_pk_bf16_f32 v124, v124, v125
	v_mul_f32_e32 v125, v167, v153
	v_mul_f32_e32 v126, v183, v193
	v_fma_f32 v120, v120, v188, v157
	v_mul_f32_e32 v159, v163, v184
	v_cvt_pk_bf16_f32 v125, v125, v126
	v_mul_f32_e32 v126, v182, v120
	v_mul_f32_e32 v127, v185, v121
	v_fma_f32 v122, v122, v188, v161
	v_cvt_pk_bf16_f32 v126, v126, v127
	v_mul_f32_e32 v127, v184, v122
	v_mul_f32_e32 v157, v159, v123
	v_cvt_pk_bf16_f32 v127, v127, v157
	v_mul_f32_e32 v157, v150, v190
	v_mul_f32_e32 v120, v158, v120
	v_mul_f32_e32 v121, v160, v121
	v_mul_f32_e32 v161, v152, v191
	v_cvt_pk_bf16_f32 v188, v157, v161
	v_mul_f32_e32 v153, v154, v153
	v_mul_f32_e32 v157, v156, v193
	v_cvt_pk_bf16_f32 v189, v153, v157
	v_cvt_pk_bf16_f32 v190, v120, v121
	v_mul_f32_e32 v120, v151, v122
	v_mul_f32_e32 v121, v155, v123
	v_cvt_pk_bf16_f32 v191, v120, v121
	v_lshlrev_b64 v[120:121], 17, v[164:165]
	v_lshl_add_u64 v[120:121], s[80:81], 0, v[120:121]
	v_ashrrev_i32_e32 v163, 31, v162
	v_lshl_add_u64 v[120:121], v[162:163], 1, v[120:121]
	s_mov_b64 s[0:1], 0x2000000
	global_store_dwordx4 v[120:121], v[124:127], off
	s_nop 1
	v_lshl_add_u64 v[126:127], v[120:121], 0, s[0:1]
	s_brev_b32 s0, 64
	v_add_co_u32_e64 v122, s[4:5], s0, v120
	s_nop 1
	v_addc_co_u32_e64 v123, s[4:5], 0, v121, s[4:5]
	global_store_dwordx4 v[122:123], v[188:191], off
	v_add_u32_e32 v122, 0x80, v162
	v_lshrrev_b32_e32 v122, 2, v122
	v_and_b32_e32 v153, 0x1f0, v122
	v_add_u32_e32 v122, v153, v192
	v_add_u32_e32 v124, v153, v136
	v_ashrrev_i32_e32 v123, 31, v122
	v_ashrrev_i32_e32 v125, 31, v124
	v_lshl_add_u64 v[122:123], v[122:123], 2, s[16:17]
	v_lshl_add_u64 v[124:125], v[124:125], 2, s[16:17]
	global_load_dword v163, v[122:123], off
	global_load_dword v164, v[124:125], off
	ds_bpermute_b32 v157, v177, v116
	v_mov_b32_e32 v162, v116
	ds_bpermute_b32 v116, v177, v117
	ds_bpermute_b32 v161, v177, v118
	ds_bpermute_b32 v166, v177, v119
	s_waitcnt lgkmcnt(3)
;     __device__ __forceinline__ void operator()(const AccT& acc, const Unit& u, int wr, int wc, int fr, int fq) const {
;     ...
;             for (int m = 0; m < 4; ++m) {
;                 const int r = rbase + ai * 128 + m * 16;
;                 const int d = 4 * (2 * m + (fr >> 3)) + j;
; #pragma unroll
;                 for (int bj = 0; bj < 2; ++bj) {
;                     const int t0 = tb + bj * 128;
;                     float v[8];
; #pragma unroll
;                     for (int jj = 0; jj < 4; ++jj) { v[jj] = acc[ai][bj][m][0][jj]; v[4 + jj] = acc[ai][bj][m][1][jj]; }
;                     if constexpr (ROPE) {
;                         const int t = t0 & 2047;
; #pragma unroll
;                         for (int hf = 0; hf < 2; ++hf) {
;                             f32x4 cs, sn;
;                             if (m < 2) { const float c1 = ropeA[(t >> 6) * 16 + d], s1 = ropeA[1024 + (t >> 6) * 16 + d]; cs = (f32x4){c1, c1, c1, c1}; sn = (f32x4){s1, s1, s1, s1}; }
;                             else { const float* cb = ropeA + 2048 + (d - 16) * 64 + (t & 63) + 4 * hf; cs = *(const f32x4*)(cb); sn = *(const f32x4*)(cb + 1024); }
; #pragma unroll
;                             for (int jj = 0; jj < 4; ++jj) { const float pr = __shfl_xor(v[4 * hf + jj], 4); v[4 * hf + jj] = v[4 * hf + jj] * cs[jj] + sgn * pr * sn[jj]; }
;                             __builtin_amdgcn_sched_barrier(0);
;                         }
;                     }
;                     float zf[8], zb[8]; zf[0] = zf0; zb[0] = zb0;
; #pragma unroll
;                     for (int jj = 1; jj < 8; ++jj) { zf[jj] = zf[jj - 1] * zfs; zb[jj] = zb[jj - 1] * zbs; }
;                     u32x4 wf, wb;
;                     wf.x = cvt_pk_bf16(v[0] * zf[0], v[1] * zf[1]); wf.y = cvt_pk_bf16(v[2] * zf[2], v[3] * zf[3]); wf.z = cvt_pk_bf16(v[4] * zf[4], v[5] * zf[5]); wf.w = cvt_pk_bf16(v[6] * zf[6], v[7] * zf[7]);
;                     wb.x = cvt_pk_bf16(v[0] * zb[0], v[1] * zb[1]); wb.y = cvt_pk_bf16(v[2] * zb[2], v[3] * zb[3]); wb.z = cvt_pk_bf16(v[4] * zb[4], v[5] * zb[5]); wb.w = cvt_pk_bf16(v[6] * zb[6], v[7] * zb[7]);
;                     *(u32x4*)(KTZ + (size_t)r * NT + t0) = wf;
;                     *(u32x4*)(KTZ + (size_t)(256 + r) * NT + t0) = wb;
;                     __builtin_amdgcn_sched_barrier(0);
	v_cndmask_b32_e64 v165, v157, -v157, vcc
	s_waitcnt vmcnt(0)
	v_pk_mul_f32 v[188:189], v[162:163], v[164:165]
	s_waitcnt lgkmcnt(2)
	v_cndmask_b32_e64 v165, v116, -v116, vcc
	v_mov_b32_e32 v162, v117
	v_pk_mul_f32 v[116:117], v[162:163], v[164:165]
	s_waitcnt lgkmcnt(1)
	v_cndmask_b32_e64 v165, v161, -v161, vcc
	v_mov_b32_e32 v162, v118
	v_add_f32_e32 v161, v116, v117
	v_pk_mul_f32 v[116:117], v[162:163], v[164:165]
	s_waitcnt lgkmcnt(0)
	v_cndmask_b32_e64 v165, v166, -v166, vcc
	v_mov_b32_e32 v162, v119
	v_add_f32_e32 v166, v116, v117
	v_pk_mul_f32 v[116:117], v[162:163], v[164:165]
	v_add_f32_e32 v157, v188, v189
	v_add_f32_e32 v164, v116, v117
	global_load_dword v117, v[122:123], off
	global_load_dword v118, v[124:125], off
	ds_bpermute_b32 v119, v177, v112
	v_mov_b32_e32 v116, v112
	ds_bpermute_b32 v112, v177, v113
	ds_bpermute_b32 v165, v177, v114
	ds_bpermute_b32 v188, v177, v115
	s_waitcnt lgkmcnt(3)
	v_cndmask_b32_e64 v119, v119, -v119, vcc
	s_waitcnt vmcnt(0)
	v_pk_mul_f32 v[162:163], v[116:117], v[118:119]
	s_waitcnt lgkmcnt(2)
	v_cndmask_b32_e64 v119, v112, -v112, vcc
	v_mov_b32_e32 v116, v113
	v_pk_mul_f32 v[112:113], v[116:117], v[118:119]
	s_waitcnt lgkmcnt(1)
	v_cndmask_b32_e64 v119, v165, -v165, vcc
	v_mov_b32_e32 v116, v114
	v_add_f32_e32 v162, v162, v163
	v_add_f32_e32 v163, v112, v113
	v_pk_mul_f32 v[112:113], v[116:117], v[118:119]
	s_waitcnt lgkmcnt(0)
	v_cndmask_b32_e64 v119, v188, -v188, vcc
	v_mov_b32_e32 v116, v115
	v_add_f32_e32 v165, v112, v113
	v_pk_mul_f32 v[112:113], v[116:117], v[118:119]
	s_nop 0
	v_add_f32_e32 v119, v112, v113
	v_mul_f32_e32 v112, v180, v157
	v_mul_f32_e32 v113, v181, v161
	v_cvt_pk_bf16_f32 v112, v112, v113
	v_mul_f32_e32 v113, v167, v166
	v_mul_f32_e32 v114, v183, v164
	v_cvt_pk_bf16_f32 v113, v113, v114
	v_mul_f32_e32 v114, v182, v162
	v_mul_f32_e32 v115, v185, v163
	v_cvt_pk_bf16_f32 v114, v114, v115
	v_mul_f32_e32 v115, v184, v165
	v_mul_f32_e32 v116, v159, v119
	v_cvt_pk_bf16_f32 v115, v115, v116
	v_mul_f32_e32 v116, v150, v157
	v_mul_f32_e32 v117, v152, v161
	v_cvt_pk_bf16_f32 v116, v116, v117
	v_mul_f32_e32 v117, v154, v166
	v_mul_f32_e32 v118, v156, v164
	v_cvt_pk_bf16_f32 v117, v117, v118
	v_mul_f32_e32 v118, v158, v162
	v_mul_f32_e32 v157, v160, v163
	v_mul_f32_e32 v119, v155, v119
	v_cvt_pk_bf16_f32 v118, v118, v157
	v_mul_f32_e32 v157, v151, v165
	v_cvt_pk_bf16_f32 v119, v157, v119
	global_store_dwordx4 v[120:121], v[112:115], off offset:256
	global_store_dwordx4 v[126:127], v[116:119], off offset:256
	v_add_u32_e32 v161, 0x408, v136
	v_add_u32_e32 v157, 8, v136
	v_add_u32_e32 v112, v161, v187
	v_add_u32_e32 v114, v187, v157
	v_ashrrev_i32_e32 v113, 31, v112
	v_ashrrev_i32_e32 v115, 31, v114
	v_lshl_add_u64 v[112:113], v[112:113], 2, s[16:17]
	v_lshl_add_u64 v[114:115], v[114:115], 2, s[16:17]
	global_load_dword v117, v[112:113], off
	global_load_dword v118, v[114:115], off
	ds_bpermute_b32 v119, v177, v108
	v_mov_b32_e32 v116, v108
	ds_bpermute_b32 v108, v177, v109
	ds_bpermute_b32 v162, v177, v110
	ds_bpermute_b32 v163, v177, v111
	s_waitcnt lgkmcnt(3)
	v_cndmask_b32_e64 v119, v119, -v119, vcc
	s_waitcnt vmcnt(0)
	v_pk_mul_f32 v[126:127], v[116:117], v[118:119]
	s_waitcnt lgkmcnt(2)
	v_cndmask_b32_e64 v119, v108, -v108, vcc
	v_mov_b32_e32 v116, v109
	v_pk_mul_f32 v[108:109], v[116:117], v[118:119]
	s_waitcnt lgkmcnt(1)
	v_cndmask_b32_e64 v119, v162, -v162, vcc
	v_mov_b32_e32 v116, v110
	v_add_f32_e32 v126, v126, v127
	v_add_f32_e32 v127, v108, v109
	v_pk_mul_f32 v[108:109], v[116:117], v[118:119]
	s_waitcnt lgkmcnt(0)
	v_cndmask_b32_e64 v119, v163, -v163, vcc
	v_mov_b32_e32 v116, v111
	v_add_f32_e32 v162, v108, v109
	v_pk_mul_f32 v[108:109], v[116:117], v[118:119]
	s_nop 0
	v_add_f32_e32 v118, v108, v109
	global_load_dword v109, v[112:113], off
	global_load_dword v110, v[114:115], off
	ds_bpermute_b32 v111, v177, v104
	v_mov_b32_e32 v108, v104
	ds_bpermute_b32 v104, v177, v105
	ds_bpermute_b32 v119, v177, v106
	ds_bpermute_b32 v163, v177, v107
	s_waitcnt lgkmcnt(3)
	v_cndmask_b32_e64 v111, v111, -v111, vcc
	s_waitcnt vmcnt(0)
	v_pk_mul_f32 v[116:117], v[108:109], v[110:111]
	s_waitcnt lgkmcnt(2)
	v_cndmask_b32_e64 v111, v104, -v104, vcc
	v_mov_b32_e32 v108, v105
	v_pk_mul_f32 v[104:105], v[108:109], v[110:111]
	s_waitcnt lgkmcnt(1)
	v_cndmask_b32_e64 v111, v119, -v119, vcc
	v_mov_b32_e32 v108, v106
	v_add_f32_e32 v119, v104, v105
	v_pk_mul_f32 v[104:105], v[108:109], v[110:111]
	s_waitcnt lgkmcnt(0)
	v_cndmask_b32_e64 v111, v163, -v163, vcc
	v_mov_b32_e32 v108, v107
	v_add_f32_e32 v163, v104, v105
	v_pk_mul_f32 v[104:105], v[108:109], v[110:111]
	v_add_f32_e32 v164, v116, v117
	v_add_f32_e32 v108, v104, v105
	v_mul_f32_e32 v104, v180, v126
	v_mul_f32_e32 v105, v181, v127
	v_cvt_pk_bf16_f32 v104, v104, v105
	v_mul_f32_e32 v105, v167, v162
	v_mul_f32_e32 v106, v183, v118
	v_cvt_pk_bf16_f32 v105, v105, v106
	v_mul_f32_e32 v106, v182, v164
	v_mul_f32_e32 v107, v185, v119
	v_cvt_pk_bf16_f32 v106, v106, v107
	v_mul_f32_e32 v107, v184, v163
	v_mul_f32_e32 v109, v159, v108
	v_cvt_pk_bf16_f32 v107, v107, v109
	v_mul_f32_e32 v109, v150, v126
	v_mul_f32_e32 v110, v152, v127
	v_cvt_pk_bf16_f32 v116, v109, v110
	v_mul_f32_e32 v109, v154, v162
	v_mul_f32_e32 v110, v156, v118
	v_cvt_pk_bf16_f32 v117, v109, v110
	v_mul_f32_e32 v109, v158, v164
	v_mul_f32_e32 v110, v160, v119
	v_cvt_pk_bf16_f32 v118, v109, v110
	v_mul_f32_e32 v109, v151, v163
	v_mul_f32_e32 v108, v155, v108
	s_mov_b64 s[0:1], 0x200000
	v_cvt_pk_bf16_f32 v119, v109, v108
	v_lshl_add_u64 v[108:109], v[120:121], 0, s[0:1]
	s_mov_b32 s0, 0x200000
	v_add_co_u32_e64 v110, s[4:5], s0, v120
	s_mov_b64 s[0:1], 0x2200000
	s_nop 0
	v_addc_co_u32_e64 v111, s[4:5], 0, v121, s[4:5]
	global_store_dwordx4 v[110:111], v[104:107], off
	v_lshl_add_u64 v[110:111], v[120:121], 0, s[0:1]
	s_mov_b32 s0, 0x2200000
	v_add_co_u32_e64 v104, s[4:5], s0, v120
	s_nop 1
	v_addc_co_u32_e64 v105, s[4:5], 0, v121, s[4:5]
	global_store_dwordx4 v[104:105], v[116:119], off
	v_add_u32_e32 v104, v153, v161
	v_add_u32_e32 v106, v153, v157
	v_ashrrev_i32_e32 v105, 31, v104
	v_ashrrev_i32_e32 v107, 31, v106
	v_lshl_add_u64 v[104:105], v[104:105], 2, s[16:17]
	v_lshl_add_u64 v[106:107], v[106:107], 2, s[16:17]
	global_load_dword v117, v[104:105], off
	global_load_dword v118, v[106:107], off
	ds_bpermute_b32 v119, v177, v100
	v_mov_b32_e32 v116, v100
	ds_bpermute_b32 v100, v177, v101
	ds_bpermute_b32 v153, v177, v102
	ds_bpermute_b32 v157, v177, v103
	s_waitcnt lgkmcnt(3)
;     __device__ __forceinline__ void operator()(const AccT& acc, const Unit& u, int wr, int wc, int fr, int fq) const {
;     ...
;             for (int m = 0; m < 4; ++m) {
;                 const int r = rbase + ai * 128 + m * 16;
;                 const int d = 4 * (2 * m + (fr >> 3)) + j;
; #pragma unroll
;                 for (int bj = 0; bj < 2; ++bj) {
;                     const int t0 = tb + bj * 128;
;                     float v[8];
; #pragma unroll
;                     for (int jj = 0; jj < 4; ++jj) { v[jj] = acc[ai][bj][m][0][jj]; v[4 + jj] = acc[ai][bj][m][1][jj]; }
;                     if constexpr (ROPE) {
;                         const int t = t0 & 2047;
; #pragma unroll
;                         for (int hf = 0; hf < 2; ++hf) {
;                             f32x4 cs, sn;
;                             if (m < 2) { const float c1 = ropeA[(t >> 6) * 16 + d], s1 = ropeA[1024 + (t >> 6) * 16 + d]; cs = (f32x4){c1, c1, c1, c1}; sn = (f32x4){s1, s1, s1, s1}; }
;                             else { const float* cb = ropeA + 2048 + (d - 16) * 64 + (t & 63) + 4 * hf; cs = *(const f32x4*)(cb); sn = *(const f32x4*)(cb + 1024); }
; #pragma unroll
;                             for (int jj = 0; jj < 4; ++jj) { const float pr = __shfl_xor(v[4 * hf + jj], 4); v[4 * hf + jj] = v[4 * hf + jj] * cs[jj] + sgn * pr * sn[jj]; }
;                             __builtin_amdgcn_sched_barrier(0);
;                         }
;                     }
;                     float zf[8], zb[8]; zf[0] = zf0; zb[0] = zb0;
; #pragma unroll
;                     for (int jj = 1; jj < 8; ++jj) { zf[jj] = zf[jj - 1] * zfs; zb[jj] = zb[jj - 1] * zbs; }
;                     u32x4 wf, wb;
;                     wf.x = cvt_pk_bf16(v[0] * zf[0], v[1] * zf[1]); wf.y = cvt_pk_bf16(v[2] * zf[2], v[3] * zf[3]); wf.z = cvt_pk_bf16(v[4] * zf[4], v[5] * zf[5]); wf.w = cvt_pk_bf16(v[6] * zf[6], v[7] * zf[7]);
;                     wb.x = cvt_pk_bf16(v[0] * zb[0], v[1] * zb[1]); wb.y = cvt_pk_bf16(v[2] * zb[2], v[3] * zb[3]); wb.z = cvt_pk_bf16(v[4] * zb[4], v[5] * zb[5]); wb.w = cvt_pk_bf16(v[6] * zb[6], v[7] * zb[7]);
;                     *(u32x4*)(KTZ + (size_t)r * NT + t0) = wf;
;                     *(u32x4*)(KTZ + (size_t)(256 + r) * NT + t0) = wb;
;                     __builtin_amdgcn_sched_barrier(0);
	v_cndmask_b32_e64 v119, v119, -v119, vcc
	s_waitcnt vmcnt(0)
	v_pk_mul_f32 v[126:127], v[116:117], v[118:119]
	s_waitcnt lgkmcnt(2)
	v_cndmask_b32_e64 v119, v100, -v100, vcc
	v_mov_b32_e32 v116, v101
	v_pk_mul_f32 v[100:101], v[116:117], v[118:119]
	s_waitcnt lgkmcnt(1)
	v_cndmask_b32_e64 v119, v153, -v153, vcc
	v_mov_b32_e32 v116, v102
	v_add_f32_e32 v126, v126, v127
	v_add_f32_e32 v127, v100, v101
	v_pk_mul_f32 v[100:101], v[116:117], v[118:119]
	s_waitcnt lgkmcnt(0)
	v_cndmask_b32_e64 v119, v157, -v157, vcc
	v_mov_b32_e32 v116, v103
	v_add_f32_e32 v153, v100, v101
	v_pk_mul_f32 v[100:101], v[116:117], v[118:119]
	s_nop 0
	v_add_f32_e32 v118, v100, v101
	global_load_dword v101, v[104:105], off
	global_load_dword v102, v[106:107], off
	ds_bpermute_b32 v103, v177, v96
	v_mov_b32_e32 v100, v96
	ds_bpermute_b32 v96, v177, v97
	ds_bpermute_b32 v119, v177, v98
	ds_bpermute_b32 v157, v177, v99
	s_waitcnt lgkmcnt(3)
	v_cndmask_b32_e64 v103, v103, -v103, vcc
	s_waitcnt vmcnt(0)
	v_pk_mul_f32 v[116:117], v[100:101], v[102:103]
	s_waitcnt lgkmcnt(2)
	v_cndmask_b32_e64 v103, v96, -v96, vcc
	v_mov_b32_e32 v100, v97
	v_pk_mul_f32 v[96:97], v[100:101], v[102:103]
	s_waitcnt lgkmcnt(1)
	v_cndmask_b32_e64 v103, v119, -v119, vcc
	v_mov_b32_e32 v100, v98
	v_add_f32_e32 v116, v116, v117
	v_add_f32_e32 v117, v96, v97
	v_pk_mul_f32 v[96:97], v[100:101], v[102:103]
	s_waitcnt lgkmcnt(0)
	v_cndmask_b32_e64 v103, v157, -v157, vcc
	v_mov_b32_e32 v100, v99
	v_add_f32_e32 v119, v96, v97
	v_pk_mul_f32 v[96:97], v[100:101], v[102:103]
	s_nop 0
	v_add_f32_e32 v103, v96, v97
	v_mul_f32_e32 v96, v180, v126
	v_mul_f32_e32 v97, v181, v127
	v_cvt_pk_bf16_f32 v96, v96, v97
	v_mul_f32_e32 v97, v167, v153
	v_mul_f32_e32 v98, v183, v118
	v_cvt_pk_bf16_f32 v97, v97, v98
	v_mul_f32_e32 v98, v182, v116
	v_mul_f32_e32 v99, v185, v117
	v_cvt_pk_bf16_f32 v98, v98, v99
	v_mul_f32_e32 v99, v184, v119
	v_mul_f32_e32 v100, v159, v103
	v_cvt_pk_bf16_f32 v99, v99, v100
	v_mul_f32_e32 v100, v150, v126
	v_mul_f32_e32 v101, v152, v127
	v_cvt_pk_bf16_f32 v100, v100, v101
	v_mul_f32_e32 v101, v154, v153
	v_mul_f32_e32 v102, v156, v118
	v_cvt_pk_bf16_f32 v101, v101, v102
	v_mul_f32_e32 v102, v158, v116
	v_mul_f32_e32 v116, v160, v117
	v_mul_f32_e32 v103, v155, v103
	v_cvt_pk_bf16_f32 v102, v102, v116
	v_mul_f32_e32 v116, v151, v119
	v_cvt_pk_bf16_f32 v103, v116, v103
	global_store_dwordx4 v[108:109], v[96:99], off offset:256
	global_store_dwordx4 v[110:111], v[100:103], off offset:256
	s_nop 1
	v_lshlrev_b32_e32 v100, 6, v136
	v_ashrrev_i32_e32 v101, 31, v100
	v_lshlrev_b64 v[102:103], 2, v[100:101]
	v_lshl_add_u64 v[96:97], s[24:25], 0, v[102:103]
	v_lshlrev_b32_e32 v136, 2, v186
	v_lshl_add_u64 v[96:97], v[96:97], 0, v[136:137]
	v_add_co_u32_e64 v98, s[4:5], s61, v96
	ds_bpermute_b32 v101, v177, v92
	s_nop 0
	v_addc_co_u32_e64 v99, s[4:5], 0, v97, s[4:5]
	global_load_dwordx4 v[108:111], v[98:99], off
	global_load_dwordx4 v[116:119], v[96:97], off
	ds_bpermute_b32 v127, v177, v93
	ds_bpermute_b32 v153, v177, v94
	ds_bpermute_b32 v157, v177, v95
	v_mov_b32_e32 v126, v92
	v_mov_b32_e32 v92, v94
	s_waitcnt lgkmcnt(3)
	v_cndmask_b32_e64 v163, v101, -v101, vcc
	s_waitcnt lgkmcnt(2)
	v_cndmask_b32_e64 v165, v127, -v127, vcc
	s_waitcnt lgkmcnt(1)
	v_cndmask_b32_e64 v187, v153, -v153, vcc
	s_waitcnt lgkmcnt(0)
	v_cndmask_b32_e64 v189, v157, -v157, vcc
	s_waitcnt vmcnt(1)
	v_mov_b32_e32 v127, v108
	s_waitcnt vmcnt(0)
	v_mov_b32_e32 v162, v116
	v_mov_b32_e32 v108, v93
	v_mov_b32_e32 v164, v117
	v_mov_b32_e32 v93, v110
	v_mov_b32_e32 v186, v118
	v_mov_b32_e32 v110, v95
	v_mov_b32_e32 v188, v119
	v_pk_mul_f32 v[94:95], v[126:127], v[162:163]
	v_pk_mul_f32 v[108:109], v[108:109], v[164:165]
	v_pk_mul_f32 v[92:93], v[92:93], v[186:187]
	v_pk_mul_f32 v[110:111], v[110:111], v[188:189]
	v_add_f32_e32 v101, v94, v95
	v_add_f32_e32 v153, v108, v109
	v_add_f32_e32 v157, v92, v93
	v_add_f32_e32 v161, v110, v111
	v_lshl_add_u64 v[92:93], s[16:17], 0, v[102:103]
	v_lshl_add_u64 v[94:95], v[92:93], 0, v[136:137]
	v_add_co_u32_e64 v92, s[4:5], s62, v94
	ds_bpermute_b32 v103, v177, v88
	s_nop 0
	v_addc_co_u32_e64 v93, s[4:5], 0, v95, s[4:5]
	v_add_co_u32_e64 v94, s[4:5], s49, v94
	ds_bpermute_b32 v126, v177, v89
	s_nop 0
	v_addc_co_u32_e64 v95, s[4:5], 0, v95, s[4:5]
	global_load_dwordx4 v[108:111], v[92:93], off offset:16
	global_load_dwordx4 v[116:119], v[94:95], off offset:16
	ds_bpermute_b32 v162, v177, v90
	ds_bpermute_b32 v164, v177, v91
	v_mov_b32_e32 v102, v88
	v_mov_b32_e32 v88, v90
	s_waitcnt lgkmcnt(3)
	v_cndmask_b32_e64 v127, v103, -v103, vcc
	s_waitcnt lgkmcnt(2)
	v_cndmask_b32_e64 v163, v126, -v126, vcc
	s_waitcnt lgkmcnt(1)
	v_cndmask_b32_e64 v165, v162, -v162, vcc
	s_waitcnt lgkmcnt(0)
	v_cndmask_b32_e64 v187, v164, -v164, vcc
	s_waitcnt vmcnt(1)
	v_mov_b32_e32 v103, v108
	s_waitcnt vmcnt(0)
;     __device__ __forceinline__ void operator()(const AccT& acc, const Unit& u, int wr, int wc, int fr, int fq) const {
;     ...
;             for (int m = 0; m < 4; ++m) {
;                 const int r = rbase + ai * 128 + m * 16;
;                 const int d = 4 * (2 * m + (fr >> 3)) + j;
; #pragma unroll
;                 for (int bj = 0; bj < 2; ++bj) {
;                     const int t0 = tb + bj * 128;
;                     float v[8];
; #pragma unroll
;                     for (int jj = 0; jj < 4; ++jj) { v[jj] = acc[ai][bj][m][0][jj]; v[4 + jj] = acc[ai][bj][m][1][jj]; }
;                     if constexpr (ROPE) {
;                         const int t = t0 & 2047;
; #pragma unroll
;                         for (int hf = 0; hf < 2; ++hf) {
;                             f32x4 cs, sn;
;                             if (m < 2) { const float c1 = ropeA[(t >> 6) * 16 + d], s1 = ropeA[1024 + (t >> 6) * 16 + d]; cs = (f32x4){c1, c1, c1, c1}; sn = (f32x4){s1, s1, s1, s1}; }
;                             else { const float* cb = ropeA + 2048 + (d - 16) * 64 + (t & 63) + 4 * hf; cs = *(const f32x4*)(cb); sn = *(const f32x4*)(cb + 1024); }
; #pragma unroll
;                             for (int jj = 0; jj < 4; ++jj) { const float pr = __shfl_xor(v[4 * hf + jj], 4); v[4 * hf + jj] = v[4 * hf + jj] * cs[jj] + sgn * pr * sn[jj]; }
;                             __builtin_amdgcn_sched_barrier(0);
;                         }
;                     }
;                     float zf[8], zb[8]; zf[0] = zf0; zb[0] = zb0;
; #pragma unroll
;                     for (int jj = 1; jj < 8; ++jj) { zf[jj] = zf[jj - 1] * zfs; zb[jj] = zb[jj - 1] * zbs; }
;                     u32x4 wf, wb;
;                     wf.x = cvt_pk_bf16(v[0] * zf[0], v[1] * zf[1]); wf.y = cvt_pk_bf16(v[2] * zf[2], v[3] * zf[3]); wf.z = cvt_pk_bf16(v[4] * zf[4], v[5] * zf[5]); wf.w = cvt_pk_bf16(v[6] * zf[6], v[7] * zf[7]);
;                     wb.x = cvt_pk_bf16(v[0] * zb[0], v[1] * zb[1]); wb.y = cvt_pk_bf16(v[2] * zb[2], v[3] * zb[3]); wb.z = cvt_pk_bf16(v[4] * zb[4], v[5] * zb[5]); wb.w = cvt_pk_bf16(v[6] * zb[6], v[7] * zb[7]);
;                     *(u32x4*)(KTZ + (size_t)r * NT + t0) = wf;
;                     *(u32x4*)(KTZ + (size_t)(256 + r) * NT + t0) = wb;
;                     __builtin_amdgcn_sched_barrier(0);
	v_mov_b32_e32 v126, v116
	v_mov_b32_e32 v108, v89
	v_mov_b32_e32 v162, v117
	v_mov_b32_e32 v89, v110
	v_mov_b32_e32 v164, v118
	v_mov_b32_e32 v110, v91
	v_mov_b32_e32 v186, v119
	v_pk_mul_f32 v[90:91], v[102:103], v[126:127]
	v_pk_mul_f32 v[102:103], v[108:109], v[162:163]
	v_pk_mul_f32 v[88:89], v[88:89], v[164:165]
	v_pk_mul_f32 v[108:109], v[110:111], v[186:187]
	v_add_f32_e32 v90, v90, v91
	v_add_f32_e32 v91, v102, v103
	v_add_f32_e32 v88, v88, v89
	v_add_f32_e32 v89, v108, v109
	v_mul_f32_e32 v102, v180, v101
	v_mul_f32_e32 v103, v181, v153
	v_cvt_pk_bf16_f32 v108, v102, v103
	v_mul_f32_e32 v102, v167, v157
	v_mul_f32_e32 v103, v183, v161
	v_cvt_pk_bf16_f32 v109, v102, v103
	v_mul_f32_e32 v102, v182, v90
	v_mul_f32_e32 v103, v185, v91
	v_cvt_pk_bf16_f32 v110, v102, v103
	v_mul_f32_e32 v102, v184, v88
	v_mul_f32_e32 v103, v159, v89
	v_cvt_pk_bf16_f32 v111, v102, v103
	v_mul_f32_e32 v101, v150, v101
	v_mul_f32_e32 v102, v152, v153
	v_mul_f32_e32 v88, v151, v88
	v_mul_f32_e32 v89, v155, v89
	s_mov_b64 s[0:1], 0x400000
	v_cvt_pk_bf16_f32 v116, v101, v102
	v_mul_f32_e32 v101, v154, v157
	v_mul_f32_e32 v102, v156, v161
	v_cvt_pk_bf16_f32 v117, v101, v102
	v_mul_f32_e32 v90, v158, v90
	v_mul_f32_e32 v91, v160, v91
	v_cvt_pk_bf16_f32 v118, v90, v91
	v_cvt_pk_bf16_f32 v119, v88, v89
	v_lshl_add_u64 v[88:89], v[120:121], 0, s[0:1]
	s_mov_b32 s0, 0x400000
	v_add_co_u32_e64 v90, s[4:5], s0, v120
	s_mov_b64 s[0:1], 0x2400000
	s_nop 0
	v_addc_co_u32_e64 v91, s[4:5], 0, v121, s[4:5]
	global_store_dwordx4 v[90:91], v[108:111], off
	v_lshl_add_u64 v[90:91], v[120:121], 0, s[0:1]
	s_mov_b32 s0, 0x2400000
	v_add_co_u32_e64 v102, s[4:5], s0, v120
	s_nop 1
	v_addc_co_u32_e64 v103, s[4:5], 0, v121, s[4:5]
	global_store_dwordx4 v[102:103], v[116:119], off
	global_load_dwordx4 v[108:111], v[98:99], off
	s_nop 0
	global_load_dwordx4 v[116:119], v[96:97], off
	ds_bpermute_b32 v101, v177, v84
	ds_bpermute_b32 v103, v177, v85
	ds_bpermute_b32 v126, v177, v86
	ds_bpermute_b32 v153, v177, v87
	v_mov_b32_e32 v102, v84
	v_mov_b32_e32 v84, v86
	s_waitcnt lgkmcnt(3)
	v_cndmask_b32_e64 v127, v101, -v101, vcc
	s_waitcnt lgkmcnt(2)
	v_cndmask_b32_e64 v163, v103, -v103, vcc
	s_waitcnt lgkmcnt(1)
	v_cndmask_b32_e64 v165, v126, -v126, vcc
	s_waitcnt lgkmcnt(0)
	v_cndmask_b32_e64 v187, v153, -v153, vcc
	s_waitcnt vmcnt(1)
	v_mov_b32_e32 v103, v108
	s_waitcnt vmcnt(0)
	v_mov_b32_e32 v126, v116
	v_mov_b32_e32 v108, v85
	v_mov_b32_e32 v162, v117
	v_mov_b32_e32 v85, v110
	v_mov_b32_e32 v164, v118
	v_mov_b32_e32 v110, v87
	v_mov_b32_e32 v186, v119
	v_pk_mul_f32 v[86:87], v[102:103], v[126:127]
	v_pk_mul_f32 v[102:103], v[108:109], v[162:163]
	v_pk_mul_f32 v[84:85], v[84:85], v[164:165]
	v_pk_mul_f32 v[108:109], v[110:111], v[186:187]
	v_add_f32_e32 v101, v86, v87
	v_add_f32_e32 v153, v102, v103
	v_add_f32_e32 v157, v84, v85
	v_add_f32_e32 v161, v108, v109
	global_load_dwordx4 v[84:87], v[92:93], off offset:16
	global_load_dwordx4 v[108:111], v[94:95], off offset:16
	ds_bpermute_b32 v103, v177, v80
	ds_bpermute_b32 v116, v177, v81
	ds_bpermute_b32 v118, v177, v82
	ds_bpermute_b32 v126, v177, v83
	v_mov_b32_e32 v102, v80
	v_mov_b32_e32 v80, v82
	s_waitcnt lgkmcnt(3)
	v_cndmask_b32_e64 v117, v103, -v103, vcc
	s_waitcnt lgkmcnt(2)
	v_cndmask_b32_e64 v119, v116, -v116, vcc
	s_waitcnt lgkmcnt(1)
	v_cndmask_b32_e64 v127, v118, -v118, vcc
	s_waitcnt lgkmcnt(0)
	v_cndmask_b32_e64 v163, v126, -v126, vcc
	s_waitcnt vmcnt(1)
	v_mov_b32_e32 v103, v84
	s_waitcnt vmcnt(0)
	v_mov_b32_e32 v116, v108
	v_mov_b32_e32 v84, v81
	v_mov_b32_e32 v118, v109
	v_mov_b32_e32 v81, v86
	v_mov_b32_e32 v126, v110
	v_mov_b32_e32 v86, v83
	v_mov_b32_e32 v162, v111
	v_pk_mul_f32 v[82:83], v[102:103], v[116:117]
	v_pk_mul_f32 v[84:85], v[84:85], v[118:119]
	v_pk_mul_f32 v[80:81], v[80:81], v[126:127]
	v_pk_mul_f32 v[86:87], v[86:87], v[162:163]
	v_add_f32_e32 v102, v82, v83
	v_add_f32_e32 v103, v84, v85
	v_add_f32_e32 v108, v80, v81
	v_add_f32_e32 v87, v86, v87
	v_mul_f32_e32 v80, v180, v101
	v_mul_f32_e32 v81, v181, v153
	v_cvt_pk_bf16_f32 v80, v80, v81
	v_mul_f32_e32 v81, v167, v157
	v_mul_f32_e32 v82, v183, v161
	v_cvt_pk_bf16_f32 v81, v81, v82
	v_mul_f32_e32 v82, v182, v102
	v_mul_f32_e32 v83, v185, v103
	v_cvt_pk_bf16_f32 v82, v82, v83
	v_mul_f32_e32 v83, v184, v108
	v_mul_f32_e32 v84, v159, v87
	v_cvt_pk_bf16_f32 v83, v83, v84
	v_mul_f32_e32 v84, v150, v101
	v_mul_f32_e32 v85, v152, v153
	v_cvt_pk_bf16_f32 v84, v84, v85
	v_mul_f32_e32 v85, v154, v157
	v_mul_f32_e32 v86, v156, v161
	v_cvt_pk_bf16_f32 v85, v85, v86
	v_mul_f32_e32 v86, v158, v102
	v_mul_f32_e32 v101, v160, v103
	v_mul_f32_e32 v87, v155, v87
	v_cvt_pk_bf16_f32 v86, v86, v101
	v_mul_f32_e32 v101, v151, v108
	v_cvt_pk_bf16_f32 v87, v101, v87
	global_store_dwordx4 v[88:89], v[80:83], off offset:256
	global_store_dwordx4 v[90:91], v[84:87], off offset:256
	s_nop 0
	v_add_u32_e32 v80, 0x200, v100
	v_ashrrev_i32_e32 v81, 31, v80
	v_lshl_add_u64 v[82:83], s[24:25], 0, v[136:137]
	v_lshlrev_b64 v[100:101], 2, v[80:81]
	v_lshl_add_u64 v[80:81], v[82:83], 0, v[100:101]
	v_add_co_u32_e64 v82, s[4:5], s61, v80
	ds_bpermute_b32 v103, v177, v76
	s_nop 0
	v_addc_co_u32_e64 v83, s[4:5], 0, v81, s[4:5]
	global_load_dwordx4 v[84:87], v[82:83], off
	global_load_dwordx4 v[88:91], v[80:81], off
	ds_bpermute_b32 v108, v177, v77
	ds_bpermute_b32 v110, v177, v78
	ds_bpermute_b32 v116, v177, v79
	v_mov_b32_e32 v102, v76
	v_mov_b32_e32 v76, v78
	s_waitcnt lgkmcnt(3)
	v_cndmask_b32_e64 v109, v103, -v103, vcc
	s_waitcnt lgkmcnt(2)
	v_cndmask_b32_e64 v111, v108, -v108, vcc
	s_waitcnt lgkmcnt(1)
	v_cndmask_b32_e64 v117, v110, -v110, vcc
	s_waitcnt lgkmcnt(0)
;     __device__ __forceinline__ void operator()(const AccT& acc, const Unit& u, int wr, int wc, int fr, int fq) const {
;     ...
;             for (int m = 0; m < 4; ++m) {
;                 const int r = rbase + ai * 128 + m * 16;
;                 const int d = 4 * (2 * m + (fr >> 3)) + j;
; #pragma unroll
;                 for (int bj = 0; bj < 2; ++bj) {
;                     const int t0 = tb + bj * 128;
;                     float v[8];
; #pragma unroll
;                     for (int jj = 0; jj < 4; ++jj) { v[jj] = acc[ai][bj][m][0][jj]; v[4 + jj] = acc[ai][bj][m][1][jj]; }
;                     if constexpr (ROPE) {
;                         const int t = t0 & 2047;
; #pragma unroll
;                         for (int hf = 0; hf < 2; ++hf) {
;                             f32x4 cs, sn;
;                             if (m < 2) { const float c1 = ropeA[(t >> 6) * 16 + d], s1 = ropeA[1024 + (t >> 6) * 16 + d]; cs = (f32x4){c1, c1, c1, c1}; sn = (f32x4){s1, s1, s1, s1}; }
;                             else { const float* cb = ropeA + 2048 + (d - 16) * 64 + (t & 63) + 4 * hf; cs = *(const f32x4*)(cb); sn = *(const f32x4*)(cb + 1024); }
; #pragma unroll
;                             for (int jj = 0; jj < 4; ++jj) { const float pr = __shfl_xor(v[4 * hf + jj], 4); v[4 * hf + jj] = v[4 * hf + jj] * cs[jj] + sgn * pr * sn[jj]; }
;                             __builtin_amdgcn_sched_barrier(0);
;                         }
;                     }
;                     float zf[8], zb[8]; zf[0] = zf0; zb[0] = zb0;
; #pragma unroll
;                     for (int jj = 1; jj < 8; ++jj) { zf[jj] = zf[jj - 1] * zfs; zb[jj] = zb[jj - 1] * zbs; }
;                     u32x4 wf, wb;
;                     wf.x = cvt_pk_bf16(v[0] * zf[0], v[1] * zf[1]); wf.y = cvt_pk_bf16(v[2] * zf[2], v[3] * zf[3]); wf.z = cvt_pk_bf16(v[4] * zf[4], v[5] * zf[5]); wf.w = cvt_pk_bf16(v[6] * zf[6], v[7] * zf[7]);
;                     wb.x = cvt_pk_bf16(v[0] * zb[0], v[1] * zb[1]); wb.y = cvt_pk_bf16(v[2] * zb[2], v[3] * zb[3]); wb.z = cvt_pk_bf16(v[4] * zb[4], v[5] * zb[5]); wb.w = cvt_pk_bf16(v[6] * zb[6], v[7] * zb[7]);
;                     *(u32x4*)(KTZ + (size_t)r * NT + t0) = wf;
;                     *(u32x4*)(KTZ + (size_t)(256 + r) * NT + t0) = wb;
;                     __builtin_amdgcn_sched_barrier(0);
	v_cndmask_b32_e64 v119, v116, -v116, vcc
	s_waitcnt vmcnt(1)
	v_mov_b32_e32 v103, v84
	s_waitcnt vmcnt(0)
	v_mov_b32_e32 v108, v88
	v_mov_b32_e32 v84, v77
	v_mov_b32_e32 v110, v89
	v_mov_b32_e32 v77, v86
	v_mov_b32_e32 v116, v90
	v_mov_b32_e32 v86, v79
	v_mov_b32_e32 v118, v91
	v_pk_mul_f32 v[78:79], v[102:103], v[108:109]
	v_pk_mul_f32 v[84:85], v[84:85], v[110:111]
	v_pk_mul_f32 v[76:77], v[76:77], v[116:117]
	v_pk_mul_f32 v[86:87], v[86:87], v[118:119]
	v_add_f32_e32 v118, v78, v79
	v_add_f32_e32 v119, v84, v85
	v_add_f32_e32 v126, v76, v77
	v_add_f32_e32 v127, v86, v87
	v_lshl_add_u64 v[76:77], s[16:17], 0, v[100:101]
	v_lshl_add_u64 v[78:79], v[76:77], 0, v[136:137]
	v_add_co_u32_e64 v76, s[4:5], s62, v78
	ds_bpermute_b32 v101, v177, v72
	s_nop 0
	v_addc_co_u32_e64 v77, s[4:5], 0, v79, s[4:5]
	v_add_co_u32_e64 v78, s[4:5], s49, v78
	ds_bpermute_b32 v102, v177, v73
	s_nop 0
	v_addc_co_u32_e64 v79, s[4:5], 0, v79, s[4:5]
	global_load_dwordx4 v[84:87], v[76:77], off offset:16
	global_load_dwordx4 v[88:91], v[78:79], off offset:16
	ds_bpermute_b32 v108, v177, v74
	ds_bpermute_b32 v110, v177, v75
	v_mov_b32_e32 v100, v72
	v_mov_b32_e32 v72, v74
	s_waitcnt lgkmcnt(3)
	v_cndmask_b32_e64 v103, v101, -v101, vcc
	s_waitcnt lgkmcnt(2)
	v_cndmask_b32_e64 v109, v102, -v102, vcc
	s_waitcnt lgkmcnt(1)
	v_cndmask_b32_e64 v111, v108, -v108, vcc
	s_waitcnt lgkmcnt(0)
	v_cndmask_b32_e64 v117, v110, -v110, vcc
	s_waitcnt vmcnt(1)
	v_mov_b32_e32 v101, v84
	s_waitcnt vmcnt(0)
	v_mov_b32_e32 v102, v88
	v_mov_b32_e32 v84, v73
	v_mov_b32_e32 v108, v89
	v_mov_b32_e32 v73, v86
	v_mov_b32_e32 v110, v90
	v_mov_b32_e32 v86, v75
	v_mov_b32_e32 v116, v91
	v_pk_mul_f32 v[74:75], v[100:101], v[102:103]
	v_pk_mul_f32 v[84:85], v[84:85], v[108:109]
	v_pk_mul_f32 v[72:73], v[72:73], v[110:111]
	v_pk_mul_f32 v[86:87], v[86:87], v[116:117]
	v_add_f32_e32 v74, v74, v75
	v_add_f32_e32 v75, v84, v85
	v_add_f32_e32 v72, v72, v73
	v_add_f32_e32 v73, v86, v87
	v_mul_f32_e32 v84, v180, v118
	v_mul_f32_e32 v85, v181, v119
	v_cvt_pk_bf16_f32 v84, v84, v85
	v_mul_f32_e32 v85, v167, v126
	v_mul_f32_e32 v86, v183, v127
	v_cvt_pk_bf16_f32 v85, v85, v86
	v_mul_f32_e32 v86, v182, v74
	v_mul_f32_e32 v87, v185, v75
	v_cvt_pk_bf16_f32 v86, v86, v87
	v_mul_f32_e32 v87, v184, v72
	v_mul_f32_e32 v88, v159, v73
	v_cvt_pk_bf16_f32 v87, v87, v88
	v_mul_f32_e32 v88, v150, v118
	v_mul_f32_e32 v89, v152, v119
	v_cvt_pk_bf16_f32 v88, v88, v89
	v_mul_f32_e32 v89, v154, v126
	v_mul_f32_e32 v90, v156, v127
	v_mul_f32_e32 v72, v151, v72
	v_mul_f32_e32 v73, v155, v73
	s_mov_b64 s[0:1], 0x600000
	v_cvt_pk_bf16_f32 v89, v89, v90
	v_mul_f32_e32 v74, v158, v74
	v_mul_f32_e32 v75, v160, v75
	v_cvt_pk_bf16_f32 v90, v74, v75
	v_cvt_pk_bf16_f32 v91, v72, v73
	v_lshl_add_u64 v[72:73], v[120:121], 0, s[0:1]
	s_mov_b32 s0, 0x600000
	v_add_co_u32_e64 v74, s[4:5], s0, v120
	s_mov_b64 s[0:1], 0x2600000
	s_nop 0
	v_addc_co_u32_e64 v75, s[4:5], 0, v121, s[4:5]
	global_store_dwordx4 v[74:75], v[84:87], off
	v_lshl_add_u64 v[74:75], v[120:121], 0, s[0:1]
	s_mov_b32 s0, 0x2600000
	v_add_co_u32_e64 v84, s[4:5], s0, v120
	s_nop 1
	v_addc_co_u32_e64 v85, s[4:5], 0, v121, s[4:5]
	global_store_dwordx4 v[84:85], v[88:91], off
	global_load_dwordx4 v[84:87], v[82:83], off
	s_nop 0
	global_load_dwordx4 v[88:91], v[80:81], off
	ds_bpermute_b32 v101, v177, v68
	ds_bpermute_b32 v102, v177, v69
	ds_bpermute_b32 v108, v177, v70
	ds_bpermute_b32 v110, v177, v71
	v_mov_b32_e32 v100, v68
	v_mov_b32_e32 v68, v70
	s_waitcnt lgkmcnt(3)
	v_cndmask_b32_e64 v103, v101, -v101, vcc
	s_waitcnt lgkmcnt(2)
	v_cndmask_b32_e64 v109, v102, -v102, vcc
	s_waitcnt lgkmcnt(1)
	v_cndmask_b32_e64 v111, v108, -v108, vcc
	s_waitcnt lgkmcnt(0)
	v_cndmask_b32_e64 v117, v110, -v110, vcc
	s_waitcnt vmcnt(1)
	v_mov_b32_e32 v101, v84
	s_waitcnt vmcnt(0)
	v_mov_b32_e32 v102, v88
	v_mov_b32_e32 v84, v69
	v_mov_b32_e32 v108, v89
	v_mov_b32_e32 v69, v86
	v_mov_b32_e32 v110, v90
	v_mov_b32_e32 v86, v71
	v_mov_b32_e32 v116, v91
	v_pk_mul_f32 v[70:71], v[100:101], v[102:103]
	v_pk_mul_f32 v[84:85], v[84:85], v[108:109]
	v_pk_mul_f32 v[68:69], v[68:69], v[110:111]
	v_pk_mul_f32 v[86:87], v[86:87], v[116:117]
	v_add_f32_e32 v110, v70, v71
	v_add_f32_e32 v111, v84, v85
	v_add_f32_e32 v116, v68, v69
	v_add_f32_e32 v117, v86, v87
	global_load_dwordx4 v[68:71], v[76:77], off offset:16
	global_load_dwordx4 v[84:87], v[78:79], off offset:16
	ds_bpermute_b32 v89, v177, v64
	ds_bpermute_b32 v90, v177, v65
	ds_bpermute_b32 v100, v177, v66
	ds_bpermute_b32 v102, v177, v67
	v_mov_b32_e32 v88, v64
	v_mov_b32_e32 v64, v66
	s_waitcnt lgkmcnt(3)
	v_cndmask_b32_e64 v91, v89, -v89, vcc
	s_waitcnt lgkmcnt(2)
	v_cndmask_b32_e64 v101, v90, -v90, vcc
	s_waitcnt lgkmcnt(1)
	v_cndmask_b32_e64 v103, v100, -v100, vcc
	s_waitcnt lgkmcnt(0)
	v_cndmask_b32_e64 v109, v102, -v102, vcc
	s_waitcnt vmcnt(1)
	v_mov_b32_e32 v89, v68
	s_waitcnt vmcnt(0)
;     __device__ __forceinline__ void operator()(const AccT& acc, const Unit& u, int wr, int wc, int fr, int fq) const {
;     ...
;         for (int ai = 0; ai < 2; ++ai) {
;             const int hh = 2 * ai + wr;
;             const float l2f = lgd[hh] * 1.4426950408889634f, l2b = lgd[4 + hh] * 1.4426950408889634f;
;             const float zf0 = exp2f((float)(127 - o0) * l2f), zfs = exp2f(-l2f), zb0 = exp2f((float)o0 * l2b), zbs = exp2f(l2b);
; #pragma unroll
;             for (int m = 0; m < 4; ++m) {
;                 const int r = rbase + ai * 128 + m * 16;
;                 const int d = 4 * (2 * m + (fr >> 3)) + j;
; #pragma unroll
;                 for (int bj = 0; bj < 2; ++bj) {
;                     const int t0 = tb + bj * 128;
;                     float v[8];
; #pragma unroll
;                     for (int jj = 0; jj < 4; ++jj) { v[jj] = acc[ai][bj][m][0][jj]; v[4 + jj] = acc[ai][bj][m][1][jj]; }
;                     if constexpr (ROPE) {
;                         const int t = t0 & 2047;
; #pragma unroll
;                         for (int hf = 0; hf < 2; ++hf) {
;                             f32x4 cs, sn;
;                             if (m < 2) { const float c1 = ropeA[(t >> 6) * 16 + d], s1 = ropeA[1024 + (t >> 6) * 16 + d]; cs = (f32x4){c1, c1, c1, c1}; sn = (f32x4){s1, s1, s1, s1}; }
;                             else { const float* cb = ropeA + 2048 + (d - 16) * 64 + (t & 63) + 4 * hf; cs = *(const f32x4*)(cb); sn = *(const f32x4*)(cb + 1024); }
; #pragma unroll
;                             for (int jj = 0; jj < 4; ++jj) { const float pr = __shfl_xor(v[4 * hf + jj], 4); v[4 * hf + jj] = v[4 * hf + jj] * cs[jj] + sgn * pr * sn[jj]; }
;                             __builtin_amdgcn_sched_barrier(0);
;                         }
;                     }
;                     float zf[8], zb[8]; zf[0] = zf0; zb[0] = zb0;
; #pragma unroll
;                     for (int jj = 1; jj < 8; ++jj) { zf[jj] = zf[jj - 1] * zfs; zb[jj] = zb[jj - 1] * zbs; }
;                     u32x4 wf, wb;
;                     wf.x = cvt_pk_bf16(v[0] * zf[0], v[1] * zf[1]); wf.y = cvt_pk_bf16(v[2] * zf[2], v[3] * zf[3]); wf.z = cvt_pk_bf16(v[4] * zf[4], v[5] * zf[5]); wf.w = cvt_pk_bf16(v[6] * zf[6], v[7] * zf[7]);
	v_mov_b32_e32 v90, v84
	v_mov_b32_e32 v68, v65
	v_mov_b32_e32 v100, v85
	v_mov_b32_e32 v65, v70
	v_mov_b32_e32 v102, v86
	v_mov_b32_e32 v70, v67
	v_mov_b32_e32 v108, v87
	v_pk_mul_f32 v[66:67], v[88:89], v[90:91]
	v_pk_mul_f32 v[68:69], v[68:69], v[100:101]
	v_pk_mul_f32 v[64:65], v[64:65], v[102:103]
	v_pk_mul_f32 v[70:71], v[70:71], v[108:109]
	v_add_f32_e32 v84, v66, v67
	v_add_f32_e32 v85, v68, v69
	v_add_f32_e32 v86, v64, v65
	v_add_f32_e32 v71, v70, v71
	v_mul_f32_e32 v64, v180, v110
	v_mul_f32_e32 v65, v181, v111
	v_cvt_pk_bf16_f32 v64, v64, v65
	v_mul_f32_e32 v65, v167, v116
	v_mul_f32_e32 v66, v183, v117
	v_cvt_pk_bf16_f32 v65, v65, v66
	v_mul_f32_e32 v66, v182, v84
	v_mul_f32_e32 v67, v185, v85
	v_cvt_pk_bf16_f32 v66, v66, v67
	v_mul_f32_e32 v67, v184, v86
	v_mul_f32_e32 v68, v159, v71
	v_cvt_pk_bf16_f32 v67, v67, v68
	v_mul_f32_e32 v68, v150, v110
	v_mul_f32_e32 v69, v152, v111
	v_cvt_pk_bf16_f32 v68, v68, v69
	v_mul_f32_e32 v69, v154, v116
	v_mul_f32_e32 v70, v156, v117
	v_cvt_pk_bf16_f32 v69, v69, v70
	v_mul_f32_e32 v70, v158, v84
	v_mul_f32_e32 v84, v160, v85
	v_mul_f32_e32 v71, v155, v71
	v_cvt_pk_bf16_f32 v70, v70, v84
	v_mul_f32_e32 v84, v151, v86
	v_cvt_pk_bf16_f32 v71, v84, v71
	global_store_dwordx4 v[72:73], v[64:67], off offset:256
	global_store_dwordx4 v[74:75], v[68:71], off offset:256
	global_load_dword v64, v137, s[22:23] offset:8
	s_nop 0
	global_load_dword v70, v137, s[22:23] offset:24
	global_load_dword v67, v[146:147], off
	global_load_dword v74, v[148:149], off
	ds_bpermute_b32 v65, v177, v60
	ds_bpermute_b32 v68, v177, v62
	v_mov_b32_e32 v66, v60
	ds_bpermute_b32 v60, v177, v61
	ds_bpermute_b32 v71, v177, v63
	s_waitcnt lgkmcnt(3)
	v_cndmask_b32_e64 v75, v65, -v65, vcc
	s_waitcnt lgkmcnt(2)
	v_cndmask_b32_e64 v65, v68, -v68, vcc
	s_waitcnt vmcnt(3)
	v_mul_f32_e32 v72, 0x3fb8aa3b, v64
	s_waitcnt vmcnt(2)
	v_mul_f32_e32 v73, 0x3fb8aa3b, v70
	v_mul_f32_e32 v84, v72, v179
	s_waitcnt vmcnt(0)
	v_pk_mul_f32 v[68:69], v[66:67], v[74:75]
	s_waitcnt lgkmcnt(1)
	v_cndmask_b32_e64 v75, v60, -v60, vcc
	v_mov_b32_e32 v66, v61
	v_cmp_lt_f32_e64 s[4:5], s60, v72
	v_mul_f32_e32 v87, v73, v178
	v_pk_mul_f32 v[60:61], v[66:67], v[74:75]
	s_waitcnt lgkmcnt(0)
	v_cndmask_b32_e64 v75, v71, -v71, vcc
	v_mov_b32_e32 v66, v63
	v_cmp_gt_f32_e64 s[8:9], s59, v84
	v_cndmask_b32_e64 v86, 0, v176, s[4:5]
	v_cmp_gt_f32_e64 s[6:7], s59, v73
	s_and_b64 s[0:1], s[4:5], exec
	v_cmp_gt_f32_e64 s[4:5], s59, v87
	v_add_f32_e32 v110, v60, v61
	v_pk_mul_f32 v[60:61], v[66:67], v[74:75]
	v_cndmask_b32_e64 v66, 0, v176, s[8:9]
	v_cndmask_b32_e64 v88, 0, v176, s[6:7]
	v_add_f32_e32 v89, v68, v69
	v_fmac_f32_e32 v86, 0xbfb8aa3b, v64
	v_cndmask_b32_e64 v69, 0, v176, s[4:5]
	v_fmac_f32_e32 v66, v72, v179
	v_fmac_f32_e32 v88, 0x3fb8aa3b, v70
	v_exp_f32_e32 v68, v86
	v_fmac_f32_e32 v69, v73, v178
	v_exp_f32_e32 v66, v66
	v_exp_f32_e32 v70, v88
	v_exp_f32_e32 v69, v69
	v_cndmask_b32_e64 v63, 0, v175, s[8:9]
	s_cselect_b32 s8, 0xffffffc0, 0
	s_and_b64 s[0:1], s[6:7], exec
	v_cndmask_b32_e64 v64, 0, v175, s[4:5]
	s_cselect_b32 s0, 0xffffffc0, 0
	v_ldexp_f32 v100, v68, s8
	v_ldexp_f32 v63, v66, v63
	v_mul_f32_e32 v85, v62, v74
	v_ldexp_f32 v90, v70, s0
	v_ldexp_f32 v64, v69, v64
	v_mul_f32_e32 v75, v100, v63
	v_add_f32_e32 v111, v60, v61
	global_load_dword v108, v[148:149], off
	global_load_dword v69, v[146:147], off
	ds_bpermute_b32 v61, v177, v57
	ds_bpermute_b32 v60, v177, v56
	v_mov_b32_e32 v68, v57
	ds_bpermute_b32 v57, v177, v59
	ds_bpermute_b32 v66, v177, v58
	s_waitcnt lgkmcnt(3)
	v_cndmask_b32_e64 v109, v61, -v61, vcc
	s_waitcnt lgkmcnt(2)
	v_cndmask_b32_e64 v70, v60, -v60, vcc
	s_waitcnt lgkmcnt(0)
	v_cndmask_b32_e64 v72, v66, -v66, vcc
	s_waitcnt vmcnt(1)
	v_mul_f32_e32 v71, v56, v108
	s_waitcnt vmcnt(0)
	v_pk_mul_f32 v[60:61], v[68:69], v[108:109]
	v_cndmask_b32_e64 v109, v57, -v57, vcc
	v_mov_b32_e32 v68, v59
	v_add_f32_e32 v57, v60, v61
	v_pk_mul_f32 v[60:61], v[68:69], v[108:109]
	s_nop 0
	v_add_f32_e32 v59, v60, v61
	v_mov_b32_e32 v91, v67
	v_pk_mul_f32 v[60:61], v[90:91], v[64:65]
	v_mov_b32_e32 v91, v85
	v_pk_mul_f32 v[66:67], v[90:91], v[60:61]
	v_mov_b32_e32 v91, v69
	v_mov_b32_e32 v67, v70
	v_mul_f32_e32 v84, v100, v75
	v_pk_mul_f32 v[68:69], v[90:91], v[66:67]
	v_mov_b32_e32 v70, v90
	v_mul_f32_e32 v86, v100, v84
	v_pk_mul_f32 v[70:71], v[70:71], v[68:69]
	v_mul_f32_e32 v85, v100, v86
	v_mov_b32_e32 v71, v72
	v_mul_f32_e32 v88, v100, v85
	v_pk_mul_f32 v[72:73], v[90:91], v[70:71]
	v_fma_f32 v61, v62, v74, v61
	v_mul_f32_e32 v87, v100, v88
	v_mul_f32_e32 v65, v90, v72
	v_mul_f32_e32 v62, v84, v61
	v_fma_f32 v56, v56, v108, v69
	v_mul_f32_e32 v71, v100, v87
	v_mul_f32_e32 v67, v90, v65
	v_mul_f32_e32 v90, v63, v89
	v_mul_f32_e32 v91, v75, v110
	v_cvt_pk_bf16_f32 v100, v90, v91
	v_mul_f32_e32 v74, v86, v111
	v_cvt_pk_bf16_f32 v101, v62, v74
	v_mul_f32_e32 v62, v85, v56
	v_fma_f32 v58, v58, v108, v73
	v_mul_f32_e32 v69, v88, v57
	v_cvt_pk_bf16_f32 v102, v62, v69
	v_mul_f32_e32 v62, v87, v58
	v_mul_f32_e32 v69, v71, v59
	v_cvt_pk_bf16_f32 v103, v62, v69
	v_mul_f32_e32 v62, v64, v89
	v_mul_f32_e32 v56, v70, v56
	v_mul_f32_e32 v57, v72, v57
	v_mul_f32_e32 v69, v60, v110
	v_cvt_pk_bf16_f32 v108, v62, v69
	v_mul_f32_e32 v61, v66, v61
	v_mul_f32_e32 v62, v68, v111
	v_cvt_pk_bf16_f32 v109, v61, v62
	v_cvt_pk_bf16_f32 v110, v56, v57
	v_mul_f32_e32 v56, v65, v58
	v_mul_f32_e32 v57, v67, v59
	s_mov_b64 s[0:1], 0x1000000
	v_cvt_pk_bf16_f32 v111, v56, v57
	v_lshl_add_u64 v[56:57], v[120:121], 0, s[0:1]
	s_mov_b32 s0, 0x1000000
	v_add_co_u32_e64 v58, s[4:5], s0, v120
	s_mov_b64 s[0:1], 0x3000000
	s_nop 0
	v_addc_co_u32_e64 v59, s[4:5], 0, v121, s[4:5]
	global_store_dwordx4 v[58:59], v[100:103], off
	v_lshl_add_u64 v[58:59], v[120:121], 0, s[0:1]
	s_mov_b32 s0, 0x3000000
	v_add_co_u32_e64 v90, s[4:5], s0, v120
	s_nop 1
	v_addc_co_u32_e64 v91, s[4:5], 0, v121, s[4:5]
	global_store_dwordx4 v[90:91], v[108:111], off
	global_load_dword v91, v[122:123], off
	s_nop 0
	global_load_dword v100, v[124:125], off
	ds_bpermute_b32 v61, v177, v52
	v_mov_b32_e32 v90, v52
	ds_bpermute_b32 v52, v177, v53
	ds_bpermute_b32 v62, v177, v54
	ds_bpermute_b32 v69, v177, v55
	s_waitcnt lgkmcnt(3)
;     __device__ __forceinline__ void operator()(const AccT& acc, const Unit& u, int wr, int wc, int fr, int fq) const {
;     ...
;             for (int m = 0; m < 4; ++m) {
;                 const int r = rbase + ai * 128 + m * 16;
;                 const int d = 4 * (2 * m + (fr >> 3)) + j;
; #pragma unroll
;                 for (int bj = 0; bj < 2; ++bj) {
;                     const int t0 = tb + bj * 128;
;                     float v[8];
; #pragma unroll
;                     for (int jj = 0; jj < 4; ++jj) { v[jj] = acc[ai][bj][m][0][jj]; v[4 + jj] = acc[ai][bj][m][1][jj]; }
;                     if constexpr (ROPE) {
;                         const int t = t0 & 2047;
; #pragma unroll
;                         for (int hf = 0; hf < 2; ++hf) {
;                             f32x4 cs, sn;
;                             if (m < 2) { const float c1 = ropeA[(t >> 6) * 16 + d], s1 = ropeA[1024 + (t >> 6) * 16 + d]; cs = (f32x4){c1, c1, c1, c1}; sn = (f32x4){s1, s1, s1, s1}; }
;                             else { const float* cb = ropeA + 2048 + (d - 16) * 64 + (t & 63) + 4 * hf; cs = *(const f32x4*)(cb); sn = *(const f32x4*)(cb + 1024); }
; #pragma unroll
;                             for (int jj = 0; jj < 4; ++jj) { const float pr = __shfl_xor(v[4 * hf + jj], 4); v[4 * hf + jj] = v[4 * hf + jj] * cs[jj] + sgn * pr * sn[jj]; }
;                             __builtin_amdgcn_sched_barrier(0);
;                         }
;                     }
;                     float zf[8], zb[8]; zf[0] = zf0; zb[0] = zb0;
; #pragma unroll
;                     for (int jj = 1; jj < 8; ++jj) { zf[jj] = zf[jj - 1] * zfs; zb[jj] = zb[jj - 1] * zbs; }
;                     u32x4 wf, wb;
;                     wf.x = cvt_pk_bf16(v[0] * zf[0], v[1] * zf[1]); wf.y = cvt_pk_bf16(v[2] * zf[2], v[3] * zf[3]); wf.z = cvt_pk_bf16(v[4] * zf[4], v[5] * zf[5]); wf.w = cvt_pk_bf16(v[6] * zf[6], v[7] * zf[7]);
;                     wb.x = cvt_pk_bf16(v[0] * zb[0], v[1] * zb[1]); wb.y = cvt_pk_bf16(v[2] * zb[2], v[3] * zb[3]); wb.z = cvt_pk_bf16(v[4] * zb[4], v[5] * zb[5]); wb.w = cvt_pk_bf16(v[6] * zb[6], v[7] * zb[7]);
;                     *(u32x4*)(KTZ + (size_t)r * NT + t0) = wf;
;                     *(u32x4*)(KTZ + (size_t)(256 + r) * NT + t0) = wb;
;                     __builtin_amdgcn_sched_barrier(0);
	v_cndmask_b32_e64 v101, v61, -v61, vcc
	s_waitcnt vmcnt(0)
	v_pk_mul_f32 v[102:103], v[90:91], v[100:101]
	s_waitcnt lgkmcnt(2)
	v_cndmask_b32_e64 v101, v52, -v52, vcc
	v_mov_b32_e32 v90, v53
	v_pk_mul_f32 v[52:53], v[90:91], v[100:101]
	s_waitcnt lgkmcnt(1)
	v_cndmask_b32_e64 v101, v62, -v62, vcc
	v_mov_b32_e32 v90, v54
	v_add_f32_e32 v62, v52, v53
	v_pk_mul_f32 v[52:53], v[90:91], v[100:101]
	s_waitcnt lgkmcnt(0)
	v_cndmask_b32_e64 v101, v69, -v69, vcc
	v_mov_b32_e32 v90, v55
	v_add_f32_e32 v69, v52, v53
	v_pk_mul_f32 v[52:53], v[90:91], v[100:101]
	v_add_f32_e32 v61, v102, v103
	v_add_f32_e32 v73, v52, v53
	global_load_dword v53, v[122:123], off
	global_load_dword v54, v[124:125], off
	ds_bpermute_b32 v55, v177, v48
	v_mov_b32_e32 v52, v48
	ds_bpermute_b32 v48, v177, v49
	ds_bpermute_b32 v74, v177, v50
	ds_bpermute_b32 v89, v177, v51
	s_waitcnt lgkmcnt(3)
	v_cndmask_b32_e64 v55, v55, -v55, vcc
	s_waitcnt vmcnt(0)
	v_pk_mul_f32 v[90:91], v[52:53], v[54:55]
	s_waitcnt lgkmcnt(2)
	v_cndmask_b32_e64 v55, v48, -v48, vcc
	v_mov_b32_e32 v52, v49
	v_pk_mul_f32 v[48:49], v[52:53], v[54:55]
	s_waitcnt lgkmcnt(1)
	v_cndmask_b32_e64 v55, v74, -v74, vcc
	v_mov_b32_e32 v52, v50
	v_add_f32_e32 v74, v48, v49
	v_pk_mul_f32 v[48:49], v[52:53], v[54:55]
	s_waitcnt lgkmcnt(0)
	v_cndmask_b32_e64 v55, v89, -v89, vcc
	v_mov_b32_e32 v52, v51
	v_add_f32_e32 v89, v48, v49
	v_pk_mul_f32 v[48:49], v[52:53], v[54:55]
	v_add_f32_e32 v90, v90, v91
	v_add_f32_e32 v55, v48, v49
	v_mul_f32_e32 v48, v63, v61
	v_mul_f32_e32 v49, v75, v62
	v_cvt_pk_bf16_f32 v48, v48, v49
	v_mul_f32_e32 v49, v84, v69
	v_mul_f32_e32 v50, v86, v73
	v_cvt_pk_bf16_f32 v49, v49, v50
	v_mul_f32_e32 v50, v85, v90
	v_mul_f32_e32 v51, v88, v74
	v_cvt_pk_bf16_f32 v50, v50, v51
	v_mul_f32_e32 v51, v87, v89
	v_mul_f32_e32 v52, v71, v55
	v_cvt_pk_bf16_f32 v51, v51, v52
	v_mul_f32_e32 v52, v64, v61
	v_mul_f32_e32 v53, v60, v62
	v_cvt_pk_bf16_f32 v52, v52, v53
	v_mul_f32_e32 v53, v66, v69
	v_mul_f32_e32 v54, v68, v73
	v_cvt_pk_bf16_f32 v53, v53, v54
	v_mul_f32_e32 v54, v70, v90
	v_mul_f32_e32 v61, v72, v74
	v_mul_f32_e32 v55, v67, v55
	v_cvt_pk_bf16_f32 v54, v54, v61
	v_mul_f32_e32 v61, v65, v89
	v_cvt_pk_bf16_f32 v55, v61, v55
	global_store_dwordx4 v[56:57], v[48:51], off offset:256
	global_store_dwordx4 v[58:59], v[52:55], off offset:256
	global_load_dword v49, v[112:113], off
	s_nop 0
	global_load_dword v50, v[114:115], off
	ds_bpermute_b32 v51, v177, v44
	v_mov_b32_e32 v48, v44
	ds_bpermute_b32 v44, v177, v45
	ds_bpermute_b32 v54, v177, v46
	ds_bpermute_b32 v55, v177, v47
	s_waitcnt lgkmcnt(3)
	v_cndmask_b32_e64 v51, v51, -v51, vcc
	s_waitcnt vmcnt(0)
	v_pk_mul_f32 v[52:53], v[48:49], v[50:51]
	s_waitcnt lgkmcnt(2)
	v_cndmask_b32_e64 v51, v44, -v44, vcc
	v_mov_b32_e32 v48, v45
	v_pk_mul_f32 v[44:45], v[48:49], v[50:51]
	s_waitcnt lgkmcnt(1)
	v_cndmask_b32_e64 v51, v54, -v54, vcc
	v_mov_b32_e32 v48, v46
	v_add_f32_e32 v52, v52, v53
	v_add_f32_e32 v53, v44, v45
	v_pk_mul_f32 v[44:45], v[48:49], v[50:51]
	s_waitcnt lgkmcnt(0)
	v_cndmask_b32_e64 v51, v55, -v55, vcc
	v_mov_b32_e32 v48, v47
	v_add_f32_e32 v54, v44, v45
	v_pk_mul_f32 v[44:45], v[48:49], v[50:51]
	s_nop 0
	v_add_f32_e32 v50, v44, v45
	global_load_dword v45, v[112:113], off
	global_load_dword v46, v[114:115], off
	ds_bpermute_b32 v47, v177, v40
	v_mov_b32_e32 v44, v40
	ds_bpermute_b32 v40, v177, v41
	ds_bpermute_b32 v51, v177, v42
	ds_bpermute_b32 v55, v177, v43
	s_waitcnt lgkmcnt(3)
	v_cndmask_b32_e64 v47, v47, -v47, vcc
	s_waitcnt vmcnt(0)
	v_pk_mul_f32 v[48:49], v[44:45], v[46:47]
	s_waitcnt lgkmcnt(2)
	v_cndmask_b32_e64 v47, v40, -v40, vcc
	v_mov_b32_e32 v44, v41
	v_pk_mul_f32 v[40:41], v[44:45], v[46:47]
	s_waitcnt lgkmcnt(1)
	v_cndmask_b32_e64 v47, v51, -v51, vcc
	v_mov_b32_e32 v44, v42
	v_add_f32_e32 v48, v48, v49
	v_add_f32_e32 v49, v40, v41
	v_pk_mul_f32 v[40:41], v[44:45], v[46:47]
	s_waitcnt lgkmcnt(0)
	v_cndmask_b32_e64 v47, v55, -v55, vcc
	v_mov_b32_e32 v44, v43
	v_add_f32_e32 v51, v40, v41
	v_pk_mul_f32 v[40:41], v[44:45], v[46:47]
	s_nop 0
	v_add_f32_e32 v40, v40, v41
	v_mul_f32_e32 v41, v63, v52
	v_mul_f32_e32 v42, v75, v53
	v_cvt_pk_bf16_f32 v42, v41, v42
	v_mul_f32_e32 v41, v84, v54
	v_mul_f32_e32 v43, v86, v50
	v_cvt_pk_bf16_f32 v43, v41, v43
	v_mul_f32_e32 v41, v85, v48
	v_mul_f32_e32 v44, v88, v49
	v_cvt_pk_bf16_f32 v44, v41, v44
	v_mul_f32_e32 v41, v87, v51
	v_mul_f32_e32 v45, v71, v40
	v_cvt_pk_bf16_f32 v45, v41, v45
	v_mul_f32_e32 v41, v64, v52
	v_mul_f32_e32 v46, v60, v53
	v_cvt_pk_bf16_f32 v46, v41, v46
	v_mul_f32_e32 v41, v66, v54
	v_mul_f32_e32 v47, v68, v50
	v_cvt_pk_bf16_f32 v47, v41, v47
	v_mul_f32_e32 v41, v70, v48
	v_mul_f32_e32 v48, v72, v49
	v_cvt_pk_bf16_f32 v48, v41, v48
	v_mul_f32_e32 v41, v65, v51
	v_mul_f32_e32 v40, v67, v40
	s_mov_b64 s[0:1], 0x1200000
	v_cvt_pk_bf16_f32 v49, v41, v40
	v_lshl_add_u64 v[40:41], v[120:121], 0, s[0:1]
	s_mov_b32 s0, 0x1200000
	v_add_co_u32_e64 v50, s[4:5], s0, v120
	s_mov_b64 s[0:1], 0x3200000
	s_nop 0
	v_addc_co_u32_e64 v51, s[4:5], 0, v121, s[4:5]
	global_store_dwordx4 v[50:51], v[42:45], off
	s_nop 1
	v_lshl_add_u64 v[42:43], v[120:121], 0, s[0:1]
	s_mov_b32 s0, 0x3200000
	v_add_co_u32_e64 v44, s[4:5], s0, v120
	s_nop 1
	v_addc_co_u32_e64 v45, s[4:5], 0, v121, s[4:5]
	global_store_dwordx4 v[44:45], v[46:49], off
	global_load_dword v45, v[104:105], off
	s_nop 0
	global_load_dword v46, v[106:107], off
	ds_bpermute_b32 v47, v177, v36
	v_mov_b32_e32 v44, v36
	ds_bpermute_b32 v36, v177, v37
	ds_bpermute_b32 v50, v177, v38
	ds_bpermute_b32 v51, v177, v39
	s_waitcnt lgkmcnt(3)
	v_cndmask_b32_e64 v47, v47, -v47, vcc
	s_waitcnt vmcnt(0)
	v_pk_mul_f32 v[48:49], v[44:45], v[46:47]
	s_waitcnt lgkmcnt(2)
;     __device__ __forceinline__ void operator()(const AccT& acc, const Unit& u, int wr, int wc, int fr, int fq) const {
;     ...
;             for (int m = 0; m < 4; ++m) {
;                 const int r = rbase + ai * 128 + m * 16;
;                 const int d = 4 * (2 * m + (fr >> 3)) + j;
; #pragma unroll
;                 for (int bj = 0; bj < 2; ++bj) {
;                     const int t0 = tb + bj * 128;
;                     float v[8];
; #pragma unroll
;                     for (int jj = 0; jj < 4; ++jj) { v[jj] = acc[ai][bj][m][0][jj]; v[4 + jj] = acc[ai][bj][m][1][jj]; }
;                     if constexpr (ROPE) {
;                         const int t = t0 & 2047;
; #pragma unroll
;                         for (int hf = 0; hf < 2; ++hf) {
;                             f32x4 cs, sn;
;                             if (m < 2) { const float c1 = ropeA[(t >> 6) * 16 + d], s1 = ropeA[1024 + (t >> 6) * 16 + d]; cs = (f32x4){c1, c1, c1, c1}; sn = (f32x4){s1, s1, s1, s1}; }
;                             else { const float* cb = ropeA + 2048 + (d - 16) * 64 + (t & 63) + 4 * hf; cs = *(const f32x4*)(cb); sn = *(const f32x4*)(cb + 1024); }
; #pragma unroll
;                             for (int jj = 0; jj < 4; ++jj) { const float pr = __shfl_xor(v[4 * hf + jj], 4); v[4 * hf + jj] = v[4 * hf + jj] * cs[jj] + sgn * pr * sn[jj]; }
;                             __builtin_amdgcn_sched_barrier(0);
;                         }
;                     }
;                     float zf[8], zb[8]; zf[0] = zf0; zb[0] = zb0;
; #pragma unroll
;                     for (int jj = 1; jj < 8; ++jj) { zf[jj] = zf[jj - 1] * zfs; zb[jj] = zb[jj - 1] * zbs; }
;                     u32x4 wf, wb;
;                     wf.x = cvt_pk_bf16(v[0] * zf[0], v[1] * zf[1]); wf.y = cvt_pk_bf16(v[2] * zf[2], v[3] * zf[3]); wf.z = cvt_pk_bf16(v[4] * zf[4], v[5] * zf[5]); wf.w = cvt_pk_bf16(v[6] * zf[6], v[7] * zf[7]);
;                     wb.x = cvt_pk_bf16(v[0] * zb[0], v[1] * zb[1]); wb.y = cvt_pk_bf16(v[2] * zb[2], v[3] * zb[3]); wb.z = cvt_pk_bf16(v[4] * zb[4], v[5] * zb[5]); wb.w = cvt_pk_bf16(v[6] * zb[6], v[7] * zb[7]);
;                     *(u32x4*)(KTZ + (size_t)r * NT + t0) = wf;
;                     *(u32x4*)(KTZ + (size_t)(256 + r) * NT + t0) = wb;
;                     __builtin_amdgcn_sched_barrier(0);
	v_cndmask_b32_e64 v47, v36, -v36, vcc
	v_mov_b32_e32 v44, v37
	v_pk_mul_f32 v[36:37], v[44:45], v[46:47]
	s_waitcnt lgkmcnt(1)
	v_cndmask_b32_e64 v47, v50, -v50, vcc
	v_mov_b32_e32 v44, v38
	v_add_f32_e32 v48, v48, v49
	v_add_f32_e32 v49, v36, v37
	v_pk_mul_f32 v[36:37], v[44:45], v[46:47]
	s_waitcnt lgkmcnt(0)
	v_cndmask_b32_e64 v47, v51, -v51, vcc
	v_mov_b32_e32 v44, v39
	v_add_f32_e32 v50, v36, v37
	v_pk_mul_f32 v[36:37], v[44:45], v[46:47]
	s_nop 0
	v_add_f32_e32 v46, v36, v37
	global_load_dword v37, v[104:105], off
	global_load_dword v38, v[106:107], off
	ds_bpermute_b32 v39, v177, v32
	v_mov_b32_e32 v36, v32
	ds_bpermute_b32 v32, v177, v33
	ds_bpermute_b32 v47, v177, v34
	ds_bpermute_b32 v51, v177, v35
	s_waitcnt lgkmcnt(3)
	v_cndmask_b32_e64 v39, v39, -v39, vcc
	s_waitcnt vmcnt(0)
	v_pk_mul_f32 v[44:45], v[36:37], v[38:39]
	s_waitcnt lgkmcnt(2)
	v_cndmask_b32_e64 v39, v32, -v32, vcc
	v_mov_b32_e32 v36, v33
	v_pk_mul_f32 v[32:33], v[36:37], v[38:39]
	s_waitcnt lgkmcnt(1)
	v_cndmask_b32_e64 v39, v47, -v47, vcc
	v_mov_b32_e32 v36, v34
	v_add_f32_e32 v44, v44, v45
	v_add_f32_e32 v45, v32, v33
	v_pk_mul_f32 v[32:33], v[36:37], v[38:39]
	s_waitcnt lgkmcnt(0)
	v_cndmask_b32_e64 v39, v51, -v51, vcc
	v_mov_b32_e32 v36, v35
	v_add_f32_e32 v47, v32, v33
	v_pk_mul_f32 v[32:33], v[36:37], v[38:39]
	s_nop 0
	v_add_f32_e32 v39, v32, v33
	v_mul_f32_e32 v32, v63, v48
	v_mul_f32_e32 v33, v75, v49
	v_cvt_pk_bf16_f32 v32, v32, v33
	v_mul_f32_e32 v33, v84, v50
	v_mul_f32_e32 v34, v86, v46
	v_cvt_pk_bf16_f32 v33, v33, v34
	v_mul_f32_e32 v34, v85, v44
	v_mul_f32_e32 v35, v88, v45
	v_cvt_pk_bf16_f32 v34, v34, v35
	v_mul_f32_e32 v35, v87, v47
	v_mul_f32_e32 v36, v71, v39
	v_cvt_pk_bf16_f32 v35, v35, v36
	v_mul_f32_e32 v36, v64, v48
	v_mul_f32_e32 v37, v60, v49
	v_cvt_pk_bf16_f32 v36, v36, v37
	v_mul_f32_e32 v37, v66, v50
	v_mul_f32_e32 v38, v68, v46
	v_cvt_pk_bf16_f32 v37, v37, v38
	v_mul_f32_e32 v38, v70, v44
	v_mul_f32_e32 v44, v72, v45
	v_mul_f32_e32 v39, v67, v39
	v_cvt_pk_bf16_f32 v38, v38, v44
	v_mul_f32_e32 v44, v65, v47
	v_cvt_pk_bf16_f32 v39, v44, v39
	global_store_dwordx4 v[40:41], v[32:35], off offset:256
	global_store_dwordx4 v[42:43], v[36:39], off offset:256
	global_load_dwordx4 v[32:35], v[98:99], off
	s_nop 0
	global_load_dwordx4 v[36:39], v[96:97], off
	ds_bpermute_b32 v41, v177, v28
	ds_bpermute_b32 v42, v177, v29
	ds_bpermute_b32 v44, v177, v30
	ds_bpermute_b32 v46, v177, v31
	v_mov_b32_e32 v40, v28
	v_mov_b32_e32 v28, v30
	s_waitcnt lgkmcnt(3)
	v_cndmask_b32_e64 v43, v41, -v41, vcc
	s_waitcnt lgkmcnt(2)
	v_cndmask_b32_e64 v45, v42, -v42, vcc
	s_waitcnt lgkmcnt(1)
	v_cndmask_b32_e64 v47, v44, -v44, vcc
	s_waitcnt lgkmcnt(0)
	v_cndmask_b32_e64 v49, v46, -v46, vcc
	s_waitcnt vmcnt(1)
	v_mov_b32_e32 v41, v32
	s_waitcnt vmcnt(0)
	v_mov_b32_e32 v42, v36
	v_mov_b32_e32 v32, v29
	v_mov_b32_e32 v44, v37
	v_mov_b32_e32 v29, v34
	v_mov_b32_e32 v46, v38
	v_mov_b32_e32 v34, v31
	v_mov_b32_e32 v48, v39
	v_pk_mul_f32 v[30:31], v[40:41], v[42:43]
	v_pk_mul_f32 v[32:33], v[32:33], v[44:45]
	v_pk_mul_f32 v[28:29], v[28:29], v[46:47]
	v_pk_mul_f32 v[34:35], v[34:35], v[48:49]
	v_add_f32_e32 v46, v30, v31
	v_add_f32_e32 v47, v32, v33
	v_add_f32_e32 v48, v28, v29
	v_add_f32_e32 v49, v34, v35
	global_load_dwordx4 v[28:31], v[92:93], off offset:16
	global_load_dwordx4 v[32:35], v[94:95], off offset:16
	ds_bpermute_b32 v37, v177, v24
	ds_bpermute_b32 v38, v177, v25
	ds_bpermute_b32 v40, v177, v26
	ds_bpermute_b32 v42, v177, v27
	v_mov_b32_e32 v36, v24
	v_mov_b32_e32 v24, v26
	s_waitcnt lgkmcnt(3)
	v_cndmask_b32_e64 v39, v37, -v37, vcc
	s_waitcnt lgkmcnt(2)
	v_cndmask_b32_e64 v41, v38, -v38, vcc
	s_waitcnt lgkmcnt(1)
	v_cndmask_b32_e64 v43, v40, -v40, vcc
	s_waitcnt lgkmcnt(0)
	v_cndmask_b32_e64 v45, v42, -v42, vcc
	s_waitcnt vmcnt(1)
	v_mov_b32_e32 v37, v28
	s_waitcnt vmcnt(0)
	v_mov_b32_e32 v38, v32
	v_mov_b32_e32 v28, v25
	v_mov_b32_e32 v40, v33
	v_mov_b32_e32 v25, v30
	v_mov_b32_e32 v42, v34
	v_mov_b32_e32 v30, v27
	v_mov_b32_e32 v44, v35
	v_pk_mul_f32 v[26:27], v[36:37], v[38:39]
	v_pk_mul_f32 v[28:29], v[28:29], v[40:41]
	v_pk_mul_f32 v[24:25], v[24:25], v[42:43]
	v_pk_mul_f32 v[30:31], v[30:31], v[44:45]
	v_add_f32_e32 v32, v26, v27
	v_add_f32_e32 v33, v28, v29
	v_add_f32_e32 v24, v24, v25
	v_add_f32_e32 v25, v30, v31
	v_mul_f32_e32 v26, v63, v46
	v_mul_f32_e32 v27, v75, v47
	v_cvt_pk_bf16_f32 v26, v26, v27
	v_mul_f32_e32 v27, v84, v48
	v_mul_f32_e32 v28, v86, v49
	v_cvt_pk_bf16_f32 v27, v27, v28
	v_mul_f32_e32 v28, v85, v32
	v_mul_f32_e32 v29, v88, v33
	v_cvt_pk_bf16_f32 v28, v28, v29
	v_mul_f32_e32 v29, v87, v24
	v_mul_f32_e32 v30, v71, v25
	v_cvt_pk_bf16_f32 v29, v29, v30
	v_mul_f32_e32 v30, v64, v46
	v_mul_f32_e32 v31, v60, v47
	v_cvt_pk_bf16_f32 v30, v30, v31
	v_mul_f32_e32 v31, v66, v48
	v_mul_f32_e32 v32, v70, v32
	v_mul_f32_e32 v33, v72, v33
	v_mul_f32_e32 v24, v65, v24
	v_mul_f32_e32 v25, v67, v25
	s_mov_b64 s[0:1], 0x1400000
	v_mul_f32_e32 v34, v68, v49
	v_cvt_pk_bf16_f32 v31, v31, v34
	v_cvt_pk_bf16_f32 v32, v32, v33
	v_cvt_pk_bf16_f32 v33, v24, v25
	v_lshl_add_u64 v[24:25], v[120:121], 0, s[0:1]
	s_mov_b32 s0, 0x1400000
	v_add_co_u32_e64 v34, s[4:5], s0, v120
	s_mov_b64 s[0:1], 0x3400000
	s_nop 0
	v_addc_co_u32_e64 v35, s[4:5], 0, v121, s[4:5]
	global_store_dwordx4 v[34:35], v[26:29], off
	s_nop 1
	v_lshl_add_u64 v[26:27], v[120:121], 0, s[0:1]
	s_mov_b32 s0, 0x3400000
	v_add_co_u32_e64 v28, s[4:5], s0, v120
	s_nop 1
	v_addc_co_u32_e64 v29, s[4:5], 0, v121, s[4:5]
	global_store_dwordx4 v[28:29], v[30:33], off
	global_load_dwordx4 v[28:31], v[98:99], off
	s_nop 0
	global_load_dwordx4 v[32:35], v[96:97], off
	ds_bpermute_b32 v37, v177, v20
	ds_bpermute_b32 v38, v177, v21
	ds_bpermute_b32 v40, v177, v22
	ds_bpermute_b32 v42, v177, v23
	v_mov_b32_e32 v36, v20
	v_mov_b32_e32 v20, v22
	s_waitcnt lgkmcnt(3)
;     __device__ __forceinline__ void operator()(const AccT& acc, const Unit& u, int wr, int wc, int fr, int fq) const {
;     ...
;             for (int m = 0; m < 4; ++m) {
;                 const int r = rbase + ai * 128 + m * 16;
;                 const int d = 4 * (2 * m + (fr >> 3)) + j;
; #pragma unroll
;                 for (int bj = 0; bj < 2; ++bj) {
;                     const int t0 = tb + bj * 128;
;                     float v[8];
; #pragma unroll
;                     for (int jj = 0; jj < 4; ++jj) { v[jj] = acc[ai][bj][m][0][jj]; v[4 + jj] = acc[ai][bj][m][1][jj]; }
;                     if constexpr (ROPE) {
;                         const int t = t0 & 2047;
; #pragma unroll
;                         for (int hf = 0; hf < 2; ++hf) {
;                             f32x4 cs, sn;
;                             if (m < 2) { const float c1 = ropeA[(t >> 6) * 16 + d], s1 = ropeA[1024 + (t >> 6) * 16 + d]; cs = (f32x4){c1, c1, c1, c1}; sn = (f32x4){s1, s1, s1, s1}; }
;                             else { const float* cb = ropeA + 2048 + (d - 16) * 64 + (t & 63) + 4 * hf; cs = *(const f32x4*)(cb); sn = *(const f32x4*)(cb + 1024); }
; #pragma unroll
;                             for (int jj = 0; jj < 4; ++jj) { const float pr = __shfl_xor(v[4 * hf + jj], 4); v[4 * hf + jj] = v[4 * hf + jj] * cs[jj] + sgn * pr * sn[jj]; }
;                             __builtin_amdgcn_sched_barrier(0);
;                         }
;                     }
;                     float zf[8], zb[8]; zf[0] = zf0; zb[0] = zb0;
; #pragma unroll
;                     for (int jj = 1; jj < 8; ++jj) { zf[jj] = zf[jj - 1] * zfs; zb[jj] = zb[jj - 1] * zbs; }
;                     u32x4 wf, wb;
;                     wf.x = cvt_pk_bf16(v[0] * zf[0], v[1] * zf[1]); wf.y = cvt_pk_bf16(v[2] * zf[2], v[3] * zf[3]); wf.z = cvt_pk_bf16(v[4] * zf[4], v[5] * zf[5]); wf.w = cvt_pk_bf16(v[6] * zf[6], v[7] * zf[7]);
;                     wb.x = cvt_pk_bf16(v[0] * zb[0], v[1] * zb[1]); wb.y = cvt_pk_bf16(v[2] * zb[2], v[3] * zb[3]); wb.z = cvt_pk_bf16(v[4] * zb[4], v[5] * zb[5]); wb.w = cvt_pk_bf16(v[6] * zb[6], v[7] * zb[7]);
;                     *(u32x4*)(KTZ + (size_t)r * NT + t0) = wf;
;                     *(u32x4*)(KTZ + (size_t)(256 + r) * NT + t0) = wb;
;                     __builtin_amdgcn_sched_barrier(0);
	v_cndmask_b32_e64 v39, v37, -v37, vcc
	s_waitcnt lgkmcnt(2)
	v_cndmask_b32_e64 v41, v38, -v38, vcc
	s_waitcnt lgkmcnt(1)
	v_cndmask_b32_e64 v43, v40, -v40, vcc
	s_waitcnt lgkmcnt(0)
	v_cndmask_b32_e64 v45, v42, -v42, vcc
	s_waitcnt vmcnt(1)
	v_mov_b32_e32 v37, v28
	s_waitcnt vmcnt(0)
	v_mov_b32_e32 v38, v32
	v_mov_b32_e32 v28, v21
	v_mov_b32_e32 v40, v33
	v_mov_b32_e32 v21, v30
	v_mov_b32_e32 v42, v34
	v_mov_b32_e32 v30, v23
	v_mov_b32_e32 v44, v35
	v_pk_mul_f32 v[22:23], v[36:37], v[38:39]
	v_pk_mul_f32 v[28:29], v[28:29], v[40:41]
	v_pk_mul_f32 v[20:21], v[20:21], v[42:43]
	v_pk_mul_f32 v[30:31], v[30:31], v[44:45]
	v_add_f32_e32 v42, v22, v23
	v_add_f32_e32 v43, v28, v29
	v_add_f32_e32 v44, v20, v21
	v_add_f32_e32 v45, v30, v31
	global_load_dwordx4 v[20:23], v[92:93], off offset:16
	global_load_dwordx4 v[28:31], v[94:95], off offset:16
	ds_bpermute_b32 v33, v177, v16
	ds_bpermute_b32 v34, v177, v17
	ds_bpermute_b32 v36, v177, v18
	ds_bpermute_b32 v38, v177, v19
	v_mov_b32_e32 v32, v16
	v_mov_b32_e32 v16, v18
	s_waitcnt lgkmcnt(3)
	v_cndmask_b32_e64 v35, v33, -v33, vcc
	s_waitcnt lgkmcnt(2)
	v_cndmask_b32_e64 v37, v34, -v34, vcc
	s_waitcnt lgkmcnt(1)
	v_cndmask_b32_e64 v39, v36, -v36, vcc
	s_waitcnt lgkmcnt(0)
	v_cndmask_b32_e64 v41, v38, -v38, vcc
	s_waitcnt vmcnt(1)
	v_mov_b32_e32 v33, v20
	s_waitcnt vmcnt(0)
	v_mov_b32_e32 v34, v28
	v_mov_b32_e32 v20, v17
	v_mov_b32_e32 v36, v29
	v_mov_b32_e32 v17, v22
	v_mov_b32_e32 v38, v30
	v_mov_b32_e32 v22, v19
	v_mov_b32_e32 v40, v31
	v_pk_mul_f32 v[18:19], v[32:33], v[34:35]
	v_pk_mul_f32 v[20:21], v[20:21], v[36:37]
	v_pk_mul_f32 v[16:17], v[16:17], v[38:39]
	v_pk_mul_f32 v[22:23], v[22:23], v[40:41]
	v_add_f32_e32 v28, v18, v19
	v_add_f32_e32 v29, v20, v21
	v_add_f32_e32 v30, v16, v17
	v_add_f32_e32 v23, v22, v23
	v_mul_f32_e32 v16, v63, v42
	v_mul_f32_e32 v17, v75, v43
	v_cvt_pk_bf16_f32 v16, v16, v17
	v_mul_f32_e32 v17, v84, v44
	v_mul_f32_e32 v18, v86, v45
	v_cvt_pk_bf16_f32 v17, v17, v18
	v_mul_f32_e32 v18, v85, v28
	v_mul_f32_e32 v19, v88, v29
	v_cvt_pk_bf16_f32 v18, v18, v19
	v_mul_f32_e32 v19, v87, v30
	v_mul_f32_e32 v20, v71, v23
	v_cvt_pk_bf16_f32 v19, v19, v20
	v_mul_f32_e32 v20, v64, v42
	v_mul_f32_e32 v21, v60, v43
	v_cvt_pk_bf16_f32 v20, v20, v21
	v_mul_f32_e32 v21, v66, v44
	v_mul_f32_e32 v22, v68, v45
	v_cvt_pk_bf16_f32 v21, v21, v22
	v_mul_f32_e32 v22, v70, v28
	v_mul_f32_e32 v28, v72, v29
	v_mul_f32_e32 v23, v67, v23
	v_cvt_pk_bf16_f32 v22, v22, v28
	v_mul_f32_e32 v28, v65, v30
	v_cvt_pk_bf16_f32 v23, v28, v23
	global_store_dwordx4 v[24:25], v[16:19], off offset:256
	global_store_dwordx4 v[26:27], v[20:23], off offset:256
	global_load_dwordx4 v[16:19], v[82:83], off
	s_nop 0
	global_load_dwordx4 v[20:23], v[80:81], off
	ds_bpermute_b32 v25, v177, v12
	ds_bpermute_b32 v26, v177, v13
	ds_bpermute_b32 v28, v177, v14
	ds_bpermute_b32 v30, v177, v15
	v_mov_b32_e32 v24, v12
	v_mov_b32_e32 v12, v14
	s_waitcnt lgkmcnt(3)
	v_cndmask_b32_e64 v27, v25, -v25, vcc
	s_waitcnt lgkmcnt(2)
	v_cndmask_b32_e64 v29, v26, -v26, vcc
	s_waitcnt lgkmcnt(1)
	v_cndmask_b32_e64 v31, v28, -v28, vcc
	s_waitcnt lgkmcnt(0)
	v_cndmask_b32_e64 v33, v30, -v30, vcc
	s_waitcnt vmcnt(1)
	v_mov_b32_e32 v25, v16
	s_waitcnt vmcnt(0)
	v_mov_b32_e32 v26, v20
	v_mov_b32_e32 v16, v13
	v_mov_b32_e32 v28, v21
	v_mov_b32_e32 v13, v18
	v_mov_b32_e32 v30, v22
	v_mov_b32_e32 v18, v15
	v_mov_b32_e32 v32, v23
	v_pk_mul_f32 v[14:15], v[24:25], v[26:27]
	v_pk_mul_f32 v[16:17], v[16:17], v[28:29]
	v_pk_mul_f32 v[12:13], v[12:13], v[30:31]
	v_pk_mul_f32 v[18:19], v[18:19], v[32:33]
	v_add_f32_e32 v30, v14, v15
	v_add_f32_e32 v31, v16, v17
	v_add_f32_e32 v32, v12, v13
	v_add_f32_e32 v33, v18, v19
	global_load_dwordx4 v[12:15], v[76:77], off offset:16
	global_load_dwordx4 v[16:19], v[78:79], off offset:16
	ds_bpermute_b32 v21, v177, v8
	ds_bpermute_b32 v22, v177, v9
	ds_bpermute_b32 v24, v177, v10
	ds_bpermute_b32 v26, v177, v11
	v_mov_b32_e32 v20, v8
	v_mov_b32_e32 v8, v10
	s_waitcnt lgkmcnt(3)
	v_cndmask_b32_e64 v23, v21, -v21, vcc
	s_waitcnt lgkmcnt(2)
	v_cndmask_b32_e64 v25, v22, -v22, vcc
	s_waitcnt lgkmcnt(1)
	v_cndmask_b32_e64 v27, v24, -v24, vcc
	s_waitcnt lgkmcnt(0)
	v_cndmask_b32_e64 v29, v26, -v26, vcc
	s_waitcnt vmcnt(1)
	v_mov_b32_e32 v21, v12
	s_waitcnt vmcnt(0)
;     __device__ __forceinline__ void operator()(const AccT& acc, const Unit& u, int wr, int wc, int fr, int fq) const {
;     ...
;             for (int m = 0; m < 4; ++m) {
;                 const int r = rbase + ai * 128 + m * 16;
;                 const int d = 4 * (2 * m + (fr >> 3)) + j;
; #pragma unroll
;                 for (int bj = 0; bj < 2; ++bj) {
;                     const int t0 = tb + bj * 128;
;                     float v[8];
; #pragma unroll
;                     for (int jj = 0; jj < 4; ++jj) { v[jj] = acc[ai][bj][m][0][jj]; v[4 + jj] = acc[ai][bj][m][1][jj]; }
;                     if constexpr (ROPE) {
;                         const int t = t0 & 2047;
; #pragma unroll
;                         for (int hf = 0; hf < 2; ++hf) {
;                             f32x4 cs, sn;
;                             if (m < 2) { const float c1 = ropeA[(t >> 6) * 16 + d], s1 = ropeA[1024 + (t >> 6) * 16 + d]; cs = (f32x4){c1, c1, c1, c1}; sn = (f32x4){s1, s1, s1, s1}; }
;                             else { const float* cb = ropeA + 2048 + (d - 16) * 64 + (t & 63) + 4 * hf; cs = *(const f32x4*)(cb); sn = *(const f32x4*)(cb + 1024); }
; #pragma unroll
;                             for (int jj = 0; jj < 4; ++jj) { const float pr = __shfl_xor(v[4 * hf + jj], 4); v[4 * hf + jj] = v[4 * hf + jj] * cs[jj] + sgn * pr * sn[jj]; }
;                             __builtin_amdgcn_sched_barrier(0);
;                         }
;                     }
;                     float zf[8], zb[8]; zf[0] = zf0; zb[0] = zb0;
; #pragma unroll
;                     for (int jj = 1; jj < 8; ++jj) { zf[jj] = zf[jj - 1] * zfs; zb[jj] = zb[jj - 1] * zbs; }
;                     u32x4 wf, wb;
;                     wf.x = cvt_pk_bf16(v[0] * zf[0], v[1] * zf[1]); wf.y = cvt_pk_bf16(v[2] * zf[2], v[3] * zf[3]); wf.z = cvt_pk_bf16(v[4] * zf[4], v[5] * zf[5]); wf.w = cvt_pk_bf16(v[6] * zf[6], v[7] * zf[7]);
;                     wb.x = cvt_pk_bf16(v[0] * zb[0], v[1] * zb[1]); wb.y = cvt_pk_bf16(v[2] * zb[2], v[3] * zb[3]); wb.z = cvt_pk_bf16(v[4] * zb[4], v[5] * zb[5]); wb.w = cvt_pk_bf16(v[6] * zb[6], v[7] * zb[7]);
;                     *(u32x4*)(KTZ + (size_t)r * NT + t0) = wf;
;                     *(u32x4*)(KTZ + (size_t)(256 + r) * NT + t0) = wb;
;                     __builtin_amdgcn_sched_barrier(0);
	v_mov_b32_e32 v22, v16
	v_mov_b32_e32 v12, v9
	v_mov_b32_e32 v24, v17
	v_mov_b32_e32 v9, v14
	v_mov_b32_e32 v26, v18
	v_mov_b32_e32 v14, v11
	v_mov_b32_e32 v28, v19
	v_pk_mul_f32 v[10:11], v[20:21], v[22:23]
	v_pk_mul_f32 v[12:13], v[12:13], v[24:25]
	v_pk_mul_f32 v[8:9], v[8:9], v[26:27]
	v_pk_mul_f32 v[14:15], v[14:15], v[28:29]
	v_add_f32_e32 v16, v10, v11
	v_add_f32_e32 v17, v12, v13
	v_add_f32_e32 v8, v8, v9
	v_add_f32_e32 v9, v14, v15
	v_mul_f32_e32 v10, v63, v30
	v_mul_f32_e32 v11, v75, v31
	v_cvt_pk_bf16_f32 v10, v10, v11
	v_mul_f32_e32 v11, v84, v32
	v_mul_f32_e32 v12, v86, v33
	v_cvt_pk_bf16_f32 v11, v11, v12
	v_mul_f32_e32 v12, v85, v16
	v_mul_f32_e32 v13, v88, v17
	v_cvt_pk_bf16_f32 v12, v12, v13
	v_mul_f32_e32 v13, v87, v8
	v_mul_f32_e32 v14, v71, v9
	v_cvt_pk_bf16_f32 v13, v13, v14
	v_mul_f32_e32 v14, v64, v30
	v_mul_f32_e32 v15, v60, v31
	v_cvt_pk_bf16_f32 v14, v14, v15
	v_mul_f32_e32 v15, v66, v32
	v_mul_f32_e32 v18, v68, v33
	v_cvt_pk_bf16_f32 v15, v15, v18
	v_add_co_u32_e64 v18, s[4:5], s63, v120
	v_mul_f32_e32 v16, v70, v16
	v_mul_f32_e32 v17, v72, v17
	v_addc_co_u32_e64 v19, s[4:5], 0, v121, s[4:5]
	v_cvt_pk_bf16_f32 v16, v16, v17
	v_mul_f32_e32 v8, v65, v8
	v_mul_f32_e32 v9, v67, v9
	v_cvt_pk_bf16_f32 v17, v8, v9
	global_store_dwordx4 v[18:19], v[10:13], off
	v_lshl_add_u64 v[8:9], v[120:121], 0, s[26:27]
	s_nop 0
	v_add_co_u32_e64 v12, s[4:5], s64, v120
	v_lshl_add_u64 v[10:11], v[120:121], 0, s[28:29]
	s_nop 0
	v_addc_co_u32_e64 v13, s[4:5], 0, v121, s[4:5]
	global_store_dwordx4 v[12:13], v[14:17], off
	global_load_dwordx4 v[12:15], v[82:83], off
	s_nop 0
	global_load_dwordx4 v[16:19], v[80:81], off
	ds_bpermute_b32 v34, v177, v4
	ds_bpermute_b32 v32, v177, v5
	ds_bpermute_b32 v33, v177, v6
	ds_bpermute_b32 v28, v177, v7
	global_load_dwordx4 v[20:23], v[76:77], off offset:16
	global_load_dwordx4 v[24:27], v[78:79], off offset:16
	s_waitcnt lgkmcnt(0)
	v_cndmask_b32_e64 v29, v28, -v28, vcc
	v_mov_b32_e32 v30, v7
	s_waitcnt vmcnt(3)
	v_mov_b32_e32 v31, v15
	s_waitcnt vmcnt(2)
	v_mov_b32_e32 v28, v19
	v_cndmask_b32_e64 v19, v33, -v33, vcc
	v_mov_b32_e32 v7, v14
	v_cndmask_b32_e64 v15, v32, -v32, vcc
	v_mov_b32_e32 v32, v5
	v_mov_b32_e32 v33, v13
	v_mov_b32_e32 v14, v17
	v_cndmask_b32_e64 v17, v34, -v34, vcc
	v_mov_b32_e32 v5, v12
	ds_bpermute_b32 v13, v177, v0
	v_mov_b32_e32 v12, v0
	ds_bpermute_b32 v34, v177, v1
	ds_bpermute_b32 v35, v177, v2
	v_mov_b32_e32 v0, v2
	ds_bpermute_b32 v2, v177, v3
	v_pk_mul_f32 v[28:29], v[30:31], v[28:29]
	v_pk_mul_f32 v[6:7], v[6:7], v[18:19]
	v_pk_mul_f32 v[14:15], v[32:33], v[14:15]
	v_pk_mul_f32 v[4:5], v[4:5], v[16:17]
	v_add_f32_e32 v18, v28, v29
	v_add_f32_e32 v19, v6, v7
	v_add_f32_e32 v28, v14, v15
	v_add_f32_e32 v29, v4, v5
	s_waitcnt lgkmcnt(3)
	v_cndmask_b32_e64 v5, v13, -v13, vcc
	s_waitcnt lgkmcnt(2)
	v_cndmask_b32_e64 v7, v34, -v34, vcc
	s_waitcnt lgkmcnt(1)
	v_cndmask_b32_e64 v15, v35, -v35, vcc
	s_waitcnt lgkmcnt(0)
	v_cndmask_b32_e64 v17, v2, -v2, vcc
	s_waitcnt vmcnt(1)
	v_mov_b32_e32 v13, v20
	s_waitcnt vmcnt(0)
	v_mov_b32_e32 v4, v24
	v_mov_b32_e32 v20, v1
	v_mov_b32_e32 v6, v25
	v_mov_b32_e32 v1, v22
	v_mov_b32_e32 v14, v26
	v_mov_b32_e32 v22, v3
	v_mov_b32_e32 v16, v27
	v_pk_mul_f32 v[2:3], v[12:13], v[4:5]
	v_pk_mul_f32 v[4:5], v[20:21], v[6:7]
	v_pk_mul_f32 v[0:1], v[0:1], v[14:15]
	v_pk_mul_f32 v[6:7], v[22:23], v[16:17]
	v_add_f32_e32 v12, v2, v3
	v_add_f32_e32 v13, v4, v5
	v_add_f32_e32 v14, v0, v1
	v_add_f32_e32 v7, v6, v7
	v_mul_f32_e32 v0, v63, v29
	v_mul_f32_e32 v1, v75, v28
	v_cvt_pk_bf16_f32 v0, v0, v1
	v_mul_f32_e32 v1, v84, v19
	v_mul_f32_e32 v2, v86, v18
	v_cvt_pk_bf16_f32 v1, v1, v2
	v_mul_f32_e32 v2, v85, v12
	v_mul_f32_e32 v3, v88, v13
	v_cvt_pk_bf16_f32 v2, v2, v3
	v_mul_f32_e32 v3, v87, v14
	v_mul_f32_e32 v4, v71, v7
	v_cvt_pk_bf16_f32 v3, v3, v4
	v_mul_f32_e32 v4, v64, v29
	v_mul_f32_e32 v5, v60, v28
	v_cvt_pk_bf16_f32 v4, v4, v5
	v_mul_f32_e32 v5, v66, v19
	v_mul_f32_e32 v6, v68, v18
	v_cvt_pk_bf16_f32 v5, v5, v6
	v_mul_f32_e32 v6, v70, v12
	v_mul_f32_e32 v12, v72, v13
	v_mul_f32_e32 v7, v67, v7
	v_cvt_pk_bf16_f32 v6, v6, v12
	v_mul_f32_e32 v12, v65, v14
	v_cvt_pk_bf16_f32 v7, v12, v7
	global_store_dwordx4 v[8:9], v[0:3], off offset:256
	global_store_dwordx4 v[10:11], v[4:7], off offset:256
	s_and_b64 vcc, exec, s[2:3]
	s_mov_b32 s33, s30
	s_mov_b64 s[4:5], s[38:39]
	s_mov_b64 s[0:1], s[36:37]
	s_cbranch_vccz .LBB0_606
	s_waitcnt vmcnt(0)
	s_cmpk_gt_u32 s42, 0xff
	s_cbranch_scc1 .LBB0_617
	s_barrier

; #define PG8_STAGE(bufoff, gbase, voff) do { _Pragma("unroll") for (int _i = 0; _i < 2; ++_i) \
;         __builtin_amdgcn_global_load_lds((const unsigned*)((const char*)(gbase) + (voff)[_i]), (LAS unsigned*)(lds + (bufoff) + ldsw + _i * 8192), 16, 0, 0); } while (0)
; #define PG8_LDA(dst, b, h) do { _Pragma("unroll") for (int m = 0; m < 4; ++m) _Pragma("unroll") for (int k = 0; k < 2; ++k) dst[m][k] = *(const LAS bf16x8*)(lds + PG8_SA(b, h) + aoff + m * 2048 + k * 1024); } while (0)
; #define PG8_LDB(dst, b, h) do { _Pragma("unroll") for (int n = 0; n < 2; ++n) _Pragma("unroll") for (int k = 0; k < 2; ++k) dst[n][k] = *(const LAS bf16x8*)(lds + PG8_SB(b, h) + boff + n * 2048 + k * 1024); } while (0)
; #define PG8_WAIT_V(n) asm volatile("s_waitcnt vmcnt(" #n ")" ::: "memory")
; #define PG8_WAIT_L(n) asm volatile("s_waitcnt lgkmcnt(" #n ")" ::: "memory")
; #define PG8_BAR __builtin_amdgcn_s_barrier()
; #define PG8_SCHED __builtin_amdgcn_sched_barrier(0)
; template <class Epi, class Sched>
; __device__ __forceinline__ void gemm_phase(LAS unsigned char* lds, const Gemm g, const Sched& S, const Epi& E) {
;     ...
;         const bool has_next = S.next(ui + 1, nxt);
;         const char* nA = has_next ? (const char*)g.A + (size_t)nxt.pm * tstep : cA; const char* nB = has_next ? (const char*)g.Bt + (size_t)nxt.pn * tstep : cB;
;         for (int t = 0; t < nt; t += 2) {
;             const bool last = (t == nt - 2);
;             const char* a1 = cA + (size_t)(t + 1) * kstep;
;             const char* a2 = last ? nA : cA + (size_t)(t + 2) * kstep; const char* b2 = last ? nB : cB + (size_t)(t + 2) * kstep;
;             const char* a3 = a2 + kstep; const char* b3 = b2 + kstep;
;             PG8_LDB(B0, 0, 0); PG8_SCHED; PG8_LDA(At, 0, 0); PG8_STAGE(PG8_SA(1, 1), a1 + hstep, voffA);
;             PG8_WAIT_L(8); PG8_BAR; PG8_WAIT_L(0); PG8_MMA(0, 0, At, B0); PG8_BAR; PG8_SCHED;
;             PG8_LDB(B1, 0, 1); PG8_STAGE(PG8_SB(0, 0), b2, voffB);
;             PG8_BAR; PG8_WAIT_L(0); PG8_MMA(0, 1, At, B1); PG8_BAR;
;             PG8_LDA(At, 0, 1); PG8_STAGE(PG8_SA(0, 0), a2, voffA);
;             PG8_BAR; PG8_WAIT_L(0); PG8_MMA(1, 0, At, B0); PG8_BAR; PG8_SCHED;
;             PG8_STAGE(PG8_SB(0, 1), b2 + hstep, voffB);
;             PG8_WAIT_V(6); PG8_BAR; PG8_MMA(1, 1, At, B1); PG8_BAR;
.LBB0_632:
	s_ashr_i32 s23, s22, 31
	v_cmp_lt_i64_e32 vcc, s[24:25], v[140:141]
	s_lshl_b64 s[24:25], s[22:23], 19
	s_add_u32 s24, s38, s24
	s_addc_u32 s25, s39, s25
	s_and_b64 s[26:27], vcc, exec
	s_cselect_b32 s23, s25, s31
	s_cselect_b32 s61, s24, s30
	s_ashr_i32 s21, s20, 31
	s_lshl_b64 s[26:27], s[20:21], 19
	s_add_u32 s26, s96, s26
	s_addc_u32 s27, s97, s27
	s_and_b64 s[36:37], vcc, exec
	s_cselect_b32 s21, s27, s35
	s_cselect_b32 s62, s26, s34
	s_add_u32 s30, s30, 0x40080
	s_addc_u32 s31, s31, 0
	s_add_u32 s63, s34, 0x100
	s_addc_u32 s64, s35, 0
	s_mov_b32 s65, -2
	s_waitcnt lgkmcnt(0)
	ds_read_b128 v[150:153], v147
	ds_read_b128 v[154:157], v147 offset:1024
	ds_read_b128 v[158:161], v147 offset:2048
	ds_read_b128 v[162:165], v147 offset:3072
	s_add_u32 s34, s30, 0xfffc0080
	s_addc_u32 s35, s31, -1
	s_cmp_eq_u32 s65, 12
	s_cselect_b32 s37, s23, s35
	s_cselect_b32 s36, s61, s34
	s_cselect_b32 s35, s21, s64
	s_cselect_b32 s34, s62, s63
	s_add_i32 m0, s29, 0xc000
	ds_read_b128 v[166:169], v148
	ds_read_b128 v[170:173], v148 offset:1024
	ds_read_b128 v[174:177], v148 offset:2048
	ds_read_b128 v[178:181], v148 offset:3072
	ds_read_b128 v[182:185], v148 offset:4096
	ds_read_b128 v[186:189], v148 offset:5120
	ds_read_b128 v[190:193], v148 offset:6144
	ds_read_b128 v[194:197], v148 offset:7168
	global_load_lds_dwordx4 v136, s[30:31]
	s_add_i32 m0, s29, 0xe000
	s_nop 0
	global_load_lds_dwordx4 v138, s[30:31]
	s_waitcnt lgkmcnt(8)
	s_waitcnt vmcnt(8)
	s_setprio 1
	s_barrier
	s_waitcnt lgkmcnt(0)
	v_mfma_f32_16x16x32_bf16 v[124:127], v[150:153], v[166:169], 0
	v_mfma_f32_16x16x32_bf16 v[120:123], v[158:161], v[166:169], 0
	v_mfma_f32_16x16x32_bf16 v[116:119], v[150:153], v[174:177], 0
	v_mfma_f32_16x16x32_bf16 v[108:111], v[158:161], v[174:177], 0
	v_mfma_f32_16x16x32_bf16 v[100:103], v[150:153], v[182:185], 0
	v_mfma_f32_16x16x32_bf16 v[92:95], v[158:161], v[182:185], 0
	v_mfma_f32_16x16x32_bf16 v[84:87], v[150:153], v[190:193], 0
	v_mfma_f32_16x16x32_bf16 v[76:79], v[158:161], v[190:193], 0
	v_mfma_f32_16x16x32_bf16 v[124:127], v[154:157], v[170:173], v[124:127]
	v_mfma_f32_16x16x32_bf16 v[120:123], v[162:165], v[170:173], v[120:123]
	v_mfma_f32_16x16x32_bf16 v[116:119], v[154:157], v[178:181], v[116:119]
	v_mfma_f32_16x16x32_bf16 v[108:111], v[162:165], v[178:181], v[108:111]
	v_mfma_f32_16x16x32_bf16 v[100:103], v[154:157], v[186:189], v[100:103]
	v_mfma_f32_16x16x32_bf16 v[92:95], v[162:165], v[186:189], v[92:95]
	v_mfma_f32_16x16x32_bf16 v[84:87], v[154:157], v[194:197], v[84:87]
	v_mfma_f32_16x16x32_bf16 v[76:79], v[162:165], v[194:197], v[76:79]
	s_barrier
	s_setprio 0
	s_add_i32 s66, s54, s43
	s_mov_b32 m0, s66
	ds_read_b128 v[202:205], v149
	ds_read_b128 v[206:209], v149 offset:1024
	ds_read_b128 v[210:213], v149 offset:2048
	ds_read_b128 v[214:217], v149 offset:3072
	global_load_lds_dwordx4 v130, s[34:35]
	s_add_i32 m0, s66, 0x2000
	s_nop 0
	global_load_lds_dwordx4 v134, s[34:35]
	s_waitcnt vmcnt(8)
	s_setprio 1
	s_barrier
	s_waitcnt lgkmcnt(0)
	v_mfma_f32_16x16x32_bf16 v[112:115], v[202:205], v[166:169], 0
	v_mfma_f32_16x16x32_bf16 v[104:107], v[210:213], v[166:169], 0
	v_mfma_f32_16x16x32_bf16 v[96:99], v[202:205], v[174:177], 0
	v_mfma_f32_16x16x32_bf16 v[88:91], v[210:213], v[174:177], 0
	v_mfma_f32_16x16x32_bf16 v[80:83], v[202:205], v[182:185], 0
	v_mfma_f32_16x16x32_bf16 v[72:75], v[210:213], v[182:185], 0
	v_mfma_f32_16x16x32_bf16 v[68:71], v[202:205], v[190:193], 0
	v_mfma_f32_16x16x32_bf16 v[64:67], v[210:213], v[190:193], 0
	v_mfma_f32_16x16x32_bf16 v[112:115], v[206:209], v[170:173], v[112:115]
	v_mfma_f32_16x16x32_bf16 v[104:107], v[214:217], v[170:173], v[104:107]
	v_mfma_f32_16x16x32_bf16 v[96:99], v[206:209], v[178:181], v[96:99]
	v_mfma_f32_16x16x32_bf16 v[88:91], v[214:217], v[178:181], v[88:91]
	v_mfma_f32_16x16x32_bf16 v[80:83], v[206:209], v[186:189], v[80:83]
	v_mfma_f32_16x16x32_bf16 v[72:75], v[214:217], v[186:189], v[72:75]
	v_mfma_f32_16x16x32_bf16 v[68:71], v[206:209], v[194:197], v[68:71]
	v_mfma_f32_16x16x32_bf16 v[64:67], v[214:217], v[194:197], v[64:67]
	s_barrier
	s_setprio 0
	s_mov_b32 m0, s29
	v_lshl_add_u64 v[220:221], s[36:37], 0, v[128:129]
	ds_read_b128 v[166:169], v148 offset:16384
	ds_read_b128 v[170:173], v148 offset:17408
	ds_read_b128 v[174:177], v148 offset:18432
	ds_read_b128 v[178:181], v148 offset:19456
	ds_read_b128 v[182:185], v148 offset:20480
	ds_read_b128 v[186:189], v148 offset:21504
	ds_read_b128 v[190:193], v148 offset:22528
	ds_read_b128 v[194:197], v148 offset:23552
	global_load_lds_dwordx4 v128, s[36:37]
	v_lshl_add_u64 v[222:223], s[36:37], 0, v[132:133]
	s_mov_b32 m0, s44
	s_nop 0
	global_load_lds_dwordx4 v132, s[36:37]
	s_setprio 1
	s_barrier
	s_waitcnt lgkmcnt(0)
	v_mfma_f32_16x16x32_bf16 v[60:63], v[150:153], v[166:169], 0
	v_mfma_f32_16x16x32_bf16 v[56:59], v[158:161], v[166:169], 0
	v_mfma_f32_16x16x32_bf16 v[52:55], v[150:153], v[174:177], 0
	v_mfma_f32_16x16x32_bf16 v[44:47], v[158:161], v[174:177], 0
	v_mfma_f32_16x16x32_bf16 v[36:39], v[150:153], v[182:185], 0
	v_mfma_f32_16x16x32_bf16 v[28:31], v[158:161], v[182:185], 0
	v_mfma_f32_16x16x32_bf16 v[20:23], v[150:153], v[190:193], 0
	v_mfma_f32_16x16x32_bf16 v[12:15], v[158:161], v[190:193], 0
	v_mfma_f32_16x16x32_bf16 v[60:63], v[154:157], v[170:173], v[60:63]
	v_mfma_f32_16x16x32_bf16 v[56:59], v[162:165], v[170:173], v[56:59]
	v_mfma_f32_16x16x32_bf16 v[52:55], v[154:157], v[178:181], v[52:55]
	v_mfma_f32_16x16x32_bf16 v[44:47], v[162:165], v[178:181], v[44:47]
	v_mfma_f32_16x16x32_bf16 v[36:39], v[154:157], v[186:189], v[36:39]
	v_mfma_f32_16x16x32_bf16 v[28:31], v[162:165], v[186:189], v[28:31]
	v_mfma_f32_16x16x32_bf16 v[20:23], v[154:157], v[194:197], v[20:23]
	v_mfma_f32_16x16x32_bf16 v[12:15], v[162:165], v[194:197], v[12:15]
	s_barrier
; #define PG8_STAGE(bufoff, gbase, voff) do { _Pragma("unroll") for (int _i = 0; _i < 2; ++_i) \
;         __builtin_amdgcn_global_load_lds((const unsigned*)((const char*)(gbase) + (voff)[_i]), (LAS unsigned*)(lds + (bufoff) + ldsw + _i * 8192), 16, 0, 0); } while (0)
; #define PG8_LDA(dst, b, h) do { _Pragma("unroll") for (int m = 0; m < 4; ++m) _Pragma("unroll") for (int k = 0; k < 2; ++k) dst[m][k] = *(const LAS bf16x8*)(lds + PG8_SA(b, h) + aoff + m * 2048 + k * 1024); } while (0)
; #define PG8_LDB(dst, b, h) do { _Pragma("unroll") for (int n = 0; n < 2; ++n) _Pragma("unroll") for (int k = 0; k < 2; ++k) dst[n][k] = *(const LAS bf16x8*)(lds + PG8_SB(b, h) + boff + n * 2048 + k * 1024); } while (0)
; #define PG8_WAIT_V(n) asm volatile("s_waitcnt vmcnt(" #n ")" ::: "memory")
; #define PG8_WAIT_L(n) asm volatile("s_waitcnt lgkmcnt(" #n ")" ::: "memory")
; #define PG8_BAR __builtin_amdgcn_s_barrier()
; #define PG8_SCHED __builtin_amdgcn_sched_barrier(0)
; template <class Epi, class Sched>
; __device__ __forceinline__ void gemm_phase(LAS unsigned char* lds, const Gemm g, const Sched& S, const Epi& E) {
;     ...
;             PG8_LDB(B0, 0, 0); PG8_SCHED; PG8_LDA(At, 0, 0); PG8_STAGE(PG8_SA(1, 1), a1 + hstep, voffA);
;             PG8_WAIT_L(8); PG8_BAR; PG8_WAIT_L(0); PG8_MMA(0, 0, At, B0); PG8_BAR; PG8_SCHED;
;             PG8_LDB(B1, 0, 1); PG8_STAGE(PG8_SB(0, 0), b2, voffB);
;             PG8_BAR; PG8_WAIT_L(0); PG8_MMA(0, 1, At, B1); PG8_BAR;
;             PG8_LDA(At, 0, 1); PG8_STAGE(PG8_SA(0, 0), a2, voffA);
;             PG8_BAR; PG8_WAIT_L(0); PG8_MMA(1, 0, At, B0); PG8_BAR; PG8_SCHED;
;             PG8_STAGE(PG8_SB(0, 1), b2 + hstep, voffB);
;             PG8_WAIT_V(6); PG8_BAR; PG8_MMA(1, 1, At, B1); PG8_BAR;
;             PG8_LDB(B0, 1, 0); PG8_SCHED; PG8_LDA(At, 1, 0); PG8_STAGE(PG8_SA(0, 1), a2 + hstep, voffA);
;             PG8_WAIT_L(8); PG8_BAR; PG8_WAIT_L(0); PG8_MMA(0, 0, At, B0); PG8_BAR; PG8_SCHED;
;             PG8_LDB(B1, 1, 1); PG8_STAGE(PG8_SB(1, 0), b3, voffB);
;             PG8_BAR; PG8_WAIT_L(0); PG8_MMA(0, 1, At, B1); PG8_BAR;
;             PG8_LDA(At, 1, 1); PG8_STAGE(PG8_SA(1, 0), a3, voffA);
;             PG8_BAR; PG8_WAIT_L(0); PG8_MMA(1, 0, At, B0); PG8_BAR; PG8_SCHED;
;             PG8_STAGE(PG8_SB(1, 1), b3 + hstep, voffB);
;             PG8_WAIT_V(6); PG8_BAR; PG8_MMA(1, 1, At, B1); PG8_BAR;
	s_setprio 0
	s_add_u32 s66, s34, 0x40000
	s_addc_u32 s67, s35, 0
	s_add_i32 s68, s55, s43
	s_mov_b32 m0, s68
	s_nop 0
	global_load_lds_dwordx4 v130, s[66:67]
	s_add_i32 m0, s68, 0x2000
	s_nop 0
	global_load_lds_dwordx4 v134, s[66:67]
	s_add_u32 s36, s36, 0x40000
	s_addc_u32 s37, s37, 0
	s_mov_b32 m0, s45
	s_nop 0
	global_load_lds_dwordx4 v128, s[36:37]
	s_mov_b32 m0, s46
	s_nop 0
	global_load_lds_dwordx4 v132, s[36:37]
	s_waitcnt vmcnt(10)
	s_setprio 1
	s_barrier
	v_mfma_f32_16x16x32_bf16 v[48:51], v[202:205], v[166:169], 0
	v_mfma_f32_16x16x32_bf16 v[40:43], v[210:213], v[166:169], 0
	v_mfma_f32_16x16x32_bf16 v[32:35], v[202:205], v[174:177], 0
	v_mfma_f32_16x16x32_bf16 v[24:27], v[210:213], v[174:177], 0
	v_mfma_f32_16x16x32_bf16 v[16:19], v[202:205], v[182:185], 0
	v_mfma_f32_16x16x32_bf16 v[8:11], v[210:213], v[182:185], 0
	v_mfma_f32_16x16x32_bf16 v[4:7], v[202:205], v[190:193], 0
	v_mfma_f32_16x16x32_bf16 v[0:3], v[210:213], v[190:193], 0
	v_mfma_f32_16x16x32_bf16 v[48:51], v[206:209], v[170:173], v[48:51]
	v_mfma_f32_16x16x32_bf16 v[40:43], v[214:217], v[170:173], v[40:43]
	v_mfma_f32_16x16x32_bf16 v[32:35], v[206:209], v[178:181], v[32:35]
	v_mfma_f32_16x16x32_bf16 v[24:27], v[214:217], v[178:181], v[24:27]
	v_mfma_f32_16x16x32_bf16 v[16:19], v[206:209], v[186:189], v[16:19]
	v_mfma_f32_16x16x32_bf16 v[8:11], v[214:217], v[186:189], v[8:11]
	v_mfma_f32_16x16x32_bf16 v[4:7], v[206:209], v[194:197], v[4:7]
	v_mfma_f32_16x16x32_bf16 v[0:3], v[214:217], v[194:197], v[0:3]
	s_barrier
	s_setprio 0
	s_add_i32 s66, 0, 0x18000
	ds_read_b128 v[150:153], v149 offset:16384
	ds_read_b128 v[154:157], v149 offset:17408
	ds_read_b128 v[158:161], v149 offset:18432
	ds_read_b128 v[162:165], v149 offset:19456
	ds_read_b128 v[166:169], v148 offset:32768
	ds_read_b128 v[170:173], v148 offset:33792
	ds_read_b128 v[174:177], v148 offset:34816
	ds_read_b128 v[178:181], v148 offset:35840
	ds_read_b128 v[182:185], v148 offset:36864
	ds_read_b128 v[186:189], v148 offset:37888
	ds_read_b128 v[190:193], v148 offset:38912
	ds_read_b128 v[194:197], v148 offset:39936
	s_waitcnt lgkmcnt(8)
	s_waitcnt vmcnt(8)
	s_setprio 1
	s_barrier
	s_waitcnt lgkmcnt(0)
	v_mfma_f32_16x16x32_bf16 v[124:127], v[150:153], v[166:169], v[124:127]
	v_mfma_f32_16x16x32_bf16 v[120:123], v[158:161], v[166:169], v[120:123]
	v_mfma_f32_16x16x32_bf16 v[116:119], v[150:153], v[174:177], v[116:119]
	v_mfma_f32_16x16x32_bf16 v[108:111], v[158:161], v[174:177], v[108:111]
	v_mfma_f32_16x16x32_bf16 v[100:103], v[150:153], v[182:185], v[100:103]
	v_mfma_f32_16x16x32_bf16 v[92:95], v[158:161], v[182:185], v[92:95]
	v_mfma_f32_16x16x32_bf16 v[84:87], v[150:153], v[190:193], v[84:87]
	v_mfma_f32_16x16x32_bf16 v[76:79], v[158:161], v[190:193], v[76:79]
	v_mfma_f32_16x16x32_bf16 v[124:127], v[154:157], v[170:173], v[124:127]
	v_mfma_f32_16x16x32_bf16 v[120:123], v[162:165], v[170:173], v[120:123]
	v_mfma_f32_16x16x32_bf16 v[116:119], v[154:157], v[178:181], v[116:119]
	v_mfma_f32_16x16x32_bf16 v[108:111], v[162:165], v[178:181], v[108:111]
	v_mfma_f32_16x16x32_bf16 v[100:103], v[154:157], v[186:189], v[100:103]
	v_mfma_f32_16x16x32_bf16 v[92:95], v[162:165], v[186:189], v[92:95]
	v_mfma_f32_16x16x32_bf16 v[84:87], v[154:157], v[194:197], v[84:87]
	v_mfma_f32_16x16x32_bf16 v[76:79], v[162:165], v[194:197], v[76:79]
	s_barrier
	s_setprio 0
	s_add_i32 s36, 0, 0x1c000
	s_add_i32 s37, s66, s43
	s_add_u32 s4, s34, 0x80
	s_addc_u32 s5, s35, 0
	s_mov_b32 m0, s37
	ds_read_b128 v[202:205], v149 offset:32768
	ds_read_b128 v[206:209], v149 offset:33792
	ds_read_b128 v[210:213], v149 offset:34816
	ds_read_b128 v[214:217], v149 offset:35840
	global_load_lds_dwordx4 v130, s[4:5]
	s_add_i32 m0, s37, 0x2000
	s_nop 0
	global_load_lds_dwordx4 v134, s[4:5]
	s_waitcnt vmcnt(8)
	s_setprio 1
	s_barrier
	s_waitcnt lgkmcnt(0)
	v_mfma_f32_16x16x32_bf16 v[112:115], v[202:205], v[166:169], v[112:115]
	v_mfma_f32_16x16x32_bf16 v[104:107], v[210:213], v[166:169], v[104:107]
	v_mfma_f32_16x16x32_bf16 v[96:99], v[202:205], v[174:177], v[96:99]
	v_mfma_f32_16x16x32_bf16 v[88:91], v[210:213], v[174:177], v[88:91]
	v_mfma_f32_16x16x32_bf16 v[80:83], v[202:205], v[182:185], v[80:83]
	v_mfma_f32_16x16x32_bf16 v[72:75], v[210:213], v[182:185], v[72:75]
	v_mfma_f32_16x16x32_bf16 v[68:71], v[202:205], v[190:193], v[68:71]
	v_mfma_f32_16x16x32_bf16 v[64:67], v[210:213], v[190:193], v[64:67]
	v_mfma_f32_16x16x32_bf16 v[112:115], v[206:209], v[170:173], v[112:115]
	v_mfma_f32_16x16x32_bf16 v[104:107], v[214:217], v[170:173], v[104:107]
	v_mfma_f32_16x16x32_bf16 v[96:99], v[206:209], v[178:181], v[96:99]
	v_mfma_f32_16x16x32_bf16 v[88:91], v[214:217], v[178:181], v[88:91]
	v_mfma_f32_16x16x32_bf16 v[80:83], v[206:209], v[186:189], v[80:83]
	v_mfma_f32_16x16x32_bf16 v[72:75], v[214:217], v[186:189], v[72:75]
	v_mfma_f32_16x16x32_bf16 v[68:71], v[206:209], v[194:197], v[68:71]
	v_mfma_f32_16x16x32_bf16 v[64:67], v[214:217], v[194:197], v[64:67]
	s_barrier
	s_setprio 0
	s_mov_b32 m0, s51
	s_mov_b64 s[4:5], 0x80
	v_lshl_add_u64 v[198:199], v[220:221], 0, s[4:5]
	ds_read_b128 v[166:169], v148 offset:49152
	ds_read_b128 v[170:173], v148 offset:50176
	ds_read_b128 v[174:177], v148 offset:51200
	ds_read_b128 v[178:181], v148 offset:52224
	ds_read_b128 v[182:185], v148 offset:53248
	ds_read_b128 v[186:189], v148 offset:54272
	ds_read_b128 v[190:193], v148 offset:55296
	ds_read_b128 v[194:197], v148 offset:56320
	global_load_lds_dwordx4 v[198:199], off
	v_lshl_add_u64 v[198:199], v[222:223], 0, s[4:5]
	s_mov_b32 m0, s52
	s_nop 0
	global_load_lds_dwordx4 v[198:199], off
	s_setprio 1
	s_barrier
; #define PG8_STAGE(bufoff, gbase, voff) do { _Pragma("unroll") for (int _i = 0; _i < 2; ++_i) \
;         __builtin_amdgcn_global_load_lds((const unsigned*)((const char*)(gbase) + (voff)[_i]), (LAS unsigned*)(lds + (bufoff) + ldsw + _i * 8192), 16, 0, 0); } while (0)
; #define PG8_LDA(dst, b, h) do { _Pragma("unroll") for (int m = 0; m < 4; ++m) _Pragma("unroll") for (int k = 0; k < 2; ++k) dst[m][k] = *(const LAS bf16x8*)(lds + PG8_SA(b, h) + aoff + m * 2048 + k * 1024); } while (0)
; #define PG8_WAIT_V(n) asm volatile("s_waitcnt vmcnt(" #n ")" ::: "memory")
; #define PG8_WAIT_L(n) asm volatile("s_waitcnt lgkmcnt(" #n ")" ::: "memory")
; template <class Epi, class Sched>
; __device__ __forceinline__ void gemm_phase(LAS unsigned char* lds, const Gemm g, const Sched& S, const Epi& E) {
;     ...
;         for (int t = 0; t < nt; t += 2) {
;             const bool last = (t == nt - 2);
;             const char* a1 = cA + (size_t)(t + 1) * kstep;
;             const char* a2 = last ? nA : cA + (size_t)(t + 2) * kstep; const char* b2 = last ? nB : cB + (size_t)(t + 2) * kstep;
;             const char* a3 = a2 + kstep; const char* b3 = b2 + kstep;
;             PG8_LDB(B0, 0, 0); PG8_SCHED; PG8_LDA(At, 0, 0); PG8_STAGE(PG8_SA(1, 1), a1 + hstep, voffA);
;             PG8_WAIT_L(8); PG8_BAR; PG8_WAIT_L(0); PG8_MMA(0, 0, At, B0); PG8_BAR; PG8_SCHED;
;             PG8_LDB(B1, 0, 1); PG8_STAGE(PG8_SB(0, 0), b2, voffB);
;             PG8_BAR; PG8_WAIT_L(0); PG8_MMA(0, 1, At, B1); PG8_BAR;
;             PG8_LDA(At, 0, 1); PG8_STAGE(PG8_SA(0, 0), a2, voffA);
;             PG8_BAR; PG8_WAIT_L(0); PG8_MMA(1, 0, At, B0); PG8_BAR; PG8_SCHED;
;             PG8_STAGE(PG8_SB(0, 1), b2 + hstep, voffB);
;             PG8_WAIT_V(6); PG8_BAR; PG8_MMA(1, 1, At, B1); PG8_BAR;
;             PG8_LDB(B0, 1, 0); PG8_SCHED; PG8_LDA(At, 1, 0); PG8_STAGE(PG8_SA(0, 1), a2 + hstep, voffA);
;             PG8_WAIT_L(8); PG8_BAR; PG8_WAIT_L(0); PG8_MMA(0, 0, At, B0); PG8_BAR; PG8_SCHED;
;             PG8_LDB(B1, 1, 1); PG8_STAGE(PG8_SB(1, 0), b3, voffB);
;             PG8_BAR; PG8_WAIT_L(0); PG8_MMA(0, 1, At, B1); PG8_BAR;
;             PG8_LDA(At, 1, 1); PG8_STAGE(PG8_SA(1, 0), a3, voffA);
;             PG8_BAR; PG8_WAIT_L(0); PG8_MMA(1, 0, At, B0); PG8_BAR; PG8_SCHED;
;             PG8_STAGE(PG8_SB(1, 1), b3 + hstep, voffB);
;             PG8_WAIT_V(6); PG8_BAR; PG8_MMA(1, 1, At, B1); PG8_BAR;
	s_waitcnt lgkmcnt(0)
	v_mfma_f32_16x16x32_bf16 v[60:63], v[150:153], v[166:169], v[60:63]
	v_mfma_f32_16x16x32_bf16 v[56:59], v[158:161], v[166:169], v[56:59]
	v_mfma_f32_16x16x32_bf16 v[52:55], v[150:153], v[174:177], v[52:55]
	v_mfma_f32_16x16x32_bf16 v[44:47], v[158:161], v[174:177], v[44:47]
	v_mfma_f32_16x16x32_bf16 v[36:39], v[150:153], v[182:185], v[36:39]
	v_mfma_f32_16x16x32_bf16 v[28:31], v[158:161], v[182:185], v[28:31]
	v_mfma_f32_16x16x32_bf16 v[20:23], v[150:153], v[190:193], v[20:23]
	v_mfma_f32_16x16x32_bf16 v[12:15], v[158:161], v[190:193], v[12:15]
	v_mfma_f32_16x16x32_bf16 v[60:63], v[154:157], v[170:173], v[60:63]
	v_mfma_f32_16x16x32_bf16 v[56:59], v[162:165], v[170:173], v[56:59]
	v_mfma_f32_16x16x32_bf16 v[52:55], v[154:157], v[178:181], v[52:55]
	v_mfma_f32_16x16x32_bf16 v[44:47], v[162:165], v[178:181], v[44:47]
	v_mfma_f32_16x16x32_bf16 v[36:39], v[154:157], v[186:189], v[36:39]
	v_mfma_f32_16x16x32_bf16 v[28:31], v[162:165], v[186:189], v[28:31]
	v_mfma_f32_16x16x32_bf16 v[20:23], v[154:157], v[194:197], v[20:23]
	v_mfma_f32_16x16x32_bf16 v[12:15], v[162:165], v[194:197], v[12:15]
	s_barrier
	s_setprio 0
	s_add_u32 s34, s34, 0x40080
	s_addc_u32 s35, s35, 0
	s_add_i32 s36, s36, s43
	s_mov_b32 m0, s36
	s_nop 0
	global_load_lds_dwordx4 v130, s[34:35]
	s_add_i32 m0, s36, 0x2000
	s_nop 0
	global_load_lds_dwordx4 v134, s[34:35]
	s_waitcnt vmcnt(8)
	s_setprio 1
	s_barrier
	v_mfma_f32_16x16x32_bf16 v[48:51], v[202:205], v[166:169], v[48:51]
	v_mfma_f32_16x16x32_bf16 v[40:43], v[210:213], v[166:169], v[40:43]
	v_mfma_f32_16x16x32_bf16 v[32:35], v[202:205], v[174:177], v[32:35]
	v_mfma_f32_16x16x32_bf16 v[24:27], v[210:213], v[174:177], v[24:27]
	v_mfma_f32_16x16x32_bf16 v[16:19], v[202:205], v[182:185], v[16:19]
	v_mfma_f32_16x16x32_bf16 v[8:11], v[210:213], v[182:185], v[8:11]
	v_mfma_f32_16x16x32_bf16 v[4:7], v[202:205], v[190:193], v[4:7]
	v_mfma_f32_16x16x32_bf16 v[0:3], v[210:213], v[190:193], v[0:3]
	v_mfma_f32_16x16x32_bf16 v[48:51], v[206:209], v[170:173], v[48:51]
	v_mfma_f32_16x16x32_bf16 v[40:43], v[214:217], v[170:173], v[40:43]
	v_mfma_f32_16x16x32_bf16 v[32:35], v[206:209], v[178:181], v[32:35]
	v_mfma_f32_16x16x32_bf16 v[24:27], v[214:217], v[178:181], v[24:27]
	v_mfma_f32_16x16x32_bf16 v[16:19], v[206:209], v[186:189], v[16:19]
	v_mfma_f32_16x16x32_bf16 v[8:11], v[214:217], v[186:189], v[8:11]
	v_mfma_f32_16x16x32_bf16 v[4:7], v[206:209], v[194:197], v[4:7]
	v_mfma_f32_16x16x32_bf16 v[0:3], v[214:217], v[194:197], v[0:3]
	s_barrier
	s_setprio 0
	s_add_i32 s65, s65, 2
	s_add_u32 s30, s30, 0x100
	s_addc_u32 s31, s31, 0
	s_add_u32 s63, s63, 0x100
	s_addc_u32 s64, s64, 0
	s_cmp_gt_u32 s65, 13
.LBB0_633:
	ds_read_b128 v[150:153], v147
	ds_read_b128 v[154:157], v147 offset:1024
	ds_read_b128 v[158:161], v147 offset:2048
	ds_read_b128 v[162:165], v147 offset:3072
	s_add_u32 s34, s30, 0xfffc0080
	s_addc_u32 s35, s31, -1
	s_cmp_eq_u32 s65, 12
	s_cselect_b32 s37, s23, s35
	s_cselect_b32 s36, s61, s34
	s_cselect_b32 s35, s21, s64
	s_cselect_b32 s34, s62, s63
	s_add_i32 m0, s29, 0xc000
	ds_read_b128 v[166:169], v148
	ds_read_b128 v[170:173], v148 offset:1024
	ds_read_b128 v[174:177], v148 offset:2048
	ds_read_b128 v[178:181], v148 offset:3072
	ds_read_b128 v[182:185], v148 offset:4096
	ds_read_b128 v[186:189], v148 offset:5120
	ds_read_b128 v[190:193], v148 offset:6144
	ds_read_b128 v[194:197], v148 offset:7168
	global_load_lds_dwordx4 v136, s[30:31]
	s_add_i32 m0, s29, 0xe000
	s_nop 0
	global_load_lds_dwordx4 v138, s[30:31]
	s_waitcnt lgkmcnt(8)
	s_waitcnt vmcnt(8)
	s_setprio 1
	s_barrier
	s_waitcnt lgkmcnt(0)
	v_mfma_f32_16x16x32_bf16 v[124:127], v[150:153], v[166:169], v[124:127]
	v_mfma_f32_16x16x32_bf16 v[120:123], v[158:161], v[166:169], v[120:123]
	v_mfma_f32_16x16x32_bf16 v[116:119], v[150:153], v[174:177], v[116:119]
	v_mfma_f32_16x16x32_bf16 v[108:111], v[158:161], v[174:177], v[108:111]
	v_mfma_f32_16x16x32_bf16 v[100:103], v[150:153], v[182:185], v[100:103]
	v_mfma_f32_16x16x32_bf16 v[92:95], v[158:161], v[182:185], v[92:95]
	v_mfma_f32_16x16x32_bf16 v[84:87], v[150:153], v[190:193], v[84:87]
	v_mfma_f32_16x16x32_bf16 v[76:79], v[158:161], v[190:193], v[76:79]
	v_mfma_f32_16x16x32_bf16 v[124:127], v[154:157], v[170:173], v[124:127]
	v_mfma_f32_16x16x32_bf16 v[120:123], v[162:165], v[170:173], v[120:123]
	v_mfma_f32_16x16x32_bf16 v[116:119], v[154:157], v[178:181], v[116:119]
	v_mfma_f32_16x16x32_bf16 v[108:111], v[162:165], v[178:181], v[108:111]
	v_mfma_f32_16x16x32_bf16 v[100:103], v[154:157], v[186:189], v[100:103]
	v_mfma_f32_16x16x32_bf16 v[92:95], v[162:165], v[186:189], v[92:95]
	v_mfma_f32_16x16x32_bf16 v[84:87], v[154:157], v[194:197], v[84:87]
	v_mfma_f32_16x16x32_bf16 v[76:79], v[162:165], v[194:197], v[76:79]
	s_barrier
	s_setprio 0
	s_add_i32 s66, s54, s43
	s_mov_b32 m0, s66
	ds_read_b128 v[202:205], v149
	ds_read_b128 v[206:209], v149 offset:1024
	ds_read_b128 v[210:213], v149 offset:2048
	ds_read_b128 v[214:217], v149 offset:3072
	global_load_lds_dwordx4 v130, s[34:35]
	s_add_i32 m0, s66, 0x2000
	s_nop 0
	global_load_lds_dwordx4 v134, s[34:35]
	s_waitcnt vmcnt(8)
	s_setprio 1
	s_barrier
; #define PG8_STAGE(bufoff, gbase, voff) do { _Pragma("unroll") for (int _i = 0; _i < 2; ++_i) \
;         __builtin_amdgcn_global_load_lds((const unsigned*)((const char*)(gbase) + (voff)[_i]), (LAS unsigned*)(lds + (bufoff) + ldsw + _i * 8192), 16, 0, 0); } while (0)
; #define PG8_LDA(dst, b, h) do { _Pragma("unroll") for (int m = 0; m < 4; ++m) _Pragma("unroll") for (int k = 0; k < 2; ++k) dst[m][k] = *(const LAS bf16x8*)(lds + PG8_SA(b, h) + aoff + m * 2048 + k * 1024); } while (0)
; #define PG8_LDB(dst, b, h) do { _Pragma("unroll") for (int n = 0; n < 2; ++n) _Pragma("unroll") for (int k = 0; k < 2; ++k) dst[n][k] = *(const LAS bf16x8*)(lds + PG8_SB(b, h) + boff + n * 2048 + k * 1024); } while (0)
; #define PG8_WAIT_V(n) asm volatile("s_waitcnt vmcnt(" #n ")" ::: "memory")
; #define PG8_WAIT_L(n) asm volatile("s_waitcnt lgkmcnt(" #n ")" ::: "memory")
; #define PG8_BAR __builtin_amdgcn_s_barrier()
; #define PG8_SCHED __builtin_amdgcn_sched_barrier(0)
; template <class Epi, class Sched>
; __device__ __forceinline__ void gemm_phase(LAS unsigned char* lds, const Gemm g, const Sched& S, const Epi& E) {
;     ...
;             PG8_LDB(B0, 0, 0); PG8_SCHED; PG8_LDA(At, 0, 0); PG8_STAGE(PG8_SA(1, 1), a1 + hstep, voffA);
;             PG8_WAIT_L(8); PG8_BAR; PG8_WAIT_L(0); PG8_MMA(0, 0, At, B0); PG8_BAR; PG8_SCHED;
;             PG8_LDB(B1, 0, 1); PG8_STAGE(PG8_SB(0, 0), b2, voffB);
;             PG8_BAR; PG8_WAIT_L(0); PG8_MMA(0, 1, At, B1); PG8_BAR;
;             PG8_LDA(At, 0, 1); PG8_STAGE(PG8_SA(0, 0), a2, voffA);
;             PG8_BAR; PG8_WAIT_L(0); PG8_MMA(1, 0, At, B0); PG8_BAR; PG8_SCHED;
;             PG8_STAGE(PG8_SB(0, 1), b2 + hstep, voffB);
;             PG8_WAIT_V(6); PG8_BAR; PG8_MMA(1, 1, At, B1); PG8_BAR;
;             PG8_LDB(B0, 1, 0); PG8_SCHED; PG8_LDA(At, 1, 0); PG8_STAGE(PG8_SA(0, 1), a2 + hstep, voffA);
;             PG8_WAIT_L(8); PG8_BAR; PG8_WAIT_L(0); PG8_MMA(0, 0, At, B0); PG8_BAR; PG8_SCHED;
;             PG8_LDB(B1, 1, 1); PG8_STAGE(PG8_SB(1, 0), b3, voffB);
;             PG8_BAR; PG8_WAIT_L(0); PG8_MMA(0, 1, At, B1); PG8_BAR;
;             PG8_LDA(At, 1, 1); PG8_STAGE(PG8_SA(1, 0), a3, voffA);
;             PG8_BAR; PG8_WAIT_L(0); PG8_MMA(1, 0, At, B0); PG8_BAR; PG8_SCHED;
;             PG8_STAGE(PG8_SB(1, 1), b3 + hstep, voffB);
;             PG8_WAIT_V(6); PG8_BAR; PG8_MMA(1, 1, At, B1); PG8_BAR;
	s_waitcnt lgkmcnt(0)
	v_mfma_f32_16x16x32_bf16 v[112:115], v[202:205], v[166:169], v[112:115]
	v_mfma_f32_16x16x32_bf16 v[104:107], v[210:213], v[166:169], v[104:107]
	v_mfma_f32_16x16x32_bf16 v[96:99], v[202:205], v[174:177], v[96:99]
	v_mfma_f32_16x16x32_bf16 v[88:91], v[210:213], v[174:177], v[88:91]
	v_mfma_f32_16x16x32_bf16 v[80:83], v[202:205], v[182:185], v[80:83]
	v_mfma_f32_16x16x32_bf16 v[72:75], v[210:213], v[182:185], v[72:75]
	v_mfma_f32_16x16x32_bf16 v[68:71], v[202:205], v[190:193], v[68:71]
	v_mfma_f32_16x16x32_bf16 v[64:67], v[210:213], v[190:193], v[64:67]
	v_mfma_f32_16x16x32_bf16 v[112:115], v[206:209], v[170:173], v[112:115]
	v_mfma_f32_16x16x32_bf16 v[104:107], v[214:217], v[170:173], v[104:107]
	v_mfma_f32_16x16x32_bf16 v[96:99], v[206:209], v[178:181], v[96:99]
	v_mfma_f32_16x16x32_bf16 v[88:91], v[214:217], v[178:181], v[88:91]
	v_mfma_f32_16x16x32_bf16 v[80:83], v[206:209], v[186:189], v[80:83]
	v_mfma_f32_16x16x32_bf16 v[72:75], v[214:217], v[186:189], v[72:75]
	v_mfma_f32_16x16x32_bf16 v[68:71], v[206:209], v[194:197], v[68:71]
	v_mfma_f32_16x16x32_bf16 v[64:67], v[214:217], v[194:197], v[64:67]
	s_barrier
	s_setprio 0
	s_mov_b32 m0, s29
	v_lshl_add_u64 v[220:221], s[36:37], 0, v[128:129]
	ds_read_b128 v[166:169], v148 offset:16384
	ds_read_b128 v[170:173], v148 offset:17408
	ds_read_b128 v[174:177], v148 offset:18432
	ds_read_b128 v[178:181], v148 offset:19456
	ds_read_b128 v[182:185], v148 offset:20480
	ds_read_b128 v[186:189], v148 offset:21504
	ds_read_b128 v[190:193], v148 offset:22528
	ds_read_b128 v[194:197], v148 offset:23552
	global_load_lds_dwordx4 v128, s[36:37]
	v_lshl_add_u64 v[222:223], s[36:37], 0, v[132:133]
	s_mov_b32 m0, s44
	s_nop 0
	global_load_lds_dwordx4 v132, s[36:37]
	s_setprio 1
	s_barrier
	s_waitcnt lgkmcnt(0)
	v_mfma_f32_16x16x32_bf16 v[60:63], v[150:153], v[166:169], v[60:63]
	v_mfma_f32_16x16x32_bf16 v[56:59], v[158:161], v[166:169], v[56:59]
	v_mfma_f32_16x16x32_bf16 v[52:55], v[150:153], v[174:177], v[52:55]
	v_mfma_f32_16x16x32_bf16 v[44:47], v[158:161], v[174:177], v[44:47]
	v_mfma_f32_16x16x32_bf16 v[36:39], v[150:153], v[182:185], v[36:39]
	v_mfma_f32_16x16x32_bf16 v[28:31], v[158:161], v[182:185], v[28:31]
	v_mfma_f32_16x16x32_bf16 v[20:23], v[150:153], v[190:193], v[20:23]
	v_mfma_f32_16x16x32_bf16 v[12:15], v[158:161], v[190:193], v[12:15]
	v_mfma_f32_16x16x32_bf16 v[60:63], v[154:157], v[170:173], v[60:63]
	v_mfma_f32_16x16x32_bf16 v[56:59], v[162:165], v[170:173], v[56:59]
	v_mfma_f32_16x16x32_bf16 v[52:55], v[154:157], v[178:181], v[52:55]
	v_mfma_f32_16x16x32_bf16 v[44:47], v[162:165], v[178:181], v[44:47]
	v_mfma_f32_16x16x32_bf16 v[36:39], v[154:157], v[186:189], v[36:39]
	v_mfma_f32_16x16x32_bf16 v[28:31], v[162:165], v[186:189], v[28:31]
	v_mfma_f32_16x16x32_bf16 v[20:23], v[154:157], v[194:197], v[20:23]
	v_mfma_f32_16x16x32_bf16 v[12:15], v[162:165], v[194:197], v[12:15]
	s_barrier
	s_setprio 0
	s_add_u32 s66, s34, 0x40000
	s_addc_u32 s67, s35, 0
	s_add_i32 s68, s55, s43
	s_mov_b32 m0, s68
	s_nop 0
	global_load_lds_dwordx4 v130, s[66:67]
	s_add_i32 m0, s68, 0x2000
	s_nop 0
	global_load_lds_dwordx4 v134, s[66:67]
	s_add_u32 s36, s36, 0x40000
	s_addc_u32 s37, s37, 0
	s_mov_b32 m0, s45
	s_nop 0
	global_load_lds_dwordx4 v128, s[36:37]
	s_mov_b32 m0, s46
	s_nop 0
	global_load_lds_dwordx4 v132, s[36:37]
	s_waitcnt vmcnt(10)
	s_setprio 1
	s_barrier
	v_mfma_f32_16x16x32_bf16 v[48:51], v[202:205], v[166:169], v[48:51]
	v_mfma_f32_16x16x32_bf16 v[40:43], v[210:213], v[166:169], v[40:43]
	v_mfma_f32_16x16x32_bf16 v[32:35], v[202:205], v[174:177], v[32:35]
	v_mfma_f32_16x16x32_bf16 v[24:27], v[210:213], v[174:177], v[24:27]
	v_mfma_f32_16x16x32_bf16 v[16:19], v[202:205], v[182:185], v[16:19]
	v_mfma_f32_16x16x32_bf16 v[8:11], v[210:213], v[182:185], v[8:11]
	v_mfma_f32_16x16x32_bf16 v[4:7], v[202:205], v[190:193], v[4:7]
	v_mfma_f32_16x16x32_bf16 v[0:3], v[210:213], v[190:193], v[0:3]
	v_mfma_f32_16x16x32_bf16 v[48:51], v[206:209], v[170:173], v[48:51]
	v_mfma_f32_16x16x32_bf16 v[40:43], v[214:217], v[170:173], v[40:43]
	v_mfma_f32_16x16x32_bf16 v[32:35], v[206:209], v[178:181], v[32:35]
	v_mfma_f32_16x16x32_bf16 v[24:27], v[214:217], v[178:181], v[24:27]
	v_mfma_f32_16x16x32_bf16 v[16:19], v[206:209], v[186:189], v[16:19]
	v_mfma_f32_16x16x32_bf16 v[8:11], v[214:217], v[186:189], v[8:11]
	v_mfma_f32_16x16x32_bf16 v[4:7], v[206:209], v[194:197], v[4:7]
	v_mfma_f32_16x16x32_bf16 v[0:3], v[214:217], v[194:197], v[0:3]
	s_barrier
	s_setprio 0
	s_add_i32 s66, 0, 0x18000
	ds_read_b128 v[150:153], v149 offset:16384
	ds_read_b128 v[154:157], v149 offset:17408
	ds_read_b128 v[158:161], v149 offset:18432
	ds_read_b128 v[162:165], v149 offset:19456
	ds_read_b128 v[166:169], v148 offset:32768
	ds_read_b128 v[170:173], v148 offset:33792
	ds_read_b128 v[174:177], v148 offset:34816
	ds_read_b128 v[178:181], v148 offset:35840
	ds_read_b128 v[182:185], v148 offset:36864
	ds_read_b128 v[186:189], v148 offset:37888
	ds_read_b128 v[190:193], v148 offset:38912
	ds_read_b128 v[194:197], v148 offset:39936
	s_waitcnt lgkmcnt(8)
	s_waitcnt vmcnt(8)
	s_setprio 1
	s_barrier
; #define PG8_STAGE(bufoff, gbase, voff) do { _Pragma("unroll") for (int _i = 0; _i < 2; ++_i) \
;         __builtin_amdgcn_global_load_lds((const unsigned*)((const char*)(gbase) + (voff)[_i]), (LAS unsigned*)(lds + (bufoff) + ldsw + _i * 8192), 16, 0, 0); } while (0)
; #define PG8_LDA(dst, b, h) do { _Pragma("unroll") for (int m = 0; m < 4; ++m) _Pragma("unroll") for (int k = 0; k < 2; ++k) dst[m][k] = *(const LAS bf16x8*)(lds + PG8_SA(b, h) + aoff + m * 2048 + k * 1024); } while (0)
; #define PG8_LDB(dst, b, h) do { _Pragma("unroll") for (int n = 0; n < 2; ++n) _Pragma("unroll") for (int k = 0; k < 2; ++k) dst[n][k] = *(const LAS bf16x8*)(lds + PG8_SB(b, h) + boff + n * 2048 + k * 1024); } while (0)
; #define PG8_WAIT_V(n) asm volatile("s_waitcnt vmcnt(" #n ")" ::: "memory")
; #define PG8_WAIT_L(n) asm volatile("s_waitcnt lgkmcnt(" #n ")" ::: "memory")
; #define PG8_BAR __builtin_amdgcn_s_barrier()
; #define PG8_SCHED __builtin_amdgcn_sched_barrier(0)
; template <class Epi, class Sched>
; __device__ __forceinline__ void gemm_phase(LAS unsigned char* lds, const Gemm g, const Sched& S, const Epi& E) {
;     ...
;             PG8_LDB(B0, 0, 0); PG8_SCHED; PG8_LDA(At, 0, 0); PG8_STAGE(PG8_SA(1, 1), a1 + hstep, voffA);
;             PG8_WAIT_L(8); PG8_BAR; PG8_WAIT_L(0); PG8_MMA(0, 0, At, B0); PG8_BAR; PG8_SCHED;
;             PG8_LDB(B1, 0, 1); PG8_STAGE(PG8_SB(0, 0), b2, voffB);
;             PG8_BAR; PG8_WAIT_L(0); PG8_MMA(0, 1, At, B1); PG8_BAR;
;             PG8_LDA(At, 0, 1); PG8_STAGE(PG8_SA(0, 0), a2, voffA);
;             PG8_BAR; PG8_WAIT_L(0); PG8_MMA(1, 0, At, B0); PG8_BAR; PG8_SCHED;
;             PG8_STAGE(PG8_SB(0, 1), b2 + hstep, voffB);
;             PG8_WAIT_V(6); PG8_BAR; PG8_MMA(1, 1, At, B1); PG8_BAR;
;             PG8_LDB(B0, 1, 0); PG8_SCHED; PG8_LDA(At, 1, 0); PG8_STAGE(PG8_SA(0, 1), a2 + hstep, voffA);
;             PG8_WAIT_L(8); PG8_BAR; PG8_WAIT_L(0); PG8_MMA(0, 0, At, B0); PG8_BAR; PG8_SCHED;
;             PG8_LDB(B1, 1, 1); PG8_STAGE(PG8_SB(1, 0), b3, voffB);
;             PG8_BAR; PG8_WAIT_L(0); PG8_MMA(0, 1, At, B1); PG8_BAR;
;             PG8_LDA(At, 1, 1); PG8_STAGE(PG8_SA(1, 0), a3, voffA);
;             PG8_BAR; PG8_WAIT_L(0); PG8_MMA(1, 0, At, B0); PG8_BAR; PG8_SCHED;
;             PG8_STAGE(PG8_SB(1, 1), b3 + hstep, voffB);
;             PG8_WAIT_V(6); PG8_BAR; PG8_MMA(1, 1, At, B1); PG8_BAR;
	s_waitcnt lgkmcnt(0)
	v_mfma_f32_16x16x32_bf16 v[124:127], v[150:153], v[166:169], v[124:127]
	v_mfma_f32_16x16x32_bf16 v[120:123], v[158:161], v[166:169], v[120:123]
	v_mfma_f32_16x16x32_bf16 v[116:119], v[150:153], v[174:177], v[116:119]
	v_mfma_f32_16x16x32_bf16 v[108:111], v[158:161], v[174:177], v[108:111]
	v_mfma_f32_16x16x32_bf16 v[100:103], v[150:153], v[182:185], v[100:103]
	v_mfma_f32_16x16x32_bf16 v[92:95], v[158:161], v[182:185], v[92:95]
	v_mfma_f32_16x16x32_bf16 v[84:87], v[150:153], v[190:193], v[84:87]
	v_mfma_f32_16x16x32_bf16 v[76:79], v[158:161], v[190:193], v[76:79]
	v_mfma_f32_16x16x32_bf16 v[124:127], v[154:157], v[170:173], v[124:127]
	v_mfma_f32_16x16x32_bf16 v[120:123], v[162:165], v[170:173], v[120:123]
	v_mfma_f32_16x16x32_bf16 v[116:119], v[154:157], v[178:181], v[116:119]
	v_mfma_f32_16x16x32_bf16 v[108:111], v[162:165], v[178:181], v[108:111]
	v_mfma_f32_16x16x32_bf16 v[100:103], v[154:157], v[186:189], v[100:103]
	v_mfma_f32_16x16x32_bf16 v[92:95], v[162:165], v[186:189], v[92:95]
	v_mfma_f32_16x16x32_bf16 v[84:87], v[154:157], v[194:197], v[84:87]
	v_mfma_f32_16x16x32_bf16 v[76:79], v[162:165], v[194:197], v[76:79]
	s_barrier
	s_setprio 0
	s_add_i32 s36, 0, 0x1c000
	s_add_i32 s37, s66, s43
	s_add_u32 s4, s34, 0x80
	s_addc_u32 s5, s35, 0
	s_mov_b32 m0, s37
	ds_read_b128 v[202:205], v149 offset:32768
	ds_read_b128 v[206:209], v149 offset:33792
	ds_read_b128 v[210:213], v149 offset:34816
	ds_read_b128 v[214:217], v149 offset:35840
	global_load_lds_dwordx4 v130, s[4:5]
	s_add_i32 m0, s37, 0x2000
	s_nop 0
	global_load_lds_dwordx4 v134, s[4:5]
	s_waitcnt vmcnt(8)
	s_setprio 1
	s_barrier
	s_waitcnt lgkmcnt(0)
	v_mfma_f32_16x16x32_bf16 v[112:115], v[202:205], v[166:169], v[112:115]
	v_mfma_f32_16x16x32_bf16 v[104:107], v[210:213], v[166:169], v[104:107]
	v_mfma_f32_16x16x32_bf16 v[96:99], v[202:205], v[174:177], v[96:99]
	v_mfma_f32_16x16x32_bf16 v[88:91], v[210:213], v[174:177], v[88:91]
	v_mfma_f32_16x16x32_bf16 v[80:83], v[202:205], v[182:185], v[80:83]
	v_mfma_f32_16x16x32_bf16 v[72:75], v[210:213], v[182:185], v[72:75]
	v_mfma_f32_16x16x32_bf16 v[68:71], v[202:205], v[190:193], v[68:71]
	v_mfma_f32_16x16x32_bf16 v[64:67], v[210:213], v[190:193], v[64:67]
	v_mfma_f32_16x16x32_bf16 v[112:115], v[206:209], v[170:173], v[112:115]
	v_mfma_f32_16x16x32_bf16 v[104:107], v[214:217], v[170:173], v[104:107]
	v_mfma_f32_16x16x32_bf16 v[96:99], v[206:209], v[178:181], v[96:99]
	v_mfma_f32_16x16x32_bf16 v[88:91], v[214:217], v[178:181], v[88:91]
	v_mfma_f32_16x16x32_bf16 v[80:83], v[206:209], v[186:189], v[80:83]
	v_mfma_f32_16x16x32_bf16 v[72:75], v[214:217], v[186:189], v[72:75]
	v_mfma_f32_16x16x32_bf16 v[68:71], v[206:209], v[194:197], v[68:71]
	v_mfma_f32_16x16x32_bf16 v[64:67], v[214:217], v[194:197], v[64:67]
	s_barrier
	s_setprio 0
	s_mov_b32 m0, s51
	s_mov_b64 s[4:5], 0x80
	v_lshl_add_u64 v[198:199], v[220:221], 0, s[4:5]
	ds_read_b128 v[166:169], v148 offset:49152
	ds_read_b128 v[170:173], v148 offset:50176
	ds_read_b128 v[174:177], v148 offset:51200
	ds_read_b128 v[178:181], v148 offset:52224
	ds_read_b128 v[182:185], v148 offset:53248
	ds_read_b128 v[186:189], v148 offset:54272
	ds_read_b128 v[190:193], v148 offset:55296
	ds_read_b128 v[194:197], v148 offset:56320
	global_load_lds_dwordx4 v[198:199], off
	v_lshl_add_u64 v[198:199], v[222:223], 0, s[4:5]
	s_mov_b32 m0, s52
	s_nop 0
	global_load_lds_dwordx4 v[198:199], off
	s_setprio 1
	s_barrier
	s_waitcnt lgkmcnt(0)
	v_mfma_f32_16x16x32_bf16 v[60:63], v[150:153], v[166:169], v[60:63]
	v_mfma_f32_16x16x32_bf16 v[56:59], v[158:161], v[166:169], v[56:59]
	v_mfma_f32_16x16x32_bf16 v[52:55], v[150:153], v[174:177], v[52:55]
	v_mfma_f32_16x16x32_bf16 v[44:47], v[158:161], v[174:177], v[44:47]
	v_mfma_f32_16x16x32_bf16 v[36:39], v[150:153], v[182:185], v[36:39]
	v_mfma_f32_16x16x32_bf16 v[28:31], v[158:161], v[182:185], v[28:31]
	v_mfma_f32_16x16x32_bf16 v[20:23], v[150:153], v[190:193], v[20:23]
	v_mfma_f32_16x16x32_bf16 v[12:15], v[158:161], v[190:193], v[12:15]
	v_mfma_f32_16x16x32_bf16 v[60:63], v[154:157], v[170:173], v[60:63]
	v_mfma_f32_16x16x32_bf16 v[56:59], v[162:165], v[170:173], v[56:59]
	v_mfma_f32_16x16x32_bf16 v[52:55], v[154:157], v[178:181], v[52:55]
	v_mfma_f32_16x16x32_bf16 v[44:47], v[162:165], v[178:181], v[44:47]
	v_mfma_f32_16x16x32_bf16 v[36:39], v[154:157], v[186:189], v[36:39]
	v_mfma_f32_16x16x32_bf16 v[28:31], v[162:165], v[186:189], v[28:31]
	v_mfma_f32_16x16x32_bf16 v[20:23], v[154:157], v[194:197], v[20:23]
	v_mfma_f32_16x16x32_bf16 v[12:15], v[162:165], v[194:197], v[12:15]
	s_barrier
	s_setprio 0
	s_add_u32 s34, s34, 0x40080
	s_addc_u32 s35, s35, 0
	s_add_i32 s36, s36, s43
	s_mov_b32 m0, s36
	s_nop 0
	global_load_lds_dwordx4 v130, s[34:35]
	s_add_i32 m0, s36, 0x2000
	s_nop 0
	global_load_lds_dwordx4 v134, s[34:35]
	s_waitcnt vmcnt(8)
	s_setprio 1
	s_barrier
	v_mfma_f32_16x16x32_bf16 v[48:51], v[202:205], v[166:169], v[48:51]
	v_mfma_f32_16x16x32_bf16 v[40:43], v[210:213], v[166:169], v[40:43]
	v_mfma_f32_16x16x32_bf16 v[32:35], v[202:205], v[174:177], v[32:35]
	v_mfma_f32_16x16x32_bf16 v[24:27], v[210:213], v[174:177], v[24:27]
	v_mfma_f32_16x16x32_bf16 v[16:19], v[202:205], v[182:185], v[16:19]
	v_mfma_f32_16x16x32_bf16 v[8:11], v[210:213], v[182:185], v[8:11]
	v_mfma_f32_16x16x32_bf16 v[4:7], v[202:205], v[190:193], v[4:7]
	v_mfma_f32_16x16x32_bf16 v[0:3], v[210:213], v[190:193], v[0:3]
	v_mfma_f32_16x16x32_bf16 v[48:51], v[206:209], v[170:173], v[48:51]
	v_mfma_f32_16x16x32_bf16 v[40:43], v[214:217], v[170:173], v[40:43]
	v_mfma_f32_16x16x32_bf16 v[32:35], v[206:209], v[178:181], v[32:35]
	v_mfma_f32_16x16x32_bf16 v[24:27], v[214:217], v[178:181], v[24:27]
	v_mfma_f32_16x16x32_bf16 v[16:19], v[206:209], v[186:189], v[16:19]
	v_mfma_f32_16x16x32_bf16 v[8:11], v[214:217], v[186:189], v[8:11]
	v_mfma_f32_16x16x32_bf16 v[4:7], v[206:209], v[194:197], v[4:7]
	v_mfma_f32_16x16x32_bf16 v[0:3], v[214:217], v[194:197], v[0:3]
	s_barrier
; __device__ __forceinline__ unsigned cvt_pk_bf16(float lo, float hi) { unsigned r; asm volatile("v_cvt_pk_bf16_f32 %0, %1, %2" : "=v"(r) : "v"(lo), "v"(hi)); return r; }
; #define PG8_WAIT_V(n) asm volatile("s_waitcnt vmcnt(" #n ")" ::: "memory")
; #define PG8_BAR __builtin_amdgcn_s_barrier()
; template <class Epi, class Sched>
; __device__ __forceinline__ void gemm_phase(LAS unsigned char* lds, const Gemm g, const Sched& S, const Epi& E) {
;     ...
;         if (!has_next) break;
; #pragma unroll
;         for (int a = 0; a < 2; ++a)
; #pragma unroll
;             for (int b = 0; b < 2; ++b)
; #pragma unroll
;                 for (int m = 0; m < 4; ++m)
; #pragma unroll
;                     for (int n = 0; n < 2; ++n) acc[a][b][m][n] = (f32x4){0.f, 0.f, 0.f, 0.f};
;         cur = nxt; cA = nA; cB = nB; ++ui;
;     }
;     PG8_WAIT_V(0);
;     if (wr == 0) PG8_BAR;
;     PG8_BAR;
;     __device__ __forceinline__ void operator()(const AccT& acc, const Unit& u, int wr, int wc, int fr, int fq) const {
;         asm volatile("" : "+v"(fr), "+v"(fq));
;         const int rbase = u.pm * 256 + wr * 64 + fr;
;         const int tb = u.pn * 256 + wc * 32 + 8 * fq;
; #pragma unroll
;         for (int ai = 0; ai < 2; ++ai)
; #pragma unroll
;             for (int m = 0; m < 4; ++m) {
;                 const int r = rbase + ai * 128 + m * 16;
; #pragma unroll
;                 for (int bj = 0; bj < 2; ++bj) {
;                     const int t0 = tb + bj * 128;
;                     const f32x4 v0 = acc[ai][bj][m][0], v1 = acc[ai][bj][m][1];
;                     u32x4 w; w.x = cvt_pk_bf16(v0[0], v0[1]); w.y = cvt_pk_bf16(v0[2], v0[3]); w.z = cvt_pk_bf16(v1[0], v1[1]); w.w = cvt_pk_bf16(v1[2], v1[3]);
;                     *(u32x4*)(VT + (size_t)r * NT + t0) = w;
;                 }
;             }
;     }
	s_setprio 0
	s_add_i32 s65, s65, 2
	s_add_u32 s30, s30, 0x100
	s_addc_u32 s31, s31, 0
	s_add_u32 s63, s63, 0x100
	s_addc_u32 s64, s64, 0
	s_cmp_gt_u32 s65, 13
	s_cbranch_scc0 .LBB0_633
	v_mov_b32_e32 v150, v144
	v_mov_b32_e32 v151, v145
	s_lshl_b32 s21, s28, 8
	s_add_i32 s21, s21, s48
	v_add_u32_e32 v150, s21, v150
	s_lshl_b32 s21, s60, 8
	s_or_b32 s21, s21, s49
	v_lshl_add_u32 v152, v151, 3, s21
	v_ashrrev_i32_e32 v151, 31, v150
	v_cvt_pk_bf16_f32 v124, v124, v125
	v_cvt_pk_bf16_f32 v125, v126, v127
	v_cvt_pk_bf16_f32 v126, v120, v121
	v_lshlrev_b64 v[120:121], 17, v[150:151]
	v_lshl_add_u64 v[120:121], s[0:1], 0, v[120:121]
	v_ashrrev_i32_e32 v153, 31, v152
	v_lshl_add_u64 v[120:121], v[152:153], 1, v[120:121]
	s_mov_b32 s21, 0x200000
	v_cvt_pk_bf16_f32 v127, v122, v123
	global_store_dwordx4 v[120:121], v[124:127], off
	v_cvt_pk_bf16_f32 v112, v112, v113
	v_cvt_pk_bf16_f32 v113, v114, v115
	v_cvt_pk_bf16_f32 v114, v104, v105
	v_cvt_pk_bf16_f32 v115, v106, v107
	global_store_dwordx4 v[120:121], v[112:115], off offset:256
	v_cvt_pk_bf16_f32 v104, v116, v117
	v_cvt_pk_bf16_f32 v105, v118, v119
	v_cvt_pk_bf16_f32 v106, v108, v109
	v_cvt_pk_bf16_f32 v107, v110, v111
	s_mov_b64 s[30:31], 0x200000
	v_add_co_u32_e32 v110, vcc, s21, v120
	v_lshl_add_u64 v[108:109], v[120:121], 0, s[30:31]
	s_nop 0
	v_addc_co_u32_e32 v111, vcc, 0, v121, vcc
	s_mov_b32 s21, 0x400000
	global_store_dwordx4 v[110:111], v[104:107], off
	v_cvt_pk_bf16_f32 v96, v96, v97
	v_cvt_pk_bf16_f32 v97, v98, v99
	v_cvt_pk_bf16_f32 v98, v88, v89
	v_cvt_pk_bf16_f32 v99, v90, v91
	global_store_dwordx4 v[108:109], v[96:99], off offset:256
	v_cvt_pk_bf16_f32 v88, v100, v101
	v_cvt_pk_bf16_f32 v89, v102, v103
	v_cvt_pk_bf16_f32 v90, v92, v93
	v_cvt_pk_bf16_f32 v91, v94, v95
	s_mov_b64 s[30:31], 0x400000
	v_add_co_u32_e32 v94, vcc, s21, v120
	v_lshl_add_u64 v[92:93], v[120:121], 0, s[30:31]
	s_nop 0
	v_addc_co_u32_e32 v95, vcc, 0, v121, vcc
	s_mov_b32 s21, 0x600000
	global_store_dwordx4 v[94:95], v[88:91], off
	v_cvt_pk_bf16_f32 v80, v80, v81
	v_cvt_pk_bf16_f32 v81, v82, v83
	v_cvt_pk_bf16_f32 v82, v72, v73
	v_cvt_pk_bf16_f32 v83, v74, v75
	global_store_dwordx4 v[92:93], v[80:83], off offset:256
	v_cvt_pk_bf16_f32 v72, v84, v85
	v_cvt_pk_bf16_f32 v73, v86, v87
	v_cvt_pk_bf16_f32 v74, v76, v77
	v_cvt_pk_bf16_f32 v75, v78, v79
	s_mov_b64 s[30:31], 0x600000
	v_add_co_u32_e32 v78, vcc, s21, v120
	v_lshl_add_u64 v[76:77], v[120:121], 0, s[30:31]
	s_nop 0
	v_addc_co_u32_e32 v79, vcc, 0, v121, vcc
	global_store_dwordx4 v[78:79], v[72:75], off
	v_cvt_pk_bf16_f32 v68, v68, v69
	v_cvt_pk_bf16_f32 v69, v70, v71
	v_cvt_pk_bf16_f32 v70, v64, v65
	v_cvt_pk_bf16_f32 v71, v66, v67
	global_store_dwordx4 v[76:77], v[68:71], off offset:256
	v_cvt_pk_bf16_f32 v60, v60, v61
	v_cvt_pk_bf16_f32 v61, v62, v63
	v_cvt_pk_bf16_f32 v62, v56, v57
	v_cvt_pk_bf16_f32 v63, v58, v59
	s_mov_b64 s[30:31], 0x1000000
	v_add_co_u32_e32 v58, vcc, s56, v120
	v_lshl_add_u64 v[56:57], v[120:121], 0, s[30:31]
	s_nop 0
	v_addc_co_u32_e32 v59, vcc, 0, v121, vcc
	global_store_dwordx4 v[58:59], v[60:63], off
	v_cvt_pk_bf16_f32 v48, v48, v49
	v_cvt_pk_bf16_f32 v49, v50, v51
	v_cvt_pk_bf16_f32 v50, v40, v41
	v_cvt_pk_bf16_f32 v51, v42, v43
	global_store_dwordx4 v[56:57], v[48:51], off offset:256
	v_cvt_pk_bf16_f32 v40, v52, v53
	v_cvt_pk_bf16_f32 v41, v54, v55
	v_cvt_pk_bf16_f32 v42, v44, v45
	v_cvt_pk_bf16_f32 v43, v46, v47
	v_add_co_u32_e32 v46, vcc, s57, v120
	v_lshl_add_u64 v[44:45], v[120:121], 0, s[6:7]
	s_nop 0
	v_addc_co_u32_e32 v47, vcc, 0, v121, vcc
	global_store_dwordx4 v[46:47], v[40:43], off
	v_cvt_pk_bf16_f32 v32, v32, v33
	v_cvt_pk_bf16_f32 v33, v34, v35
	v_cvt_pk_bf16_f32 v34, v24, v25
	v_cvt_pk_bf16_f32 v35, v26, v27
	global_store_dwordx4 v[44:45], v[32:35], off offset:256
	v_cvt_pk_bf16_f32 v24, v36, v37
	v_cvt_pk_bf16_f32 v25, v38, v39
	v_cvt_pk_bf16_f32 v26, v28, v29
	v_cvt_pk_bf16_f32 v27, v30, v31
	v_add_co_u32_e32 v30, vcc, s58, v120
	v_lshl_add_u64 v[28:29], v[120:121], 0, s[8:9]
	s_nop 0
	v_addc_co_u32_e32 v31, vcc, 0, v121, vcc
	global_store_dwordx4 v[30:31], v[24:27], off
	v_cvt_pk_bf16_f32 v16, v16, v17
	v_cvt_pk_bf16_f32 v17, v18, v19
	v_cvt_pk_bf16_f32 v18, v8, v9
	v_cvt_pk_bf16_f32 v19, v10, v11
	global_store_dwordx4 v[28:29], v[16:19], off offset:256
	v_cvt_pk_bf16_f32 v8, v20, v21
	v_cvt_pk_bf16_f32 v9, v22, v23
	v_cvt_pk_bf16_f32 v10, v12, v13
	v_cvt_pk_bf16_f32 v11, v14, v15
	v_add_co_u32_e32 v14, vcc, s59, v120
	v_lshl_add_u64 v[12:13], v[120:121], 0, s[16:17]
	s_nop 0
	v_addc_co_u32_e32 v15, vcc, 0, v121, vcc
	s_and_b64 vcc, exec, s[2:3]
	s_mov_b32 s60, s20
	s_mov_b32 s28, s22
	s_mov_b64 s[34:35], s[26:27]
	s_mov_b64 s[30:31], s[24:25]
	global_store_dwordx4 v[14:15], v[8:11], off
	v_cvt_pk_bf16_f32 v4, v4, v5
	v_cvt_pk_bf16_f32 v5, v6, v7
	v_cvt_pk_bf16_f32 v6, v0, v1
	v_cvt_pk_bf16_f32 v7, v2, v3
	global_store_dwordx4 v[12:13], v[4:7], off offset:256
	s_cbranch_vccz .LBB0_626
	s_waitcnt vmcnt(0)
	s_cmpk_gt_u32 s33, 0xff
	s_cbranch_scc1 .LBB0_637
	s_barrier

; #define PG8_STAGE(bufoff, gbase, voff) do { _Pragma("unroll") for (int _i = 0; _i < 2; ++_i) \
;         __builtin_amdgcn_global_load_lds((const unsigned*)((const char*)(gbase) + (voff)[_i]), (LAS unsigned*)(lds + (bufoff) + ldsw + _i * 8192), 16, 0, 0); } while (0)
; #define PG8_LDA(dst, b, h) do { _Pragma("unroll") for (int m = 0; m < 4; ++m) _Pragma("unroll") for (int k = 0; k < 2; ++k) dst[m][k] = *(const LAS bf16x8*)(lds + PG8_SA(b, h) + aoff + m * 2048 + k * 1024); } while (0)
; #define PG8_LDB(dst, b, h) do { _Pragma("unroll") for (int n = 0; n < 2; ++n) _Pragma("unroll") for (int k = 0; k < 2; ++k) dst[n][k] = *(const LAS bf16x8*)(lds + PG8_SB(b, h) + boff + n * 2048 + k * 1024); } while (0)
; #define PG8_WAIT_V(n) asm volatile("s_waitcnt vmcnt(" #n ")" ::: "memory")
; #define PG8_WAIT_L(n) asm volatile("s_waitcnt lgkmcnt(" #n ")" ::: "memory")
; #define PG8_BAR __builtin_amdgcn_s_barrier()
; #define PG8_SCHED __builtin_amdgcn_sched_barrier(0)
; template <class Epi, class Sched>
; __device__ __forceinline__ void gemm_phase(LAS unsigned char* lds, const Gemm g, const Sched& S, const Epi& E) {
;     ...
;         const bool has_next = S.next(ui + 1, nxt);
;         const char* nA = has_next ? (const char*)g.A + (size_t)nxt.pm * tstep : cA; const char* nB = has_next ? (const char*)g.Bt + (size_t)nxt.pn * tstep : cB;
;         for (int t = 0; t < nt; t += 2) {
;             const bool last = (t == nt - 2);
;             const char* a1 = cA + (size_t)(t + 1) * kstep;
;             const char* a2 = last ? nA : cA + (size_t)(t + 2) * kstep; const char* b2 = last ? nB : cB + (size_t)(t + 2) * kstep;
;             const char* a3 = a2 + kstep; const char* b3 = b2 + kstep;
;             PG8_LDB(B0, 0, 0); PG8_SCHED; PG8_LDA(At, 0, 0); PG8_STAGE(PG8_SA(1, 1), a1 + hstep, voffA);
;             PG8_WAIT_L(8); PG8_BAR; PG8_WAIT_L(0); PG8_MMA(0, 0, At, B0); PG8_BAR; PG8_SCHED;
;             PG8_LDB(B1, 0, 1); PG8_STAGE(PG8_SB(0, 0), b2, voffB);
;             PG8_BAR; PG8_WAIT_L(0); PG8_MMA(0, 1, At, B1); PG8_BAR;
;             PG8_LDA(At, 0, 1); PG8_STAGE(PG8_SA(0, 0), a2, voffA);
;             PG8_BAR; PG8_WAIT_L(0); PG8_MMA(1, 0, At, B0); PG8_BAR; PG8_SCHED;
;             PG8_STAGE(PG8_SB(0, 1), b2 + hstep, voffB);
;             PG8_WAIT_V(6); PG8_BAR; PG8_MMA(1, 1, At, B1); PG8_BAR;
.LBB0_652:
	s_ashr_i32 s9, s8, 31
	v_cmp_lt_i64_e32 vcc, s[16:17], v[142:143]
	s_lshl_b64 s[16:17], s[8:9], 19
	s_add_u32 s16, s14, s16
	s_addc_u32 s17, s15, s17
	s_and_b64 s[18:19], vcc, exec
	s_cselect_b32 s9, s17, s23
	s_cselect_b32 s48, s16, s22
	s_ashr_i32 s7, s6, 31
	s_lshl_b64 s[18:19], s[6:7], 19
	s_add_u32 s18, s12, s18
	s_addc_u32 s19, s13, s19
	s_and_b64 s[26:27], vcc, exec
	s_cselect_b32 s7, s19, s25
	s_cselect_b32 s49, s18, s24
	s_add_u32 s22, s22, 0x40080
	s_addc_u32 s23, s23, 0
	s_add_u32 s51, s24, 0x100
	s_addc_u32 s52, s25, 0
	s_mov_b32 s53, -2
	s_waitcnt lgkmcnt(0)
	ds_read_b128 v[152:155], v149
	ds_read_b128 v[156:159], v149 offset:1024
	ds_read_b128 v[160:163], v149 offset:2048
	ds_read_b128 v[164:167], v149 offset:3072
	s_add_u32 s24, s22, 0xfffc0080
	s_addc_u32 s25, s23, -1
	s_cmp_eq_u32 s53, 12
	s_cselect_b32 s27, s9, s25
	s_cselect_b32 s26, s48, s24
	s_cselect_b32 s25, s7, s52
	s_cselect_b32 s24, s49, s51
	s_add_i32 m0, s21, 0xc000
	ds_read_b128 v[168:171], v150
	ds_read_b128 v[172:175], v150 offset:1024
	ds_read_b128 v[176:179], v150 offset:2048
	ds_read_b128 v[180:183], v150 offset:3072
	ds_read_b128 v[184:187], v150 offset:4096
	ds_read_b128 v[188:191], v150 offset:5120
	ds_read_b128 v[192:195], v150 offset:6144
	ds_read_b128 v[196:199], v150 offset:7168
	global_load_lds_dwordx4 v138, s[22:23]
	s_add_i32 m0, s21, 0xe000
	s_nop 0
	global_load_lds_dwordx4 v140, s[22:23]
	s_waitcnt lgkmcnt(8)
	s_waitcnt vmcnt(8)
	s_setprio 1
	s_barrier
	s_waitcnt lgkmcnt(0)
	v_mfma_f32_16x16x32_bf16 v[124:127], v[152:155], v[168:171], 0
	v_mfma_f32_16x16x32_bf16 v[120:123], v[160:163], v[168:171], 0
	v_mfma_f32_16x16x32_bf16 v[112:115], v[152:155], v[176:179], 0
	v_mfma_f32_16x16x32_bf16 v[104:107], v[160:163], v[176:179], 0
	v_mfma_f32_16x16x32_bf16 v[96:99], v[152:155], v[184:187], 0
	v_mfma_f32_16x16x32_bf16 v[88:91], v[160:163], v[184:187], 0
	v_mfma_f32_16x16x32_bf16 v[80:83], v[152:155], v[192:195], 0
	v_mfma_f32_16x16x32_bf16 v[72:75], v[160:163], v[192:195], 0
	v_mfma_f32_16x16x32_bf16 v[124:127], v[156:159], v[172:175], v[124:127]
	v_mfma_f32_16x16x32_bf16 v[120:123], v[164:167], v[172:175], v[120:123]
	v_mfma_f32_16x16x32_bf16 v[112:115], v[156:159], v[180:183], v[112:115]
	v_mfma_f32_16x16x32_bf16 v[104:107], v[164:167], v[180:183], v[104:107]
	v_mfma_f32_16x16x32_bf16 v[96:99], v[156:159], v[188:191], v[96:99]
	v_mfma_f32_16x16x32_bf16 v[88:91], v[164:167], v[188:191], v[88:91]
	v_mfma_f32_16x16x32_bf16 v[80:83], v[156:159], v[196:199], v[80:83]
	v_mfma_f32_16x16x32_bf16 v[72:75], v[164:167], v[196:199], v[72:75]
	s_barrier
	s_setprio 0
	s_add_i32 s54, s45, s30
	s_mov_b32 m0, s54
	ds_read_b128 v[202:205], v151
	ds_read_b128 v[206:209], v151 offset:1024
	ds_read_b128 v[210:213], v151 offset:2048
	ds_read_b128 v[214:217], v151 offset:3072
	global_load_lds_dwordx4 v130, s[24:25]
	s_add_i32 m0, s54, 0x2000
	s_nop 0
	global_load_lds_dwordx4 v134, s[24:25]
	s_waitcnt vmcnt(8)
	s_setprio 1
	s_barrier
	s_waitcnt lgkmcnt(0)
	v_mfma_f32_16x16x32_bf16 v[116:119], v[202:205], v[168:171], 0
	v_mfma_f32_16x16x32_bf16 v[108:111], v[210:213], v[168:171], 0
	v_mfma_f32_16x16x32_bf16 v[100:103], v[202:205], v[176:179], 0
	v_mfma_f32_16x16x32_bf16 v[92:95], v[210:213], v[176:179], 0
	v_mfma_f32_16x16x32_bf16 v[84:87], v[202:205], v[184:187], 0
	v_mfma_f32_16x16x32_bf16 v[76:79], v[210:213], v[184:187], 0
	v_mfma_f32_16x16x32_bf16 v[68:71], v[202:205], v[192:195], 0
	v_mfma_f32_16x16x32_bf16 v[64:67], v[210:213], v[192:195], 0
	v_mfma_f32_16x16x32_bf16 v[116:119], v[206:209], v[172:175], v[116:119]
	v_mfma_f32_16x16x32_bf16 v[108:111], v[214:217], v[172:175], v[108:111]
	v_mfma_f32_16x16x32_bf16 v[100:103], v[206:209], v[180:183], v[100:103]
	v_mfma_f32_16x16x32_bf16 v[92:95], v[214:217], v[180:183], v[92:95]
	v_mfma_f32_16x16x32_bf16 v[84:87], v[206:209], v[188:191], v[84:87]
	v_mfma_f32_16x16x32_bf16 v[76:79], v[214:217], v[188:191], v[76:79]
	v_mfma_f32_16x16x32_bf16 v[68:71], v[206:209], v[196:199], v[68:71]
	v_mfma_f32_16x16x32_bf16 v[64:67], v[214:217], v[196:199], v[64:67]
	s_barrier
	s_setprio 0
	s_mov_b32 m0, s21
	v_lshl_add_u64 v[222:223], s[26:27], 0, v[128:129]
	ds_read_b128 v[168:171], v150 offset:16384
	ds_read_b128 v[172:175], v150 offset:17408
	ds_read_b128 v[176:179], v150 offset:18432
	ds_read_b128 v[180:183], v150 offset:19456
	ds_read_b128 v[184:187], v150 offset:20480
	ds_read_b128 v[188:191], v150 offset:21504
	ds_read_b128 v[192:195], v150 offset:22528
	ds_read_b128 v[196:199], v150 offset:23552
	global_load_lds_dwordx4 v128, s[26:27]
	v_lshl_add_u64 v[224:225], s[26:27], 0, v[132:133]
	s_mov_b32 m0, s31
	s_nop 0
	global_load_lds_dwordx4 v132, s[26:27]
	s_setprio 1
	s_barrier
	s_waitcnt lgkmcnt(0)
	v_mfma_f32_16x16x32_bf16 v[60:63], v[152:155], v[168:171], 0
	v_mfma_f32_16x16x32_bf16 v[56:59], v[160:163], v[168:171], 0
	v_mfma_f32_16x16x32_bf16 v[48:51], v[152:155], v[176:179], 0
	v_mfma_f32_16x16x32_bf16 v[40:43], v[160:163], v[176:179], 0
	v_mfma_f32_16x16x32_bf16 v[32:35], v[152:155], v[184:187], 0
	v_mfma_f32_16x16x32_bf16 v[24:27], v[160:163], v[184:187], 0
	v_mfma_f32_16x16x32_bf16 v[16:19], v[152:155], v[192:195], 0
	v_mfma_f32_16x16x32_bf16 v[8:11], v[160:163], v[192:195], 0
	v_mfma_f32_16x16x32_bf16 v[60:63], v[156:159], v[172:175], v[60:63]
	v_mfma_f32_16x16x32_bf16 v[56:59], v[164:167], v[172:175], v[56:59]
	v_mfma_f32_16x16x32_bf16 v[48:51], v[156:159], v[180:183], v[48:51]
	v_mfma_f32_16x16x32_bf16 v[40:43], v[164:167], v[180:183], v[40:43]
	v_mfma_f32_16x16x32_bf16 v[32:35], v[156:159], v[188:191], v[32:35]
	v_mfma_f32_16x16x32_bf16 v[24:27], v[164:167], v[188:191], v[24:27]
	v_mfma_f32_16x16x32_bf16 v[16:19], v[156:159], v[196:199], v[16:19]
	v_mfma_f32_16x16x32_bf16 v[8:11], v[164:167], v[196:199], v[8:11]
	s_barrier
; #define PG8_STAGE(bufoff, gbase, voff) do { _Pragma("unroll") for (int _i = 0; _i < 2; ++_i) \
;         __builtin_amdgcn_global_load_lds((const unsigned*)((const char*)(gbase) + (voff)[_i]), (LAS unsigned*)(lds + (bufoff) + ldsw + _i * 8192), 16, 0, 0); } while (0)
; #define PG8_LDA(dst, b, h) do { _Pragma("unroll") for (int m = 0; m < 4; ++m) _Pragma("unroll") for (int k = 0; k < 2; ++k) dst[m][k] = *(const LAS bf16x8*)(lds + PG8_SA(b, h) + aoff + m * 2048 + k * 1024); } while (0)
; #define PG8_LDB(dst, b, h) do { _Pragma("unroll") for (int n = 0; n < 2; ++n) _Pragma("unroll") for (int k = 0; k < 2; ++k) dst[n][k] = *(const LAS bf16x8*)(lds + PG8_SB(b, h) + boff + n * 2048 + k * 1024); } while (0)
; #define PG8_WAIT_V(n) asm volatile("s_waitcnt vmcnt(" #n ")" ::: "memory")
; #define PG8_WAIT_L(n) asm volatile("s_waitcnt lgkmcnt(" #n ")" ::: "memory")
; #define PG8_BAR __builtin_amdgcn_s_barrier()
; #define PG8_SCHED __builtin_amdgcn_sched_barrier(0)
; template <class Epi, class Sched>
; __device__ __forceinline__ void gemm_phase(LAS unsigned char* lds, const Gemm g, const Sched& S, const Epi& E) {
;     ...
;             PG8_LDB(B0, 0, 0); PG8_SCHED; PG8_LDA(At, 0, 0); PG8_STAGE(PG8_SA(1, 1), a1 + hstep, voffA);
;             PG8_WAIT_L(8); PG8_BAR; PG8_WAIT_L(0); PG8_MMA(0, 0, At, B0); PG8_BAR; PG8_SCHED;
;             PG8_LDB(B1, 0, 1); PG8_STAGE(PG8_SB(0, 0), b2, voffB);
;             PG8_BAR; PG8_WAIT_L(0); PG8_MMA(0, 1, At, B1); PG8_BAR;
;             PG8_LDA(At, 0, 1); PG8_STAGE(PG8_SA(0, 0), a2, voffA);
;             PG8_BAR; PG8_WAIT_L(0); PG8_MMA(1, 0, At, B0); PG8_BAR; PG8_SCHED;
;             PG8_STAGE(PG8_SB(0, 1), b2 + hstep, voffB);
;             PG8_WAIT_V(6); PG8_BAR; PG8_MMA(1, 1, At, B1); PG8_BAR;
;             PG8_LDB(B0, 1, 0); PG8_SCHED; PG8_LDA(At, 1, 0); PG8_STAGE(PG8_SA(0, 1), a2 + hstep, voffA);
;             PG8_WAIT_L(8); PG8_BAR; PG8_WAIT_L(0); PG8_MMA(0, 0, At, B0); PG8_BAR; PG8_SCHED;
;             PG8_LDB(B1, 1, 1); PG8_STAGE(PG8_SB(1, 0), b3, voffB);
;             PG8_BAR; PG8_WAIT_L(0); PG8_MMA(0, 1, At, B1); PG8_BAR;
;             PG8_LDA(At, 1, 1); PG8_STAGE(PG8_SA(1, 0), a3, voffA);
;             PG8_BAR; PG8_WAIT_L(0); PG8_MMA(1, 0, At, B0); PG8_BAR; PG8_SCHED;
;             PG8_STAGE(PG8_SB(1, 1), b3 + hstep, voffB);
;             PG8_WAIT_V(6); PG8_BAR; PG8_MMA(1, 1, At, B1); PG8_BAR;
	s_setprio 0
	s_add_u32 s54, s24, 0x40000
	s_addc_u32 s55, s25, 0
	s_add_i32 s56, s46, s30
	s_mov_b32 m0, s56
	s_nop 0
	global_load_lds_dwordx4 v130, s[54:55]
	s_add_i32 m0, s56, 0x2000
	s_nop 0
	global_load_lds_dwordx4 v134, s[54:55]
	s_add_u32 s26, s26, 0x40000
	s_addc_u32 s27, s27, 0
	s_mov_b32 m0, s33
	s_nop 0
	global_load_lds_dwordx4 v128, s[26:27]
	s_mov_b32 m0, s34
	s_nop 0
	global_load_lds_dwordx4 v132, s[26:27]
	s_waitcnt vmcnt(10)
	s_setprio 1
	s_barrier
	v_mfma_f32_16x16x32_bf16 v[52:55], v[202:205], v[168:171], 0
	v_mfma_f32_16x16x32_bf16 v[44:47], v[210:213], v[168:171], 0
	v_mfma_f32_16x16x32_bf16 v[36:39], v[202:205], v[176:179], 0
	v_mfma_f32_16x16x32_bf16 v[28:31], v[210:213], v[176:179], 0
	v_mfma_f32_16x16x32_bf16 v[20:23], v[202:205], v[184:187], 0
	v_mfma_f32_16x16x32_bf16 v[12:15], v[210:213], v[184:187], 0
	v_mfma_f32_16x16x32_bf16 v[4:7], v[202:205], v[192:195], 0
	v_mfma_f32_16x16x32_bf16 v[0:3], v[210:213], v[192:195], 0
	v_mfma_f32_16x16x32_bf16 v[52:55], v[206:209], v[172:175], v[52:55]
	v_mfma_f32_16x16x32_bf16 v[44:47], v[214:217], v[172:175], v[44:47]
	v_mfma_f32_16x16x32_bf16 v[36:39], v[206:209], v[180:183], v[36:39]
	v_mfma_f32_16x16x32_bf16 v[28:31], v[214:217], v[180:183], v[28:31]
	v_mfma_f32_16x16x32_bf16 v[20:23], v[206:209], v[188:191], v[20:23]
	v_mfma_f32_16x16x32_bf16 v[12:15], v[214:217], v[188:191], v[12:15]
	v_mfma_f32_16x16x32_bf16 v[4:7], v[206:209], v[196:199], v[4:7]
	v_mfma_f32_16x16x32_bf16 v[0:3], v[214:217], v[196:199], v[0:3]
	s_barrier
	s_setprio 0
	s_add_i32 s54, 0, 0x18000
	ds_read_b128 v[152:155], v151 offset:16384
	ds_read_b128 v[156:159], v151 offset:17408
	ds_read_b128 v[160:163], v151 offset:18432
	ds_read_b128 v[164:167], v151 offset:19456
	ds_read_b128 v[168:171], v150 offset:32768
	ds_read_b128 v[172:175], v150 offset:33792
	ds_read_b128 v[176:179], v150 offset:34816
	ds_read_b128 v[180:183], v150 offset:35840
	ds_read_b128 v[184:187], v150 offset:36864
	ds_read_b128 v[188:191], v150 offset:37888
	ds_read_b128 v[192:195], v150 offset:38912
	ds_read_b128 v[196:199], v150 offset:39936
	s_waitcnt lgkmcnt(8)
	s_waitcnt vmcnt(8)
	s_setprio 1
	s_barrier
	s_waitcnt lgkmcnt(0)
	v_mfma_f32_16x16x32_bf16 v[124:127], v[152:155], v[168:171], v[124:127]
	v_mfma_f32_16x16x32_bf16 v[120:123], v[160:163], v[168:171], v[120:123]
	v_mfma_f32_16x16x32_bf16 v[112:115], v[152:155], v[176:179], v[112:115]
	v_mfma_f32_16x16x32_bf16 v[104:107], v[160:163], v[176:179], v[104:107]
	v_mfma_f32_16x16x32_bf16 v[96:99], v[152:155], v[184:187], v[96:99]
	v_mfma_f32_16x16x32_bf16 v[88:91], v[160:163], v[184:187], v[88:91]
	v_mfma_f32_16x16x32_bf16 v[80:83], v[152:155], v[192:195], v[80:83]
	v_mfma_f32_16x16x32_bf16 v[72:75], v[160:163], v[192:195], v[72:75]
	v_mfma_f32_16x16x32_bf16 v[124:127], v[156:159], v[172:175], v[124:127]
	v_mfma_f32_16x16x32_bf16 v[120:123], v[164:167], v[172:175], v[120:123]
	v_mfma_f32_16x16x32_bf16 v[112:115], v[156:159], v[180:183], v[112:115]
	v_mfma_f32_16x16x32_bf16 v[104:107], v[164:167], v[180:183], v[104:107]
	v_mfma_f32_16x16x32_bf16 v[96:99], v[156:159], v[188:191], v[96:99]
	v_mfma_f32_16x16x32_bf16 v[88:91], v[164:167], v[188:191], v[88:91]
	v_mfma_f32_16x16x32_bf16 v[80:83], v[156:159], v[196:199], v[80:83]
	v_mfma_f32_16x16x32_bf16 v[72:75], v[164:167], v[196:199], v[72:75]
	s_barrier
	s_setprio 0
	s_add_i32 s26, 0, 0x1c000
	s_add_i32 s27, s54, s30
	s_add_u32 s0, s24, 0x80
	s_addc_u32 s1, s25, 0
	s_mov_b32 m0, s27
	ds_read_b128 v[202:205], v151 offset:32768
	ds_read_b128 v[206:209], v151 offset:33792
	ds_read_b128 v[210:213], v151 offset:34816
	ds_read_b128 v[214:217], v151 offset:35840
	global_load_lds_dwordx4 v130, s[0:1]
	s_add_i32 m0, s27, 0x2000
	s_nop 0
	global_load_lds_dwordx4 v134, s[0:1]
	s_waitcnt vmcnt(8)
	s_setprio 1
	s_barrier
	s_waitcnt lgkmcnt(0)
	v_mfma_f32_16x16x32_bf16 v[116:119], v[202:205], v[168:171], v[116:119]
	v_mfma_f32_16x16x32_bf16 v[108:111], v[210:213], v[168:171], v[108:111]
	v_mfma_f32_16x16x32_bf16 v[100:103], v[202:205], v[176:179], v[100:103]
	v_mfma_f32_16x16x32_bf16 v[92:95], v[210:213], v[176:179], v[92:95]
	v_mfma_f32_16x16x32_bf16 v[84:87], v[202:205], v[184:187], v[84:87]
	v_mfma_f32_16x16x32_bf16 v[76:79], v[210:213], v[184:187], v[76:79]
	v_mfma_f32_16x16x32_bf16 v[68:71], v[202:205], v[192:195], v[68:71]
	v_mfma_f32_16x16x32_bf16 v[64:67], v[210:213], v[192:195], v[64:67]
	v_mfma_f32_16x16x32_bf16 v[116:119], v[206:209], v[172:175], v[116:119]
	v_mfma_f32_16x16x32_bf16 v[108:111], v[214:217], v[172:175], v[108:111]
	v_mfma_f32_16x16x32_bf16 v[100:103], v[206:209], v[180:183], v[100:103]
	v_mfma_f32_16x16x32_bf16 v[92:95], v[214:217], v[180:183], v[92:95]
	v_mfma_f32_16x16x32_bf16 v[84:87], v[206:209], v[188:191], v[84:87]
	v_mfma_f32_16x16x32_bf16 v[76:79], v[214:217], v[188:191], v[76:79]
	v_mfma_f32_16x16x32_bf16 v[68:71], v[206:209], v[196:199], v[68:71]
	v_mfma_f32_16x16x32_bf16 v[64:67], v[214:217], v[196:199], v[64:67]
	s_barrier
	s_setprio 0
	s_mov_b32 m0, s42
	s_mov_b64 s[0:1], 0x80
	v_lshl_add_u64 v[218:219], v[222:223], 0, s[0:1]
	ds_read_b128 v[168:171], v150 offset:49152
	ds_read_b128 v[172:175], v150 offset:50176
	ds_read_b128 v[176:179], v150 offset:51200
	ds_read_b128 v[180:183], v150 offset:52224
	ds_read_b128 v[184:187], v150 offset:53248
	ds_read_b128 v[188:191], v150 offset:54272
	ds_read_b128 v[192:195], v150 offset:55296
	ds_read_b128 v[196:199], v150 offset:56320
	global_load_lds_dwordx4 v[218:219], off
	v_lshl_add_u64 v[218:219], v[224:225], 0, s[0:1]
	s_mov_b32 m0, s43
	s_nop 0
	global_load_lds_dwordx4 v[218:219], off
	s_setprio 1
	s_barrier
; #define PG8_STAGE(bufoff, gbase, voff) do { _Pragma("unroll") for (int _i = 0; _i < 2; ++_i) \
;         __builtin_amdgcn_global_load_lds((const unsigned*)((const char*)(gbase) + (voff)[_i]), (LAS unsigned*)(lds + (bufoff) + ldsw + _i * 8192), 16, 0, 0); } while (0)
; #define PG8_LDA(dst, b, h) do { _Pragma("unroll") for (int m = 0; m < 4; ++m) _Pragma("unroll") for (int k = 0; k < 2; ++k) dst[m][k] = *(const LAS bf16x8*)(lds + PG8_SA(b, h) + aoff + m * 2048 + k * 1024); } while (0)
; #define PG8_LDB(dst, b, h) do { _Pragma("unroll") for (int n = 0; n < 2; ++n) _Pragma("unroll") for (int k = 0; k < 2; ++k) dst[n][k] = *(const LAS bf16x8*)(lds + PG8_SB(b, h) + boff + n * 2048 + k * 1024); } while (0)
; #define PG8_WAIT_V(n) asm volatile("s_waitcnt vmcnt(" #n ")" ::: "memory")
; #define PG8_WAIT_L(n) asm volatile("s_waitcnt lgkmcnt(" #n ")" ::: "memory")
; #define PG8_BAR __builtin_amdgcn_s_barrier()
; #define PG8_SCHED __builtin_amdgcn_sched_barrier(0)
; template <class Epi, class Sched>
; __device__ __forceinline__ void gemm_phase(LAS unsigned char* lds, const Gemm g, const Sched& S, const Epi& E) {
;     ...
;             PG8_LDB(B0, 0, 0); PG8_SCHED; PG8_LDA(At, 0, 0); PG8_STAGE(PG8_SA(1, 1), a1 + hstep, voffA);
;             PG8_WAIT_L(8); PG8_BAR; PG8_WAIT_L(0); PG8_MMA(0, 0, At, B0); PG8_BAR; PG8_SCHED;
;             PG8_LDB(B1, 0, 1); PG8_STAGE(PG8_SB(0, 0), b2, voffB);
;             PG8_BAR; PG8_WAIT_L(0); PG8_MMA(0, 1, At, B1); PG8_BAR;
;             PG8_LDA(At, 0, 1); PG8_STAGE(PG8_SA(0, 0), a2, voffA);
;             PG8_BAR; PG8_WAIT_L(0); PG8_MMA(1, 0, At, B0); PG8_BAR; PG8_SCHED;
;             PG8_STAGE(PG8_SB(0, 1), b2 + hstep, voffB);
;             PG8_WAIT_V(6); PG8_BAR; PG8_MMA(1, 1, At, B1); PG8_BAR;
;             PG8_LDB(B0, 1, 0); PG8_SCHED; PG8_LDA(At, 1, 0); PG8_STAGE(PG8_SA(0, 1), a2 + hstep, voffA);
;             PG8_WAIT_L(8); PG8_BAR; PG8_WAIT_L(0); PG8_MMA(0, 0, At, B0); PG8_BAR; PG8_SCHED;
;             PG8_LDB(B1, 1, 1); PG8_STAGE(PG8_SB(1, 0), b3, voffB);
;             PG8_BAR; PG8_WAIT_L(0); PG8_MMA(0, 1, At, B1); PG8_BAR;
;             PG8_LDA(At, 1, 1); PG8_STAGE(PG8_SA(1, 0), a3, voffA);
;             PG8_BAR; PG8_WAIT_L(0); PG8_MMA(1, 0, At, B0); PG8_BAR; PG8_SCHED;
;             PG8_STAGE(PG8_SB(1, 1), b3 + hstep, voffB);
;             PG8_WAIT_V(6); PG8_BAR; PG8_MMA(1, 1, At, B1); PG8_BAR;
	s_waitcnt lgkmcnt(0)
	v_mfma_f32_16x16x32_bf16 v[60:63], v[152:155], v[168:171], v[60:63]
	v_mfma_f32_16x16x32_bf16 v[56:59], v[160:163], v[168:171], v[56:59]
	v_mfma_f32_16x16x32_bf16 v[48:51], v[152:155], v[176:179], v[48:51]
	v_mfma_f32_16x16x32_bf16 v[40:43], v[160:163], v[176:179], v[40:43]
	v_mfma_f32_16x16x32_bf16 v[32:35], v[152:155], v[184:187], v[32:35]
	v_mfma_f32_16x16x32_bf16 v[24:27], v[160:163], v[184:187], v[24:27]
	v_mfma_f32_16x16x32_bf16 v[16:19], v[152:155], v[192:195], v[16:19]
	v_mfma_f32_16x16x32_bf16 v[8:11], v[160:163], v[192:195], v[8:11]
	v_mfma_f32_16x16x32_bf16 v[60:63], v[156:159], v[172:175], v[60:63]
	v_mfma_f32_16x16x32_bf16 v[56:59], v[164:167], v[172:175], v[56:59]
	v_mfma_f32_16x16x32_bf16 v[48:51], v[156:159], v[180:183], v[48:51]
	v_mfma_f32_16x16x32_bf16 v[40:43], v[164:167], v[180:183], v[40:43]
	v_mfma_f32_16x16x32_bf16 v[32:35], v[156:159], v[188:191], v[32:35]
	v_mfma_f32_16x16x32_bf16 v[24:27], v[164:167], v[188:191], v[24:27]
	v_mfma_f32_16x16x32_bf16 v[16:19], v[156:159], v[196:199], v[16:19]
	v_mfma_f32_16x16x32_bf16 v[8:11], v[164:167], v[196:199], v[8:11]
	s_barrier
	s_setprio 0
	s_add_u32 s24, s24, 0x40080
	s_addc_u32 s25, s25, 0
	s_add_i32 s26, s26, s30
	s_mov_b32 m0, s26
	s_nop 0
	global_load_lds_dwordx4 v130, s[24:25]
	s_add_i32 m0, s26, 0x2000
	s_nop 0
	global_load_lds_dwordx4 v134, s[24:25]
	s_waitcnt vmcnt(8)
	s_setprio 1
	s_barrier
	v_mfma_f32_16x16x32_bf16 v[52:55], v[202:205], v[168:171], v[52:55]
	v_mfma_f32_16x16x32_bf16 v[44:47], v[210:213], v[168:171], v[44:47]
	v_mfma_f32_16x16x32_bf16 v[36:39], v[202:205], v[176:179], v[36:39]
	v_mfma_f32_16x16x32_bf16 v[28:31], v[210:213], v[176:179], v[28:31]
	v_mfma_f32_16x16x32_bf16 v[20:23], v[202:205], v[184:187], v[20:23]
	v_mfma_f32_16x16x32_bf16 v[12:15], v[210:213], v[184:187], v[12:15]
	v_mfma_f32_16x16x32_bf16 v[4:7], v[202:205], v[192:195], v[4:7]
	v_mfma_f32_16x16x32_bf16 v[0:3], v[210:213], v[192:195], v[0:3]
	v_mfma_f32_16x16x32_bf16 v[52:55], v[206:209], v[172:175], v[52:55]
	v_mfma_f32_16x16x32_bf16 v[44:47], v[214:217], v[172:175], v[44:47]
	v_mfma_f32_16x16x32_bf16 v[36:39], v[206:209], v[180:183], v[36:39]
	v_mfma_f32_16x16x32_bf16 v[28:31], v[214:217], v[180:183], v[28:31]
	v_mfma_f32_16x16x32_bf16 v[20:23], v[206:209], v[188:191], v[20:23]
	v_mfma_f32_16x16x32_bf16 v[12:15], v[214:217], v[188:191], v[12:15]
	v_mfma_f32_16x16x32_bf16 v[4:7], v[206:209], v[196:199], v[4:7]
	v_mfma_f32_16x16x32_bf16 v[0:3], v[214:217], v[196:199], v[0:3]
	s_barrier
	s_setprio 0
	s_add_i32 s53, s53, 2
	s_add_u32 s22, s22, 0x100
	s_addc_u32 s23, s23, 0
	s_add_u32 s51, s51, 0x100
	s_addc_u32 s52, s52, 0
	s_cmp_gt_u32 s53, 13
.LBB0_653:
	ds_read_b128 v[152:155], v149
	ds_read_b128 v[156:159], v149 offset:1024
	ds_read_b128 v[160:163], v149 offset:2048
	ds_read_b128 v[164:167], v149 offset:3072
	s_add_u32 s24, s22, 0xfffc0080
	s_addc_u32 s25, s23, -1
	s_cmp_eq_u32 s53, 12
	s_cselect_b32 s27, s9, s25
	s_cselect_b32 s26, s48, s24
	s_cselect_b32 s25, s7, s52
	s_cselect_b32 s24, s49, s51
	s_add_i32 m0, s21, 0xc000
	ds_read_b128 v[168:171], v150
	ds_read_b128 v[172:175], v150 offset:1024
	ds_read_b128 v[176:179], v150 offset:2048
	ds_read_b128 v[180:183], v150 offset:3072
	ds_read_b128 v[184:187], v150 offset:4096
	ds_read_b128 v[188:191], v150 offset:5120
	ds_read_b128 v[192:195], v150 offset:6144
	ds_read_b128 v[196:199], v150 offset:7168
	global_load_lds_dwordx4 v138, s[22:23]
	s_add_i32 m0, s21, 0xe000
	s_nop 0
	global_load_lds_dwordx4 v140, s[22:23]
	s_waitcnt lgkmcnt(8)
	s_waitcnt vmcnt(8)
	s_setprio 1
	s_barrier
	s_waitcnt lgkmcnt(0)
	v_mfma_f32_16x16x32_bf16 v[124:127], v[152:155], v[168:171], v[124:127]
	v_mfma_f32_16x16x32_bf16 v[120:123], v[160:163], v[168:171], v[120:123]
	v_mfma_f32_16x16x32_bf16 v[112:115], v[152:155], v[176:179], v[112:115]
	v_mfma_f32_16x16x32_bf16 v[104:107], v[160:163], v[176:179], v[104:107]
	v_mfma_f32_16x16x32_bf16 v[96:99], v[152:155], v[184:187], v[96:99]
	v_mfma_f32_16x16x32_bf16 v[88:91], v[160:163], v[184:187], v[88:91]
	v_mfma_f32_16x16x32_bf16 v[80:83], v[152:155], v[192:195], v[80:83]
	v_mfma_f32_16x16x32_bf16 v[72:75], v[160:163], v[192:195], v[72:75]
	v_mfma_f32_16x16x32_bf16 v[124:127], v[156:159], v[172:175], v[124:127]
	v_mfma_f32_16x16x32_bf16 v[120:123], v[164:167], v[172:175], v[120:123]
	v_mfma_f32_16x16x32_bf16 v[112:115], v[156:159], v[180:183], v[112:115]
	v_mfma_f32_16x16x32_bf16 v[104:107], v[164:167], v[180:183], v[104:107]
	v_mfma_f32_16x16x32_bf16 v[96:99], v[156:159], v[188:191], v[96:99]
	v_mfma_f32_16x16x32_bf16 v[88:91], v[164:167], v[188:191], v[88:91]
	v_mfma_f32_16x16x32_bf16 v[80:83], v[156:159], v[196:199], v[80:83]
	v_mfma_f32_16x16x32_bf16 v[72:75], v[164:167], v[196:199], v[72:75]
	s_barrier
	s_setprio 0
	s_add_i32 s54, s45, s30
	s_mov_b32 m0, s54
	ds_read_b128 v[202:205], v151
	ds_read_b128 v[206:209], v151 offset:1024
	ds_read_b128 v[210:213], v151 offset:2048
	ds_read_b128 v[214:217], v151 offset:3072
	global_load_lds_dwordx4 v130, s[24:25]
	s_add_i32 m0, s54, 0x2000
	s_nop 0
	global_load_lds_dwordx4 v134, s[24:25]
	s_waitcnt vmcnt(8)
	s_setprio 1
	s_barrier
; #define PG8_STAGE(bufoff, gbase, voff) do { _Pragma("unroll") for (int _i = 0; _i < 2; ++_i) \
;         __builtin_amdgcn_global_load_lds((const unsigned*)((const char*)(gbase) + (voff)[_i]), (LAS unsigned*)(lds + (bufoff) + ldsw + _i * 8192), 16, 0, 0); } while (0)
; #define PG8_LDA(dst, b, h) do { _Pragma("unroll") for (int m = 0; m < 4; ++m) _Pragma("unroll") for (int k = 0; k < 2; ++k) dst[m][k] = *(const LAS bf16x8*)(lds + PG8_SA(b, h) + aoff + m * 2048 + k * 1024); } while (0)
; #define PG8_LDB(dst, b, h) do { _Pragma("unroll") for (int n = 0; n < 2; ++n) _Pragma("unroll") for (int k = 0; k < 2; ++k) dst[n][k] = *(const LAS bf16x8*)(lds + PG8_SB(b, h) + boff + n * 2048 + k * 1024); } while (0)
; #define PG8_MMA(ai, bj, At, Bt) do { __builtin_amdgcn_s_setprio(1); _Pragma("unroll") for (int m = 0; m < 4; ++m) _Pragma("unroll") for (int n = 0; n < 2; ++n) _Pragma("unroll") for (int k = 0; k < 2; ++k) \
;         acc[ai][bj][m][n] = __builtin_amdgcn_mfma_f32_16x16x32_bf16(Bt[n][k], At[m][k], acc[ai][bj][m][n], 0, 0, 0); __builtin_amdgcn_s_setprio(0); } while (0)
; #define PG8_WAIT_V(n) asm volatile("s_waitcnt vmcnt(" #n ")" ::: "memory")
; #define PG8_WAIT_L(n) asm volatile("s_waitcnt lgkmcnt(" #n ")" ::: "memory")
; #define PG8_BAR __builtin_amdgcn_s_barrier()
; #define PG8_SCHED __builtin_amdgcn_sched_barrier(0)
; template <class Epi, class Sched>
; __device__ __forceinline__ void gemm_phase(LAS unsigned char* lds, const Gemm g, const Sched& S, const Epi& E) {
;     ...
;             PG8_BAR; PG8_WAIT_L(0); PG8_MMA(0, 1, At, B1); PG8_BAR;
;             PG8_LDA(At, 0, 1); PG8_STAGE(PG8_SA(0, 0), a2, voffA);
;             PG8_BAR; PG8_WAIT_L(0); PG8_MMA(1, 0, At, B0); PG8_BAR; PG8_SCHED;
;             PG8_STAGE(PG8_SB(0, 1), b2 + hstep, voffB);
;             PG8_WAIT_V(6); PG8_BAR; PG8_MMA(1, 1, At, B1); PG8_BAR;
;             PG8_LDB(B0, 1, 0); PG8_SCHED; PG8_LDA(At, 1, 0); PG8_STAGE(PG8_SA(0, 1), a2 + hstep, voffA);
	s_waitcnt lgkmcnt(0)
	v_mfma_f32_16x16x32_bf16 v[116:119], v[202:205], v[168:171], v[116:119]
	v_mfma_f32_16x16x32_bf16 v[108:111], v[210:213], v[168:171], v[108:111]
	v_mfma_f32_16x16x32_bf16 v[100:103], v[202:205], v[176:179], v[100:103]
	v_mfma_f32_16x16x32_bf16 v[92:95], v[210:213], v[176:179], v[92:95]
	v_mfma_f32_16x16x32_bf16 v[84:87], v[202:205], v[184:187], v[84:87]
	v_mfma_f32_16x16x32_bf16 v[76:79], v[210:213], v[184:187], v[76:79]
	v_mfma_f32_16x16x32_bf16 v[68:71], v[202:205], v[192:195], v[68:71]
	v_mfma_f32_16x16x32_bf16 v[64:67], v[210:213], v[192:195], v[64:67]
	v_mfma_f32_16x16x32_bf16 v[116:119], v[206:209], v[172:175], v[116:119]
	v_mfma_f32_16x16x32_bf16 v[108:111], v[214:217], v[172:175], v[108:111]
	v_mfma_f32_16x16x32_bf16 v[100:103], v[206:209], v[180:183], v[100:103]
	v_mfma_f32_16x16x32_bf16 v[92:95], v[214:217], v[180:183], v[92:95]
	v_mfma_f32_16x16x32_bf16 v[84:87], v[206:209], v[188:191], v[84:87]
	v_mfma_f32_16x16x32_bf16 v[76:79], v[214:217], v[188:191], v[76:79]
	v_mfma_f32_16x16x32_bf16 v[68:71], v[206:209], v[196:199], v[68:71]
	v_mfma_f32_16x16x32_bf16 v[64:67], v[214:217], v[196:199], v[64:67]
	s_barrier
	s_setprio 0
	s_mov_b32 m0, s21
	v_lshl_add_u64 v[222:223], s[26:27], 0, v[128:129]
	ds_read_b128 v[168:171], v150 offset:16384
	ds_read_b128 v[172:175], v150 offset:17408
	ds_read_b128 v[176:179], v150 offset:18432
	ds_read_b128 v[180:183], v150 offset:19456
	ds_read_b128 v[184:187], v150 offset:20480
	ds_read_b128 v[188:191], v150 offset:21504
	ds_read_b128 v[192:195], v150 offset:22528
	ds_read_b128 v[196:199], v150 offset:23552
	global_load_lds_dwordx4 v128, s[26:27]
	v_lshl_add_u64 v[224:225], s[26:27], 0, v[132:133]
	s_mov_b32 m0, s31
	s_nop 0
	global_load_lds_dwordx4 v132, s[26:27]
	s_setprio 1
	s_barrier
	s_waitcnt lgkmcnt(0)
	v_mfma_f32_16x16x32_bf16 v[60:63], v[152:155], v[168:171], v[60:63]
	v_mfma_f32_16x16x32_bf16 v[56:59], v[160:163], v[168:171], v[56:59]
	v_mfma_f32_16x16x32_bf16 v[48:51], v[152:155], v[176:179], v[48:51]
	v_mfma_f32_16x16x32_bf16 v[40:43], v[160:163], v[176:179], v[40:43]
	v_mfma_f32_16x16x32_bf16 v[32:35], v[152:155], v[184:187], v[32:35]
	v_mfma_f32_16x16x32_bf16 v[24:27], v[160:163], v[184:187], v[24:27]
	v_mfma_f32_16x16x32_bf16 v[16:19], v[152:155], v[192:195], v[16:19]
	v_mfma_f32_16x16x32_bf16 v[8:11], v[160:163], v[192:195], v[8:11]
	v_mfma_f32_16x16x32_bf16 v[60:63], v[156:159], v[172:175], v[60:63]
	v_mfma_f32_16x16x32_bf16 v[56:59], v[164:167], v[172:175], v[56:59]
	v_mfma_f32_16x16x32_bf16 v[48:51], v[156:159], v[180:183], v[48:51]
	v_mfma_f32_16x16x32_bf16 v[40:43], v[164:167], v[180:183], v[40:43]
	v_mfma_f32_16x16x32_bf16 v[32:35], v[156:159], v[188:191], v[32:35]
	v_mfma_f32_16x16x32_bf16 v[24:27], v[164:167], v[188:191], v[24:27]
	v_mfma_f32_16x16x32_bf16 v[16:19], v[156:159], v[196:199], v[16:19]
	v_mfma_f32_16x16x32_bf16 v[8:11], v[164:167], v[196:199], v[8:11]
	s_barrier
	s_setprio 0
	s_add_u32 s54, s24, 0x40000
	s_addc_u32 s55, s25, 0
	s_add_i32 s56, s46, s30
	s_mov_b32 m0, s56
	s_nop 0
	global_load_lds_dwordx4 v130, s[54:55]
	s_add_i32 m0, s56, 0x2000
	s_nop 0
	global_load_lds_dwordx4 v134, s[54:55]
	s_add_u32 s26, s26, 0x40000
	s_addc_u32 s27, s27, 0
	s_mov_b32 m0, s33
	s_nop 0
	global_load_lds_dwordx4 v128, s[26:27]
	s_mov_b32 m0, s34
	s_nop 0
	global_load_lds_dwordx4 v132, s[26:27]
	s_waitcnt vmcnt(10)
	s_setprio 1
	s_barrier
	v_mfma_f32_16x16x32_bf16 v[52:55], v[202:205], v[168:171], v[52:55]
	v_mfma_f32_16x16x32_bf16 v[44:47], v[210:213], v[168:171], v[44:47]
	v_mfma_f32_16x16x32_bf16 v[36:39], v[202:205], v[176:179], v[36:39]
	v_mfma_f32_16x16x32_bf16 v[28:31], v[210:213], v[176:179], v[28:31]
	v_mfma_f32_16x16x32_bf16 v[20:23], v[202:205], v[184:187], v[20:23]
	v_mfma_f32_16x16x32_bf16 v[12:15], v[210:213], v[184:187], v[12:15]
	v_mfma_f32_16x16x32_bf16 v[4:7], v[202:205], v[192:195], v[4:7]
	v_mfma_f32_16x16x32_bf16 v[0:3], v[210:213], v[192:195], v[0:3]
	v_mfma_f32_16x16x32_bf16 v[52:55], v[206:209], v[172:175], v[52:55]
	v_mfma_f32_16x16x32_bf16 v[44:47], v[214:217], v[172:175], v[44:47]
	v_mfma_f32_16x16x32_bf16 v[36:39], v[206:209], v[180:183], v[36:39]
	v_mfma_f32_16x16x32_bf16 v[28:31], v[214:217], v[180:183], v[28:31]
	v_mfma_f32_16x16x32_bf16 v[20:23], v[206:209], v[188:191], v[20:23]
	v_mfma_f32_16x16x32_bf16 v[12:15], v[214:217], v[188:191], v[12:15]
	v_mfma_f32_16x16x32_bf16 v[4:7], v[206:209], v[196:199], v[4:7]
	v_mfma_f32_16x16x32_bf16 v[0:3], v[214:217], v[196:199], v[0:3]
	s_barrier
	s_setprio 0
	s_add_i32 s54, 0, 0x18000
	ds_read_b128 v[152:155], v151 offset:16384
	ds_read_b128 v[156:159], v151 offset:17408
	ds_read_b128 v[160:163], v151 offset:18432
	ds_read_b128 v[164:167], v151 offset:19456
	ds_read_b128 v[168:171], v150 offset:32768
	ds_read_b128 v[172:175], v150 offset:33792
	ds_read_b128 v[176:179], v150 offset:34816
	ds_read_b128 v[180:183], v150 offset:35840
	ds_read_b128 v[184:187], v150 offset:36864
	ds_read_b128 v[188:191], v150 offset:37888
	ds_read_b128 v[192:195], v150 offset:38912
	ds_read_b128 v[196:199], v150 offset:39936
	s_waitcnt lgkmcnt(8)
	s_waitcnt vmcnt(8)
	s_setprio 1
	s_barrier
; #define PG8_STAGE(bufoff, gbase, voff) do { _Pragma("unroll") for (int _i = 0; _i < 2; ++_i) \
;         __builtin_amdgcn_global_load_lds((const unsigned*)((const char*)(gbase) + (voff)[_i]), (LAS unsigned*)(lds + (bufoff) + ldsw + _i * 8192), 16, 0, 0); } while (0)
; #define PG8_LDA(dst, b, h) do { _Pragma("unroll") for (int m = 0; m < 4; ++m) _Pragma("unroll") for (int k = 0; k < 2; ++k) dst[m][k] = *(const LAS bf16x8*)(lds + PG8_SA(b, h) + aoff + m * 2048 + k * 1024); } while (0)
; #define PG8_LDB(dst, b, h) do { _Pragma("unroll") for (int n = 0; n < 2; ++n) _Pragma("unroll") for (int k = 0; k < 2; ++k) dst[n][k] = *(const LAS bf16x8*)(lds + PG8_SB(b, h) + boff + n * 2048 + k * 1024); } while (0)
; #define PG8_MMA(ai, bj, At, Bt) do { __builtin_amdgcn_s_setprio(1); _Pragma("unroll") for (int m = 0; m < 4; ++m) _Pragma("unroll") for (int n = 0; n < 2; ++n) _Pragma("unroll") for (int k = 0; k < 2; ++k) \
;         acc[ai][bj][m][n] = __builtin_amdgcn_mfma_f32_16x16x32_bf16(Bt[n][k], At[m][k], acc[ai][bj][m][n], 0, 0, 0); __builtin_amdgcn_s_setprio(0); } while (0)
; #define PG8_WAIT_V(n) asm volatile("s_waitcnt vmcnt(" #n ")" ::: "memory")
; #define PG8_WAIT_L(n) asm volatile("s_waitcnt lgkmcnt(" #n ")" ::: "memory")
; #define PG8_BAR __builtin_amdgcn_s_barrier()
; #define PG8_SCHED __builtin_amdgcn_sched_barrier(0)
; template <class Epi, class Sched>
; __device__ __forceinline__ void gemm_phase(LAS unsigned char* lds, const Gemm g, const Sched& S, const Epi& E) {
;     ...
;             PG8_WAIT_L(8); PG8_BAR; PG8_WAIT_L(0); PG8_MMA(0, 0, At, B0); PG8_BAR; PG8_SCHED;
;             PG8_LDB(B1, 1, 1); PG8_STAGE(PG8_SB(1, 0), b3, voffB);
;             PG8_BAR; PG8_WAIT_L(0); PG8_MMA(0, 1, At, B1); PG8_BAR;
;             PG8_LDA(At, 1, 1); PG8_STAGE(PG8_SA(1, 0), a3, voffA);
;             PG8_BAR; PG8_WAIT_L(0); PG8_MMA(1, 0, At, B0); PG8_BAR; PG8_SCHED;
;             PG8_STAGE(PG8_SB(1, 1), b3 + hstep, voffB);
;             PG8_WAIT_V(6); PG8_BAR; PG8_MMA(1, 1, At, B1); PG8_BAR;
	s_waitcnt lgkmcnt(0)
	v_mfma_f32_16x16x32_bf16 v[124:127], v[152:155], v[168:171], v[124:127]
	v_mfma_f32_16x16x32_bf16 v[120:123], v[160:163], v[168:171], v[120:123]
	v_mfma_f32_16x16x32_bf16 v[112:115], v[152:155], v[176:179], v[112:115]
	v_mfma_f32_16x16x32_bf16 v[104:107], v[160:163], v[176:179], v[104:107]
	v_mfma_f32_16x16x32_bf16 v[96:99], v[152:155], v[184:187], v[96:99]
	v_mfma_f32_16x16x32_bf16 v[88:91], v[160:163], v[184:187], v[88:91]
	v_mfma_f32_16x16x32_bf16 v[80:83], v[152:155], v[192:195], v[80:83]
	v_mfma_f32_16x16x32_bf16 v[72:75], v[160:163], v[192:195], v[72:75]
	v_mfma_f32_16x16x32_bf16 v[124:127], v[156:159], v[172:175], v[124:127]
	v_mfma_f32_16x16x32_bf16 v[120:123], v[164:167], v[172:175], v[120:123]
	v_mfma_f32_16x16x32_bf16 v[112:115], v[156:159], v[180:183], v[112:115]
	v_mfma_f32_16x16x32_bf16 v[104:107], v[164:167], v[180:183], v[104:107]
	v_mfma_f32_16x16x32_bf16 v[96:99], v[156:159], v[188:191], v[96:99]
	v_mfma_f32_16x16x32_bf16 v[88:91], v[164:167], v[188:191], v[88:91]
	v_mfma_f32_16x16x32_bf16 v[80:83], v[156:159], v[196:199], v[80:83]
	v_mfma_f32_16x16x32_bf16 v[72:75], v[164:167], v[196:199], v[72:75]
	s_barrier
	s_setprio 0
	s_add_i32 s26, 0, 0x1c000
	s_add_i32 s27, s54, s30
	s_add_u32 s0, s24, 0x80
	s_addc_u32 s1, s25, 0
	s_mov_b32 m0, s27
	ds_read_b128 v[202:205], v151 offset:32768
	ds_read_b128 v[206:209], v151 offset:33792
	ds_read_b128 v[210:213], v151 offset:34816
	ds_read_b128 v[214:217], v151 offset:35840
	global_load_lds_dwordx4 v130, s[0:1]
	s_add_i32 m0, s27, 0x2000
	s_nop 0
	global_load_lds_dwordx4 v134, s[0:1]
	s_waitcnt vmcnt(8)
	s_setprio 1
	s_barrier
	s_waitcnt lgkmcnt(0)
	v_mfma_f32_16x16x32_bf16 v[116:119], v[202:205], v[168:171], v[116:119]
	v_mfma_f32_16x16x32_bf16 v[108:111], v[210:213], v[168:171], v[108:111]
	v_mfma_f32_16x16x32_bf16 v[100:103], v[202:205], v[176:179], v[100:103]
	v_mfma_f32_16x16x32_bf16 v[92:95], v[210:213], v[176:179], v[92:95]
	v_mfma_f32_16x16x32_bf16 v[84:87], v[202:205], v[184:187], v[84:87]
	v_mfma_f32_16x16x32_bf16 v[76:79], v[210:213], v[184:187], v[76:79]
	v_mfma_f32_16x16x32_bf16 v[68:71], v[202:205], v[192:195], v[68:71]
	v_mfma_f32_16x16x32_bf16 v[64:67], v[210:213], v[192:195], v[64:67]
	v_mfma_f32_16x16x32_bf16 v[116:119], v[206:209], v[172:175], v[116:119]
	v_mfma_f32_16x16x32_bf16 v[108:111], v[214:217], v[172:175], v[108:111]
	v_mfma_f32_16x16x32_bf16 v[100:103], v[206:209], v[180:183], v[100:103]
	v_mfma_f32_16x16x32_bf16 v[92:95], v[214:217], v[180:183], v[92:95]
	v_mfma_f32_16x16x32_bf16 v[84:87], v[206:209], v[188:191], v[84:87]
	v_mfma_f32_16x16x32_bf16 v[76:79], v[214:217], v[188:191], v[76:79]
	v_mfma_f32_16x16x32_bf16 v[68:71], v[206:209], v[196:199], v[68:71]
	v_mfma_f32_16x16x32_bf16 v[64:67], v[214:217], v[196:199], v[64:67]
	s_barrier
	s_setprio 0
	s_mov_b32 m0, s42
	s_mov_b64 s[0:1], 0x80
	v_lshl_add_u64 v[218:219], v[222:223], 0, s[0:1]
	ds_read_b128 v[168:171], v150 offset:49152
	ds_read_b128 v[172:175], v150 offset:50176
	ds_read_b128 v[176:179], v150 offset:51200
	ds_read_b128 v[180:183], v150 offset:52224
	ds_read_b128 v[184:187], v150 offset:53248
	ds_read_b128 v[188:191], v150 offset:54272
	ds_read_b128 v[192:195], v150 offset:55296
	ds_read_b128 v[196:199], v150 offset:56320
	global_load_lds_dwordx4 v[218:219], off
	v_lshl_add_u64 v[218:219], v[224:225], 0, s[0:1]
	s_mov_b32 m0, s43
	s_nop 0
	global_load_lds_dwordx4 v[218:219], off
	s_setprio 1
	s_barrier
	s_waitcnt lgkmcnt(0)
	v_mfma_f32_16x16x32_bf16 v[60:63], v[152:155], v[168:171], v[60:63]
	v_mfma_f32_16x16x32_bf16 v[56:59], v[160:163], v[168:171], v[56:59]
	v_mfma_f32_16x16x32_bf16 v[48:51], v[152:155], v[176:179], v[48:51]
	v_mfma_f32_16x16x32_bf16 v[40:43], v[160:163], v[176:179], v[40:43]
	v_mfma_f32_16x16x32_bf16 v[32:35], v[152:155], v[184:187], v[32:35]
	v_mfma_f32_16x16x32_bf16 v[24:27], v[160:163], v[184:187], v[24:27]
	v_mfma_f32_16x16x32_bf16 v[16:19], v[152:155], v[192:195], v[16:19]
	v_mfma_f32_16x16x32_bf16 v[8:11], v[160:163], v[192:195], v[8:11]
	v_mfma_f32_16x16x32_bf16 v[60:63], v[156:159], v[172:175], v[60:63]
	v_mfma_f32_16x16x32_bf16 v[56:59], v[164:167], v[172:175], v[56:59]
	v_mfma_f32_16x16x32_bf16 v[48:51], v[156:159], v[180:183], v[48:51]
	v_mfma_f32_16x16x32_bf16 v[40:43], v[164:167], v[180:183], v[40:43]
	v_mfma_f32_16x16x32_bf16 v[32:35], v[156:159], v[188:191], v[32:35]
	v_mfma_f32_16x16x32_bf16 v[24:27], v[164:167], v[188:191], v[24:27]
	v_mfma_f32_16x16x32_bf16 v[16:19], v[156:159], v[196:199], v[16:19]
	v_mfma_f32_16x16x32_bf16 v[8:11], v[164:167], v[196:199], v[8:11]
	s_barrier
	s_setprio 0
	s_add_u32 s24, s24, 0x40080
	s_addc_u32 s25, s25, 0
	s_add_i32 s26, s26, s30
	s_mov_b32 m0, s26
	s_nop 0
	global_load_lds_dwordx4 v130, s[24:25]
	s_add_i32 m0, s26, 0x2000
	s_nop 0
	global_load_lds_dwordx4 v134, s[24:25]
	s_waitcnt vmcnt(8)
	s_setprio 1
	s_barrier
	v_mfma_f32_16x16x32_bf16 v[52:55], v[202:205], v[168:171], v[52:55]
	v_mfma_f32_16x16x32_bf16 v[44:47], v[210:213], v[168:171], v[44:47]
	v_mfma_f32_16x16x32_bf16 v[36:39], v[202:205], v[176:179], v[36:39]
	v_mfma_f32_16x16x32_bf16 v[28:31], v[210:213], v[176:179], v[28:31]
	v_mfma_f32_16x16x32_bf16 v[20:23], v[202:205], v[184:187], v[20:23]
	v_mfma_f32_16x16x32_bf16 v[12:15], v[210:213], v[184:187], v[12:15]
	v_mfma_f32_16x16x32_bf16 v[4:7], v[202:205], v[192:195], v[4:7]
	v_mfma_f32_16x16x32_bf16 v[0:3], v[210:213], v[192:195], v[0:3]
	v_mfma_f32_16x16x32_bf16 v[52:55], v[206:209], v[172:175], v[52:55]
	v_mfma_f32_16x16x32_bf16 v[44:47], v[214:217], v[172:175], v[44:47]
	v_mfma_f32_16x16x32_bf16 v[36:39], v[206:209], v[180:183], v[36:39]
	v_mfma_f32_16x16x32_bf16 v[28:31], v[214:217], v[180:183], v[28:31]
	v_mfma_f32_16x16x32_bf16 v[20:23], v[206:209], v[188:191], v[20:23]
	v_mfma_f32_16x16x32_bf16 v[12:15], v[214:217], v[188:191], v[12:15]
	v_mfma_f32_16x16x32_bf16 v[4:7], v[206:209], v[196:199], v[4:7]
	v_mfma_f32_16x16x32_bf16 v[0:3], v[214:217], v[196:199], v[0:3]
	s_barrier
; __device__ __forceinline__ unsigned cvt_pk_bf16(float lo, float hi) { unsigned r; asm volatile("v_cvt_pk_bf16_f32 %0, %1, %2" : "=v"(r) : "v"(lo), "v"(hi)); return r; }
;     __device__ __forceinline__ void operator()(const AccT& acc, const Unit& u, int wr, int wc, int fr, int fq) const {
;         asm volatile("" : "+v"(fr), "+v"(fq));
;         const int rbase = u.pm * 256 + wr * 64 + fr;
;         const int tb = u.pn * 256 + wc * 32 + 8 * fq;
; #pragma unroll
;         for (int ai = 0; ai < 2; ++ai)
; #pragma unroll
;             for (int m = 0; m < 4; ++m) {
;                 const int gm = rbase + ai * 128 + m * 16;
; #pragma unroll
;                 for (int bj = 0; bj < 2; ++bj) {
;                     const int t0 = tb + bj * 128;
;                     const f32x4 v0 = acc[ai][bj][m][0], v1 = acc[ai][bj][m][1];
;                     u32x4 w; w.x = cvt_pk_bf16(v0[0], v0[1]); w.y = cvt_pk_bf16(v0[2], v0[3]); w.z = cvt_pk_bf16(v1[0], v1[1]); w.w = cvt_pk_bf16(v1[2], v1[3]);
;                     *(u32x4*)(YT + ((size_t)((t0 >> 10) * 512 + gm)) * 2048 + part * 1024 + (t0 & 1023)) = w;
;                 }
;             }
	s_setprio 0
	s_add_i32 s53, s53, 2
	s_add_u32 s22, s22, 0x100
	s_addc_u32 s23, s23, 0
	s_add_u32 s51, s51, 0x100
	s_addc_u32 s52, s52, 0
	s_cmp_gt_u32 s53, 13
	s_cbranch_scc0 .LBB0_653
	v_mov_b32_e32 v136, v147
	v_mov_b32_e32 v152, v146
	s_lshl_b32 s7, s20, 8
	s_add_i32 s7, s7, s36
	v_add_u32_e32 v152, s7, v152
	s_lshl_b32 s7, s47, 8
	s_or_b32 s7, s7, s37
	v_lshl_add_u32 v153, v136, 3, s7
	v_cvt_pk_bf16_f32 v124, v124, v125
	v_cvt_pk_bf16_f32 v125, v126, v127
	v_cvt_pk_bf16_f32 v126, v120, v121
	v_ashrrev_i32_e32 v120, 1, v153
	v_cvt_pk_bf16_f32 v127, v122, v123
	v_and_b32_e32 v122, 0xfffffe00, v120
	v_add_u32_e32 v120, v122, v152
	v_ashrrev_i32_e32 v121, 31, v120
	v_lshlrev_b64 v[120:121], 12, v[120:121]
	v_and_b32_e32 v123, 0x3f8, v153
	v_lshl_add_u64 v[120:121], s[68:69], 0, v[120:121]
	v_lshlrev_b32_e32 v136, 1, v123
	v_lshl_add_u64 v[120:121], v[120:121], 0, v[136:137]
	global_store_dwordx4 v[120:121], v[124:127], off
	v_add_u32_e32 v120, 0x80, v153
	v_cvt_pk_bf16_f32 v116, v116, v117
	v_cvt_pk_bf16_f32 v117, v118, v119
	v_cvt_pk_bf16_f32 v118, v108, v109
	v_ashrrev_i32_e32 v108, 1, v120
	v_and_b32_e32 v121, 0xfffffe00, v108
	v_add_u32_e32 v108, v121, v152
	v_ashrrev_i32_e32 v109, 31, v108
	v_lshlrev_b64 v[108:109], 12, v[108:109]
	v_cvt_pk_bf16_f32 v119, v110, v111
	v_lshl_add_u64 v[110:111], s[68:69], 0, v[108:109]
	v_and_b32_e32 v108, 0x3f8, v120
	v_lshlrev_b32_e32 v108, 1, v108
	v_mov_b32_e32 v109, v137
	v_lshl_add_u64 v[110:111], v[110:111], 0, v[108:109]
	global_store_dwordx4 v[110:111], v[116:119], off
	v_cvt_pk_bf16_f32 v110, v112, v113
	v_cvt_pk_bf16_f32 v111, v114, v115
	v_cvt_pk_bf16_f32 v112, v104, v105
	v_cvt_pk_bf16_f32 v113, v106, v107
	s_and_b64 vcc, exec, s[4:5]
	s_nop 0
	v_add_u32_e32 v116, 16, v152
	v_add_u32_e32 v104, v122, v116
	v_ashrrev_i32_e32 v105, 31, v104
	v_lshlrev_b64 v[104:105], 12, v[104:105]
	v_lshl_add_u64 v[104:105], s[68:69], 0, v[104:105]
	v_lshl_add_u64 v[104:105], v[104:105], 0, v[136:137]
	global_store_dwordx4 v[104:105], v[110:113], off
	v_cvt_pk_bf16_f32 v100, v100, v101
	v_cvt_pk_bf16_f32 v101, v102, v103
	v_cvt_pk_bf16_f32 v102, v92, v93
	v_add_u32_e32 v92, v121, v116
	v_ashrrev_i32_e32 v93, 31, v92
	v_lshlrev_b64 v[92:93], 12, v[92:93]
	v_lshl_add_u64 v[92:93], s[68:69], 0, v[92:93]
	v_lshl_add_u64 v[92:93], v[92:93], 0, v[108:109]
	v_cvt_pk_bf16_f32 v103, v94, v95
	global_store_dwordx4 v[92:93], v[100:103], off
	v_cvt_pk_bf16_f32 v92, v96, v97
	v_cvt_pk_bf16_f32 v93, v98, v99
	v_cvt_pk_bf16_f32 v94, v88, v89
	v_cvt_pk_bf16_f32 v95, v90, v91
	s_mov_b32 s47, s6
	s_nop 0
	v_add_u32_e32 v100, 32, v152
	v_add_u32_e32 v88, v122, v100
	v_ashrrev_i32_e32 v89, 31, v88
	v_lshlrev_b64 v[88:89], 12, v[88:89]
	v_lshl_add_u64 v[88:89], s[68:69], 0, v[88:89]
	v_lshl_add_u64 v[88:89], v[88:89], 0, v[136:137]
	global_store_dwordx4 v[88:89], v[92:95], off
	v_cvt_pk_bf16_f32 v84, v84, v85
	v_cvt_pk_bf16_f32 v85, v86, v87
	v_cvt_pk_bf16_f32 v86, v76, v77
	v_add_u32_e32 v76, v121, v100
	v_ashrrev_i32_e32 v77, 31, v76
	v_lshlrev_b64 v[76:77], 12, v[76:77]
	v_lshl_add_u64 v[76:77], s[68:69], 0, v[76:77]
	v_lshl_add_u64 v[76:77], v[76:77], 0, v[108:109]
	v_cvt_pk_bf16_f32 v87, v78, v79
	global_store_dwordx4 v[76:77], v[84:87], off
	v_cvt_pk_bf16_f32 v76, v80, v81
	v_cvt_pk_bf16_f32 v77, v82, v83
	v_cvt_pk_bf16_f32 v78, v72, v73
	v_cvt_pk_bf16_f32 v79, v74, v75
	s_mov_b32 s20, s8
	s_nop 0
	v_add_u32_e32 v84, 48, v152
	v_add_u32_e32 v72, v122, v84
	v_ashrrev_i32_e32 v73, 31, v72
	v_lshlrev_b64 v[72:73], 12, v[72:73]
	v_lshl_add_u64 v[72:73], s[68:69], 0, v[72:73]
	v_lshl_add_u64 v[72:73], v[72:73], 0, v[136:137]
	global_store_dwordx4 v[72:73], v[76:79], off
; __device__ __forceinline__ unsigned cvt_pk_bf16(float lo, float hi) { unsigned r; asm volatile("v_cvt_pk_bf16_f32 %0, %1, %2" : "=v"(r) : "v"(lo), "v"(hi)); return r; }
; #define PG8_WAIT_V(n) asm volatile("s_waitcnt vmcnt(" #n ")" ::: "memory")
; #define PG8_BAR __builtin_amdgcn_s_barrier()
; template <class Epi, class Sched>
; __device__ __forceinline__ void gemm_phase(LAS unsigned char* lds, const Gemm g, const Sched& S, const Epi& E) {
;     ...
;         E(acc, cur, wr, wc, fr, fq);
;         if (!has_next) break;
; #pragma unroll
;         for (int a = 0; a < 2; ++a)
; #pragma unroll
;             for (int b = 0; b < 2; ++b)
; #pragma unroll
;                 for (int m = 0; m < 4; ++m)
; #pragma unroll
;                     for (int n = 0; n < 2; ++n) acc[a][b][m][n] = (f32x4){0.f, 0.f, 0.f, 0.f};
;         cur = nxt; cA = nA; cB = nB; ++ui;
;     }
;     PG8_WAIT_V(0);
;     if (wr == 0) PG8_BAR;
;     PG8_BAR;
;     __device__ __forceinline__ void operator()(const AccT& acc, const Unit& u, int wr, int wc, int fr, int fq) const {
;     ...
;                 const int gm = rbase + ai * 128 + m * 16;
; #pragma unroll
;                 for (int bj = 0; bj < 2; ++bj) {
;                     const int t0 = tb + bj * 128;
;                     const f32x4 v0 = acc[ai][bj][m][0], v1 = acc[ai][bj][m][1];
;                     u32x4 w; w.x = cvt_pk_bf16(v0[0], v0[1]); w.y = cvt_pk_bf16(v0[2], v0[3]); w.z = cvt_pk_bf16(v1[0], v1[1]); w.w = cvt_pk_bf16(v1[2], v1[3]);
;                     *(u32x4*)(YT + ((size_t)((t0 >> 10) * 512 + gm)) * 2048 + part * 1024 + (t0 & 1023)) = w;
;                 }
;             }
	v_cvt_pk_bf16_f32 v68, v68, v69
	v_cvt_pk_bf16_f32 v69, v70, v71
	v_cvt_pk_bf16_f32 v70, v64, v65
	v_add_u32_e32 v64, v121, v84
	v_ashrrev_i32_e32 v65, 31, v64
	v_lshlrev_b64 v[64:65], 12, v[64:65]
	v_lshl_add_u64 v[64:65], s[68:69], 0, v[64:65]
	v_lshl_add_u64 v[64:65], v[64:65], 0, v[108:109]
	v_cvt_pk_bf16_f32 v71, v66, v67
	global_store_dwordx4 v[64:65], v[68:71], off
	v_add_u32_e32 v64, 0x80, v152
	v_cvt_pk_bf16_f32 v60, v60, v61
	v_cvt_pk_bf16_f32 v61, v62, v63
	v_cvt_pk_bf16_f32 v62, v56, v57
	v_add_u32_e32 v56, v122, v64
	v_ashrrev_i32_e32 v57, 31, v56
	v_lshlrev_b64 v[56:57], 12, v[56:57]
	v_lshl_add_u64 v[56:57], s[68:69], 0, v[56:57]
	v_lshl_add_u64 v[56:57], v[56:57], 0, v[136:137]
	v_cvt_pk_bf16_f32 v63, v58, v59
	global_store_dwordx4 v[56:57], v[60:63], off
	v_cvt_pk_bf16_f32 v52, v52, v53
	v_cvt_pk_bf16_f32 v53, v54, v55
	v_cvt_pk_bf16_f32 v54, v44, v45
	v_add_u32_e32 v44, v121, v64
	v_ashrrev_i32_e32 v45, 31, v44
	v_lshlrev_b64 v[44:45], 12, v[44:45]
	v_lshl_add_u64 v[44:45], s[68:69], 0, v[44:45]
	v_lshl_add_u64 v[44:45], v[44:45], 0, v[108:109]
	v_cvt_pk_bf16_f32 v55, v46, v47
	global_store_dwordx4 v[44:45], v[52:55], off
	v_cvt_pk_bf16_f32 v44, v48, v49
	v_cvt_pk_bf16_f32 v45, v50, v51
	v_cvt_pk_bf16_f32 v46, v40, v41
	v_cvt_pk_bf16_f32 v47, v42, v43
	s_mov_b64 s[24:25], s[18:19]
	s_nop 0
	v_add_u32_e32 v52, 0x90, v152
	v_add_u32_e32 v40, v122, v52
	v_ashrrev_i32_e32 v41, 31, v40
	v_lshlrev_b64 v[40:41], 12, v[40:41]
	v_lshl_add_u64 v[40:41], s[68:69], 0, v[40:41]
	v_lshl_add_u64 v[40:41], v[40:41], 0, v[136:137]
	global_store_dwordx4 v[40:41], v[44:47], off
	v_cvt_pk_bf16_f32 v36, v36, v37
	v_cvt_pk_bf16_f32 v37, v38, v39
	v_cvt_pk_bf16_f32 v38, v28, v29
	v_add_u32_e32 v28, v121, v52
	v_ashrrev_i32_e32 v29, 31, v28
	v_lshlrev_b64 v[28:29], 12, v[28:29]
	v_lshl_add_u64 v[28:29], s[68:69], 0, v[28:29]
	v_lshl_add_u64 v[28:29], v[28:29], 0, v[108:109]
	v_cvt_pk_bf16_f32 v39, v30, v31
	global_store_dwordx4 v[28:29], v[36:39], off
	v_cvt_pk_bf16_f32 v28, v32, v33
	v_cvt_pk_bf16_f32 v29, v34, v35
	v_cvt_pk_bf16_f32 v30, v24, v25
	v_cvt_pk_bf16_f32 v31, v26, v27
	s_mov_b64 s[22:23], s[16:17]
	s_nop 0
	v_add_u32_e32 v36, 0xa0, v152
	v_add_u32_e32 v24, v122, v36
	v_ashrrev_i32_e32 v25, 31, v24
	v_lshlrev_b64 v[24:25], 12, v[24:25]
	v_lshl_add_u64 v[24:25], s[68:69], 0, v[24:25]
	v_lshl_add_u64 v[24:25], v[24:25], 0, v[136:137]
	global_store_dwordx4 v[24:25], v[28:31], off
	v_cvt_pk_bf16_f32 v20, v20, v21
	v_cvt_pk_bf16_f32 v21, v22, v23
	v_cvt_pk_bf16_f32 v22, v12, v13
	v_add_u32_e32 v12, v121, v36
	v_ashrrev_i32_e32 v13, 31, v12
	v_lshlrev_b64 v[12:13], 12, v[12:13]
	v_lshl_add_u64 v[12:13], s[68:69], 0, v[12:13]
	v_lshl_add_u64 v[12:13], v[12:13], 0, v[108:109]
	v_cvt_pk_bf16_f32 v23, v14, v15
	global_store_dwordx4 v[12:13], v[20:23], off
	v_cvt_pk_bf16_f32 v12, v16, v17
	v_cvt_pk_bf16_f32 v13, v18, v19
	v_cvt_pk_bf16_f32 v14, v8, v9
	v_cvt_pk_bf16_f32 v15, v10, v11
	s_nop 1
	v_add_u32_e32 v20, 0xb0, v152
	v_add_u32_e32 v8, v122, v20
	v_ashrrev_i32_e32 v9, 31, v8
	v_lshlrev_b64 v[8:9], 12, v[8:9]
	v_lshl_add_u64 v[8:9], s[68:69], 0, v[8:9]
	v_lshl_add_u64 v[8:9], v[8:9], 0, v[136:137]
	global_store_dwordx4 v[8:9], v[12:15], off
	v_cvt_pk_bf16_f32 v4, v4, v5
	v_cvt_pk_bf16_f32 v5, v6, v7
	v_cvt_pk_bf16_f32 v6, v0, v1
	v_add_u32_e32 v0, v121, v20
	v_ashrrev_i32_e32 v1, 31, v0
	v_lshlrev_b64 v[0:1], 12, v[0:1]
	v_lshl_add_u64 v[0:1], s[68:69], 0, v[0:1]
	v_lshl_add_u64 v[0:1], v[0:1], 0, v[108:109]
	v_cvt_pk_bf16_f32 v7, v2, v3
	global_store_dwordx4 v[0:1], v[4:7], off
	s_cbranch_vccz .LBB0_646
	s_waitcnt vmcnt(0)
	s_cmpk_gt_u32 s28, 0xff
	s_cbranch_scc1 .LBB0_657
	s_barrier

; #define PG8_STAGE(bufoff, gbase, voff) do { _Pragma("unroll") for (int _i = 0; _i < 2; ++_i) \
;         __builtin_amdgcn_global_load_lds((const unsigned*)((const char*)(gbase) + (voff)[_i]), (LAS unsigned*)(lds + (bufoff) + ldsw + _i * 8192), 16, 0, 0); } while (0)
; #define PG8_LDA(dst, b, h) do { _Pragma("unroll") for (int m = 0; m < 4; ++m) _Pragma("unroll") for (int k = 0; k < 2; ++k) dst[m][k] = *(const LAS bf16x8*)(lds + PG8_SA(b, h) + aoff + m * 2048 + k * 1024); } while (0)
; #define PG8_LDB(dst, b, h) do { _Pragma("unroll") for (int n = 0; n < 2; ++n) _Pragma("unroll") for (int k = 0; k < 2; ++k) dst[n][k] = *(const LAS bf16x8*)(lds + PG8_SB(b, h) + boff + n * 2048 + k * 1024); } while (0)
; #define PG8_MMA(ai, bj, At, Bt) do { __builtin_amdgcn_s_setprio(1); _Pragma("unroll") for (int m = 0; m < 4; ++m) _Pragma("unroll") for (int n = 0; n < 2; ++n) _Pragma("unroll") for (int k = 0; k < 2; ++k) \
;         acc[ai][bj][m][n] = __builtin_amdgcn_mfma_f32_16x16x32_bf16(Bt[n][k], At[m][k], acc[ai][bj][m][n], 0, 0, 0); __builtin_amdgcn_s_setprio(0); } while (0)
; #define PG8_WAIT_L(n) asm volatile("s_waitcnt lgkmcnt(" #n ")" ::: "memory")
; template <class Epi, class Sched>
; __device__ __forceinline__ void gemm_phase(LAS unsigned char* lds, const Gemm g, const Sched& S, const Epi& E) {
;     ...
;     for (;;) {
;         const bool has_next = S.next(ui + 1, nxt);
;         const char* nA = has_next ? (const char*)g.A + (size_t)nxt.pm * tstep : cA; const char* nB = has_next ? (const char*)g.Bt + (size_t)nxt.pn * tstep : cB;
;         for (int t = 0; t < nt; t += 2) {
;             const bool last = (t == nt - 2);
;             const char* a1 = cA + (size_t)(t + 1) * kstep;
;             const char* a2 = last ? nA : cA + (size_t)(t + 2) * kstep; const char* b2 = last ? nB : cB + (size_t)(t + 2) * kstep;
;             const char* a3 = a2 + kstep; const char* b3 = b2 + kstep;
;             PG8_LDB(B0, 0, 0); PG8_SCHED; PG8_LDA(At, 0, 0); PG8_STAGE(PG8_SA(1, 1), a1 + hstep, voffA);
;             PG8_WAIT_L(8); PG8_BAR; PG8_WAIT_L(0); PG8_MMA(0, 0, At, B0); PG8_BAR; PG8_SCHED;
;             PG8_LDB(B1, 0, 1); PG8_STAGE(PG8_SB(0, 0), b2, voffB);
;             PG8_BAR; PG8_WAIT_L(0); PG8_MMA(0, 1, At, B1); PG8_BAR;
;             PG8_LDA(At, 0, 1); PG8_STAGE(PG8_SA(0, 0), a2, voffA);
;             PG8_BAR; PG8_WAIT_L(0); PG8_MMA(1, 0, At, B0); PG8_BAR; PG8_SCHED;
.LBB0_672:
	s_ashr_i32 s9, s8, 31
	v_cmp_lt_i64_e32 vcc, s[12:13], v[142:143]
	s_lshl_b64 s[12:13], s[8:9], 19
	s_add_u32 s12, s26, s12
	s_addc_u32 s13, s27, s13
	s_and_b64 s[14:15], vcc, exec
	s_cselect_b32 s9, s13, s19
	s_cselect_b32 s46, s12, s18
	s_ashr_i32 s7, s6, 31
	s_lshl_b64 s[14:15], s[6:7], 19
	s_add_u32 s14, s10, s14
	s_addc_u32 s15, s11, s15
	s_and_b64 s[22:23], vcc, exec
	s_cselect_b32 s7, s15, s21
	s_cselect_b32 s47, s14, s20
	s_add_u32 s18, s18, 0x40080
	s_addc_u32 s19, s19, 0
	s_add_u32 s48, s20, 0x100
	s_addc_u32 s49, s21, 0
	s_mov_b32 s51, -2
	s_waitcnt lgkmcnt(0)
	ds_read_b128 v[152:155], v149
	ds_read_b128 v[156:159], v149 offset:1024
	ds_read_b128 v[160:163], v149 offset:2048
	ds_read_b128 v[164:167], v149 offset:3072
	s_add_u32 s20, s18, 0xfffc0080
	s_addc_u32 s21, s19, -1
	s_cmp_eq_u32 s51, 12
	s_cselect_b32 s23, s9, s21
	s_cselect_b32 s22, s46, s20
	s_cselect_b32 s21, s7, s49
	s_cselect_b32 s20, s47, s48
	s_add_i32 m0, s17, 0xc000
	ds_read_b128 v[168:171], v150
	ds_read_b128 v[172:175], v150 offset:1024
	ds_read_b128 v[176:179], v150 offset:2048
	ds_read_b128 v[180:183], v150 offset:3072
	ds_read_b128 v[184:187], v150 offset:4096
	ds_read_b128 v[188:191], v150 offset:5120
	ds_read_b128 v[192:195], v150 offset:6144
	ds_read_b128 v[196:199], v150 offset:7168
	global_load_lds_dwordx4 v138, s[18:19]
	s_add_i32 m0, s17, 0xe000
	s_nop 0
	global_load_lds_dwordx4 v140, s[18:19]
	s_waitcnt lgkmcnt(8)
	s_waitcnt vmcnt(8)
	s_setprio 1
	s_barrier
	s_waitcnt lgkmcnt(0)
	v_mfma_f32_16x16x32_bf16 v[124:127], v[152:155], v[168:171], 0
	v_mfma_f32_16x16x32_bf16 v[120:123], v[160:163], v[168:171], 0
	v_mfma_f32_16x16x32_bf16 v[112:115], v[152:155], v[176:179], 0
	v_mfma_f32_16x16x32_bf16 v[104:107], v[160:163], v[176:179], 0
	v_mfma_f32_16x16x32_bf16 v[96:99], v[152:155], v[184:187], 0
	v_mfma_f32_16x16x32_bf16 v[88:91], v[160:163], v[184:187], 0
	v_mfma_f32_16x16x32_bf16 v[80:83], v[152:155], v[192:195], 0
	v_mfma_f32_16x16x32_bf16 v[72:75], v[160:163], v[192:195], 0
	v_mfma_f32_16x16x32_bf16 v[124:127], v[156:159], v[172:175], v[124:127]
	v_mfma_f32_16x16x32_bf16 v[120:123], v[164:167], v[172:175], v[120:123]
	v_mfma_f32_16x16x32_bf16 v[112:115], v[156:159], v[180:183], v[112:115]
	v_mfma_f32_16x16x32_bf16 v[104:107], v[164:167], v[180:183], v[104:107]
	v_mfma_f32_16x16x32_bf16 v[96:99], v[156:159], v[188:191], v[96:99]
	v_mfma_f32_16x16x32_bf16 v[88:91], v[164:167], v[188:191], v[88:91]
	v_mfma_f32_16x16x32_bf16 v[80:83], v[156:159], v[196:199], v[80:83]
	v_mfma_f32_16x16x32_bf16 v[72:75], v[164:167], v[196:199], v[72:75]
	s_barrier
	s_setprio 0
	s_add_i32 s52, s43, s28
	s_mov_b32 m0, s52
	ds_read_b128 v[202:205], v151
	ds_read_b128 v[206:209], v151 offset:1024
	ds_read_b128 v[210:213], v151 offset:2048
	ds_read_b128 v[214:217], v151 offset:3072
	global_load_lds_dwordx4 v130, s[20:21]
	s_add_i32 m0, s52, 0x2000
	s_nop 0
	global_load_lds_dwordx4 v134, s[20:21]
	s_waitcnt vmcnt(8)
	s_setprio 1
	s_barrier
	s_waitcnt lgkmcnt(0)
	v_mfma_f32_16x16x32_bf16 v[116:119], v[202:205], v[168:171], 0
	v_mfma_f32_16x16x32_bf16 v[108:111], v[210:213], v[168:171], 0
	v_mfma_f32_16x16x32_bf16 v[100:103], v[202:205], v[176:179], 0
	v_mfma_f32_16x16x32_bf16 v[92:95], v[210:213], v[176:179], 0
	v_mfma_f32_16x16x32_bf16 v[84:87], v[202:205], v[184:187], 0
	v_mfma_f32_16x16x32_bf16 v[76:79], v[210:213], v[184:187], 0
	v_mfma_f32_16x16x32_bf16 v[68:71], v[202:205], v[192:195], 0
	v_mfma_f32_16x16x32_bf16 v[64:67], v[210:213], v[192:195], 0
	v_mfma_f32_16x16x32_bf16 v[116:119], v[206:209], v[172:175], v[116:119]
	v_mfma_f32_16x16x32_bf16 v[108:111], v[214:217], v[172:175], v[108:111]
	v_mfma_f32_16x16x32_bf16 v[100:103], v[206:209], v[180:183], v[100:103]
	v_mfma_f32_16x16x32_bf16 v[92:95], v[214:217], v[180:183], v[92:95]
	v_mfma_f32_16x16x32_bf16 v[84:87], v[206:209], v[188:191], v[84:87]
	v_mfma_f32_16x16x32_bf16 v[76:79], v[214:217], v[188:191], v[76:79]
	v_mfma_f32_16x16x32_bf16 v[68:71], v[206:209], v[196:199], v[68:71]
	v_mfma_f32_16x16x32_bf16 v[64:67], v[214:217], v[196:199], v[64:67]
	s_barrier
	s_setprio 0
	s_mov_b32 m0, s17
	v_lshl_add_u64 v[222:223], s[22:23], 0, v[128:129]
	ds_read_b128 v[168:171], v150 offset:16384
	ds_read_b128 v[172:175], v150 offset:17408
	ds_read_b128 v[176:179], v150 offset:18432
	ds_read_b128 v[180:183], v150 offset:19456
	ds_read_b128 v[184:187], v150 offset:20480
	ds_read_b128 v[188:191], v150 offset:21504
	ds_read_b128 v[192:195], v150 offset:22528
	ds_read_b128 v[196:199], v150 offset:23552
	global_load_lds_dwordx4 v128, s[22:23]
	v_lshl_add_u64 v[224:225], s[22:23], 0, v[132:133]
	s_mov_b32 m0, s29
	s_nop 0
	global_load_lds_dwordx4 v132, s[22:23]
	s_setprio 1
	s_barrier
	s_waitcnt lgkmcnt(0)
	v_mfma_f32_16x16x32_bf16 v[60:63], v[152:155], v[168:171], 0
	v_mfma_f32_16x16x32_bf16 v[56:59], v[160:163], v[168:171], 0
	v_mfma_f32_16x16x32_bf16 v[48:51], v[152:155], v[176:179], 0
	v_mfma_f32_16x16x32_bf16 v[40:43], v[160:163], v[176:179], 0
	v_mfma_f32_16x16x32_bf16 v[32:35], v[152:155], v[184:187], 0
	v_mfma_f32_16x16x32_bf16 v[24:27], v[160:163], v[184:187], 0
	v_mfma_f32_16x16x32_bf16 v[16:19], v[152:155], v[192:195], 0
	v_mfma_f32_16x16x32_bf16 v[8:11], v[160:163], v[192:195], 0
	v_mfma_f32_16x16x32_bf16 v[60:63], v[156:159], v[172:175], v[60:63]
	v_mfma_f32_16x16x32_bf16 v[56:59], v[164:167], v[172:175], v[56:59]
	v_mfma_f32_16x16x32_bf16 v[48:51], v[156:159], v[180:183], v[48:51]
	v_mfma_f32_16x16x32_bf16 v[40:43], v[164:167], v[180:183], v[40:43]
	v_mfma_f32_16x16x32_bf16 v[32:35], v[156:159], v[188:191], v[32:35]
	v_mfma_f32_16x16x32_bf16 v[24:27], v[164:167], v[188:191], v[24:27]
	v_mfma_f32_16x16x32_bf16 v[16:19], v[156:159], v[196:199], v[16:19]
	v_mfma_f32_16x16x32_bf16 v[8:11], v[164:167], v[196:199], v[8:11]
	s_barrier
; #define PG8_STAGE(bufoff, gbase, voff) do { _Pragma("unroll") for (int _i = 0; _i < 2; ++_i) \
;         __builtin_amdgcn_global_load_lds((const unsigned*)((const char*)(gbase) + (voff)[_i]), (LAS unsigned*)(lds + (bufoff) + ldsw + _i * 8192), 16, 0, 0); } while (0)
; #define PG8_LDA(dst, b, h) do { _Pragma("unroll") for (int m = 0; m < 4; ++m) _Pragma("unroll") for (int k = 0; k < 2; ++k) dst[m][k] = *(const LAS bf16x8*)(lds + PG8_SA(b, h) + aoff + m * 2048 + k * 1024); } while (0)
; #define PG8_LDB(dst, b, h) do { _Pragma("unroll") for (int n = 0; n < 2; ++n) _Pragma("unroll") for (int k = 0; k < 2; ++k) dst[n][k] = *(const LAS bf16x8*)(lds + PG8_SB(b, h) + boff + n * 2048 + k * 1024); } while (0)
; #define PG8_MMA(ai, bj, At, Bt) do { __builtin_amdgcn_s_setprio(1); _Pragma("unroll") for (int m = 0; m < 4; ++m) _Pragma("unroll") for (int n = 0; n < 2; ++n) _Pragma("unroll") for (int k = 0; k < 2; ++k) \
;         acc[ai][bj][m][n] = __builtin_amdgcn_mfma_f32_16x16x32_bf16(Bt[n][k], At[m][k], acc[ai][bj][m][n], 0, 0, 0); __builtin_amdgcn_s_setprio(0); } while (0)
; #define PG8_WAIT_V(n) asm volatile("s_waitcnt vmcnt(" #n ")" ::: "memory")
; #define PG8_WAIT_L(n) asm volatile("s_waitcnt lgkmcnt(" #n ")" ::: "memory")
; #define PG8_BAR __builtin_amdgcn_s_barrier()
; #define PG8_SCHED __builtin_amdgcn_sched_barrier(0)
; template <class Epi, class Sched>
; __device__ __forceinline__ void gemm_phase(LAS unsigned char* lds, const Gemm g, const Sched& S, const Epi& E) {
;     ...
;             PG8_BAR; PG8_WAIT_L(0); PG8_MMA(1, 0, At, B0); PG8_BAR; PG8_SCHED;
;             PG8_STAGE(PG8_SB(0, 1), b2 + hstep, voffB);
;             PG8_WAIT_V(6); PG8_BAR; PG8_MMA(1, 1, At, B1); PG8_BAR;
;             PG8_LDB(B0, 1, 0); PG8_SCHED; PG8_LDA(At, 1, 0); PG8_STAGE(PG8_SA(0, 1), a2 + hstep, voffA);
;             PG8_WAIT_L(8); PG8_BAR; PG8_WAIT_L(0); PG8_MMA(0, 0, At, B0); PG8_BAR; PG8_SCHED;
;             PG8_LDB(B1, 1, 1); PG8_STAGE(PG8_SB(1, 0), b3, voffB);
;             PG8_BAR; PG8_WAIT_L(0); PG8_MMA(0, 1, At, B1); PG8_BAR;
;             PG8_LDA(At, 1, 1); PG8_STAGE(PG8_SA(1, 0), a3, voffA);
;             PG8_BAR; PG8_WAIT_L(0); PG8_MMA(1, 0, At, B0); PG8_BAR; PG8_SCHED;
	s_setprio 0
	s_add_u32 s52, s20, 0x40000
	s_addc_u32 s53, s21, 0
	s_add_i32 s54, s44, s28
	s_mov_b32 m0, s54
	s_nop 0
	global_load_lds_dwordx4 v130, s[52:53]
	s_add_i32 m0, s54, 0x2000
	s_nop 0
	global_load_lds_dwordx4 v134, s[52:53]
	s_add_u32 s22, s22, 0x40000
	s_addc_u32 s23, s23, 0
	s_mov_b32 m0, s30
	s_nop 0
	global_load_lds_dwordx4 v128, s[22:23]
	s_mov_b32 m0, s31
	s_nop 0
	global_load_lds_dwordx4 v132, s[22:23]
	s_waitcnt vmcnt(10)
	s_setprio 1
	s_barrier
	v_mfma_f32_16x16x32_bf16 v[52:55], v[202:205], v[168:171], 0
	v_mfma_f32_16x16x32_bf16 v[44:47], v[210:213], v[168:171], 0
	v_mfma_f32_16x16x32_bf16 v[36:39], v[202:205], v[176:179], 0
	v_mfma_f32_16x16x32_bf16 v[28:31], v[210:213], v[176:179], 0
	v_mfma_f32_16x16x32_bf16 v[20:23], v[202:205], v[184:187], 0
	v_mfma_f32_16x16x32_bf16 v[12:15], v[210:213], v[184:187], 0
	v_mfma_f32_16x16x32_bf16 v[4:7], v[202:205], v[192:195], 0
	v_mfma_f32_16x16x32_bf16 v[0:3], v[210:213], v[192:195], 0
	v_mfma_f32_16x16x32_bf16 v[52:55], v[206:209], v[172:175], v[52:55]
	v_mfma_f32_16x16x32_bf16 v[44:47], v[214:217], v[172:175], v[44:47]
	v_mfma_f32_16x16x32_bf16 v[36:39], v[206:209], v[180:183], v[36:39]
	v_mfma_f32_16x16x32_bf16 v[28:31], v[214:217], v[180:183], v[28:31]
	v_mfma_f32_16x16x32_bf16 v[20:23], v[206:209], v[188:191], v[20:23]
	v_mfma_f32_16x16x32_bf16 v[12:15], v[214:217], v[188:191], v[12:15]
	v_mfma_f32_16x16x32_bf16 v[4:7], v[206:209], v[196:199], v[4:7]
	v_mfma_f32_16x16x32_bf16 v[0:3], v[214:217], v[196:199], v[0:3]
	s_barrier
	s_setprio 0
	s_add_i32 s52, 0, 0x18000
	ds_read_b128 v[152:155], v151 offset:16384
	ds_read_b128 v[156:159], v151 offset:17408
	ds_read_b128 v[160:163], v151 offset:18432
	ds_read_b128 v[164:167], v151 offset:19456
	ds_read_b128 v[168:171], v150 offset:32768
	ds_read_b128 v[172:175], v150 offset:33792
	ds_read_b128 v[176:179], v150 offset:34816
	ds_read_b128 v[180:183], v150 offset:35840
	ds_read_b128 v[184:187], v150 offset:36864
	ds_read_b128 v[188:191], v150 offset:37888
	ds_read_b128 v[192:195], v150 offset:38912
	ds_read_b128 v[196:199], v150 offset:39936
	s_waitcnt lgkmcnt(8)
	s_waitcnt vmcnt(8)
	s_setprio 1
	s_barrier
	s_waitcnt lgkmcnt(0)
	v_mfma_f32_16x16x32_bf16 v[124:127], v[152:155], v[168:171], v[124:127]
	v_mfma_f32_16x16x32_bf16 v[120:123], v[160:163], v[168:171], v[120:123]
	v_mfma_f32_16x16x32_bf16 v[112:115], v[152:155], v[176:179], v[112:115]
	v_mfma_f32_16x16x32_bf16 v[104:107], v[160:163], v[176:179], v[104:107]
	v_mfma_f32_16x16x32_bf16 v[96:99], v[152:155], v[184:187], v[96:99]
	v_mfma_f32_16x16x32_bf16 v[88:91], v[160:163], v[184:187], v[88:91]
	v_mfma_f32_16x16x32_bf16 v[80:83], v[152:155], v[192:195], v[80:83]
	v_mfma_f32_16x16x32_bf16 v[72:75], v[160:163], v[192:195], v[72:75]
	v_mfma_f32_16x16x32_bf16 v[124:127], v[156:159], v[172:175], v[124:127]
	v_mfma_f32_16x16x32_bf16 v[120:123], v[164:167], v[172:175], v[120:123]
	v_mfma_f32_16x16x32_bf16 v[112:115], v[156:159], v[180:183], v[112:115]
	v_mfma_f32_16x16x32_bf16 v[104:107], v[164:167], v[180:183], v[104:107]
	v_mfma_f32_16x16x32_bf16 v[96:99], v[156:159], v[188:191], v[96:99]
	v_mfma_f32_16x16x32_bf16 v[88:91], v[164:167], v[188:191], v[88:91]
	v_mfma_f32_16x16x32_bf16 v[80:83], v[156:159], v[196:199], v[80:83]
	v_mfma_f32_16x16x32_bf16 v[72:75], v[164:167], v[196:199], v[72:75]
	s_barrier
	s_setprio 0
	s_add_i32 s22, 0, 0x1c000
	s_add_i32 s23, s52, s28
	s_add_u32 s0, s20, 0x80
	s_addc_u32 s1, s21, 0
	s_mov_b32 m0, s23
	ds_read_b128 v[202:205], v151 offset:32768
	ds_read_b128 v[206:209], v151 offset:33792
	ds_read_b128 v[210:213], v151 offset:34816
	ds_read_b128 v[214:217], v151 offset:35840
	global_load_lds_dwordx4 v130, s[0:1]
	s_add_i32 m0, s23, 0x2000
	s_nop 0
	global_load_lds_dwordx4 v134, s[0:1]
	s_waitcnt vmcnt(8)
	s_setprio 1
	s_barrier
	s_waitcnt lgkmcnt(0)
	v_mfma_f32_16x16x32_bf16 v[116:119], v[202:205], v[168:171], v[116:119]
	v_mfma_f32_16x16x32_bf16 v[108:111], v[210:213], v[168:171], v[108:111]
	v_mfma_f32_16x16x32_bf16 v[100:103], v[202:205], v[176:179], v[100:103]
	v_mfma_f32_16x16x32_bf16 v[92:95], v[210:213], v[176:179], v[92:95]
	v_mfma_f32_16x16x32_bf16 v[84:87], v[202:205], v[184:187], v[84:87]
	v_mfma_f32_16x16x32_bf16 v[76:79], v[210:213], v[184:187], v[76:79]
	v_mfma_f32_16x16x32_bf16 v[68:71], v[202:205], v[192:195], v[68:71]
	v_mfma_f32_16x16x32_bf16 v[64:67], v[210:213], v[192:195], v[64:67]
	v_mfma_f32_16x16x32_bf16 v[116:119], v[206:209], v[172:175], v[116:119]
	v_mfma_f32_16x16x32_bf16 v[108:111], v[214:217], v[172:175], v[108:111]
	v_mfma_f32_16x16x32_bf16 v[100:103], v[206:209], v[180:183], v[100:103]
	v_mfma_f32_16x16x32_bf16 v[92:95], v[214:217], v[180:183], v[92:95]
	v_mfma_f32_16x16x32_bf16 v[84:87], v[206:209], v[188:191], v[84:87]
	v_mfma_f32_16x16x32_bf16 v[76:79], v[214:217], v[188:191], v[76:79]
	v_mfma_f32_16x16x32_bf16 v[68:71], v[206:209], v[196:199], v[68:71]
	v_mfma_f32_16x16x32_bf16 v[64:67], v[214:217], v[196:199], v[64:67]
	s_barrier
	s_setprio 0
	s_mov_b32 m0, s36
	s_mov_b64 s[0:1], 0x80
	v_lshl_add_u64 v[218:219], v[222:223], 0, s[0:1]
	ds_read_b128 v[168:171], v150 offset:49152
	ds_read_b128 v[172:175], v150 offset:50176
	ds_read_b128 v[176:179], v150 offset:51200
	ds_read_b128 v[180:183], v150 offset:52224
	ds_read_b128 v[184:187], v150 offset:53248
	ds_read_b128 v[188:191], v150 offset:54272
	ds_read_b128 v[192:195], v150 offset:55296
	ds_read_b128 v[196:199], v150 offset:56320
	global_load_lds_dwordx4 v[218:219], off
	v_lshl_add_u64 v[218:219], v[224:225], 0, s[0:1]
	s_mov_b32 m0, s37
	s_nop 0
	global_load_lds_dwordx4 v[218:219], off
	s_setprio 1
	s_barrier
; #define PG8_STAGE(bufoff, gbase, voff) do { _Pragma("unroll") for (int _i = 0; _i < 2; ++_i) \
;         __builtin_amdgcn_global_load_lds((const unsigned*)((const char*)(gbase) + (voff)[_i]), (LAS unsigned*)(lds + (bufoff) + ldsw + _i * 8192), 16, 0, 0); } while (0)
; #define PG8_LDA(dst, b, h) do { _Pragma("unroll") for (int m = 0; m < 4; ++m) _Pragma("unroll") for (int k = 0; k < 2; ++k) dst[m][k] = *(const LAS bf16x8*)(lds + PG8_SA(b, h) + aoff + m * 2048 + k * 1024); } while (0)
; #define PG8_LDB(dst, b, h) do { _Pragma("unroll") for (int n = 0; n < 2; ++n) _Pragma("unroll") for (int k = 0; k < 2; ++k) dst[n][k] = *(const LAS bf16x8*)(lds + PG8_SB(b, h) + boff + n * 2048 + k * 1024); } while (0)
; #define PG8_WAIT_V(n) asm volatile("s_waitcnt vmcnt(" #n ")" ::: "memory")
; #define PG8_WAIT_L(n) asm volatile("s_waitcnt lgkmcnt(" #n ")" ::: "memory")
; #define PG8_BAR __builtin_amdgcn_s_barrier()
; #define PG8_SCHED __builtin_amdgcn_sched_barrier(0)
; template <class Epi, class Sched>
; __device__ __forceinline__ void gemm_phase(LAS unsigned char* lds, const Gemm g, const Sched& S, const Epi& E) {
;     ...
;             PG8_LDB(B0, 0, 0); PG8_SCHED; PG8_LDA(At, 0, 0); PG8_STAGE(PG8_SA(1, 1), a1 + hstep, voffA);
;             PG8_WAIT_L(8); PG8_BAR; PG8_WAIT_L(0); PG8_MMA(0, 0, At, B0); PG8_BAR; PG8_SCHED;
;             PG8_LDB(B1, 0, 1); PG8_STAGE(PG8_SB(0, 0), b2, voffB);
;             PG8_BAR; PG8_WAIT_L(0); PG8_MMA(0, 1, At, B1); PG8_BAR;
;             PG8_LDA(At, 0, 1); PG8_STAGE(PG8_SA(0, 0), a2, voffA);
;             PG8_BAR; PG8_WAIT_L(0); PG8_MMA(1, 0, At, B0); PG8_BAR; PG8_SCHED;
;             PG8_STAGE(PG8_SB(0, 1), b2 + hstep, voffB);
;             PG8_WAIT_V(6); PG8_BAR; PG8_MMA(1, 1, At, B1); PG8_BAR;
;             PG8_LDB(B0, 1, 0); PG8_SCHED; PG8_LDA(At, 1, 0); PG8_STAGE(PG8_SA(0, 1), a2 + hstep, voffA);
;             PG8_WAIT_L(8); PG8_BAR; PG8_WAIT_L(0); PG8_MMA(0, 0, At, B0); PG8_BAR; PG8_SCHED;
;             PG8_LDB(B1, 1, 1); PG8_STAGE(PG8_SB(1, 0), b3, voffB);
;             PG8_BAR; PG8_WAIT_L(0); PG8_MMA(0, 1, At, B1); PG8_BAR;
;             PG8_LDA(At, 1, 1); PG8_STAGE(PG8_SA(1, 0), a3, voffA);
;             PG8_BAR; PG8_WAIT_L(0); PG8_MMA(1, 0, At, B0); PG8_BAR; PG8_SCHED;
;             PG8_STAGE(PG8_SB(1, 1), b3 + hstep, voffB);
;             PG8_WAIT_V(6); PG8_BAR; PG8_MMA(1, 1, At, B1); PG8_BAR;
	s_waitcnt lgkmcnt(0)
	v_mfma_f32_16x16x32_bf16 v[60:63], v[152:155], v[168:171], v[60:63]
	v_mfma_f32_16x16x32_bf16 v[56:59], v[160:163], v[168:171], v[56:59]
	v_mfma_f32_16x16x32_bf16 v[48:51], v[152:155], v[176:179], v[48:51]
	v_mfma_f32_16x16x32_bf16 v[40:43], v[160:163], v[176:179], v[40:43]
	v_mfma_f32_16x16x32_bf16 v[32:35], v[152:155], v[184:187], v[32:35]
	v_mfma_f32_16x16x32_bf16 v[24:27], v[160:163], v[184:187], v[24:27]
	v_mfma_f32_16x16x32_bf16 v[16:19], v[152:155], v[192:195], v[16:19]
	v_mfma_f32_16x16x32_bf16 v[8:11], v[160:163], v[192:195], v[8:11]
	v_mfma_f32_16x16x32_bf16 v[60:63], v[156:159], v[172:175], v[60:63]
	v_mfma_f32_16x16x32_bf16 v[56:59], v[164:167], v[172:175], v[56:59]
	v_mfma_f32_16x16x32_bf16 v[48:51], v[156:159], v[180:183], v[48:51]
	v_mfma_f32_16x16x32_bf16 v[40:43], v[164:167], v[180:183], v[40:43]
	v_mfma_f32_16x16x32_bf16 v[32:35], v[156:159], v[188:191], v[32:35]
	v_mfma_f32_16x16x32_bf16 v[24:27], v[164:167], v[188:191], v[24:27]
	v_mfma_f32_16x16x32_bf16 v[16:19], v[156:159], v[196:199], v[16:19]
	v_mfma_f32_16x16x32_bf16 v[8:11], v[164:167], v[196:199], v[8:11]
	s_barrier
	s_setprio 0
	s_add_u32 s20, s20, 0x40080
	s_addc_u32 s21, s21, 0
	s_add_i32 s22, s22, s28
	s_mov_b32 m0, s22
	s_nop 0
	global_load_lds_dwordx4 v130, s[20:21]
	s_add_i32 m0, s22, 0x2000
	s_nop 0
	global_load_lds_dwordx4 v134, s[20:21]
	s_waitcnt vmcnt(8)
	s_setprio 1
	s_barrier
	v_mfma_f32_16x16x32_bf16 v[52:55], v[202:205], v[168:171], v[52:55]
	v_mfma_f32_16x16x32_bf16 v[44:47], v[210:213], v[168:171], v[44:47]
	v_mfma_f32_16x16x32_bf16 v[36:39], v[202:205], v[176:179], v[36:39]
	v_mfma_f32_16x16x32_bf16 v[28:31], v[210:213], v[176:179], v[28:31]
	v_mfma_f32_16x16x32_bf16 v[20:23], v[202:205], v[184:187], v[20:23]
	v_mfma_f32_16x16x32_bf16 v[12:15], v[210:213], v[184:187], v[12:15]
	v_mfma_f32_16x16x32_bf16 v[4:7], v[202:205], v[192:195], v[4:7]
	v_mfma_f32_16x16x32_bf16 v[0:3], v[210:213], v[192:195], v[0:3]
	v_mfma_f32_16x16x32_bf16 v[52:55], v[206:209], v[172:175], v[52:55]
	v_mfma_f32_16x16x32_bf16 v[44:47], v[214:217], v[172:175], v[44:47]
	v_mfma_f32_16x16x32_bf16 v[36:39], v[206:209], v[180:183], v[36:39]
	v_mfma_f32_16x16x32_bf16 v[28:31], v[214:217], v[180:183], v[28:31]
	v_mfma_f32_16x16x32_bf16 v[20:23], v[206:209], v[188:191], v[20:23]
	v_mfma_f32_16x16x32_bf16 v[12:15], v[214:217], v[188:191], v[12:15]
	v_mfma_f32_16x16x32_bf16 v[4:7], v[206:209], v[196:199], v[4:7]
	v_mfma_f32_16x16x32_bf16 v[0:3], v[214:217], v[196:199], v[0:3]
	s_barrier
	s_setprio 0
	s_add_i32 s51, s51, 2
	s_add_u32 s18, s18, 0x100
	s_addc_u32 s19, s19, 0
	s_add_u32 s48, s48, 0x100
	s_addc_u32 s49, s49, 0
	s_cmp_gt_u32 s51, 13
.LBB0_673:
	ds_read_b128 v[152:155], v149
	ds_read_b128 v[156:159], v149 offset:1024
	ds_read_b128 v[160:163], v149 offset:2048
	ds_read_b128 v[164:167], v149 offset:3072
	s_add_u32 s20, s18, 0xfffc0080
	s_addc_u32 s21, s19, -1
	s_cmp_eq_u32 s51, 12
	s_cselect_b32 s23, s9, s21
	s_cselect_b32 s22, s46, s20
	s_cselect_b32 s21, s7, s49
	s_cselect_b32 s20, s47, s48
	s_add_i32 m0, s17, 0xc000
	ds_read_b128 v[168:171], v150
	ds_read_b128 v[172:175], v150 offset:1024
	ds_read_b128 v[176:179], v150 offset:2048
	ds_read_b128 v[180:183], v150 offset:3072
	ds_read_b128 v[184:187], v150 offset:4096
	ds_read_b128 v[188:191], v150 offset:5120
	ds_read_b128 v[192:195], v150 offset:6144
	ds_read_b128 v[196:199], v150 offset:7168
	global_load_lds_dwordx4 v138, s[18:19]
	s_add_i32 m0, s17, 0xe000
	s_nop 0
	global_load_lds_dwordx4 v140, s[18:19]
	s_waitcnt lgkmcnt(8)
	s_waitcnt vmcnt(8)
	s_setprio 1
	s_barrier
	s_waitcnt lgkmcnt(0)
	v_mfma_f32_16x16x32_bf16 v[124:127], v[152:155], v[168:171], v[124:127]
	v_mfma_f32_16x16x32_bf16 v[120:123], v[160:163], v[168:171], v[120:123]
	v_mfma_f32_16x16x32_bf16 v[112:115], v[152:155], v[176:179], v[112:115]
	v_mfma_f32_16x16x32_bf16 v[104:107], v[160:163], v[176:179], v[104:107]
	v_mfma_f32_16x16x32_bf16 v[96:99], v[152:155], v[184:187], v[96:99]
	v_mfma_f32_16x16x32_bf16 v[88:91], v[160:163], v[184:187], v[88:91]
	v_mfma_f32_16x16x32_bf16 v[80:83], v[152:155], v[192:195], v[80:83]
	v_mfma_f32_16x16x32_bf16 v[72:75], v[160:163], v[192:195], v[72:75]
	v_mfma_f32_16x16x32_bf16 v[124:127], v[156:159], v[172:175], v[124:127]
	v_mfma_f32_16x16x32_bf16 v[120:123], v[164:167], v[172:175], v[120:123]
	v_mfma_f32_16x16x32_bf16 v[112:115], v[156:159], v[180:183], v[112:115]
	v_mfma_f32_16x16x32_bf16 v[104:107], v[164:167], v[180:183], v[104:107]
	v_mfma_f32_16x16x32_bf16 v[96:99], v[156:159], v[188:191], v[96:99]
	v_mfma_f32_16x16x32_bf16 v[88:91], v[164:167], v[188:191], v[88:91]
	v_mfma_f32_16x16x32_bf16 v[80:83], v[156:159], v[196:199], v[80:83]
	v_mfma_f32_16x16x32_bf16 v[72:75], v[164:167], v[196:199], v[72:75]
	s_barrier
	s_setprio 0
	s_add_i32 s52, s43, s28
	s_mov_b32 m0, s52
	ds_read_b128 v[202:205], v151
	ds_read_b128 v[206:209], v151 offset:1024
	ds_read_b128 v[210:213], v151 offset:2048
	ds_read_b128 v[214:217], v151 offset:3072
	global_load_lds_dwordx4 v130, s[20:21]
	s_add_i32 m0, s52, 0x2000
	s_nop 0
	global_load_lds_dwordx4 v134, s[20:21]
	s_waitcnt vmcnt(8)
	s_setprio 1
	s_barrier
; #define PG8_STAGE(bufoff, gbase, voff) do { _Pragma("unroll") for (int _i = 0; _i < 2; ++_i) \
;         __builtin_amdgcn_global_load_lds((const unsigned*)((const char*)(gbase) + (voff)[_i]), (LAS unsigned*)(lds + (bufoff) + ldsw + _i * 8192), 16, 0, 0); } while (0)
; #define PG8_LDA(dst, b, h) do { _Pragma("unroll") for (int m = 0; m < 4; ++m) _Pragma("unroll") for (int k = 0; k < 2; ++k) dst[m][k] = *(const LAS bf16x8*)(lds + PG8_SA(b, h) + aoff + m * 2048 + k * 1024); } while (0)
; #define PG8_LDB(dst, b, h) do { _Pragma("unroll") for (int n = 0; n < 2; ++n) _Pragma("unroll") for (int k = 0; k < 2; ++k) dst[n][k] = *(const LAS bf16x8*)(lds + PG8_SB(b, h) + boff + n * 2048 + k * 1024); } while (0)
; #define PG8_MMA(ai, bj, At, Bt) do { __builtin_amdgcn_s_setprio(1); _Pragma("unroll") for (int m = 0; m < 4; ++m) _Pragma("unroll") for (int n = 0; n < 2; ++n) _Pragma("unroll") for (int k = 0; k < 2; ++k) \
;         acc[ai][bj][m][n] = __builtin_amdgcn_mfma_f32_16x16x32_bf16(Bt[n][k], At[m][k], acc[ai][bj][m][n], 0, 0, 0); __builtin_amdgcn_s_setprio(0); } while (0)
; #define PG8_WAIT_V(n) asm volatile("s_waitcnt vmcnt(" #n ")" ::: "memory")
; #define PG8_WAIT_L(n) asm volatile("s_waitcnt lgkmcnt(" #n ")" ::: "memory")
; #define PG8_BAR __builtin_amdgcn_s_barrier()
; #define PG8_SCHED __builtin_amdgcn_sched_barrier(0)
; template <class Epi, class Sched>
; __device__ __forceinline__ void gemm_phase(LAS unsigned char* lds, const Gemm g, const Sched& S, const Epi& E) {
;     ...
;             PG8_BAR; PG8_WAIT_L(0); PG8_MMA(0, 1, At, B1); PG8_BAR;
;             PG8_LDA(At, 0, 1); PG8_STAGE(PG8_SA(0, 0), a2, voffA);
;             PG8_BAR; PG8_WAIT_L(0); PG8_MMA(1, 0, At, B0); PG8_BAR; PG8_SCHED;
;             PG8_STAGE(PG8_SB(0, 1), b2 + hstep, voffB);
;             PG8_WAIT_V(6); PG8_BAR; PG8_MMA(1, 1, At, B1); PG8_BAR;
;             PG8_LDB(B0, 1, 0); PG8_SCHED; PG8_LDA(At, 1, 0); PG8_STAGE(PG8_SA(0, 1), a2 + hstep, voffA);
	s_waitcnt lgkmcnt(0)
	v_mfma_f32_16x16x32_bf16 v[116:119], v[202:205], v[168:171], v[116:119]
	v_mfma_f32_16x16x32_bf16 v[108:111], v[210:213], v[168:171], v[108:111]
	v_mfma_f32_16x16x32_bf16 v[100:103], v[202:205], v[176:179], v[100:103]
	v_mfma_f32_16x16x32_bf16 v[92:95], v[210:213], v[176:179], v[92:95]
	v_mfma_f32_16x16x32_bf16 v[84:87], v[202:205], v[184:187], v[84:87]
	v_mfma_f32_16x16x32_bf16 v[76:79], v[210:213], v[184:187], v[76:79]
	v_mfma_f32_16x16x32_bf16 v[68:71], v[202:205], v[192:195], v[68:71]
	v_mfma_f32_16x16x32_bf16 v[64:67], v[210:213], v[192:195], v[64:67]
	v_mfma_f32_16x16x32_bf16 v[116:119], v[206:209], v[172:175], v[116:119]
	v_mfma_f32_16x16x32_bf16 v[108:111], v[214:217], v[172:175], v[108:111]
	v_mfma_f32_16x16x32_bf16 v[100:103], v[206:209], v[180:183], v[100:103]
	v_mfma_f32_16x16x32_bf16 v[92:95], v[214:217], v[180:183], v[92:95]
	v_mfma_f32_16x16x32_bf16 v[84:87], v[206:209], v[188:191], v[84:87]
	v_mfma_f32_16x16x32_bf16 v[76:79], v[214:217], v[188:191], v[76:79]
	v_mfma_f32_16x16x32_bf16 v[68:71], v[206:209], v[196:199], v[68:71]
	v_mfma_f32_16x16x32_bf16 v[64:67], v[214:217], v[196:199], v[64:67]
	s_barrier
	s_setprio 0
	s_mov_b32 m0, s17
	v_lshl_add_u64 v[222:223], s[22:23], 0, v[128:129]
	ds_read_b128 v[168:171], v150 offset:16384
	ds_read_b128 v[172:175], v150 offset:17408
	ds_read_b128 v[176:179], v150 offset:18432
	ds_read_b128 v[180:183], v150 offset:19456
	ds_read_b128 v[184:187], v150 offset:20480
	ds_read_b128 v[188:191], v150 offset:21504
	ds_read_b128 v[192:195], v150 offset:22528
	ds_read_b128 v[196:199], v150 offset:23552
	global_load_lds_dwordx4 v128, s[22:23]
	v_lshl_add_u64 v[224:225], s[22:23], 0, v[132:133]
	s_mov_b32 m0, s29
	s_nop 0
	global_load_lds_dwordx4 v132, s[22:23]
	s_setprio 1
	s_barrier
	s_waitcnt lgkmcnt(0)
	v_mfma_f32_16x16x32_bf16 v[60:63], v[152:155], v[168:171], v[60:63]
	v_mfma_f32_16x16x32_bf16 v[56:59], v[160:163], v[168:171], v[56:59]
	v_mfma_f32_16x16x32_bf16 v[48:51], v[152:155], v[176:179], v[48:51]
	v_mfma_f32_16x16x32_bf16 v[40:43], v[160:163], v[176:179], v[40:43]
	v_mfma_f32_16x16x32_bf16 v[32:35], v[152:155], v[184:187], v[32:35]
	v_mfma_f32_16x16x32_bf16 v[24:27], v[160:163], v[184:187], v[24:27]
	v_mfma_f32_16x16x32_bf16 v[16:19], v[152:155], v[192:195], v[16:19]
	v_mfma_f32_16x16x32_bf16 v[8:11], v[160:163], v[192:195], v[8:11]
	v_mfma_f32_16x16x32_bf16 v[60:63], v[156:159], v[172:175], v[60:63]
	v_mfma_f32_16x16x32_bf16 v[56:59], v[164:167], v[172:175], v[56:59]
	v_mfma_f32_16x16x32_bf16 v[48:51], v[156:159], v[180:183], v[48:51]
	v_mfma_f32_16x16x32_bf16 v[40:43], v[164:167], v[180:183], v[40:43]
	v_mfma_f32_16x16x32_bf16 v[32:35], v[156:159], v[188:191], v[32:35]
	v_mfma_f32_16x16x32_bf16 v[24:27], v[164:167], v[188:191], v[24:27]
	v_mfma_f32_16x16x32_bf16 v[16:19], v[156:159], v[196:199], v[16:19]
	v_mfma_f32_16x16x32_bf16 v[8:11], v[164:167], v[196:199], v[8:11]
	s_barrier
	s_setprio 0
	s_add_u32 s52, s20, 0x40000
	s_addc_u32 s53, s21, 0
	s_add_i32 s54, s44, s28
	s_mov_b32 m0, s54
	s_nop 0
	global_load_lds_dwordx4 v130, s[52:53]
	s_add_i32 m0, s54, 0x2000
	s_nop 0
	global_load_lds_dwordx4 v134, s[52:53]
	s_add_u32 s22, s22, 0x40000
	s_addc_u32 s23, s23, 0
	s_mov_b32 m0, s30
	s_nop 0
	global_load_lds_dwordx4 v128, s[22:23]
	s_mov_b32 m0, s31
	s_nop 0
	global_load_lds_dwordx4 v132, s[22:23]
	s_waitcnt vmcnt(10)
	s_setprio 1
	s_barrier
	v_mfma_f32_16x16x32_bf16 v[52:55], v[202:205], v[168:171], v[52:55]
	v_mfma_f32_16x16x32_bf16 v[44:47], v[210:213], v[168:171], v[44:47]
	v_mfma_f32_16x16x32_bf16 v[36:39], v[202:205], v[176:179], v[36:39]
	v_mfma_f32_16x16x32_bf16 v[28:31], v[210:213], v[176:179], v[28:31]
	v_mfma_f32_16x16x32_bf16 v[20:23], v[202:205], v[184:187], v[20:23]
	v_mfma_f32_16x16x32_bf16 v[12:15], v[210:213], v[184:187], v[12:15]
	v_mfma_f32_16x16x32_bf16 v[4:7], v[202:205], v[192:195], v[4:7]
	v_mfma_f32_16x16x32_bf16 v[0:3], v[210:213], v[192:195], v[0:3]
	v_mfma_f32_16x16x32_bf16 v[52:55], v[206:209], v[172:175], v[52:55]
	v_mfma_f32_16x16x32_bf16 v[44:47], v[214:217], v[172:175], v[44:47]
	v_mfma_f32_16x16x32_bf16 v[36:39], v[206:209], v[180:183], v[36:39]
	v_mfma_f32_16x16x32_bf16 v[28:31], v[214:217], v[180:183], v[28:31]
	v_mfma_f32_16x16x32_bf16 v[20:23], v[206:209], v[188:191], v[20:23]
	v_mfma_f32_16x16x32_bf16 v[12:15], v[214:217], v[188:191], v[12:15]
	v_mfma_f32_16x16x32_bf16 v[4:7], v[206:209], v[196:199], v[4:7]
	v_mfma_f32_16x16x32_bf16 v[0:3], v[214:217], v[196:199], v[0:3]
	s_barrier
	s_setprio 0
	s_add_i32 s52, 0, 0x18000
	ds_read_b128 v[152:155], v151 offset:16384
	ds_read_b128 v[156:159], v151 offset:17408
	ds_read_b128 v[160:163], v151 offset:18432
	ds_read_b128 v[164:167], v151 offset:19456
	ds_read_b128 v[168:171], v150 offset:32768
	ds_read_b128 v[172:175], v150 offset:33792
	ds_read_b128 v[176:179], v150 offset:34816
	ds_read_b128 v[180:183], v150 offset:35840
	ds_read_b128 v[184:187], v150 offset:36864
	ds_read_b128 v[188:191], v150 offset:37888
	ds_read_b128 v[192:195], v150 offset:38912
	ds_read_b128 v[196:199], v150 offset:39936
	s_waitcnt lgkmcnt(8)
	s_waitcnt vmcnt(8)
	s_setprio 1
	s_barrier
; #define PG8_STAGE(bufoff, gbase, voff) do { _Pragma("unroll") for (int _i = 0; _i < 2; ++_i) \
;         __builtin_amdgcn_global_load_lds((const unsigned*)((const char*)(gbase) + (voff)[_i]), (LAS unsigned*)(lds + (bufoff) + ldsw + _i * 8192), 16, 0, 0); } while (0)
; #define PG8_LDA(dst, b, h) do { _Pragma("unroll") for (int m = 0; m < 4; ++m) _Pragma("unroll") for (int k = 0; k < 2; ++k) dst[m][k] = *(const LAS bf16x8*)(lds + PG8_SA(b, h) + aoff + m * 2048 + k * 1024); } while (0)
; #define PG8_LDB(dst, b, h) do { _Pragma("unroll") for (int n = 0; n < 2; ++n) _Pragma("unroll") for (int k = 0; k < 2; ++k) dst[n][k] = *(const LAS bf16x8*)(lds + PG8_SB(b, h) + boff + n * 2048 + k * 1024); } while (0)
; #define PG8_MMA(ai, bj, At, Bt) do { __builtin_amdgcn_s_setprio(1); _Pragma("unroll") for (int m = 0; m < 4; ++m) _Pragma("unroll") for (int n = 0; n < 2; ++n) _Pragma("unroll") for (int k = 0; k < 2; ++k) \
;         acc[ai][bj][m][n] = __builtin_amdgcn_mfma_f32_16x16x32_bf16(Bt[n][k], At[m][k], acc[ai][bj][m][n], 0, 0, 0); __builtin_amdgcn_s_setprio(0); } while (0)
; #define PG8_WAIT_V(n) asm volatile("s_waitcnt vmcnt(" #n ")" ::: "memory")
; #define PG8_WAIT_L(n) asm volatile("s_waitcnt lgkmcnt(" #n ")" ::: "memory")
; #define PG8_BAR __builtin_amdgcn_s_barrier()
; #define PG8_SCHED __builtin_amdgcn_sched_barrier(0)
; template <class Epi, class Sched>
; __device__ __forceinline__ void gemm_phase(LAS unsigned char* lds, const Gemm g, const Sched& S, const Epi& E) {
;     ...
;             PG8_WAIT_L(8); PG8_BAR; PG8_WAIT_L(0); PG8_MMA(0, 0, At, B0); PG8_BAR; PG8_SCHED;
;             PG8_LDB(B1, 1, 1); PG8_STAGE(PG8_SB(1, 0), b3, voffB);
;             PG8_BAR; PG8_WAIT_L(0); PG8_MMA(0, 1, At, B1); PG8_BAR;
;             PG8_LDA(At, 1, 1); PG8_STAGE(PG8_SA(1, 0), a3, voffA);
;             PG8_BAR; PG8_WAIT_L(0); PG8_MMA(1, 0, At, B0); PG8_BAR; PG8_SCHED;
;             PG8_STAGE(PG8_SB(1, 1), b3 + hstep, voffB);
;             PG8_WAIT_V(6); PG8_BAR; PG8_MMA(1, 1, At, B1); PG8_BAR;
	s_waitcnt lgkmcnt(0)
	v_mfma_f32_16x16x32_bf16 v[124:127], v[152:155], v[168:171], v[124:127]
	v_mfma_f32_16x16x32_bf16 v[120:123], v[160:163], v[168:171], v[120:123]
	v_mfma_f32_16x16x32_bf16 v[112:115], v[152:155], v[176:179], v[112:115]
	v_mfma_f32_16x16x32_bf16 v[104:107], v[160:163], v[176:179], v[104:107]
	v_mfma_f32_16x16x32_bf16 v[96:99], v[152:155], v[184:187], v[96:99]
	v_mfma_f32_16x16x32_bf16 v[88:91], v[160:163], v[184:187], v[88:91]
	v_mfma_f32_16x16x32_bf16 v[80:83], v[152:155], v[192:195], v[80:83]
	v_mfma_f32_16x16x32_bf16 v[72:75], v[160:163], v[192:195], v[72:75]
	v_mfma_f32_16x16x32_bf16 v[124:127], v[156:159], v[172:175], v[124:127]
	v_mfma_f32_16x16x32_bf16 v[120:123], v[164:167], v[172:175], v[120:123]
	v_mfma_f32_16x16x32_bf16 v[112:115], v[156:159], v[180:183], v[112:115]
	v_mfma_f32_16x16x32_bf16 v[104:107], v[164:167], v[180:183], v[104:107]
	v_mfma_f32_16x16x32_bf16 v[96:99], v[156:159], v[188:191], v[96:99]
	v_mfma_f32_16x16x32_bf16 v[88:91], v[164:167], v[188:191], v[88:91]
	v_mfma_f32_16x16x32_bf16 v[80:83], v[156:159], v[196:199], v[80:83]
	v_mfma_f32_16x16x32_bf16 v[72:75], v[164:167], v[196:199], v[72:75]
	s_barrier
	s_setprio 0
	s_add_i32 s22, 0, 0x1c000
	s_add_i32 s23, s52, s28
	s_add_u32 s0, s20, 0x80
	s_addc_u32 s1, s21, 0
	s_mov_b32 m0, s23
	ds_read_b128 v[202:205], v151 offset:32768
	ds_read_b128 v[206:209], v151 offset:33792
	ds_read_b128 v[210:213], v151 offset:34816
	ds_read_b128 v[214:217], v151 offset:35840
	global_load_lds_dwordx4 v130, s[0:1]
	s_add_i32 m0, s23, 0x2000
	s_nop 0
	global_load_lds_dwordx4 v134, s[0:1]
	s_waitcnt vmcnt(8)
	s_setprio 1
	s_barrier
	s_waitcnt lgkmcnt(0)
	v_mfma_f32_16x16x32_bf16 v[116:119], v[202:205], v[168:171], v[116:119]
	v_mfma_f32_16x16x32_bf16 v[108:111], v[210:213], v[168:171], v[108:111]
	v_mfma_f32_16x16x32_bf16 v[100:103], v[202:205], v[176:179], v[100:103]
	v_mfma_f32_16x16x32_bf16 v[92:95], v[210:213], v[176:179], v[92:95]
	v_mfma_f32_16x16x32_bf16 v[84:87], v[202:205], v[184:187], v[84:87]
	v_mfma_f32_16x16x32_bf16 v[76:79], v[210:213], v[184:187], v[76:79]
	v_mfma_f32_16x16x32_bf16 v[68:71], v[202:205], v[192:195], v[68:71]
	v_mfma_f32_16x16x32_bf16 v[64:67], v[210:213], v[192:195], v[64:67]
	v_mfma_f32_16x16x32_bf16 v[116:119], v[206:209], v[172:175], v[116:119]
	v_mfma_f32_16x16x32_bf16 v[108:111], v[214:217], v[172:175], v[108:111]
	v_mfma_f32_16x16x32_bf16 v[100:103], v[206:209], v[180:183], v[100:103]
	v_mfma_f32_16x16x32_bf16 v[92:95], v[214:217], v[180:183], v[92:95]
	v_mfma_f32_16x16x32_bf16 v[84:87], v[206:209], v[188:191], v[84:87]
	v_mfma_f32_16x16x32_bf16 v[76:79], v[214:217], v[188:191], v[76:79]
	v_mfma_f32_16x16x32_bf16 v[68:71], v[206:209], v[196:199], v[68:71]
	v_mfma_f32_16x16x32_bf16 v[64:67], v[214:217], v[196:199], v[64:67]
	s_barrier
	s_setprio 0
	s_mov_b32 m0, s36
	s_mov_b64 s[0:1], 0x80
	v_lshl_add_u64 v[218:219], v[222:223], 0, s[0:1]
	ds_read_b128 v[168:171], v150 offset:49152
	ds_read_b128 v[172:175], v150 offset:50176
	ds_read_b128 v[176:179], v150 offset:51200
	ds_read_b128 v[180:183], v150 offset:52224
	ds_read_b128 v[184:187], v150 offset:53248
	ds_read_b128 v[188:191], v150 offset:54272
	ds_read_b128 v[192:195], v150 offset:55296
	ds_read_b128 v[196:199], v150 offset:56320
	global_load_lds_dwordx4 v[218:219], off
	v_lshl_add_u64 v[218:219], v[224:225], 0, s[0:1]
	s_mov_b32 m0, s37
	s_nop 0
	global_load_lds_dwordx4 v[218:219], off
	s_setprio 1
	s_barrier
	s_waitcnt lgkmcnt(0)
	v_mfma_f32_16x16x32_bf16 v[60:63], v[152:155], v[168:171], v[60:63]
	v_mfma_f32_16x16x32_bf16 v[56:59], v[160:163], v[168:171], v[56:59]
	v_mfma_f32_16x16x32_bf16 v[48:51], v[152:155], v[176:179], v[48:51]
	v_mfma_f32_16x16x32_bf16 v[40:43], v[160:163], v[176:179], v[40:43]
	v_mfma_f32_16x16x32_bf16 v[32:35], v[152:155], v[184:187], v[32:35]
	v_mfma_f32_16x16x32_bf16 v[24:27], v[160:163], v[184:187], v[24:27]
	v_mfma_f32_16x16x32_bf16 v[16:19], v[152:155], v[192:195], v[16:19]
	v_mfma_f32_16x16x32_bf16 v[8:11], v[160:163], v[192:195], v[8:11]
	v_mfma_f32_16x16x32_bf16 v[60:63], v[156:159], v[172:175], v[60:63]
	v_mfma_f32_16x16x32_bf16 v[56:59], v[164:167], v[172:175], v[56:59]
	v_mfma_f32_16x16x32_bf16 v[48:51], v[156:159], v[180:183], v[48:51]
	v_mfma_f32_16x16x32_bf16 v[40:43], v[164:167], v[180:183], v[40:43]
	v_mfma_f32_16x16x32_bf16 v[32:35], v[156:159], v[188:191], v[32:35]
	v_mfma_f32_16x16x32_bf16 v[24:27], v[164:167], v[188:191], v[24:27]
	v_mfma_f32_16x16x32_bf16 v[16:19], v[156:159], v[196:199], v[16:19]
	v_mfma_f32_16x16x32_bf16 v[8:11], v[164:167], v[196:199], v[8:11]
	s_barrier
	s_setprio 0
	s_add_u32 s20, s20, 0x40080
	s_addc_u32 s21, s21, 0
	s_add_i32 s22, s22, s28
	s_mov_b32 m0, s22
	s_nop 0
	global_load_lds_dwordx4 v130, s[20:21]
	s_add_i32 m0, s22, 0x2000
	s_nop 0
	global_load_lds_dwordx4 v134, s[20:21]
	s_waitcnt vmcnt(8)
	s_setprio 1
	s_barrier
	v_mfma_f32_16x16x32_bf16 v[52:55], v[202:205], v[168:171], v[52:55]
	v_mfma_f32_16x16x32_bf16 v[44:47], v[210:213], v[168:171], v[44:47]
	v_mfma_f32_16x16x32_bf16 v[36:39], v[202:205], v[176:179], v[36:39]
	v_mfma_f32_16x16x32_bf16 v[28:31], v[210:213], v[176:179], v[28:31]
	v_mfma_f32_16x16x32_bf16 v[20:23], v[202:205], v[184:187], v[20:23]
	v_mfma_f32_16x16x32_bf16 v[12:15], v[210:213], v[184:187], v[12:15]
	v_mfma_f32_16x16x32_bf16 v[4:7], v[202:205], v[192:195], v[4:7]
	v_mfma_f32_16x16x32_bf16 v[0:3], v[210:213], v[192:195], v[0:3]
	v_mfma_f32_16x16x32_bf16 v[52:55], v[206:209], v[172:175], v[52:55]
	v_mfma_f32_16x16x32_bf16 v[44:47], v[214:217], v[172:175], v[44:47]
	v_mfma_f32_16x16x32_bf16 v[36:39], v[206:209], v[180:183], v[36:39]
	v_mfma_f32_16x16x32_bf16 v[28:31], v[214:217], v[180:183], v[28:31]
	v_mfma_f32_16x16x32_bf16 v[20:23], v[206:209], v[188:191], v[20:23]
	v_mfma_f32_16x16x32_bf16 v[12:15], v[214:217], v[188:191], v[12:15]
	v_mfma_f32_16x16x32_bf16 v[4:7], v[206:209], v[196:199], v[4:7]
	v_mfma_f32_16x16x32_bf16 v[0:3], v[214:217], v[196:199], v[0:3]
	s_barrier
; __device__ __forceinline__ unsigned cvt_pk_bf16(float lo, float hi) { unsigned r; asm volatile("v_cvt_pk_bf16_f32 %0, %1, %2" : "=v"(r) : "v"(lo), "v"(hi)); return r; }
;     __device__ __forceinline__ void operator()(const AccT& acc, const Unit& u, int wr, int wc, int fr, int fq) const {
;         asm volatile("" : "+v"(fr), "+v"(fq));
;         const int rbase = u.pm * 256 + wr * 64 + fr;
;         const int tb = u.pn * 256 + wc * 32 + 8 * fq;
; #pragma unroll
;         for (int ai = 0; ai < 2; ++ai)
; #pragma unroll
;             for (int m = 0; m < 4; ++m) {
;                 const int gm = rbase + ai * 128 + m * 16;
; #pragma unroll
;                 for (int bj = 0; bj < 2; ++bj) {
;                     const int t0 = tb + bj * 128;
;                     const f32x4 v0 = acc[ai][bj][m][0], v1 = acc[ai][bj][m][1];
;                     u32x4 w; w.x = cvt_pk_bf16(v0[0], v0[1]); w.y = cvt_pk_bf16(v0[2], v0[3]); w.z = cvt_pk_bf16(v1[0], v1[1]); w.w = cvt_pk_bf16(v1[2], v1[3]);
;                     *(u32x4*)(YT + ((size_t)((t0 >> 10) * 512 + gm)) * 2048 + part * 1024 + (t0 & 1023)) = w;
;                 }
;             }
	s_setprio 0
	s_add_i32 s51, s51, 2
	s_add_u32 s18, s18, 0x100
	s_addc_u32 s19, s19, 0
	s_add_u32 s48, s48, 0x100
	s_addc_u32 s49, s49, 0
	s_cmp_gt_u32 s51, 13
	s_cbranch_scc0 .LBB0_673
	v_mov_b32_e32 v136, v147
	v_mov_b32_e32 v152, v146
	s_lshl_b32 s7, s16, 8
	s_add_i32 s7, s7, s34
	v_add_u32_e32 v152, s7, v152
	s_lshl_b32 s7, s45, 8
	s_or_b32 s7, s7, s35
	v_lshl_add_u32 v153, v136, 3, s7
	v_cvt_pk_bf16_f32 v124, v124, v125
	v_cvt_pk_bf16_f32 v125, v126, v127
	v_cvt_pk_bf16_f32 v126, v120, v121
	v_ashrrev_i32_e32 v120, 1, v153
	v_cvt_pk_bf16_f32 v127, v122, v123
	v_and_b32_e32 v122, 0xfffffe00, v120
	v_add_u32_e32 v120, v122, v152
	v_ashrrev_i32_e32 v121, 31, v120
	v_lshlrev_b64 v[120:121], 12, v[120:121]
	v_and_b32_e32 v123, 0x3f8, v153
	v_lshl_add_u64 v[120:121], s[4:5], 0, v[120:121]
	v_lshlrev_b32_e32 v136, 1, v123
	v_lshl_add_u64 v[120:121], v[120:121], 0, v[136:137]
	global_store_dwordx4 v[120:121], v[124:127], off
	v_add_u32_e32 v120, 0x80, v153
	v_cvt_pk_bf16_f32 v116, v116, v117
	v_cvt_pk_bf16_f32 v117, v118, v119
	v_cvt_pk_bf16_f32 v118, v108, v109
	v_ashrrev_i32_e32 v108, 1, v120
	v_and_b32_e32 v121, 0xfffffe00, v108
	v_add_u32_e32 v108, v121, v152
	v_ashrrev_i32_e32 v109, 31, v108
	v_lshlrev_b64 v[108:109], 12, v[108:109]
	v_cvt_pk_bf16_f32 v119, v110, v111
	v_lshl_add_u64 v[110:111], s[4:5], 0, v[108:109]
	v_and_b32_e32 v108, 0x3f8, v120
	v_lshlrev_b32_e32 v108, 1, v108
	v_mov_b32_e32 v109, v137
	v_lshl_add_u64 v[110:111], v[110:111], 0, v[108:109]
	global_store_dwordx4 v[110:111], v[116:119], off
	v_cvt_pk_bf16_f32 v110, v112, v113
	v_cvt_pk_bf16_f32 v111, v114, v115
	v_cvt_pk_bf16_f32 v112, v104, v105
	v_cvt_pk_bf16_f32 v113, v106, v107
	s_and_b64 vcc, exec, s[2:3]
	s_nop 0
	v_add_u32_e32 v116, 16, v152
	v_add_u32_e32 v104, v122, v116
	v_ashrrev_i32_e32 v105, 31, v104
	v_lshlrev_b64 v[104:105], 12, v[104:105]
	v_lshl_add_u64 v[104:105], s[4:5], 0, v[104:105]
	v_lshl_add_u64 v[104:105], v[104:105], 0, v[136:137]
	global_store_dwordx4 v[104:105], v[110:113], off
	v_cvt_pk_bf16_f32 v100, v100, v101
	v_cvt_pk_bf16_f32 v101, v102, v103
	v_cvt_pk_bf16_f32 v102, v92, v93
	v_add_u32_e32 v92, v121, v116
	v_ashrrev_i32_e32 v93, 31, v92
	v_lshlrev_b64 v[92:93], 12, v[92:93]
	v_lshl_add_u64 v[92:93], s[4:5], 0, v[92:93]
	v_lshl_add_u64 v[92:93], v[92:93], 0, v[108:109]
	v_cvt_pk_bf16_f32 v103, v94, v95
	global_store_dwordx4 v[92:93], v[100:103], off
	v_cvt_pk_bf16_f32 v92, v96, v97
	v_cvt_pk_bf16_f32 v93, v98, v99
	v_cvt_pk_bf16_f32 v94, v88, v89
	v_cvt_pk_bf16_f32 v95, v90, v91
	s_mov_b32 s45, s6
	s_nop 0
	v_add_u32_e32 v100, 32, v152
	v_add_u32_e32 v88, v122, v100
	v_ashrrev_i32_e32 v89, 31, v88
	v_lshlrev_b64 v[88:89], 12, v[88:89]
	v_lshl_add_u64 v[88:89], s[4:5], 0, v[88:89]
	v_lshl_add_u64 v[88:89], v[88:89], 0, v[136:137]
	global_store_dwordx4 v[88:89], v[92:95], off
	v_cvt_pk_bf16_f32 v84, v84, v85
	v_cvt_pk_bf16_f32 v85, v86, v87
	v_cvt_pk_bf16_f32 v86, v76, v77
	v_add_u32_e32 v76, v121, v100
	v_ashrrev_i32_e32 v77, 31, v76
	v_lshlrev_b64 v[76:77], 12, v[76:77]
	v_lshl_add_u64 v[76:77], s[4:5], 0, v[76:77]
	v_lshl_add_u64 v[76:77], v[76:77], 0, v[108:109]
	v_cvt_pk_bf16_f32 v87, v78, v79
	global_store_dwordx4 v[76:77], v[84:87], off
	v_cvt_pk_bf16_f32 v76, v80, v81
	v_cvt_pk_bf16_f32 v77, v82, v83
	v_cvt_pk_bf16_f32 v78, v72, v73
	v_cvt_pk_bf16_f32 v79, v74, v75
	s_mov_b32 s16, s8
	s_nop 0
	v_add_u32_e32 v84, 48, v152
	v_add_u32_e32 v72, v122, v84
	v_ashrrev_i32_e32 v73, 31, v72
	v_lshlrev_b64 v[72:73], 12, v[72:73]
	v_lshl_add_u64 v[72:73], s[4:5], 0, v[72:73]
	v_lshl_add_u64 v[72:73], v[72:73], 0, v[136:137]
	global_store_dwordx4 v[72:73], v[76:79], off
; __device__ __forceinline__ unsigned cvt_pk_bf16(float lo, float hi) { unsigned r; asm volatile("v_cvt_pk_bf16_f32 %0, %1, %2" : "=v"(r) : "v"(lo), "v"(hi)); return r; }
; #define PG8_WAIT_V(n) asm volatile("s_waitcnt vmcnt(" #n ")" ::: "memory")
; #define PG8_BAR __builtin_amdgcn_s_barrier()
; template <class Epi, class Sched>
; __device__ __forceinline__ void gemm_phase(LAS unsigned char* lds, const Gemm g, const Sched& S, const Epi& E) {
;     ...
;         E(acc, cur, wr, wc, fr, fq);
;         if (!has_next) break;
; #pragma unroll
;         for (int a = 0; a < 2; ++a)
; #pragma unroll
;             for (int b = 0; b < 2; ++b)
; #pragma unroll
;                 for (int m = 0; m < 4; ++m)
; #pragma unroll
;                     for (int n = 0; n < 2; ++n) acc[a][b][m][n] = (f32x4){0.f, 0.f, 0.f, 0.f};
;         cur = nxt; cA = nA; cB = nB; ++ui;
;     }
;     PG8_WAIT_V(0);
;     if (wr == 0) PG8_BAR;
;     PG8_BAR;
;     __device__ __forceinline__ void operator()(const AccT& acc, const Unit& u, int wr, int wc, int fr, int fq) const {
;     ...
;                 const int gm = rbase + ai * 128 + m * 16;
; #pragma unroll
;                 for (int bj = 0; bj < 2; ++bj) {
;                     const int t0 = tb + bj * 128;
;                     const f32x4 v0 = acc[ai][bj][m][0], v1 = acc[ai][bj][m][1];
;                     u32x4 w; w.x = cvt_pk_bf16(v0[0], v0[1]); w.y = cvt_pk_bf16(v0[2], v0[3]); w.z = cvt_pk_bf16(v1[0], v1[1]); w.w = cvt_pk_bf16(v1[2], v1[3]);
;                     *(u32x4*)(YT + ((size_t)((t0 >> 10) * 512 + gm)) * 2048 + part * 1024 + (t0 & 1023)) = w;
;                 }
;             }
	v_cvt_pk_bf16_f32 v68, v68, v69
	v_cvt_pk_bf16_f32 v69, v70, v71
	v_cvt_pk_bf16_f32 v70, v64, v65
	v_add_u32_e32 v64, v121, v84
	v_ashrrev_i32_e32 v65, 31, v64
	v_lshlrev_b64 v[64:65], 12, v[64:65]
	v_lshl_add_u64 v[64:65], s[4:5], 0, v[64:65]
	v_lshl_add_u64 v[64:65], v[64:65], 0, v[108:109]
	v_cvt_pk_bf16_f32 v71, v66, v67
	global_store_dwordx4 v[64:65], v[68:71], off
	v_add_u32_e32 v64, 0x80, v152
	v_cvt_pk_bf16_f32 v60, v60, v61
	v_cvt_pk_bf16_f32 v61, v62, v63
	v_cvt_pk_bf16_f32 v62, v56, v57
	v_add_u32_e32 v56, v122, v64
	v_ashrrev_i32_e32 v57, 31, v56
	v_lshlrev_b64 v[56:57], 12, v[56:57]
	v_lshl_add_u64 v[56:57], s[4:5], 0, v[56:57]
	v_lshl_add_u64 v[56:57], v[56:57], 0, v[136:137]
	v_cvt_pk_bf16_f32 v63, v58, v59
	global_store_dwordx4 v[56:57], v[60:63], off
	v_cvt_pk_bf16_f32 v52, v52, v53
	v_cvt_pk_bf16_f32 v53, v54, v55
	v_cvt_pk_bf16_f32 v54, v44, v45
	v_add_u32_e32 v44, v121, v64
	v_ashrrev_i32_e32 v45, 31, v44
	v_lshlrev_b64 v[44:45], 12, v[44:45]
	v_lshl_add_u64 v[44:45], s[4:5], 0, v[44:45]
	v_lshl_add_u64 v[44:45], v[44:45], 0, v[108:109]
	v_cvt_pk_bf16_f32 v55, v46, v47
	global_store_dwordx4 v[44:45], v[52:55], off
	v_cvt_pk_bf16_f32 v44, v48, v49
	v_cvt_pk_bf16_f32 v45, v50, v51
	v_cvt_pk_bf16_f32 v46, v40, v41
	v_cvt_pk_bf16_f32 v47, v42, v43
	s_mov_b64 s[20:21], s[14:15]
	s_nop 0
	v_add_u32_e32 v52, 0x90, v152
	v_add_u32_e32 v40, v122, v52
	v_ashrrev_i32_e32 v41, 31, v40
	v_lshlrev_b64 v[40:41], 12, v[40:41]
	v_lshl_add_u64 v[40:41], s[4:5], 0, v[40:41]
	v_lshl_add_u64 v[40:41], v[40:41], 0, v[136:137]
	global_store_dwordx4 v[40:41], v[44:47], off
	v_cvt_pk_bf16_f32 v36, v36, v37
	v_cvt_pk_bf16_f32 v37, v38, v39
	v_cvt_pk_bf16_f32 v38, v28, v29
	v_add_u32_e32 v28, v121, v52
	v_ashrrev_i32_e32 v29, 31, v28
	v_lshlrev_b64 v[28:29], 12, v[28:29]
	v_lshl_add_u64 v[28:29], s[4:5], 0, v[28:29]
	v_lshl_add_u64 v[28:29], v[28:29], 0, v[108:109]
	v_cvt_pk_bf16_f32 v39, v30, v31
	global_store_dwordx4 v[28:29], v[36:39], off
	v_cvt_pk_bf16_f32 v28, v32, v33
	v_cvt_pk_bf16_f32 v29, v34, v35
	v_cvt_pk_bf16_f32 v30, v24, v25
	v_cvt_pk_bf16_f32 v31, v26, v27
	s_mov_b64 s[18:19], s[12:13]
	s_nop 0
	v_add_u32_e32 v36, 0xa0, v152
	v_add_u32_e32 v24, v122, v36
	v_ashrrev_i32_e32 v25, 31, v24
	v_lshlrev_b64 v[24:25], 12, v[24:25]
	v_lshl_add_u64 v[24:25], s[4:5], 0, v[24:25]
	v_lshl_add_u64 v[24:25], v[24:25], 0, v[136:137]
	global_store_dwordx4 v[24:25], v[28:31], off
	v_cvt_pk_bf16_f32 v20, v20, v21
	v_cvt_pk_bf16_f32 v21, v22, v23
	v_cvt_pk_bf16_f32 v22, v12, v13
	v_add_u32_e32 v12, v121, v36
	v_ashrrev_i32_e32 v13, 31, v12
	v_lshlrev_b64 v[12:13], 12, v[12:13]
	v_lshl_add_u64 v[12:13], s[4:5], 0, v[12:13]
	v_lshl_add_u64 v[12:13], v[12:13], 0, v[108:109]
	v_cvt_pk_bf16_f32 v23, v14, v15
	global_store_dwordx4 v[12:13], v[20:23], off
	v_cvt_pk_bf16_f32 v12, v16, v17
	v_cvt_pk_bf16_f32 v13, v18, v19
	v_cvt_pk_bf16_f32 v14, v8, v9
	v_cvt_pk_bf16_f32 v15, v10, v11
	s_nop 1
	v_add_u32_e32 v20, 0xb0, v152
	v_add_u32_e32 v8, v122, v20
	v_ashrrev_i32_e32 v9, 31, v8
	v_lshlrev_b64 v[8:9], 12, v[8:9]
	v_lshl_add_u64 v[8:9], s[4:5], 0, v[8:9]
	v_lshl_add_u64 v[8:9], v[8:9], 0, v[136:137]
	global_store_dwordx4 v[8:9], v[12:15], off
	v_cvt_pk_bf16_f32 v4, v4, v5
	v_cvt_pk_bf16_f32 v5, v6, v7
	v_cvt_pk_bf16_f32 v6, v0, v1
	v_add_u32_e32 v0, v121, v20
	v_ashrrev_i32_e32 v1, 31, v0
	v_lshlrev_b64 v[0:1], 12, v[0:1]
	v_lshl_add_u64 v[0:1], s[4:5], 0, v[0:1]
	v_lshl_add_u64 v[0:1], v[0:1], 0, v[108:109]
	v_cvt_pk_bf16_f32 v7, v2, v3
	global_store_dwordx4 v[0:1], v[4:7], off
	s_cbranch_vccz .LBB0_666
	s_waitcnt vmcnt(0)
	s_cmpk_gt_u32 s24, 0xff
	s_cbranch_scc1 .LBB0_677
	s_barrier

; #define PG8_STAGE(bufoff, gbase, voff) do { _Pragma("unroll") for (int _i = 0; _i < 2; ++_i) \
;         __builtin_amdgcn_global_load_lds((const unsigned*)((const char*)(gbase) + (voff)[_i]), (LAS unsigned*)(lds + (bufoff) + ldsw + _i * 8192), 16, 0, 0); } while (0)
; #define PG8_LDA(dst, b, h) do { _Pragma("unroll") for (int m = 0; m < 4; ++m) _Pragma("unroll") for (int k = 0; k < 2; ++k) dst[m][k] = *(const LAS bf16x8*)(lds + PG8_SA(b, h) + aoff + m * 2048 + k * 1024); } while (0)
; #define PG8_LDB(dst, b, h) do { _Pragma("unroll") for (int n = 0; n < 2; ++n) _Pragma("unroll") for (int k = 0; k < 2; ++k) dst[n][k] = *(const LAS bf16x8*)(lds + PG8_SB(b, h) + boff + n * 2048 + k * 1024); } while (0)
; #define PG8_MMA(ai, bj, At, Bt) do { __builtin_amdgcn_s_setprio(1); _Pragma("unroll") for (int m = 0; m < 4; ++m) _Pragma("unroll") for (int n = 0; n < 2; ++n) _Pragma("unroll") for (int k = 0; k < 2; ++k) \
;         acc[ai][bj][m][n] = __builtin_amdgcn_mfma_f32_16x16x32_bf16(Bt[n][k], At[m][k], acc[ai][bj][m][n], 0, 0, 0); __builtin_amdgcn_s_setprio(0); } while (0)
; #define PG8_WAIT_L(n) asm volatile("s_waitcnt lgkmcnt(" #n ")" ::: "memory")
; template <class Epi, class Sched>
; __device__ __forceinline__ void gemm_phase(LAS unsigned char* lds, const Gemm g, const Sched& S, const Epi& E) {
;     ...
;     for (;;) {
;         const bool has_next = S.next(ui + 1, nxt);
;         const char* nA = has_next ? (const char*)g.A + (size_t)nxt.pm * tstep : cA; const char* nB = has_next ? (const char*)g.Bt + (size_t)nxt.pn * tstep : cB;
;         for (int t = 0; t < nt; t += 2) {
;             const bool last = (t == nt - 2);
;             const char* a1 = cA + (size_t)(t + 1) * kstep;
;             const char* a2 = last ? nA : cA + (size_t)(t + 2) * kstep; const char* b2 = last ? nB : cB + (size_t)(t + 2) * kstep;
;             const char* a3 = a2 + kstep; const char* b3 = b2 + kstep;
;             PG8_LDB(B0, 0, 0); PG8_SCHED; PG8_LDA(At, 0, 0); PG8_STAGE(PG8_SA(1, 1), a1 + hstep, voffA);
;             PG8_WAIT_L(8); PG8_BAR; PG8_WAIT_L(0); PG8_MMA(0, 0, At, B0); PG8_BAR; PG8_SCHED;
;             PG8_LDB(B1, 0, 1); PG8_STAGE(PG8_SB(0, 0), b2, voffB);
;             PG8_BAR; PG8_WAIT_L(0); PG8_MMA(0, 1, At, B1); PG8_BAR;
;             PG8_LDA(At, 0, 1); PG8_STAGE(PG8_SA(0, 0), a2, voffA);
;             PG8_BAR; PG8_WAIT_L(0); PG8_MMA(1, 0, At, B0); PG8_BAR; PG8_SCHED;
.LBB0_692:
	s_ashr_i32 s19, s18, 31
	v_cmp_lt_i64_e64 s[24:25], s[20:21], 32
	s_lshl_b64 s[20:21], s[18:19], 19
	s_add_u32 s20, s40, s20
	s_addc_u32 s21, s41, s21
	s_and_b64 s[22:23], s[24:25], exec
	s_cselect_b32 s19, s21, s3
	s_cselect_b32 s57, s20, s2
	s_ashr_i32 s17, s16, 31
	s_lshl_b64 s[22:23], s[16:17], 19
	s_add_u32 s22, s28, s22
	s_addc_u32 s23, s29, s23
	s_and_b64 s[24:25], s[24:25], exec
	s_cselect_b32 s17, s23, s5
	s_cselect_b32 s58, s22, s4
	s_add_u32 s2, s2, 0x40080
	s_addc_u32 s3, s3, 0
	s_add_u32 s59, s4, 0x100
	s_addc_u32 s60, s5, 0
	s_mov_b32 s61, -2
	s_waitcnt lgkmcnt(0)
	ds_read_b128 v[140:143], v149
	ds_read_b128 v[154:157], v149 offset:1024
	ds_read_b128 v[158:161], v149 offset:2048
	ds_read_b128 v[162:165], v149 offset:3072
	s_add_u32 s4, s2, 0xfffc0080
	s_addc_u32 s5, s3, -1
	s_cmp_eq_u32 s61, 12
	s_cselect_b32 s25, s19, s5
	s_cselect_b32 s24, s57, s4
	s_cselect_b32 s5, s17, s60
	s_cselect_b32 s4, s58, s59
	s_add_i32 m0, s33, 0xc000
	ds_read_b128 v[166:169], v150
	ds_read_b128 v[170:173], v150 offset:1024
	ds_read_b128 v[174:177], v150 offset:2048
	ds_read_b128 v[178:181], v150 offset:3072
	ds_read_b128 v[182:185], v150 offset:4096
	ds_read_b128 v[186:189], v150 offset:5120
	ds_read_b128 v[190:193], v150 offset:6144
	ds_read_b128 v[194:197], v150 offset:7168
	global_load_lds_dwordx4 v136, s[2:3]
	s_add_i32 m0, s33, 0xe000
	s_nop 0
	global_load_lds_dwordx4 v138, s[2:3]
	s_waitcnt lgkmcnt(8)
	s_waitcnt vmcnt(8)
	s_setprio 1
	s_barrier
	s_waitcnt lgkmcnt(0)
	v_mfma_f32_16x16x32_bf16 v[124:127], v[140:143], v[166:169], 0
	v_mfma_f32_16x16x32_bf16 v[120:123], v[158:161], v[166:169], 0
	v_mfma_f32_16x16x32_bf16 v[108:111], v[140:143], v[174:177], 0
	v_mfma_f32_16x16x32_bf16 v[104:107], v[158:161], v[174:177], 0
	v_mfma_f32_16x16x32_bf16 v[92:95], v[140:143], v[182:185], 0
	v_mfma_f32_16x16x32_bf16 v[88:91], v[158:161], v[182:185], 0
	v_mfma_f32_16x16x32_bf16 v[76:79], v[140:143], v[190:193], 0
	v_mfma_f32_16x16x32_bf16 v[72:75], v[158:161], v[190:193], 0
	v_mfma_f32_16x16x32_bf16 v[124:127], v[154:157], v[170:173], v[124:127]
	v_mfma_f32_16x16x32_bf16 v[120:123], v[162:165], v[170:173], v[120:123]
	v_mfma_f32_16x16x32_bf16 v[108:111], v[154:157], v[178:181], v[108:111]
	v_mfma_f32_16x16x32_bf16 v[104:107], v[162:165], v[178:181], v[104:107]
	v_mfma_f32_16x16x32_bf16 v[92:95], v[154:157], v[186:189], v[92:95]
	v_mfma_f32_16x16x32_bf16 v[88:91], v[162:165], v[186:189], v[88:91]
	v_mfma_f32_16x16x32_bf16 v[76:79], v[154:157], v[194:197], v[76:79]
	v_mfma_f32_16x16x32_bf16 v[72:75], v[162:165], v[194:197], v[72:75]
	s_barrier
	s_setprio 0
	s_add_i32 s62, s47, s31
	s_mov_b32 m0, s62
	ds_read_b128 v[202:205], v151
	ds_read_b128 v[206:209], v151 offset:1024
	ds_read_b128 v[210:213], v151 offset:2048
	ds_read_b128 v[214:217], v151 offset:3072
	global_load_lds_dwordx4 v130, s[4:5]
	s_add_i32 m0, s62, 0x2000
	s_nop 0
	global_load_lds_dwordx4 v134, s[4:5]
	s_waitcnt vmcnt(8)
	s_setprio 1
	s_barrier
	s_waitcnt lgkmcnt(0)
	v_mfma_f32_16x16x32_bf16 v[116:119], v[202:205], v[166:169], 0
	v_mfma_f32_16x16x32_bf16 v[112:115], v[210:213], v[166:169], 0
	v_mfma_f32_16x16x32_bf16 v[100:103], v[202:205], v[174:177], 0
	v_mfma_f32_16x16x32_bf16 v[96:99], v[210:213], v[174:177], 0
	v_mfma_f32_16x16x32_bf16 v[84:87], v[202:205], v[182:185], 0
	v_mfma_f32_16x16x32_bf16 v[80:83], v[210:213], v[182:185], 0
	v_mfma_f32_16x16x32_bf16 v[68:71], v[202:205], v[190:193], 0
	v_mfma_f32_16x16x32_bf16 v[64:67], v[210:213], v[190:193], 0
	v_mfma_f32_16x16x32_bf16 v[116:119], v[206:209], v[170:173], v[116:119]
	v_mfma_f32_16x16x32_bf16 v[112:115], v[214:217], v[170:173], v[112:115]
	v_mfma_f32_16x16x32_bf16 v[100:103], v[206:209], v[178:181], v[100:103]
	v_mfma_f32_16x16x32_bf16 v[96:99], v[214:217], v[178:181], v[96:99]
	v_mfma_f32_16x16x32_bf16 v[84:87], v[206:209], v[186:189], v[84:87]
	v_mfma_f32_16x16x32_bf16 v[80:83], v[214:217], v[186:189], v[80:83]
	v_mfma_f32_16x16x32_bf16 v[68:71], v[206:209], v[194:197], v[68:71]
	v_mfma_f32_16x16x32_bf16 v[64:67], v[214:217], v[194:197], v[64:67]
	s_barrier
	s_setprio 0
	s_mov_b32 m0, s33
	v_lshl_add_u64 v[218:219], s[24:25], 0, v[128:129]
	ds_read_b128 v[166:169], v150 offset:16384
	ds_read_b128 v[170:173], v150 offset:17408
	ds_read_b128 v[174:177], v150 offset:18432
	ds_read_b128 v[178:181], v150 offset:19456
	ds_read_b128 v[182:185], v150 offset:20480
	ds_read_b128 v[186:189], v150 offset:21504
	ds_read_b128 v[190:193], v150 offset:22528
	ds_read_b128 v[194:197], v150 offset:23552
	global_load_lds_dwordx4 v128, s[24:25]
	v_lshl_add_u64 v[220:221], s[24:25], 0, v[132:133]
	s_mov_b32 m0, s34
	s_nop 0
	global_load_lds_dwordx4 v132, s[24:25]
	s_setprio 1
	s_barrier
	s_waitcnt lgkmcnt(0)
	v_mfma_f32_16x16x32_bf16 v[60:63], v[140:143], v[166:169], 0
	v_mfma_f32_16x16x32_bf16 v[56:59], v[158:161], v[166:169], 0
	v_mfma_f32_16x16x32_bf16 v[44:47], v[140:143], v[174:177], 0
	v_mfma_f32_16x16x32_bf16 v[40:43], v[158:161], v[174:177], 0
	v_mfma_f32_16x16x32_bf16 v[28:31], v[140:143], v[182:185], 0
	v_mfma_f32_16x16x32_bf16 v[24:27], v[158:161], v[182:185], 0
	v_mfma_f32_16x16x32_bf16 v[12:15], v[140:143], v[190:193], 0
	v_mfma_f32_16x16x32_bf16 v[8:11], v[158:161], v[190:193], 0
	v_mfma_f32_16x16x32_bf16 v[60:63], v[154:157], v[170:173], v[60:63]
	v_mfma_f32_16x16x32_bf16 v[56:59], v[162:165], v[170:173], v[56:59]
	v_mfma_f32_16x16x32_bf16 v[44:47], v[154:157], v[178:181], v[44:47]
	v_mfma_f32_16x16x32_bf16 v[40:43], v[162:165], v[178:181], v[40:43]
	v_mfma_f32_16x16x32_bf16 v[28:31], v[154:157], v[186:189], v[28:31]
	v_mfma_f32_16x16x32_bf16 v[24:27], v[162:165], v[186:189], v[24:27]
	v_mfma_f32_16x16x32_bf16 v[12:15], v[154:157], v[194:197], v[12:15]
	v_mfma_f32_16x16x32_bf16 v[8:11], v[162:165], v[194:197], v[8:11]
	s_barrier
; #define PG8_STAGE(bufoff, gbase, voff) do { _Pragma("unroll") for (int _i = 0; _i < 2; ++_i) \
;         __builtin_amdgcn_global_load_lds((const unsigned*)((const char*)(gbase) + (voff)[_i]), (LAS unsigned*)(lds + (bufoff) + ldsw + _i * 8192), 16, 0, 0); } while (0)
; #define PG8_LDA(dst, b, h) do { _Pragma("unroll") for (int m = 0; m < 4; ++m) _Pragma("unroll") for (int k = 0; k < 2; ++k) dst[m][k] = *(const LAS bf16x8*)(lds + PG8_SA(b, h) + aoff + m * 2048 + k * 1024); } while (0)
; #define PG8_LDB(dst, b, h) do { _Pragma("unroll") for (int n = 0; n < 2; ++n) _Pragma("unroll") for (int k = 0; k < 2; ++k) dst[n][k] = *(const LAS bf16x8*)(lds + PG8_SB(b, h) + boff + n * 2048 + k * 1024); } while (0)
; #define PG8_MMA(ai, bj, At, Bt) do { __builtin_amdgcn_s_setprio(1); _Pragma("unroll") for (int m = 0; m < 4; ++m) _Pragma("unroll") for (int n = 0; n < 2; ++n) _Pragma("unroll") for (int k = 0; k < 2; ++k) \
;         acc[ai][bj][m][n] = __builtin_amdgcn_mfma_f32_16x16x32_bf16(Bt[n][k], At[m][k], acc[ai][bj][m][n], 0, 0, 0); __builtin_amdgcn_s_setprio(0); } while (0)
; #define PG8_WAIT_V(n) asm volatile("s_waitcnt vmcnt(" #n ")" ::: "memory")
; #define PG8_WAIT_L(n) asm volatile("s_waitcnt lgkmcnt(" #n ")" ::: "memory")
; #define PG8_BAR __builtin_amdgcn_s_barrier()
; #define PG8_SCHED __builtin_amdgcn_sched_barrier(0)
; template <class Epi, class Sched>
; __device__ __forceinline__ void gemm_phase(LAS unsigned char* lds, const Gemm g, const Sched& S, const Epi& E) {
;     ...
;             PG8_BAR; PG8_WAIT_L(0); PG8_MMA(1, 0, At, B0); PG8_BAR; PG8_SCHED;
;             PG8_STAGE(PG8_SB(0, 1), b2 + hstep, voffB);
;             PG8_WAIT_V(6); PG8_BAR; PG8_MMA(1, 1, At, B1); PG8_BAR;
;             PG8_LDB(B0, 1, 0); PG8_SCHED; PG8_LDA(At, 1, 0); PG8_STAGE(PG8_SA(0, 1), a2 + hstep, voffA);
;             PG8_WAIT_L(8); PG8_BAR; PG8_WAIT_L(0); PG8_MMA(0, 0, At, B0); PG8_BAR; PG8_SCHED;
;             PG8_LDB(B1, 1, 1); PG8_STAGE(PG8_SB(1, 0), b3, voffB);
;             PG8_BAR; PG8_WAIT_L(0); PG8_MMA(0, 1, At, B1); PG8_BAR;
;             PG8_LDA(At, 1, 1); PG8_STAGE(PG8_SA(1, 0), a3, voffA);
;             PG8_BAR; PG8_WAIT_L(0); PG8_MMA(1, 0, At, B0); PG8_BAR; PG8_SCHED;
	s_setprio 0
	s_add_u32 s62, s4, 0x40000
	s_addc_u32 s63, s5, 0
	s_add_i32 s64, s48, s31
	s_mov_b32 m0, s64
	s_nop 0
	global_load_lds_dwordx4 v130, s[62:63]
	s_add_i32 m0, s64, 0x2000
	s_nop 0
	global_load_lds_dwordx4 v134, s[62:63]
	s_add_u32 s24, s24, 0x40000
	s_addc_u32 s25, s25, 0
	s_mov_b32 m0, s35
	s_nop 0
	global_load_lds_dwordx4 v128, s[24:25]
	s_mov_b32 m0, s36
	s_nop 0
	global_load_lds_dwordx4 v132, s[24:25]
	s_waitcnt vmcnt(10)
	s_setprio 1
	s_barrier
	v_mfma_f32_16x16x32_bf16 v[52:55], v[202:205], v[166:169], 0
	v_mfma_f32_16x16x32_bf16 v[48:51], v[210:213], v[166:169], 0
	v_mfma_f32_16x16x32_bf16 v[36:39], v[202:205], v[174:177], 0
	v_mfma_f32_16x16x32_bf16 v[32:35], v[210:213], v[174:177], 0
	v_mfma_f32_16x16x32_bf16 v[20:23], v[202:205], v[182:185], 0
	v_mfma_f32_16x16x32_bf16 v[16:19], v[210:213], v[182:185], 0
	v_mfma_f32_16x16x32_bf16 v[4:7], v[202:205], v[190:193], 0
	v_mfma_f32_16x16x32_bf16 v[0:3], v[210:213], v[190:193], 0
	v_mfma_f32_16x16x32_bf16 v[52:55], v[206:209], v[170:173], v[52:55]
	v_mfma_f32_16x16x32_bf16 v[48:51], v[214:217], v[170:173], v[48:51]
	v_mfma_f32_16x16x32_bf16 v[36:39], v[206:209], v[178:181], v[36:39]
	v_mfma_f32_16x16x32_bf16 v[32:35], v[214:217], v[178:181], v[32:35]
	v_mfma_f32_16x16x32_bf16 v[20:23], v[206:209], v[186:189], v[20:23]
	v_mfma_f32_16x16x32_bf16 v[16:19], v[214:217], v[186:189], v[16:19]
	v_mfma_f32_16x16x32_bf16 v[4:7], v[206:209], v[194:197], v[4:7]
	v_mfma_f32_16x16x32_bf16 v[0:3], v[214:217], v[194:197], v[0:3]
	s_barrier
	s_setprio 0
	s_add_i32 s62, 0, 0x18000
	ds_read_b128 v[140:143], v151 offset:16384
	ds_read_b128 v[154:157], v151 offset:17408
	ds_read_b128 v[158:161], v151 offset:18432
	ds_read_b128 v[162:165], v151 offset:19456
	ds_read_b128 v[166:169], v150 offset:32768
	ds_read_b128 v[170:173], v150 offset:33792
	ds_read_b128 v[174:177], v150 offset:34816
	ds_read_b128 v[178:181], v150 offset:35840
	ds_read_b128 v[182:185], v150 offset:36864
	ds_read_b128 v[186:189], v150 offset:37888
	ds_read_b128 v[190:193], v150 offset:38912
	ds_read_b128 v[194:197], v150 offset:39936
	s_waitcnt lgkmcnt(8)
	s_waitcnt vmcnt(8)
	s_setprio 1
	s_barrier
	s_waitcnt lgkmcnt(0)
	v_mfma_f32_16x16x32_bf16 v[124:127], v[140:143], v[166:169], v[124:127]
	v_mfma_f32_16x16x32_bf16 v[120:123], v[158:161], v[166:169], v[120:123]
	v_mfma_f32_16x16x32_bf16 v[108:111], v[140:143], v[174:177], v[108:111]
	v_mfma_f32_16x16x32_bf16 v[104:107], v[158:161], v[174:177], v[104:107]
	v_mfma_f32_16x16x32_bf16 v[92:95], v[140:143], v[182:185], v[92:95]
	v_mfma_f32_16x16x32_bf16 v[88:91], v[158:161], v[182:185], v[88:91]
	v_mfma_f32_16x16x32_bf16 v[76:79], v[140:143], v[190:193], v[76:79]
	v_mfma_f32_16x16x32_bf16 v[72:75], v[158:161], v[190:193], v[72:75]
	v_mfma_f32_16x16x32_bf16 v[124:127], v[154:157], v[170:173], v[124:127]
	v_mfma_f32_16x16x32_bf16 v[120:123], v[162:165], v[170:173], v[120:123]
	v_mfma_f32_16x16x32_bf16 v[108:111], v[154:157], v[178:181], v[108:111]
	v_mfma_f32_16x16x32_bf16 v[104:107], v[162:165], v[178:181], v[104:107]
	v_mfma_f32_16x16x32_bf16 v[92:95], v[154:157], v[186:189], v[92:95]
	v_mfma_f32_16x16x32_bf16 v[88:91], v[162:165], v[186:189], v[88:91]
	v_mfma_f32_16x16x32_bf16 v[76:79], v[154:157], v[194:197], v[76:79]
	v_mfma_f32_16x16x32_bf16 v[72:75], v[162:165], v[194:197], v[72:75]
	s_barrier
	s_setprio 0
	s_add_i32 s24, 0, 0x1c000
	s_add_i32 s25, s62, s31
	s_add_u32 s0, s4, 0x80
	s_addc_u32 s1, s5, 0
	s_mov_b32 m0, s25
	ds_read_b128 v[202:205], v151 offset:32768
	ds_read_b128 v[206:209], v151 offset:33792
	ds_read_b128 v[210:213], v151 offset:34816
	ds_read_b128 v[214:217], v151 offset:35840
	global_load_lds_dwordx4 v130, s[0:1]
	s_add_i32 m0, s25, 0x2000
	s_nop 0
	global_load_lds_dwordx4 v134, s[0:1]
	s_waitcnt vmcnt(8)
	s_setprio 1
	s_barrier
	s_waitcnt lgkmcnt(0)
	v_mfma_f32_16x16x32_bf16 v[116:119], v[202:205], v[166:169], v[116:119]
	v_mfma_f32_16x16x32_bf16 v[112:115], v[210:213], v[166:169], v[112:115]
	v_mfma_f32_16x16x32_bf16 v[100:103], v[202:205], v[174:177], v[100:103]
	v_mfma_f32_16x16x32_bf16 v[96:99], v[210:213], v[174:177], v[96:99]
	v_mfma_f32_16x16x32_bf16 v[84:87], v[202:205], v[182:185], v[84:87]
	v_mfma_f32_16x16x32_bf16 v[80:83], v[210:213], v[182:185], v[80:83]
	v_mfma_f32_16x16x32_bf16 v[68:71], v[202:205], v[190:193], v[68:71]
	v_mfma_f32_16x16x32_bf16 v[64:67], v[210:213], v[190:193], v[64:67]
	v_mfma_f32_16x16x32_bf16 v[116:119], v[206:209], v[170:173], v[116:119]
	v_mfma_f32_16x16x32_bf16 v[112:115], v[214:217], v[170:173], v[112:115]
	v_mfma_f32_16x16x32_bf16 v[100:103], v[206:209], v[178:181], v[100:103]
	v_mfma_f32_16x16x32_bf16 v[96:99], v[214:217], v[178:181], v[96:99]
	v_mfma_f32_16x16x32_bf16 v[84:87], v[206:209], v[186:189], v[84:87]
	v_mfma_f32_16x16x32_bf16 v[80:83], v[214:217], v[186:189], v[80:83]
	v_mfma_f32_16x16x32_bf16 v[68:71], v[206:209], v[194:197], v[68:71]
	v_mfma_f32_16x16x32_bf16 v[64:67], v[214:217], v[194:197], v[64:67]
	s_barrier
	s_setprio 0
	s_mov_b32 m0, s44
	s_mov_b64 s[0:1], 0x80
	v_lshl_add_u64 v[144:145], v[218:219], 0, s[0:1]
	ds_read_b128 v[166:169], v150 offset:49152
	ds_read_b128 v[170:173], v150 offset:50176
	ds_read_b128 v[174:177], v150 offset:51200
	ds_read_b128 v[178:181], v150 offset:52224
	ds_read_b128 v[182:185], v150 offset:53248
	ds_read_b128 v[186:189], v150 offset:54272
	ds_read_b128 v[190:193], v150 offset:55296
	ds_read_b128 v[194:197], v150 offset:56320
	global_load_lds_dwordx4 v[144:145], off
	v_lshl_add_u64 v[144:145], v[220:221], 0, s[0:1]
	s_mov_b32 m0, s45
	s_nop 0
	global_load_lds_dwordx4 v[144:145], off
	s_setprio 1
	s_barrier
; #define PG8_STAGE(bufoff, gbase, voff) do { _Pragma("unroll") for (int _i = 0; _i < 2; ++_i) \
;         __builtin_amdgcn_global_load_lds((const unsigned*)((const char*)(gbase) + (voff)[_i]), (LAS unsigned*)(lds + (bufoff) + ldsw + _i * 8192), 16, 0, 0); } while (0)
; #define PG8_LDA(dst, b, h) do { _Pragma("unroll") for (int m = 0; m < 4; ++m) _Pragma("unroll") for (int k = 0; k < 2; ++k) dst[m][k] = *(const LAS bf16x8*)(lds + PG8_SA(b, h) + aoff + m * 2048 + k * 1024); } while (0)
; #define PG8_LDB(dst, b, h) do { _Pragma("unroll") for (int n = 0; n < 2; ++n) _Pragma("unroll") for (int k = 0; k < 2; ++k) dst[n][k] = *(const LAS bf16x8*)(lds + PG8_SB(b, h) + boff + n * 2048 + k * 1024); } while (0)
; #define PG8_WAIT_V(n) asm volatile("s_waitcnt vmcnt(" #n ")" ::: "memory")
; #define PG8_WAIT_L(n) asm volatile("s_waitcnt lgkmcnt(" #n ")" ::: "memory")
; #define PG8_BAR __builtin_amdgcn_s_barrier()
; #define PG8_SCHED __builtin_amdgcn_sched_barrier(0)
; template <class Epi, class Sched>
; __device__ __forceinline__ void gemm_phase(LAS unsigned char* lds, const Gemm g, const Sched& S, const Epi& E) {
;     ...
;             PG8_LDB(B0, 0, 0); PG8_SCHED; PG8_LDA(At, 0, 0); PG8_STAGE(PG8_SA(1, 1), a1 + hstep, voffA);
;             PG8_WAIT_L(8); PG8_BAR; PG8_WAIT_L(0); PG8_MMA(0, 0, At, B0); PG8_BAR; PG8_SCHED;
;             PG8_LDB(B1, 0, 1); PG8_STAGE(PG8_SB(0, 0), b2, voffB);
;             PG8_BAR; PG8_WAIT_L(0); PG8_MMA(0, 1, At, B1); PG8_BAR;
;             PG8_LDA(At, 0, 1); PG8_STAGE(PG8_SA(0, 0), a2, voffA);
;             PG8_BAR; PG8_WAIT_L(0); PG8_MMA(1, 0, At, B0); PG8_BAR; PG8_SCHED;
;             PG8_STAGE(PG8_SB(0, 1), b2 + hstep, voffB);
;             PG8_WAIT_V(6); PG8_BAR; PG8_MMA(1, 1, At, B1); PG8_BAR;
;             PG8_LDB(B0, 1, 0); PG8_SCHED; PG8_LDA(At, 1, 0); PG8_STAGE(PG8_SA(0, 1), a2 + hstep, voffA);
;             PG8_WAIT_L(8); PG8_BAR; PG8_WAIT_L(0); PG8_MMA(0, 0, At, B0); PG8_BAR; PG8_SCHED;
;             PG8_LDB(B1, 1, 1); PG8_STAGE(PG8_SB(1, 0), b3, voffB);
;             PG8_BAR; PG8_WAIT_L(0); PG8_MMA(0, 1, At, B1); PG8_BAR;
;             PG8_LDA(At, 1, 1); PG8_STAGE(PG8_SA(1, 0), a3, voffA);
;             PG8_BAR; PG8_WAIT_L(0); PG8_MMA(1, 0, At, B0); PG8_BAR; PG8_SCHED;
;             PG8_STAGE(PG8_SB(1, 1), b3 + hstep, voffB);
;             PG8_WAIT_V(6); PG8_BAR; PG8_MMA(1, 1, At, B1); PG8_BAR;
	s_waitcnt lgkmcnt(0)
	v_mfma_f32_16x16x32_bf16 v[60:63], v[140:143], v[166:169], v[60:63]
	v_mfma_f32_16x16x32_bf16 v[56:59], v[158:161], v[166:169], v[56:59]
	v_mfma_f32_16x16x32_bf16 v[44:47], v[140:143], v[174:177], v[44:47]
	v_mfma_f32_16x16x32_bf16 v[40:43], v[158:161], v[174:177], v[40:43]
	v_mfma_f32_16x16x32_bf16 v[28:31], v[140:143], v[182:185], v[28:31]
	v_mfma_f32_16x16x32_bf16 v[24:27], v[158:161], v[182:185], v[24:27]
	v_mfma_f32_16x16x32_bf16 v[12:15], v[140:143], v[190:193], v[12:15]
	v_mfma_f32_16x16x32_bf16 v[8:11], v[158:161], v[190:193], v[8:11]
	v_mfma_f32_16x16x32_bf16 v[60:63], v[154:157], v[170:173], v[60:63]
	v_mfma_f32_16x16x32_bf16 v[56:59], v[162:165], v[170:173], v[56:59]
	v_mfma_f32_16x16x32_bf16 v[44:47], v[154:157], v[178:181], v[44:47]
	v_mfma_f32_16x16x32_bf16 v[40:43], v[162:165], v[178:181], v[40:43]
	v_mfma_f32_16x16x32_bf16 v[28:31], v[154:157], v[186:189], v[28:31]
	v_mfma_f32_16x16x32_bf16 v[24:27], v[162:165], v[186:189], v[24:27]
	v_mfma_f32_16x16x32_bf16 v[12:15], v[154:157], v[194:197], v[12:15]
	v_mfma_f32_16x16x32_bf16 v[8:11], v[162:165], v[194:197], v[8:11]
	s_barrier
	s_setprio 0
	s_add_u32 s4, s4, 0x40080
	s_addc_u32 s5, s5, 0
	s_add_i32 s24, s24, s31
	s_mov_b32 m0, s24
	s_nop 0
	global_load_lds_dwordx4 v130, s[4:5]
	s_add_i32 m0, s24, 0x2000
	s_nop 0
	global_load_lds_dwordx4 v134, s[4:5]
	s_waitcnt vmcnt(8)
	s_setprio 1
	s_barrier
	v_mfma_f32_16x16x32_bf16 v[52:55], v[202:205], v[166:169], v[52:55]
	v_mfma_f32_16x16x32_bf16 v[48:51], v[210:213], v[166:169], v[48:51]
	v_mfma_f32_16x16x32_bf16 v[36:39], v[202:205], v[174:177], v[36:39]
	v_mfma_f32_16x16x32_bf16 v[32:35], v[210:213], v[174:177], v[32:35]
	v_mfma_f32_16x16x32_bf16 v[20:23], v[202:205], v[182:185], v[20:23]
	v_mfma_f32_16x16x32_bf16 v[16:19], v[210:213], v[182:185], v[16:19]
	v_mfma_f32_16x16x32_bf16 v[4:7], v[202:205], v[190:193], v[4:7]
	v_mfma_f32_16x16x32_bf16 v[0:3], v[210:213], v[190:193], v[0:3]
	v_mfma_f32_16x16x32_bf16 v[52:55], v[206:209], v[170:173], v[52:55]
	v_mfma_f32_16x16x32_bf16 v[48:51], v[214:217], v[170:173], v[48:51]
	v_mfma_f32_16x16x32_bf16 v[36:39], v[206:209], v[178:181], v[36:39]
	v_mfma_f32_16x16x32_bf16 v[32:35], v[214:217], v[178:181], v[32:35]
	v_mfma_f32_16x16x32_bf16 v[20:23], v[206:209], v[186:189], v[20:23]
	v_mfma_f32_16x16x32_bf16 v[16:19], v[214:217], v[186:189], v[16:19]
	v_mfma_f32_16x16x32_bf16 v[4:7], v[206:209], v[194:197], v[4:7]
	v_mfma_f32_16x16x32_bf16 v[0:3], v[214:217], v[194:197], v[0:3]
	s_barrier
	s_setprio 0
	s_add_i32 s61, s61, 2
	s_add_u32 s2, s2, 0x100
	s_addc_u32 s3, s3, 0
	s_add_u32 s59, s59, 0x100
	s_addc_u32 s60, s60, 0
	s_cmp_gt_u32 s61, 13
.LBB0_693:
	ds_read_b128 v[140:143], v149
	ds_read_b128 v[154:157], v149 offset:1024
	ds_read_b128 v[158:161], v149 offset:2048
	ds_read_b128 v[162:165], v149 offset:3072
	s_add_u32 s4, s2, 0xfffc0080
	s_addc_u32 s5, s3, -1
	s_cmp_eq_u32 s61, 12
	s_cselect_b32 s25, s19, s5
	s_cselect_b32 s24, s57, s4
	s_cselect_b32 s5, s17, s60
	s_cselect_b32 s4, s58, s59
	s_add_i32 m0, s33, 0xc000
	ds_read_b128 v[166:169], v150
	ds_read_b128 v[170:173], v150 offset:1024
	ds_read_b128 v[174:177], v150 offset:2048
	ds_read_b128 v[178:181], v150 offset:3072
	ds_read_b128 v[182:185], v150 offset:4096
	ds_read_b128 v[186:189], v150 offset:5120
	ds_read_b128 v[190:193], v150 offset:6144
	ds_read_b128 v[194:197], v150 offset:7168
	global_load_lds_dwordx4 v136, s[2:3]
	s_add_i32 m0, s33, 0xe000
	s_nop 0
	global_load_lds_dwordx4 v138, s[2:3]
	s_waitcnt lgkmcnt(8)
	s_waitcnt vmcnt(8)
	s_setprio 1
	s_barrier
	s_waitcnt lgkmcnt(0)
	v_mfma_f32_16x16x32_bf16 v[124:127], v[140:143], v[166:169], v[124:127]
	v_mfma_f32_16x16x32_bf16 v[120:123], v[158:161], v[166:169], v[120:123]
	v_mfma_f32_16x16x32_bf16 v[108:111], v[140:143], v[174:177], v[108:111]
	v_mfma_f32_16x16x32_bf16 v[104:107], v[158:161], v[174:177], v[104:107]
	v_mfma_f32_16x16x32_bf16 v[92:95], v[140:143], v[182:185], v[92:95]
	v_mfma_f32_16x16x32_bf16 v[88:91], v[158:161], v[182:185], v[88:91]
	v_mfma_f32_16x16x32_bf16 v[76:79], v[140:143], v[190:193], v[76:79]
	v_mfma_f32_16x16x32_bf16 v[72:75], v[158:161], v[190:193], v[72:75]
	v_mfma_f32_16x16x32_bf16 v[124:127], v[154:157], v[170:173], v[124:127]
	v_mfma_f32_16x16x32_bf16 v[120:123], v[162:165], v[170:173], v[120:123]
	v_mfma_f32_16x16x32_bf16 v[108:111], v[154:157], v[178:181], v[108:111]
	v_mfma_f32_16x16x32_bf16 v[104:107], v[162:165], v[178:181], v[104:107]
	v_mfma_f32_16x16x32_bf16 v[92:95], v[154:157], v[186:189], v[92:95]
	v_mfma_f32_16x16x32_bf16 v[88:91], v[162:165], v[186:189], v[88:91]
	v_mfma_f32_16x16x32_bf16 v[76:79], v[154:157], v[194:197], v[76:79]
	v_mfma_f32_16x16x32_bf16 v[72:75], v[162:165], v[194:197], v[72:75]
	s_barrier
	s_setprio 0
	s_add_i32 s62, s47, s31
	s_mov_b32 m0, s62
	ds_read_b128 v[202:205], v151
	ds_read_b128 v[206:209], v151 offset:1024
	ds_read_b128 v[210:213], v151 offset:2048
	ds_read_b128 v[214:217], v151 offset:3072
	global_load_lds_dwordx4 v130, s[4:5]
	s_add_i32 m0, s62, 0x2000
	s_nop 0
	global_load_lds_dwordx4 v134, s[4:5]
	s_waitcnt vmcnt(8)
	s_setprio 1
	s_barrier
; #define PG8_STAGE(bufoff, gbase, voff) do { _Pragma("unroll") for (int _i = 0; _i < 2; ++_i) \
;         __builtin_amdgcn_global_load_lds((const unsigned*)((const char*)(gbase) + (voff)[_i]), (LAS unsigned*)(lds + (bufoff) + ldsw + _i * 8192), 16, 0, 0); } while (0)
; #define PG8_LDA(dst, b, h) do { _Pragma("unroll") for (int m = 0; m < 4; ++m) _Pragma("unroll") for (int k = 0; k < 2; ++k) dst[m][k] = *(const LAS bf16x8*)(lds + PG8_SA(b, h) + aoff + m * 2048 + k * 1024); } while (0)
; #define PG8_LDB(dst, b, h) do { _Pragma("unroll") for (int n = 0; n < 2; ++n) _Pragma("unroll") for (int k = 0; k < 2; ++k) dst[n][k] = *(const LAS bf16x8*)(lds + PG8_SB(b, h) + boff + n * 2048 + k * 1024); } while (0)
; #define PG8_MMA(ai, bj, At, Bt) do { __builtin_amdgcn_s_setprio(1); _Pragma("unroll") for (int m = 0; m < 4; ++m) _Pragma("unroll") for (int n = 0; n < 2; ++n) _Pragma("unroll") for (int k = 0; k < 2; ++k) \
;         acc[ai][bj][m][n] = __builtin_amdgcn_mfma_f32_16x16x32_bf16(Bt[n][k], At[m][k], acc[ai][bj][m][n], 0, 0, 0); __builtin_amdgcn_s_setprio(0); } while (0)
; #define PG8_WAIT_V(n) asm volatile("s_waitcnt vmcnt(" #n ")" ::: "memory")
; #define PG8_WAIT_L(n) asm volatile("s_waitcnt lgkmcnt(" #n ")" ::: "memory")
; #define PG8_BAR __builtin_amdgcn_s_barrier()
; #define PG8_SCHED __builtin_amdgcn_sched_barrier(0)
; template <class Epi, class Sched>
; __device__ __forceinline__ void gemm_phase(LAS unsigned char* lds, const Gemm g, const Sched& S, const Epi& E) {
;     ...
;             PG8_BAR; PG8_WAIT_L(0); PG8_MMA(0, 1, At, B1); PG8_BAR;
;             PG8_LDA(At, 0, 1); PG8_STAGE(PG8_SA(0, 0), a2, voffA);
;             PG8_BAR; PG8_WAIT_L(0); PG8_MMA(1, 0, At, B0); PG8_BAR; PG8_SCHED;
;             PG8_STAGE(PG8_SB(0, 1), b2 + hstep, voffB);
;             PG8_WAIT_V(6); PG8_BAR; PG8_MMA(1, 1, At, B1); PG8_BAR;
;             PG8_LDB(B0, 1, 0); PG8_SCHED; PG8_LDA(At, 1, 0); PG8_STAGE(PG8_SA(0, 1), a2 + hstep, voffA);
	s_waitcnt lgkmcnt(0)
	v_mfma_f32_16x16x32_bf16 v[116:119], v[202:205], v[166:169], v[116:119]
	v_mfma_f32_16x16x32_bf16 v[112:115], v[210:213], v[166:169], v[112:115]
	v_mfma_f32_16x16x32_bf16 v[100:103], v[202:205], v[174:177], v[100:103]
	v_mfma_f32_16x16x32_bf16 v[96:99], v[210:213], v[174:177], v[96:99]
	v_mfma_f32_16x16x32_bf16 v[84:87], v[202:205], v[182:185], v[84:87]
	v_mfma_f32_16x16x32_bf16 v[80:83], v[210:213], v[182:185], v[80:83]
	v_mfma_f32_16x16x32_bf16 v[68:71], v[202:205], v[190:193], v[68:71]
	v_mfma_f32_16x16x32_bf16 v[64:67], v[210:213], v[190:193], v[64:67]
	v_mfma_f32_16x16x32_bf16 v[116:119], v[206:209], v[170:173], v[116:119]
	v_mfma_f32_16x16x32_bf16 v[112:115], v[214:217], v[170:173], v[112:115]
	v_mfma_f32_16x16x32_bf16 v[100:103], v[206:209], v[178:181], v[100:103]
	v_mfma_f32_16x16x32_bf16 v[96:99], v[214:217], v[178:181], v[96:99]
	v_mfma_f32_16x16x32_bf16 v[84:87], v[206:209], v[186:189], v[84:87]
	v_mfma_f32_16x16x32_bf16 v[80:83], v[214:217], v[186:189], v[80:83]
	v_mfma_f32_16x16x32_bf16 v[68:71], v[206:209], v[194:197], v[68:71]
	v_mfma_f32_16x16x32_bf16 v[64:67], v[214:217], v[194:197], v[64:67]
	s_barrier
	s_setprio 0
	s_mov_b32 m0, s33
	v_lshl_add_u64 v[218:219], s[24:25], 0, v[128:129]
	ds_read_b128 v[166:169], v150 offset:16384
	ds_read_b128 v[170:173], v150 offset:17408
	ds_read_b128 v[174:177], v150 offset:18432
	ds_read_b128 v[178:181], v150 offset:19456
	ds_read_b128 v[182:185], v150 offset:20480
	ds_read_b128 v[186:189], v150 offset:21504
	ds_read_b128 v[190:193], v150 offset:22528
	ds_read_b128 v[194:197], v150 offset:23552
	global_load_lds_dwordx4 v128, s[24:25]
	v_lshl_add_u64 v[220:221], s[24:25], 0, v[132:133]
	s_mov_b32 m0, s34
	s_nop 0
	global_load_lds_dwordx4 v132, s[24:25]
	s_setprio 1
	s_barrier
	s_waitcnt lgkmcnt(0)
	v_mfma_f32_16x16x32_bf16 v[60:63], v[140:143], v[166:169], v[60:63]
	v_mfma_f32_16x16x32_bf16 v[56:59], v[158:161], v[166:169], v[56:59]
	v_mfma_f32_16x16x32_bf16 v[44:47], v[140:143], v[174:177], v[44:47]
	v_mfma_f32_16x16x32_bf16 v[40:43], v[158:161], v[174:177], v[40:43]
	v_mfma_f32_16x16x32_bf16 v[28:31], v[140:143], v[182:185], v[28:31]
	v_mfma_f32_16x16x32_bf16 v[24:27], v[158:161], v[182:185], v[24:27]
	v_mfma_f32_16x16x32_bf16 v[12:15], v[140:143], v[190:193], v[12:15]
	v_mfma_f32_16x16x32_bf16 v[8:11], v[158:161], v[190:193], v[8:11]
	v_mfma_f32_16x16x32_bf16 v[60:63], v[154:157], v[170:173], v[60:63]
	v_mfma_f32_16x16x32_bf16 v[56:59], v[162:165], v[170:173], v[56:59]
	v_mfma_f32_16x16x32_bf16 v[44:47], v[154:157], v[178:181], v[44:47]
	v_mfma_f32_16x16x32_bf16 v[40:43], v[162:165], v[178:181], v[40:43]
	v_mfma_f32_16x16x32_bf16 v[28:31], v[154:157], v[186:189], v[28:31]
	v_mfma_f32_16x16x32_bf16 v[24:27], v[162:165], v[186:189], v[24:27]
	v_mfma_f32_16x16x32_bf16 v[12:15], v[154:157], v[194:197], v[12:15]
	v_mfma_f32_16x16x32_bf16 v[8:11], v[162:165], v[194:197], v[8:11]
	s_barrier
	s_setprio 0
	s_add_u32 s62, s4, 0x40000
	s_addc_u32 s63, s5, 0
	s_add_i32 s64, s48, s31
	s_mov_b32 m0, s64
	s_nop 0
	global_load_lds_dwordx4 v130, s[62:63]
	s_add_i32 m0, s64, 0x2000
	s_nop 0
	global_load_lds_dwordx4 v134, s[62:63]
	s_add_u32 s24, s24, 0x40000
	s_addc_u32 s25, s25, 0
	s_mov_b32 m0, s35
	s_nop 0
	global_load_lds_dwordx4 v128, s[24:25]
	s_mov_b32 m0, s36
	s_nop 0
	global_load_lds_dwordx4 v132, s[24:25]
	s_waitcnt vmcnt(10)
	s_setprio 1
	s_barrier
	v_mfma_f32_16x16x32_bf16 v[52:55], v[202:205], v[166:169], v[52:55]
	v_mfma_f32_16x16x32_bf16 v[48:51], v[210:213], v[166:169], v[48:51]
	v_mfma_f32_16x16x32_bf16 v[36:39], v[202:205], v[174:177], v[36:39]
	v_mfma_f32_16x16x32_bf16 v[32:35], v[210:213], v[174:177], v[32:35]
	v_mfma_f32_16x16x32_bf16 v[20:23], v[202:205], v[182:185], v[20:23]
	v_mfma_f32_16x16x32_bf16 v[16:19], v[210:213], v[182:185], v[16:19]
	v_mfma_f32_16x16x32_bf16 v[4:7], v[202:205], v[190:193], v[4:7]
	v_mfma_f32_16x16x32_bf16 v[0:3], v[210:213], v[190:193], v[0:3]
	v_mfma_f32_16x16x32_bf16 v[52:55], v[206:209], v[170:173], v[52:55]
	v_mfma_f32_16x16x32_bf16 v[48:51], v[214:217], v[170:173], v[48:51]
	v_mfma_f32_16x16x32_bf16 v[36:39], v[206:209], v[178:181], v[36:39]
	v_mfma_f32_16x16x32_bf16 v[32:35], v[214:217], v[178:181], v[32:35]
	v_mfma_f32_16x16x32_bf16 v[20:23], v[206:209], v[186:189], v[20:23]
	v_mfma_f32_16x16x32_bf16 v[16:19], v[214:217], v[186:189], v[16:19]
	v_mfma_f32_16x16x32_bf16 v[4:7], v[206:209], v[194:197], v[4:7]
	v_mfma_f32_16x16x32_bf16 v[0:3], v[214:217], v[194:197], v[0:3]
	s_barrier
	s_setprio 0
	s_add_i32 s62, 0, 0x18000
	ds_read_b128 v[140:143], v151 offset:16384
	ds_read_b128 v[154:157], v151 offset:17408
	ds_read_b128 v[158:161], v151 offset:18432
	ds_read_b128 v[162:165], v151 offset:19456
	ds_read_b128 v[166:169], v150 offset:32768
	ds_read_b128 v[170:173], v150 offset:33792
	ds_read_b128 v[174:177], v150 offset:34816
	ds_read_b128 v[178:181], v150 offset:35840
	ds_read_b128 v[182:185], v150 offset:36864
	ds_read_b128 v[186:189], v150 offset:37888
	ds_read_b128 v[190:193], v150 offset:38912
	ds_read_b128 v[194:197], v150 offset:39936
	s_waitcnt lgkmcnt(8)
	s_waitcnt vmcnt(8)
	s_setprio 1
	s_barrier
; #define PG8_STAGE(bufoff, gbase, voff) do { _Pragma("unroll") for (int _i = 0; _i < 2; ++_i) \
;         __builtin_amdgcn_global_load_lds((const unsigned*)((const char*)(gbase) + (voff)[_i]), (LAS unsigned*)(lds + (bufoff) + ldsw + _i * 8192), 16, 0, 0); } while (0)
; #define PG8_LDA(dst, b, h) do { _Pragma("unroll") for (int m = 0; m < 4; ++m) _Pragma("unroll") for (int k = 0; k < 2; ++k) dst[m][k] = *(const LAS bf16x8*)(lds + PG8_SA(b, h) + aoff + m * 2048 + k * 1024); } while (0)
; #define PG8_LDB(dst, b, h) do { _Pragma("unroll") for (int n = 0; n < 2; ++n) _Pragma("unroll") for (int k = 0; k < 2; ++k) dst[n][k] = *(const LAS bf16x8*)(lds + PG8_SB(b, h) + boff + n * 2048 + k * 1024); } while (0)
; #define PG8_MMA(ai, bj, At, Bt) do { __builtin_amdgcn_s_setprio(1); _Pragma("unroll") for (int m = 0; m < 4; ++m) _Pragma("unroll") for (int n = 0; n < 2; ++n) _Pragma("unroll") for (int k = 0; k < 2; ++k) \
;         acc[ai][bj][m][n] = __builtin_amdgcn_mfma_f32_16x16x32_bf16(Bt[n][k], At[m][k], acc[ai][bj][m][n], 0, 0, 0); __builtin_amdgcn_s_setprio(0); } while (0)
; #define PG8_WAIT_V(n) asm volatile("s_waitcnt vmcnt(" #n ")" ::: "memory")
; #define PG8_WAIT_L(n) asm volatile("s_waitcnt lgkmcnt(" #n ")" ::: "memory")
; #define PG8_BAR __builtin_amdgcn_s_barrier()
; #define PG8_SCHED __builtin_amdgcn_sched_barrier(0)
; template <class Epi, class Sched>
; __device__ __forceinline__ void gemm_phase(LAS unsigned char* lds, const Gemm g, const Sched& S, const Epi& E) {
;     ...
;             PG8_WAIT_L(8); PG8_BAR; PG8_WAIT_L(0); PG8_MMA(0, 0, At, B0); PG8_BAR; PG8_SCHED;
;             PG8_LDB(B1, 1, 1); PG8_STAGE(PG8_SB(1, 0), b3, voffB);
;             PG8_BAR; PG8_WAIT_L(0); PG8_MMA(0, 1, At, B1); PG8_BAR;
;             PG8_LDA(At, 1, 1); PG8_STAGE(PG8_SA(1, 0), a3, voffA);
;             PG8_BAR; PG8_WAIT_L(0); PG8_MMA(1, 0, At, B0); PG8_BAR; PG8_SCHED;
;             PG8_STAGE(PG8_SB(1, 1), b3 + hstep, voffB);
;             PG8_WAIT_V(6); PG8_BAR; PG8_MMA(1, 1, At, B1); PG8_BAR;
	s_waitcnt lgkmcnt(0)
	v_mfma_f32_16x16x32_bf16 v[124:127], v[140:143], v[166:169], v[124:127]
	v_mfma_f32_16x16x32_bf16 v[120:123], v[158:161], v[166:169], v[120:123]
	v_mfma_f32_16x16x32_bf16 v[108:111], v[140:143], v[174:177], v[108:111]
	v_mfma_f32_16x16x32_bf16 v[104:107], v[158:161], v[174:177], v[104:107]
	v_mfma_f32_16x16x32_bf16 v[92:95], v[140:143], v[182:185], v[92:95]
	v_mfma_f32_16x16x32_bf16 v[88:91], v[158:161], v[182:185], v[88:91]
	v_mfma_f32_16x16x32_bf16 v[76:79], v[140:143], v[190:193], v[76:79]
	v_mfma_f32_16x16x32_bf16 v[72:75], v[158:161], v[190:193], v[72:75]
	v_mfma_f32_16x16x32_bf16 v[124:127], v[154:157], v[170:173], v[124:127]
	v_mfma_f32_16x16x32_bf16 v[120:123], v[162:165], v[170:173], v[120:123]
	v_mfma_f32_16x16x32_bf16 v[108:111], v[154:157], v[178:181], v[108:111]
	v_mfma_f32_16x16x32_bf16 v[104:107], v[162:165], v[178:181], v[104:107]
	v_mfma_f32_16x16x32_bf16 v[92:95], v[154:157], v[186:189], v[92:95]
	v_mfma_f32_16x16x32_bf16 v[88:91], v[162:165], v[186:189], v[88:91]
	v_mfma_f32_16x16x32_bf16 v[76:79], v[154:157], v[194:197], v[76:79]
	v_mfma_f32_16x16x32_bf16 v[72:75], v[162:165], v[194:197], v[72:75]
	s_barrier
	s_setprio 0
	s_add_i32 s24, 0, 0x1c000
	s_add_i32 s25, s62, s31
	s_add_u32 s0, s4, 0x80
	s_addc_u32 s1, s5, 0
	s_mov_b32 m0, s25
	ds_read_b128 v[202:205], v151 offset:32768
	ds_read_b128 v[206:209], v151 offset:33792
	ds_read_b128 v[210:213], v151 offset:34816
	ds_read_b128 v[214:217], v151 offset:35840
	global_load_lds_dwordx4 v130, s[0:1]
	s_add_i32 m0, s25, 0x2000
	s_nop 0
	global_load_lds_dwordx4 v134, s[0:1]
	s_waitcnt vmcnt(8)
	s_setprio 1
	s_barrier
	s_waitcnt lgkmcnt(0)
	v_mfma_f32_16x16x32_bf16 v[116:119], v[202:205], v[166:169], v[116:119]
	v_mfma_f32_16x16x32_bf16 v[112:115], v[210:213], v[166:169], v[112:115]
	v_mfma_f32_16x16x32_bf16 v[100:103], v[202:205], v[174:177], v[100:103]
	v_mfma_f32_16x16x32_bf16 v[96:99], v[210:213], v[174:177], v[96:99]
	v_mfma_f32_16x16x32_bf16 v[84:87], v[202:205], v[182:185], v[84:87]
	v_mfma_f32_16x16x32_bf16 v[80:83], v[210:213], v[182:185], v[80:83]
	v_mfma_f32_16x16x32_bf16 v[68:71], v[202:205], v[190:193], v[68:71]
	v_mfma_f32_16x16x32_bf16 v[64:67], v[210:213], v[190:193], v[64:67]
	v_mfma_f32_16x16x32_bf16 v[116:119], v[206:209], v[170:173], v[116:119]
	v_mfma_f32_16x16x32_bf16 v[112:115], v[214:217], v[170:173], v[112:115]
	v_mfma_f32_16x16x32_bf16 v[100:103], v[206:209], v[178:181], v[100:103]
	v_mfma_f32_16x16x32_bf16 v[96:99], v[214:217], v[178:181], v[96:99]
	v_mfma_f32_16x16x32_bf16 v[84:87], v[206:209], v[186:189], v[84:87]
	v_mfma_f32_16x16x32_bf16 v[80:83], v[214:217], v[186:189], v[80:83]
	v_mfma_f32_16x16x32_bf16 v[68:71], v[206:209], v[194:197], v[68:71]
	v_mfma_f32_16x16x32_bf16 v[64:67], v[214:217], v[194:197], v[64:67]
	s_barrier
	s_setprio 0
	s_mov_b32 m0, s44
	s_mov_b64 s[0:1], 0x80
	v_lshl_add_u64 v[144:145], v[218:219], 0, s[0:1]
	ds_read_b128 v[166:169], v150 offset:49152
	ds_read_b128 v[170:173], v150 offset:50176
	ds_read_b128 v[174:177], v150 offset:51200
	ds_read_b128 v[178:181], v150 offset:52224
	ds_read_b128 v[182:185], v150 offset:53248
	ds_read_b128 v[186:189], v150 offset:54272
	ds_read_b128 v[190:193], v150 offset:55296
	ds_read_b128 v[194:197], v150 offset:56320
	global_load_lds_dwordx4 v[144:145], off
	v_lshl_add_u64 v[144:145], v[220:221], 0, s[0:1]
	s_mov_b32 m0, s45
	s_nop 0
	global_load_lds_dwordx4 v[144:145], off
	s_setprio 1
	s_barrier
	s_waitcnt lgkmcnt(0)
	v_mfma_f32_16x16x32_bf16 v[60:63], v[140:143], v[166:169], v[60:63]
	v_mfma_f32_16x16x32_bf16 v[56:59], v[158:161], v[166:169], v[56:59]
	v_mfma_f32_16x16x32_bf16 v[44:47], v[140:143], v[174:177], v[44:47]
	v_mfma_f32_16x16x32_bf16 v[40:43], v[158:161], v[174:177], v[40:43]
	v_mfma_f32_16x16x32_bf16 v[28:31], v[140:143], v[182:185], v[28:31]
	v_mfma_f32_16x16x32_bf16 v[24:27], v[158:161], v[182:185], v[24:27]
	v_mfma_f32_16x16x32_bf16 v[12:15], v[140:143], v[190:193], v[12:15]
	v_mfma_f32_16x16x32_bf16 v[8:11], v[158:161], v[190:193], v[8:11]
	v_mfma_f32_16x16x32_bf16 v[60:63], v[154:157], v[170:173], v[60:63]
	v_mfma_f32_16x16x32_bf16 v[56:59], v[162:165], v[170:173], v[56:59]
	v_mfma_f32_16x16x32_bf16 v[44:47], v[154:157], v[178:181], v[44:47]
	v_mfma_f32_16x16x32_bf16 v[40:43], v[162:165], v[178:181], v[40:43]
	v_mfma_f32_16x16x32_bf16 v[28:31], v[154:157], v[186:189], v[28:31]
	v_mfma_f32_16x16x32_bf16 v[24:27], v[162:165], v[186:189], v[24:27]
	v_mfma_f32_16x16x32_bf16 v[12:15], v[154:157], v[194:197], v[12:15]
	v_mfma_f32_16x16x32_bf16 v[8:11], v[162:165], v[194:197], v[8:11]
	s_barrier
	s_setprio 0
	s_add_u32 s4, s4, 0x40080
	s_addc_u32 s5, s5, 0
	s_add_i32 s24, s24, s31
	s_mov_b32 m0, s24
	s_nop 0
	global_load_lds_dwordx4 v130, s[4:5]
	s_add_i32 m0, s24, 0x2000
	s_nop 0
	global_load_lds_dwordx4 v134, s[4:5]
	s_waitcnt vmcnt(8)
	s_setprio 1
	s_barrier
	v_mfma_f32_16x16x32_bf16 v[52:55], v[202:205], v[166:169], v[52:55]
	v_mfma_f32_16x16x32_bf16 v[48:51], v[210:213], v[166:169], v[48:51]
	v_mfma_f32_16x16x32_bf16 v[36:39], v[202:205], v[174:177], v[36:39]
	v_mfma_f32_16x16x32_bf16 v[32:35], v[210:213], v[174:177], v[32:35]
	v_mfma_f32_16x16x32_bf16 v[20:23], v[202:205], v[182:185], v[20:23]
	v_mfma_f32_16x16x32_bf16 v[16:19], v[210:213], v[182:185], v[16:19]
	v_mfma_f32_16x16x32_bf16 v[4:7], v[202:205], v[190:193], v[4:7]
	v_mfma_f32_16x16x32_bf16 v[0:3], v[210:213], v[190:193], v[0:3]
	v_mfma_f32_16x16x32_bf16 v[52:55], v[206:209], v[170:173], v[52:55]
	v_mfma_f32_16x16x32_bf16 v[48:51], v[214:217], v[170:173], v[48:51]
	v_mfma_f32_16x16x32_bf16 v[36:39], v[206:209], v[178:181], v[36:39]
	v_mfma_f32_16x16x32_bf16 v[32:35], v[214:217], v[178:181], v[32:35]
	v_mfma_f32_16x16x32_bf16 v[20:23], v[206:209], v[186:189], v[20:23]
	v_mfma_f32_16x16x32_bf16 v[16:19], v[214:217], v[186:189], v[16:19]
	v_mfma_f32_16x16x32_bf16 v[4:7], v[206:209], v[194:197], v[4:7]
	v_mfma_f32_16x16x32_bf16 v[0:3], v[214:217], v[194:197], v[0:3]
	s_barrier
;     __device__ __forceinline__ void operator()(const AccT& acc, const Unit& u, int wr, int wc, int fr, int fq) const {
;         asm volatile("" : "+v"(fr), "+v"(fq));
;         const int rbase = wr * 64 + fr;
;         const int tb = u.pn * 256 + wc * 32 + 8 * fq;
;         const int o0 = wc * 32 + 8 * fq;
;         const int j = fr & 3; const float sgn = ((fr >> 2) & 1) ? 1.0f : -1.0f;
; #pragma unroll
;         for (int ai = 0; ai < 2; ++ai) {
;             const int hh = 2 * ai + wr;
;             const float l2f = lgd[hh] * 1.4426950408889634f, l2b = lgd[4 + hh] * 1.4426950408889634f;
;             const float zf0 = exp2f((float)(127 - o0) * l2f), zfs = exp2f(-l2f), zb0 = exp2f((float)o0 * l2b), zbs = exp2f(l2b);
; #pragma unroll
;             for (int m = 0; m < 4; ++m) {
;                 const int r = rbase + ai * 128 + m * 16;
;                 const int d = 4 * (2 * m + (fr >> 3)) + j;
; #pragma unroll
;                 for (int bj = 0; bj < 2; ++bj) {
;                     const int t0 = tb + bj * 128;
;                     float v[8];
; #pragma unroll
;                     for (int jj = 0; jj < 4; ++jj) { v[jj] = acc[ai][bj][m][0][jj]; v[4 + jj] = acc[ai][bj][m][1][jj]; }
;                     if constexpr (ROPE) {
;                         const int t = t0 & 2047;
; #pragma unroll
;                         for (int hf = 0; hf < 2; ++hf) {
;                             f32x4 cs, sn;
;                             if (m < 2) { const float c1 = ropeA[(t >> 6) * 16 + d], s1 = ropeA[1024 + (t >> 6) * 16 + d]; cs = (f32x4){c1, c1, c1, c1}; sn = (f32x4){s1, s1, s1, s1}; }
;                             else { const float* cb = ropeA + 2048 + (d - 16) * 64 + (t & 63) + 4 * hf; cs = *(const f32x4*)(cb); sn = *(const f32x4*)(cb + 1024); }
; #pragma unroll
;                             for (int jj = 0; jj < 4; ++jj) { const float pr = __shfl_xor(v[4 * hf + jj], 4); v[4 * hf + jj] = v[4 * hf + jj] * cs[jj] + sgn * pr * sn[jj]; }
;                             __builtin_amdgcn_sched_barrier(0);
;                         }
;                     }
;                     float zf[8], zb[8]; zf[0] = zf0; zb[0] = zb0;
; #pragma unroll
;                     for (int jj = 1; jj < 8; ++jj) { zf[jj] = zf[jj - 1] * zfs; zb[jj] = zb[jj - 1] * zbs; }
;                     u32x4 wf, wb;
	s_setprio 0
	s_add_i32 s61, s61, 2
	s_add_u32 s2, s2, 0x100
	s_addc_u32 s3, s3, 0
	s_add_u32 s59, s59, 0x100
	s_addc_u32 s60, s60, 0
	s_cmp_gt_u32 s61, 13
	s_cbranch_scc0 .LBB0_693
	v_mov_b32_e32 v141, v147
	v_mov_b32_e32 v140, v146
	global_load_dword v156, v131, s[6:7]
	global_load_dword v157, v131, s[6:7] offset:16
	s_lshl_b32 s2, s56, 8
	s_or_b32 s2, s2, s43
	v_add_u32_e32 v140, s42, v140
	v_lshlrev_b32_e32 v141, 3, v141
	v_add_u32_e32 v142, s2, v141
	v_add_u32_e32 v143, s43, v141
	v_ashrrev_i32_e32 v141, 31, v140
	v_sub_u32_e32 v144, 0x7f, v143
	v_lshlrev_b64 v[140:141], 14, v[140:141]
	v_cvt_f32_i32_e32 v154, v143
	v_ashrrev_i32_e32 v143, 31, v142
	v_cvt_f32_i32_e32 v155, v144
	v_lshl_add_u64 v[140:141], s[70:71], 0, v[140:141]
	s_mov_b32 s3, 0x400000
	v_lshl_add_u64 v[140:141], v[142:143], 1, v[140:141]
	v_add_co_u32_e32 v144, vcc, s3, v140
	s_mov_b64 s[4:5], 0x400000
	s_nop 0
	v_addc_co_u32_e32 v145, vcc, 0, v141, vcc
	v_lshl_add_u64 v[142:143], v[140:141], 0, s[4:5]
	s_waitcnt vmcnt(0)
	v_mul_f32_e32 v158, 0x3fb8aa3b, v156
	v_mul_f32_e32 v159, 0x3fb8aa3b, v157
	v_mul_f32_e32 v160, v158, v155
	v_cmp_lt_f32_e32 vcc, s51, v158
	v_mul_f32_e32 v162, v159, v154
	v_cmp_gt_f32_e64 s[2:3], s49, v159
	v_cndmask_b32_e32 v161, 0, v153, vcc
	v_cmp_gt_f32_e64 s[4:5], s49, v160
	v_cndmask_b32_e64 v163, 0, v153, s[2:3]
	s_and_b64 s[24:25], vcc, exec
	v_cmp_gt_f32_e32 vcc, s49, v162
	v_fmac_f32_e32 v163, 0x3fb8aa3b, v157
	v_cndmask_b32_e64 v157, 0, v153, s[4:5]
	v_cndmask_b32_e32 v162, 0, v153, vcc
	v_fmac_f32_e32 v161, 0xbfb8aa3b, v156
	v_fmac_f32_e32 v157, v158, v155
	v_fmac_f32_e32 v162, v159, v154
	v_exp_f32_e32 v161, v161
	v_exp_f32_e32 v163, v163
	v_exp_f32_e32 v157, v157
	v_exp_f32_e32 v158, v162
	v_cndmask_b32_e64 v160, 0, v152, s[4:5]
	s_cselect_b32 s4, 0xffffffc0, 0
	s_and_b64 s[2:3], s[2:3], exec
	v_cndmask_b32_e32 v156, 0, v152, vcc
	s_cselect_b32 s2, 0xffffffc0, 0
	v_ldexp_f32 v161, v161, s4
	v_ldexp_f32 v162, v163, s2
	v_ldexp_f32 v163, v157, v160
	v_ldexp_f32 v156, v158, v156
	v_mul_f32_e32 v164, v161, v163
	v_mul_f32_e32 v157, v162, v156
	v_mul_f32_e32 v158, v124, v163
	v_mul_f32_e32 v165, v124, v156
	v_mul_f32_e32 v166, v161, v164
	v_mul_f32_e32 v124, v162, v157
	v_mul_f32_e32 v159, v125, v164
	v_mul_f32_e32 v167, v125, v157
	v_mul_f32_e32 v168, v161, v166
	v_mul_f32_e32 v125, v162, v124
	v_cvt_pk_bf16_f32 v158, v158, v159
	v_mul_f32_e32 v159, v126, v166
	v_mul_f32_e32 v169, v126, v124
	v_mul_f32_e32 v170, v161, v168
	v_mul_f32_e32 v126, v162, v125
	v_mul_f32_e32 v171, v161, v170
	v_mul_f32_e32 v172, v162, v126
	v_mul_f32_e32 v160, v127, v168
	v_mul_f32_e32 v174, v161, v171
	v_mul_f32_e32 v175, v162, v172
	v_cvt_pk_bf16_f32 v159, v159, v160
	v_mul_f32_e32 v160, v120, v170
	v_mul_f32_e32 v173, v120, v126
	v_mul_f32_e32 v120, v121, v171
	v_mul_f32_e32 v177, v161, v174
	v_mul_f32_e32 v162, v162, v175
	v_mul_f32_e32 v176, v121, v172
	v_cvt_pk_bf16_f32 v160, v160, v120
	v_mul_f32_e32 v120, v122, v174
	v_mul_f32_e32 v121, v123, v177
	v_mul_f32_e32 v123, v123, v162
	v_cvt_pk_bf16_f32 v161, v120, v121
	v_mul_f32_e32 v127, v127, v125
	v_mul_f32_e32 v178, v122, v175
	v_cvt_pk_bf16_f32 v120, v165, v167
	v_cvt_pk_bf16_f32 v121, v169, v127
	v_cvt_pk_bf16_f32 v122, v173, v176
	v_cvt_pk_bf16_f32 v123, v178, v123
	global_store_dwordx4 v[140:141], v[158:161], off
	global_store_dwordx4 v[144:145], v[120:123], off
	s_nop 1
	v_mul_f32_e32 v120, v116, v163
	v_mul_f32_e32 v121, v117, v164
	v_cvt_pk_bf16_f32 v120, v120, v121
	v_mul_f32_e32 v121, v118, v166
	v_mul_f32_e32 v122, v119, v168
	v_cvt_pk_bf16_f32 v121, v121, v122
	v_mul_f32_e32 v122, v112, v170
	v_mul_f32_e32 v123, v113, v171
	v_cvt_pk_bf16_f32 v122, v122, v123
	v_mul_f32_e32 v123, v114, v174
	v_mul_f32_e32 v116, v116, v156
	v_mul_f32_e32 v117, v117, v157
	v_mul_f32_e32 v127, v115, v177
	v_cvt_pk_bf16_f32 v123, v123, v127
	v_cvt_pk_bf16_f32 v116, v116, v117
	v_mul_f32_e32 v117, v118, v124
	v_mul_f32_e32 v118, v119, v125
	v_mul_f32_e32 v112, v112, v126
	v_mul_f32_e32 v113, v113, v172
	v_cvt_pk_bf16_f32 v117, v117, v118
	v_cvt_pk_bf16_f32 v118, v112, v113
	v_mul_f32_e32 v112, v114, v175
	v_mul_f32_e32 v113, v115, v162
	v_cvt_pk_bf16_f32 v119, v112, v113
	global_store_dwordx4 v[140:141], v[120:123], off offset:256
	global_store_dwordx4 v[142:143], v[116:119], off offset:256
	v_mul_f32_e32 v112, v108, v163
	v_mul_f32_e32 v113, v109, v164
	v_cvt_pk_bf16_f32 v112, v112, v113
	v_mul_f32_e32 v113, v110, v166
	v_mul_f32_e32 v114, v111, v168
	v_cvt_pk_bf16_f32 v113, v113, v114
	v_mul_f32_e32 v114, v104, v170
	v_mul_f32_e32 v115, v105, v171
	v_cvt_pk_bf16_f32 v114, v114, v115
	v_mul_f32_e32 v115, v106, v174
	v_mul_f32_e32 v108, v108, v156
	v_mul_f32_e32 v109, v109, v157
	v_mul_f32_e32 v116, v107, v177
	v_cvt_pk_bf16_f32 v115, v115, v116
	v_cvt_pk_bf16_f32 v108, v108, v109
	v_mul_f32_e32 v109, v110, v124
	v_mul_f32_e32 v110, v111, v125
	v_mul_f32_e32 v104, v104, v126
	s_mov_b64 s[2:3], 0x40000
	v_cvt_pk_bf16_f32 v109, v109, v110
	v_mul_f32_e32 v105, v105, v172
	v_cvt_pk_bf16_f32 v110, v104, v105
	v_mul_f32_e32 v104, v106, v175
	v_lshl_add_u64 v[116:117], v[140:141], 0, s[2:3]
	s_mov_b32 s2, 0x40000
	v_mul_f32_e32 v105, v107, v162
	v_cvt_pk_bf16_f32 v111, v104, v105
	v_add_co_u32_e32 v104, vcc, s2, v140
	s_mov_b64 s[2:3], 0x440000
	s_nop 0
	v_addc_co_u32_e32 v105, vcc, 0, v141, vcc
	global_store_dwordx4 v[104:105], v[112:115], off
	s_nop 1
	v_lshl_add_u64 v[112:113], v[140:141], 0, s[2:3]
	s_mov_b32 s2, 0x440000
	v_add_co_u32_e32 v104, vcc, s2, v140
	s_nop 1
	v_addc_co_u32_e32 v105, vcc, 0, v141, vcc
	global_store_dwordx4 v[104:105], v[108:111], off
	v_mul_f32_e32 v104, v100, v163
	v_mul_f32_e32 v105, v101, v164
;     __device__ __forceinline__ void operator()(const AccT& acc, const Unit& u, int wr, int wc, int fr, int fq) const {
;     ...
;         for (int ai = 0; ai < 2; ++ai) {
;             const int hh = 2 * ai + wr;
;             const float l2f = lgd[hh] * 1.4426950408889634f, l2b = lgd[4 + hh] * 1.4426950408889634f;
;             const float zf0 = exp2f((float)(127 - o0) * l2f), zfs = exp2f(-l2f), zb0 = exp2f((float)o0 * l2b), zbs = exp2f(l2b);
; #pragma unroll
;             for (int m = 0; m < 4; ++m) {
;                 const int r = rbase + ai * 128 + m * 16;
;                 const int d = 4 * (2 * m + (fr >> 3)) + j;
; #pragma unroll
;                 for (int bj = 0; bj < 2; ++bj) {
;                     const int t0 = tb + bj * 128;
;                     float v[8];
; #pragma unroll
;                     for (int jj = 0; jj < 4; ++jj) { v[jj] = acc[ai][bj][m][0][jj]; v[4 + jj] = acc[ai][bj][m][1][jj]; }
;                     if constexpr (ROPE) {
;                         const int t = t0 & 2047;
; #pragma unroll
;                         for (int hf = 0; hf < 2; ++hf) {
;                             f32x4 cs, sn;
;                             if (m < 2) { const float c1 = ropeA[(t >> 6) * 16 + d], s1 = ropeA[1024 + (t >> 6) * 16 + d]; cs = (f32x4){c1, c1, c1, c1}; sn = (f32x4){s1, s1, s1, s1}; }
;                             else { const float* cb = ropeA + 2048 + (d - 16) * 64 + (t & 63) + 4 * hf; cs = *(const f32x4*)(cb); sn = *(const f32x4*)(cb + 1024); }
; #pragma unroll
;                             for (int jj = 0; jj < 4; ++jj) { const float pr = __shfl_xor(v[4 * hf + jj], 4); v[4 * hf + jj] = v[4 * hf + jj] * cs[jj] + sgn * pr * sn[jj]; }
;                             __builtin_amdgcn_sched_barrier(0);
;                         }
;                     }
;                     float zf[8], zb[8]; zf[0] = zf0; zb[0] = zb0;
; #pragma unroll
;                     for (int jj = 1; jj < 8; ++jj) { zf[jj] = zf[jj - 1] * zfs; zb[jj] = zb[jj - 1] * zbs; }
;                     u32x4 wf, wb;
;                     wf.x = cvt_pk_bf16(v[0] * zf[0], v[1] * zf[1]); wf.y = cvt_pk_bf16(v[2] * zf[2], v[3] * zf[3]); wf.z = cvt_pk_bf16(v[4] * zf[4], v[5] * zf[5]); wf.w = cvt_pk_bf16(v[6] * zf[6], v[7] * zf[7]);
	v_cvt_pk_bf16_f32 v104, v104, v105
	v_mul_f32_e32 v105, v102, v166
	v_mul_f32_e32 v106, v103, v168
	v_cvt_pk_bf16_f32 v105, v105, v106
	v_mul_f32_e32 v106, v96, v170
	v_mul_f32_e32 v107, v97, v171
	v_cvt_pk_bf16_f32 v106, v106, v107
	v_mul_f32_e32 v107, v98, v174
	v_mul_f32_e32 v100, v100, v156
	v_mul_f32_e32 v101, v101, v157
	v_mul_f32_e32 v108, v99, v177
	v_cvt_pk_bf16_f32 v107, v107, v108
	v_cvt_pk_bf16_f32 v100, v100, v101
	v_mul_f32_e32 v101, v102, v124
	v_mul_f32_e32 v102, v103, v125
	v_mul_f32_e32 v96, v96, v126
	v_mul_f32_e32 v97, v97, v172
	v_cvt_pk_bf16_f32 v101, v101, v102
	v_cvt_pk_bf16_f32 v102, v96, v97
	v_mul_f32_e32 v96, v98, v175
	v_mul_f32_e32 v97, v99, v162
	v_cvt_pk_bf16_f32 v103, v96, v97
	global_store_dwordx4 v[116:117], v[104:107], off offset:256
	global_store_dwordx4 v[112:113], v[100:103], off offset:256
	v_mul_f32_e32 v96, v92, v163
	v_mul_f32_e32 v97, v93, v164
	v_cvt_pk_bf16_f32 v96, v96, v97
	v_mul_f32_e32 v97, v94, v166
	v_mul_f32_e32 v98, v95, v168
	v_cvt_pk_bf16_f32 v97, v97, v98
	v_mul_f32_e32 v98, v88, v170
	v_mul_f32_e32 v99, v89, v171
	v_cvt_pk_bf16_f32 v98, v98, v99
	v_mul_f32_e32 v99, v90, v174
	v_mul_f32_e32 v92, v92, v156
	v_mul_f32_e32 v93, v93, v157
	v_mul_f32_e32 v100, v91, v177
	v_cvt_pk_bf16_f32 v99, v99, v100
	v_cvt_pk_bf16_f32 v92, v92, v93
	v_mul_f32_e32 v93, v94, v124
	v_mul_f32_e32 v94, v95, v125
	v_mul_f32_e32 v88, v88, v126
	s_mov_b64 s[2:3], 0x80000
	v_cvt_pk_bf16_f32 v93, v93, v94
	v_mul_f32_e32 v89, v89, v172
	v_cvt_pk_bf16_f32 v94, v88, v89
	v_mul_f32_e32 v88, v90, v175
	v_lshl_add_u64 v[100:101], v[140:141], 0, s[2:3]
	s_mov_b32 s2, 0x80000
	v_mul_f32_e32 v89, v91, v162
	v_cvt_pk_bf16_f32 v95, v88, v89
	v_add_co_u32_e32 v88, vcc, s2, v140
	s_mov_b64 s[2:3], 0x480000
	s_nop 0
	v_addc_co_u32_e32 v89, vcc, 0, v141, vcc
	global_store_dwordx4 v[88:89], v[96:99], off
	s_nop 1
	v_lshl_add_u64 v[96:97], v[140:141], 0, s[2:3]
	s_mov_b32 s2, 0x480000
	v_add_co_u32_e32 v88, vcc, s2, v140
	s_nop 1
	v_addc_co_u32_e32 v89, vcc, 0, v141, vcc
	global_store_dwordx4 v[88:89], v[92:95], off
	v_mul_f32_e32 v88, v84, v163
	v_mul_f32_e32 v89, v85, v164
	v_cvt_pk_bf16_f32 v88, v88, v89
	v_mul_f32_e32 v89, v86, v166
	v_mul_f32_e32 v90, v87, v168
	v_cvt_pk_bf16_f32 v89, v89, v90
	v_mul_f32_e32 v90, v80, v170
	v_mul_f32_e32 v91, v81, v171
	v_cvt_pk_bf16_f32 v90, v90, v91
	v_mul_f32_e32 v91, v82, v174
	v_mul_f32_e32 v84, v84, v156
	v_mul_f32_e32 v85, v85, v157
	v_mul_f32_e32 v92, v83, v177
	v_cvt_pk_bf16_f32 v91, v91, v92
	v_cvt_pk_bf16_f32 v84, v84, v85
	v_mul_f32_e32 v85, v86, v124
	v_mul_f32_e32 v86, v87, v125
	v_mul_f32_e32 v80, v80, v126
	v_mul_f32_e32 v81, v81, v172
	v_cvt_pk_bf16_f32 v85, v85, v86
	v_cvt_pk_bf16_f32 v86, v80, v81
	v_mul_f32_e32 v80, v82, v175
	v_mul_f32_e32 v81, v83, v162
	v_cvt_pk_bf16_f32 v87, v80, v81
	global_store_dwordx4 v[100:101], v[88:91], off offset:256
	global_store_dwordx4 v[96:97], v[84:87], off offset:256
	v_mul_f32_e32 v80, v76, v163
	v_mul_f32_e32 v81, v77, v164
	v_cvt_pk_bf16_f32 v80, v80, v81
	v_mul_f32_e32 v81, v78, v166
	v_mul_f32_e32 v82, v79, v168
	v_cvt_pk_bf16_f32 v81, v81, v82
	v_mul_f32_e32 v82, v72, v170
	v_mul_f32_e32 v83, v73, v171
	v_cvt_pk_bf16_f32 v82, v82, v83
	v_mul_f32_e32 v83, v74, v174
	v_mul_f32_e32 v76, v76, v156
	v_mul_f32_e32 v77, v77, v157
	v_mul_f32_e32 v84, v75, v177
	v_cvt_pk_bf16_f32 v83, v83, v84
	v_cvt_pk_bf16_f32 v76, v76, v77
	v_mul_f32_e32 v77, v78, v124
	v_mul_f32_e32 v78, v79, v125
	v_mul_f32_e32 v72, v72, v126
	s_mov_b64 s[2:3], 0xc0000
	v_cvt_pk_bf16_f32 v77, v77, v78
	v_mul_f32_e32 v73, v73, v172
	v_cvt_pk_bf16_f32 v78, v72, v73
	v_mul_f32_e32 v72, v74, v175
	v_lshl_add_u64 v[84:85], v[140:141], 0, s[2:3]
	s_mov_b32 s2, 0xc0000
	v_mul_f32_e32 v73, v75, v162
	v_cvt_pk_bf16_f32 v79, v72, v73
	v_add_co_u32_e32 v72, vcc, s2, v140
	s_mov_b64 s[2:3], 0x4c0000
	s_nop 0
	v_addc_co_u32_e32 v73, vcc, 0, v141, vcc
	global_store_dwordx4 v[72:73], v[80:83], off
	s_nop 1
	v_lshl_add_u64 v[80:81], v[140:141], 0, s[2:3]
	s_mov_b32 s2, 0x4c0000
	v_add_co_u32_e32 v72, vcc, s2, v140
	s_nop 1
	v_addc_co_u32_e32 v73, vcc, 0, v141, vcc
	global_store_dwordx4 v[72:73], v[76:79], off
	v_mul_f32_e32 v72, v68, v163
	v_mul_f32_e32 v73, v69, v164
	v_cvt_pk_bf16_f32 v72, v72, v73
	v_mul_f32_e32 v73, v70, v166
	v_mul_f32_e32 v74, v71, v168
	v_cvt_pk_bf16_f32 v73, v73, v74
	v_mul_f32_e32 v74, v64, v170
	v_mul_f32_e32 v75, v65, v171
	v_cvt_pk_bf16_f32 v74, v74, v75
	v_mul_f32_e32 v75, v66, v174
	v_mul_f32_e32 v68, v68, v156
	v_mul_f32_e32 v69, v69, v157
	v_mul_f32_e32 v76, v67, v177
	v_cvt_pk_bf16_f32 v75, v75, v76
	v_cvt_pk_bf16_f32 v68, v68, v69
	v_mul_f32_e32 v69, v70, v124
	v_mul_f32_e32 v70, v71, v125
	v_mul_f32_e32 v64, v64, v126
	v_mul_f32_e32 v65, v65, v172
	v_cvt_pk_bf16_f32 v69, v69, v70
	v_cvt_pk_bf16_f32 v70, v64, v65
	v_mul_f32_e32 v64, v66, v175
	v_mul_f32_e32 v65, v67, v162
	v_cvt_pk_bf16_f32 v71, v64, v65
	global_store_dwordx4 v[84:85], v[72:75], off offset:256
	global_store_dwordx4 v[80:81], v[68:71], off offset:256
	global_load_dword v70, v131, s[6:7] offset:8
	s_nop 0
	global_load_dword v71, v131, s[6:7] offset:24
	s_mov_b32 s17, 0x200000
	v_add_co_u32_e32 v76, vcc, s17, v140
	s_mov_b32 s19, 0x600000
	s_nop 0
	v_addc_co_u32_e32 v77, vcc, 0, v141, vcc
	v_add_co_u32_e32 v68, vcc, s19, v140
	s_mov_b64 s[2:3], 0x200000
	s_nop 0
	v_addc_co_u32_e32 v69, vcc, 0, v141, vcc
	s_mov_b64 s[4:5], 0x600000
	v_lshl_add_u64 v[64:65], v[140:141], 0, s[2:3]
	v_lshl_add_u64 v[66:67], v[140:141], 0, s[4:5]
	s_waitcnt vmcnt(0)
;     __device__ __forceinline__ void operator()(const AccT& acc, const Unit& u, int wr, int wc, int fr, int fq) const {
;     ...
;         for (int ai = 0; ai < 2; ++ai) {
;             const int hh = 2 * ai + wr;
;             const float l2f = lgd[hh] * 1.4426950408889634f, l2b = lgd[4 + hh] * 1.4426950408889634f;
;             const float zf0 = exp2f((float)(127 - o0) * l2f), zfs = exp2f(-l2f), zb0 = exp2f((float)o0 * l2b), zbs = exp2f(l2b);
; #pragma unroll
;             for (int m = 0; m < 4; ++m) {
;                 const int r = rbase + ai * 128 + m * 16;
;                 const int d = 4 * (2 * m + (fr >> 3)) + j;
; #pragma unroll
;                 for (int bj = 0; bj < 2; ++bj) {
;                     const int t0 = tb + bj * 128;
;                     float v[8];
; #pragma unroll
;                     for (int jj = 0; jj < 4; ++jj) { v[jj] = acc[ai][bj][m][0][jj]; v[4 + jj] = acc[ai][bj][m][1][jj]; }
;                     if constexpr (ROPE) {
;                         const int t = t0 & 2047;
; #pragma unroll
;                         for (int hf = 0; hf < 2; ++hf) {
;                             f32x4 cs, sn;
;                             if (m < 2) { const float c1 = ropeA[(t >> 6) * 16 + d], s1 = ropeA[1024 + (t >> 6) * 16 + d]; cs = (f32x4){c1, c1, c1, c1}; sn = (f32x4){s1, s1, s1, s1}; }
;                             else { const float* cb = ropeA + 2048 + (d - 16) * 64 + (t & 63) + 4 * hf; cs = *(const f32x4*)(cb); sn = *(const f32x4*)(cb + 1024); }
; #pragma unroll
;                             for (int jj = 0; jj < 4; ++jj) { const float pr = __shfl_xor(v[4 * hf + jj], 4); v[4 * hf + jj] = v[4 * hf + jj] * cs[jj] + sgn * pr * sn[jj]; }
;                             __builtin_amdgcn_sched_barrier(0);
;                         }
;                     }
;                     float zf[8], zb[8]; zf[0] = zf0; zb[0] = zb0;
; #pragma unroll
;                     for (int jj = 1; jj < 8; ++jj) { zf[jj] = zf[jj - 1] * zfs; zb[jj] = zb[jj - 1] * zbs; }
;                     u32x4 wf, wb;
;                     wf.x = cvt_pk_bf16(v[0] * zf[0], v[1] * zf[1]); wf.y = cvt_pk_bf16(v[2] * zf[2], v[3] * zf[3]); wf.z = cvt_pk_bf16(v[4] * zf[4], v[5] * zf[5]); wf.w = cvt_pk_bf16(v[6] * zf[6], v[7] * zf[7]);
	v_mul_f32_e32 v72, 0x3fb8aa3b, v70
	v_mul_f32_e32 v73, 0x3fb8aa3b, v71
	v_mul_f32_e32 v74, v72, v155
	v_cmp_lt_f32_e32 vcc, s51, v72
	v_mul_f32_e32 v78, v73, v154
	v_cmp_gt_f32_e64 s[2:3], s49, v73
	v_cndmask_b32_e32 v75, 0, v153, vcc
	v_cmp_gt_f32_e64 s[4:5], s49, v74
	v_cndmask_b32_e64 v79, 0, v153, s[2:3]
	s_and_b64 s[24:25], vcc, exec
	v_cmp_gt_f32_e32 vcc, s49, v78
	v_fmac_f32_e32 v79, 0x3fb8aa3b, v71
	v_cndmask_b32_e64 v71, 0, v153, s[4:5]
	v_cndmask_b32_e32 v78, 0, v153, vcc
	v_fmac_f32_e32 v75, 0xbfb8aa3b, v70
	v_fmac_f32_e32 v71, v72, v155
	v_fmac_f32_e32 v78, v73, v154
	v_exp_f32_e32 v75, v75
	v_exp_f32_e32 v79, v79
	v_exp_f32_e32 v71, v71
	v_exp_f32_e32 v72, v78
	v_cndmask_b32_e64 v74, 0, v152, s[4:5]
	s_cselect_b32 s4, 0xffffffc0, 0
	s_and_b64 s[2:3], s[2:3], exec
	v_cndmask_b32_e32 v70, 0, v152, vcc
	s_cselect_b32 s2, 0xffffffc0, 0
	v_ldexp_f32 v75, v75, s4
	v_ldexp_f32 v78, v79, s2
	v_ldexp_f32 v79, v71, v74
	v_ldexp_f32 v70, v72, v70
	v_mul_f32_e32 v80, v75, v79
	v_mul_f32_e32 v71, v78, v70
	v_mul_f32_e32 v72, v60, v79
	v_mul_f32_e32 v81, v60, v70
	v_mul_f32_e32 v82, v75, v80
	v_mul_f32_e32 v60, v78, v71
	v_mul_f32_e32 v83, v75, v82
	v_mul_f32_e32 v84, v78, v60
	v_mul_f32_e32 v85, v75, v83
	v_mul_f32_e32 v86, v78, v84
	v_mul_f32_e32 v73, v61, v80
	v_mul_f32_e32 v87, v75, v85
	v_mul_f32_e32 v88, v78, v86
	v_cvt_pk_bf16_f32 v72, v72, v73
	v_mul_f32_e32 v73, v62, v82
	v_mul_f32_e32 v74, v63, v83
	v_mul_f32_e32 v90, v75, v87
	v_mul_f32_e32 v91, v78, v88
	v_cvt_pk_bf16_f32 v73, v73, v74
	v_mul_f32_e32 v74, v56, v85
	v_mul_f32_e32 v89, v56, v86
	v_mul_f32_e32 v56, v57, v87
	v_mul_f32_e32 v93, v75, v90
	v_mul_f32_e32 v78, v78, v91
	v_mul_f32_e32 v92, v57, v88
	v_cvt_pk_bf16_f32 v74, v74, v56
	v_mul_f32_e32 v56, v58, v90
	v_mul_f32_e32 v57, v59, v93
	v_mul_f32_e32 v59, v59, v78
	v_cvt_pk_bf16_f32 v75, v56, v57
	v_mul_f32_e32 v61, v61, v71
	v_mul_f32_e32 v62, v62, v60
	v_mul_f32_e32 v63, v63, v84
	v_mul_f32_e32 v94, v58, v91
	v_cvt_pk_bf16_f32 v56, v81, v61
	v_cvt_pk_bf16_f32 v57, v62, v63
	v_cvt_pk_bf16_f32 v58, v89, v92
	v_cvt_pk_bf16_f32 v59, v94, v59
	global_store_dwordx4 v[76:77], v[72:75], off
	global_store_dwordx4 v[68:69], v[56:59], off
	s_nop 1
	v_mul_f32_e32 v56, v52, v79
	v_mul_f32_e32 v57, v53, v80
	v_cvt_pk_bf16_f32 v56, v56, v57
	v_mul_f32_e32 v57, v54, v82
	v_mul_f32_e32 v58, v55, v83
	v_cvt_pk_bf16_f32 v57, v57, v58
	v_mul_f32_e32 v58, v48, v85
	v_mul_f32_e32 v59, v49, v87
	v_cvt_pk_bf16_f32 v58, v58, v59
	v_mul_f32_e32 v59, v50, v90
	v_mul_f32_e32 v52, v52, v70
	v_mul_f32_e32 v53, v53, v71
	v_mul_f32_e32 v61, v51, v93
	v_cvt_pk_bf16_f32 v59, v59, v61
	v_cvt_pk_bf16_f32 v52, v52, v53
	v_mul_f32_e32 v53, v54, v60
	v_mul_f32_e32 v54, v55, v84
	v_mul_f32_e32 v48, v48, v86
	v_mul_f32_e32 v49, v49, v88
	v_cvt_pk_bf16_f32 v53, v53, v54
	v_cvt_pk_bf16_f32 v54, v48, v49
	v_mul_f32_e32 v48, v50, v91
	v_mul_f32_e32 v49, v51, v78
	v_cvt_pk_bf16_f32 v55, v48, v49
	global_store_dwordx4 v[64:65], v[56:59], off offset:256
	global_store_dwordx4 v[66:67], v[52:55], off offset:256
	v_mul_f32_e32 v48, v44, v79
	v_mul_f32_e32 v49, v45, v80
	v_cvt_pk_bf16_f32 v48, v48, v49
	v_mul_f32_e32 v49, v46, v82
	v_mul_f32_e32 v50, v47, v83
	v_cvt_pk_bf16_f32 v49, v49, v50
	v_mul_f32_e32 v50, v40, v85
	v_mul_f32_e32 v51, v41, v87
	v_cvt_pk_bf16_f32 v50, v50, v51
	v_mul_f32_e32 v51, v42, v90
	v_mul_f32_e32 v44, v44, v70
	v_mul_f32_e32 v45, v45, v71
	v_mul_f32_e32 v52, v43, v93
	v_cvt_pk_bf16_f32 v51, v51, v52
	v_cvt_pk_bf16_f32 v44, v44, v45
	v_mul_f32_e32 v45, v46, v60
	v_mul_f32_e32 v46, v47, v84
	v_mul_f32_e32 v40, v40, v86
	s_mov_b64 s[2:3], 0x240000
	v_cvt_pk_bf16_f32 v45, v45, v46
	v_mul_f32_e32 v41, v41, v88
	v_cvt_pk_bf16_f32 v46, v40, v41
	v_mul_f32_e32 v40, v42, v91
	v_lshl_add_u64 v[52:53], v[140:141], 0, s[2:3]
	s_mov_b32 s2, 0x240000
	v_mul_f32_e32 v41, v43, v78
	v_cvt_pk_bf16_f32 v47, v40, v41
	v_add_co_u32_e32 v40, vcc, s2, v140
	s_mov_b64 s[2:3], 0x640000
	s_nop 0
	v_addc_co_u32_e32 v41, vcc, 0, v141, vcc
	global_store_dwordx4 v[40:41], v[48:51], off
	s_nop 1
	v_lshl_add_u64 v[48:49], v[140:141], 0, s[2:3]
	s_mov_b32 s2, 0x640000
	v_add_co_u32_e32 v40, vcc, s2, v140
	s_nop 1
	v_addc_co_u32_e32 v41, vcc, 0, v141, vcc
	global_store_dwordx4 v[40:41], v[44:47], off
	v_mul_f32_e32 v40, v36, v79
	v_mul_f32_e32 v41, v37, v80
	v_cvt_pk_bf16_f32 v40, v40, v41
	v_mul_f32_e32 v41, v38, v82
	v_mul_f32_e32 v42, v39, v83
	v_cvt_pk_bf16_f32 v41, v41, v42
	v_mul_f32_e32 v42, v32, v85
	v_mul_f32_e32 v43, v33, v87
	v_cvt_pk_bf16_f32 v42, v42, v43
	v_mul_f32_e32 v43, v34, v90
	v_mul_f32_e32 v36, v36, v70
;     __device__ __forceinline__ void operator()(const AccT& acc, const Unit& u, int wr, int wc, int fr, int fq) const {
;     ...
;             for (int m = 0; m < 4; ++m) {
;                 const int r = rbase + ai * 128 + m * 16;
;                 const int d = 4 * (2 * m + (fr >> 3)) + j;
; #pragma unroll
;                 for (int bj = 0; bj < 2; ++bj) {
;                     const int t0 = tb + bj * 128;
;                     float v[8];
; #pragma unroll
;                     for (int jj = 0; jj < 4; ++jj) { v[jj] = acc[ai][bj][m][0][jj]; v[4 + jj] = acc[ai][bj][m][1][jj]; }
;                     if constexpr (ROPE) {
;                         const int t = t0 & 2047;
; #pragma unroll
;                         for (int hf = 0; hf < 2; ++hf) {
;                             f32x4 cs, sn;
;                             if (m < 2) { const float c1 = ropeA[(t >> 6) * 16 + d], s1 = ropeA[1024 + (t >> 6) * 16 + d]; cs = (f32x4){c1, c1, c1, c1}; sn = (f32x4){s1, s1, s1, s1}; }
;                             else { const float* cb = ropeA + 2048 + (d - 16) * 64 + (t & 63) + 4 * hf; cs = *(const f32x4*)(cb); sn = *(const f32x4*)(cb + 1024); }
; #pragma unroll
;                             for (int jj = 0; jj < 4; ++jj) { const float pr = __shfl_xor(v[4 * hf + jj], 4); v[4 * hf + jj] = v[4 * hf + jj] * cs[jj] + sgn * pr * sn[jj]; }
;                             __builtin_amdgcn_sched_barrier(0);
;                         }
;                     }
;                     float zf[8], zb[8]; zf[0] = zf0; zb[0] = zb0;
; #pragma unroll
;                     for (int jj = 1; jj < 8; ++jj) { zf[jj] = zf[jj - 1] * zfs; zb[jj] = zb[jj - 1] * zbs; }
;                     u32x4 wf, wb;
;                     wf.x = cvt_pk_bf16(v[0] * zf[0], v[1] * zf[1]); wf.y = cvt_pk_bf16(v[2] * zf[2], v[3] * zf[3]); wf.z = cvt_pk_bf16(v[4] * zf[4], v[5] * zf[5]); wf.w = cvt_pk_bf16(v[6] * zf[6], v[7] * zf[7]);
;                     wb.x = cvt_pk_bf16(v[0] * zb[0], v[1] * zb[1]); wb.y = cvt_pk_bf16(v[2] * zb[2], v[3] * zb[3]); wb.z = cvt_pk_bf16(v[4] * zb[4], v[5] * zb[5]); wb.w = cvt_pk_bf16(v[6] * zb[6], v[7] * zb[7]);
;                     *(u32x4*)(KTZ + (size_t)r * NT + t0) = wf;
;                     *(u32x4*)(KTZ + (size_t)(256 + r) * NT + t0) = wb;
;                     __builtin_amdgcn_sched_barrier(0);
;                 }
;             }
;         }
;     }
	v_mul_f32_e32 v37, v37, v71
	v_mul_f32_e32 v44, v35, v93
	v_cvt_pk_bf16_f32 v43, v43, v44
	v_cvt_pk_bf16_f32 v36, v36, v37
	v_mul_f32_e32 v37, v38, v60
	v_mul_f32_e32 v38, v39, v84
	v_mul_f32_e32 v32, v32, v86
	v_mul_f32_e32 v33, v33, v88
	v_cvt_pk_bf16_f32 v37, v37, v38
	v_cvt_pk_bf16_f32 v38, v32, v33
	v_mul_f32_e32 v32, v34, v91
	v_mul_f32_e32 v33, v35, v78
	v_cvt_pk_bf16_f32 v39, v32, v33
	global_store_dwordx4 v[52:53], v[40:43], off offset:256
	global_store_dwordx4 v[48:49], v[36:39], off offset:256
	v_mul_f32_e32 v32, v28, v79
	v_mul_f32_e32 v33, v29, v80
	v_cvt_pk_bf16_f32 v32, v32, v33
	v_mul_f32_e32 v33, v30, v82
	v_mul_f32_e32 v34, v31, v83
	v_cvt_pk_bf16_f32 v33, v33, v34
	v_mul_f32_e32 v34, v24, v85
	v_mul_f32_e32 v35, v25, v87
	v_cvt_pk_bf16_f32 v34, v34, v35
	v_mul_f32_e32 v35, v26, v90
	v_mul_f32_e32 v28, v28, v70
	v_mul_f32_e32 v29, v29, v71
	v_mul_f32_e32 v36, v27, v93
	v_cvt_pk_bf16_f32 v35, v35, v36
	v_cvt_pk_bf16_f32 v28, v28, v29
	v_mul_f32_e32 v29, v30, v60
	v_mul_f32_e32 v30, v31, v84
	v_mul_f32_e32 v24, v24, v86
	v_cvt_pk_bf16_f32 v29, v29, v30
	v_mul_f32_e32 v25, v25, v88
	v_cvt_pk_bf16_f32 v30, v24, v25
	v_mul_f32_e32 v24, v26, v91
	v_mul_f32_e32 v25, v27, v78
	v_cvt_pk_bf16_f32 v31, v24, v25
	v_add_co_u32_e32 v24, vcc, s52, v140
	s_mov_b64 s[2:3], 0x280000
	s_nop 0
	v_addc_co_u32_e32 v25, vcc, 0, v141, vcc
	global_store_dwordx4 v[24:25], v[32:35], off
	v_add_co_u32_e32 v24, vcc, s53, v140
	v_lshl_add_u64 v[36:37], v[140:141], 0, s[2:3]
	s_nop 0
	v_addc_co_u32_e32 v25, vcc, 0, v141, vcc
	v_lshl_add_u64 v[32:33], v[140:141], 0, s[8:9]
	global_store_dwordx4 v[24:25], v[28:31], off
	v_mul_f32_e32 v24, v20, v79
	v_mul_f32_e32 v25, v21, v80
	v_cvt_pk_bf16_f32 v24, v24, v25
	v_mul_f32_e32 v25, v22, v82
	v_mul_f32_e32 v26, v23, v83
	v_cvt_pk_bf16_f32 v25, v25, v26
	v_mul_f32_e32 v26, v16, v85
	v_mul_f32_e32 v27, v17, v87
	v_cvt_pk_bf16_f32 v26, v26, v27
	v_mul_f32_e32 v27, v18, v90
	v_mul_f32_e32 v20, v20, v70
	v_mul_f32_e32 v21, v21, v71
	v_mul_f32_e32 v28, v19, v93
	v_cvt_pk_bf16_f32 v27, v27, v28
	v_cvt_pk_bf16_f32 v20, v20, v21
	v_mul_f32_e32 v21, v22, v60
	v_mul_f32_e32 v22, v23, v84
	v_mul_f32_e32 v16, v16, v86
	v_mul_f32_e32 v17, v17, v88
	v_cvt_pk_bf16_f32 v21, v21, v22
	v_cvt_pk_bf16_f32 v22, v16, v17
	v_mul_f32_e32 v16, v18, v91
	v_mul_f32_e32 v17, v19, v78
	v_cvt_pk_bf16_f32 v23, v16, v17
	global_store_dwordx4 v[36:37], v[24:27], off offset:256
	global_store_dwordx4 v[32:33], v[20:23], off offset:256
	v_mul_f32_e32 v16, v12, v79
	v_mul_f32_e32 v17, v13, v80
	v_cvt_pk_bf16_f32 v16, v16, v17
	v_mul_f32_e32 v17, v14, v82
	v_mul_f32_e32 v18, v15, v83
	v_cvt_pk_bf16_f32 v17, v17, v18
	v_mul_f32_e32 v18, v8, v85
	v_mul_f32_e32 v19, v9, v87
	v_cvt_pk_bf16_f32 v18, v18, v19
	v_mul_f32_e32 v19, v10, v90
	v_mul_f32_e32 v12, v12, v70
	v_mul_f32_e32 v13, v13, v71
	v_mul_f32_e32 v20, v11, v93
	v_cvt_pk_bf16_f32 v19, v19, v20
	v_cvt_pk_bf16_f32 v12, v12, v13
	v_mul_f32_e32 v13, v14, v60
	v_mul_f32_e32 v14, v15, v84
	v_mul_f32_e32 v8, v8, v86
	v_cvt_pk_bf16_f32 v13, v13, v14
	v_mul_f32_e32 v9, v9, v88
	v_cvt_pk_bf16_f32 v14, v8, v9
	v_mul_f32_e32 v8, v10, v91
	v_mul_f32_e32 v9, v11, v78
	v_cvt_pk_bf16_f32 v15, v8, v9
	v_add_co_u32_e32 v8, vcc, s54, v140
	v_lshl_add_u64 v[20:21], v[140:141], 0, s[10:11]
	s_nop 0
	v_addc_co_u32_e32 v9, vcc, 0, v141, vcc
	global_store_dwordx4 v[8:9], v[16:19], off
	v_add_co_u32_e32 v8, vcc, s55, v140
	s_nop 0
	v_lshl_add_u64 v[16:17], v[140:141], 0, s[12:13]
	v_addc_co_u32_e32 v9, vcc, 0, v141, vcc
	global_store_dwordx4 v[8:9], v[12:15], off
	v_mul_f32_e32 v8, v4, v79
	v_mul_f32_e32 v9, v5, v80
	v_cvt_pk_bf16_f32 v8, v8, v9
	v_mul_f32_e32 v9, v6, v82
	v_mul_f32_e32 v10, v7, v83
	v_cvt_pk_bf16_f32 v9, v9, v10
	v_mul_f32_e32 v10, v0, v85
	v_mul_f32_e32 v11, v1, v87
	v_cvt_pk_bf16_f32 v10, v10, v11
	v_mul_f32_e32 v11, v2, v90
	v_mul_f32_e32 v4, v4, v70
	v_mul_f32_e32 v5, v5, v71
	v_mul_f32_e32 v12, v3, v93
	v_cvt_pk_bf16_f32 v11, v11, v12
	v_cvt_pk_bf16_f32 v4, v4, v5
	v_mul_f32_e32 v5, v6, v60
	v_mul_f32_e32 v6, v7, v84
	v_mul_f32_e32 v0, v0, v86
	v_mul_f32_e32 v1, v1, v88
	v_cvt_pk_bf16_f32 v5, v5, v6
	v_cvt_pk_bf16_f32 v6, v0, v1
	v_mul_f32_e32 v0, v2, v91
	v_mul_f32_e32 v1, v3, v78
	v_cvt_pk_bf16_f32 v7, v0, v1
	global_store_dwordx4 v[20:21], v[8:11], off offset:256
	global_store_dwordx4 v[16:17], v[4:7], off offset:256
	s_and_b64 vcc, exec, s[14:15]
	s_mov_b32 s56, s16
	s_mov_b64 s[4:5], s[22:23]
	s_mov_b64 s[2:3], s[20:21]
	s_cbranch_vccz .LBB0_686
	s_waitcnt vmcnt(0)
	s_cmpk_gt_u32 s27, 0xff
	s_cbranch_scc1 .LBB0_697
	s_barrier

; #define PG8_STAGE(bufoff, gbase, voff) do { _Pragma("unroll") for (int _i = 0; _i < 2; ++_i) \
;         __builtin_amdgcn_global_load_lds((const unsigned*)((const char*)(gbase) + (voff)[_i]), (LAS unsigned*)(lds + (bufoff) + ldsw + _i * 8192), 16, 0, 0); } while (0)
; #define PG8_LDA(dst, b, h) do { _Pragma("unroll") for (int m = 0; m < 4; ++m) _Pragma("unroll") for (int k = 0; k < 2; ++k) dst[m][k] = *(const LAS bf16x8*)(lds + PG8_SA(b, h) + aoff + m * 2048 + k * 1024); } while (0)
; #define PG8_LDB(dst, b, h) do { _Pragma("unroll") for (int n = 0; n < 2; ++n) _Pragma("unroll") for (int k = 0; k < 2; ++k) dst[n][k] = *(const LAS bf16x8*)(lds + PG8_SB(b, h) + boff + n * 2048 + k * 1024); } while (0)
; #define PG8_MMA(ai, bj, At, Bt) do { __builtin_amdgcn_s_setprio(1); _Pragma("unroll") for (int m = 0; m < 4; ++m) _Pragma("unroll") for (int n = 0; n < 2; ++n) _Pragma("unroll") for (int k = 0; k < 2; ++k) \
;         acc[ai][bj][m][n] = __builtin_amdgcn_mfma_f32_16x16x32_bf16(Bt[n][k], At[m][k], acc[ai][bj][m][n], 0, 0, 0); __builtin_amdgcn_s_setprio(0); } while (0)
; #define PG8_WAIT_L(n) asm volatile("s_waitcnt lgkmcnt(" #n ")" ::: "memory")
; template <class Epi, class Sched>
; __device__ __forceinline__ void gemm_phase(LAS unsigned char* lds, const Gemm g, const Sched& S, const Epi& E) {
;     ...
;     for (;;) {
;         const bool has_next = S.next(ui + 1, nxt);
;         const char* nA = has_next ? (const char*)g.A + (size_t)nxt.pm * tstep : cA; const char* nB = has_next ? (const char*)g.Bt + (size_t)nxt.pn * tstep : cB;
;         for (int t = 0; t < nt; t += 2) {
;             const bool last = (t == nt - 2);
;             const char* a1 = cA + (size_t)(t + 1) * kstep;
;             const char* a2 = last ? nA : cA + (size_t)(t + 2) * kstep; const char* b2 = last ? nB : cB + (size_t)(t + 2) * kstep;
;             const char* a3 = a2 + kstep; const char* b3 = b2 + kstep;
;             PG8_LDB(B0, 0, 0); PG8_SCHED; PG8_LDA(At, 0, 0); PG8_STAGE(PG8_SA(1, 1), a1 + hstep, voffA);
;             PG8_WAIT_L(8); PG8_BAR; PG8_WAIT_L(0); PG8_MMA(0, 0, At, B0); PG8_BAR; PG8_SCHED;
;             PG8_LDB(B1, 0, 1); PG8_STAGE(PG8_SB(0, 0), b2, voffB);
;             PG8_BAR; PG8_WAIT_L(0); PG8_MMA(0, 1, At, B1); PG8_BAR;
;             PG8_LDA(At, 0, 1); PG8_STAGE(PG8_SA(0, 0), a2, voffA);
;             PG8_BAR; PG8_WAIT_L(0); PG8_MMA(1, 0, At, B0); PG8_BAR; PG8_SCHED;
.LBB0_712:
	s_ashr_i32 s15, s14, 31
	v_cmp_lt_i64_e64 s[26:27], s[16:17], 64
	s_lshl_b64 s[16:17], s[14:15], 19
	s_add_u32 s16, s38, s16
	s_addc_u32 s17, s39, s17
	s_and_b64 s[18:19], s[26:27], exec
	s_cselect_b32 s15, s17, s23
	s_cselect_b32 s54, s16, s22
	s_ashr_i32 s13, s12, 31
	s_lshl_b64 s[18:19], s[12:13], 19
	s_add_u32 s18, s28, s18
	s_addc_u32 s19, s29, s19
	s_and_b64 s[26:27], s[26:27], exec
	s_cselect_b32 s13, s19, s25
	s_cselect_b32 s55, s18, s24
	s_add_u32 s22, s22, 0x40080
	s_addc_u32 s23, s23, 0
	s_add_u32 s56, s24, 0x100
	s_addc_u32 s57, s25, 0
	s_mov_b32 s58, -2
	s_waitcnt lgkmcnt(0)
	ds_read_b128 v[146:149], v143
	ds_read_b128 v[150:153], v143 offset:1024
	ds_read_b128 v[154:157], v143 offset:2048
	ds_read_b128 v[158:161], v143 offset:3072
	s_add_u32 s24, s22, 0xfffc0080
	s_addc_u32 s25, s23, -1
	s_cmp_eq_u32 s58, 12
	s_cselect_b32 s27, s15, s25
	s_cselect_b32 s26, s54, s24
	s_cselect_b32 s25, s13, s57
	s_cselect_b32 s24, s55, s56
	s_add_i32 m0, s21, 0xc000
	ds_read_b128 v[162:165], v144
	ds_read_b128 v[166:169], v144 offset:1024
	ds_read_b128 v[170:173], v144 offset:2048
	ds_read_b128 v[174:177], v144 offset:3072
	ds_read_b128 v[178:181], v144 offset:4096
	ds_read_b128 v[182:185], v144 offset:5120
	ds_read_b128 v[186:189], v144 offset:6144
	ds_read_b128 v[190:193], v144 offset:7168
	global_load_lds_dwordx4 v136, s[22:23]
	s_add_i32 m0, s21, 0xe000
	s_nop 0
	global_load_lds_dwordx4 v138, s[22:23]
	s_waitcnt lgkmcnt(8)
	s_waitcnt vmcnt(8)
	s_setprio 1
	s_barrier
	s_waitcnt lgkmcnt(0)
	v_mfma_f32_16x16x32_bf16 v[124:127], v[146:149], v[162:165], 0
	v_mfma_f32_16x16x32_bf16 v[120:123], v[154:157], v[162:165], 0
	v_mfma_f32_16x16x32_bf16 v[116:119], v[146:149], v[170:173], 0
	v_mfma_f32_16x16x32_bf16 v[108:111], v[154:157], v[170:173], 0
	v_mfma_f32_16x16x32_bf16 v[100:103], v[146:149], v[178:181], 0
	v_mfma_f32_16x16x32_bf16 v[92:95], v[154:157], v[178:181], 0
	v_mfma_f32_16x16x32_bf16 v[84:87], v[146:149], v[186:189], 0
	v_mfma_f32_16x16x32_bf16 v[76:79], v[154:157], v[186:189], 0
	v_mfma_f32_16x16x32_bf16 v[124:127], v[150:153], v[166:169], v[124:127]
	v_mfma_f32_16x16x32_bf16 v[120:123], v[158:161], v[166:169], v[120:123]
	v_mfma_f32_16x16x32_bf16 v[116:119], v[150:153], v[174:177], v[116:119]
	v_mfma_f32_16x16x32_bf16 v[108:111], v[158:161], v[174:177], v[108:111]
	v_mfma_f32_16x16x32_bf16 v[100:103], v[150:153], v[182:185], v[100:103]
	v_mfma_f32_16x16x32_bf16 v[92:95], v[158:161], v[182:185], v[92:95]
	v_mfma_f32_16x16x32_bf16 v[84:87], v[150:153], v[190:193], v[84:87]
	v_mfma_f32_16x16x32_bf16 v[76:79], v[158:161], v[190:193], v[76:79]
	s_barrier
	s_setprio 0
	s_add_i32 s59, s46, s34
	s_mov_b32 m0, s59
	ds_read_b128 v[194:197], v145
	ds_read_b128 v[202:205], v145 offset:1024
	ds_read_b128 v[206:209], v145 offset:2048
	ds_read_b128 v[210:213], v145 offset:3072
	global_load_lds_dwordx4 v130, s[24:25]
	s_add_i32 m0, s59, 0x2000
	s_nop 0
	global_load_lds_dwordx4 v134, s[24:25]
	s_waitcnt vmcnt(8)
	s_setprio 1
	s_barrier
	s_waitcnt lgkmcnt(0)
	v_mfma_f32_16x16x32_bf16 v[112:115], v[194:197], v[162:165], 0
	v_mfma_f32_16x16x32_bf16 v[104:107], v[206:209], v[162:165], 0
	v_mfma_f32_16x16x32_bf16 v[96:99], v[194:197], v[170:173], 0
	v_mfma_f32_16x16x32_bf16 v[88:91], v[206:209], v[170:173], 0
	v_mfma_f32_16x16x32_bf16 v[80:83], v[194:197], v[178:181], 0
	v_mfma_f32_16x16x32_bf16 v[72:75], v[206:209], v[178:181], 0
	v_mfma_f32_16x16x32_bf16 v[68:71], v[194:197], v[186:189], 0
	v_mfma_f32_16x16x32_bf16 v[64:67], v[206:209], v[186:189], 0
	v_mfma_f32_16x16x32_bf16 v[112:115], v[202:205], v[166:169], v[112:115]
	v_mfma_f32_16x16x32_bf16 v[104:107], v[210:213], v[166:169], v[104:107]
	v_mfma_f32_16x16x32_bf16 v[96:99], v[202:205], v[174:177], v[96:99]
	v_mfma_f32_16x16x32_bf16 v[88:91], v[210:213], v[174:177], v[88:91]
	v_mfma_f32_16x16x32_bf16 v[80:83], v[202:205], v[182:185], v[80:83]
	v_mfma_f32_16x16x32_bf16 v[72:75], v[210:213], v[182:185], v[72:75]
	v_mfma_f32_16x16x32_bf16 v[68:71], v[202:205], v[190:193], v[68:71]
	v_mfma_f32_16x16x32_bf16 v[64:67], v[210:213], v[190:193], v[64:67]
	s_barrier
	s_setprio 0
	s_mov_b32 m0, s21
	v_lshl_add_u64 v[216:217], s[26:27], 0, v[128:129]
	ds_read_b128 v[162:165], v144 offset:16384
	ds_read_b128 v[166:169], v144 offset:17408
	ds_read_b128 v[170:173], v144 offset:18432
	ds_read_b128 v[174:177], v144 offset:19456
	ds_read_b128 v[178:181], v144 offset:20480
	ds_read_b128 v[182:185], v144 offset:21504
	ds_read_b128 v[186:189], v144 offset:22528
	ds_read_b128 v[190:193], v144 offset:23552
	global_load_lds_dwordx4 v128, s[26:27]
	v_lshl_add_u64 v[218:219], s[26:27], 0, v[132:133]
	s_mov_b32 m0, s35
	s_nop 0
	global_load_lds_dwordx4 v132, s[26:27]
	s_setprio 1
	s_barrier
	s_waitcnt lgkmcnt(0)
	v_mfma_f32_16x16x32_bf16 v[60:63], v[146:149], v[162:165], 0
	v_mfma_f32_16x16x32_bf16 v[56:59], v[154:157], v[162:165], 0
	v_mfma_f32_16x16x32_bf16 v[52:55], v[146:149], v[170:173], 0
	v_mfma_f32_16x16x32_bf16 v[44:47], v[154:157], v[170:173], 0
	v_mfma_f32_16x16x32_bf16 v[36:39], v[146:149], v[178:181], 0
	v_mfma_f32_16x16x32_bf16 v[28:31], v[154:157], v[178:181], 0
	v_mfma_f32_16x16x32_bf16 v[20:23], v[146:149], v[186:189], 0
	v_mfma_f32_16x16x32_bf16 v[12:15], v[154:157], v[186:189], 0
	v_mfma_f32_16x16x32_bf16 v[60:63], v[150:153], v[166:169], v[60:63]
	v_mfma_f32_16x16x32_bf16 v[56:59], v[158:161], v[166:169], v[56:59]
	v_mfma_f32_16x16x32_bf16 v[52:55], v[150:153], v[174:177], v[52:55]
	v_mfma_f32_16x16x32_bf16 v[44:47], v[158:161], v[174:177], v[44:47]
	v_mfma_f32_16x16x32_bf16 v[36:39], v[150:153], v[182:185], v[36:39]
	v_mfma_f32_16x16x32_bf16 v[28:31], v[158:161], v[182:185], v[28:31]
	v_mfma_f32_16x16x32_bf16 v[20:23], v[150:153], v[190:193], v[20:23]
	v_mfma_f32_16x16x32_bf16 v[12:15], v[158:161], v[190:193], v[12:15]
	s_barrier
; #define PG8_STAGE(bufoff, gbase, voff) do { _Pragma("unroll") for (int _i = 0; _i < 2; ++_i) \
;         __builtin_amdgcn_global_load_lds((const unsigned*)((const char*)(gbase) + (voff)[_i]), (LAS unsigned*)(lds + (bufoff) + ldsw + _i * 8192), 16, 0, 0); } while (0)
; #define PG8_LDA(dst, b, h) do { _Pragma("unroll") for (int m = 0; m < 4; ++m) _Pragma("unroll") for (int k = 0; k < 2; ++k) dst[m][k] = *(const LAS bf16x8*)(lds + PG8_SA(b, h) + aoff + m * 2048 + k * 1024); } while (0)
; #define PG8_LDB(dst, b, h) do { _Pragma("unroll") for (int n = 0; n < 2; ++n) _Pragma("unroll") for (int k = 0; k < 2; ++k) dst[n][k] = *(const LAS bf16x8*)(lds + PG8_SB(b, h) + boff + n * 2048 + k * 1024); } while (0)
; #define PG8_MMA(ai, bj, At, Bt) do { __builtin_amdgcn_s_setprio(1); _Pragma("unroll") for (int m = 0; m < 4; ++m) _Pragma("unroll") for (int n = 0; n < 2; ++n) _Pragma("unroll") for (int k = 0; k < 2; ++k) \
;         acc[ai][bj][m][n] = __builtin_amdgcn_mfma_f32_16x16x32_bf16(Bt[n][k], At[m][k], acc[ai][bj][m][n], 0, 0, 0); __builtin_amdgcn_s_setprio(0); } while (0)
; #define PG8_WAIT_V(n) asm volatile("s_waitcnt vmcnt(" #n ")" ::: "memory")
; #define PG8_WAIT_L(n) asm volatile("s_waitcnt lgkmcnt(" #n ")" ::: "memory")
; #define PG8_BAR __builtin_amdgcn_s_barrier()
; #define PG8_SCHED __builtin_amdgcn_sched_barrier(0)
; template <class Epi, class Sched>
; __device__ __forceinline__ void gemm_phase(LAS unsigned char* lds, const Gemm g, const Sched& S, const Epi& E) {
;     ...
;             PG8_BAR; PG8_WAIT_L(0); PG8_MMA(1, 0, At, B0); PG8_BAR; PG8_SCHED;
;             PG8_STAGE(PG8_SB(0, 1), b2 + hstep, voffB);
;             PG8_WAIT_V(6); PG8_BAR; PG8_MMA(1, 1, At, B1); PG8_BAR;
;             PG8_LDB(B0, 1, 0); PG8_SCHED; PG8_LDA(At, 1, 0); PG8_STAGE(PG8_SA(0, 1), a2 + hstep, voffA);
;             PG8_WAIT_L(8); PG8_BAR; PG8_WAIT_L(0); PG8_MMA(0, 0, At, B0); PG8_BAR; PG8_SCHED;
;             PG8_LDB(B1, 1, 1); PG8_STAGE(PG8_SB(1, 0), b3, voffB);
;             PG8_BAR; PG8_WAIT_L(0); PG8_MMA(0, 1, At, B1); PG8_BAR;
;             PG8_LDA(At, 1, 1); PG8_STAGE(PG8_SA(1, 0), a3, voffA);
;             PG8_BAR; PG8_WAIT_L(0); PG8_MMA(1, 0, At, B0); PG8_BAR; PG8_SCHED;
	s_setprio 0
	s_add_u32 s60, s24, 0x40000
	s_addc_u32 s61, s25, 0
	s_add_i32 s59, s47, s34
	s_mov_b32 m0, s59
	s_nop 0
	global_load_lds_dwordx4 v130, s[60:61]
	s_add_i32 m0, s59, 0x2000
	s_nop 0
	global_load_lds_dwordx4 v134, s[60:61]
	s_add_u32 s26, s26, 0x40000
	s_addc_u32 s27, s27, 0
	s_mov_b32 m0, s36
	s_nop 0
	global_load_lds_dwordx4 v128, s[26:27]
	s_mov_b32 m0, s37
	s_nop 0
	global_load_lds_dwordx4 v132, s[26:27]
	s_waitcnt vmcnt(10)
	s_setprio 1
	s_barrier
	v_mfma_f32_16x16x32_bf16 v[48:51], v[194:197], v[162:165], 0
	v_mfma_f32_16x16x32_bf16 v[40:43], v[206:209], v[162:165], 0
	v_mfma_f32_16x16x32_bf16 v[32:35], v[194:197], v[170:173], 0
	v_mfma_f32_16x16x32_bf16 v[24:27], v[206:209], v[170:173], 0
	v_mfma_f32_16x16x32_bf16 v[16:19], v[194:197], v[178:181], 0
	v_mfma_f32_16x16x32_bf16 v[8:11], v[206:209], v[178:181], 0
	v_mfma_f32_16x16x32_bf16 v[4:7], v[194:197], v[186:189], 0
	v_mfma_f32_16x16x32_bf16 v[0:3], v[206:209], v[186:189], 0
	v_mfma_f32_16x16x32_bf16 v[48:51], v[202:205], v[166:169], v[48:51]
	v_mfma_f32_16x16x32_bf16 v[40:43], v[210:213], v[166:169], v[40:43]
	v_mfma_f32_16x16x32_bf16 v[32:35], v[202:205], v[174:177], v[32:35]
	v_mfma_f32_16x16x32_bf16 v[24:27], v[210:213], v[174:177], v[24:27]
	v_mfma_f32_16x16x32_bf16 v[16:19], v[202:205], v[182:185], v[16:19]
	v_mfma_f32_16x16x32_bf16 v[8:11], v[210:213], v[182:185], v[8:11]
	v_mfma_f32_16x16x32_bf16 v[4:7], v[202:205], v[190:193], v[4:7]
	v_mfma_f32_16x16x32_bf16 v[0:3], v[210:213], v[190:193], v[0:3]
	s_barrier
	s_setprio 0
	s_add_i32 s59, 0, 0x18000
	ds_read_b128 v[146:149], v145 offset:16384
	ds_read_b128 v[150:153], v145 offset:17408
	ds_read_b128 v[154:157], v145 offset:18432
	ds_read_b128 v[158:161], v145 offset:19456
	ds_read_b128 v[162:165], v144 offset:32768
	ds_read_b128 v[166:169], v144 offset:33792
	ds_read_b128 v[170:173], v144 offset:34816
	ds_read_b128 v[174:177], v144 offset:35840
	ds_read_b128 v[178:181], v144 offset:36864
	ds_read_b128 v[182:185], v144 offset:37888
	ds_read_b128 v[186:189], v144 offset:38912
	ds_read_b128 v[190:193], v144 offset:39936
	s_waitcnt lgkmcnt(8)
	s_waitcnt vmcnt(8)
	s_setprio 1
	s_barrier
	s_waitcnt lgkmcnt(0)
	v_mfma_f32_16x16x32_bf16 v[124:127], v[146:149], v[162:165], v[124:127]
	v_mfma_f32_16x16x32_bf16 v[120:123], v[154:157], v[162:165], v[120:123]
	v_mfma_f32_16x16x32_bf16 v[116:119], v[146:149], v[170:173], v[116:119]
	v_mfma_f32_16x16x32_bf16 v[108:111], v[154:157], v[170:173], v[108:111]
	v_mfma_f32_16x16x32_bf16 v[100:103], v[146:149], v[178:181], v[100:103]
	v_mfma_f32_16x16x32_bf16 v[92:95], v[154:157], v[178:181], v[92:95]
	v_mfma_f32_16x16x32_bf16 v[84:87], v[146:149], v[186:189], v[84:87]
	v_mfma_f32_16x16x32_bf16 v[76:79], v[154:157], v[186:189], v[76:79]
	v_mfma_f32_16x16x32_bf16 v[124:127], v[150:153], v[166:169], v[124:127]
	v_mfma_f32_16x16x32_bf16 v[120:123], v[158:161], v[166:169], v[120:123]
	v_mfma_f32_16x16x32_bf16 v[116:119], v[150:153], v[174:177], v[116:119]
	v_mfma_f32_16x16x32_bf16 v[108:111], v[158:161], v[174:177], v[108:111]
	v_mfma_f32_16x16x32_bf16 v[100:103], v[150:153], v[182:185], v[100:103]
	v_mfma_f32_16x16x32_bf16 v[92:95], v[158:161], v[182:185], v[92:95]
	v_mfma_f32_16x16x32_bf16 v[84:87], v[150:153], v[190:193], v[84:87]
	v_mfma_f32_16x16x32_bf16 v[76:79], v[158:161], v[190:193], v[76:79]
	s_barrier
	s_setprio 0
	s_add_i32 s26, 0, 0x1c000
	s_add_i32 s27, s59, s34
	s_add_u32 s0, s24, 0x80
	s_addc_u32 s1, s25, 0
	s_mov_b32 m0, s27
	ds_read_b128 v[194:197], v145 offset:32768
	ds_read_b128 v[202:205], v145 offset:33792
	ds_read_b128 v[206:209], v145 offset:34816
	ds_read_b128 v[210:213], v145 offset:35840
	global_load_lds_dwordx4 v130, s[0:1]
	s_add_i32 m0, s27, 0x2000
	s_nop 0
	global_load_lds_dwordx4 v134, s[0:1]
	s_waitcnt vmcnt(8)
	s_setprio 1
	s_barrier
	s_waitcnt lgkmcnt(0)
	v_mfma_f32_16x16x32_bf16 v[112:115], v[194:197], v[162:165], v[112:115]
	v_mfma_f32_16x16x32_bf16 v[104:107], v[206:209], v[162:165], v[104:107]
	v_mfma_f32_16x16x32_bf16 v[96:99], v[194:197], v[170:173], v[96:99]
	v_mfma_f32_16x16x32_bf16 v[88:91], v[206:209], v[170:173], v[88:91]
	v_mfma_f32_16x16x32_bf16 v[80:83], v[194:197], v[178:181], v[80:83]
	v_mfma_f32_16x16x32_bf16 v[72:75], v[206:209], v[178:181], v[72:75]
	v_mfma_f32_16x16x32_bf16 v[68:71], v[194:197], v[186:189], v[68:71]
	v_mfma_f32_16x16x32_bf16 v[64:67], v[206:209], v[186:189], v[64:67]
	v_mfma_f32_16x16x32_bf16 v[112:115], v[202:205], v[166:169], v[112:115]
	v_mfma_f32_16x16x32_bf16 v[104:107], v[210:213], v[166:169], v[104:107]
	v_mfma_f32_16x16x32_bf16 v[96:99], v[202:205], v[174:177], v[96:99]
	v_mfma_f32_16x16x32_bf16 v[88:91], v[210:213], v[174:177], v[88:91]
	v_mfma_f32_16x16x32_bf16 v[80:83], v[202:205], v[182:185], v[80:83]
	v_mfma_f32_16x16x32_bf16 v[72:75], v[210:213], v[182:185], v[72:75]
	v_mfma_f32_16x16x32_bf16 v[68:71], v[202:205], v[190:193], v[68:71]
	v_mfma_f32_16x16x32_bf16 v[64:67], v[210:213], v[190:193], v[64:67]
	s_barrier
	s_setprio 0
	s_mov_b32 m0, s43
	s_mov_b64 s[0:1], 0x80
	v_lshl_add_u64 v[198:199], v[216:217], 0, s[0:1]
	ds_read_b128 v[162:165], v144 offset:49152
	ds_read_b128 v[166:169], v144 offset:50176
	ds_read_b128 v[170:173], v144 offset:51200
	ds_read_b128 v[174:177], v144 offset:52224
	ds_read_b128 v[178:181], v144 offset:53248
	ds_read_b128 v[182:185], v144 offset:54272
	ds_read_b128 v[186:189], v144 offset:55296
	ds_read_b128 v[190:193], v144 offset:56320
	global_load_lds_dwordx4 v[198:199], off
	v_lshl_add_u64 v[198:199], v[218:219], 0, s[0:1]
	s_mov_b32 m0, s44
	s_nop 0
	global_load_lds_dwordx4 v[198:199], off
	s_setprio 1
	s_barrier
; #define PG8_STAGE(bufoff, gbase, voff) do { _Pragma("unroll") for (int _i = 0; _i < 2; ++_i) \
;         __builtin_amdgcn_global_load_lds((const unsigned*)((const char*)(gbase) + (voff)[_i]), (LAS unsigned*)(lds + (bufoff) + ldsw + _i * 8192), 16, 0, 0); } while (0)
; #define PG8_LDA(dst, b, h) do { _Pragma("unroll") for (int m = 0; m < 4; ++m) _Pragma("unroll") for (int k = 0; k < 2; ++k) dst[m][k] = *(const LAS bf16x8*)(lds + PG8_SA(b, h) + aoff + m * 2048 + k * 1024); } while (0)
; #define PG8_LDB(dst, b, h) do { _Pragma("unroll") for (int n = 0; n < 2; ++n) _Pragma("unroll") for (int k = 0; k < 2; ++k) dst[n][k] = *(const LAS bf16x8*)(lds + PG8_SB(b, h) + boff + n * 2048 + k * 1024); } while (0)
; #define PG8_WAIT_V(n) asm volatile("s_waitcnt vmcnt(" #n ")" ::: "memory")
; #define PG8_WAIT_L(n) asm volatile("s_waitcnt lgkmcnt(" #n ")" ::: "memory")
; #define PG8_BAR __builtin_amdgcn_s_barrier()
; #define PG8_SCHED __builtin_amdgcn_sched_barrier(0)
; template <class Epi, class Sched>
; __device__ __forceinline__ void gemm_phase(LAS unsigned char* lds, const Gemm g, const Sched& S, const Epi& E) {
;     ...
;             PG8_LDB(B0, 0, 0); PG8_SCHED; PG8_LDA(At, 0, 0); PG8_STAGE(PG8_SA(1, 1), a1 + hstep, voffA);
;             PG8_WAIT_L(8); PG8_BAR; PG8_WAIT_L(0); PG8_MMA(0, 0, At, B0); PG8_BAR; PG8_SCHED;
;             PG8_LDB(B1, 0, 1); PG8_STAGE(PG8_SB(0, 0), b2, voffB);
;             PG8_BAR; PG8_WAIT_L(0); PG8_MMA(0, 1, At, B1); PG8_BAR;
;             PG8_LDA(At, 0, 1); PG8_STAGE(PG8_SA(0, 0), a2, voffA);
;             PG8_BAR; PG8_WAIT_L(0); PG8_MMA(1, 0, At, B0); PG8_BAR; PG8_SCHED;
;             PG8_STAGE(PG8_SB(0, 1), b2 + hstep, voffB);
;             PG8_WAIT_V(6); PG8_BAR; PG8_MMA(1, 1, At, B1); PG8_BAR;
;             PG8_LDB(B0, 1, 0); PG8_SCHED; PG8_LDA(At, 1, 0); PG8_STAGE(PG8_SA(0, 1), a2 + hstep, voffA);
;             PG8_WAIT_L(8); PG8_BAR; PG8_WAIT_L(0); PG8_MMA(0, 0, At, B0); PG8_BAR; PG8_SCHED;
;             PG8_LDB(B1, 1, 1); PG8_STAGE(PG8_SB(1, 0), b3, voffB);
;             PG8_BAR; PG8_WAIT_L(0); PG8_MMA(0, 1, At, B1); PG8_BAR;
;             PG8_LDA(At, 1, 1); PG8_STAGE(PG8_SA(1, 0), a3, voffA);
;             PG8_BAR; PG8_WAIT_L(0); PG8_MMA(1, 0, At, B0); PG8_BAR; PG8_SCHED;
;             PG8_STAGE(PG8_SB(1, 1), b3 + hstep, voffB);
;             PG8_WAIT_V(6); PG8_BAR; PG8_MMA(1, 1, At, B1); PG8_BAR;
	s_waitcnt lgkmcnt(0)
	v_mfma_f32_16x16x32_bf16 v[60:63], v[146:149], v[162:165], v[60:63]
	v_mfma_f32_16x16x32_bf16 v[56:59], v[154:157], v[162:165], v[56:59]
	v_mfma_f32_16x16x32_bf16 v[52:55], v[146:149], v[170:173], v[52:55]
	v_mfma_f32_16x16x32_bf16 v[44:47], v[154:157], v[170:173], v[44:47]
	v_mfma_f32_16x16x32_bf16 v[36:39], v[146:149], v[178:181], v[36:39]
	v_mfma_f32_16x16x32_bf16 v[28:31], v[154:157], v[178:181], v[28:31]
	v_mfma_f32_16x16x32_bf16 v[20:23], v[146:149], v[186:189], v[20:23]
	v_mfma_f32_16x16x32_bf16 v[12:15], v[154:157], v[186:189], v[12:15]
	v_mfma_f32_16x16x32_bf16 v[60:63], v[150:153], v[166:169], v[60:63]
	v_mfma_f32_16x16x32_bf16 v[56:59], v[158:161], v[166:169], v[56:59]
	v_mfma_f32_16x16x32_bf16 v[52:55], v[150:153], v[174:177], v[52:55]
	v_mfma_f32_16x16x32_bf16 v[44:47], v[158:161], v[174:177], v[44:47]
	v_mfma_f32_16x16x32_bf16 v[36:39], v[150:153], v[182:185], v[36:39]
	v_mfma_f32_16x16x32_bf16 v[28:31], v[158:161], v[182:185], v[28:31]
	v_mfma_f32_16x16x32_bf16 v[20:23], v[150:153], v[190:193], v[20:23]
	v_mfma_f32_16x16x32_bf16 v[12:15], v[158:161], v[190:193], v[12:15]
	s_barrier
	s_setprio 0
	s_add_u32 s24, s24, 0x40080
	s_addc_u32 s25, s25, 0
	s_add_i32 s26, s26, s34
	s_mov_b32 m0, s26
	s_nop 0
	global_load_lds_dwordx4 v130, s[24:25]
	s_add_i32 m0, s26, 0x2000
	s_nop 0
	global_load_lds_dwordx4 v134, s[24:25]
	s_waitcnt vmcnt(8)
	s_setprio 1
	s_barrier
	v_mfma_f32_16x16x32_bf16 v[48:51], v[194:197], v[162:165], v[48:51]
	v_mfma_f32_16x16x32_bf16 v[40:43], v[206:209], v[162:165], v[40:43]
	v_mfma_f32_16x16x32_bf16 v[32:35], v[194:197], v[170:173], v[32:35]
	v_mfma_f32_16x16x32_bf16 v[24:27], v[206:209], v[170:173], v[24:27]
	v_mfma_f32_16x16x32_bf16 v[16:19], v[194:197], v[178:181], v[16:19]
	v_mfma_f32_16x16x32_bf16 v[8:11], v[206:209], v[178:181], v[8:11]
	v_mfma_f32_16x16x32_bf16 v[4:7], v[194:197], v[186:189], v[4:7]
	v_mfma_f32_16x16x32_bf16 v[0:3], v[206:209], v[186:189], v[0:3]
	v_mfma_f32_16x16x32_bf16 v[48:51], v[202:205], v[166:169], v[48:51]
	v_mfma_f32_16x16x32_bf16 v[40:43], v[210:213], v[166:169], v[40:43]
	v_mfma_f32_16x16x32_bf16 v[32:35], v[202:205], v[174:177], v[32:35]
	v_mfma_f32_16x16x32_bf16 v[24:27], v[210:213], v[174:177], v[24:27]
	v_mfma_f32_16x16x32_bf16 v[16:19], v[202:205], v[182:185], v[16:19]
	v_mfma_f32_16x16x32_bf16 v[8:11], v[210:213], v[182:185], v[8:11]
	v_mfma_f32_16x16x32_bf16 v[4:7], v[202:205], v[190:193], v[4:7]
	v_mfma_f32_16x16x32_bf16 v[0:3], v[210:213], v[190:193], v[0:3]
	s_barrier
	s_setprio 0
	s_add_i32 s58, s58, 2
	s_add_u32 s22, s22, 0x100
	s_addc_u32 s23, s23, 0
	s_add_u32 s56, s56, 0x100
	s_addc_u32 s57, s57, 0
	s_cmp_gt_u32 s58, 13
.LBB0_713:
	ds_read_b128 v[146:149], v143
	ds_read_b128 v[150:153], v143 offset:1024
	ds_read_b128 v[154:157], v143 offset:2048
	ds_read_b128 v[158:161], v143 offset:3072
	s_add_u32 s24, s22, 0xfffc0080
	s_addc_u32 s25, s23, -1
	s_cmp_eq_u32 s58, 12
	s_cselect_b32 s27, s15, s25
	s_cselect_b32 s26, s54, s24
	s_cselect_b32 s25, s13, s57
	s_cselect_b32 s24, s55, s56
	s_add_i32 m0, s21, 0xc000
	ds_read_b128 v[162:165], v144
	ds_read_b128 v[166:169], v144 offset:1024
	ds_read_b128 v[170:173], v144 offset:2048
	ds_read_b128 v[174:177], v144 offset:3072
	ds_read_b128 v[178:181], v144 offset:4096
	ds_read_b128 v[182:185], v144 offset:5120
	ds_read_b128 v[186:189], v144 offset:6144
	ds_read_b128 v[190:193], v144 offset:7168
	global_load_lds_dwordx4 v136, s[22:23]
	s_add_i32 m0, s21, 0xe000
	s_nop 0
	global_load_lds_dwordx4 v138, s[22:23]
	s_waitcnt lgkmcnt(8)
	s_waitcnt vmcnt(8)
	s_setprio 1
	s_barrier
	s_waitcnt lgkmcnt(0)
	v_mfma_f32_16x16x32_bf16 v[124:127], v[146:149], v[162:165], v[124:127]
	v_mfma_f32_16x16x32_bf16 v[120:123], v[154:157], v[162:165], v[120:123]
	v_mfma_f32_16x16x32_bf16 v[116:119], v[146:149], v[170:173], v[116:119]
	v_mfma_f32_16x16x32_bf16 v[108:111], v[154:157], v[170:173], v[108:111]
	v_mfma_f32_16x16x32_bf16 v[100:103], v[146:149], v[178:181], v[100:103]
	v_mfma_f32_16x16x32_bf16 v[92:95], v[154:157], v[178:181], v[92:95]
	v_mfma_f32_16x16x32_bf16 v[84:87], v[146:149], v[186:189], v[84:87]
	v_mfma_f32_16x16x32_bf16 v[76:79], v[154:157], v[186:189], v[76:79]
	v_mfma_f32_16x16x32_bf16 v[124:127], v[150:153], v[166:169], v[124:127]
	v_mfma_f32_16x16x32_bf16 v[120:123], v[158:161], v[166:169], v[120:123]
	v_mfma_f32_16x16x32_bf16 v[116:119], v[150:153], v[174:177], v[116:119]
	v_mfma_f32_16x16x32_bf16 v[108:111], v[158:161], v[174:177], v[108:111]
	v_mfma_f32_16x16x32_bf16 v[100:103], v[150:153], v[182:185], v[100:103]
	v_mfma_f32_16x16x32_bf16 v[92:95], v[158:161], v[182:185], v[92:95]
	v_mfma_f32_16x16x32_bf16 v[84:87], v[150:153], v[190:193], v[84:87]
	v_mfma_f32_16x16x32_bf16 v[76:79], v[158:161], v[190:193], v[76:79]
	s_barrier
	s_setprio 0
	s_add_i32 s59, s46, s34
	s_mov_b32 m0, s59
	ds_read_b128 v[194:197], v145
	ds_read_b128 v[202:205], v145 offset:1024
	ds_read_b128 v[206:209], v145 offset:2048
	ds_read_b128 v[210:213], v145 offset:3072
	global_load_lds_dwordx4 v130, s[24:25]
	s_add_i32 m0, s59, 0x2000
	s_nop 0
	global_load_lds_dwordx4 v134, s[24:25]
	s_waitcnt vmcnt(8)
	s_setprio 1
	s_barrier
; #define PG8_STAGE(bufoff, gbase, voff) do { _Pragma("unroll") for (int _i = 0; _i < 2; ++_i) \
;         __builtin_amdgcn_global_load_lds((const unsigned*)((const char*)(gbase) + (voff)[_i]), (LAS unsigned*)(lds + (bufoff) + ldsw + _i * 8192), 16, 0, 0); } while (0)
; #define PG8_LDA(dst, b, h) do { _Pragma("unroll") for (int m = 0; m < 4; ++m) _Pragma("unroll") for (int k = 0; k < 2; ++k) dst[m][k] = *(const LAS bf16x8*)(lds + PG8_SA(b, h) + aoff + m * 2048 + k * 1024); } while (0)
; #define PG8_LDB(dst, b, h) do { _Pragma("unroll") for (int n = 0; n < 2; ++n) _Pragma("unroll") for (int k = 0; k < 2; ++k) dst[n][k] = *(const LAS bf16x8*)(lds + PG8_SB(b, h) + boff + n * 2048 + k * 1024); } while (0)
; #define PG8_MMA(ai, bj, At, Bt) do { __builtin_amdgcn_s_setprio(1); _Pragma("unroll") for (int m = 0; m < 4; ++m) _Pragma("unroll") for (int n = 0; n < 2; ++n) _Pragma("unroll") for (int k = 0; k < 2; ++k) \
;         acc[ai][bj][m][n] = __builtin_amdgcn_mfma_f32_16x16x32_bf16(Bt[n][k], At[m][k], acc[ai][bj][m][n], 0, 0, 0); __builtin_amdgcn_s_setprio(0); } while (0)
; #define PG8_WAIT_V(n) asm volatile("s_waitcnt vmcnt(" #n ")" ::: "memory")
; #define PG8_WAIT_L(n) asm volatile("s_waitcnt lgkmcnt(" #n ")" ::: "memory")
; #define PG8_BAR __builtin_amdgcn_s_barrier()
; #define PG8_SCHED __builtin_amdgcn_sched_barrier(0)
; template <class Epi, class Sched>
; __device__ __forceinline__ void gemm_phase(LAS unsigned char* lds, const Gemm g, const Sched& S, const Epi& E) {
;     ...
;             PG8_BAR; PG8_WAIT_L(0); PG8_MMA(0, 1, At, B1); PG8_BAR;
;             PG8_LDA(At, 0, 1); PG8_STAGE(PG8_SA(0, 0), a2, voffA);
;             PG8_BAR; PG8_WAIT_L(0); PG8_MMA(1, 0, At, B0); PG8_BAR; PG8_SCHED;
;             PG8_STAGE(PG8_SB(0, 1), b2 + hstep, voffB);
;             PG8_WAIT_V(6); PG8_BAR; PG8_MMA(1, 1, At, B1); PG8_BAR;
;             PG8_LDB(B0, 1, 0); PG8_SCHED; PG8_LDA(At, 1, 0); PG8_STAGE(PG8_SA(0, 1), a2 + hstep, voffA);
;             PG8_WAIT_L(8); PG8_BAR; PG8_WAIT_L(0); PG8_MMA(0, 0, At, B0); PG8_BAR; PG8_SCHED;
	s_waitcnt lgkmcnt(0)
	v_mfma_f32_16x16x32_bf16 v[112:115], v[194:197], v[162:165], v[112:115]
	v_mfma_f32_16x16x32_bf16 v[104:107], v[206:209], v[162:165], v[104:107]
	v_mfma_f32_16x16x32_bf16 v[96:99], v[194:197], v[170:173], v[96:99]
	v_mfma_f32_16x16x32_bf16 v[88:91], v[206:209], v[170:173], v[88:91]
	v_mfma_f32_16x16x32_bf16 v[80:83], v[194:197], v[178:181], v[80:83]
	v_mfma_f32_16x16x32_bf16 v[72:75], v[206:209], v[178:181], v[72:75]
	v_mfma_f32_16x16x32_bf16 v[68:71], v[194:197], v[186:189], v[68:71]
	v_mfma_f32_16x16x32_bf16 v[64:67], v[206:209], v[186:189], v[64:67]
	v_mfma_f32_16x16x32_bf16 v[112:115], v[202:205], v[166:169], v[112:115]
	v_mfma_f32_16x16x32_bf16 v[104:107], v[210:213], v[166:169], v[104:107]
	v_mfma_f32_16x16x32_bf16 v[96:99], v[202:205], v[174:177], v[96:99]
	v_mfma_f32_16x16x32_bf16 v[88:91], v[210:213], v[174:177], v[88:91]
	v_mfma_f32_16x16x32_bf16 v[80:83], v[202:205], v[182:185], v[80:83]
	v_mfma_f32_16x16x32_bf16 v[72:75], v[210:213], v[182:185], v[72:75]
	v_mfma_f32_16x16x32_bf16 v[68:71], v[202:205], v[190:193], v[68:71]
	v_mfma_f32_16x16x32_bf16 v[64:67], v[210:213], v[190:193], v[64:67]
	s_barrier
	s_setprio 0
	s_mov_b32 m0, s21
	v_lshl_add_u64 v[216:217], s[26:27], 0, v[128:129]
	ds_read_b128 v[162:165], v144 offset:16384
	ds_read_b128 v[166:169], v144 offset:17408
	ds_read_b128 v[170:173], v144 offset:18432
	ds_read_b128 v[174:177], v144 offset:19456
	ds_read_b128 v[178:181], v144 offset:20480
	ds_read_b128 v[182:185], v144 offset:21504
	ds_read_b128 v[186:189], v144 offset:22528
	ds_read_b128 v[190:193], v144 offset:23552
	global_load_lds_dwordx4 v128, s[26:27]
	v_lshl_add_u64 v[218:219], s[26:27], 0, v[132:133]
	s_mov_b32 m0, s35
	s_nop 0
	global_load_lds_dwordx4 v132, s[26:27]
	s_setprio 1
	s_barrier
	s_waitcnt lgkmcnt(0)
	v_mfma_f32_16x16x32_bf16 v[60:63], v[146:149], v[162:165], v[60:63]
	v_mfma_f32_16x16x32_bf16 v[56:59], v[154:157], v[162:165], v[56:59]
	v_mfma_f32_16x16x32_bf16 v[52:55], v[146:149], v[170:173], v[52:55]
	v_mfma_f32_16x16x32_bf16 v[44:47], v[154:157], v[170:173], v[44:47]
	v_mfma_f32_16x16x32_bf16 v[36:39], v[146:149], v[178:181], v[36:39]
	v_mfma_f32_16x16x32_bf16 v[28:31], v[154:157], v[178:181], v[28:31]
	v_mfma_f32_16x16x32_bf16 v[20:23], v[146:149], v[186:189], v[20:23]
	v_mfma_f32_16x16x32_bf16 v[12:15], v[154:157], v[186:189], v[12:15]
	v_mfma_f32_16x16x32_bf16 v[60:63], v[150:153], v[166:169], v[60:63]
	v_mfma_f32_16x16x32_bf16 v[56:59], v[158:161], v[166:169], v[56:59]
	v_mfma_f32_16x16x32_bf16 v[52:55], v[150:153], v[174:177], v[52:55]
	v_mfma_f32_16x16x32_bf16 v[44:47], v[158:161], v[174:177], v[44:47]
	v_mfma_f32_16x16x32_bf16 v[36:39], v[150:153], v[182:185], v[36:39]
	v_mfma_f32_16x16x32_bf16 v[28:31], v[158:161], v[182:185], v[28:31]
	v_mfma_f32_16x16x32_bf16 v[20:23], v[150:153], v[190:193], v[20:23]
	v_mfma_f32_16x16x32_bf16 v[12:15], v[158:161], v[190:193], v[12:15]
	s_barrier
	s_setprio 0
	s_add_u32 s60, s24, 0x40000
	s_addc_u32 s61, s25, 0
	s_add_i32 s59, s47, s34
	s_mov_b32 m0, s59
	s_nop 0
	global_load_lds_dwordx4 v130, s[60:61]
	s_add_i32 m0, s59, 0x2000
	s_nop 0
	global_load_lds_dwordx4 v134, s[60:61]
	s_add_u32 s26, s26, 0x40000
	s_addc_u32 s27, s27, 0
	s_mov_b32 m0, s36
	s_nop 0
	global_load_lds_dwordx4 v128, s[26:27]
	s_mov_b32 m0, s37
	s_nop 0
	global_load_lds_dwordx4 v132, s[26:27]
	s_waitcnt vmcnt(10)
	s_setprio 1
	s_barrier
	v_mfma_f32_16x16x32_bf16 v[48:51], v[194:197], v[162:165], v[48:51]
	v_mfma_f32_16x16x32_bf16 v[40:43], v[206:209], v[162:165], v[40:43]
	v_mfma_f32_16x16x32_bf16 v[32:35], v[194:197], v[170:173], v[32:35]
	v_mfma_f32_16x16x32_bf16 v[24:27], v[206:209], v[170:173], v[24:27]
	v_mfma_f32_16x16x32_bf16 v[16:19], v[194:197], v[178:181], v[16:19]
	v_mfma_f32_16x16x32_bf16 v[8:11], v[206:209], v[178:181], v[8:11]
	v_mfma_f32_16x16x32_bf16 v[4:7], v[194:197], v[186:189], v[4:7]
	v_mfma_f32_16x16x32_bf16 v[0:3], v[206:209], v[186:189], v[0:3]
	v_mfma_f32_16x16x32_bf16 v[48:51], v[202:205], v[166:169], v[48:51]
	v_mfma_f32_16x16x32_bf16 v[40:43], v[210:213], v[166:169], v[40:43]
	v_mfma_f32_16x16x32_bf16 v[32:35], v[202:205], v[174:177], v[32:35]
	v_mfma_f32_16x16x32_bf16 v[24:27], v[210:213], v[174:177], v[24:27]
	v_mfma_f32_16x16x32_bf16 v[16:19], v[202:205], v[182:185], v[16:19]
	v_mfma_f32_16x16x32_bf16 v[8:11], v[210:213], v[182:185], v[8:11]
	v_mfma_f32_16x16x32_bf16 v[4:7], v[202:205], v[190:193], v[4:7]
	v_mfma_f32_16x16x32_bf16 v[0:3], v[210:213], v[190:193], v[0:3]
	s_barrier
	s_setprio 0
	s_add_i32 s59, 0, 0x18000
	ds_read_b128 v[146:149], v145 offset:16384
	ds_read_b128 v[150:153], v145 offset:17408
	ds_read_b128 v[154:157], v145 offset:18432
	ds_read_b128 v[158:161], v145 offset:19456
	ds_read_b128 v[162:165], v144 offset:32768
	ds_read_b128 v[166:169], v144 offset:33792
	ds_read_b128 v[170:173], v144 offset:34816
	ds_read_b128 v[174:177], v144 offset:35840
	ds_read_b128 v[178:181], v144 offset:36864
	ds_read_b128 v[182:185], v144 offset:37888
	ds_read_b128 v[186:189], v144 offset:38912
	ds_read_b128 v[190:193], v144 offset:39936
	s_waitcnt lgkmcnt(8)
	s_waitcnt vmcnt(8)
	s_setprio 1
	s_barrier
; #define PG8_STAGE(bufoff, gbase, voff) do { _Pragma("unroll") for (int _i = 0; _i < 2; ++_i) \
;         __builtin_amdgcn_global_load_lds((const unsigned*)((const char*)(gbase) + (voff)[_i]), (LAS unsigned*)(lds + (bufoff) + ldsw + _i * 8192), 16, 0, 0); } while (0)
; #define PG8_LDA(dst, b, h) do { _Pragma("unroll") for (int m = 0; m < 4; ++m) _Pragma("unroll") for (int k = 0; k < 2; ++k) dst[m][k] = *(const LAS bf16x8*)(lds + PG8_SA(b, h) + aoff + m * 2048 + k * 1024); } while (0)
; #define PG8_LDB(dst, b, h) do { _Pragma("unroll") for (int n = 0; n < 2; ++n) _Pragma("unroll") for (int k = 0; k < 2; ++k) dst[n][k] = *(const LAS bf16x8*)(lds + PG8_SB(b, h) + boff + n * 2048 + k * 1024); } while (0)
; #define PG8_MMA(ai, bj, At, Bt) do { __builtin_amdgcn_s_setprio(1); _Pragma("unroll") for (int m = 0; m < 4; ++m) _Pragma("unroll") for (int n = 0; n < 2; ++n) _Pragma("unroll") for (int k = 0; k < 2; ++k) \
;         acc[ai][bj][m][n] = __builtin_amdgcn_mfma_f32_16x16x32_bf16(Bt[n][k], At[m][k], acc[ai][bj][m][n], 0, 0, 0); __builtin_amdgcn_s_setprio(0); } while (0)
; #define PG8_WAIT_V(n) asm volatile("s_waitcnt vmcnt(" #n ")" ::: "memory")
; #define PG8_WAIT_L(n) asm volatile("s_waitcnt lgkmcnt(" #n ")" ::: "memory")
; #define PG8_BAR __builtin_amdgcn_s_barrier()
; #define PG8_SCHED __builtin_amdgcn_sched_barrier(0)
; template <class Epi, class Sched>
; __device__ __forceinline__ void gemm_phase(LAS unsigned char* lds, const Gemm g, const Sched& S, const Epi& E) {
;     ...
;             PG8_WAIT_L(8); PG8_BAR; PG8_WAIT_L(0); PG8_MMA(0, 0, At, B0); PG8_BAR; PG8_SCHED;
;             PG8_LDB(B1, 1, 1); PG8_STAGE(PG8_SB(1, 0), b3, voffB);
;             PG8_BAR; PG8_WAIT_L(0); PG8_MMA(0, 1, At, B1); PG8_BAR;
;             PG8_LDA(At, 1, 1); PG8_STAGE(PG8_SA(1, 0), a3, voffA);
;             PG8_BAR; PG8_WAIT_L(0); PG8_MMA(1, 0, At, B0); PG8_BAR; PG8_SCHED;
;             PG8_STAGE(PG8_SB(1, 1), b3 + hstep, voffB);
;             PG8_WAIT_V(6); PG8_BAR; PG8_MMA(1, 1, At, B1); PG8_BAR;
	s_waitcnt lgkmcnt(0)
	v_mfma_f32_16x16x32_bf16 v[124:127], v[146:149], v[162:165], v[124:127]
	v_mfma_f32_16x16x32_bf16 v[120:123], v[154:157], v[162:165], v[120:123]
	v_mfma_f32_16x16x32_bf16 v[116:119], v[146:149], v[170:173], v[116:119]
	v_mfma_f32_16x16x32_bf16 v[108:111], v[154:157], v[170:173], v[108:111]
	v_mfma_f32_16x16x32_bf16 v[100:103], v[146:149], v[178:181], v[100:103]
	v_mfma_f32_16x16x32_bf16 v[92:95], v[154:157], v[178:181], v[92:95]
	v_mfma_f32_16x16x32_bf16 v[84:87], v[146:149], v[186:189], v[84:87]
	v_mfma_f32_16x16x32_bf16 v[76:79], v[154:157], v[186:189], v[76:79]
	v_mfma_f32_16x16x32_bf16 v[124:127], v[150:153], v[166:169], v[124:127]
	v_mfma_f32_16x16x32_bf16 v[120:123], v[158:161], v[166:169], v[120:123]
	v_mfma_f32_16x16x32_bf16 v[116:119], v[150:153], v[174:177], v[116:119]
	v_mfma_f32_16x16x32_bf16 v[108:111], v[158:161], v[174:177], v[108:111]
	v_mfma_f32_16x16x32_bf16 v[100:103], v[150:153], v[182:185], v[100:103]
	v_mfma_f32_16x16x32_bf16 v[92:95], v[158:161], v[182:185], v[92:95]
	v_mfma_f32_16x16x32_bf16 v[84:87], v[150:153], v[190:193], v[84:87]
	v_mfma_f32_16x16x32_bf16 v[76:79], v[158:161], v[190:193], v[76:79]
	s_barrier
	s_setprio 0
	s_add_i32 s26, 0, 0x1c000
	s_add_i32 s27, s59, s34
	s_add_u32 s0, s24, 0x80
	s_addc_u32 s1, s25, 0
	s_mov_b32 m0, s27
	ds_read_b128 v[194:197], v145 offset:32768
	ds_read_b128 v[202:205], v145 offset:33792
	ds_read_b128 v[206:209], v145 offset:34816
	ds_read_b128 v[210:213], v145 offset:35840
	global_load_lds_dwordx4 v130, s[0:1]
	s_add_i32 m0, s27, 0x2000
	s_nop 0
	global_load_lds_dwordx4 v134, s[0:1]
	s_waitcnt vmcnt(8)
	s_setprio 1
	s_barrier
	s_waitcnt lgkmcnt(0)
	v_mfma_f32_16x16x32_bf16 v[112:115], v[194:197], v[162:165], v[112:115]
	v_mfma_f32_16x16x32_bf16 v[104:107], v[206:209], v[162:165], v[104:107]
	v_mfma_f32_16x16x32_bf16 v[96:99], v[194:197], v[170:173], v[96:99]
	v_mfma_f32_16x16x32_bf16 v[88:91], v[206:209], v[170:173], v[88:91]
	v_mfma_f32_16x16x32_bf16 v[80:83], v[194:197], v[178:181], v[80:83]
	v_mfma_f32_16x16x32_bf16 v[72:75], v[206:209], v[178:181], v[72:75]
	v_mfma_f32_16x16x32_bf16 v[68:71], v[194:197], v[186:189], v[68:71]
	v_mfma_f32_16x16x32_bf16 v[64:67], v[206:209], v[186:189], v[64:67]
	v_mfma_f32_16x16x32_bf16 v[112:115], v[202:205], v[166:169], v[112:115]
	v_mfma_f32_16x16x32_bf16 v[104:107], v[210:213], v[166:169], v[104:107]
	v_mfma_f32_16x16x32_bf16 v[96:99], v[202:205], v[174:177], v[96:99]
	v_mfma_f32_16x16x32_bf16 v[88:91], v[210:213], v[174:177], v[88:91]
	v_mfma_f32_16x16x32_bf16 v[80:83], v[202:205], v[182:185], v[80:83]
	v_mfma_f32_16x16x32_bf16 v[72:75], v[210:213], v[182:185], v[72:75]
	v_mfma_f32_16x16x32_bf16 v[68:71], v[202:205], v[190:193], v[68:71]
	v_mfma_f32_16x16x32_bf16 v[64:67], v[210:213], v[190:193], v[64:67]
	s_barrier
	s_setprio 0
	s_mov_b32 m0, s43
	s_mov_b64 s[0:1], 0x80
	v_lshl_add_u64 v[198:199], v[216:217], 0, s[0:1]
	ds_read_b128 v[162:165], v144 offset:49152
	ds_read_b128 v[166:169], v144 offset:50176
	ds_read_b128 v[170:173], v144 offset:51200
	ds_read_b128 v[174:177], v144 offset:52224
	ds_read_b128 v[178:181], v144 offset:53248
	ds_read_b128 v[182:185], v144 offset:54272
	ds_read_b128 v[186:189], v144 offset:55296
	ds_read_b128 v[190:193], v144 offset:56320
	global_load_lds_dwordx4 v[198:199], off
	v_lshl_add_u64 v[198:199], v[218:219], 0, s[0:1]
	s_mov_b32 m0, s44
	s_nop 0
	global_load_lds_dwordx4 v[198:199], off
	s_setprio 1
	s_barrier
	s_waitcnt lgkmcnt(0)
	v_mfma_f32_16x16x32_bf16 v[60:63], v[146:149], v[162:165], v[60:63]
	v_mfma_f32_16x16x32_bf16 v[56:59], v[154:157], v[162:165], v[56:59]
	v_mfma_f32_16x16x32_bf16 v[52:55], v[146:149], v[170:173], v[52:55]
	v_mfma_f32_16x16x32_bf16 v[44:47], v[154:157], v[170:173], v[44:47]
	v_mfma_f32_16x16x32_bf16 v[36:39], v[146:149], v[178:181], v[36:39]
	v_mfma_f32_16x16x32_bf16 v[28:31], v[154:157], v[178:181], v[28:31]
	v_mfma_f32_16x16x32_bf16 v[20:23], v[146:149], v[186:189], v[20:23]
	v_mfma_f32_16x16x32_bf16 v[12:15], v[154:157], v[186:189], v[12:15]
	v_mfma_f32_16x16x32_bf16 v[60:63], v[150:153], v[166:169], v[60:63]
	v_mfma_f32_16x16x32_bf16 v[56:59], v[158:161], v[166:169], v[56:59]
	v_mfma_f32_16x16x32_bf16 v[52:55], v[150:153], v[174:177], v[52:55]
	v_mfma_f32_16x16x32_bf16 v[44:47], v[158:161], v[174:177], v[44:47]
	v_mfma_f32_16x16x32_bf16 v[36:39], v[150:153], v[182:185], v[36:39]
	v_mfma_f32_16x16x32_bf16 v[28:31], v[158:161], v[182:185], v[28:31]
	v_mfma_f32_16x16x32_bf16 v[20:23], v[150:153], v[190:193], v[20:23]
	v_mfma_f32_16x16x32_bf16 v[12:15], v[158:161], v[190:193], v[12:15]
	s_barrier
	s_setprio 0
	s_add_u32 s24, s24, 0x40080
	s_addc_u32 s25, s25, 0
	s_add_i32 s26, s26, s34
	s_mov_b32 m0, s26
	s_nop 0
	global_load_lds_dwordx4 v130, s[24:25]
	s_add_i32 m0, s26, 0x2000
	s_nop 0
	global_load_lds_dwordx4 v134, s[24:25]
	s_waitcnt vmcnt(8)
	s_setprio 1
	s_barrier
	v_mfma_f32_16x16x32_bf16 v[48:51], v[194:197], v[162:165], v[48:51]
	v_mfma_f32_16x16x32_bf16 v[40:43], v[206:209], v[162:165], v[40:43]
	v_mfma_f32_16x16x32_bf16 v[32:35], v[194:197], v[170:173], v[32:35]
	v_mfma_f32_16x16x32_bf16 v[24:27], v[206:209], v[170:173], v[24:27]
	v_mfma_f32_16x16x32_bf16 v[16:19], v[194:197], v[178:181], v[16:19]
	v_mfma_f32_16x16x32_bf16 v[8:11], v[206:209], v[178:181], v[8:11]
	v_mfma_f32_16x16x32_bf16 v[4:7], v[194:197], v[186:189], v[4:7]
	v_mfma_f32_16x16x32_bf16 v[0:3], v[206:209], v[186:189], v[0:3]
	v_mfma_f32_16x16x32_bf16 v[48:51], v[202:205], v[166:169], v[48:51]
	v_mfma_f32_16x16x32_bf16 v[40:43], v[210:213], v[166:169], v[40:43]
	v_mfma_f32_16x16x32_bf16 v[32:35], v[202:205], v[174:177], v[32:35]
	v_mfma_f32_16x16x32_bf16 v[24:27], v[210:213], v[174:177], v[24:27]
	v_mfma_f32_16x16x32_bf16 v[16:19], v[202:205], v[182:185], v[16:19]
	v_mfma_f32_16x16x32_bf16 v[8:11], v[210:213], v[182:185], v[8:11]
	v_mfma_f32_16x16x32_bf16 v[4:7], v[202:205], v[190:193], v[4:7]
	v_mfma_f32_16x16x32_bf16 v[0:3], v[210:213], v[190:193], v[0:3]
	s_barrier
; __device__ __forceinline__ unsigned cvt_pk_bf16(float lo, float hi) { unsigned r; asm volatile("v_cvt_pk_bf16_f32 %0, %1, %2" : "=v"(r) : "v"(lo), "v"(hi)); return r; }
; #define PG8_WAIT_V(n) asm volatile("s_waitcnt vmcnt(" #n ")" ::: "memory")
; #define PG8_BAR __builtin_amdgcn_s_barrier()
; template <class Epi, class Sched>
; __device__ __forceinline__ void gemm_phase(LAS unsigned char* lds, const Gemm g, const Sched& S, const Epi& E) {
;     ...
;         }
;         E(acc, cur, wr, wc, fr, fq);
;         if (!has_next) break;
; #pragma unroll
;         for (int a = 0; a < 2; ++a)
; #pragma unroll
;             for (int b = 0; b < 2; ++b)
; #pragma unroll
;                 for (int m = 0; m < 4; ++m)
; #pragma unroll
;                     for (int n = 0; n < 2; ++n) acc[a][b][m][n] = (f32x4){0.f, 0.f, 0.f, 0.f};
;         cur = nxt; cA = nA; cB = nB; ++ui;
;     }
;     PG8_WAIT_V(0);
;     if (wr == 0) PG8_BAR;
;     PG8_BAR;
;     __device__ __forceinline__ void operator()(const AccT& acc, const Unit& u, int wr, int wc, int fr, int fq) const {
;     ...
;         const int rbase = u.pm * 256 + wr * 64 + fr;
;         const int tb = u.pn * 256 + wc * 32 + 8 * fq;
; #pragma unroll
;         for (int ai = 0; ai < 2; ++ai)
; #pragma unroll
;             for (int m = 0; m < 4; ++m) {
;                 const int r = rbase + ai * 128 + m * 16;
; #pragma unroll
;                 for (int bj = 0; bj < 2; ++bj) {
;                     const int t0 = tb + bj * 128;
;                     const f32x4 v0 = acc[ai][bj][m][0], v1 = acc[ai][bj][m][1];
;                     u32x4 w; w.x = cvt_pk_bf16(v0[0], v0[1]); w.y = cvt_pk_bf16(v0[2], v0[3]); w.z = cvt_pk_bf16(v1[0], v1[1]); w.w = cvt_pk_bf16(v1[2], v1[3]);
;                     *(u32x4*)(VT + (size_t)r * NT + t0) = w;
;                 }
	s_setprio 0
	s_add_i32 s58, s58, 2
	s_add_u32 s22, s22, 0x100
	s_addc_u32 s23, s23, 0
	s_add_u32 s56, s56, 0x100
	s_addc_u32 s57, s57, 0
	s_cmp_gt_u32 s58, 13
	s_cbranch_scc0 .LBB0_713
	v_mov_b32_e32 v146, v140
	v_mov_b32_e32 v147, v141
	s_lshl_b32 s13, s20, 8
	s_add_i32 s13, s13, s41
	v_add_u32_e32 v146, s13, v146
	s_lshl_b32 s13, s53, 8
	s_or_b32 s13, s13, s42
	v_lshl_add_u32 v148, v147, 3, s13
	v_ashrrev_i32_e32 v147, 31, v146
	v_cvt_pk_bf16_f32 v124, v124, v125
	v_cvt_pk_bf16_f32 v125, v126, v127
	v_cvt_pk_bf16_f32 v126, v120, v121
	v_lshlrev_b64 v[120:121], 14, v[146:147]
	v_lshl_add_u64 v[120:121], s[62:63], 0, v[120:121]
	v_ashrrev_i32_e32 v149, 31, v148
	v_lshl_add_u64 v[120:121], v[148:149], 1, v[120:121]
	s_mov_b32 s13, 0x40000
	v_cvt_pk_bf16_f32 v127, v122, v123
	global_store_dwordx4 v[120:121], v[124:127], off
	v_cvt_pk_bf16_f32 v112, v112, v113
	v_cvt_pk_bf16_f32 v113, v114, v115
	v_cvt_pk_bf16_f32 v114, v104, v105
	v_cvt_pk_bf16_f32 v115, v106, v107
	global_store_dwordx4 v[120:121], v[112:115], off offset:256
	v_cvt_pk_bf16_f32 v104, v116, v117
	v_cvt_pk_bf16_f32 v105, v118, v119
	v_cvt_pk_bf16_f32 v106, v108, v109
	v_cvt_pk_bf16_f32 v107, v110, v111
	s_mov_b64 s[22:23], 0x40000
	v_add_co_u32_e32 v110, vcc, s13, v120
	v_lshl_add_u64 v[108:109], v[120:121], 0, s[22:23]
	s_nop 0
	v_addc_co_u32_e32 v111, vcc, 0, v121, vcc
	s_mov_b32 s13, 0x80000
	global_store_dwordx4 v[110:111], v[104:107], off
	v_cvt_pk_bf16_f32 v96, v96, v97
	v_cvt_pk_bf16_f32 v97, v98, v99
	v_cvt_pk_bf16_f32 v98, v88, v89
	v_cvt_pk_bf16_f32 v99, v90, v91
	global_store_dwordx4 v[108:109], v[96:99], off offset:256
	v_cvt_pk_bf16_f32 v88, v100, v101
	v_cvt_pk_bf16_f32 v89, v102, v103
	v_cvt_pk_bf16_f32 v90, v92, v93
	v_cvt_pk_bf16_f32 v91, v94, v95
	s_mov_b64 s[22:23], 0x80000
	v_add_co_u32_e32 v94, vcc, s13, v120
	v_lshl_add_u64 v[92:93], v[120:121], 0, s[22:23]
	s_nop 0
	v_addc_co_u32_e32 v95, vcc, 0, v121, vcc
	global_store_dwordx4 v[94:95], v[88:91], off
	v_cvt_pk_bf16_f32 v80, v80, v81
	v_cvt_pk_bf16_f32 v81, v82, v83
	v_cvt_pk_bf16_f32 v82, v72, v73
	v_cvt_pk_bf16_f32 v83, v74, v75
	global_store_dwordx4 v[92:93], v[80:83], off offset:256
	v_cvt_pk_bf16_f32 v72, v84, v85
	v_cvt_pk_bf16_f32 v73, v86, v87
	v_cvt_pk_bf16_f32 v74, v76, v77
	v_cvt_pk_bf16_f32 v75, v78, v79
	s_mov_b64 s[22:23], 0xc0000
	v_add_co_u32_e32 v78, vcc, s48, v120
	v_lshl_add_u64 v[76:77], v[120:121], 0, s[22:23]
	s_nop 0
	v_addc_co_u32_e32 v79, vcc, 0, v121, vcc
	global_store_dwordx4 v[78:79], v[72:75], off
	v_cvt_pk_bf16_f32 v68, v68, v69
	v_cvt_pk_bf16_f32 v69, v70, v71
	v_cvt_pk_bf16_f32 v70, v64, v65
	v_cvt_pk_bf16_f32 v71, v66, v67
	global_store_dwordx4 v[76:77], v[68:71], off offset:256
	v_cvt_pk_bf16_f32 v60, v60, v61
	v_cvt_pk_bf16_f32 v61, v62, v63
	v_cvt_pk_bf16_f32 v62, v56, v57
	v_cvt_pk_bf16_f32 v63, v58, v59
	v_add_co_u32_e32 v58, vcc, s49, v120
	v_lshl_add_u64 v[56:57], v[120:121], 0, s[2:3]
	s_nop 0
	v_addc_co_u32_e32 v59, vcc, 0, v121, vcc
	global_store_dwordx4 v[58:59], v[60:63], off
	v_cvt_pk_bf16_f32 v48, v48, v49
	v_cvt_pk_bf16_f32 v49, v50, v51
	v_cvt_pk_bf16_f32 v50, v40, v41
	v_cvt_pk_bf16_f32 v51, v42, v43
	global_store_dwordx4 v[56:57], v[48:51], off offset:256
	v_cvt_pk_bf16_f32 v40, v52, v53
	v_cvt_pk_bf16_f32 v41, v54, v55
	v_cvt_pk_bf16_f32 v42, v44, v45
	v_cvt_pk_bf16_f32 v43, v46, v47
	v_add_co_u32_e32 v46, vcc, s50, v120
	v_lshl_add_u64 v[44:45], v[120:121], 0, s[4:5]
	s_nop 0
	v_addc_co_u32_e32 v47, vcc, 0, v121, vcc
	global_store_dwordx4 v[46:47], v[40:43], off
	v_cvt_pk_bf16_f32 v32, v32, v33
	v_cvt_pk_bf16_f32 v33, v34, v35
	v_cvt_pk_bf16_f32 v34, v24, v25
	v_cvt_pk_bf16_f32 v35, v26, v27
	global_store_dwordx4 v[44:45], v[32:35], off offset:256
	v_cvt_pk_bf16_f32 v24, v36, v37
	v_cvt_pk_bf16_f32 v25, v38, v39
	v_cvt_pk_bf16_f32 v26, v28, v29
	v_cvt_pk_bf16_f32 v27, v30, v31
	v_add_co_u32_e32 v30, vcc, s51, v120
	v_lshl_add_u64 v[28:29], v[120:121], 0, s[6:7]
	s_nop 0
	v_addc_co_u32_e32 v31, vcc, 0, v121, vcc
	global_store_dwordx4 v[30:31], v[24:27], off
	v_cvt_pk_bf16_f32 v16, v16, v17
	v_cvt_pk_bf16_f32 v17, v18, v19
	v_cvt_pk_bf16_f32 v18, v8, v9
	v_cvt_pk_bf16_f32 v19, v10, v11
	global_store_dwordx4 v[28:29], v[16:19], off offset:256
	v_cvt_pk_bf16_f32 v8, v20, v21
	v_cvt_pk_bf16_f32 v9, v22, v23
	v_cvt_pk_bf16_f32 v10, v12, v13
	v_cvt_pk_bf16_f32 v11, v14, v15
	v_add_co_u32_e32 v14, vcc, s52, v120
	v_lshl_add_u64 v[12:13], v[120:121], 0, s[8:9]
	s_nop 0
	v_addc_co_u32_e32 v15, vcc, 0, v121, vcc
	s_and_b64 vcc, exec, s[10:11]
	s_mov_b32 s53, s12
	s_mov_b32 s20, s14
	s_mov_b64 s[24:25], s[18:19]
	s_mov_b64 s[22:23], s[16:17]
	global_store_dwordx4 v[14:15], v[8:11], off
	v_cvt_pk_bf16_f32 v4, v4, v5
	v_cvt_pk_bf16_f32 v5, v6, v7
	v_cvt_pk_bf16_f32 v6, v0, v1
	v_cvt_pk_bf16_f32 v7, v2, v3
	global_store_dwordx4 v[12:13], v[4:7], off offset:256
	s_cbranch_vccz .LBB0_706
	s_waitcnt vmcnt(0)
	s_cmpk_gt_u32 s31, 0xff
	s_cbranch_scc1 .LBB0_717
	s_barrier

; #define PG8_STAGE(bufoff, gbase, voff) do { _Pragma("unroll") for (int _i = 0; _i < 2; ++_i) \
;         __builtin_amdgcn_global_load_lds((const unsigned*)((const char*)(gbase) + (voff)[_i]), (LAS unsigned*)(lds + (bufoff) + ldsw + _i * 8192), 16, 0, 0); } while (0)
; #define PG8_LDA(dst, b, h) do { _Pragma("unroll") for (int m = 0; m < 4; ++m) _Pragma("unroll") for (int k = 0; k < 2; ++k) dst[m][k] = *(const LAS bf16x8*)(lds + PG8_SA(b, h) + aoff + m * 2048 + k * 1024); } while (0)
; #define PG8_LDB(dst, b, h) do { _Pragma("unroll") for (int n = 0; n < 2; ++n) _Pragma("unroll") for (int k = 0; k < 2; ++k) dst[n][k] = *(const LAS bf16x8*)(lds + PG8_SB(b, h) + boff + n * 2048 + k * 1024); } while (0)
; #define PG8_MMA(ai, bj, At, Bt) do { __builtin_amdgcn_s_setprio(1); _Pragma("unroll") for (int m = 0; m < 4; ++m) _Pragma("unroll") for (int n = 0; n < 2; ++n) _Pragma("unroll") for (int k = 0; k < 2; ++k) \
;         acc[ai][bj][m][n] = __builtin_amdgcn_mfma_f32_16x16x32_bf16(Bt[n][k], At[m][k], acc[ai][bj][m][n], 0, 0, 0); __builtin_amdgcn_s_setprio(0); } while (0)
; #define PG8_WAIT_L(n) asm volatile("s_waitcnt lgkmcnt(" #n ")" ::: "memory")
; template <class Epi, class Sched>
; __device__ __forceinline__ void gemm_phase(LAS unsigned char* lds, const Gemm g, const Sched& S, const Epi& E) {
;     ...
;         const bool has_next = S.next(ui + 1, nxt);
;         const char* nA = has_next ? (const char*)g.A + (size_t)nxt.pm * tstep : cA; const char* nB = has_next ? (const char*)g.Bt + (size_t)nxt.pn * tstep : cB;
;         for (int t = 0; t < nt; t += 2) {
;             const bool last = (t == nt - 2);
;             const char* a1 = cA + (size_t)(t + 1) * kstep;
;             const char* a2 = last ? nA : cA + (size_t)(t + 2) * kstep; const char* b2 = last ? nB : cB + (size_t)(t + 2) * kstep;
;             const char* a3 = a2 + kstep; const char* b3 = b2 + kstep;
;             PG8_LDB(B0, 0, 0); PG8_SCHED; PG8_LDA(At, 0, 0); PG8_STAGE(PG8_SA(1, 1), a1 + hstep, voffA);
;             PG8_WAIT_L(8); PG8_BAR; PG8_WAIT_L(0); PG8_MMA(0, 0, At, B0); PG8_BAR; PG8_SCHED;
;             PG8_LDB(B1, 0, 1); PG8_STAGE(PG8_SB(0, 0), b2, voffB);
;             PG8_BAR; PG8_WAIT_L(0); PG8_MMA(0, 1, At, B1); PG8_BAR;
;             PG8_LDA(At, 0, 1); PG8_STAGE(PG8_SA(0, 0), a2, voffA);
;             PG8_BAR; PG8_WAIT_L(0); PG8_MMA(1, 0, At, B0); PG8_BAR; PG8_SCHED;
.LBB0_825:
	s_ashr_i32 s7, s6, 31
	v_cmp_lt_i64_e32 vcc, s[8:9], v[156:157]
	s_lshl_b64 s[8:9], s[6:7], 20
	s_add_u32 s8, s22, s8
	s_addc_u32 s9, s23, s9
	s_and_b64 s[10:11], vcc, exec
	s_cselect_b32 s7, s9, s15
	s_cselect_b32 s39, s8, s14
	s_ashr_i32 s5, s4, 31
	s_lshl_b64 s[10:11], s[4:5], 20
	s_add_u32 s10, s50, s10
	s_addc_u32 s11, s51, s11
	s_and_b64 s[18:19], vcc, exec
	s_cselect_b32 s5, s11, s17
	s_cselect_b32 s40, s10, s16
	s_add_u32 s14, s14, 0x80080
	s_addc_u32 s15, s15, 0
	s_add_u32 s41, s16, 0x100
	s_addc_u32 s42, s17, 0
	s_mov_b32 s43, -2
	ds_read_b128 v[128:131], v168
	ds_read_b128 v[132:135], v168 offset:1024
	ds_read_b128 v[136:139], v168 offset:2048
	ds_read_b128 v[140:143], v168 offset:3072
	s_add_u32 s16, s14, 0xfff80080
	s_addc_u32 s17, s15, -1
	s_cmp_eq_u32 s43, 28
	s_cselect_b32 s19, s7, s17
	s_cselect_b32 s18, s39, s16
	s_cselect_b32 s17, s5, s42
	s_cselect_b32 s16, s40, s41
	s_add_i32 m0, s13, 0xc000
	ds_read_b128 v[162:165], v169
	ds_read_b128 v[172:175], v169 offset:1024
	ds_read_b128 v[176:179], v169 offset:2048
	ds_read_b128 v[180:183], v169 offset:3072
	ds_read_b128 v[184:187], v169 offset:4096
	ds_read_b128 v[188:191], v169 offset:5120
	ds_read_b128 v[192:195], v169 offset:6144
	ds_read_b128 v[196:199], v169 offset:7168
	global_load_lds_dwordx4 v152, s[14:15]
	s_add_i32 m0, s13, 0xe000
	s_nop 0
	global_load_lds_dwordx4 v154, s[14:15]
	s_waitcnt lgkmcnt(8)
	s_waitcnt vmcnt(8)
	s_setprio 1
	s_barrier
	s_waitcnt lgkmcnt(0)
	v_mfma_f32_16x16x32_bf16 v[124:127], v[128:131], v[162:165], 0
	v_mfma_f32_16x16x32_bf16 v[120:123], v[136:139], v[162:165], 0
	v_mfma_f32_16x16x32_bf16 v[116:119], v[128:131], v[176:179], 0
	v_mfma_f32_16x16x32_bf16 v[112:115], v[136:139], v[176:179], 0
	v_mfma_f32_16x16x32_bf16 v[108:111], v[128:131], v[184:187], 0
	v_mfma_f32_16x16x32_bf16 v[100:103], v[136:139], v[184:187], 0
	v_mfma_f32_16x16x32_bf16 v[76:79], v[128:131], v[192:195], 0
	v_mfma_f32_16x16x32_bf16 v[72:75], v[136:139], v[192:195], 0
	v_mfma_f32_16x16x32_bf16 v[124:127], v[132:135], v[172:175], v[124:127]
	v_mfma_f32_16x16x32_bf16 v[120:123], v[140:143], v[172:175], v[120:123]
	v_mfma_f32_16x16x32_bf16 v[116:119], v[132:135], v[180:183], v[116:119]
	v_mfma_f32_16x16x32_bf16 v[112:115], v[140:143], v[180:183], v[112:115]
	v_mfma_f32_16x16x32_bf16 v[108:111], v[132:135], v[188:191], v[108:111]
	v_mfma_f32_16x16x32_bf16 v[100:103], v[140:143], v[188:191], v[100:103]
	v_mfma_f32_16x16x32_bf16 v[76:79], v[132:135], v[196:199], v[76:79]
	v_mfma_f32_16x16x32_bf16 v[72:75], v[140:143], v[196:199], v[72:75]
	s_barrier
	s_setprio 0
	s_add_i32 s44, s35, s24
	s_mov_b32 m0, s44
	ds_read_b128 v[202:205], v170
	ds_read_b128 v[206:209], v170 offset:1024
	ds_read_b128 v[210:213], v170 offset:2048
	ds_read_b128 v[214:217], v170 offset:3072
	global_load_lds_dwordx4 v146, s[16:17]
	s_add_i32 m0, s44, 0x2000
	s_nop 0
	global_load_lds_dwordx4 v150, s[16:17]
	s_waitcnt vmcnt(8)
	s_setprio 1
	s_barrier
	s_waitcnt lgkmcnt(0)
	v_mfma_f32_16x16x32_bf16 v[104:107], v[202:205], v[162:165], 0
	v_mfma_f32_16x16x32_bf16 v[96:99], v[210:213], v[162:165], 0
	v_mfma_f32_16x16x32_bf16 v[92:95], v[202:205], v[176:179], 0
	v_mfma_f32_16x16x32_bf16 v[88:91], v[210:213], v[176:179], 0
	v_mfma_f32_16x16x32_bf16 v[84:87], v[202:205], v[184:187], 0
	v_mfma_f32_16x16x32_bf16 v[80:83], v[210:213], v[184:187], 0
	v_mfma_f32_16x16x32_bf16 v[68:71], v[202:205], v[192:195], 0
	v_mfma_f32_16x16x32_bf16 v[64:67], v[210:213], v[192:195], 0
	v_mfma_f32_16x16x32_bf16 v[104:107], v[206:209], v[172:175], v[104:107]
	v_mfma_f32_16x16x32_bf16 v[96:99], v[214:217], v[172:175], v[96:99]
	v_mfma_f32_16x16x32_bf16 v[92:95], v[206:209], v[180:183], v[92:95]
	v_mfma_f32_16x16x32_bf16 v[88:91], v[214:217], v[180:183], v[88:91]
	v_mfma_f32_16x16x32_bf16 v[84:87], v[206:209], v[188:191], v[84:87]
	v_mfma_f32_16x16x32_bf16 v[80:83], v[214:217], v[188:191], v[80:83]
	v_mfma_f32_16x16x32_bf16 v[68:71], v[206:209], v[196:199], v[68:71]
	v_mfma_f32_16x16x32_bf16 v[64:67], v[214:217], v[196:199], v[64:67]
	s_barrier
	s_setprio 0
	s_mov_b32 m0, s13
	v_lshl_add_u64 v[222:223], s[18:19], 0, v[144:145]
	ds_read_b128 v[162:165], v169 offset:16384
	ds_read_b128 v[172:175], v169 offset:17408
	ds_read_b128 v[176:179], v169 offset:18432
	ds_read_b128 v[180:183], v169 offset:19456
	ds_read_b128 v[184:187], v169 offset:20480
	ds_read_b128 v[188:191], v169 offset:21504
	ds_read_b128 v[192:195], v169 offset:22528
	ds_read_b128 v[196:199], v169 offset:23552
	global_load_lds_dwordx4 v144, s[18:19]
	v_lshl_add_u64 v[224:225], s[18:19], 0, v[148:149]
	s_mov_b32 m0, s25
	s_nop 0
	global_load_lds_dwordx4 v148, s[18:19]
	s_setprio 1
	s_barrier
	s_waitcnt lgkmcnt(0)
	v_mfma_f32_16x16x32_bf16 v[60:63], v[128:131], v[162:165], 0
	v_mfma_f32_16x16x32_bf16 v[56:59], v[136:139], v[162:165], 0
	v_mfma_f32_16x16x32_bf16 v[48:51], v[128:131], v[176:179], 0
	v_mfma_f32_16x16x32_bf16 v[40:43], v[136:139], v[176:179], 0
	v_mfma_f32_16x16x32_bf16 v[32:35], v[128:131], v[184:187], 0
	v_mfma_f32_16x16x32_bf16 v[24:27], v[136:139], v[184:187], 0
	v_mfma_f32_16x16x32_bf16 v[16:19], v[128:131], v[192:195], 0
	v_mfma_f32_16x16x32_bf16 v[8:11], v[136:139], v[192:195], 0
	v_mfma_f32_16x16x32_bf16 v[60:63], v[132:135], v[172:175], v[60:63]
	v_mfma_f32_16x16x32_bf16 v[56:59], v[140:143], v[172:175], v[56:59]
	v_mfma_f32_16x16x32_bf16 v[48:51], v[132:135], v[180:183], v[48:51]
	v_mfma_f32_16x16x32_bf16 v[40:43], v[140:143], v[180:183], v[40:43]
	v_mfma_f32_16x16x32_bf16 v[32:35], v[132:135], v[188:191], v[32:35]
	v_mfma_f32_16x16x32_bf16 v[24:27], v[140:143], v[188:191], v[24:27]
	v_mfma_f32_16x16x32_bf16 v[16:19], v[132:135], v[196:199], v[16:19]
	v_mfma_f32_16x16x32_bf16 v[8:11], v[140:143], v[196:199], v[8:11]
	s_barrier
; #define PG8_STAGE(bufoff, gbase, voff) do { _Pragma("unroll") for (int _i = 0; _i < 2; ++_i) \
;         __builtin_amdgcn_global_load_lds((const unsigned*)((const char*)(gbase) + (voff)[_i]), (LAS unsigned*)(lds + (bufoff) + ldsw + _i * 8192), 16, 0, 0); } while (0)
; #define PG8_LDA(dst, b, h) do { _Pragma("unroll") for (int m = 0; m < 4; ++m) _Pragma("unroll") for (int k = 0; k < 2; ++k) dst[m][k] = *(const LAS bf16x8*)(lds + PG8_SA(b, h) + aoff + m * 2048 + k * 1024); } while (0)
; #define PG8_LDB(dst, b, h) do { _Pragma("unroll") for (int n = 0; n < 2; ++n) _Pragma("unroll") for (int k = 0; k < 2; ++k) dst[n][k] = *(const LAS bf16x8*)(lds + PG8_SB(b, h) + boff + n * 2048 + k * 1024); } while (0)
; #define PG8_MMA(ai, bj, At, Bt) do { __builtin_amdgcn_s_setprio(1); _Pragma("unroll") for (int m = 0; m < 4; ++m) _Pragma("unroll") for (int n = 0; n < 2; ++n) _Pragma("unroll") for (int k = 0; k < 2; ++k) \
;         acc[ai][bj][m][n] = __builtin_amdgcn_mfma_f32_16x16x32_bf16(Bt[n][k], At[m][k], acc[ai][bj][m][n], 0, 0, 0); __builtin_amdgcn_s_setprio(0); } while (0)
; #define PG8_WAIT_V(n) asm volatile("s_waitcnt vmcnt(" #n ")" ::: "memory")
; #define PG8_WAIT_L(n) asm volatile("s_waitcnt lgkmcnt(" #n ")" ::: "memory")
; #define PG8_BAR __builtin_amdgcn_s_barrier()
; #define PG8_SCHED __builtin_amdgcn_sched_barrier(0)
; template <class Epi, class Sched>
; __device__ __forceinline__ void gemm_phase(LAS unsigned char* lds, const Gemm g, const Sched& S, const Epi& E) {
;     ...
;             PG8_WAIT_V(6); PG8_BAR; PG8_MMA(1, 1, At, B1); PG8_BAR;
;             PG8_LDB(B0, 1, 0); PG8_SCHED; PG8_LDA(At, 1, 0); PG8_STAGE(PG8_SA(0, 1), a2 + hstep, voffA);
;             PG8_WAIT_L(8); PG8_BAR; PG8_WAIT_L(0); PG8_MMA(0, 0, At, B0); PG8_BAR; PG8_SCHED;
;             PG8_LDB(B1, 1, 1); PG8_STAGE(PG8_SB(1, 0), b3, voffB);
;             PG8_BAR; PG8_WAIT_L(0); PG8_MMA(0, 1, At, B1); PG8_BAR;
;             PG8_LDA(At, 1, 1); PG8_STAGE(PG8_SA(1, 0), a3, voffA);
;             PG8_BAR; PG8_WAIT_L(0); PG8_MMA(1, 0, At, B0); PG8_BAR; PG8_SCHED;
	s_setprio 0
	s_add_u32 s44, s16, 0x80000
	s_addc_u32 s45, s17, 0
	s_add_i32 s46, s36, s24
	s_mov_b32 m0, s46
	s_nop 0
	global_load_lds_dwordx4 v146, s[44:45]
	s_add_i32 m0, s46, 0x2000
	s_nop 0
	global_load_lds_dwordx4 v150, s[44:45]
	s_add_u32 s18, s18, 0x80000
	s_addc_u32 s19, s19, 0
	s_mov_b32 m0, s26
	s_nop 0
	global_load_lds_dwordx4 v144, s[18:19]
	s_mov_b32 m0, s27
	s_nop 0
	global_load_lds_dwordx4 v148, s[18:19]
	s_waitcnt vmcnt(10)
	s_setprio 1
	s_barrier
	v_mfma_f32_16x16x32_bf16 v[52:55], v[202:205], v[162:165], 0
	v_mfma_f32_16x16x32_bf16 v[44:47], v[210:213], v[162:165], 0
	v_mfma_f32_16x16x32_bf16 v[36:39], v[202:205], v[176:179], 0
	v_mfma_f32_16x16x32_bf16 v[28:31], v[210:213], v[176:179], 0
	v_mfma_f32_16x16x32_bf16 v[20:23], v[202:205], v[184:187], 0
	v_mfma_f32_16x16x32_bf16 v[12:15], v[210:213], v[184:187], 0
	v_mfma_f32_16x16x32_bf16 v[4:7], v[202:205], v[192:195], 0
	v_mfma_f32_16x16x32_bf16 v[0:3], v[210:213], v[192:195], 0
	v_mfma_f32_16x16x32_bf16 v[52:55], v[206:209], v[172:175], v[52:55]
	v_mfma_f32_16x16x32_bf16 v[44:47], v[214:217], v[172:175], v[44:47]
	v_mfma_f32_16x16x32_bf16 v[36:39], v[206:209], v[180:183], v[36:39]
	v_mfma_f32_16x16x32_bf16 v[28:31], v[214:217], v[180:183], v[28:31]
	v_mfma_f32_16x16x32_bf16 v[20:23], v[206:209], v[188:191], v[20:23]
	v_mfma_f32_16x16x32_bf16 v[12:15], v[214:217], v[188:191], v[12:15]
	v_mfma_f32_16x16x32_bf16 v[4:7], v[206:209], v[196:199], v[4:7]
	v_mfma_f32_16x16x32_bf16 v[0:3], v[214:217], v[196:199], v[0:3]
	s_barrier
	s_setprio 0
	s_add_i32 s44, 0, 0x18000
	ds_read_b128 v[128:131], v170 offset:16384
	ds_read_b128 v[132:135], v170 offset:17408
	ds_read_b128 v[136:139], v170 offset:18432
	ds_read_b128 v[140:143], v170 offset:19456
	ds_read_b128 v[162:165], v169 offset:32768
	ds_read_b128 v[172:175], v169 offset:33792
	ds_read_b128 v[176:179], v169 offset:34816
	ds_read_b128 v[180:183], v169 offset:35840
	ds_read_b128 v[184:187], v169 offset:36864
	ds_read_b128 v[188:191], v169 offset:37888
	ds_read_b128 v[192:195], v169 offset:38912
	ds_read_b128 v[196:199], v169 offset:39936
	s_waitcnt lgkmcnt(8)
	s_waitcnt vmcnt(8)
	s_setprio 1
	s_barrier
	s_waitcnt lgkmcnt(0)
	v_mfma_f32_16x16x32_bf16 v[124:127], v[128:131], v[162:165], v[124:127]
	v_mfma_f32_16x16x32_bf16 v[120:123], v[136:139], v[162:165], v[120:123]
	v_mfma_f32_16x16x32_bf16 v[116:119], v[128:131], v[176:179], v[116:119]
	v_mfma_f32_16x16x32_bf16 v[112:115], v[136:139], v[176:179], v[112:115]
	v_mfma_f32_16x16x32_bf16 v[108:111], v[128:131], v[184:187], v[108:111]
	v_mfma_f32_16x16x32_bf16 v[100:103], v[136:139], v[184:187], v[100:103]
	v_mfma_f32_16x16x32_bf16 v[76:79], v[128:131], v[192:195], v[76:79]
	v_mfma_f32_16x16x32_bf16 v[72:75], v[136:139], v[192:195], v[72:75]
	v_mfma_f32_16x16x32_bf16 v[124:127], v[132:135], v[172:175], v[124:127]
	v_mfma_f32_16x16x32_bf16 v[120:123], v[140:143], v[172:175], v[120:123]
	v_mfma_f32_16x16x32_bf16 v[116:119], v[132:135], v[180:183], v[116:119]
	v_mfma_f32_16x16x32_bf16 v[112:115], v[140:143], v[180:183], v[112:115]
	v_mfma_f32_16x16x32_bf16 v[108:111], v[132:135], v[188:191], v[108:111]
	v_mfma_f32_16x16x32_bf16 v[100:103], v[140:143], v[188:191], v[100:103]
	v_mfma_f32_16x16x32_bf16 v[76:79], v[132:135], v[196:199], v[76:79]
	v_mfma_f32_16x16x32_bf16 v[72:75], v[140:143], v[196:199], v[72:75]
	s_barrier
	s_setprio 0
	s_add_i32 s18, 0, 0x1c000
	s_add_i32 s19, s44, s24
	s_add_u32 s0, s16, 0x80
	s_addc_u32 s1, s17, 0
	s_mov_b32 m0, s19
	ds_read_b128 v[202:205], v170 offset:32768
	ds_read_b128 v[206:209], v170 offset:33792
	ds_read_b128 v[210:213], v170 offset:34816
	ds_read_b128 v[214:217], v170 offset:35840
	global_load_lds_dwordx4 v146, s[0:1]
	s_add_i32 m0, s19, 0x2000
	s_nop 0
	global_load_lds_dwordx4 v150, s[0:1]
	s_waitcnt vmcnt(8)
	s_setprio 1
	s_barrier
	s_waitcnt lgkmcnt(0)
	v_mfma_f32_16x16x32_bf16 v[104:107], v[202:205], v[162:165], v[104:107]
	v_mfma_f32_16x16x32_bf16 v[96:99], v[210:213], v[162:165], v[96:99]
	v_mfma_f32_16x16x32_bf16 v[92:95], v[202:205], v[176:179], v[92:95]
	v_mfma_f32_16x16x32_bf16 v[88:91], v[210:213], v[176:179], v[88:91]
	v_mfma_f32_16x16x32_bf16 v[84:87], v[202:205], v[184:187], v[84:87]
	v_mfma_f32_16x16x32_bf16 v[80:83], v[210:213], v[184:187], v[80:83]
	v_mfma_f32_16x16x32_bf16 v[68:71], v[202:205], v[192:195], v[68:71]
	v_mfma_f32_16x16x32_bf16 v[64:67], v[210:213], v[192:195], v[64:67]
	v_mfma_f32_16x16x32_bf16 v[104:107], v[206:209], v[172:175], v[104:107]
	v_mfma_f32_16x16x32_bf16 v[96:99], v[214:217], v[172:175], v[96:99]
	v_mfma_f32_16x16x32_bf16 v[92:95], v[206:209], v[180:183], v[92:95]
	v_mfma_f32_16x16x32_bf16 v[88:91], v[214:217], v[180:183], v[88:91]
	v_mfma_f32_16x16x32_bf16 v[84:87], v[206:209], v[188:191], v[84:87]
	v_mfma_f32_16x16x32_bf16 v[80:83], v[214:217], v[188:191], v[80:83]
	v_mfma_f32_16x16x32_bf16 v[68:71], v[206:209], v[196:199], v[68:71]
	v_mfma_f32_16x16x32_bf16 v[64:67], v[214:217], v[196:199], v[64:67]
	s_barrier
	s_setprio 0
	s_mov_b32 m0, s31
	s_mov_b64 s[0:1], 0x80
	v_lshl_add_u64 v[218:219], v[222:223], 0, s[0:1]
	ds_read_b128 v[162:165], v169 offset:49152
	ds_read_b128 v[172:175], v169 offset:50176
	ds_read_b128 v[176:179], v169 offset:51200
	ds_read_b128 v[180:183], v169 offset:52224
	ds_read_b128 v[184:187], v169 offset:53248
	ds_read_b128 v[188:191], v169 offset:54272
	ds_read_b128 v[192:195], v169 offset:55296
	ds_read_b128 v[196:199], v169 offset:56320
	global_load_lds_dwordx4 v[218:219], off
	v_lshl_add_u64 v[218:219], v[224:225], 0, s[0:1]
	s_mov_b32 m0, s33
	s_nop 0
	global_load_lds_dwordx4 v[218:219], off
	s_setprio 1
	s_barrier
; #define PG8_STAGE(bufoff, gbase, voff) do { _Pragma("unroll") for (int _i = 0; _i < 2; ++_i) \
;         __builtin_amdgcn_global_load_lds((const unsigned*)((const char*)(gbase) + (voff)[_i]), (LAS unsigned*)(lds + (bufoff) + ldsw + _i * 8192), 16, 0, 0); } while (0)
; #define PG8_LDA(dst, b, h) do { _Pragma("unroll") for (int m = 0; m < 4; ++m) _Pragma("unroll") for (int k = 0; k < 2; ++k) dst[m][k] = *(const LAS bf16x8*)(lds + PG8_SA(b, h) + aoff + m * 2048 + k * 1024); } while (0)
; #define PG8_LDB(dst, b, h) do { _Pragma("unroll") for (int n = 0; n < 2; ++n) _Pragma("unroll") for (int k = 0; k < 2; ++k) dst[n][k] = *(const LAS bf16x8*)(lds + PG8_SB(b, h) + boff + n * 2048 + k * 1024); } while (0)
; #define PG8_MMA(ai, bj, At, Bt) do { __builtin_amdgcn_s_setprio(1); _Pragma("unroll") for (int m = 0; m < 4; ++m) _Pragma("unroll") for (int n = 0; n < 2; ++n) _Pragma("unroll") for (int k = 0; k < 2; ++k) \
;         acc[ai][bj][m][n] = __builtin_amdgcn_mfma_f32_16x16x32_bf16(Bt[n][k], At[m][k], acc[ai][bj][m][n], 0, 0, 0); __builtin_amdgcn_s_setprio(0); } while (0)
; #define PG8_WAIT_V(n) asm volatile("s_waitcnt vmcnt(" #n ")" ::: "memory")
; #define PG8_WAIT_L(n) asm volatile("s_waitcnt lgkmcnt(" #n ")" ::: "memory")
; #define PG8_BAR __builtin_amdgcn_s_barrier()
; #define PG8_SCHED __builtin_amdgcn_sched_barrier(0)
; template <class Epi, class Sched>
; __device__ __forceinline__ void gemm_phase(LAS unsigned char* lds, const Gemm g, const Sched& S, const Epi& E) {
;     ...
;         for (int t = 0; t < nt; t += 2) {
;             const bool last = (t == nt - 2);
;             const char* a1 = cA + (size_t)(t + 1) * kstep;
;             const char* a2 = last ? nA : cA + (size_t)(t + 2) * kstep; const char* b2 = last ? nB : cB + (size_t)(t + 2) * kstep;
;             const char* a3 = a2 + kstep; const char* b3 = b2 + kstep;
;             PG8_LDB(B0, 0, 0); PG8_SCHED; PG8_LDA(At, 0, 0); PG8_STAGE(PG8_SA(1, 1), a1 + hstep, voffA);
;             PG8_WAIT_L(8); PG8_BAR; PG8_WAIT_L(0); PG8_MMA(0, 0, At, B0); PG8_BAR; PG8_SCHED;
;             PG8_LDB(B1, 0, 1); PG8_STAGE(PG8_SB(0, 0), b2, voffB);
;     ...
;             PG8_BAR; PG8_WAIT_L(0); PG8_MMA(1, 0, At, B0); PG8_BAR; PG8_SCHED;
;             PG8_STAGE(PG8_SB(1, 1), b3 + hstep, voffB);
;             PG8_WAIT_V(6); PG8_BAR; PG8_MMA(1, 1, At, B1); PG8_BAR;
	s_waitcnt lgkmcnt(0)
	v_mfma_f32_16x16x32_bf16 v[60:63], v[128:131], v[162:165], v[60:63]
	v_mfma_f32_16x16x32_bf16 v[56:59], v[136:139], v[162:165], v[56:59]
	v_mfma_f32_16x16x32_bf16 v[48:51], v[128:131], v[176:179], v[48:51]
	v_mfma_f32_16x16x32_bf16 v[40:43], v[136:139], v[176:179], v[40:43]
	v_mfma_f32_16x16x32_bf16 v[32:35], v[128:131], v[184:187], v[32:35]
	v_mfma_f32_16x16x32_bf16 v[24:27], v[136:139], v[184:187], v[24:27]
	v_mfma_f32_16x16x32_bf16 v[16:19], v[128:131], v[192:195], v[16:19]
	v_mfma_f32_16x16x32_bf16 v[8:11], v[136:139], v[192:195], v[8:11]
	v_mfma_f32_16x16x32_bf16 v[60:63], v[132:135], v[172:175], v[60:63]
	v_mfma_f32_16x16x32_bf16 v[56:59], v[140:143], v[172:175], v[56:59]
	v_mfma_f32_16x16x32_bf16 v[48:51], v[132:135], v[180:183], v[48:51]
	v_mfma_f32_16x16x32_bf16 v[40:43], v[140:143], v[180:183], v[40:43]
	v_mfma_f32_16x16x32_bf16 v[32:35], v[132:135], v[188:191], v[32:35]
	v_mfma_f32_16x16x32_bf16 v[24:27], v[140:143], v[188:191], v[24:27]
	v_mfma_f32_16x16x32_bf16 v[16:19], v[132:135], v[196:199], v[16:19]
	v_mfma_f32_16x16x32_bf16 v[8:11], v[140:143], v[196:199], v[8:11]
	s_barrier
	s_setprio 0
	s_add_u32 s16, s16, 0x80080
	s_addc_u32 s17, s17, 0
	s_add_i32 s18, s18, s24
	s_mov_b32 m0, s18
	s_nop 0
	global_load_lds_dwordx4 v146, s[16:17]
	s_add_i32 m0, s18, 0x2000
	s_nop 0
	global_load_lds_dwordx4 v150, s[16:17]
	s_waitcnt vmcnt(8)
	s_setprio 1
	s_barrier
	v_mfma_f32_16x16x32_bf16 v[52:55], v[202:205], v[162:165], v[52:55]
	v_mfma_f32_16x16x32_bf16 v[44:47], v[210:213], v[162:165], v[44:47]
	v_mfma_f32_16x16x32_bf16 v[36:39], v[202:205], v[176:179], v[36:39]
	v_mfma_f32_16x16x32_bf16 v[28:31], v[210:213], v[176:179], v[28:31]
	v_mfma_f32_16x16x32_bf16 v[20:23], v[202:205], v[184:187], v[20:23]
	v_mfma_f32_16x16x32_bf16 v[12:15], v[210:213], v[184:187], v[12:15]
	v_mfma_f32_16x16x32_bf16 v[4:7], v[202:205], v[192:195], v[4:7]
	v_mfma_f32_16x16x32_bf16 v[0:3], v[210:213], v[192:195], v[0:3]
	v_mfma_f32_16x16x32_bf16 v[52:55], v[206:209], v[172:175], v[52:55]
	v_mfma_f32_16x16x32_bf16 v[44:47], v[214:217], v[172:175], v[44:47]
	v_mfma_f32_16x16x32_bf16 v[36:39], v[206:209], v[180:183], v[36:39]
	v_mfma_f32_16x16x32_bf16 v[28:31], v[214:217], v[180:183], v[28:31]
	v_mfma_f32_16x16x32_bf16 v[20:23], v[206:209], v[188:191], v[20:23]
	v_mfma_f32_16x16x32_bf16 v[12:15], v[214:217], v[188:191], v[12:15]
	v_mfma_f32_16x16x32_bf16 v[4:7], v[206:209], v[196:199], v[4:7]
	v_mfma_f32_16x16x32_bf16 v[0:3], v[214:217], v[196:199], v[0:3]
	s_barrier
	s_setprio 0
	s_add_i32 s43, s43, 2
	s_add_u32 s14, s14, 0x100
	s_addc_u32 s15, s15, 0
	s_add_u32 s41, s41, 0x100
	s_addc_u32 s42, s42, 0
	s_cmp_gt_u32 s43, 29
.LBB0_826:
	ds_read_b128 v[128:131], v168
	ds_read_b128 v[132:135], v168 offset:1024
	ds_read_b128 v[136:139], v168 offset:2048
	ds_read_b128 v[140:143], v168 offset:3072
	s_add_u32 s16, s14, 0xfff80080
	s_addc_u32 s17, s15, -1
	s_cmp_eq_u32 s43, 28
	s_cselect_b32 s19, s7, s17
	s_cselect_b32 s18, s39, s16
	s_cselect_b32 s17, s5, s42
	s_cselect_b32 s16, s40, s41
	s_add_i32 m0, s13, 0xc000
	ds_read_b128 v[162:165], v169
	ds_read_b128 v[172:175], v169 offset:1024
	ds_read_b128 v[176:179], v169 offset:2048
	ds_read_b128 v[180:183], v169 offset:3072
	ds_read_b128 v[184:187], v169 offset:4096
	ds_read_b128 v[188:191], v169 offset:5120
	ds_read_b128 v[192:195], v169 offset:6144
	ds_read_b128 v[196:199], v169 offset:7168
	global_load_lds_dwordx4 v152, s[14:15]
	s_add_i32 m0, s13, 0xe000
	s_nop 0
	global_load_lds_dwordx4 v154, s[14:15]
	s_waitcnt lgkmcnt(8)
	s_waitcnt vmcnt(8)
	s_setprio 1
	s_barrier
	s_waitcnt lgkmcnt(0)
	v_mfma_f32_16x16x32_bf16 v[124:127], v[128:131], v[162:165], v[124:127]
	v_mfma_f32_16x16x32_bf16 v[120:123], v[136:139], v[162:165], v[120:123]
	v_mfma_f32_16x16x32_bf16 v[116:119], v[128:131], v[176:179], v[116:119]
	v_mfma_f32_16x16x32_bf16 v[112:115], v[136:139], v[176:179], v[112:115]
	v_mfma_f32_16x16x32_bf16 v[108:111], v[128:131], v[184:187], v[108:111]
	v_mfma_f32_16x16x32_bf16 v[100:103], v[136:139], v[184:187], v[100:103]
	v_mfma_f32_16x16x32_bf16 v[76:79], v[128:131], v[192:195], v[76:79]
	v_mfma_f32_16x16x32_bf16 v[72:75], v[136:139], v[192:195], v[72:75]
	v_mfma_f32_16x16x32_bf16 v[124:127], v[132:135], v[172:175], v[124:127]
	v_mfma_f32_16x16x32_bf16 v[120:123], v[140:143], v[172:175], v[120:123]
	v_mfma_f32_16x16x32_bf16 v[116:119], v[132:135], v[180:183], v[116:119]
	v_mfma_f32_16x16x32_bf16 v[112:115], v[140:143], v[180:183], v[112:115]
	v_mfma_f32_16x16x32_bf16 v[108:111], v[132:135], v[188:191], v[108:111]
	v_mfma_f32_16x16x32_bf16 v[100:103], v[140:143], v[188:191], v[100:103]
	v_mfma_f32_16x16x32_bf16 v[76:79], v[132:135], v[196:199], v[76:79]
	v_mfma_f32_16x16x32_bf16 v[72:75], v[140:143], v[196:199], v[72:75]
	s_barrier
	s_setprio 0
	s_add_i32 s44, s35, s24
	s_mov_b32 m0, s44
	ds_read_b128 v[202:205], v170
	ds_read_b128 v[206:209], v170 offset:1024
	ds_read_b128 v[210:213], v170 offset:2048
	ds_read_b128 v[214:217], v170 offset:3072
	global_load_lds_dwordx4 v146, s[16:17]
	s_add_i32 m0, s44, 0x2000
	s_nop 0
	global_load_lds_dwordx4 v150, s[16:17]
	s_waitcnt vmcnt(8)
	s_setprio 1
	s_barrier
; #define PG8_STAGE(bufoff, gbase, voff) do { _Pragma("unroll") for (int _i = 0; _i < 2; ++_i) \
;         __builtin_amdgcn_global_load_lds((const unsigned*)((const char*)(gbase) + (voff)[_i]), (LAS unsigned*)(lds + (bufoff) + ldsw + _i * 8192), 16, 0, 0); } while (0)
; #define PG8_LDA(dst, b, h) do { _Pragma("unroll") for (int m = 0; m < 4; ++m) _Pragma("unroll") for (int k = 0; k < 2; ++k) dst[m][k] = *(const LAS bf16x8*)(lds + PG8_SA(b, h) + aoff + m * 2048 + k * 1024); } while (0)
; #define PG8_LDB(dst, b, h) do { _Pragma("unroll") for (int n = 0; n < 2; ++n) _Pragma("unroll") for (int k = 0; k < 2; ++k) dst[n][k] = *(const LAS bf16x8*)(lds + PG8_SB(b, h) + boff + n * 2048 + k * 1024); } while (0)
; #define PG8_MMA(ai, bj, At, Bt) do { __builtin_amdgcn_s_setprio(1); _Pragma("unroll") for (int m = 0; m < 4; ++m) _Pragma("unroll") for (int n = 0; n < 2; ++n) _Pragma("unroll") for (int k = 0; k < 2; ++k) \
;         acc[ai][bj][m][n] = __builtin_amdgcn_mfma_f32_16x16x32_bf16(Bt[n][k], At[m][k], acc[ai][bj][m][n], 0, 0, 0); __builtin_amdgcn_s_setprio(0); } while (0)
; #define PG8_WAIT_V(n) asm volatile("s_waitcnt vmcnt(" #n ")" ::: "memory")
; #define PG8_WAIT_L(n) asm volatile("s_waitcnt lgkmcnt(" #n ")" ::: "memory")
; #define PG8_BAR __builtin_amdgcn_s_barrier()
; #define PG8_SCHED __builtin_amdgcn_sched_barrier(0)
; template <class Epi, class Sched>
; __device__ __forceinline__ void gemm_phase(LAS unsigned char* lds, const Gemm g, const Sched& S, const Epi& E) {
;     ...
;             PG8_BAR; PG8_WAIT_L(0); PG8_MMA(0, 1, At, B1); PG8_BAR;
;             PG8_LDA(At, 0, 1); PG8_STAGE(PG8_SA(0, 0), a2, voffA);
;             PG8_BAR; PG8_WAIT_L(0); PG8_MMA(1, 0, At, B0); PG8_BAR; PG8_SCHED;
;             PG8_STAGE(PG8_SB(0, 1), b2 + hstep, voffB);
;             PG8_WAIT_V(6); PG8_BAR; PG8_MMA(1, 1, At, B1); PG8_BAR;
;             PG8_LDB(B0, 1, 0); PG8_SCHED; PG8_LDA(At, 1, 0); PG8_STAGE(PG8_SA(0, 1), a2 + hstep, voffA);
;             PG8_WAIT_L(8); PG8_BAR; PG8_WAIT_L(0); PG8_MMA(0, 0, At, B0); PG8_BAR; PG8_SCHED;
	s_waitcnt lgkmcnt(0)
	v_mfma_f32_16x16x32_bf16 v[104:107], v[202:205], v[162:165], v[104:107]
	v_mfma_f32_16x16x32_bf16 v[96:99], v[210:213], v[162:165], v[96:99]
	v_mfma_f32_16x16x32_bf16 v[92:95], v[202:205], v[176:179], v[92:95]
	v_mfma_f32_16x16x32_bf16 v[88:91], v[210:213], v[176:179], v[88:91]
	v_mfma_f32_16x16x32_bf16 v[84:87], v[202:205], v[184:187], v[84:87]
	v_mfma_f32_16x16x32_bf16 v[80:83], v[210:213], v[184:187], v[80:83]
	v_mfma_f32_16x16x32_bf16 v[68:71], v[202:205], v[192:195], v[68:71]
	v_mfma_f32_16x16x32_bf16 v[64:67], v[210:213], v[192:195], v[64:67]
	v_mfma_f32_16x16x32_bf16 v[104:107], v[206:209], v[172:175], v[104:107]
	v_mfma_f32_16x16x32_bf16 v[96:99], v[214:217], v[172:175], v[96:99]
	v_mfma_f32_16x16x32_bf16 v[92:95], v[206:209], v[180:183], v[92:95]
	v_mfma_f32_16x16x32_bf16 v[88:91], v[214:217], v[180:183], v[88:91]
	v_mfma_f32_16x16x32_bf16 v[84:87], v[206:209], v[188:191], v[84:87]
	v_mfma_f32_16x16x32_bf16 v[80:83], v[214:217], v[188:191], v[80:83]
	v_mfma_f32_16x16x32_bf16 v[68:71], v[206:209], v[196:199], v[68:71]
	v_mfma_f32_16x16x32_bf16 v[64:67], v[214:217], v[196:199], v[64:67]
	s_barrier
	s_setprio 0
	s_mov_b32 m0, s13
	v_lshl_add_u64 v[222:223], s[18:19], 0, v[144:145]
	ds_read_b128 v[162:165], v169 offset:16384
	ds_read_b128 v[172:175], v169 offset:17408
	ds_read_b128 v[176:179], v169 offset:18432
	ds_read_b128 v[180:183], v169 offset:19456
	ds_read_b128 v[184:187], v169 offset:20480
	ds_read_b128 v[188:191], v169 offset:21504
	ds_read_b128 v[192:195], v169 offset:22528
	ds_read_b128 v[196:199], v169 offset:23552
	global_load_lds_dwordx4 v144, s[18:19]
	v_lshl_add_u64 v[224:225], s[18:19], 0, v[148:149]
	s_mov_b32 m0, s25
	s_nop 0
	global_load_lds_dwordx4 v148, s[18:19]
	s_setprio 1
	s_barrier
	s_waitcnt lgkmcnt(0)
	v_mfma_f32_16x16x32_bf16 v[60:63], v[128:131], v[162:165], v[60:63]
	v_mfma_f32_16x16x32_bf16 v[56:59], v[136:139], v[162:165], v[56:59]
	v_mfma_f32_16x16x32_bf16 v[48:51], v[128:131], v[176:179], v[48:51]
	v_mfma_f32_16x16x32_bf16 v[40:43], v[136:139], v[176:179], v[40:43]
	v_mfma_f32_16x16x32_bf16 v[32:35], v[128:131], v[184:187], v[32:35]
	v_mfma_f32_16x16x32_bf16 v[24:27], v[136:139], v[184:187], v[24:27]
	v_mfma_f32_16x16x32_bf16 v[16:19], v[128:131], v[192:195], v[16:19]
	v_mfma_f32_16x16x32_bf16 v[8:11], v[136:139], v[192:195], v[8:11]
	v_mfma_f32_16x16x32_bf16 v[60:63], v[132:135], v[172:175], v[60:63]
	v_mfma_f32_16x16x32_bf16 v[56:59], v[140:143], v[172:175], v[56:59]
	v_mfma_f32_16x16x32_bf16 v[48:51], v[132:135], v[180:183], v[48:51]
	v_mfma_f32_16x16x32_bf16 v[40:43], v[140:143], v[180:183], v[40:43]
	v_mfma_f32_16x16x32_bf16 v[32:35], v[132:135], v[188:191], v[32:35]
	v_mfma_f32_16x16x32_bf16 v[24:27], v[140:143], v[188:191], v[24:27]
	v_mfma_f32_16x16x32_bf16 v[16:19], v[132:135], v[196:199], v[16:19]
	v_mfma_f32_16x16x32_bf16 v[8:11], v[140:143], v[196:199], v[8:11]
	s_barrier
	s_setprio 0
	s_add_u32 s44, s16, 0x80000
	s_addc_u32 s45, s17, 0
	s_add_i32 s46, s36, s24
	s_mov_b32 m0, s46
	s_nop 0
	global_load_lds_dwordx4 v146, s[44:45]
	s_add_i32 m0, s46, 0x2000
	s_nop 0
	global_load_lds_dwordx4 v150, s[44:45]
	s_add_u32 s18, s18, 0x80000
	s_addc_u32 s19, s19, 0
	s_mov_b32 m0, s26
	s_nop 0
	global_load_lds_dwordx4 v144, s[18:19]
	s_mov_b32 m0, s27
	s_nop 0
	global_load_lds_dwordx4 v148, s[18:19]
	s_waitcnt vmcnt(10)
	s_setprio 1
	s_barrier
	v_mfma_f32_16x16x32_bf16 v[52:55], v[202:205], v[162:165], v[52:55]
	v_mfma_f32_16x16x32_bf16 v[44:47], v[210:213], v[162:165], v[44:47]
	v_mfma_f32_16x16x32_bf16 v[36:39], v[202:205], v[176:179], v[36:39]
	v_mfma_f32_16x16x32_bf16 v[28:31], v[210:213], v[176:179], v[28:31]
	v_mfma_f32_16x16x32_bf16 v[20:23], v[202:205], v[184:187], v[20:23]
	v_mfma_f32_16x16x32_bf16 v[12:15], v[210:213], v[184:187], v[12:15]
	v_mfma_f32_16x16x32_bf16 v[4:7], v[202:205], v[192:195], v[4:7]
	v_mfma_f32_16x16x32_bf16 v[0:3], v[210:213], v[192:195], v[0:3]
	v_mfma_f32_16x16x32_bf16 v[52:55], v[206:209], v[172:175], v[52:55]
	v_mfma_f32_16x16x32_bf16 v[44:47], v[214:217], v[172:175], v[44:47]
	v_mfma_f32_16x16x32_bf16 v[36:39], v[206:209], v[180:183], v[36:39]
	v_mfma_f32_16x16x32_bf16 v[28:31], v[214:217], v[180:183], v[28:31]
	v_mfma_f32_16x16x32_bf16 v[20:23], v[206:209], v[188:191], v[20:23]
	v_mfma_f32_16x16x32_bf16 v[12:15], v[214:217], v[188:191], v[12:15]
	v_mfma_f32_16x16x32_bf16 v[4:7], v[206:209], v[196:199], v[4:7]
	v_mfma_f32_16x16x32_bf16 v[0:3], v[214:217], v[196:199], v[0:3]
	s_barrier
	s_setprio 0
	s_add_i32 s44, 0, 0x18000
	ds_read_b128 v[128:131], v170 offset:16384
	ds_read_b128 v[132:135], v170 offset:17408
	ds_read_b128 v[136:139], v170 offset:18432
	ds_read_b128 v[140:143], v170 offset:19456
	ds_read_b128 v[162:165], v169 offset:32768
	ds_read_b128 v[172:175], v169 offset:33792
	ds_read_b128 v[176:179], v169 offset:34816
	ds_read_b128 v[180:183], v169 offset:35840
	ds_read_b128 v[184:187], v169 offset:36864
	ds_read_b128 v[188:191], v169 offset:37888
	ds_read_b128 v[192:195], v169 offset:38912
	ds_read_b128 v[196:199], v169 offset:39936
	s_waitcnt lgkmcnt(8)
	s_waitcnt vmcnt(8)
	s_setprio 1
	s_barrier
; #define PG8_STAGE(bufoff, gbase, voff) do { _Pragma("unroll") for (int _i = 0; _i < 2; ++_i) \
;         __builtin_amdgcn_global_load_lds((const unsigned*)((const char*)(gbase) + (voff)[_i]), (LAS unsigned*)(lds + (bufoff) + ldsw + _i * 8192), 16, 0, 0); } while (0)
; #define PG8_LDA(dst, b, h) do { _Pragma("unroll") for (int m = 0; m < 4; ++m) _Pragma("unroll") for (int k = 0; k < 2; ++k) dst[m][k] = *(const LAS bf16x8*)(lds + PG8_SA(b, h) + aoff + m * 2048 + k * 1024); } while (0)
; #define PG8_LDB(dst, b, h) do { _Pragma("unroll") for (int n = 0; n < 2; ++n) _Pragma("unroll") for (int k = 0; k < 2; ++k) dst[n][k] = *(const LAS bf16x8*)(lds + PG8_SB(b, h) + boff + n * 2048 + k * 1024); } while (0)
; #define PG8_MMA(ai, bj, At, Bt) do { __builtin_amdgcn_s_setprio(1); _Pragma("unroll") for (int m = 0; m < 4; ++m) _Pragma("unroll") for (int n = 0; n < 2; ++n) _Pragma("unroll") for (int k = 0; k < 2; ++k) \
;         acc[ai][bj][m][n] = __builtin_amdgcn_mfma_f32_16x16x32_bf16(Bt[n][k], At[m][k], acc[ai][bj][m][n], 0, 0, 0); __builtin_amdgcn_s_setprio(0); } while (0)
; #define PG8_WAIT_V(n) asm volatile("s_waitcnt vmcnt(" #n ")" ::: "memory")
; #define PG8_WAIT_L(n) asm volatile("s_waitcnt lgkmcnt(" #n ")" ::: "memory")
; #define PG8_BAR __builtin_amdgcn_s_barrier()
; #define PG8_SCHED __builtin_amdgcn_sched_barrier(0)
; template <class Epi, class Sched>
; __device__ __forceinline__ void gemm_phase(LAS unsigned char* lds, const Gemm g, const Sched& S, const Epi& E) {
;     ...
;             PG8_WAIT_L(8); PG8_BAR; PG8_WAIT_L(0); PG8_MMA(0, 0, At, B0); PG8_BAR; PG8_SCHED;
;             PG8_LDB(B1, 1, 1); PG8_STAGE(PG8_SB(1, 0), b3, voffB);
;             PG8_BAR; PG8_WAIT_L(0); PG8_MMA(0, 1, At, B1); PG8_BAR;
;             PG8_LDA(At, 1, 1); PG8_STAGE(PG8_SA(1, 0), a3, voffA);
;             PG8_BAR; PG8_WAIT_L(0); PG8_MMA(1, 0, At, B0); PG8_BAR; PG8_SCHED;
;             PG8_STAGE(PG8_SB(1, 1), b3 + hstep, voffB);
;             PG8_WAIT_V(6); PG8_BAR; PG8_MMA(1, 1, At, B1); PG8_BAR;
	s_waitcnt lgkmcnt(0)
	v_mfma_f32_16x16x32_bf16 v[124:127], v[128:131], v[162:165], v[124:127]
	v_mfma_f32_16x16x32_bf16 v[120:123], v[136:139], v[162:165], v[120:123]
	v_mfma_f32_16x16x32_bf16 v[116:119], v[128:131], v[176:179], v[116:119]
	v_mfma_f32_16x16x32_bf16 v[112:115], v[136:139], v[176:179], v[112:115]
	v_mfma_f32_16x16x32_bf16 v[108:111], v[128:131], v[184:187], v[108:111]
	v_mfma_f32_16x16x32_bf16 v[100:103], v[136:139], v[184:187], v[100:103]
	v_mfma_f32_16x16x32_bf16 v[76:79], v[128:131], v[192:195], v[76:79]
	v_mfma_f32_16x16x32_bf16 v[72:75], v[136:139], v[192:195], v[72:75]
	v_mfma_f32_16x16x32_bf16 v[124:127], v[132:135], v[172:175], v[124:127]
	v_mfma_f32_16x16x32_bf16 v[120:123], v[140:143], v[172:175], v[120:123]
	v_mfma_f32_16x16x32_bf16 v[116:119], v[132:135], v[180:183], v[116:119]
	v_mfma_f32_16x16x32_bf16 v[112:115], v[140:143], v[180:183], v[112:115]
	v_mfma_f32_16x16x32_bf16 v[108:111], v[132:135], v[188:191], v[108:111]
	v_mfma_f32_16x16x32_bf16 v[100:103], v[140:143], v[188:191], v[100:103]
	v_mfma_f32_16x16x32_bf16 v[76:79], v[132:135], v[196:199], v[76:79]
	v_mfma_f32_16x16x32_bf16 v[72:75], v[140:143], v[196:199], v[72:75]
	s_barrier
	s_setprio 0
	s_add_i32 s18, 0, 0x1c000
	s_add_i32 s19, s44, s24
	s_add_u32 s0, s16, 0x80
	s_addc_u32 s1, s17, 0
	s_mov_b32 m0, s19
	ds_read_b128 v[202:205], v170 offset:32768
	ds_read_b128 v[206:209], v170 offset:33792
	ds_read_b128 v[210:213], v170 offset:34816
	ds_read_b128 v[214:217], v170 offset:35840
	global_load_lds_dwordx4 v146, s[0:1]
	s_add_i32 m0, s19, 0x2000
	s_nop 0
	global_load_lds_dwordx4 v150, s[0:1]
	s_waitcnt vmcnt(8)
	s_setprio 1
	s_barrier
	s_waitcnt lgkmcnt(0)
	v_mfma_f32_16x16x32_bf16 v[104:107], v[202:205], v[162:165], v[104:107]
	v_mfma_f32_16x16x32_bf16 v[96:99], v[210:213], v[162:165], v[96:99]
	v_mfma_f32_16x16x32_bf16 v[92:95], v[202:205], v[176:179], v[92:95]
	v_mfma_f32_16x16x32_bf16 v[88:91], v[210:213], v[176:179], v[88:91]
	v_mfma_f32_16x16x32_bf16 v[84:87], v[202:205], v[184:187], v[84:87]
	v_mfma_f32_16x16x32_bf16 v[80:83], v[210:213], v[184:187], v[80:83]
	v_mfma_f32_16x16x32_bf16 v[68:71], v[202:205], v[192:195], v[68:71]
	v_mfma_f32_16x16x32_bf16 v[64:67], v[210:213], v[192:195], v[64:67]
	v_mfma_f32_16x16x32_bf16 v[104:107], v[206:209], v[172:175], v[104:107]
	v_mfma_f32_16x16x32_bf16 v[96:99], v[214:217], v[172:175], v[96:99]
	v_mfma_f32_16x16x32_bf16 v[92:95], v[206:209], v[180:183], v[92:95]
	v_mfma_f32_16x16x32_bf16 v[88:91], v[214:217], v[180:183], v[88:91]
	v_mfma_f32_16x16x32_bf16 v[84:87], v[206:209], v[188:191], v[84:87]
	v_mfma_f32_16x16x32_bf16 v[80:83], v[214:217], v[188:191], v[80:83]
	v_mfma_f32_16x16x32_bf16 v[68:71], v[206:209], v[196:199], v[68:71]
	v_mfma_f32_16x16x32_bf16 v[64:67], v[214:217], v[196:199], v[64:67]
	s_barrier
	s_setprio 0
	s_mov_b32 m0, s31
	s_mov_b64 s[0:1], 0x80
	v_lshl_add_u64 v[218:219], v[222:223], 0, s[0:1]
	ds_read_b128 v[162:165], v169 offset:49152
	ds_read_b128 v[172:175], v169 offset:50176
	ds_read_b128 v[176:179], v169 offset:51200
	ds_read_b128 v[180:183], v169 offset:52224
	ds_read_b128 v[184:187], v169 offset:53248
	ds_read_b128 v[188:191], v169 offset:54272
	ds_read_b128 v[192:195], v169 offset:55296
	ds_read_b128 v[196:199], v169 offset:56320
	global_load_lds_dwordx4 v[218:219], off
	v_lshl_add_u64 v[218:219], v[224:225], 0, s[0:1]
	s_mov_b32 m0, s33
	s_nop 0
	global_load_lds_dwordx4 v[218:219], off
	s_setprio 1
	s_barrier
	s_waitcnt lgkmcnt(0)
	v_mfma_f32_16x16x32_bf16 v[60:63], v[128:131], v[162:165], v[60:63]
	v_mfma_f32_16x16x32_bf16 v[56:59], v[136:139], v[162:165], v[56:59]
	v_mfma_f32_16x16x32_bf16 v[48:51], v[128:131], v[176:179], v[48:51]
	v_mfma_f32_16x16x32_bf16 v[40:43], v[136:139], v[176:179], v[40:43]
	v_mfma_f32_16x16x32_bf16 v[32:35], v[128:131], v[184:187], v[32:35]
	v_mfma_f32_16x16x32_bf16 v[24:27], v[136:139], v[184:187], v[24:27]
	v_mfma_f32_16x16x32_bf16 v[16:19], v[128:131], v[192:195], v[16:19]
	v_mfma_f32_16x16x32_bf16 v[8:11], v[136:139], v[192:195], v[8:11]
	v_mfma_f32_16x16x32_bf16 v[60:63], v[132:135], v[172:175], v[60:63]
	v_mfma_f32_16x16x32_bf16 v[56:59], v[140:143], v[172:175], v[56:59]
	v_mfma_f32_16x16x32_bf16 v[48:51], v[132:135], v[180:183], v[48:51]
	v_mfma_f32_16x16x32_bf16 v[40:43], v[140:143], v[180:183], v[40:43]
	v_mfma_f32_16x16x32_bf16 v[32:35], v[132:135], v[188:191], v[32:35]
	v_mfma_f32_16x16x32_bf16 v[24:27], v[140:143], v[188:191], v[24:27]
	v_mfma_f32_16x16x32_bf16 v[16:19], v[132:135], v[196:199], v[16:19]
	v_mfma_f32_16x16x32_bf16 v[8:11], v[140:143], v[196:199], v[8:11]
	s_barrier
	s_setprio 0
	s_add_u32 s16, s16, 0x80080
	s_addc_u32 s17, s17, 0
	s_add_i32 s18, s18, s24
	s_mov_b32 m0, s18
	s_nop 0
	global_load_lds_dwordx4 v146, s[16:17]
	s_add_i32 m0, s18, 0x2000
	s_nop 0
	global_load_lds_dwordx4 v150, s[16:17]
	s_waitcnt vmcnt(8)
	s_setprio 1
	s_barrier
	v_mfma_f32_16x16x32_bf16 v[52:55], v[202:205], v[162:165], v[52:55]
	v_mfma_f32_16x16x32_bf16 v[44:47], v[210:213], v[162:165], v[44:47]
	v_mfma_f32_16x16x32_bf16 v[36:39], v[202:205], v[176:179], v[36:39]
	v_mfma_f32_16x16x32_bf16 v[28:31], v[210:213], v[176:179], v[28:31]
	v_mfma_f32_16x16x32_bf16 v[20:23], v[202:205], v[184:187], v[20:23]
	v_mfma_f32_16x16x32_bf16 v[12:15], v[210:213], v[184:187], v[12:15]
	v_mfma_f32_16x16x32_bf16 v[4:7], v[202:205], v[192:195], v[4:7]
	v_mfma_f32_16x16x32_bf16 v[0:3], v[210:213], v[192:195], v[0:3]
	v_mfma_f32_16x16x32_bf16 v[52:55], v[206:209], v[172:175], v[52:55]
	v_mfma_f32_16x16x32_bf16 v[44:47], v[214:217], v[172:175], v[44:47]
	v_mfma_f32_16x16x32_bf16 v[36:39], v[206:209], v[180:183], v[36:39]
	v_mfma_f32_16x16x32_bf16 v[28:31], v[214:217], v[180:183], v[28:31]
	v_mfma_f32_16x16x32_bf16 v[20:23], v[206:209], v[188:191], v[20:23]
	v_mfma_f32_16x16x32_bf16 v[12:15], v[214:217], v[188:191], v[12:15]
	v_mfma_f32_16x16x32_bf16 v[4:7], v[206:209], v[196:199], v[4:7]
	v_mfma_f32_16x16x32_bf16 v[0:3], v[214:217], v[196:199], v[0:3]
	s_barrier
; __device__ __forceinline__ unsigned cvt_pk_bf16(float lo, float hi) { unsigned r; asm volatile("v_cvt_pk_bf16_f32 %0, %1, %2" : "=v"(r) : "v"(lo), "v"(hi)); return r; }
;     __device__ __forceinline__ void operator()(const AccT& acc, const Unit& u, int wr, int wc, int fr, int fq) const {
;         asm volatile("" : "+v"(fr), "+v"(fq));
;         const int row0 = u.pm * 256 + wr * 64 + fr; const int b = u.pn >> 1, ch0 = (u.pn & 1) * 256 + wc * 32 + 8 * fq;
;         const float sg = (fr & 1) ? -1.0f : 1.0f;
;         f32x4 yh[2][2];
; #pragma unroll
;         for (int bj = 0; bj < 2; ++bj)
; #pragma unroll
;             for (int n = 0; n < 2; ++n) yh[bj][n] = *(const f32x4*)(YCH + b * 512 + ch0 + bj * 128 + 4 * n) * sg;
; #pragma unroll
;         for (int ai = 0; ai < 2; ++ai)
; #pragma unroll
;             for (int m = 0; m < 4; ++m) {
;                 const int k = row0 + ai * 128 + m * 16;
; #pragma unroll
;                 for (int bj = 0; bj < 2; ++bj) {
;                     const f32x4 v0 = acc[ai][bj][m][0] + yh[bj][0], v1 = acc[ai][bj][m][1] + yh[bj][1];
;                     u32x4 w; w.x = cvt_pk_bf16(v0[0], v0[1]); w.y = cvt_pk_bf16(v0[2], v0[3]); w.z = cvt_pk_bf16(v1[0], v1[1]); w.w = cvt_pk_bf16(v1[2], v1[3]);
;                     *(u32x4*)(CAT + (size_t)(b * 2048 + k) * CATW + 1024 + ch0 + bj * 128) = w;
;                 }
	s_setprio 0
	s_add_i32 s43, s43, 2
	s_add_u32 s14, s14, 0x100
	s_addc_u32 s15, s15, 0
	s_add_u32 s41, s41, 0x100
	s_addc_u32 s42, s42, 0
	s_cmp_gt_u32 s43, 29
	s_cbranch_scc0 .LBB0_826
	s_ashr_i32 s5, s38, 1
	s_lshl_b32 s7, s38, 8
	s_lshl_b32 s14, s5, 9
	s_and_b32 s7, s7, 0x100
	s_ashr_i32 s15, s14, 31
	v_mov_b32_e32 v171, v161
	v_mov_b32_e32 v128, v166
	s_or_b32 s7, s7, s30
	s_lshl_b64 s[14:15], s[14:15], 2
	s_add_u32 s14, s48, s14
	v_lshl_add_u32 v164, v128, 3, s7
	s_addc_u32 s15, s49, s15
	v_ashrrev_i32_e32 v165, 31, v164
	v_lshl_add_u64 v[128:129], v[164:165], 2, s[14:15]
	global_load_dwordx4 v[140:143], v[128:129], off
	global_load_dwordx4 v[136:139], v[128:129], off offset:16
	global_load_dwordx4 v[132:135], v[128:129], off offset:512
	s_nop 0
	global_load_dwordx4 v[128:131], v[128:129], off offset:528
	s_lshl_b32 s7, s12, 8
	s_lshl_b32 s5, s5, 11
	s_add_i32 s7, s7, s29
	v_and_b32_e32 v160, 1, v171
	s_add_i32 s7, s7, s5
	v_mov_b64_e32 v[162:163], s[96:97]
	v_cmp_eq_u32_e32 vcc, 0, v160
	v_add_u32_e32 v171, s7, v171
	v_lshlrev_b64 v[164:165], 1, v[164:165]
	v_cndmask_b32_e64 v160, -1.0, 1.0, vcc
	v_mad_i64_i32 v[172:173], s[14:15], v171, s37, v[162:163]
	v_add_u32_e32 v174, 16, v171
	v_lshl_add_u64 v[172:173], v[172:173], 0, v[164:165]
	v_mad_i64_i32 v[174:175], s[14:15], v174, s37, v[162:163]
	v_add_u32_e32 v176, 32, v171
	v_lshl_add_u64 v[174:175], v[174:175], 0, v[164:165]
	v_mad_i64_i32 v[176:177], s[14:15], v176, s37, v[162:163]
	v_lshl_add_u64 v[176:177], v[176:177], 0, v[164:165]
	v_add_u32_e32 v182, 48, v171
	s_and_b64 vcc, exec, s[2:3]
	s_mov_b32 s38, s4
	s_mov_b32 s12, s6
	s_mov_b64 s[16:17], s[10:11]
	s_waitcnt vmcnt(0)
	v_pk_fma_f32 v[126:127], v[142:143], v[160:161], v[126:127] op_sel_hi:[1,0,1]
	v_pk_fma_f32 v[124:125], v[140:141], v[160:161], v[124:125] op_sel_hi:[1,0,1]
	v_pk_fma_f32 v[122:123], v[138:139], v[160:161], v[122:123] op_sel_hi:[1,0,1]
	v_pk_fma_f32 v[180:181], v[128:129], v[160:161], v[80:81] op_sel_hi:[1,0,1]
	v_cvt_pk_bf16_f32 v80, v124, v125
	v_cvt_pk_bf16_f32 v81, v126, v127
	v_pk_fma_f32 v[120:121], v[136:137], v[160:161], v[120:121] op_sel_hi:[1,0,1]
	v_pk_fma_f32 v[106:107], v[134:135], v[160:161], v[106:107] op_sel_hi:[1,0,1]
	v_pk_fma_f32 v[104:105], v[132:133], v[160:161], v[104:105] op_sel_hi:[1,0,1]
	v_pk_fma_f32 v[178:179], v[130:131], v[160:161], v[82:83] op_sel_hi:[1,0,1]
	v_cvt_pk_bf16_f32 v82, v120, v121
	v_cvt_pk_bf16_f32 v83, v122, v123
	global_store_dwordx4 v[172:173], v[80:83], off offset:2048
	v_pk_fma_f32 v[98:99], v[130:131], v[160:161], v[98:99] op_sel_hi:[1,0,1]
	v_pk_fma_f32 v[96:97], v[128:129], v[160:161], v[96:97] op_sel_hi:[1,0,1]
	v_cvt_pk_bf16_f32 v80, v104, v105
	v_cvt_pk_bf16_f32 v81, v106, v107
	v_pk_fma_f32 v[118:119], v[142:143], v[160:161], v[118:119] op_sel_hi:[1,0,1]
	v_pk_fma_f32 v[116:117], v[140:141], v[160:161], v[116:117] op_sel_hi:[1,0,1]
	v_cvt_pk_bf16_f32 v82, v96, v97
	v_cvt_pk_bf16_f32 v83, v98, v99
	global_store_dwordx4 v[172:173], v[80:83], off offset:2304
	v_pk_fma_f32 v[114:115], v[138:139], v[160:161], v[114:115] op_sel_hi:[1,0,1]
	v_pk_fma_f32 v[112:113], v[136:137], v[160:161], v[112:113] op_sel_hi:[1,0,1]
	v_cvt_pk_bf16_f32 v80, v116, v117
	v_cvt_pk_bf16_f32 v81, v118, v119
	v_pk_fma_f32 v[94:95], v[134:135], v[160:161], v[94:95] op_sel_hi:[1,0,1]
	v_pk_fma_f32 v[92:93], v[132:133], v[160:161], v[92:93] op_sel_hi:[1,0,1]
	v_cvt_pk_bf16_f32 v82, v112, v113
	v_cvt_pk_bf16_f32 v83, v114, v115
	global_store_dwordx4 v[174:175], v[80:83], off offset:2048
	v_pk_fma_f32 v[90:91], v[130:131], v[160:161], v[90:91] op_sel_hi:[1,0,1]
	v_pk_fma_f32 v[88:89], v[128:129], v[160:161], v[88:89] op_sel_hi:[1,0,1]
	v_cvt_pk_bf16_f32 v80, v92, v93
	v_cvt_pk_bf16_f32 v81, v94, v95
	v_pk_fma_f32 v[110:111], v[142:143], v[160:161], v[110:111] op_sel_hi:[1,0,1]
	v_pk_fma_f32 v[108:109], v[140:141], v[160:161], v[108:109] op_sel_hi:[1,0,1]
	v_cvt_pk_bf16_f32 v82, v88, v89
	v_cvt_pk_bf16_f32 v83, v90, v91
	global_store_dwordx4 v[174:175], v[80:83], off offset:2304
	v_pk_fma_f32 v[102:103], v[138:139], v[160:161], v[102:103] op_sel_hi:[1,0,1]
	v_pk_fma_f32 v[100:101], v[136:137], v[160:161], v[100:101] op_sel_hi:[1,0,1]
	v_cvt_pk_bf16_f32 v80, v108, v109
	v_cvt_pk_bf16_f32 v81, v110, v111
	v_pk_fma_f32 v[86:87], v[134:135], v[160:161], v[86:87] op_sel_hi:[1,0,1]
	v_pk_fma_f32 v[84:85], v[132:133], v[160:161], v[84:85] op_sel_hi:[1,0,1]
	v_cvt_pk_bf16_f32 v82, v100, v101
	v_cvt_pk_bf16_f32 v83, v102, v103
	global_store_dwordx4 v[176:177], v[80:83], off offset:2048
	v_pk_fma_f32 v[76:77], v[140:141], v[160:161], v[76:77] op_sel_hi:[1,0,1]
	v_pk_fma_f32 v[78:79], v[142:143], v[160:161], v[78:79] op_sel_hi:[1,0,1]
	v_cvt_pk_bf16_f32 v80, v84, v85
	v_cvt_pk_bf16_f32 v81, v86, v87
	v_cvt_pk_bf16_f32 v82, v180, v181
	v_cvt_pk_bf16_f32 v83, v178, v179
	global_store_dwordx4 v[176:177], v[80:83], off offset:2304
	v_pk_fma_f32 v[70:71], v[134:135], v[160:161], v[70:71] op_sel_hi:[1,0,1]
	v_pk_fma_f32 v[68:69], v[132:133], v[160:161], v[68:69] op_sel_hi:[1,0,1]
	v_pk_fma_f32 v[80:81], v[138:139], v[160:161], v[74:75] op_sel_hi:[1,0,1]
	v_pk_fma_f32 v[74:75], v[136:137], v[160:161], v[72:73] op_sel_hi:[1,0,1]
	v_cvt_pk_bf16_f32 v72, v76, v77
; __device__ __forceinline__ unsigned cvt_pk_bf16(float lo, float hi) { unsigned r; asm volatile("v_cvt_pk_bf16_f32 %0, %1, %2" : "=v"(r) : "v"(lo), "v"(hi)); return r; }
; #define PG8_WAIT_V(n) asm volatile("s_waitcnt vmcnt(" #n ")" ::: "memory")
; #define PG8_BAR __builtin_amdgcn_s_barrier()
; template <class Epi, class Sched>
; __device__ __forceinline__ void gemm_phase(LAS unsigned char* lds, const Gemm g, const Sched& S, const Epi& E) {
;     ...
;         if (!has_next) break;
; #pragma unroll
;         for (int a = 0; a < 2; ++a)
; #pragma unroll
;             for (int b = 0; b < 2; ++b)
; #pragma unroll
;                 for (int m = 0; m < 4; ++m)
; #pragma unroll
;                     for (int n = 0; n < 2; ++n) acc[a][b][m][n] = (f32x4){0.f, 0.f, 0.f, 0.f};
;         cur = nxt; cA = nA; cB = nB; ++ui;
;     }
;     PG8_WAIT_V(0);
;     if (wr == 0) PG8_BAR;
;     PG8_BAR;
;     __device__ __forceinline__ void operator()(const AccT& acc, const Unit& u, int wr, int wc, int fr, int fq) const {
;     ...
;         for (int ai = 0; ai < 2; ++ai)
; #pragma unroll
;             for (int m = 0; m < 4; ++m) {
;                 const int k = row0 + ai * 128 + m * 16;
; #pragma unroll
;                 for (int bj = 0; bj < 2; ++bj) {
;                     const f32x4 v0 = acc[ai][bj][m][0] + yh[bj][0], v1 = acc[ai][bj][m][1] + yh[bj][1];
;                     u32x4 w; w.x = cvt_pk_bf16(v0[0], v0[1]); w.y = cvt_pk_bf16(v0[2], v0[3]); w.z = cvt_pk_bf16(v1[0], v1[1]); w.w = cvt_pk_bf16(v1[2], v1[3]);
;                     *(u32x4*)(CAT + (size_t)(b * 2048 + k) * CATW + 1024 + ch0 + bj * 128) = w;
;                 }
	v_mad_i64_i32 v[76:77], s[14:15], v182, s37, v[162:163]
	v_cvt_pk_bf16_f32 v73, v78, v79
	v_lshl_add_u64 v[76:77], v[76:77], 0, v[164:165]
	v_cvt_pk_bf16_f32 v74, v74, v75
	v_cvt_pk_bf16_f32 v75, v80, v81
	global_store_dwordx4 v[76:77], v[72:75], off offset:2048
	v_pk_fma_f32 v[60:61], v[140:141], v[160:161], v[60:61] op_sel_hi:[1,0,1]
	v_pk_fma_f32 v[62:63], v[142:143], v[160:161], v[62:63] op_sel_hi:[1,0,1]
	v_pk_fma_f32 v[72:73], v[130:131], v[160:161], v[66:67] op_sel_hi:[1,0,1]
	v_pk_fma_f32 v[66:67], v[128:129], v[160:161], v[64:65] op_sel_hi:[1,0,1]
	v_cvt_pk_bf16_f32 v64, v68, v69
	v_cvt_pk_bf16_f32 v65, v70, v71
	v_pk_fma_f32 v[54:55], v[134:135], v[160:161], v[54:55] op_sel_hi:[1,0,1]
	v_cvt_pk_bf16_f32 v66, v66, v67
	v_cvt_pk_bf16_f32 v67, v72, v73
	global_store_dwordx4 v[76:77], v[64:67], off offset:2304
	v_pk_fma_f32 v[52:53], v[132:133], v[160:161], v[52:53] op_sel_hi:[1,0,1]
	v_pk_fma_f32 v[38:39], v[134:135], v[160:161], v[38:39] op_sel_hi:[1,0,1]
	v_add_u32_e32 v66, 0x80, v171
	v_pk_fma_f32 v[64:65], v[138:139], v[160:161], v[58:59] op_sel_hi:[1,0,1]
	v_pk_fma_f32 v[58:59], v[136:137], v[160:161], v[56:57] op_sel_hi:[1,0,1]
	v_cvt_pk_bf16_f32 v56, v60, v61
	v_mad_i64_i32 v[60:61], s[14:15], v66, s37, v[162:163]
	v_cvt_pk_bf16_f32 v57, v62, v63
	v_lshl_add_u64 v[60:61], v[60:61], 0, v[164:165]
	v_cvt_pk_bf16_f32 v58, v58, v59
	v_cvt_pk_bf16_f32 v59, v64, v65
	global_store_dwordx4 v[60:61], v[56:59], off offset:2048
	v_pk_fma_f32 v[36:37], v[132:133], v[160:161], v[36:37] op_sel_hi:[1,0,1]
	v_pk_fma_f32 v[22:23], v[134:135], v[160:161], v[22:23] op_sel_hi:[1,0,1]
	v_pk_fma_f32 v[56:57], v[130:131], v[160:161], v[46:47] op_sel_hi:[1,0,1]
	v_pk_fma_f32 v[46:47], v[128:129], v[160:161], v[44:45] op_sel_hi:[1,0,1]
	v_cvt_pk_bf16_f32 v44, v52, v53
	v_cvt_pk_bf16_f32 v45, v54, v55
	v_add_u32_e32 v52, 0x90, v171
	v_cvt_pk_bf16_f32 v46, v46, v47
	v_cvt_pk_bf16_f32 v47, v56, v57
	global_store_dwordx4 v[60:61], v[44:47], off offset:2304
	v_pk_fma_f32 v[20:21], v[132:133], v[160:161], v[20:21] op_sel_hi:[1,0,1]
	v_pk_fma_f32 v[6:7], v[134:135], v[160:161], v[6:7] op_sel_hi:[1,0,1]
	v_pk_fma_f32 v[44:45], v[142:143], v[160:161], v[50:51] op_sel_hi:[1,0,1]
	v_pk_fma_f32 v[46:47], v[140:141], v[160:161], v[48:49] op_sel_hi:[1,0,1]
	v_pk_fma_f32 v[48:49], v[138:139], v[160:161], v[42:43] op_sel_hi:[1,0,1]
	v_pk_fma_f32 v[42:43], v[136:137], v[160:161], v[40:41] op_sel_hi:[1,0,1]
	v_cvt_pk_bf16_f32 v40, v46, v47
	v_cvt_pk_bf16_f32 v41, v44, v45
	v_mad_i64_i32 v[44:45], s[14:15], v52, s37, v[162:163]
	v_lshl_add_u64 v[44:45], v[44:45], 0, v[164:165]
	v_cvt_pk_bf16_f32 v42, v42, v43
	v_cvt_pk_bf16_f32 v43, v48, v49
	global_store_dwordx4 v[44:45], v[40:43], off offset:2048
	v_pk_fma_f32 v[4:5], v[132:133], v[160:161], v[4:5] op_sel_hi:[1,0,1]
	s_nop 0
	v_pk_fma_f32 v[40:41], v[130:131], v[160:161], v[30:31] op_sel_hi:[1,0,1]
	v_pk_fma_f32 v[30:31], v[128:129], v[160:161], v[28:29] op_sel_hi:[1,0,1]
	v_cvt_pk_bf16_f32 v28, v36, v37
	v_cvt_pk_bf16_f32 v29, v38, v39
	v_add_u32_e32 v36, 0xa0, v171
	v_cvt_pk_bf16_f32 v30, v30, v31
	v_cvt_pk_bf16_f32 v31, v40, v41
	global_store_dwordx4 v[44:45], v[28:31], off offset:2304
	s_nop 1
	v_pk_fma_f32 v[28:29], v[142:143], v[160:161], v[34:35] op_sel_hi:[1,0,1]
	v_pk_fma_f32 v[30:31], v[140:141], v[160:161], v[32:33] op_sel_hi:[1,0,1]
	v_pk_fma_f32 v[32:33], v[138:139], v[160:161], v[26:27] op_sel_hi:[1,0,1]
	v_pk_fma_f32 v[26:27], v[136:137], v[160:161], v[24:25] op_sel_hi:[1,0,1]
	v_cvt_pk_bf16_f32 v24, v30, v31
	v_cvt_pk_bf16_f32 v25, v28, v29
	v_mad_i64_i32 v[28:29], s[14:15], v36, s37, v[162:163]
	v_lshl_add_u64 v[28:29], v[28:29], 0, v[164:165]
	v_cvt_pk_bf16_f32 v26, v26, v27
	v_cvt_pk_bf16_f32 v27, v32, v33
	global_store_dwordx4 v[28:29], v[24:27], off offset:2048
	s_nop 1
	v_pk_fma_f32 v[24:25], v[130:131], v[160:161], v[14:15] op_sel_hi:[1,0,1]
	v_pk_fma_f32 v[14:15], v[128:129], v[160:161], v[12:13] op_sel_hi:[1,0,1]
	v_cvt_pk_bf16_f32 v12, v20, v21
	v_cvt_pk_bf16_f32 v13, v22, v23
	v_add_u32_e32 v20, 0xb0, v171
	v_cvt_pk_bf16_f32 v14, v14, v15
	v_cvt_pk_bf16_f32 v15, v24, v25
	global_store_dwordx4 v[28:29], v[12:15], off offset:2304
	s_nop 1
	v_pk_fma_f32 v[12:13], v[142:143], v[160:161], v[18:19] op_sel_hi:[1,0,1]
	v_pk_fma_f32 v[14:15], v[140:141], v[160:161], v[16:17] op_sel_hi:[1,0,1]
	v_pk_fma_f32 v[16:17], v[138:139], v[160:161], v[10:11] op_sel_hi:[1,0,1]
	v_pk_fma_f32 v[10:11], v[136:137], v[160:161], v[8:9] op_sel_hi:[1,0,1]
	v_cvt_pk_bf16_f32 v8, v14, v15
	v_cvt_pk_bf16_f32 v9, v12, v13
	v_mad_i64_i32 v[12:13], s[14:15], v20, s37, v[162:163]
	v_lshl_add_u64 v[12:13], v[12:13], 0, v[164:165]
	v_cvt_pk_bf16_f32 v10, v10, v11
	v_cvt_pk_bf16_f32 v11, v16, v17
	global_store_dwordx4 v[12:13], v[8:11], off offset:2048
	s_mov_b64 s[14:15], s[8:9]
	s_nop 0
	v_pk_fma_f32 v[8:9], v[130:131], v[160:161], v[2:3] op_sel_hi:[1,0,1]
	v_pk_fma_f32 v[2:3], v[128:129], v[160:161], v[0:1] op_sel_hi:[1,0,1]
	v_cvt_pk_bf16_f32 v0, v4, v5
	v_cvt_pk_bf16_f32 v1, v6, v7
	s_nop 0
	v_cvt_pk_bf16_f32 v2, v2, v3
	v_cvt_pk_bf16_f32 v3, v8, v9
	global_store_dwordx4 v[12:13], v[0:3], off offset:2304
	s_cbranch_vccz .LBB0_819
	s_waitcnt vmcnt(0)
	s_cmpk_gt_u32 s20, 0xff
	s_cbranch_scc1 .LBB0_830
	s_barrier

; #define PG8_STAGE(bufoff, gbase, voff) do { _Pragma("unroll") for (int _i = 0; _i < 2; ++_i) \
;         __builtin_amdgcn_global_load_lds((const unsigned*)((const char*)(gbase) + (voff)[_i]), (LAS unsigned*)(lds + (bufoff) + ldsw + _i * 8192), 16, 0, 0); } while (0)
; #define PG8_LDA(dst, b, h) do { _Pragma("unroll") for (int m = 0; m < 4; ++m) _Pragma("unroll") for (int k = 0; k < 2; ++k) dst[m][k] = *(const LAS bf16x8*)(lds + PG8_SA(b, h) + aoff + m * 2048 + k * 1024); } while (0)
; #define PG8_LDB(dst, b, h) do { _Pragma("unroll") for (int n = 0; n < 2; ++n) _Pragma("unroll") for (int k = 0; k < 2; ++k) dst[n][k] = *(const LAS bf16x8*)(lds + PG8_SB(b, h) + boff + n * 2048 + k * 1024); } while (0)
; #define PG8_WAIT_V(n) asm volatile("s_waitcnt vmcnt(" #n ")" ::: "memory")
; #define PG8_WAIT_L(n) asm volatile("s_waitcnt lgkmcnt(" #n ")" ::: "memory")
; #define PG8_BAR __builtin_amdgcn_s_barrier()
; #define PG8_SCHED __builtin_amdgcn_sched_barrier(0)
; template <class Epi, class Sched>
; __device__ __forceinline__ void gemm_phase(LAS unsigned char* lds, const Gemm g, const Sched& S, const Epi& E) {
;     ...
;         const bool has_next = S.next(ui + 1, nxt);
;         const char* nA = has_next ? (const char*)g.A + (size_t)nxt.pm * tstep : cA; const char* nB = has_next ? (const char*)g.Bt + (size_t)nxt.pn * tstep : cB;
;         for (int t = 0; t < nt; t += 2) {
;             const bool last = (t == nt - 2);
;             const char* a1 = cA + (size_t)(t + 1) * kstep;
;             const char* a2 = last ? nA : cA + (size_t)(t + 2) * kstep; const char* b2 = last ? nB : cB + (size_t)(t + 2) * kstep;
;             const char* a3 = a2 + kstep; const char* b3 = b2 + kstep;
;             PG8_LDB(B0, 0, 0); PG8_SCHED; PG8_LDA(At, 0, 0); PG8_STAGE(PG8_SA(1, 1), a1 + hstep, voffA);
;             PG8_WAIT_L(8); PG8_BAR; PG8_WAIT_L(0); PG8_MMA(0, 0, At, B0); PG8_BAR; PG8_SCHED;
;             PG8_LDB(B1, 0, 1); PG8_STAGE(PG8_SB(0, 0), b2, voffB);
;             PG8_BAR; PG8_WAIT_L(0); PG8_MMA(0, 1, At, B1); PG8_BAR;
;             PG8_LDA(At, 0, 1); PG8_STAGE(PG8_SA(0, 0), a2, voffA);
;             PG8_BAR; PG8_WAIT_L(0); PG8_MMA(1, 0, At, B0); PG8_BAR; PG8_SCHED;
;             PG8_STAGE(PG8_SB(0, 1), b2 + hstep, voffB);
;             PG8_WAIT_V(6); PG8_BAR; PG8_MMA(1, 1, At, B1); PG8_BAR;
.LBB0_901:
	s_add_u32 s56, s26, 0x100
	s_addc_u32 s57, s27, 0
	s_mov_b32 s58, -2
	s_waitcnt vmcnt(0)
	ds_read_b128 v[128:131], v237
	ds_read_b128 v[132:135], v237 offset:1024
	ds_read_b128 v[136:139], v237 offset:2048
	ds_read_b128 v[140:143], v237 offset:3072
	s_add_u32 s26, s24, 0x100
	s_addc_u32 s27, s25, 0
	s_cmp_eq_u32 s58, 20
	s_cselect_b32 s31, s5, s27
	s_cselect_b32 s30, s4, s26
	s_cselect_b32 s29, s7, s57
	s_cselect_b32 s28, s6, s56
	v_lshl_add_u64 v[176:177], s[24:25], 0, v[210:211]
	s_add_i32 m0, s38, 0xc000
	ds_read_b128 v[144:147], v238
	ds_read_b128 v[148:151], v238 offset:1024
	ds_read_b128 v[152:155], v238 offset:2048
	ds_read_b128 v[156:159], v238 offset:3072
	ds_read_b128 v[160:163], v238 offset:4096
	ds_read_b128 v[164:167], v238 offset:5120
	ds_read_b128 v[168:171], v238 offset:6144
	ds_read_b128 v[172:175], v238 offset:7168
	global_load_lds_dwordx4 v[176:177], off
	v_lshl_add_u64 v[176:177], s[24:25], 0, v[212:213]
	s_add_i32 m0, s38, 0xe000
	s_nop 0
	global_load_lds_dwordx4 v[176:177], off
	s_waitcnt lgkmcnt(8)
	s_waitcnt vmcnt(8)
	s_setprio 1
	s_barrier
	s_waitcnt lgkmcnt(0)
	v_mfma_f32_16x16x32_bf16 v[124:127], v[128:131], v[144:147], 0
	v_mfma_f32_16x16x32_bf16 v[120:123], v[136:139], v[144:147], 0
	v_mfma_f32_16x16x32_bf16 v[108:111], v[128:131], v[152:155], 0
	v_mfma_f32_16x16x32_bf16 v[104:107], v[136:139], v[152:155], 0
	v_mfma_f32_16x16x32_bf16 v[92:95], v[128:131], v[160:163], 0
	v_mfma_f32_16x16x32_bf16 v[88:91], v[136:139], v[160:163], 0
	v_mfma_f32_16x16x32_bf16 v[76:79], v[128:131], v[168:171], 0
	v_mfma_f32_16x16x32_bf16 v[72:75], v[136:139], v[168:171], 0
	v_mfma_f32_16x16x32_bf16 v[124:127], v[132:135], v[148:151], v[124:127]
	v_mfma_f32_16x16x32_bf16 v[120:123], v[140:143], v[148:151], v[120:123]
	v_mfma_f32_16x16x32_bf16 v[108:111], v[132:135], v[156:159], v[108:111]
	v_mfma_f32_16x16x32_bf16 v[104:107], v[140:143], v[156:159], v[104:107]
	v_mfma_f32_16x16x32_bf16 v[92:95], v[132:135], v[164:167], v[92:95]
	v_mfma_f32_16x16x32_bf16 v[88:91], v[140:143], v[164:167], v[88:91]
	v_mfma_f32_16x16x32_bf16 v[76:79], v[132:135], v[172:175], v[76:79]
	v_mfma_f32_16x16x32_bf16 v[72:75], v[140:143], v[172:175], v[72:75]
	s_barrier
	s_setprio 0
	s_add_i32 s24, s50, s37
	s_mov_b32 m0, s24
	ds_read_b128 v[176:179], v239
	ds_read_b128 v[180:183], v239 offset:1024
	ds_read_b128 v[184:187], v239 offset:2048
	ds_read_b128 v[188:191], v239 offset:3072
	global_load_lds_dwordx4 v204, s[28:29]
	s_add_i32 m0, s24, 0x2000
	s_nop 0
	global_load_lds_dwordx4 v208, s[28:29]
	s_waitcnt vmcnt(8)
	s_setprio 1
	s_barrier
	s_waitcnt lgkmcnt(0)
	v_mfma_f32_16x16x32_bf16 v[116:119], v[176:179], v[144:147], 0
	v_mfma_f32_16x16x32_bf16 v[112:115], v[184:187], v[144:147], 0
	v_mfma_f32_16x16x32_bf16 v[100:103], v[176:179], v[152:155], 0
	v_mfma_f32_16x16x32_bf16 v[96:99], v[184:187], v[152:155], 0
	v_mfma_f32_16x16x32_bf16 v[84:87], v[176:179], v[160:163], 0
	v_mfma_f32_16x16x32_bf16 v[80:83], v[184:187], v[160:163], 0
	v_mfma_f32_16x16x32_bf16 v[68:71], v[176:179], v[168:171], 0
	v_mfma_f32_16x16x32_bf16 v[64:67], v[184:187], v[168:171], 0
	v_mfma_f32_16x16x32_bf16 v[116:119], v[180:183], v[148:151], v[116:119]
	v_mfma_f32_16x16x32_bf16 v[112:115], v[188:191], v[148:151], v[112:115]
	v_mfma_f32_16x16x32_bf16 v[100:103], v[180:183], v[156:159], v[100:103]
	v_mfma_f32_16x16x32_bf16 v[96:99], v[188:191], v[156:159], v[96:99]
	v_mfma_f32_16x16x32_bf16 v[84:87], v[180:183], v[164:167], v[84:87]
	v_mfma_f32_16x16x32_bf16 v[80:83], v[188:191], v[164:167], v[80:83]
	v_mfma_f32_16x16x32_bf16 v[68:71], v[180:183], v[172:175], v[68:71]
	v_mfma_f32_16x16x32_bf16 v[64:67], v[188:191], v[172:175], v[64:67]
	s_barrier
	s_setprio 0
	s_mov_b32 m0, s38
	v_lshl_add_u64 v[196:197], s[30:31], 0, v[202:203]
	ds_read_b128 v[144:147], v238 offset:16384
	ds_read_b128 v[148:151], v238 offset:17408
	ds_read_b128 v[152:155], v238 offset:18432
	ds_read_b128 v[156:159], v238 offset:19456
	ds_read_b128 v[160:163], v238 offset:20480
	ds_read_b128 v[164:167], v238 offset:21504
	ds_read_b128 v[168:171], v238 offset:22528
	ds_read_b128 v[172:175], v238 offset:23552
	global_load_lds_dwordx4 v202, s[30:31]
	v_lshl_add_u64 v[198:199], s[30:31], 0, v[206:207]
	s_mov_b32 m0, s39
	s_nop 0
	global_load_lds_dwordx4 v206, s[30:31]
	s_setprio 1
	s_barrier
	s_waitcnt lgkmcnt(0)
	v_mfma_f32_16x16x32_bf16 v[60:63], v[128:131], v[144:147], 0
	v_mfma_f32_16x16x32_bf16 v[56:59], v[136:139], v[144:147], 0
	v_mfma_f32_16x16x32_bf16 v[44:47], v[128:131], v[152:155], 0
	v_mfma_f32_16x16x32_bf16 v[40:43], v[136:139], v[152:155], 0
	v_mfma_f32_16x16x32_bf16 v[28:31], v[128:131], v[160:163], 0
	v_mfma_f32_16x16x32_bf16 v[24:27], v[136:139], v[160:163], 0
	v_mfma_f32_16x16x32_bf16 v[12:15], v[128:131], v[168:171], 0
	v_mfma_f32_16x16x32_bf16 v[8:11], v[136:139], v[168:171], 0
	v_mfma_f32_16x16x32_bf16 v[60:63], v[132:135], v[148:151], v[60:63]
	v_mfma_f32_16x16x32_bf16 v[56:59], v[140:143], v[148:151], v[56:59]
	v_mfma_f32_16x16x32_bf16 v[44:47], v[132:135], v[156:159], v[44:47]
	v_mfma_f32_16x16x32_bf16 v[40:43], v[140:143], v[156:159], v[40:43]
	v_mfma_f32_16x16x32_bf16 v[28:31], v[132:135], v[164:167], v[28:31]
	v_mfma_f32_16x16x32_bf16 v[24:27], v[140:143], v[164:167], v[24:27]
	v_mfma_f32_16x16x32_bf16 v[12:15], v[132:135], v[172:175], v[12:15]
	v_mfma_f32_16x16x32_bf16 v[8:11], v[140:143], v[172:175], v[8:11]
	s_barrier
	s_setprio 0
	s_add_u32 s24, s28, 0x60000
	s_addc_u32 s25, s29, 0
	s_add_i32 s59, s51, s37
	s_mov_b32 m0, s59
	s_nop 0
	global_load_lds_dwordx4 v204, s[24:25]
	s_add_i32 m0, s59, 0x2000
	s_nop 0
	global_load_lds_dwordx4 v208, s[24:25]
	s_add_u32 s24, s30, 0x60000
	s_addc_u32 s25, s31, 0
	s_mov_b32 m0, s40
	s_nop 0
	global_load_lds_dwordx4 v202, s[24:25]
	s_mov_b32 m0, s41
	s_nop 0
	global_load_lds_dwordx4 v206, s[24:25]
	s_waitcnt vmcnt(10)
	s_setprio 1
	s_barrier
; #define PG8_STAGE(bufoff, gbase, voff) do { _Pragma("unroll") for (int _i = 0; _i < 2; ++_i) \
;         __builtin_amdgcn_global_load_lds((const unsigned*)((const char*)(gbase) + (voff)[_i]), (LAS unsigned*)(lds + (bufoff) + ldsw + _i * 8192), 16, 0, 0); } while (0)
; #define PG8_LDA(dst, b, h) do { _Pragma("unroll") for (int m = 0; m < 4; ++m) _Pragma("unroll") for (int k = 0; k < 2; ++k) dst[m][k] = *(const LAS bf16x8*)(lds + PG8_SA(b, h) + aoff + m * 2048 + k * 1024); } while (0)
; #define PG8_LDB(dst, b, h) do { _Pragma("unroll") for (int n = 0; n < 2; ++n) _Pragma("unroll") for (int k = 0; k < 2; ++k) dst[n][k] = *(const LAS bf16x8*)(lds + PG8_SB(b, h) + boff + n * 2048 + k * 1024); } while (0)
; #define PG8_MMA(ai, bj, At, Bt) do { __builtin_amdgcn_s_setprio(1); _Pragma("unroll") for (int m = 0; m < 4; ++m) _Pragma("unroll") for (int n = 0; n < 2; ++n) _Pragma("unroll") for (int k = 0; k < 2; ++k) \
;         acc[ai][bj][m][n] = __builtin_amdgcn_mfma_f32_16x16x32_bf16(Bt[n][k], At[m][k], acc[ai][bj][m][n], 0, 0, 0); __builtin_amdgcn_s_setprio(0); } while (0)
; #define PG8_WAIT_V(n) asm volatile("s_waitcnt vmcnt(" #n ")" ::: "memory")
; #define PG8_WAIT_L(n) asm volatile("s_waitcnt lgkmcnt(" #n ")" ::: "memory")
; #define PG8_BAR __builtin_amdgcn_s_barrier()
; #define PG8_SCHED __builtin_amdgcn_sched_barrier(0)
; template <class Epi, class Sched>
; __device__ __forceinline__ void gemm_phase(LAS unsigned char* lds, const Gemm g, const Sched& S, const Epi& E) {
;     ...
;             PG8_WAIT_V(6); PG8_BAR; PG8_MMA(1, 1, At, B1); PG8_BAR;
;             PG8_LDB(B0, 1, 0); PG8_SCHED; PG8_LDA(At, 1, 0); PG8_STAGE(PG8_SA(0, 1), a2 + hstep, voffA);
;             PG8_WAIT_L(8); PG8_BAR; PG8_WAIT_L(0); PG8_MMA(0, 0, At, B0); PG8_BAR; PG8_SCHED;
;             PG8_LDB(B1, 1, 1); PG8_STAGE(PG8_SB(1, 0), b3, voffB);
;             PG8_BAR; PG8_WAIT_L(0); PG8_MMA(0, 1, At, B1); PG8_BAR;
;             PG8_LDA(At, 1, 1); PG8_STAGE(PG8_SA(1, 0), a3, voffA);
;             PG8_BAR; PG8_WAIT_L(0); PG8_MMA(1, 0, At, B0); PG8_BAR; PG8_SCHED;
	v_mfma_f32_16x16x32_bf16 v[52:55], v[176:179], v[144:147], 0
	v_mfma_f32_16x16x32_bf16 v[48:51], v[184:187], v[144:147], 0
	v_mfma_f32_16x16x32_bf16 v[36:39], v[176:179], v[152:155], 0
	v_mfma_f32_16x16x32_bf16 v[32:35], v[184:187], v[152:155], 0
	v_mfma_f32_16x16x32_bf16 v[20:23], v[176:179], v[160:163], 0
	v_mfma_f32_16x16x32_bf16 v[16:19], v[184:187], v[160:163], 0
	v_mfma_f32_16x16x32_bf16 v[4:7], v[176:179], v[168:171], 0
	v_mfma_f32_16x16x32_bf16 v[0:3], v[184:187], v[168:171], 0
	v_mfma_f32_16x16x32_bf16 v[52:55], v[180:183], v[148:151], v[52:55]
	v_mfma_f32_16x16x32_bf16 v[48:51], v[188:191], v[148:151], v[48:51]
	v_mfma_f32_16x16x32_bf16 v[36:39], v[180:183], v[156:159], v[36:39]
	v_mfma_f32_16x16x32_bf16 v[32:35], v[188:191], v[156:159], v[32:35]
	v_mfma_f32_16x16x32_bf16 v[20:23], v[180:183], v[164:167], v[20:23]
	v_mfma_f32_16x16x32_bf16 v[16:19], v[188:191], v[164:167], v[16:19]
	v_mfma_f32_16x16x32_bf16 v[4:7], v[180:183], v[172:175], v[4:7]
	v_mfma_f32_16x16x32_bf16 v[0:3], v[188:191], v[172:175], v[0:3]
	s_barrier
	s_setprio 0
	s_add_i32 s59, 0, 0x18000
	ds_read_b128 v[128:131], v239 offset:16384
	ds_read_b128 v[132:135], v239 offset:17408
	ds_read_b128 v[136:139], v239 offset:18432
	ds_read_b128 v[140:143], v239 offset:19456
	ds_read_b128 v[144:147], v238 offset:32768
	ds_read_b128 v[148:151], v238 offset:33792
	ds_read_b128 v[152:155], v238 offset:34816
	ds_read_b128 v[156:159], v238 offset:35840
	ds_read_b128 v[160:163], v238 offset:36864
	ds_read_b128 v[164:167], v238 offset:37888
	ds_read_b128 v[168:171], v238 offset:38912
	ds_read_b128 v[172:175], v238 offset:39936
	s_waitcnt lgkmcnt(8)
	s_waitcnt vmcnt(8)
	s_setprio 1
	s_barrier
	s_waitcnt lgkmcnt(0)
	v_mfma_f32_16x16x32_bf16 v[124:127], v[128:131], v[144:147], v[124:127]
	v_mfma_f32_16x16x32_bf16 v[120:123], v[136:139], v[144:147], v[120:123]
	v_mfma_f32_16x16x32_bf16 v[108:111], v[128:131], v[152:155], v[108:111]
	v_mfma_f32_16x16x32_bf16 v[104:107], v[136:139], v[152:155], v[104:107]
	v_mfma_f32_16x16x32_bf16 v[92:95], v[128:131], v[160:163], v[92:95]
	v_mfma_f32_16x16x32_bf16 v[88:91], v[136:139], v[160:163], v[88:91]
	v_mfma_f32_16x16x32_bf16 v[76:79], v[128:131], v[168:171], v[76:79]
	v_mfma_f32_16x16x32_bf16 v[72:75], v[136:139], v[168:171], v[72:75]
	v_mfma_f32_16x16x32_bf16 v[124:127], v[132:135], v[148:151], v[124:127]
	v_mfma_f32_16x16x32_bf16 v[120:123], v[140:143], v[148:151], v[120:123]
	v_mfma_f32_16x16x32_bf16 v[108:111], v[132:135], v[156:159], v[108:111]
	v_mfma_f32_16x16x32_bf16 v[104:107], v[140:143], v[156:159], v[104:107]
	v_mfma_f32_16x16x32_bf16 v[92:95], v[132:135], v[164:167], v[92:95]
	v_mfma_f32_16x16x32_bf16 v[88:91], v[140:143], v[164:167], v[88:91]
	v_mfma_f32_16x16x32_bf16 v[76:79], v[132:135], v[172:175], v[76:79]
	v_mfma_f32_16x16x32_bf16 v[72:75], v[140:143], v[172:175], v[72:75]
	s_barrier
	s_setprio 0
	s_add_i32 s30, 0, 0x1c000
	s_add_i32 s24, s59, s37
	s_add_u32 s0, s28, 0x80
	s_addc_u32 s1, s29, 0
	s_mov_b32 m0, s24
	ds_read_b128 v[176:179], v239 offset:32768
	ds_read_b128 v[180:183], v239 offset:33792
	ds_read_b128 v[184:187], v239 offset:34816
	ds_read_b128 v[188:191], v239 offset:35840
	global_load_lds_dwordx4 v204, s[0:1]
	s_add_i32 m0, s24, 0x2000
	s_nop 0
	global_load_lds_dwordx4 v208, s[0:1]
	s_waitcnt vmcnt(8)
	s_setprio 1
	s_barrier
	s_waitcnt lgkmcnt(0)
	v_mfma_f32_16x16x32_bf16 v[116:119], v[176:179], v[144:147], v[116:119]
	v_mfma_f32_16x16x32_bf16 v[112:115], v[184:187], v[144:147], v[112:115]
	v_mfma_f32_16x16x32_bf16 v[100:103], v[176:179], v[152:155], v[100:103]
	v_mfma_f32_16x16x32_bf16 v[96:99], v[184:187], v[152:155], v[96:99]
	v_mfma_f32_16x16x32_bf16 v[84:87], v[176:179], v[160:163], v[84:87]
	v_mfma_f32_16x16x32_bf16 v[80:83], v[184:187], v[160:163], v[80:83]
	v_mfma_f32_16x16x32_bf16 v[68:71], v[176:179], v[168:171], v[68:71]
	v_mfma_f32_16x16x32_bf16 v[64:67], v[184:187], v[168:171], v[64:67]
	v_mfma_f32_16x16x32_bf16 v[116:119], v[180:183], v[148:151], v[116:119]
	v_mfma_f32_16x16x32_bf16 v[112:115], v[188:191], v[148:151], v[112:115]
	v_mfma_f32_16x16x32_bf16 v[100:103], v[180:183], v[156:159], v[100:103]
	v_mfma_f32_16x16x32_bf16 v[96:99], v[188:191], v[156:159], v[96:99]
	v_mfma_f32_16x16x32_bf16 v[84:87], v[180:183], v[164:167], v[84:87]
	v_mfma_f32_16x16x32_bf16 v[80:83], v[188:191], v[164:167], v[80:83]
	v_mfma_f32_16x16x32_bf16 v[68:71], v[180:183], v[172:175], v[68:71]
	v_mfma_f32_16x16x32_bf16 v[64:67], v[188:191], v[172:175], v[64:67]
	s_barrier
	s_setprio 0
	s_mov_b32 m0, s47
	s_mov_b64 s[0:1], 0x80
	v_lshl_add_u64 v[192:193], v[196:197], 0, s[0:1]
	ds_read_b128 v[144:147], v238 offset:49152
	ds_read_b128 v[148:151], v238 offset:50176
	ds_read_b128 v[152:155], v238 offset:51200
	ds_read_b128 v[156:159], v238 offset:52224
	ds_read_b128 v[160:163], v238 offset:53248
	ds_read_b128 v[164:167], v238 offset:54272
	ds_read_b128 v[168:171], v238 offset:55296
	ds_read_b128 v[172:175], v238 offset:56320
	global_load_lds_dwordx4 v[192:193], off
	v_lshl_add_u64 v[192:193], v[198:199], 0, s[0:1]
	s_mov_b32 m0, s48
	s_nop 0
	global_load_lds_dwordx4 v[192:193], off
	s_setprio 1
	s_barrier
; #define PG8_STAGE(bufoff, gbase, voff) do { _Pragma("unroll") for (int _i = 0; _i < 2; ++_i) \
;         __builtin_amdgcn_global_load_lds((const unsigned*)((const char*)(gbase) + (voff)[_i]), (LAS unsigned*)(lds + (bufoff) + ldsw + _i * 8192), 16, 0, 0); } while (0)
; #define PG8_LDA(dst, b, h) do { _Pragma("unroll") for (int m = 0; m < 4; ++m) _Pragma("unroll") for (int k = 0; k < 2; ++k) dst[m][k] = *(const LAS bf16x8*)(lds + PG8_SA(b, h) + aoff + m * 2048 + k * 1024); } while (0)
; #define PG8_LDB(dst, b, h) do { _Pragma("unroll") for (int n = 0; n < 2; ++n) _Pragma("unroll") for (int k = 0; k < 2; ++k) dst[n][k] = *(const LAS bf16x8*)(lds + PG8_SB(b, h) + boff + n * 2048 + k * 1024); } while (0)
; #define PG8_MMA(ai, bj, At, Bt) do { __builtin_amdgcn_s_setprio(1); _Pragma("unroll") for (int m = 0; m < 4; ++m) _Pragma("unroll") for (int n = 0; n < 2; ++n) _Pragma("unroll") for (int k = 0; k < 2; ++k) \
;         acc[ai][bj][m][n] = __builtin_amdgcn_mfma_f32_16x16x32_bf16(Bt[n][k], At[m][k], acc[ai][bj][m][n], 0, 0, 0); __builtin_amdgcn_s_setprio(0); } while (0)
; #define PG8_WAIT_V(n) asm volatile("s_waitcnt vmcnt(" #n ")" ::: "memory")
; #define PG8_WAIT_L(n) asm volatile("s_waitcnt lgkmcnt(" #n ")" ::: "memory")
; #define PG8_BAR __builtin_amdgcn_s_barrier()
; #define PG8_SCHED __builtin_amdgcn_sched_barrier(0)
; template <class Epi, class Sched>
; __device__ __forceinline__ void gemm_phase(LAS unsigned char* lds, const Gemm g, const Sched& S, const Epi& E) {
;     ...
;         for (int t = 0; t < nt; t += 2) {
;             const bool last = (t == nt - 2);
;             const char* a1 = cA + (size_t)(t + 1) * kstep;
;             const char* a2 = last ? nA : cA + (size_t)(t + 2) * kstep; const char* b2 = last ? nB : cB + (size_t)(t + 2) * kstep;
;             const char* a3 = a2 + kstep; const char* b3 = b2 + kstep;
;             PG8_LDB(B0, 0, 0); PG8_SCHED; PG8_LDA(At, 0, 0); PG8_STAGE(PG8_SA(1, 1), a1 + hstep, voffA);
;             PG8_WAIT_L(8); PG8_BAR; PG8_WAIT_L(0); PG8_MMA(0, 0, At, B0); PG8_BAR; PG8_SCHED;
;             PG8_LDB(B1, 0, 1); PG8_STAGE(PG8_SB(0, 0), b2, voffB);
;     ...
;             PG8_BAR; PG8_WAIT_L(0); PG8_MMA(1, 0, At, B0); PG8_BAR; PG8_SCHED;
;             PG8_STAGE(PG8_SB(1, 1), b3 + hstep, voffB);
;             PG8_WAIT_V(6); PG8_BAR; PG8_MMA(1, 1, At, B1); PG8_BAR;
	s_waitcnt lgkmcnt(0)
	v_mfma_f32_16x16x32_bf16 v[60:63], v[128:131], v[144:147], v[60:63]
	v_mfma_f32_16x16x32_bf16 v[56:59], v[136:139], v[144:147], v[56:59]
	v_mfma_f32_16x16x32_bf16 v[44:47], v[128:131], v[152:155], v[44:47]
	v_mfma_f32_16x16x32_bf16 v[40:43], v[136:139], v[152:155], v[40:43]
	v_mfma_f32_16x16x32_bf16 v[28:31], v[128:131], v[160:163], v[28:31]
	v_mfma_f32_16x16x32_bf16 v[24:27], v[136:139], v[160:163], v[24:27]
	v_mfma_f32_16x16x32_bf16 v[12:15], v[128:131], v[168:171], v[12:15]
	v_mfma_f32_16x16x32_bf16 v[8:11], v[136:139], v[168:171], v[8:11]
	v_mfma_f32_16x16x32_bf16 v[60:63], v[132:135], v[148:151], v[60:63]
	v_mfma_f32_16x16x32_bf16 v[56:59], v[140:143], v[148:151], v[56:59]
	v_mfma_f32_16x16x32_bf16 v[44:47], v[132:135], v[156:159], v[44:47]
	v_mfma_f32_16x16x32_bf16 v[40:43], v[140:143], v[156:159], v[40:43]
	v_mfma_f32_16x16x32_bf16 v[28:31], v[132:135], v[164:167], v[28:31]
	v_mfma_f32_16x16x32_bf16 v[24:27], v[140:143], v[164:167], v[24:27]
	v_mfma_f32_16x16x32_bf16 v[12:15], v[132:135], v[172:175], v[12:15]
	v_mfma_f32_16x16x32_bf16 v[8:11], v[140:143], v[172:175], v[8:11]
	s_barrier
	s_setprio 0
	s_add_u32 s24, s28, 0x60080
	s_addc_u32 s25, s29, 0
	s_add_i32 s28, s30, s37
	s_mov_b32 m0, s28
	s_nop 0
	global_load_lds_dwordx4 v204, s[24:25]
	s_add_i32 m0, s28, 0x2000
	s_nop 0
	global_load_lds_dwordx4 v208, s[24:25]
	s_waitcnt vmcnt(8)
	s_setprio 1
	s_barrier
	v_mfma_f32_16x16x32_bf16 v[52:55], v[176:179], v[144:147], v[52:55]
	v_mfma_f32_16x16x32_bf16 v[48:51], v[184:187], v[144:147], v[48:51]
	v_mfma_f32_16x16x32_bf16 v[36:39], v[176:179], v[152:155], v[36:39]
	v_mfma_f32_16x16x32_bf16 v[32:35], v[184:187], v[152:155], v[32:35]
	v_mfma_f32_16x16x32_bf16 v[20:23], v[176:179], v[160:163], v[20:23]
	v_mfma_f32_16x16x32_bf16 v[16:19], v[184:187], v[160:163], v[16:19]
	v_mfma_f32_16x16x32_bf16 v[4:7], v[176:179], v[168:171], v[4:7]
	v_mfma_f32_16x16x32_bf16 v[0:3], v[184:187], v[168:171], v[0:3]
	v_mfma_f32_16x16x32_bf16 v[52:55], v[180:183], v[148:151], v[52:55]
	v_mfma_f32_16x16x32_bf16 v[48:51], v[188:191], v[148:151], v[48:51]
	v_mfma_f32_16x16x32_bf16 v[36:39], v[180:183], v[156:159], v[36:39]
	v_mfma_f32_16x16x32_bf16 v[32:35], v[188:191], v[156:159], v[32:35]
	v_mfma_f32_16x16x32_bf16 v[20:23], v[180:183], v[164:167], v[20:23]
	v_mfma_f32_16x16x32_bf16 v[16:19], v[188:191], v[164:167], v[16:19]
	v_mfma_f32_16x16x32_bf16 v[4:7], v[180:183], v[172:175], v[4:7]
	v_mfma_f32_16x16x32_bf16 v[0:3], v[188:191], v[172:175], v[0:3]
	s_barrier
	s_setprio 0
	s_add_i32 s58, s58, 2
	s_add_u32 s56, s56, 0x100
	s_addc_u32 s57, s57, 0
	s_cmp_gt_u32 s58, 21
	s_mov_b64 s[24:25], s[26:27]
.LBB0_902:
	ds_read_b128 v[128:131], v237
	ds_read_b128 v[132:135], v237 offset:1024
	ds_read_b128 v[136:139], v237 offset:2048
	ds_read_b128 v[140:143], v237 offset:3072
	s_add_u32 s26, s24, 0x100
	s_addc_u32 s27, s25, 0
	s_cmp_eq_u32 s58, 20
	s_cselect_b32 s31, s5, s27
	s_cselect_b32 s30, s4, s26
	s_cselect_b32 s29, s7, s57
	s_cselect_b32 s28, s6, s56
	v_lshl_add_u64 v[176:177], s[24:25], 0, v[210:211]
	s_add_i32 m0, s38, 0xc000
	ds_read_b128 v[144:147], v238
	ds_read_b128 v[148:151], v238 offset:1024
	ds_read_b128 v[152:155], v238 offset:2048
	ds_read_b128 v[156:159], v238 offset:3072
	ds_read_b128 v[160:163], v238 offset:4096
	ds_read_b128 v[164:167], v238 offset:5120
	ds_read_b128 v[168:171], v238 offset:6144
	ds_read_b128 v[172:175], v238 offset:7168
	global_load_lds_dwordx4 v[176:177], off
	v_lshl_add_u64 v[176:177], s[24:25], 0, v[212:213]
	s_add_i32 m0, s38, 0xe000
	s_nop 0
	global_load_lds_dwordx4 v[176:177], off
	s_waitcnt lgkmcnt(8)
	s_waitcnt vmcnt(8)
	s_setprio 1
	s_barrier
	s_waitcnt lgkmcnt(0)
	v_mfma_f32_16x16x32_bf16 v[124:127], v[128:131], v[144:147], v[124:127]
	v_mfma_f32_16x16x32_bf16 v[120:123], v[136:139], v[144:147], v[120:123]
	v_mfma_f32_16x16x32_bf16 v[108:111], v[128:131], v[152:155], v[108:111]
	v_mfma_f32_16x16x32_bf16 v[104:107], v[136:139], v[152:155], v[104:107]
	v_mfma_f32_16x16x32_bf16 v[92:95], v[128:131], v[160:163], v[92:95]
	v_mfma_f32_16x16x32_bf16 v[88:91], v[136:139], v[160:163], v[88:91]
	v_mfma_f32_16x16x32_bf16 v[76:79], v[128:131], v[168:171], v[76:79]
	v_mfma_f32_16x16x32_bf16 v[72:75], v[136:139], v[168:171], v[72:75]
	v_mfma_f32_16x16x32_bf16 v[124:127], v[132:135], v[148:151], v[124:127]
	v_mfma_f32_16x16x32_bf16 v[120:123], v[140:143], v[148:151], v[120:123]
	v_mfma_f32_16x16x32_bf16 v[108:111], v[132:135], v[156:159], v[108:111]
	v_mfma_f32_16x16x32_bf16 v[104:107], v[140:143], v[156:159], v[104:107]
	v_mfma_f32_16x16x32_bf16 v[92:95], v[132:135], v[164:167], v[92:95]
	v_mfma_f32_16x16x32_bf16 v[88:91], v[140:143], v[164:167], v[88:91]
	v_mfma_f32_16x16x32_bf16 v[76:79], v[132:135], v[172:175], v[76:79]
	v_mfma_f32_16x16x32_bf16 v[72:75], v[140:143], v[172:175], v[72:75]
	s_barrier
	s_setprio 0
	s_add_i32 s24, s50, s37
	s_mov_b32 m0, s24
	ds_read_b128 v[176:179], v239
	ds_read_b128 v[180:183], v239 offset:1024
	ds_read_b128 v[184:187], v239 offset:2048
	ds_read_b128 v[188:191], v239 offset:3072
	global_load_lds_dwordx4 v204, s[28:29]
	s_add_i32 m0, s24, 0x2000
	s_nop 0
	global_load_lds_dwordx4 v208, s[28:29]
	s_waitcnt vmcnt(8)
	s_setprio 1
	s_barrier
; #define PG8_STAGE(bufoff, gbase, voff) do { _Pragma("unroll") for (int _i = 0; _i < 2; ++_i) \
;         __builtin_amdgcn_global_load_lds((const unsigned*)((const char*)(gbase) + (voff)[_i]), (LAS unsigned*)(lds + (bufoff) + ldsw + _i * 8192), 16, 0, 0); } while (0)
; #define PG8_LDA(dst, b, h) do { _Pragma("unroll") for (int m = 0; m < 4; ++m) _Pragma("unroll") for (int k = 0; k < 2; ++k) dst[m][k] = *(const LAS bf16x8*)(lds + PG8_SA(b, h) + aoff + m * 2048 + k * 1024); } while (0)
; #define PG8_LDB(dst, b, h) do { _Pragma("unroll") for (int n = 0; n < 2; ++n) _Pragma("unroll") for (int k = 0; k < 2; ++k) dst[n][k] = *(const LAS bf16x8*)(lds + PG8_SB(b, h) + boff + n * 2048 + k * 1024); } while (0)
; #define PG8_MMA(ai, bj, At, Bt) do { __builtin_amdgcn_s_setprio(1); _Pragma("unroll") for (int m = 0; m < 4; ++m) _Pragma("unroll") for (int n = 0; n < 2; ++n) _Pragma("unroll") for (int k = 0; k < 2; ++k) \
;         acc[ai][bj][m][n] = __builtin_amdgcn_mfma_f32_16x16x32_bf16(Bt[n][k], At[m][k], acc[ai][bj][m][n], 0, 0, 0); __builtin_amdgcn_s_setprio(0); } while (0)
; #define PG8_WAIT_V(n) asm volatile("s_waitcnt vmcnt(" #n ")" ::: "memory")
; #define PG8_WAIT_L(n) asm volatile("s_waitcnt lgkmcnt(" #n ")" ::: "memory")
; #define PG8_BAR __builtin_amdgcn_s_barrier()
; #define PG8_SCHED __builtin_amdgcn_sched_barrier(0)
; template <class Epi, class Sched>
; __device__ __forceinline__ void gemm_phase(LAS unsigned char* lds, const Gemm g, const Sched& S, const Epi& E) {
;     ...
;             PG8_BAR; PG8_WAIT_L(0); PG8_MMA(0, 1, At, B1); PG8_BAR;
;             PG8_LDA(At, 0, 1); PG8_STAGE(PG8_SA(0, 0), a2, voffA);
;             PG8_BAR; PG8_WAIT_L(0); PG8_MMA(1, 0, At, B0); PG8_BAR; PG8_SCHED;
;             PG8_STAGE(PG8_SB(0, 1), b2 + hstep, voffB);
;             PG8_WAIT_V(6); PG8_BAR; PG8_MMA(1, 1, At, B1); PG8_BAR;
;             PG8_LDB(B0, 1, 0); PG8_SCHED; PG8_LDA(At, 1, 0); PG8_STAGE(PG8_SA(0, 1), a2 + hstep, voffA);
;             PG8_WAIT_L(8); PG8_BAR; PG8_WAIT_L(0); PG8_MMA(0, 0, At, B0); PG8_BAR; PG8_SCHED;
	s_waitcnt lgkmcnt(0)
	v_mfma_f32_16x16x32_bf16 v[116:119], v[176:179], v[144:147], v[116:119]
	v_mfma_f32_16x16x32_bf16 v[112:115], v[184:187], v[144:147], v[112:115]
	v_mfma_f32_16x16x32_bf16 v[100:103], v[176:179], v[152:155], v[100:103]
	v_mfma_f32_16x16x32_bf16 v[96:99], v[184:187], v[152:155], v[96:99]
	v_mfma_f32_16x16x32_bf16 v[84:87], v[176:179], v[160:163], v[84:87]
	v_mfma_f32_16x16x32_bf16 v[80:83], v[184:187], v[160:163], v[80:83]
	v_mfma_f32_16x16x32_bf16 v[68:71], v[176:179], v[168:171], v[68:71]
	v_mfma_f32_16x16x32_bf16 v[64:67], v[184:187], v[168:171], v[64:67]
	v_mfma_f32_16x16x32_bf16 v[116:119], v[180:183], v[148:151], v[116:119]
	v_mfma_f32_16x16x32_bf16 v[112:115], v[188:191], v[148:151], v[112:115]
	v_mfma_f32_16x16x32_bf16 v[100:103], v[180:183], v[156:159], v[100:103]
	v_mfma_f32_16x16x32_bf16 v[96:99], v[188:191], v[156:159], v[96:99]
	v_mfma_f32_16x16x32_bf16 v[84:87], v[180:183], v[164:167], v[84:87]
	v_mfma_f32_16x16x32_bf16 v[80:83], v[188:191], v[164:167], v[80:83]
	v_mfma_f32_16x16x32_bf16 v[68:71], v[180:183], v[172:175], v[68:71]
	v_mfma_f32_16x16x32_bf16 v[64:67], v[188:191], v[172:175], v[64:67]
	s_barrier
	s_setprio 0
	s_mov_b32 m0, s38
	v_lshl_add_u64 v[196:197], s[30:31], 0, v[202:203]
	ds_read_b128 v[144:147], v238 offset:16384
	ds_read_b128 v[148:151], v238 offset:17408
	ds_read_b128 v[152:155], v238 offset:18432
	ds_read_b128 v[156:159], v238 offset:19456
	ds_read_b128 v[160:163], v238 offset:20480
	ds_read_b128 v[164:167], v238 offset:21504
	ds_read_b128 v[168:171], v238 offset:22528
	ds_read_b128 v[172:175], v238 offset:23552
	global_load_lds_dwordx4 v202, s[30:31]
	v_lshl_add_u64 v[198:199], s[30:31], 0, v[206:207]
	s_mov_b32 m0, s39
	s_nop 0
	global_load_lds_dwordx4 v206, s[30:31]
	s_setprio 1
	s_barrier
	s_waitcnt lgkmcnt(0)
	v_mfma_f32_16x16x32_bf16 v[60:63], v[128:131], v[144:147], v[60:63]
	v_mfma_f32_16x16x32_bf16 v[56:59], v[136:139], v[144:147], v[56:59]
	v_mfma_f32_16x16x32_bf16 v[44:47], v[128:131], v[152:155], v[44:47]
	v_mfma_f32_16x16x32_bf16 v[40:43], v[136:139], v[152:155], v[40:43]
	v_mfma_f32_16x16x32_bf16 v[28:31], v[128:131], v[160:163], v[28:31]
	v_mfma_f32_16x16x32_bf16 v[24:27], v[136:139], v[160:163], v[24:27]
	v_mfma_f32_16x16x32_bf16 v[12:15], v[128:131], v[168:171], v[12:15]
	v_mfma_f32_16x16x32_bf16 v[8:11], v[136:139], v[168:171], v[8:11]
	v_mfma_f32_16x16x32_bf16 v[60:63], v[132:135], v[148:151], v[60:63]
	v_mfma_f32_16x16x32_bf16 v[56:59], v[140:143], v[148:151], v[56:59]
	v_mfma_f32_16x16x32_bf16 v[44:47], v[132:135], v[156:159], v[44:47]
	v_mfma_f32_16x16x32_bf16 v[40:43], v[140:143], v[156:159], v[40:43]
	v_mfma_f32_16x16x32_bf16 v[28:31], v[132:135], v[164:167], v[28:31]
	v_mfma_f32_16x16x32_bf16 v[24:27], v[140:143], v[164:167], v[24:27]
	v_mfma_f32_16x16x32_bf16 v[12:15], v[132:135], v[172:175], v[12:15]
	v_mfma_f32_16x16x32_bf16 v[8:11], v[140:143], v[172:175], v[8:11]
	s_barrier
	s_setprio 0
	s_add_u32 s24, s28, 0x60000
	s_addc_u32 s25, s29, 0
	s_add_i32 s59, s51, s37
	s_mov_b32 m0, s59
	s_nop 0
	global_load_lds_dwordx4 v204, s[24:25]
	s_add_i32 m0, s59, 0x2000
	s_nop 0
	global_load_lds_dwordx4 v208, s[24:25]
	s_add_u32 s24, s30, 0x60000
	s_addc_u32 s25, s31, 0
	s_mov_b32 m0, s40
	s_nop 0
	global_load_lds_dwordx4 v202, s[24:25]
	s_mov_b32 m0, s41
	s_nop 0
	global_load_lds_dwordx4 v206, s[24:25]
	s_waitcnt vmcnt(10)
	s_setprio 1
	s_barrier
	v_mfma_f32_16x16x32_bf16 v[52:55], v[176:179], v[144:147], v[52:55]
	v_mfma_f32_16x16x32_bf16 v[48:51], v[184:187], v[144:147], v[48:51]
	v_mfma_f32_16x16x32_bf16 v[36:39], v[176:179], v[152:155], v[36:39]
	v_mfma_f32_16x16x32_bf16 v[32:35], v[184:187], v[152:155], v[32:35]
	v_mfma_f32_16x16x32_bf16 v[20:23], v[176:179], v[160:163], v[20:23]
	v_mfma_f32_16x16x32_bf16 v[16:19], v[184:187], v[160:163], v[16:19]
	v_mfma_f32_16x16x32_bf16 v[4:7], v[176:179], v[168:171], v[4:7]
	v_mfma_f32_16x16x32_bf16 v[0:3], v[184:187], v[168:171], v[0:3]
	v_mfma_f32_16x16x32_bf16 v[52:55], v[180:183], v[148:151], v[52:55]
	v_mfma_f32_16x16x32_bf16 v[48:51], v[188:191], v[148:151], v[48:51]
	v_mfma_f32_16x16x32_bf16 v[36:39], v[180:183], v[156:159], v[36:39]
	v_mfma_f32_16x16x32_bf16 v[32:35], v[188:191], v[156:159], v[32:35]
	v_mfma_f32_16x16x32_bf16 v[20:23], v[180:183], v[164:167], v[20:23]
	v_mfma_f32_16x16x32_bf16 v[16:19], v[188:191], v[164:167], v[16:19]
	v_mfma_f32_16x16x32_bf16 v[4:7], v[180:183], v[172:175], v[4:7]
	v_mfma_f32_16x16x32_bf16 v[0:3], v[188:191], v[172:175], v[0:3]
	s_barrier
	s_setprio 0
	s_add_i32 s59, 0, 0x18000
	ds_read_b128 v[128:131], v239 offset:16384
	ds_read_b128 v[132:135], v239 offset:17408
	ds_read_b128 v[136:139], v239 offset:18432
	ds_read_b128 v[140:143], v239 offset:19456
	ds_read_b128 v[144:147], v238 offset:32768
	ds_read_b128 v[148:151], v238 offset:33792
	ds_read_b128 v[152:155], v238 offset:34816
	ds_read_b128 v[156:159], v238 offset:35840
	ds_read_b128 v[160:163], v238 offset:36864
	ds_read_b128 v[164:167], v238 offset:37888
	ds_read_b128 v[168:171], v238 offset:38912
	ds_read_b128 v[172:175], v238 offset:39936
	s_waitcnt lgkmcnt(8)
	s_waitcnt vmcnt(8)
	s_setprio 1
	s_barrier
; #define PG8_STAGE(bufoff, gbase, voff) do { _Pragma("unroll") for (int _i = 0; _i < 2; ++_i) \
;         __builtin_amdgcn_global_load_lds((const unsigned*)((const char*)(gbase) + (voff)[_i]), (LAS unsigned*)(lds + (bufoff) + ldsw + _i * 8192), 16, 0, 0); } while (0)
; #define PG8_LDA(dst, b, h) do { _Pragma("unroll") for (int m = 0; m < 4; ++m) _Pragma("unroll") for (int k = 0; k < 2; ++k) dst[m][k] = *(const LAS bf16x8*)(lds + PG8_SA(b, h) + aoff + m * 2048 + k * 1024); } while (0)
; #define PG8_LDB(dst, b, h) do { _Pragma("unroll") for (int n = 0; n < 2; ++n) _Pragma("unroll") for (int k = 0; k < 2; ++k) dst[n][k] = *(const LAS bf16x8*)(lds + PG8_SB(b, h) + boff + n * 2048 + k * 1024); } while (0)
; #define PG8_MMA(ai, bj, At, Bt) do { __builtin_amdgcn_s_setprio(1); _Pragma("unroll") for (int m = 0; m < 4; ++m) _Pragma("unroll") for (int n = 0; n < 2; ++n) _Pragma("unroll") for (int k = 0; k < 2; ++k) \
;         acc[ai][bj][m][n] = __builtin_amdgcn_mfma_f32_16x16x32_bf16(Bt[n][k], At[m][k], acc[ai][bj][m][n], 0, 0, 0); __builtin_amdgcn_s_setprio(0); } while (0)
; #define PG8_WAIT_V(n) asm volatile("s_waitcnt vmcnt(" #n ")" ::: "memory")
; #define PG8_WAIT_L(n) asm volatile("s_waitcnt lgkmcnt(" #n ")" ::: "memory")
; #define PG8_BAR __builtin_amdgcn_s_barrier()
; #define PG8_SCHED __builtin_amdgcn_sched_barrier(0)
; template <class Epi, class Sched>
; __device__ __forceinline__ void gemm_phase(LAS unsigned char* lds, const Gemm g, const Sched& S, const Epi& E) {
;     ...
;             PG8_WAIT_L(8); PG8_BAR; PG8_WAIT_L(0); PG8_MMA(0, 0, At, B0); PG8_BAR; PG8_SCHED;
;             PG8_LDB(B1, 1, 1); PG8_STAGE(PG8_SB(1, 0), b3, voffB);
;             PG8_BAR; PG8_WAIT_L(0); PG8_MMA(0, 1, At, B1); PG8_BAR;
;             PG8_LDA(At, 1, 1); PG8_STAGE(PG8_SA(1, 0), a3, voffA);
;             PG8_BAR; PG8_WAIT_L(0); PG8_MMA(1, 0, At, B0); PG8_BAR; PG8_SCHED;
;             PG8_STAGE(PG8_SB(1, 1), b3 + hstep, voffB);
;             PG8_WAIT_V(6); PG8_BAR; PG8_MMA(1, 1, At, B1); PG8_BAR;
	s_waitcnt lgkmcnt(0)
	v_mfma_f32_16x16x32_bf16 v[124:127], v[128:131], v[144:147], v[124:127]
	v_mfma_f32_16x16x32_bf16 v[120:123], v[136:139], v[144:147], v[120:123]
	v_mfma_f32_16x16x32_bf16 v[108:111], v[128:131], v[152:155], v[108:111]
	v_mfma_f32_16x16x32_bf16 v[104:107], v[136:139], v[152:155], v[104:107]
	v_mfma_f32_16x16x32_bf16 v[92:95], v[128:131], v[160:163], v[92:95]
	v_mfma_f32_16x16x32_bf16 v[88:91], v[136:139], v[160:163], v[88:91]
	v_mfma_f32_16x16x32_bf16 v[76:79], v[128:131], v[168:171], v[76:79]
	v_mfma_f32_16x16x32_bf16 v[72:75], v[136:139], v[168:171], v[72:75]
	v_mfma_f32_16x16x32_bf16 v[124:127], v[132:135], v[148:151], v[124:127]
	v_mfma_f32_16x16x32_bf16 v[120:123], v[140:143], v[148:151], v[120:123]
	v_mfma_f32_16x16x32_bf16 v[108:111], v[132:135], v[156:159], v[108:111]
	v_mfma_f32_16x16x32_bf16 v[104:107], v[140:143], v[156:159], v[104:107]
	v_mfma_f32_16x16x32_bf16 v[92:95], v[132:135], v[164:167], v[92:95]
	v_mfma_f32_16x16x32_bf16 v[88:91], v[140:143], v[164:167], v[88:91]
	v_mfma_f32_16x16x32_bf16 v[76:79], v[132:135], v[172:175], v[76:79]
	v_mfma_f32_16x16x32_bf16 v[72:75], v[140:143], v[172:175], v[72:75]
	s_barrier
	s_setprio 0
	s_add_i32 s30, 0, 0x1c000
	s_add_i32 s24, s59, s37
	s_add_u32 s0, s28, 0x80
	s_addc_u32 s1, s29, 0
	s_mov_b32 m0, s24
	ds_read_b128 v[176:179], v239 offset:32768
	ds_read_b128 v[180:183], v239 offset:33792
	ds_read_b128 v[184:187], v239 offset:34816
	ds_read_b128 v[188:191], v239 offset:35840
	global_load_lds_dwordx4 v204, s[0:1]
	s_add_i32 m0, s24, 0x2000
	s_nop 0
	global_load_lds_dwordx4 v208, s[0:1]
	s_waitcnt vmcnt(8)
	s_setprio 1
	s_barrier
	s_waitcnt lgkmcnt(0)
	v_mfma_f32_16x16x32_bf16 v[116:119], v[176:179], v[144:147], v[116:119]
	v_mfma_f32_16x16x32_bf16 v[112:115], v[184:187], v[144:147], v[112:115]
	v_mfma_f32_16x16x32_bf16 v[100:103], v[176:179], v[152:155], v[100:103]
	v_mfma_f32_16x16x32_bf16 v[96:99], v[184:187], v[152:155], v[96:99]
	v_mfma_f32_16x16x32_bf16 v[84:87], v[176:179], v[160:163], v[84:87]
	v_mfma_f32_16x16x32_bf16 v[80:83], v[184:187], v[160:163], v[80:83]
	v_mfma_f32_16x16x32_bf16 v[68:71], v[176:179], v[168:171], v[68:71]
	v_mfma_f32_16x16x32_bf16 v[64:67], v[184:187], v[168:171], v[64:67]
	v_mfma_f32_16x16x32_bf16 v[116:119], v[180:183], v[148:151], v[116:119]
	v_mfma_f32_16x16x32_bf16 v[112:115], v[188:191], v[148:151], v[112:115]
	v_mfma_f32_16x16x32_bf16 v[100:103], v[180:183], v[156:159], v[100:103]
	v_mfma_f32_16x16x32_bf16 v[96:99], v[188:191], v[156:159], v[96:99]
	v_mfma_f32_16x16x32_bf16 v[84:87], v[180:183], v[164:167], v[84:87]
	v_mfma_f32_16x16x32_bf16 v[80:83], v[188:191], v[164:167], v[80:83]
	v_mfma_f32_16x16x32_bf16 v[68:71], v[180:183], v[172:175], v[68:71]
	v_mfma_f32_16x16x32_bf16 v[64:67], v[188:191], v[172:175], v[64:67]
	s_barrier
	s_setprio 0
	s_mov_b32 m0, s47
	s_mov_b64 s[0:1], 0x80
	v_lshl_add_u64 v[192:193], v[196:197], 0, s[0:1]
	ds_read_b128 v[144:147], v238 offset:49152
	ds_read_b128 v[148:151], v238 offset:50176
	ds_read_b128 v[152:155], v238 offset:51200
	ds_read_b128 v[156:159], v238 offset:52224
	ds_read_b128 v[160:163], v238 offset:53248
	ds_read_b128 v[164:167], v238 offset:54272
	ds_read_b128 v[168:171], v238 offset:55296
	ds_read_b128 v[172:175], v238 offset:56320
	global_load_lds_dwordx4 v[192:193], off
	v_lshl_add_u64 v[192:193], v[198:199], 0, s[0:1]
	s_mov_b32 m0, s48
	s_nop 0
	global_load_lds_dwordx4 v[192:193], off
	s_setprio 1
	s_barrier
	s_waitcnt lgkmcnt(0)
	v_mfma_f32_16x16x32_bf16 v[60:63], v[128:131], v[144:147], v[60:63]
	v_mfma_f32_16x16x32_bf16 v[56:59], v[136:139], v[144:147], v[56:59]
	v_mfma_f32_16x16x32_bf16 v[44:47], v[128:131], v[152:155], v[44:47]
	v_mfma_f32_16x16x32_bf16 v[40:43], v[136:139], v[152:155], v[40:43]
	v_mfma_f32_16x16x32_bf16 v[28:31], v[128:131], v[160:163], v[28:31]
	v_mfma_f32_16x16x32_bf16 v[24:27], v[136:139], v[160:163], v[24:27]
	v_mfma_f32_16x16x32_bf16 v[12:15], v[128:131], v[168:171], v[12:15]
	v_mfma_f32_16x16x32_bf16 v[8:11], v[136:139], v[168:171], v[8:11]
	v_mfma_f32_16x16x32_bf16 v[60:63], v[132:135], v[148:151], v[60:63]
	v_mfma_f32_16x16x32_bf16 v[56:59], v[140:143], v[148:151], v[56:59]
	v_mfma_f32_16x16x32_bf16 v[44:47], v[132:135], v[156:159], v[44:47]
	v_mfma_f32_16x16x32_bf16 v[40:43], v[140:143], v[156:159], v[40:43]
	v_mfma_f32_16x16x32_bf16 v[28:31], v[132:135], v[164:167], v[28:31]
	v_mfma_f32_16x16x32_bf16 v[24:27], v[140:143], v[164:167], v[24:27]
	v_mfma_f32_16x16x32_bf16 v[12:15], v[132:135], v[172:175], v[12:15]
	v_mfma_f32_16x16x32_bf16 v[8:11], v[140:143], v[172:175], v[8:11]
	s_barrier
	s_setprio 0
	s_add_u32 s24, s28, 0x60080
	s_addc_u32 s25, s29, 0
	s_add_i32 s28, s30, s37
	s_mov_b32 m0, s28
	s_nop 0
	global_load_lds_dwordx4 v204, s[24:25]
	s_add_i32 m0, s28, 0x2000
	s_nop 0
	global_load_lds_dwordx4 v208, s[24:25]
	s_waitcnt vmcnt(8)
	s_setprio 1
	s_barrier
	v_mfma_f32_16x16x32_bf16 v[52:55], v[176:179], v[144:147], v[52:55]
	v_mfma_f32_16x16x32_bf16 v[48:51], v[184:187], v[144:147], v[48:51]
	v_mfma_f32_16x16x32_bf16 v[36:39], v[176:179], v[152:155], v[36:39]
	v_mfma_f32_16x16x32_bf16 v[32:35], v[184:187], v[152:155], v[32:35]
	v_mfma_f32_16x16x32_bf16 v[20:23], v[176:179], v[160:163], v[20:23]
	v_mfma_f32_16x16x32_bf16 v[16:19], v[184:187], v[160:163], v[16:19]
	v_mfma_f32_16x16x32_bf16 v[4:7], v[176:179], v[168:171], v[4:7]
	v_mfma_f32_16x16x32_bf16 v[0:3], v[184:187], v[168:171], v[0:3]
	v_mfma_f32_16x16x32_bf16 v[52:55], v[180:183], v[148:151], v[52:55]
	v_mfma_f32_16x16x32_bf16 v[48:51], v[188:191], v[148:151], v[48:51]
	v_mfma_f32_16x16x32_bf16 v[36:39], v[180:183], v[156:159], v[36:39]
	v_mfma_f32_16x16x32_bf16 v[32:35], v[188:191], v[156:159], v[32:35]
	v_mfma_f32_16x16x32_bf16 v[20:23], v[180:183], v[164:167], v[20:23]
	v_mfma_f32_16x16x32_bf16 v[16:19], v[188:191], v[164:167], v[16:19]
	v_mfma_f32_16x16x32_bf16 v[4:7], v[180:183], v[172:175], v[4:7]
	v_mfma_f32_16x16x32_bf16 v[0:3], v[188:191], v[172:175], v[0:3]
	s_barrier
; __device__ __forceinline__ unsigned cvt_pk_bf16(float lo, float hi) { unsigned r; asm volatile("v_cvt_pk_bf16_f32 %0, %1, %2" : "=v"(r) : "v"(lo), "v"(hi)); return r; }
; __device__ __forceinline__ float bf_lo(unsigned u) { return __uint_as_float(u << 16); }
; __device__ __forceinline__ float bf_hi(unsigned u) { return __uint_as_float(u & 0xffff0000u); }
;     __device__ __forceinline__ void operator()(const AccT& acc, const Unit& u, int wr, int wc, int fr, int fq) const {
;         asm volatile("" : "+v"(fr), "+v"(fq));
;         const int rowt = u.pm * 256; const int b = rowt >> 11;
;         const bf16_t* res = res_b + (size_t)rowt * DM; bf16_t* out = hb + (size_t)rowt * DM;
;         const int col0 = u.pn * 256 + wc * 32 + 8 * fq;
;         f32x4 gv[2][2];
; #pragma unroll
;         for (int bj = 0; bj < 2; ++bj)
; #pragma unroll
;             for (int n = 0; n < 2; ++n) gv[bj][n] = *(const f32x4*)(gate + (size_t)b * NMOD + col0 + bj * 128 + n * 4) * gs;
;         u32x4 r[2][4][2];
; #pragma unroll
;         for (int ai = 0; ai < 2; ++ai)
; #pragma unroll
;             for (int m = 0; m < 4; ++m)
; #pragma unroll
;                 for (int bj = 0; bj < 2; ++bj) r[ai][m][bj] = *(const u32x4*)(res + (size_t)(wr * 64 + fr + ai * 128 + m * 16) * DM + col0 + bj * 128);
; #pragma unroll
;         for (int ai = 0; ai < 2; ++ai)
; #pragma unroll
;             for (int m = 0; m < 4; ++m)
; #pragma unroll
;                 for (int bj = 0; bj < 2; ++bj) {
;                     const u32x4 q = r[ai][m][bj];
;                     const f32x4 r0 = {bf_lo(q.x), bf_hi(q.x), bf_lo(q.y), bf_hi(q.y)}, r1 = {bf_lo(q.z), bf_hi(q.z), bf_lo(q.w), bf_hi(q.w)};
;                     const f32x4 h0 = r0 + gv[bj][0] * acc[ai][bj][m][0], h1 = r1 + gv[bj][1] * acc[ai][bj][m][1];
;                     u32x4 w; w.x = cvt_pk_bf16(h0[0], h0[1]); w.y = cvt_pk_bf16(h0[2], h0[3]); w.z = cvt_pk_bf16(h1[0], h1[1]); w.w = cvt_pk_bf16(h1[2], h1[3]);
;                     *(u32x4*)(out + (size_t)(wr * 64 + fr + ai * 128 + m * 16) * DM + col0 + bj * 128) = w;
	s_setprio 0
	s_add_i32 s58, s58, 2
	s_add_u32 s56, s56, 0x100
	s_addc_u32 s57, s57, 0
	s_cmp_gt_u32 s58, 21
	s_mov_b64 s[24:25], s[26:27]
	s_cbranch_scc0 .LBB0_902
	s_lshl_b32 s27, s55, 8
	v_mov_b32_e32 v146, v235
	v_mov_b32_e32 v128, v234
	s_lshl_b32 s24, s54, 8
	s_ashr_i32 s26, s54, 3
	s_or_b32 s27, s27, s46
	s_ashr_i32 s25, s24, 31
	v_lshl_add_u32 v144, v128, 3, s27
	s_mul_hi_i32 s27, s26, 0x9000
	s_mul_i32 s26, s26, 0x9000
	s_add_u32 s26, s43, s26
	s_addc_u32 s27, s44, s27
	v_ashrrev_i32_e32 v145, 31, v144
	s_lshl_b64 s[24:25], s[24:25], 11
	v_lshl_add_u64 v[132:133], v[144:145], 2, s[26:27]
	s_add_u32 s26, s62, s24
	v_add_u32_e32 v146, s45, v146
	s_addc_u32 s27, s63, s25
	v_lshlrev_b64 v[222:223], 1, v[144:145]
	v_ashrrev_i32_e32 v147, 31, v146
	v_lshl_add_u64 v[144:145], s[26:27], 0, v[222:223]
	v_lshlrev_b64 v[248:249], 11, v[146:147]
	v_lshl_add_u64 v[146:147], v[144:145], 0, v[248:249]
	global_load_dwordx4 v[136:139], v[132:133], off offset:16
	global_load_dwordx4 v[140:143], v[132:133], off
	global_load_dwordx4 v[128:131], v[132:133], off offset:528
	s_nop 0
	global_load_dwordx4 v[132:135], v[132:133], off offset:512
	s_nop 0
	global_load_dwordx4 v[240:243], v[146:147], off
	global_load_dwordx4 v[244:247], v[146:147], off offset:256
	v_lshl_add_u64 v[232:233], v[248:249], 0, s[10:11]
	v_lshl_add_u64 v[146:147], v[144:145], 0, v[232:233]
	global_load_dwordx4 v[196:199], v[146:147], off
	global_load_dwordx4 v[192:195], v[146:147], off offset:256
	v_lshl_add_u64 v[230:231], v[248:249], 0, s[12:13]
	v_lshl_add_u64 v[146:147], v[144:145], 0, v[230:231]
	global_load_dwordx4 v[188:191], v[146:147], off
	global_load_dwordx4 v[184:187], v[146:147], off offset:256
	v_lshl_add_u64 v[228:229], v[248:249], 0, s[14:15]
	v_lshl_add_u64 v[146:147], v[144:145], 0, v[228:229]
	global_load_dwordx4 v[180:183], v[146:147], off
	global_load_dwordx4 v[176:179], v[146:147], off offset:256
	v_lshl_add_u64 v[226:227], v[248:249], 0, s[16:17]
	v_lshl_add_u64 v[146:147], v[144:145], 0, v[226:227]
	global_load_dwordx4 v[172:175], v[146:147], off
	global_load_dwordx4 v[168:171], v[146:147], off offset:256
	v_lshl_add_u64 v[224:225], v[248:249], 0, s[18:19]
	v_lshl_add_u64 v[146:147], v[144:145], 0, v[224:225]
	global_load_dwordx4 v[164:167], v[146:147], off
	global_load_dwordx4 v[160:163], v[146:147], off offset:256
	v_lshl_add_u64 v[220:221], v[248:249], 0, s[20:21]
	v_lshl_add_u64 v[146:147], v[144:145], 0, v[220:221]
	global_load_dwordx4 v[156:159], v[146:147], off
	global_load_dwordx4 v[152:155], v[146:147], off offset:256
	v_lshl_add_u64 v[218:219], v[248:249], 0, s[22:23]
	v_lshl_add_u64 v[144:145], v[144:145], 0, v[218:219]
	global_load_dwordx4 v[148:151], v[144:145], off
	s_nop 0
	global_load_dwordx4 v[144:147], v[144:145], off offset:256
	s_add_u32 s24, s80, s24
	s_addc_u32 s25, s81, s25
	v_lshl_add_u64 v[222:223], s[24:25], 0, v[222:223]
	v_lshl_add_u64 v[248:249], v[222:223], 0, v[248:249]
	s_and_b64 vcc, exec, s[2:3]
	s_mov_b32 s55, s52
	s_mov_b32 s54, s53
	s_mov_b64 s[26:27], s[6:7]
	s_mov_b64 s[24:25], s[4:5]
	s_waitcnt vmcnt(0)
	v_lshlrev_b32_e32 v250, 16, v240
	v_and_b32_e32 v251, 0xffff0000, v240
	v_lshlrev_b32_e32 v240, 16, v241
	v_and_b32_e32 v241, 0xffff0000, v241
	v_lshlrev_b32_e32 v252, 16, v242
	v_and_b32_e32 v253, 0xffff0000, v242
	v_lshlrev_b32_e32 v242, 16, v243
	v_and_b32_e32 v243, 0xffff0000, v243
	v_pk_fma_f32 v[126:127], v[126:127], v[142:143], v[240:241]
	v_pk_fma_f32 v[124:125], v[124:125], v[140:141], v[250:251]
	v_pk_fma_f32 v[240:241], v[122:123], v[138:139], v[242:243]
	v_pk_fma_f32 v[122:123], v[120:121], v[136:137], v[252:253]
	v_cvt_pk_bf16_f32 v120, v124, v125
	v_cvt_pk_bf16_f32 v121, v126, v127
	v_lshlrev_b32_e32 v124, 16, v246
	v_cvt_pk_bf16_f32 v122, v122, v123
	v_cvt_pk_bf16_f32 v123, v240, v241
	global_store_dwordx4 v[248:249], v[120:123], off
	v_and_b32_e32 v125, 0xffff0000, v246
	v_lshlrev_b32_e32 v126, 16, v247
	v_lshlrev_b32_e32 v120, 16, v244
	v_and_b32_e32 v121, 0xffff0000, v244
	v_and_b32_e32 v127, 0xffff0000, v247
	v_lshlrev_b32_e32 v122, 16, v245
	v_and_b32_e32 v123, 0xffff0000, v245
	v_pk_fma_f32 v[116:117], v[116:117], v[132:133], v[120:121]
	v_pk_fma_f32 v[120:121], v[114:115], v[130:131], v[126:127]
	v_pk_fma_f32 v[114:115], v[112:113], v[128:129], v[124:125]
	v_pk_fma_f32 v[118:119], v[118:119], v[134:135], v[122:123]
	v_cvt_pk_bf16_f32 v112, v116, v117
	v_lshlrev_b32_e32 v116, 16, v197
	v_cvt_pk_bf16_f32 v113, v118, v119
	v_cvt_pk_bf16_f32 v114, v114, v115
	v_cvt_pk_bf16_f32 v115, v120, v121
	global_store_dwordx4 v[248:249], v[112:115], off offset:256
	v_and_b32_e32 v117, 0xffff0000, v197
	v_lshlrev_b32_e32 v118, 16, v198
	v_lshlrev_b32_e32 v114, 16, v196
	v_and_b32_e32 v115, 0xffff0000, v196
	v_and_b32_e32 v119, 0xffff0000, v198
	v_lshlrev_b32_e32 v120, 16, v199
	v_and_b32_e32 v121, 0xffff0000, v199
	v_lshl_add_u64 v[112:113], v[222:223], 0, v[232:233]
	v_pk_fma_f32 v[110:111], v[110:111], v[142:143], v[116:117]
	v_pk_fma_f32 v[108:109], v[108:109], v[140:141], v[114:115]
	v_pk_fma_f32 v[114:115], v[106:107], v[138:139], v[120:121]
	v_pk_fma_f32 v[106:107], v[104:105], v[136:137], v[118:119]
	v_cvt_pk_bf16_f32 v104, v108, v109
	v_cvt_pk_bf16_f32 v105, v110, v111
	v_lshlrev_b32_e32 v108, 16, v194
	v_cvt_pk_bf16_f32 v106, v106, v107
	v_cvt_pk_bf16_f32 v107, v114, v115
	global_store_dwordx4 v[112:113], v[104:107], off
	v_and_b32_e32 v109, 0xffff0000, v194
	v_lshlrev_b32_e32 v110, 16, v195
	v_lshlrev_b32_e32 v104, 16, v192
	v_and_b32_e32 v105, 0xffff0000, v192
	v_and_b32_e32 v111, 0xffff0000, v195
	v_lshlrev_b32_e32 v106, 16, v193
	v_and_b32_e32 v107, 0xffff0000, v193
; __device__ __forceinline__ unsigned cvt_pk_bf16(float lo, float hi) { unsigned r; asm volatile("v_cvt_pk_bf16_f32 %0, %1, %2" : "=v"(r) : "v"(lo), "v"(hi)); return r; }
; __device__ __forceinline__ float bf_lo(unsigned u) { return __uint_as_float(u << 16); }
; __device__ __forceinline__ float bf_hi(unsigned u) { return __uint_as_float(u & 0xffff0000u); }
;     __device__ __forceinline__ void operator()(const AccT& acc, const Unit& u, int wr, int wc, int fr, int fq) const {
;     ...
;         for (int ai = 0; ai < 2; ++ai)
; #pragma unroll
;             for (int m = 0; m < 4; ++m)
; #pragma unroll
;                 for (int bj = 0; bj < 2; ++bj) {
;                     const u32x4 q = r[ai][m][bj];
;                     const f32x4 r0 = {bf_lo(q.x), bf_hi(q.x), bf_lo(q.y), bf_hi(q.y)}, r1 = {bf_lo(q.z), bf_hi(q.z), bf_lo(q.w), bf_hi(q.w)};
;                     const f32x4 h0 = r0 + gv[bj][0] * acc[ai][bj][m][0], h1 = r1 + gv[bj][1] * acc[ai][bj][m][1];
;                     u32x4 w; w.x = cvt_pk_bf16(h0[0], h0[1]); w.y = cvt_pk_bf16(h0[2], h0[3]); w.z = cvt_pk_bf16(h1[0], h1[1]); w.w = cvt_pk_bf16(h1[2], h1[3]);
;                     *(u32x4*)(out + (size_t)(wr * 64 + fr + ai * 128 + m * 16) * DM + col0 + bj * 128) = w;
	v_pk_fma_f32 v[100:101], v[100:101], v[132:133], v[104:105]
	v_pk_fma_f32 v[104:105], v[98:99], v[130:131], v[110:111]
	v_pk_fma_f32 v[98:99], v[96:97], v[128:129], v[108:109]
	v_pk_fma_f32 v[102:103], v[102:103], v[134:135], v[106:107]
	v_cvt_pk_bf16_f32 v96, v100, v101
	v_lshlrev_b32_e32 v100, 16, v189
	v_cvt_pk_bf16_f32 v97, v102, v103
	v_cvt_pk_bf16_f32 v98, v98, v99
	v_cvt_pk_bf16_f32 v99, v104, v105
	global_store_dwordx4 v[112:113], v[96:99], off offset:256
	v_and_b32_e32 v101, 0xffff0000, v189
	v_lshlrev_b32_e32 v102, 16, v190
	v_lshlrev_b32_e32 v98, 16, v188
	v_and_b32_e32 v99, 0xffff0000, v188
	v_and_b32_e32 v103, 0xffff0000, v190
	v_lshlrev_b32_e32 v104, 16, v191
	v_and_b32_e32 v105, 0xffff0000, v191
	v_lshl_add_u64 v[96:97], v[222:223], 0, v[230:231]
	v_pk_fma_f32 v[94:95], v[94:95], v[142:143], v[100:101]
	v_pk_fma_f32 v[92:93], v[92:93], v[140:141], v[98:99]
	v_pk_fma_f32 v[98:99], v[90:91], v[138:139], v[104:105]
	v_pk_fma_f32 v[90:91], v[88:89], v[136:137], v[102:103]
	v_cvt_pk_bf16_f32 v88, v92, v93
	v_cvt_pk_bf16_f32 v89, v94, v95
	v_lshlrev_b32_e32 v92, 16, v186
	v_cvt_pk_bf16_f32 v90, v90, v91
	v_cvt_pk_bf16_f32 v91, v98, v99
	global_store_dwordx4 v[96:97], v[88:91], off
	v_and_b32_e32 v93, 0xffff0000, v186
	v_lshlrev_b32_e32 v94, 16, v187
	v_lshlrev_b32_e32 v88, 16, v184
	v_and_b32_e32 v89, 0xffff0000, v184
	v_and_b32_e32 v95, 0xffff0000, v187
	v_lshlrev_b32_e32 v90, 16, v185
	v_and_b32_e32 v91, 0xffff0000, v185
	v_pk_fma_f32 v[84:85], v[84:85], v[132:133], v[88:89]
	v_pk_fma_f32 v[88:89], v[82:83], v[130:131], v[94:95]
	v_pk_fma_f32 v[82:83], v[80:81], v[128:129], v[92:93]
	v_pk_fma_f32 v[86:87], v[86:87], v[134:135], v[90:91]
	v_cvt_pk_bf16_f32 v80, v84, v85
	v_lshlrev_b32_e32 v84, 16, v181
	v_cvt_pk_bf16_f32 v81, v86, v87
	v_cvt_pk_bf16_f32 v82, v82, v83
	v_cvt_pk_bf16_f32 v83, v88, v89
	global_store_dwordx4 v[96:97], v[80:83], off offset:256
	v_and_b32_e32 v85, 0xffff0000, v181
	v_lshlrev_b32_e32 v86, 16, v182
	v_lshlrev_b32_e32 v82, 16, v180
	v_and_b32_e32 v83, 0xffff0000, v180
	v_and_b32_e32 v87, 0xffff0000, v182
	v_lshlrev_b32_e32 v88, 16, v183
	v_and_b32_e32 v89, 0xffff0000, v183
	v_lshl_add_u64 v[80:81], v[222:223], 0, v[228:229]
	v_pk_fma_f32 v[78:79], v[78:79], v[142:143], v[84:85]
	v_pk_fma_f32 v[76:77], v[76:77], v[140:141], v[82:83]
	v_pk_fma_f32 v[82:83], v[74:75], v[138:139], v[88:89]
	v_pk_fma_f32 v[74:75], v[72:73], v[136:137], v[86:87]
	v_cvt_pk_bf16_f32 v72, v76, v77
	v_cvt_pk_bf16_f32 v73, v78, v79
	v_lshlrev_b32_e32 v76, 16, v178
	v_cvt_pk_bf16_f32 v74, v74, v75
	v_cvt_pk_bf16_f32 v75, v82, v83
	global_store_dwordx4 v[80:81], v[72:75], off
	v_and_b32_e32 v77, 0xffff0000, v178
	v_lshlrev_b32_e32 v78, 16, v179
	v_lshlrev_b32_e32 v72, 16, v176
	v_and_b32_e32 v73, 0xffff0000, v176
	v_and_b32_e32 v79, 0xffff0000, v179
	v_lshlrev_b32_e32 v74, 16, v177
	v_and_b32_e32 v75, 0xffff0000, v177
	v_pk_fma_f32 v[68:69], v[68:69], v[132:133], v[72:73]
	v_pk_fma_f32 v[72:73], v[66:67], v[130:131], v[78:79]
	v_pk_fma_f32 v[66:67], v[64:65], v[128:129], v[76:77]
	v_pk_fma_f32 v[70:71], v[70:71], v[134:135], v[74:75]
	v_cvt_pk_bf16_f32 v64, v68, v69
	v_lshlrev_b32_e32 v68, 16, v173
	v_cvt_pk_bf16_f32 v65, v70, v71
	v_cvt_pk_bf16_f32 v66, v66, v67
	v_cvt_pk_bf16_f32 v67, v72, v73
	global_store_dwordx4 v[80:81], v[64:67], off offset:256
	v_and_b32_e32 v69, 0xffff0000, v173
	v_lshlrev_b32_e32 v70, 16, v174
	v_lshlrev_b32_e32 v66, 16, v172
	v_and_b32_e32 v67, 0xffff0000, v172
	v_and_b32_e32 v71, 0xffff0000, v174
	v_lshlrev_b32_e32 v72, 16, v175
	v_and_b32_e32 v73, 0xffff0000, v175
	v_lshl_add_u64 v[64:65], v[222:223], 0, v[226:227]
	v_pk_fma_f32 v[62:63], v[62:63], v[142:143], v[68:69]
	v_pk_fma_f32 v[60:61], v[60:61], v[140:141], v[66:67]
	v_pk_fma_f32 v[66:67], v[58:59], v[138:139], v[72:73]
	v_pk_fma_f32 v[58:59], v[56:57], v[136:137], v[70:71]
	v_cvt_pk_bf16_f32 v56, v60, v61
	v_cvt_pk_bf16_f32 v57, v62, v63
	v_lshlrev_b32_e32 v60, 16, v170
	v_cvt_pk_bf16_f32 v58, v58, v59
	v_cvt_pk_bf16_f32 v59, v66, v67
	global_store_dwordx4 v[64:65], v[56:59], off
	v_and_b32_e32 v61, 0xffff0000, v170
	v_lshlrev_b32_e32 v62, 16, v171
	v_lshlrev_b32_e32 v56, 16, v168
	v_and_b32_e32 v57, 0xffff0000, v168
	v_and_b32_e32 v63, 0xffff0000, v171
	v_lshlrev_b32_e32 v58, 16, v169
	v_and_b32_e32 v59, 0xffff0000, v169
	v_pk_fma_f32 v[52:53], v[52:53], v[132:133], v[56:57]
	v_pk_fma_f32 v[56:57], v[50:51], v[130:131], v[62:63]
	v_pk_fma_f32 v[50:51], v[48:49], v[128:129], v[60:61]
	v_pk_fma_f32 v[54:55], v[54:55], v[134:135], v[58:59]
; __device__ __forceinline__ unsigned cvt_pk_bf16(float lo, float hi) { unsigned r; asm volatile("v_cvt_pk_bf16_f32 %0, %1, %2" : "=v"(r) : "v"(lo), "v"(hi)); return r; }
; __device__ __forceinline__ float bf_lo(unsigned u) { return __uint_as_float(u << 16); }
; __device__ __forceinline__ float bf_hi(unsigned u) { return __uint_as_float(u & 0xffff0000u); }
; #define PG8_WAIT_V(n) asm volatile("s_waitcnt vmcnt(" #n ")" ::: "memory")
; #define PG8_BAR __builtin_amdgcn_s_barrier()
; template <class Epi, class Sched>
; __device__ __forceinline__ void gemm_phase(LAS unsigned char* lds, const Gemm g, const Sched& S, const Epi& E) {
;     ...
;         if (!has_next) break;
; #pragma unroll
;         for (int a = 0; a < 2; ++a)
; #pragma unroll
;             for (int b = 0; b < 2; ++b)
; #pragma unroll
;                 for (int m = 0; m < 4; ++m)
; #pragma unroll
;                     for (int n = 0; n < 2; ++n) acc[a][b][m][n] = (f32x4){0.f, 0.f, 0.f, 0.f};
;         cur = nxt; cA = nA; cB = nB; ++ui;
;     }
;     PG8_WAIT_V(0);
;     if (wr == 0) PG8_BAR;
;     PG8_BAR;
;     __device__ __forceinline__ void operator()(const AccT& acc, const Unit& u, int wr, int wc, int fr, int fq) const {
;     ...
;         for (int ai = 0; ai < 2; ++ai)
; #pragma unroll
;             for (int m = 0; m < 4; ++m)
; #pragma unroll
;                 for (int bj = 0; bj < 2; ++bj) {
;                     const u32x4 q = r[ai][m][bj];
;                     const f32x4 r0 = {bf_lo(q.x), bf_hi(q.x), bf_lo(q.y), bf_hi(q.y)}, r1 = {bf_lo(q.z), bf_hi(q.z), bf_lo(q.w), bf_hi(q.w)};
;                     const f32x4 h0 = r0 + gv[bj][0] * acc[ai][bj][m][0], h1 = r1 + gv[bj][1] * acc[ai][bj][m][1];
;                     u32x4 w; w.x = cvt_pk_bf16(h0[0], h0[1]); w.y = cvt_pk_bf16(h0[2], h0[3]); w.z = cvt_pk_bf16(h1[0], h1[1]); w.w = cvt_pk_bf16(h1[2], h1[3]);
;                     *(u32x4*)(out + (size_t)(wr * 64 + fr + ai * 128 + m * 16) * DM + col0 + bj * 128) = w;
	v_cvt_pk_bf16_f32 v48, v52, v53
	v_lshlrev_b32_e32 v52, 16, v165
	v_cvt_pk_bf16_f32 v49, v54, v55
	v_cvt_pk_bf16_f32 v50, v50, v51
	v_cvt_pk_bf16_f32 v51, v56, v57
	global_store_dwordx4 v[64:65], v[48:51], off offset:256
	v_and_b32_e32 v53, 0xffff0000, v165
	v_lshlrev_b32_e32 v54, 16, v166
	v_lshlrev_b32_e32 v50, 16, v164
	v_and_b32_e32 v51, 0xffff0000, v164
	v_and_b32_e32 v55, 0xffff0000, v166
	v_lshlrev_b32_e32 v56, 16, v167
	v_and_b32_e32 v57, 0xffff0000, v167
	v_lshl_add_u64 v[48:49], v[222:223], 0, v[224:225]
	v_pk_fma_f32 v[46:47], v[46:47], v[142:143], v[52:53]
	v_pk_fma_f32 v[44:45], v[44:45], v[140:141], v[50:51]
	v_pk_fma_f32 v[50:51], v[42:43], v[138:139], v[56:57]
	v_pk_fma_f32 v[42:43], v[40:41], v[136:137], v[54:55]
	v_cvt_pk_bf16_f32 v40, v44, v45
	v_cvt_pk_bf16_f32 v41, v46, v47
	v_lshlrev_b32_e32 v44, 16, v162
	v_cvt_pk_bf16_f32 v42, v42, v43
	v_cvt_pk_bf16_f32 v43, v50, v51
	global_store_dwordx4 v[48:49], v[40:43], off
	v_and_b32_e32 v45, 0xffff0000, v162
	v_lshlrev_b32_e32 v46, 16, v163
	v_lshlrev_b32_e32 v40, 16, v160
	v_and_b32_e32 v41, 0xffff0000, v160
	v_and_b32_e32 v47, 0xffff0000, v163
	v_lshlrev_b32_e32 v42, 16, v161
	v_and_b32_e32 v43, 0xffff0000, v161
	v_pk_fma_f32 v[36:37], v[36:37], v[132:133], v[40:41]
	v_pk_fma_f32 v[40:41], v[34:35], v[130:131], v[46:47]
	v_pk_fma_f32 v[34:35], v[32:33], v[128:129], v[44:45]
	v_pk_fma_f32 v[38:39], v[38:39], v[134:135], v[42:43]
	v_cvt_pk_bf16_f32 v32, v36, v37
	v_lshlrev_b32_e32 v36, 16, v157
	v_cvt_pk_bf16_f32 v33, v38, v39
	v_cvt_pk_bf16_f32 v34, v34, v35
	v_cvt_pk_bf16_f32 v35, v40, v41
	global_store_dwordx4 v[48:49], v[32:35], off offset:256
	v_and_b32_e32 v37, 0xffff0000, v157
	v_lshlrev_b32_e32 v38, 16, v158
	v_lshlrev_b32_e32 v34, 16, v156
	v_and_b32_e32 v35, 0xffff0000, v156
	v_and_b32_e32 v39, 0xffff0000, v158
	v_lshlrev_b32_e32 v40, 16, v159
	v_and_b32_e32 v41, 0xffff0000, v159
	v_lshl_add_u64 v[32:33], v[222:223], 0, v[220:221]
	v_pk_fma_f32 v[30:31], v[30:31], v[142:143], v[36:37]
	v_pk_fma_f32 v[28:29], v[28:29], v[140:141], v[34:35]
	v_pk_fma_f32 v[34:35], v[26:27], v[138:139], v[40:41]
	v_pk_fma_f32 v[26:27], v[24:25], v[136:137], v[38:39]
	v_cvt_pk_bf16_f32 v24, v28, v29
	v_cvt_pk_bf16_f32 v25, v30, v31
	v_lshlrev_b32_e32 v28, 16, v154
	v_cvt_pk_bf16_f32 v26, v26, v27
	v_cvt_pk_bf16_f32 v27, v34, v35
	global_store_dwordx4 v[32:33], v[24:27], off
	v_and_b32_e32 v29, 0xffff0000, v154
	v_lshlrev_b32_e32 v30, 16, v155
	v_lshlrev_b32_e32 v24, 16, v152
	v_and_b32_e32 v25, 0xffff0000, v152
	v_and_b32_e32 v31, 0xffff0000, v155
	v_lshlrev_b32_e32 v26, 16, v153
	v_and_b32_e32 v27, 0xffff0000, v153
	v_pk_fma_f32 v[20:21], v[20:21], v[132:133], v[24:25]
	v_pk_fma_f32 v[24:25], v[18:19], v[130:131], v[30:31]
	v_pk_fma_f32 v[18:19], v[16:17], v[128:129], v[28:29]
	v_pk_fma_f32 v[22:23], v[22:23], v[134:135], v[26:27]
	v_cvt_pk_bf16_f32 v16, v20, v21
	v_lshlrev_b32_e32 v20, 16, v149
	v_cvt_pk_bf16_f32 v17, v22, v23
	v_cvt_pk_bf16_f32 v18, v18, v19
	v_cvt_pk_bf16_f32 v19, v24, v25
	global_store_dwordx4 v[32:33], v[16:19], off offset:256
	v_and_b32_e32 v21, 0xffff0000, v149
	v_lshlrev_b32_e32 v22, 16, v150
	v_lshlrev_b32_e32 v18, 16, v148
	v_and_b32_e32 v19, 0xffff0000, v148
	v_and_b32_e32 v23, 0xffff0000, v150
	v_lshlrev_b32_e32 v24, 16, v151
	v_and_b32_e32 v25, 0xffff0000, v151
	v_lshl_add_u64 v[16:17], v[222:223], 0, v[218:219]
	v_pk_fma_f32 v[14:15], v[14:15], v[142:143], v[20:21]
	v_pk_fma_f32 v[12:13], v[12:13], v[140:141], v[18:19]
	v_pk_fma_f32 v[18:19], v[10:11], v[138:139], v[24:25]
	v_pk_fma_f32 v[10:11], v[8:9], v[136:137], v[22:23]
	v_cvt_pk_bf16_f32 v8, v12, v13
	v_cvt_pk_bf16_f32 v9, v14, v15
	v_lshlrev_b32_e32 v12, 16, v146
	v_cvt_pk_bf16_f32 v10, v10, v11
	v_cvt_pk_bf16_f32 v11, v18, v19
	global_store_dwordx4 v[16:17], v[8:11], off
	v_and_b32_e32 v13, 0xffff0000, v146
	v_lshlrev_b32_e32 v14, 16, v147
	v_lshlrev_b32_e32 v8, 16, v144
	v_and_b32_e32 v9, 0xffff0000, v144
	v_and_b32_e32 v15, 0xffff0000, v147
	v_lshlrev_b32_e32 v10, 16, v145
	v_and_b32_e32 v11, 0xffff0000, v145
	v_pk_fma_f32 v[4:5], v[4:5], v[132:133], v[8:9]
	v_pk_fma_f32 v[8:9], v[2:3], v[130:131], v[14:15]
	v_pk_fma_f32 v[2:3], v[0:1], v[128:129], v[12:13]
	v_pk_fma_f32 v[6:7], v[6:7], v[134:135], v[10:11]
	v_cvt_pk_bf16_f32 v0, v4, v5
	s_nop 0
	v_cvt_pk_bf16_f32 v1, v6, v7
	v_cvt_pk_bf16_f32 v2, v2, v3
	v_cvt_pk_bf16_f32 v3, v8, v9
	global_store_dwordx4 v[16:17], v[0:3], off offset:256
	s_cbranch_vccz .LBB0_891
	s_waitcnt vmcnt(0)
	s_cmpk_gt_u32 s33, 0xff
	s_cbranch_scc1 .LBB0_906
	s_barrier

; #define PG8_STAGE(bufoff, gbase, voff) do { _Pragma("unroll") for (int _i = 0; _i < 2; ++_i) \
;         __builtin_amdgcn_global_load_lds((const unsigned*)((const char*)(gbase) + (voff)[_i]), (LAS unsigned*)(lds + (bufoff) + ldsw + _i * 8192), 16, 0, 0); } while (0)
; #define PG8_LDA(dst, b, h) do { _Pragma("unroll") for (int m = 0; m < 4; ++m) _Pragma("unroll") for (int k = 0; k < 2; ++k) dst[m][k] = *(const LAS bf16x8*)(lds + PG8_SA(b, h) + aoff + m * 2048 + k * 1024); } while (0)
; #define PG8_LDB(dst, b, h) do { _Pragma("unroll") for (int n = 0; n < 2; ++n) _Pragma("unroll") for (int k = 0; k < 2; ++k) dst[n][k] = *(const LAS bf16x8*)(lds + PG8_SB(b, h) + boff + n * 2048 + k * 1024); } while (0)
; #define PG8_MMA(ai, bj, At, Bt) do { __builtin_amdgcn_s_setprio(1); _Pragma("unroll") for (int m = 0; m < 4; ++m) _Pragma("unroll") for (int n = 0; n < 2; ++n) _Pragma("unroll") for (int k = 0; k < 2; ++k) \
;         acc[ai][bj][m][n] = __builtin_amdgcn_mfma_f32_16x16x32_bf16(Bt[n][k], At[m][k], acc[ai][bj][m][n], 0, 0, 0); __builtin_amdgcn_s_setprio(0); } while (0)
; #define PG8_WAIT_L(n) asm volatile("s_waitcnt lgkmcnt(" #n ")" ::: "memory")
; template <class Epi, class Sched>
; __device__ __forceinline__ void gemm_phase(LAS unsigned char* lds, const Gemm g, const Sched& S, const Epi& E) {
;     ...
;         const bool has_next = S.next(ui + 1, nxt);
;         const char* nA = has_next ? (const char*)g.A + (size_t)nxt.pm * tstep : cA; const char* nB = has_next ? (const char*)g.Bt + (size_t)nxt.pn * tstep : cB;
;         for (int t = 0; t < nt; t += 2) {
;             const bool last = (t == nt - 2);
;             const char* a1 = cA + (size_t)(t + 1) * kstep;
;             const char* a2 = last ? nA : cA + (size_t)(t + 2) * kstep; const char* b2 = last ? nB : cB + (size_t)(t + 2) * kstep;
;             const char* a3 = a2 + kstep; const char* b3 = b2 + kstep;
;             PG8_LDB(B0, 0, 0); PG8_SCHED; PG8_LDA(At, 0, 0); PG8_STAGE(PG8_SA(1, 1), a1 + hstep, voffA);
;             PG8_WAIT_L(8); PG8_BAR; PG8_WAIT_L(0); PG8_MMA(0, 0, At, B0); PG8_BAR; PG8_SCHED;
;             PG8_LDB(B1, 0, 1); PG8_STAGE(PG8_SB(0, 0), b2, voffB);
;             PG8_BAR; PG8_WAIT_L(0); PG8_MMA(0, 1, At, B1); PG8_BAR;
;             PG8_LDA(At, 0, 1); PG8_STAGE(PG8_SA(0, 0), a2, voffA);
;             PG8_BAR; PG8_WAIT_L(0); PG8_MMA(1, 0, At, B0); PG8_BAR; PG8_SCHED;
.LBB0_1020:
	s_ashr_i32 s7, s6, 31
	v_cmp_lt_i64_e32 vcc, s[10:11], v[140:141]
	s_lshl_b64 s[10:11], s[6:7], 19
	s_add_u32 s10, s96, s10
	s_addc_u32 s11, s97, s11
	s_and_b64 s[12:13], vcc, exec
	s_cselect_b32 s7, s11, s17
	s_cselect_b32 s42, s10, s16
	s_ashr_i32 s5, s4, 31
	s_lshl_b64 s[12:13], s[4:5], 19
	s_add_u32 s12, s23, s12
	s_addc_u32 s13, s24, s13
	s_and_b64 s[20:21], vcc, exec
	s_cselect_b32 s5, s13, s19
	s_cselect_b32 s43, s12, s18
	s_add_u32 s16, s16, 0x40080
	s_addc_u32 s17, s17, 0
	s_add_u32 s44, s18, 0x100
	s_addc_u32 s45, s19, 0
	s_mov_b32 s46, -2
	ds_read_b128 v[150:153], v147
	ds_read_b128 v[154:157], v147 offset:1024
	ds_read_b128 v[158:161], v147 offset:2048
	ds_read_b128 v[162:165], v147 offset:3072
	s_add_u32 s18, s16, 0xfffc0080
	s_addc_u32 s19, s17, -1
	s_cmp_eq_u32 s46, 12
	s_cselect_b32 s21, s7, s19
	s_cselect_b32 s20, s42, s18
	s_cselect_b32 s19, s5, s45
	s_cselect_b32 s18, s43, s44
	s_add_i32 m0, s15, 0xc000
	ds_read_b128 v[166:169], v148
	ds_read_b128 v[170:173], v148 offset:1024
	ds_read_b128 v[174:177], v148 offset:2048
	ds_read_b128 v[178:181], v148 offset:3072
	ds_read_b128 v[182:185], v148 offset:4096
	ds_read_b128 v[186:189], v148 offset:5120
	ds_read_b128 v[190:193], v148 offset:6144
	ds_read_b128 v[194:197], v148 offset:7168
	global_load_lds_dwordx4 v136, s[16:17]
	s_add_i32 m0, s15, 0xe000
	s_nop 0
	global_load_lds_dwordx4 v138, s[16:17]
	s_waitcnt lgkmcnt(8)
	s_waitcnt vmcnt(8)
	s_setprio 1
	s_barrier
	s_waitcnt lgkmcnt(0)
	v_mfma_f32_16x16x32_bf16 v[124:127], v[150:153], v[166:169], 0
	v_mfma_f32_16x16x32_bf16 v[116:119], v[158:161], v[166:169], 0
	v_mfma_f32_16x16x32_bf16 v[108:111], v[150:153], v[174:177], 0
	v_mfma_f32_16x16x32_bf16 v[100:103], v[158:161], v[174:177], 0
	v_mfma_f32_16x16x32_bf16 v[92:95], v[150:153], v[182:185], 0
	v_mfma_f32_16x16x32_bf16 v[84:87], v[158:161], v[182:185], 0
	v_mfma_f32_16x16x32_bf16 v[76:79], v[150:153], v[190:193], 0
	v_mfma_f32_16x16x32_bf16 v[68:71], v[158:161], v[190:193], 0
	v_mfma_f32_16x16x32_bf16 v[124:127], v[154:157], v[170:173], v[124:127]
	v_mfma_f32_16x16x32_bf16 v[116:119], v[162:165], v[170:173], v[116:119]
	v_mfma_f32_16x16x32_bf16 v[108:111], v[154:157], v[178:181], v[108:111]
	v_mfma_f32_16x16x32_bf16 v[100:103], v[162:165], v[178:181], v[100:103]
	v_mfma_f32_16x16x32_bf16 v[92:95], v[154:157], v[186:189], v[92:95]
	v_mfma_f32_16x16x32_bf16 v[84:87], v[162:165], v[186:189], v[84:87]
	v_mfma_f32_16x16x32_bf16 v[76:79], v[154:157], v[194:197], v[76:79]
	v_mfma_f32_16x16x32_bf16 v[68:71], v[162:165], v[194:197], v[68:71]
	s_barrier
	s_setprio 0
	s_add_i32 s47, s38, s25
	s_mov_b32 m0, s47
	ds_read_b128 v[202:205], v149
	ds_read_b128 v[206:209], v149 offset:1024
	ds_read_b128 v[210:213], v149 offset:2048
	ds_read_b128 v[214:217], v149 offset:3072
	global_load_lds_dwordx4 v132, s[18:19]
	s_add_i32 m0, s47, 0x2000
	s_nop 0
	global_load_lds_dwordx4 v128, s[18:19]
	s_waitcnt vmcnt(8)
	s_setprio 1
	s_barrier
	s_waitcnt lgkmcnt(0)
	v_mfma_f32_16x16x32_bf16 v[120:123], v[202:205], v[166:169], 0
	v_mfma_f32_16x16x32_bf16 v[112:115], v[210:213], v[166:169], 0
	v_mfma_f32_16x16x32_bf16 v[104:107], v[202:205], v[174:177], 0
	v_mfma_f32_16x16x32_bf16 v[96:99], v[210:213], v[174:177], 0
	v_mfma_f32_16x16x32_bf16 v[88:91], v[202:205], v[182:185], 0
	v_mfma_f32_16x16x32_bf16 v[80:83], v[210:213], v[182:185], 0
	v_mfma_f32_16x16x32_bf16 v[72:75], v[202:205], v[190:193], 0
	v_mfma_f32_16x16x32_bf16 v[64:67], v[210:213], v[190:193], 0
	v_mfma_f32_16x16x32_bf16 v[120:123], v[206:209], v[170:173], v[120:123]
	v_mfma_f32_16x16x32_bf16 v[112:115], v[214:217], v[170:173], v[112:115]
	v_mfma_f32_16x16x32_bf16 v[104:107], v[206:209], v[178:181], v[104:107]
	v_mfma_f32_16x16x32_bf16 v[96:99], v[214:217], v[178:181], v[96:99]
	v_mfma_f32_16x16x32_bf16 v[88:91], v[206:209], v[186:189], v[88:91]
	v_mfma_f32_16x16x32_bf16 v[80:83], v[214:217], v[186:189], v[80:83]
	v_mfma_f32_16x16x32_bf16 v[72:75], v[206:209], v[194:197], v[72:75]
	v_mfma_f32_16x16x32_bf16 v[64:67], v[214:217], v[194:197], v[64:67]
	s_barrier
	s_setprio 0
	s_mov_b32 m0, s15
	v_lshl_add_u64 v[220:221], s[20:21], 0, v[134:135]
	ds_read_b128 v[166:169], v148 offset:16384
	ds_read_b128 v[170:173], v148 offset:17408
	ds_read_b128 v[174:177], v148 offset:18432
	ds_read_b128 v[178:181], v148 offset:19456
	ds_read_b128 v[182:185], v148 offset:20480
	ds_read_b128 v[186:189], v148 offset:21504
	ds_read_b128 v[190:193], v148 offset:22528
	ds_read_b128 v[194:197], v148 offset:23552
	global_load_lds_dwordx4 v134, s[20:21]
	v_lshl_add_u64 v[222:223], s[20:21], 0, v[130:131]
	s_mov_b32 m0, s28
	s_nop 0
	global_load_lds_dwordx4 v130, s[20:21]
	s_setprio 1
	s_barrier
	s_waitcnt lgkmcnt(0)
	v_mfma_f32_16x16x32_bf16 v[60:63], v[150:153], v[166:169], 0
	v_mfma_f32_16x16x32_bf16 v[56:59], v[158:161], v[166:169], 0
	v_mfma_f32_16x16x32_bf16 v[44:47], v[150:153], v[174:177], 0
	v_mfma_f32_16x16x32_bf16 v[40:43], v[158:161], v[174:177], 0
	v_mfma_f32_16x16x32_bf16 v[28:31], v[150:153], v[182:185], 0
	v_mfma_f32_16x16x32_bf16 v[24:27], v[158:161], v[182:185], 0
	v_mfma_f32_16x16x32_bf16 v[12:15], v[150:153], v[190:193], 0
	v_mfma_f32_16x16x32_bf16 v[8:11], v[158:161], v[190:193], 0
	v_mfma_f32_16x16x32_bf16 v[60:63], v[154:157], v[170:173], v[60:63]
	v_mfma_f32_16x16x32_bf16 v[56:59], v[162:165], v[170:173], v[56:59]
	v_mfma_f32_16x16x32_bf16 v[44:47], v[154:157], v[178:181], v[44:47]
	v_mfma_f32_16x16x32_bf16 v[40:43], v[162:165], v[178:181], v[40:43]
	v_mfma_f32_16x16x32_bf16 v[28:31], v[154:157], v[186:189], v[28:31]
	v_mfma_f32_16x16x32_bf16 v[24:27], v[162:165], v[186:189], v[24:27]
	v_mfma_f32_16x16x32_bf16 v[12:15], v[154:157], v[194:197], v[12:15]
	v_mfma_f32_16x16x32_bf16 v[8:11], v[162:165], v[194:197], v[8:11]
	s_barrier
; #define PG8_STAGE(bufoff, gbase, voff) do { _Pragma("unroll") for (int _i = 0; _i < 2; ++_i) \
;         __builtin_amdgcn_global_load_lds((const unsigned*)((const char*)(gbase) + (voff)[_i]), (LAS unsigned*)(lds + (bufoff) + ldsw + _i * 8192), 16, 0, 0); } while (0)
; #define PG8_LDA(dst, b, h) do { _Pragma("unroll") for (int m = 0; m < 4; ++m) _Pragma("unroll") for (int k = 0; k < 2; ++k) dst[m][k] = *(const LAS bf16x8*)(lds + PG8_SA(b, h) + aoff + m * 2048 + k * 1024); } while (0)
; #define PG8_LDB(dst, b, h) do { _Pragma("unroll") for (int n = 0; n < 2; ++n) _Pragma("unroll") for (int k = 0; k < 2; ++k) dst[n][k] = *(const LAS bf16x8*)(lds + PG8_SB(b, h) + boff + n * 2048 + k * 1024); } while (0)
; #define PG8_MMA(ai, bj, At, Bt) do { __builtin_amdgcn_s_setprio(1); _Pragma("unroll") for (int m = 0; m < 4; ++m) _Pragma("unroll") for (int n = 0; n < 2; ++n) _Pragma("unroll") for (int k = 0; k < 2; ++k) \
;         acc[ai][bj][m][n] = __builtin_amdgcn_mfma_f32_16x16x32_bf16(Bt[n][k], At[m][k], acc[ai][bj][m][n], 0, 0, 0); __builtin_amdgcn_s_setprio(0); } while (0)
; #define PG8_WAIT_V(n) asm volatile("s_waitcnt vmcnt(" #n ")" ::: "memory")
; #define PG8_WAIT_L(n) asm volatile("s_waitcnt lgkmcnt(" #n ")" ::: "memory")
; #define PG8_BAR __builtin_amdgcn_s_barrier()
; #define PG8_SCHED __builtin_amdgcn_sched_barrier(0)
; template <class Epi, class Sched>
; __device__ __forceinline__ void gemm_phase(LAS unsigned char* lds, const Gemm g, const Sched& S, const Epi& E) {
;     ...
;             PG8_WAIT_V(6); PG8_BAR; PG8_MMA(1, 1, At, B1); PG8_BAR;
;             PG8_LDB(B0, 1, 0); PG8_SCHED; PG8_LDA(At, 1, 0); PG8_STAGE(PG8_SA(0, 1), a2 + hstep, voffA);
;             PG8_WAIT_L(8); PG8_BAR; PG8_WAIT_L(0); PG8_MMA(0, 0, At, B0); PG8_BAR; PG8_SCHED;
;             PG8_LDB(B1, 1, 1); PG8_STAGE(PG8_SB(1, 0), b3, voffB);
;             PG8_BAR; PG8_WAIT_L(0); PG8_MMA(0, 1, At, B1); PG8_BAR;
;             PG8_LDA(At, 1, 1); PG8_STAGE(PG8_SA(1, 0), a3, voffA);
;             PG8_BAR; PG8_WAIT_L(0); PG8_MMA(1, 0, At, B0); PG8_BAR; PG8_SCHED;
	s_setprio 0
	s_add_u32 s48, s18, 0x40000
	s_addc_u32 s49, s19, 0
	s_add_i32 s47, s39, s25
	s_mov_b32 m0, s47
	s_nop 0
	global_load_lds_dwordx4 v132, s[48:49]
	s_add_i32 m0, s47, 0x2000
	s_nop 0
	global_load_lds_dwordx4 v128, s[48:49]
	s_add_u32 s20, s20, 0x40000
	s_addc_u32 s21, s21, 0
	s_mov_b32 m0, s29
	s_nop 0
	global_load_lds_dwordx4 v134, s[20:21]
	s_mov_b32 m0, s30
	s_nop 0
	global_load_lds_dwordx4 v130, s[20:21]
	s_waitcnt vmcnt(10)
	s_setprio 1
	s_barrier
	v_mfma_f32_16x16x32_bf16 v[52:55], v[202:205], v[166:169], 0
	v_mfma_f32_16x16x32_bf16 v[48:51], v[210:213], v[166:169], 0
	v_mfma_f32_16x16x32_bf16 v[36:39], v[202:205], v[174:177], 0
	v_mfma_f32_16x16x32_bf16 v[32:35], v[210:213], v[174:177], 0
	v_mfma_f32_16x16x32_bf16 v[20:23], v[202:205], v[182:185], 0
	v_mfma_f32_16x16x32_bf16 v[16:19], v[210:213], v[182:185], 0
	v_mfma_f32_16x16x32_bf16 v[4:7], v[202:205], v[190:193], 0
	v_mfma_f32_16x16x32_bf16 v[0:3], v[210:213], v[190:193], 0
	v_mfma_f32_16x16x32_bf16 v[52:55], v[206:209], v[170:173], v[52:55]
	v_mfma_f32_16x16x32_bf16 v[48:51], v[214:217], v[170:173], v[48:51]
	v_mfma_f32_16x16x32_bf16 v[36:39], v[206:209], v[178:181], v[36:39]
	v_mfma_f32_16x16x32_bf16 v[32:35], v[214:217], v[178:181], v[32:35]
	v_mfma_f32_16x16x32_bf16 v[20:23], v[206:209], v[186:189], v[20:23]
	v_mfma_f32_16x16x32_bf16 v[16:19], v[214:217], v[186:189], v[16:19]
	v_mfma_f32_16x16x32_bf16 v[4:7], v[206:209], v[194:197], v[4:7]
	v_mfma_f32_16x16x32_bf16 v[0:3], v[214:217], v[194:197], v[0:3]
	s_barrier
	s_setprio 0
	s_add_i32 s47, 0, 0x18000
	ds_read_b128 v[150:153], v149 offset:16384
	ds_read_b128 v[154:157], v149 offset:17408
	ds_read_b128 v[158:161], v149 offset:18432
	ds_read_b128 v[162:165], v149 offset:19456
	ds_read_b128 v[166:169], v148 offset:32768
	ds_read_b128 v[170:173], v148 offset:33792
	ds_read_b128 v[174:177], v148 offset:34816
	ds_read_b128 v[178:181], v148 offset:35840
	ds_read_b128 v[182:185], v148 offset:36864
	ds_read_b128 v[186:189], v148 offset:37888
	ds_read_b128 v[190:193], v148 offset:38912
	ds_read_b128 v[194:197], v148 offset:39936
	s_waitcnt lgkmcnt(8)
	s_waitcnt vmcnt(8)
	s_setprio 1
	s_barrier
	s_waitcnt lgkmcnt(0)
	v_mfma_f32_16x16x32_bf16 v[124:127], v[150:153], v[166:169], v[124:127]
	v_mfma_f32_16x16x32_bf16 v[116:119], v[158:161], v[166:169], v[116:119]
	v_mfma_f32_16x16x32_bf16 v[108:111], v[150:153], v[174:177], v[108:111]
	v_mfma_f32_16x16x32_bf16 v[100:103], v[158:161], v[174:177], v[100:103]
	v_mfma_f32_16x16x32_bf16 v[92:95], v[150:153], v[182:185], v[92:95]
	v_mfma_f32_16x16x32_bf16 v[84:87], v[158:161], v[182:185], v[84:87]
	v_mfma_f32_16x16x32_bf16 v[76:79], v[150:153], v[190:193], v[76:79]
	v_mfma_f32_16x16x32_bf16 v[68:71], v[158:161], v[190:193], v[68:71]
	v_mfma_f32_16x16x32_bf16 v[124:127], v[154:157], v[170:173], v[124:127]
	v_mfma_f32_16x16x32_bf16 v[116:119], v[162:165], v[170:173], v[116:119]
	v_mfma_f32_16x16x32_bf16 v[108:111], v[154:157], v[178:181], v[108:111]
	v_mfma_f32_16x16x32_bf16 v[100:103], v[162:165], v[178:181], v[100:103]
	v_mfma_f32_16x16x32_bf16 v[92:95], v[154:157], v[186:189], v[92:95]
	v_mfma_f32_16x16x32_bf16 v[84:87], v[162:165], v[186:189], v[84:87]
	v_mfma_f32_16x16x32_bf16 v[76:79], v[154:157], v[194:197], v[76:79]
	v_mfma_f32_16x16x32_bf16 v[68:71], v[162:165], v[194:197], v[68:71]
	s_barrier
	s_setprio 0
	s_add_i32 s20, 0, 0x1c000
	s_add_i32 s21, s47, s25
	s_add_u32 s0, s18, 0x80
	s_addc_u32 s1, s19, 0
	s_mov_b32 m0, s21
	ds_read_b128 v[202:205], v149 offset:32768
	ds_read_b128 v[206:209], v149 offset:33792
	ds_read_b128 v[210:213], v149 offset:34816
	ds_read_b128 v[214:217], v149 offset:35840
	global_load_lds_dwordx4 v132, s[0:1]
	s_add_i32 m0, s21, 0x2000
	s_nop 0
	global_load_lds_dwordx4 v128, s[0:1]
	s_waitcnt vmcnt(8)
	s_setprio 1
	s_barrier
	s_waitcnt lgkmcnt(0)
	v_mfma_f32_16x16x32_bf16 v[120:123], v[202:205], v[166:169], v[120:123]
	v_mfma_f32_16x16x32_bf16 v[112:115], v[210:213], v[166:169], v[112:115]
	v_mfma_f32_16x16x32_bf16 v[104:107], v[202:205], v[174:177], v[104:107]
	v_mfma_f32_16x16x32_bf16 v[96:99], v[210:213], v[174:177], v[96:99]
	v_mfma_f32_16x16x32_bf16 v[88:91], v[202:205], v[182:185], v[88:91]
	v_mfma_f32_16x16x32_bf16 v[80:83], v[210:213], v[182:185], v[80:83]
	v_mfma_f32_16x16x32_bf16 v[72:75], v[202:205], v[190:193], v[72:75]
	v_mfma_f32_16x16x32_bf16 v[64:67], v[210:213], v[190:193], v[64:67]
	v_mfma_f32_16x16x32_bf16 v[120:123], v[206:209], v[170:173], v[120:123]
	v_mfma_f32_16x16x32_bf16 v[112:115], v[214:217], v[170:173], v[112:115]
	v_mfma_f32_16x16x32_bf16 v[104:107], v[206:209], v[178:181], v[104:107]
	v_mfma_f32_16x16x32_bf16 v[96:99], v[214:217], v[178:181], v[96:99]
	v_mfma_f32_16x16x32_bf16 v[88:91], v[206:209], v[186:189], v[88:91]
	v_mfma_f32_16x16x32_bf16 v[80:83], v[214:217], v[186:189], v[80:83]
	v_mfma_f32_16x16x32_bf16 v[72:75], v[206:209], v[194:197], v[72:75]
	v_mfma_f32_16x16x32_bf16 v[64:67], v[214:217], v[194:197], v[64:67]
	s_barrier
	s_setprio 0
	s_mov_b32 m0, s35
	s_mov_b64 s[0:1], 0x80
	v_lshl_add_u64 v[198:199], v[220:221], 0, s[0:1]
	ds_read_b128 v[166:169], v148 offset:49152
	ds_read_b128 v[170:173], v148 offset:50176
	ds_read_b128 v[174:177], v148 offset:51200
	ds_read_b128 v[178:181], v148 offset:52224
	ds_read_b128 v[182:185], v148 offset:53248
	ds_read_b128 v[186:189], v148 offset:54272
	ds_read_b128 v[190:193], v148 offset:55296
	ds_read_b128 v[194:197], v148 offset:56320
	global_load_lds_dwordx4 v[198:199], off
	v_lshl_add_u64 v[198:199], v[222:223], 0, s[0:1]
	s_mov_b32 m0, s36
	s_nop 0
	global_load_lds_dwordx4 v[198:199], off
	s_setprio 1
	s_barrier
; #define PG8_STAGE(bufoff, gbase, voff) do { _Pragma("unroll") for (int _i = 0; _i < 2; ++_i) \
;         __builtin_amdgcn_global_load_lds((const unsigned*)((const char*)(gbase) + (voff)[_i]), (LAS unsigned*)(lds + (bufoff) + ldsw + _i * 8192), 16, 0, 0); } while (0)
; #define PG8_LDA(dst, b, h) do { _Pragma("unroll") for (int m = 0; m < 4; ++m) _Pragma("unroll") for (int k = 0; k < 2; ++k) dst[m][k] = *(const LAS bf16x8*)(lds + PG8_SA(b, h) + aoff + m * 2048 + k * 1024); } while (0)
; #define PG8_LDB(dst, b, h) do { _Pragma("unroll") for (int n = 0; n < 2; ++n) _Pragma("unroll") for (int k = 0; k < 2; ++k) dst[n][k] = *(const LAS bf16x8*)(lds + PG8_SB(b, h) + boff + n * 2048 + k * 1024); } while (0)
; #define PG8_MMA(ai, bj, At, Bt) do { __builtin_amdgcn_s_setprio(1); _Pragma("unroll") for (int m = 0; m < 4; ++m) _Pragma("unroll") for (int n = 0; n < 2; ++n) _Pragma("unroll") for (int k = 0; k < 2; ++k) \
;         acc[ai][bj][m][n] = __builtin_amdgcn_mfma_f32_16x16x32_bf16(Bt[n][k], At[m][k], acc[ai][bj][m][n], 0, 0, 0); __builtin_amdgcn_s_setprio(0); } while (0)
; #define PG8_WAIT_V(n) asm volatile("s_waitcnt vmcnt(" #n ")" ::: "memory")
; #define PG8_WAIT_L(n) asm volatile("s_waitcnt lgkmcnt(" #n ")" ::: "memory")
; #define PG8_BAR __builtin_amdgcn_s_barrier()
; #define PG8_SCHED __builtin_amdgcn_sched_barrier(0)
; template <class Epi, class Sched>
; __device__ __forceinline__ void gemm_phase(LAS unsigned char* lds, const Gemm g, const Sched& S, const Epi& E) {
;     ...
;         for (int t = 0; t < nt; t += 2) {
;             const bool last = (t == nt - 2);
;             const char* a1 = cA + (size_t)(t + 1) * kstep;
;             const char* a2 = last ? nA : cA + (size_t)(t + 2) * kstep; const char* b2 = last ? nB : cB + (size_t)(t + 2) * kstep;
;             const char* a3 = a2 + kstep; const char* b3 = b2 + kstep;
;             PG8_LDB(B0, 0, 0); PG8_SCHED; PG8_LDA(At, 0, 0); PG8_STAGE(PG8_SA(1, 1), a1 + hstep, voffA);
;             PG8_WAIT_L(8); PG8_BAR; PG8_WAIT_L(0); PG8_MMA(0, 0, At, B0); PG8_BAR; PG8_SCHED;
;             PG8_LDB(B1, 0, 1); PG8_STAGE(PG8_SB(0, 0), b2, voffB);
;     ...
;             PG8_BAR; PG8_WAIT_L(0); PG8_MMA(1, 0, At, B0); PG8_BAR; PG8_SCHED;
;             PG8_STAGE(PG8_SB(1, 1), b3 + hstep, voffB);
;             PG8_WAIT_V(6); PG8_BAR; PG8_MMA(1, 1, At, B1); PG8_BAR;
	s_waitcnt lgkmcnt(0)
	v_mfma_f32_16x16x32_bf16 v[60:63], v[150:153], v[166:169], v[60:63]
	v_mfma_f32_16x16x32_bf16 v[56:59], v[158:161], v[166:169], v[56:59]
	v_mfma_f32_16x16x32_bf16 v[44:47], v[150:153], v[174:177], v[44:47]
	v_mfma_f32_16x16x32_bf16 v[40:43], v[158:161], v[174:177], v[40:43]
	v_mfma_f32_16x16x32_bf16 v[28:31], v[150:153], v[182:185], v[28:31]
	v_mfma_f32_16x16x32_bf16 v[24:27], v[158:161], v[182:185], v[24:27]
	v_mfma_f32_16x16x32_bf16 v[12:15], v[150:153], v[190:193], v[12:15]
	v_mfma_f32_16x16x32_bf16 v[8:11], v[158:161], v[190:193], v[8:11]
	v_mfma_f32_16x16x32_bf16 v[60:63], v[154:157], v[170:173], v[60:63]
	v_mfma_f32_16x16x32_bf16 v[56:59], v[162:165], v[170:173], v[56:59]
	v_mfma_f32_16x16x32_bf16 v[44:47], v[154:157], v[178:181], v[44:47]
	v_mfma_f32_16x16x32_bf16 v[40:43], v[162:165], v[178:181], v[40:43]
	v_mfma_f32_16x16x32_bf16 v[28:31], v[154:157], v[186:189], v[28:31]
	v_mfma_f32_16x16x32_bf16 v[24:27], v[162:165], v[186:189], v[24:27]
	v_mfma_f32_16x16x32_bf16 v[12:15], v[154:157], v[194:197], v[12:15]
	v_mfma_f32_16x16x32_bf16 v[8:11], v[162:165], v[194:197], v[8:11]
	s_barrier
	s_setprio 0
	s_add_u32 s18, s18, 0x40080
	s_addc_u32 s19, s19, 0
	s_add_i32 s20, s20, s25
	s_mov_b32 m0, s20
	s_nop 0
	global_load_lds_dwordx4 v132, s[18:19]
	s_add_i32 m0, s20, 0x2000
	s_nop 0
	global_load_lds_dwordx4 v128, s[18:19]
	s_waitcnt vmcnt(8)
	s_setprio 1
	s_barrier
	v_mfma_f32_16x16x32_bf16 v[52:55], v[202:205], v[166:169], v[52:55]
	v_mfma_f32_16x16x32_bf16 v[48:51], v[210:213], v[166:169], v[48:51]
	v_mfma_f32_16x16x32_bf16 v[36:39], v[202:205], v[174:177], v[36:39]
	v_mfma_f32_16x16x32_bf16 v[32:35], v[210:213], v[174:177], v[32:35]
	v_mfma_f32_16x16x32_bf16 v[20:23], v[202:205], v[182:185], v[20:23]
	v_mfma_f32_16x16x32_bf16 v[16:19], v[210:213], v[182:185], v[16:19]
	v_mfma_f32_16x16x32_bf16 v[4:7], v[202:205], v[190:193], v[4:7]
	v_mfma_f32_16x16x32_bf16 v[0:3], v[210:213], v[190:193], v[0:3]
	v_mfma_f32_16x16x32_bf16 v[52:55], v[206:209], v[170:173], v[52:55]
	v_mfma_f32_16x16x32_bf16 v[48:51], v[214:217], v[170:173], v[48:51]
	v_mfma_f32_16x16x32_bf16 v[36:39], v[206:209], v[178:181], v[36:39]
	v_mfma_f32_16x16x32_bf16 v[32:35], v[214:217], v[178:181], v[32:35]
	v_mfma_f32_16x16x32_bf16 v[20:23], v[206:209], v[186:189], v[20:23]
	v_mfma_f32_16x16x32_bf16 v[16:19], v[214:217], v[186:189], v[16:19]
	v_mfma_f32_16x16x32_bf16 v[4:7], v[206:209], v[194:197], v[4:7]
	v_mfma_f32_16x16x32_bf16 v[0:3], v[214:217], v[194:197], v[0:3]
	s_barrier
	s_setprio 0
	s_add_i32 s46, s46, 2
	s_add_u32 s16, s16, 0x100
	s_addc_u32 s17, s17, 0
	s_add_u32 s44, s44, 0x100
	s_addc_u32 s45, s45, 0
	s_cmp_gt_u32 s46, 13
.LBB0_1021:
	ds_read_b128 v[150:153], v147
	ds_read_b128 v[154:157], v147 offset:1024
	ds_read_b128 v[158:161], v147 offset:2048
	ds_read_b128 v[162:165], v147 offset:3072
	s_add_u32 s18, s16, 0xfffc0080
	s_addc_u32 s19, s17, -1
	s_cmp_eq_u32 s46, 12
	s_cselect_b32 s21, s7, s19
	s_cselect_b32 s20, s42, s18
	s_cselect_b32 s19, s5, s45
	s_cselect_b32 s18, s43, s44
	s_add_i32 m0, s15, 0xc000
	ds_read_b128 v[166:169], v148
	ds_read_b128 v[170:173], v148 offset:1024
	ds_read_b128 v[174:177], v148 offset:2048
	ds_read_b128 v[178:181], v148 offset:3072
	ds_read_b128 v[182:185], v148 offset:4096
	ds_read_b128 v[186:189], v148 offset:5120
	ds_read_b128 v[190:193], v148 offset:6144
	ds_read_b128 v[194:197], v148 offset:7168
	global_load_lds_dwordx4 v136, s[16:17]
	s_add_i32 m0, s15, 0xe000
	s_nop 0
	global_load_lds_dwordx4 v138, s[16:17]
	s_waitcnt lgkmcnt(8)
	s_waitcnt vmcnt(8)
	s_setprio 1
	s_barrier
	s_waitcnt lgkmcnt(0)
	v_mfma_f32_16x16x32_bf16 v[124:127], v[150:153], v[166:169], v[124:127]
	v_mfma_f32_16x16x32_bf16 v[116:119], v[158:161], v[166:169], v[116:119]
	v_mfma_f32_16x16x32_bf16 v[108:111], v[150:153], v[174:177], v[108:111]
	v_mfma_f32_16x16x32_bf16 v[100:103], v[158:161], v[174:177], v[100:103]
	v_mfma_f32_16x16x32_bf16 v[92:95], v[150:153], v[182:185], v[92:95]
	v_mfma_f32_16x16x32_bf16 v[84:87], v[158:161], v[182:185], v[84:87]
	v_mfma_f32_16x16x32_bf16 v[76:79], v[150:153], v[190:193], v[76:79]
	v_mfma_f32_16x16x32_bf16 v[68:71], v[158:161], v[190:193], v[68:71]
	v_mfma_f32_16x16x32_bf16 v[124:127], v[154:157], v[170:173], v[124:127]
	v_mfma_f32_16x16x32_bf16 v[116:119], v[162:165], v[170:173], v[116:119]
	v_mfma_f32_16x16x32_bf16 v[108:111], v[154:157], v[178:181], v[108:111]
	v_mfma_f32_16x16x32_bf16 v[100:103], v[162:165], v[178:181], v[100:103]
	v_mfma_f32_16x16x32_bf16 v[92:95], v[154:157], v[186:189], v[92:95]
	v_mfma_f32_16x16x32_bf16 v[84:87], v[162:165], v[186:189], v[84:87]
	v_mfma_f32_16x16x32_bf16 v[76:79], v[154:157], v[194:197], v[76:79]
	v_mfma_f32_16x16x32_bf16 v[68:71], v[162:165], v[194:197], v[68:71]
	s_barrier
	s_setprio 0
	s_add_i32 s47, s38, s25
	s_mov_b32 m0, s47
	ds_read_b128 v[202:205], v149
	ds_read_b128 v[206:209], v149 offset:1024
	ds_read_b128 v[210:213], v149 offset:2048
	ds_read_b128 v[214:217], v149 offset:3072
	global_load_lds_dwordx4 v132, s[18:19]
	s_add_i32 m0, s47, 0x2000
	s_nop 0
	global_load_lds_dwordx4 v128, s[18:19]
	s_waitcnt vmcnt(8)
	s_setprio 1
	s_barrier
; #define PG8_STAGE(bufoff, gbase, voff) do { _Pragma("unroll") for (int _i = 0; _i < 2; ++_i) \
;         __builtin_amdgcn_global_load_lds((const unsigned*)((const char*)(gbase) + (voff)[_i]), (LAS unsigned*)(lds + (bufoff) + ldsw + _i * 8192), 16, 0, 0); } while (0)
; #define PG8_LDA(dst, b, h) do { _Pragma("unroll") for (int m = 0; m < 4; ++m) _Pragma("unroll") for (int k = 0; k < 2; ++k) dst[m][k] = *(const LAS bf16x8*)(lds + PG8_SA(b, h) + aoff + m * 2048 + k * 1024); } while (0)
; #define PG8_LDB(dst, b, h) do { _Pragma("unroll") for (int n = 0; n < 2; ++n) _Pragma("unroll") for (int k = 0; k < 2; ++k) dst[n][k] = *(const LAS bf16x8*)(lds + PG8_SB(b, h) + boff + n * 2048 + k * 1024); } while (0)
; #define PG8_MMA(ai, bj, At, Bt) do { __builtin_amdgcn_s_setprio(1); _Pragma("unroll") for (int m = 0; m < 4; ++m) _Pragma("unroll") for (int n = 0; n < 2; ++n) _Pragma("unroll") for (int k = 0; k < 2; ++k) \
;         acc[ai][bj][m][n] = __builtin_amdgcn_mfma_f32_16x16x32_bf16(Bt[n][k], At[m][k], acc[ai][bj][m][n], 0, 0, 0); __builtin_amdgcn_s_setprio(0); } while (0)
; #define PG8_WAIT_V(n) asm volatile("s_waitcnt vmcnt(" #n ")" ::: "memory")
; #define PG8_WAIT_L(n) asm volatile("s_waitcnt lgkmcnt(" #n ")" ::: "memory")
; #define PG8_BAR __builtin_amdgcn_s_barrier()
; #define PG8_SCHED __builtin_amdgcn_sched_barrier(0)
; template <class Epi, class Sched>
; __device__ __forceinline__ void gemm_phase(LAS unsigned char* lds, const Gemm g, const Sched& S, const Epi& E) {
;     ...
;             PG8_BAR; PG8_WAIT_L(0); PG8_MMA(0, 1, At, B1); PG8_BAR;
;             PG8_LDA(At, 0, 1); PG8_STAGE(PG8_SA(0, 0), a2, voffA);
;             PG8_BAR; PG8_WAIT_L(0); PG8_MMA(1, 0, At, B0); PG8_BAR; PG8_SCHED;
;             PG8_STAGE(PG8_SB(0, 1), b2 + hstep, voffB);
;             PG8_WAIT_V(6); PG8_BAR; PG8_MMA(1, 1, At, B1); PG8_BAR;
;             PG8_LDB(B0, 1, 0); PG8_SCHED; PG8_LDA(At, 1, 0); PG8_STAGE(PG8_SA(0, 1), a2 + hstep, voffA);
;             PG8_WAIT_L(8); PG8_BAR; PG8_WAIT_L(0); PG8_MMA(0, 0, At, B0); PG8_BAR; PG8_SCHED;
	s_waitcnt lgkmcnt(0)
	v_mfma_f32_16x16x32_bf16 v[120:123], v[202:205], v[166:169], v[120:123]
	v_mfma_f32_16x16x32_bf16 v[112:115], v[210:213], v[166:169], v[112:115]
	v_mfma_f32_16x16x32_bf16 v[104:107], v[202:205], v[174:177], v[104:107]
	v_mfma_f32_16x16x32_bf16 v[96:99], v[210:213], v[174:177], v[96:99]
	v_mfma_f32_16x16x32_bf16 v[88:91], v[202:205], v[182:185], v[88:91]
	v_mfma_f32_16x16x32_bf16 v[80:83], v[210:213], v[182:185], v[80:83]
	v_mfma_f32_16x16x32_bf16 v[72:75], v[202:205], v[190:193], v[72:75]
	v_mfma_f32_16x16x32_bf16 v[64:67], v[210:213], v[190:193], v[64:67]
	v_mfma_f32_16x16x32_bf16 v[120:123], v[206:209], v[170:173], v[120:123]
	v_mfma_f32_16x16x32_bf16 v[112:115], v[214:217], v[170:173], v[112:115]
	v_mfma_f32_16x16x32_bf16 v[104:107], v[206:209], v[178:181], v[104:107]
	v_mfma_f32_16x16x32_bf16 v[96:99], v[214:217], v[178:181], v[96:99]
	v_mfma_f32_16x16x32_bf16 v[88:91], v[206:209], v[186:189], v[88:91]
	v_mfma_f32_16x16x32_bf16 v[80:83], v[214:217], v[186:189], v[80:83]
	v_mfma_f32_16x16x32_bf16 v[72:75], v[206:209], v[194:197], v[72:75]
	v_mfma_f32_16x16x32_bf16 v[64:67], v[214:217], v[194:197], v[64:67]
	s_barrier
	s_setprio 0
	s_mov_b32 m0, s15
	v_lshl_add_u64 v[220:221], s[20:21], 0, v[134:135]
	ds_read_b128 v[166:169], v148 offset:16384
	ds_read_b128 v[170:173], v148 offset:17408
	ds_read_b128 v[174:177], v148 offset:18432
	ds_read_b128 v[178:181], v148 offset:19456
	ds_read_b128 v[182:185], v148 offset:20480
	ds_read_b128 v[186:189], v148 offset:21504
	ds_read_b128 v[190:193], v148 offset:22528
	ds_read_b128 v[194:197], v148 offset:23552
	global_load_lds_dwordx4 v134, s[20:21]
	v_lshl_add_u64 v[222:223], s[20:21], 0, v[130:131]
	s_mov_b32 m0, s28
	s_nop 0
	global_load_lds_dwordx4 v130, s[20:21]
	s_setprio 1
	s_barrier
	s_waitcnt lgkmcnt(0)
	v_mfma_f32_16x16x32_bf16 v[60:63], v[150:153], v[166:169], v[60:63]
	v_mfma_f32_16x16x32_bf16 v[56:59], v[158:161], v[166:169], v[56:59]
	v_mfma_f32_16x16x32_bf16 v[44:47], v[150:153], v[174:177], v[44:47]
	v_mfma_f32_16x16x32_bf16 v[40:43], v[158:161], v[174:177], v[40:43]
	v_mfma_f32_16x16x32_bf16 v[28:31], v[150:153], v[182:185], v[28:31]
	v_mfma_f32_16x16x32_bf16 v[24:27], v[158:161], v[182:185], v[24:27]
	v_mfma_f32_16x16x32_bf16 v[12:15], v[150:153], v[190:193], v[12:15]
	v_mfma_f32_16x16x32_bf16 v[8:11], v[158:161], v[190:193], v[8:11]
	v_mfma_f32_16x16x32_bf16 v[60:63], v[154:157], v[170:173], v[60:63]
	v_mfma_f32_16x16x32_bf16 v[56:59], v[162:165], v[170:173], v[56:59]
	v_mfma_f32_16x16x32_bf16 v[44:47], v[154:157], v[178:181], v[44:47]
	v_mfma_f32_16x16x32_bf16 v[40:43], v[162:165], v[178:181], v[40:43]
	v_mfma_f32_16x16x32_bf16 v[28:31], v[154:157], v[186:189], v[28:31]
	v_mfma_f32_16x16x32_bf16 v[24:27], v[162:165], v[186:189], v[24:27]
	v_mfma_f32_16x16x32_bf16 v[12:15], v[154:157], v[194:197], v[12:15]
	v_mfma_f32_16x16x32_bf16 v[8:11], v[162:165], v[194:197], v[8:11]
	s_barrier
	s_setprio 0
	s_add_u32 s48, s18, 0x40000
	s_addc_u32 s49, s19, 0
	s_add_i32 s47, s39, s25
	s_mov_b32 m0, s47
	s_nop 0
	global_load_lds_dwordx4 v132, s[48:49]
	s_add_i32 m0, s47, 0x2000
	s_nop 0
	global_load_lds_dwordx4 v128, s[48:49]
	s_add_u32 s20, s20, 0x40000
	s_addc_u32 s21, s21, 0
	s_mov_b32 m0, s29
	s_nop 0
	global_load_lds_dwordx4 v134, s[20:21]
	s_mov_b32 m0, s30
	s_nop 0
	global_load_lds_dwordx4 v130, s[20:21]
	s_waitcnt vmcnt(10)
	s_setprio 1
	s_barrier
	v_mfma_f32_16x16x32_bf16 v[52:55], v[202:205], v[166:169], v[52:55]
	v_mfma_f32_16x16x32_bf16 v[48:51], v[210:213], v[166:169], v[48:51]
	v_mfma_f32_16x16x32_bf16 v[36:39], v[202:205], v[174:177], v[36:39]
	v_mfma_f32_16x16x32_bf16 v[32:35], v[210:213], v[174:177], v[32:35]
	v_mfma_f32_16x16x32_bf16 v[20:23], v[202:205], v[182:185], v[20:23]
	v_mfma_f32_16x16x32_bf16 v[16:19], v[210:213], v[182:185], v[16:19]
	v_mfma_f32_16x16x32_bf16 v[4:7], v[202:205], v[190:193], v[4:7]
	v_mfma_f32_16x16x32_bf16 v[0:3], v[210:213], v[190:193], v[0:3]
	v_mfma_f32_16x16x32_bf16 v[52:55], v[206:209], v[170:173], v[52:55]
	v_mfma_f32_16x16x32_bf16 v[48:51], v[214:217], v[170:173], v[48:51]
	v_mfma_f32_16x16x32_bf16 v[36:39], v[206:209], v[178:181], v[36:39]
	v_mfma_f32_16x16x32_bf16 v[32:35], v[214:217], v[178:181], v[32:35]
	v_mfma_f32_16x16x32_bf16 v[20:23], v[206:209], v[186:189], v[20:23]
	v_mfma_f32_16x16x32_bf16 v[16:19], v[214:217], v[186:189], v[16:19]
	v_mfma_f32_16x16x32_bf16 v[4:7], v[206:209], v[194:197], v[4:7]
	v_mfma_f32_16x16x32_bf16 v[0:3], v[214:217], v[194:197], v[0:3]
	s_barrier
	s_setprio 0
	s_add_i32 s47, 0, 0x18000
	ds_read_b128 v[150:153], v149 offset:16384
	ds_read_b128 v[154:157], v149 offset:17408
	ds_read_b128 v[158:161], v149 offset:18432
	ds_read_b128 v[162:165], v149 offset:19456
	ds_read_b128 v[166:169], v148 offset:32768
	ds_read_b128 v[170:173], v148 offset:33792
	ds_read_b128 v[174:177], v148 offset:34816
	ds_read_b128 v[178:181], v148 offset:35840
	ds_read_b128 v[182:185], v148 offset:36864
	ds_read_b128 v[186:189], v148 offset:37888
	ds_read_b128 v[190:193], v148 offset:38912
	ds_read_b128 v[194:197], v148 offset:39936
	s_waitcnt lgkmcnt(8)
	s_waitcnt vmcnt(8)
	s_setprio 1
	s_barrier
; #define PG8_STAGE(bufoff, gbase, voff) do { _Pragma("unroll") for (int _i = 0; _i < 2; ++_i) \
;         __builtin_amdgcn_global_load_lds((const unsigned*)((const char*)(gbase) + (voff)[_i]), (LAS unsigned*)(lds + (bufoff) + ldsw + _i * 8192), 16, 0, 0); } while (0)
; #define PG8_LDA(dst, b, h) do { _Pragma("unroll") for (int m = 0; m < 4; ++m) _Pragma("unroll") for (int k = 0; k < 2; ++k) dst[m][k] = *(const LAS bf16x8*)(lds + PG8_SA(b, h) + aoff + m * 2048 + k * 1024); } while (0)
; #define PG8_LDB(dst, b, h) do { _Pragma("unroll") for (int n = 0; n < 2; ++n) _Pragma("unroll") for (int k = 0; k < 2; ++k) dst[n][k] = *(const LAS bf16x8*)(lds + PG8_SB(b, h) + boff + n * 2048 + k * 1024); } while (0)
; #define PG8_MMA(ai, bj, At, Bt) do { __builtin_amdgcn_s_setprio(1); _Pragma("unroll") for (int m = 0; m < 4; ++m) _Pragma("unroll") for (int n = 0; n < 2; ++n) _Pragma("unroll") for (int k = 0; k < 2; ++k) \
;         acc[ai][bj][m][n] = __builtin_amdgcn_mfma_f32_16x16x32_bf16(Bt[n][k], At[m][k], acc[ai][bj][m][n], 0, 0, 0); __builtin_amdgcn_s_setprio(0); } while (0)
; #define PG8_WAIT_V(n) asm volatile("s_waitcnt vmcnt(" #n ")" ::: "memory")
; #define PG8_WAIT_L(n) asm volatile("s_waitcnt lgkmcnt(" #n ")" ::: "memory")
; #define PG8_BAR __builtin_amdgcn_s_barrier()
; #define PG8_SCHED __builtin_amdgcn_sched_barrier(0)
; template <class Epi, class Sched>
; __device__ __forceinline__ void gemm_phase(LAS unsigned char* lds, const Gemm g, const Sched& S, const Epi& E) {
;     ...
;             PG8_WAIT_L(8); PG8_BAR; PG8_WAIT_L(0); PG8_MMA(0, 0, At, B0); PG8_BAR; PG8_SCHED;
;             PG8_LDB(B1, 1, 1); PG8_STAGE(PG8_SB(1, 0), b3, voffB);
;             PG8_BAR; PG8_WAIT_L(0); PG8_MMA(0, 1, At, B1); PG8_BAR;
;             PG8_LDA(At, 1, 1); PG8_STAGE(PG8_SA(1, 0), a3, voffA);
;             PG8_BAR; PG8_WAIT_L(0); PG8_MMA(1, 0, At, B0); PG8_BAR; PG8_SCHED;
;             PG8_STAGE(PG8_SB(1, 1), b3 + hstep, voffB);
;             PG8_WAIT_V(6); PG8_BAR; PG8_MMA(1, 1, At, B1); PG8_BAR;
	s_waitcnt lgkmcnt(0)
	v_mfma_f32_16x16x32_bf16 v[124:127], v[150:153], v[166:169], v[124:127]
	v_mfma_f32_16x16x32_bf16 v[116:119], v[158:161], v[166:169], v[116:119]
	v_mfma_f32_16x16x32_bf16 v[108:111], v[150:153], v[174:177], v[108:111]
	v_mfma_f32_16x16x32_bf16 v[100:103], v[158:161], v[174:177], v[100:103]
	v_mfma_f32_16x16x32_bf16 v[92:95], v[150:153], v[182:185], v[92:95]
	v_mfma_f32_16x16x32_bf16 v[84:87], v[158:161], v[182:185], v[84:87]
	v_mfma_f32_16x16x32_bf16 v[76:79], v[150:153], v[190:193], v[76:79]
	v_mfma_f32_16x16x32_bf16 v[68:71], v[158:161], v[190:193], v[68:71]
	v_mfma_f32_16x16x32_bf16 v[124:127], v[154:157], v[170:173], v[124:127]
	v_mfma_f32_16x16x32_bf16 v[116:119], v[162:165], v[170:173], v[116:119]
	v_mfma_f32_16x16x32_bf16 v[108:111], v[154:157], v[178:181], v[108:111]
	v_mfma_f32_16x16x32_bf16 v[100:103], v[162:165], v[178:181], v[100:103]
	v_mfma_f32_16x16x32_bf16 v[92:95], v[154:157], v[186:189], v[92:95]
	v_mfma_f32_16x16x32_bf16 v[84:87], v[162:165], v[186:189], v[84:87]
	v_mfma_f32_16x16x32_bf16 v[76:79], v[154:157], v[194:197], v[76:79]
	v_mfma_f32_16x16x32_bf16 v[68:71], v[162:165], v[194:197], v[68:71]
	s_barrier
	s_setprio 0
	s_add_i32 s20, 0, 0x1c000
	s_add_i32 s21, s47, s25
	s_add_u32 s0, s18, 0x80
	s_addc_u32 s1, s19, 0
	s_mov_b32 m0, s21
	ds_read_b128 v[202:205], v149 offset:32768
	ds_read_b128 v[206:209], v149 offset:33792
	ds_read_b128 v[210:213], v149 offset:34816
	ds_read_b128 v[214:217], v149 offset:35840
	global_load_lds_dwordx4 v132, s[0:1]
	s_add_i32 m0, s21, 0x2000
	s_nop 0
	global_load_lds_dwordx4 v128, s[0:1]
	s_waitcnt vmcnt(8)
	s_setprio 1
	s_barrier
	s_waitcnt lgkmcnt(0)
	v_mfma_f32_16x16x32_bf16 v[120:123], v[202:205], v[166:169], v[120:123]
	v_mfma_f32_16x16x32_bf16 v[112:115], v[210:213], v[166:169], v[112:115]
	v_mfma_f32_16x16x32_bf16 v[104:107], v[202:205], v[174:177], v[104:107]
	v_mfma_f32_16x16x32_bf16 v[96:99], v[210:213], v[174:177], v[96:99]
	v_mfma_f32_16x16x32_bf16 v[88:91], v[202:205], v[182:185], v[88:91]
	v_mfma_f32_16x16x32_bf16 v[80:83], v[210:213], v[182:185], v[80:83]
	v_mfma_f32_16x16x32_bf16 v[72:75], v[202:205], v[190:193], v[72:75]
	v_mfma_f32_16x16x32_bf16 v[64:67], v[210:213], v[190:193], v[64:67]
	v_mfma_f32_16x16x32_bf16 v[120:123], v[206:209], v[170:173], v[120:123]
	v_mfma_f32_16x16x32_bf16 v[112:115], v[214:217], v[170:173], v[112:115]
	v_mfma_f32_16x16x32_bf16 v[104:107], v[206:209], v[178:181], v[104:107]
	v_mfma_f32_16x16x32_bf16 v[96:99], v[214:217], v[178:181], v[96:99]
	v_mfma_f32_16x16x32_bf16 v[88:91], v[206:209], v[186:189], v[88:91]
	v_mfma_f32_16x16x32_bf16 v[80:83], v[214:217], v[186:189], v[80:83]
	v_mfma_f32_16x16x32_bf16 v[72:75], v[206:209], v[194:197], v[72:75]
	v_mfma_f32_16x16x32_bf16 v[64:67], v[214:217], v[194:197], v[64:67]
	s_barrier
	s_setprio 0
	s_mov_b32 m0, s35
	s_mov_b64 s[0:1], 0x80
	v_lshl_add_u64 v[198:199], v[220:221], 0, s[0:1]
	ds_read_b128 v[166:169], v148 offset:49152
	ds_read_b128 v[170:173], v148 offset:50176
	ds_read_b128 v[174:177], v148 offset:51200
	ds_read_b128 v[178:181], v148 offset:52224
	ds_read_b128 v[182:185], v148 offset:53248
	ds_read_b128 v[186:189], v148 offset:54272
	ds_read_b128 v[190:193], v148 offset:55296
	ds_read_b128 v[194:197], v148 offset:56320
	global_load_lds_dwordx4 v[198:199], off
	v_lshl_add_u64 v[198:199], v[222:223], 0, s[0:1]
	s_mov_b32 m0, s36
	s_nop 0
	global_load_lds_dwordx4 v[198:199], off
	s_setprio 1
	s_barrier
	s_waitcnt lgkmcnt(0)
	v_mfma_f32_16x16x32_bf16 v[60:63], v[150:153], v[166:169], v[60:63]
	v_mfma_f32_16x16x32_bf16 v[56:59], v[158:161], v[166:169], v[56:59]
	v_mfma_f32_16x16x32_bf16 v[44:47], v[150:153], v[174:177], v[44:47]
	v_mfma_f32_16x16x32_bf16 v[40:43], v[158:161], v[174:177], v[40:43]
	v_mfma_f32_16x16x32_bf16 v[28:31], v[150:153], v[182:185], v[28:31]
	v_mfma_f32_16x16x32_bf16 v[24:27], v[158:161], v[182:185], v[24:27]
	v_mfma_f32_16x16x32_bf16 v[12:15], v[150:153], v[190:193], v[12:15]
	v_mfma_f32_16x16x32_bf16 v[8:11], v[158:161], v[190:193], v[8:11]
	v_mfma_f32_16x16x32_bf16 v[60:63], v[154:157], v[170:173], v[60:63]
	v_mfma_f32_16x16x32_bf16 v[56:59], v[162:165], v[170:173], v[56:59]
	v_mfma_f32_16x16x32_bf16 v[44:47], v[154:157], v[178:181], v[44:47]
	v_mfma_f32_16x16x32_bf16 v[40:43], v[162:165], v[178:181], v[40:43]
	v_mfma_f32_16x16x32_bf16 v[28:31], v[154:157], v[186:189], v[28:31]
	v_mfma_f32_16x16x32_bf16 v[24:27], v[162:165], v[186:189], v[24:27]
	v_mfma_f32_16x16x32_bf16 v[12:15], v[154:157], v[194:197], v[12:15]
	v_mfma_f32_16x16x32_bf16 v[8:11], v[162:165], v[194:197], v[8:11]
	s_barrier
	s_setprio 0
	s_add_u32 s18, s18, 0x40080
	s_addc_u32 s19, s19, 0
	s_add_i32 s20, s20, s25
	s_mov_b32 m0, s20
	s_nop 0
	global_load_lds_dwordx4 v132, s[18:19]
	s_add_i32 m0, s20, 0x2000
	s_nop 0
	global_load_lds_dwordx4 v128, s[18:19]
	s_waitcnt vmcnt(8)
	s_setprio 1
	s_barrier
	v_mfma_f32_16x16x32_bf16 v[52:55], v[202:205], v[166:169], v[52:55]
	v_mfma_f32_16x16x32_bf16 v[48:51], v[210:213], v[166:169], v[48:51]
	v_mfma_f32_16x16x32_bf16 v[36:39], v[202:205], v[174:177], v[36:39]
	v_mfma_f32_16x16x32_bf16 v[32:35], v[210:213], v[174:177], v[32:35]
	v_mfma_f32_16x16x32_bf16 v[20:23], v[202:205], v[182:185], v[20:23]
	v_mfma_f32_16x16x32_bf16 v[16:19], v[210:213], v[182:185], v[16:19]
	v_mfma_f32_16x16x32_bf16 v[4:7], v[202:205], v[190:193], v[4:7]
	v_mfma_f32_16x16x32_bf16 v[0:3], v[210:213], v[190:193], v[0:3]
	v_mfma_f32_16x16x32_bf16 v[52:55], v[206:209], v[170:173], v[52:55]
	v_mfma_f32_16x16x32_bf16 v[48:51], v[214:217], v[170:173], v[48:51]
	v_mfma_f32_16x16x32_bf16 v[36:39], v[206:209], v[178:181], v[36:39]
	v_mfma_f32_16x16x32_bf16 v[32:35], v[214:217], v[178:181], v[32:35]
	v_mfma_f32_16x16x32_bf16 v[20:23], v[206:209], v[186:189], v[20:23]
	v_mfma_f32_16x16x32_bf16 v[16:19], v[214:217], v[186:189], v[16:19]
	v_mfma_f32_16x16x32_bf16 v[4:7], v[206:209], v[194:197], v[4:7]
	v_mfma_f32_16x16x32_bf16 v[0:3], v[214:217], v[194:197], v[0:3]
	s_setprio 0
	s_add_i32 s46, s46, 2
	s_add_u32 s16, s16, 0x100
	s_addc_u32 s17, s17, 0
	s_add_u32 s44, s44, 0x100
	s_addc_u32 s45, s45, 0
	s_cmp_gt_u32 s46, 13
	s_cbranch_scc1 .Lconc_last_g11
	s_barrier
	s_branch .LBB0_1021

; #define PG8_STAGE(bufoff, gbase, voff) do { _Pragma("unroll") for (int _i = 0; _i < 2; ++_i) \
;         __builtin_amdgcn_global_load_lds((const unsigned*)((const char*)(gbase) + (voff)[_i]), (LAS unsigned*)(lds + (bufoff) + ldsw + _i * 8192), 16, 0, 0); } while (0)
; #define PG8_LDA(dst, b, h) do { _Pragma("unroll") for (int m = 0; m < 4; ++m) _Pragma("unroll") for (int k = 0; k < 2; ++k) dst[m][k] = *(const LAS bf16x8*)(lds + PG8_SA(b, h) + aoff + m * 2048 + k * 1024); } while (0)
; #define PG8_LDB(dst, b, h) do { _Pragma("unroll") for (int n = 0; n < 2; ++n) _Pragma("unroll") for (int k = 0; k < 2; ++k) dst[n][k] = *(const LAS bf16x8*)(lds + PG8_SB(b, h) + boff + n * 2048 + k * 1024); } while (0)
; #define PG8_MMA(ai, bj, At, Bt) do { __builtin_amdgcn_s_setprio(1); _Pragma("unroll") for (int m = 0; m < 4; ++m) _Pragma("unroll") for (int n = 0; n < 2; ++n) _Pragma("unroll") for (int k = 0; k < 2; ++k) \
;         acc[ai][bj][m][n] = __builtin_amdgcn_mfma_f32_16x16x32_bf16(Bt[n][k], At[m][k], acc[ai][bj][m][n], 0, 0, 0); __builtin_amdgcn_s_setprio(0); } while (0)
; #define PG8_WAIT_V(n) asm volatile("s_waitcnt vmcnt(" #n ")" ::: "memory")
; #define PG8_WAIT_L(n) asm volatile("s_waitcnt lgkmcnt(" #n ")" ::: "memory")
; template <class Epi, class Sched>
; __device__ __forceinline__ void gemm_phase(LAS unsigned char* lds, const Gemm g, const Sched& S, const Epi& E) {
;     ...
;         for (int t = 0; t < nt; t += 2) {
;             const bool last = (t == nt - 2);
;             const char* a1 = cA + (size_t)(t + 1) * kstep;
;             const char* a2 = last ? nA : cA + (size_t)(t + 2) * kstep; const char* b2 = last ? nB : cB + (size_t)(t + 2) * kstep;
;             const char* a3 = a2 + kstep; const char* b3 = b2 + kstep;
;             PG8_LDB(B0, 0, 0); PG8_SCHED; PG8_LDA(At, 0, 0); PG8_STAGE(PG8_SA(1, 1), a1 + hstep, voffA);
;             PG8_WAIT_L(8); PG8_BAR; PG8_WAIT_L(0); PG8_MMA(0, 0, At, B0); PG8_BAR; PG8_SCHED;
;             PG8_LDB(B1, 0, 1); PG8_STAGE(PG8_SB(0, 0), b2, voffB);
;             PG8_BAR; PG8_WAIT_L(0); PG8_MMA(0, 1, At, B1); PG8_BAR;
;             PG8_LDA(At, 0, 1); PG8_STAGE(PG8_SA(0, 0), a2, voffA);
;             PG8_BAR; PG8_WAIT_L(0); PG8_MMA(1, 0, At, B0); PG8_BAR; PG8_SCHED;
;             PG8_STAGE(PG8_SB(0, 1), b2 + hstep, voffB);
;             PG8_WAIT_V(6); PG8_BAR; PG8_MMA(1, 1, At, B1); PG8_BAR;
.LBB0_1096:
	s_add_u32 s54, s24, 0x100
	s_addc_u32 s55, s25, 0
	s_mov_b32 s56, -2
	ds_read_b128 v[128:131], v241
	ds_read_b128 v[132:135], v241 offset:1024
	ds_read_b128 v[136:139], v241 offset:2048
	ds_read_b128 v[140:143], v241 offset:3072
	s_add_u32 s24, s22, 0x100
	s_addc_u32 s25, s23, 0
	s_cmp_eq_u32 s56, 40
	s_cselect_b32 s29, s5, s25
	s_cselect_b32 s28, s4, s24
	s_cselect_b32 s27, s7, s55
	s_cselect_b32 s26, s6, s54
	v_lshl_add_u64 v[176:177], s[22:23], 0, v[196:197]
	s_add_i32 m0, s35, 0xc000
	ds_read_b128 v[144:147], v242
	ds_read_b128 v[148:151], v242 offset:1024
	ds_read_b128 v[152:155], v242 offset:2048
	ds_read_b128 v[156:159], v242 offset:3072
	ds_read_b128 v[160:163], v242 offset:4096
	ds_read_b128 v[164:167], v242 offset:5120
	ds_read_b128 v[168:171], v242 offset:6144
	ds_read_b128 v[172:175], v242 offset:7168
	global_load_lds_dwordx4 v[176:177], off
	v_lshl_add_u64 v[176:177], s[22:23], 0, v[198:199]
	s_add_i32 m0, s35, 0xe000
	s_nop 0
	global_load_lds_dwordx4 v[176:177], off
	s_waitcnt lgkmcnt(8)
	s_waitcnt vmcnt(8)
	s_setprio 1
	s_barrier
	s_waitcnt lgkmcnt(0)
	v_mfma_f32_16x16x32_bf16 v[124:127], v[128:131], v[144:147], 0
	v_mfma_f32_16x16x32_bf16 v[120:123], v[136:139], v[144:147], 0
	v_mfma_f32_16x16x32_bf16 v[108:111], v[128:131], v[152:155], 0
	v_mfma_f32_16x16x32_bf16 v[104:107], v[136:139], v[152:155], 0
	v_mfma_f32_16x16x32_bf16 v[92:95], v[128:131], v[160:163], 0
	v_mfma_f32_16x16x32_bf16 v[88:91], v[136:139], v[160:163], 0
	v_mfma_f32_16x16x32_bf16 v[76:79], v[128:131], v[168:171], 0
	v_mfma_f32_16x16x32_bf16 v[72:75], v[136:139], v[168:171], 0
	v_mfma_f32_16x16x32_bf16 v[124:127], v[132:135], v[148:151], v[124:127]
	v_mfma_f32_16x16x32_bf16 v[120:123], v[140:143], v[148:151], v[120:123]
	v_mfma_f32_16x16x32_bf16 v[108:111], v[132:135], v[156:159], v[108:111]
	v_mfma_f32_16x16x32_bf16 v[104:107], v[140:143], v[156:159], v[104:107]
	v_mfma_f32_16x16x32_bf16 v[92:95], v[132:135], v[164:167], v[92:95]
	v_mfma_f32_16x16x32_bf16 v[88:91], v[140:143], v[164:167], v[88:91]
	v_mfma_f32_16x16x32_bf16 v[76:79], v[132:135], v[172:175], v[76:79]
	v_mfma_f32_16x16x32_bf16 v[72:75], v[140:143], v[172:175], v[72:75]
	s_barrier
	s_setprio 0
	s_add_i32 s22, s48, s34
	s_mov_b32 m0, s22
	ds_read_b128 v[176:179], v243
	ds_read_b128 v[180:183], v243 offset:1024
	ds_read_b128 v[184:187], v243 offset:2048
	ds_read_b128 v[206:209], v243 offset:3072
	global_load_lds_dwordx4 v190, s[26:27]
	s_add_i32 m0, s22, 0x2000
	s_nop 0
	global_load_lds_dwordx4 v194, s[26:27]
	s_waitcnt vmcnt(8)
	s_setprio 1
	s_barrier
	s_waitcnt lgkmcnt(0)
	v_mfma_f32_16x16x32_bf16 v[116:119], v[176:179], v[144:147], 0
	v_mfma_f32_16x16x32_bf16 v[112:115], v[184:187], v[144:147], 0
	v_mfma_f32_16x16x32_bf16 v[100:103], v[176:179], v[152:155], 0
	v_mfma_f32_16x16x32_bf16 v[96:99], v[184:187], v[152:155], 0
	v_mfma_f32_16x16x32_bf16 v[84:87], v[176:179], v[160:163], 0
	v_mfma_f32_16x16x32_bf16 v[80:83], v[184:187], v[160:163], 0
	v_mfma_f32_16x16x32_bf16 v[68:71], v[176:179], v[168:171], 0
	v_mfma_f32_16x16x32_bf16 v[64:67], v[184:187], v[168:171], 0
	v_mfma_f32_16x16x32_bf16 v[116:119], v[180:183], v[148:151], v[116:119]
	v_mfma_f32_16x16x32_bf16 v[112:115], v[206:209], v[148:151], v[112:115]
	v_mfma_f32_16x16x32_bf16 v[100:103], v[180:183], v[156:159], v[100:103]
	v_mfma_f32_16x16x32_bf16 v[96:99], v[206:209], v[156:159], v[96:99]
	v_mfma_f32_16x16x32_bf16 v[84:87], v[180:183], v[164:167], v[84:87]
	v_mfma_f32_16x16x32_bf16 v[80:83], v[206:209], v[164:167], v[80:83]
	v_mfma_f32_16x16x32_bf16 v[68:71], v[180:183], v[172:175], v[68:71]
	v_mfma_f32_16x16x32_bf16 v[64:67], v[206:209], v[172:175], v[64:67]
	s_barrier
	s_setprio 0
	s_mov_b32 m0, s35
	v_lshl_add_u64 v[214:215], s[28:29], 0, v[188:189]
	ds_read_b128 v[144:147], v242 offset:16384
	ds_read_b128 v[148:151], v242 offset:17408
	ds_read_b128 v[152:155], v242 offset:18432
	ds_read_b128 v[156:159], v242 offset:19456
	ds_read_b128 v[160:163], v242 offset:20480
	ds_read_b128 v[164:167], v242 offset:21504
	ds_read_b128 v[168:171], v242 offset:22528
	ds_read_b128 v[172:175], v242 offset:23552
	global_load_lds_dwordx4 v188, s[28:29]
	v_lshl_add_u64 v[216:217], s[28:29], 0, v[192:193]
	s_mov_b32 m0, s36
	s_nop 0
	global_load_lds_dwordx4 v192, s[28:29]
	s_setprio 1
	s_barrier
	s_waitcnt lgkmcnt(0)
	v_mfma_f32_16x16x32_bf16 v[60:63], v[128:131], v[144:147], 0
	v_mfma_f32_16x16x32_bf16 v[56:59], v[136:139], v[144:147], 0
	v_mfma_f32_16x16x32_bf16 v[44:47], v[128:131], v[152:155], 0
	v_mfma_f32_16x16x32_bf16 v[40:43], v[136:139], v[152:155], 0
	v_mfma_f32_16x16x32_bf16 v[28:31], v[128:131], v[160:163], 0
	v_mfma_f32_16x16x32_bf16 v[24:27], v[136:139], v[160:163], 0
	v_mfma_f32_16x16x32_bf16 v[12:15], v[128:131], v[168:171], 0
	v_mfma_f32_16x16x32_bf16 v[8:11], v[136:139], v[168:171], 0
	v_mfma_f32_16x16x32_bf16 v[60:63], v[132:135], v[148:151], v[60:63]
	v_mfma_f32_16x16x32_bf16 v[56:59], v[140:143], v[148:151], v[56:59]
	v_mfma_f32_16x16x32_bf16 v[44:47], v[132:135], v[156:159], v[44:47]
	v_mfma_f32_16x16x32_bf16 v[40:43], v[140:143], v[156:159], v[40:43]
	v_mfma_f32_16x16x32_bf16 v[28:31], v[132:135], v[164:167], v[28:31]
	v_mfma_f32_16x16x32_bf16 v[24:27], v[140:143], v[164:167], v[24:27]
	v_mfma_f32_16x16x32_bf16 v[12:15], v[132:135], v[172:175], v[12:15]
	v_mfma_f32_16x16x32_bf16 v[8:11], v[140:143], v[172:175], v[8:11]
	s_barrier
	s_setprio 0
	s_add_u32 s22, s26, 0xb0000
	s_addc_u32 s23, s27, 0
	s_add_i32 s57, s49, s34
	s_mov_b32 m0, s57
	s_nop 0
	global_load_lds_dwordx4 v190, s[22:23]
	s_add_i32 m0, s57, 0x2000
	s_nop 0
	global_load_lds_dwordx4 v194, s[22:23]
	s_add_u32 s22, s28, 0xb0000
	s_addc_u32 s23, s29, 0
	s_mov_b32 m0, s37
	s_nop 0
	global_load_lds_dwordx4 v188, s[22:23]
	s_mov_b32 m0, s38
	s_nop 0
	global_load_lds_dwordx4 v192, s[22:23]
	s_waitcnt vmcnt(10)
	s_setprio 1
	s_barrier
; #define PG8_STAGE(bufoff, gbase, voff) do { _Pragma("unroll") for (int _i = 0; _i < 2; ++_i) \
;         __builtin_amdgcn_global_load_lds((const unsigned*)((const char*)(gbase) + (voff)[_i]), (LAS unsigned*)(lds + (bufoff) + ldsw + _i * 8192), 16, 0, 0); } while (0)
; #define PG8_LDA(dst, b, h) do { _Pragma("unroll") for (int m = 0; m < 4; ++m) _Pragma("unroll") for (int k = 0; k < 2; ++k) dst[m][k] = *(const LAS bf16x8*)(lds + PG8_SA(b, h) + aoff + m * 2048 + k * 1024); } while (0)
; #define PG8_LDB(dst, b, h) do { _Pragma("unroll") for (int n = 0; n < 2; ++n) _Pragma("unroll") for (int k = 0; k < 2; ++k) dst[n][k] = *(const LAS bf16x8*)(lds + PG8_SB(b, h) + boff + n * 2048 + k * 1024); } while (0)
; #define PG8_MMA(ai, bj, At, Bt) do { __builtin_amdgcn_s_setprio(1); _Pragma("unroll") for (int m = 0; m < 4; ++m) _Pragma("unroll") for (int n = 0; n < 2; ++n) _Pragma("unroll") for (int k = 0; k < 2; ++k) \
;         acc[ai][bj][m][n] = __builtin_amdgcn_mfma_f32_16x16x32_bf16(Bt[n][k], At[m][k], acc[ai][bj][m][n], 0, 0, 0); __builtin_amdgcn_s_setprio(0); } while (0)
; #define PG8_WAIT_V(n) asm volatile("s_waitcnt vmcnt(" #n ")" ::: "memory")
; #define PG8_WAIT_L(n) asm volatile("s_waitcnt lgkmcnt(" #n ")" ::: "memory")
; #define PG8_BAR __builtin_amdgcn_s_barrier()
; #define PG8_SCHED __builtin_amdgcn_sched_barrier(0)
; template <class Epi, class Sched>
; __device__ __forceinline__ void gemm_phase(LAS unsigned char* lds, const Gemm g, const Sched& S, const Epi& E) {
;     ...
;             PG8_WAIT_V(6); PG8_BAR; PG8_MMA(1, 1, At, B1); PG8_BAR;
;             PG8_LDB(B0, 1, 0); PG8_SCHED; PG8_LDA(At, 1, 0); PG8_STAGE(PG8_SA(0, 1), a2 + hstep, voffA);
;             PG8_WAIT_L(8); PG8_BAR; PG8_WAIT_L(0); PG8_MMA(0, 0, At, B0); PG8_BAR; PG8_SCHED;
;             PG8_LDB(B1, 1, 1); PG8_STAGE(PG8_SB(1, 0), b3, voffB);
;             PG8_BAR; PG8_WAIT_L(0); PG8_MMA(0, 1, At, B1); PG8_BAR;
;             PG8_LDA(At, 1, 1); PG8_STAGE(PG8_SA(1, 0), a3, voffA);
;             PG8_BAR; PG8_WAIT_L(0); PG8_MMA(1, 0, At, B0); PG8_BAR; PG8_SCHED;
	v_mfma_f32_16x16x32_bf16 v[52:55], v[176:179], v[144:147], 0
	v_mfma_f32_16x16x32_bf16 v[48:51], v[184:187], v[144:147], 0
	v_mfma_f32_16x16x32_bf16 v[36:39], v[176:179], v[152:155], 0
	v_mfma_f32_16x16x32_bf16 v[32:35], v[184:187], v[152:155], 0
	v_mfma_f32_16x16x32_bf16 v[20:23], v[176:179], v[160:163], 0
	v_mfma_f32_16x16x32_bf16 v[16:19], v[184:187], v[160:163], 0
	v_mfma_f32_16x16x32_bf16 v[4:7], v[176:179], v[168:171], 0
	v_mfma_f32_16x16x32_bf16 v[0:3], v[184:187], v[168:171], 0
	v_mfma_f32_16x16x32_bf16 v[52:55], v[180:183], v[148:151], v[52:55]
	v_mfma_f32_16x16x32_bf16 v[48:51], v[206:209], v[148:151], v[48:51]
	v_mfma_f32_16x16x32_bf16 v[36:39], v[180:183], v[156:159], v[36:39]
	v_mfma_f32_16x16x32_bf16 v[32:35], v[206:209], v[156:159], v[32:35]
	v_mfma_f32_16x16x32_bf16 v[20:23], v[180:183], v[164:167], v[20:23]
	v_mfma_f32_16x16x32_bf16 v[16:19], v[206:209], v[164:167], v[16:19]
	v_mfma_f32_16x16x32_bf16 v[4:7], v[180:183], v[172:175], v[4:7]
	v_mfma_f32_16x16x32_bf16 v[0:3], v[206:209], v[172:175], v[0:3]
	s_barrier
	s_setprio 0
	s_add_i32 s57, 0, 0x18000
	ds_read_b128 v[128:131], v243 offset:16384
	ds_read_b128 v[132:135], v243 offset:17408
	ds_read_b128 v[136:139], v243 offset:18432
	ds_read_b128 v[140:143], v243 offset:19456
	ds_read_b128 v[144:147], v242 offset:32768
	ds_read_b128 v[148:151], v242 offset:33792
	ds_read_b128 v[152:155], v242 offset:34816
	ds_read_b128 v[156:159], v242 offset:35840
	ds_read_b128 v[160:163], v242 offset:36864
	ds_read_b128 v[164:167], v242 offset:37888
	ds_read_b128 v[168:171], v242 offset:38912
	ds_read_b128 v[172:175], v242 offset:39936
	s_waitcnt lgkmcnt(8)
	s_waitcnt vmcnt(8)
	s_setprio 1
	s_barrier
	s_waitcnt lgkmcnt(0)
	v_mfma_f32_16x16x32_bf16 v[124:127], v[128:131], v[144:147], v[124:127]
	v_mfma_f32_16x16x32_bf16 v[120:123], v[136:139], v[144:147], v[120:123]
	v_mfma_f32_16x16x32_bf16 v[108:111], v[128:131], v[152:155], v[108:111]
	v_mfma_f32_16x16x32_bf16 v[104:107], v[136:139], v[152:155], v[104:107]
	v_mfma_f32_16x16x32_bf16 v[92:95], v[128:131], v[160:163], v[92:95]
	v_mfma_f32_16x16x32_bf16 v[88:91], v[136:139], v[160:163], v[88:91]
	v_mfma_f32_16x16x32_bf16 v[76:79], v[128:131], v[168:171], v[76:79]
	v_mfma_f32_16x16x32_bf16 v[72:75], v[136:139], v[168:171], v[72:75]
	v_mfma_f32_16x16x32_bf16 v[124:127], v[132:135], v[148:151], v[124:127]
	v_mfma_f32_16x16x32_bf16 v[120:123], v[140:143], v[148:151], v[120:123]
	v_mfma_f32_16x16x32_bf16 v[108:111], v[132:135], v[156:159], v[108:111]
	v_mfma_f32_16x16x32_bf16 v[104:107], v[140:143], v[156:159], v[104:107]
	v_mfma_f32_16x16x32_bf16 v[92:95], v[132:135], v[164:167], v[92:95]
	v_mfma_f32_16x16x32_bf16 v[88:91], v[140:143], v[164:167], v[88:91]
	v_mfma_f32_16x16x32_bf16 v[76:79], v[132:135], v[172:175], v[76:79]
	v_mfma_f32_16x16x32_bf16 v[72:75], v[140:143], v[172:175], v[72:75]
	s_barrier
	s_setprio 0
	s_add_i32 s28, 0, 0x1c000
	s_add_i32 s22, s57, s34
	s_add_u32 s0, s26, 0x80
	s_addc_u32 s1, s27, 0
	s_mov_b32 m0, s22
	ds_read_b128 v[176:179], v243 offset:32768
	ds_read_b128 v[180:183], v243 offset:33792
	ds_read_b128 v[184:187], v243 offset:34816
	ds_read_b128 v[206:209], v243 offset:35840
	global_load_lds_dwordx4 v190, s[0:1]
	s_add_i32 m0, s22, 0x2000
	s_nop 0
	global_load_lds_dwordx4 v194, s[0:1]
	s_waitcnt vmcnt(8)
	s_setprio 1
	s_barrier
	s_waitcnt lgkmcnt(0)
	v_mfma_f32_16x16x32_bf16 v[116:119], v[176:179], v[144:147], v[116:119]
	v_mfma_f32_16x16x32_bf16 v[112:115], v[184:187], v[144:147], v[112:115]
	v_mfma_f32_16x16x32_bf16 v[100:103], v[176:179], v[152:155], v[100:103]
	v_mfma_f32_16x16x32_bf16 v[96:99], v[184:187], v[152:155], v[96:99]
	v_mfma_f32_16x16x32_bf16 v[84:87], v[176:179], v[160:163], v[84:87]
	v_mfma_f32_16x16x32_bf16 v[80:83], v[184:187], v[160:163], v[80:83]
	v_mfma_f32_16x16x32_bf16 v[68:71], v[176:179], v[168:171], v[68:71]
	v_mfma_f32_16x16x32_bf16 v[64:67], v[184:187], v[168:171], v[64:67]
	v_mfma_f32_16x16x32_bf16 v[116:119], v[180:183], v[148:151], v[116:119]
	v_mfma_f32_16x16x32_bf16 v[112:115], v[206:209], v[148:151], v[112:115]
	v_mfma_f32_16x16x32_bf16 v[100:103], v[180:183], v[156:159], v[100:103]
	v_mfma_f32_16x16x32_bf16 v[96:99], v[206:209], v[156:159], v[96:99]
	v_mfma_f32_16x16x32_bf16 v[84:87], v[180:183], v[164:167], v[84:87]
	v_mfma_f32_16x16x32_bf16 v[80:83], v[206:209], v[164:167], v[80:83]
	v_mfma_f32_16x16x32_bf16 v[68:71], v[180:183], v[172:175], v[68:71]
	v_mfma_f32_16x16x32_bf16 v[64:67], v[206:209], v[172:175], v[64:67]
	s_barrier
	s_setprio 0
	s_mov_b32 m0, s44
	s_mov_b64 s[0:1], 0x80
	v_lshl_add_u64 v[210:211], v[214:215], 0, s[0:1]
	ds_read_b128 v[144:147], v242 offset:49152
	ds_read_b128 v[148:151], v242 offset:50176
	ds_read_b128 v[152:155], v242 offset:51200
	ds_read_b128 v[156:159], v242 offset:52224
	ds_read_b128 v[160:163], v242 offset:53248
	ds_read_b128 v[164:167], v242 offset:54272
	ds_read_b128 v[168:171], v242 offset:55296
	ds_read_b128 v[172:175], v242 offset:56320
	global_load_lds_dwordx4 v[210:211], off
	v_lshl_add_u64 v[210:211], v[216:217], 0, s[0:1]
	s_mov_b32 m0, s45
	s_nop 0
	global_load_lds_dwordx4 v[210:211], off
	s_setprio 1
	s_barrier
; #define PG8_STAGE(bufoff, gbase, voff) do { _Pragma("unroll") for (int _i = 0; _i < 2; ++_i) \
;         __builtin_amdgcn_global_load_lds((const unsigned*)((const char*)(gbase) + (voff)[_i]), (LAS unsigned*)(lds + (bufoff) + ldsw + _i * 8192), 16, 0, 0); } while (0)
; #define PG8_LDA(dst, b, h) do { _Pragma("unroll") for (int m = 0; m < 4; ++m) _Pragma("unroll") for (int k = 0; k < 2; ++k) dst[m][k] = *(const LAS bf16x8*)(lds + PG8_SA(b, h) + aoff + m * 2048 + k * 1024); } while (0)
; #define PG8_LDB(dst, b, h) do { _Pragma("unroll") for (int n = 0; n < 2; ++n) _Pragma("unroll") for (int k = 0; k < 2; ++k) dst[n][k] = *(const LAS bf16x8*)(lds + PG8_SB(b, h) + boff + n * 2048 + k * 1024); } while (0)
; #define PG8_WAIT_V(n) asm volatile("s_waitcnt vmcnt(" #n ")" ::: "memory")
; #define PG8_WAIT_L(n) asm volatile("s_waitcnt lgkmcnt(" #n ")" ::: "memory")
; #define PG8_BAR __builtin_amdgcn_s_barrier()
; #define PG8_SCHED __builtin_amdgcn_sched_barrier(0)
; template <class Epi, class Sched>
; __device__ __forceinline__ void gemm_phase(LAS unsigned char* lds, const Gemm g, const Sched& S, const Epi& E) {
;     ...
;             PG8_LDB(B0, 0, 0); PG8_SCHED; PG8_LDA(At, 0, 0); PG8_STAGE(PG8_SA(1, 1), a1 + hstep, voffA);
;             PG8_WAIT_L(8); PG8_BAR; PG8_WAIT_L(0); PG8_MMA(0, 0, At, B0); PG8_BAR; PG8_SCHED;
;             PG8_LDB(B1, 0, 1); PG8_STAGE(PG8_SB(0, 0), b2, voffB);
;             PG8_BAR; PG8_WAIT_L(0); PG8_MMA(0, 1, At, B1); PG8_BAR;
;             PG8_LDA(At, 0, 1); PG8_STAGE(PG8_SA(0, 0), a2, voffA);
;             PG8_BAR; PG8_WAIT_L(0); PG8_MMA(1, 0, At, B0); PG8_BAR; PG8_SCHED;
;             PG8_STAGE(PG8_SB(0, 1), b2 + hstep, voffB);
;             PG8_WAIT_V(6); PG8_BAR; PG8_MMA(1, 1, At, B1); PG8_BAR;
;             PG8_LDB(B0, 1, 0); PG8_SCHED; PG8_LDA(At, 1, 0); PG8_STAGE(PG8_SA(0, 1), a2 + hstep, voffA);
;             PG8_WAIT_L(8); PG8_BAR; PG8_WAIT_L(0); PG8_MMA(0, 0, At, B0); PG8_BAR; PG8_SCHED;
;             PG8_LDB(B1, 1, 1); PG8_STAGE(PG8_SB(1, 0), b3, voffB);
;             PG8_BAR; PG8_WAIT_L(0); PG8_MMA(0, 1, At, B1); PG8_BAR;
;             PG8_LDA(At, 1, 1); PG8_STAGE(PG8_SA(1, 0), a3, voffA);
;             PG8_BAR; PG8_WAIT_L(0); PG8_MMA(1, 0, At, B0); PG8_BAR; PG8_SCHED;
;             PG8_STAGE(PG8_SB(1, 1), b3 + hstep, voffB);
;             PG8_WAIT_V(6); PG8_BAR; PG8_MMA(1, 1, At, B1); PG8_BAR;
	s_waitcnt lgkmcnt(0)
	v_mfma_f32_16x16x32_bf16 v[60:63], v[128:131], v[144:147], v[60:63]
	v_mfma_f32_16x16x32_bf16 v[56:59], v[136:139], v[144:147], v[56:59]
	v_mfma_f32_16x16x32_bf16 v[44:47], v[128:131], v[152:155], v[44:47]
	v_mfma_f32_16x16x32_bf16 v[40:43], v[136:139], v[152:155], v[40:43]
	v_mfma_f32_16x16x32_bf16 v[28:31], v[128:131], v[160:163], v[28:31]
	v_mfma_f32_16x16x32_bf16 v[24:27], v[136:139], v[160:163], v[24:27]
	v_mfma_f32_16x16x32_bf16 v[12:15], v[128:131], v[168:171], v[12:15]
	v_mfma_f32_16x16x32_bf16 v[8:11], v[136:139], v[168:171], v[8:11]
	v_mfma_f32_16x16x32_bf16 v[60:63], v[132:135], v[148:151], v[60:63]
	v_mfma_f32_16x16x32_bf16 v[56:59], v[140:143], v[148:151], v[56:59]
	v_mfma_f32_16x16x32_bf16 v[44:47], v[132:135], v[156:159], v[44:47]
	v_mfma_f32_16x16x32_bf16 v[40:43], v[140:143], v[156:159], v[40:43]
	v_mfma_f32_16x16x32_bf16 v[28:31], v[132:135], v[164:167], v[28:31]
	v_mfma_f32_16x16x32_bf16 v[24:27], v[140:143], v[164:167], v[24:27]
	v_mfma_f32_16x16x32_bf16 v[12:15], v[132:135], v[172:175], v[12:15]
	v_mfma_f32_16x16x32_bf16 v[8:11], v[140:143], v[172:175], v[8:11]
	s_barrier
	s_setprio 0
	s_add_u32 s22, s26, 0xb0080
	s_addc_u32 s23, s27, 0
	s_add_i32 s26, s28, s34
	s_mov_b32 m0, s26
	s_nop 0
	global_load_lds_dwordx4 v190, s[22:23]
	s_add_i32 m0, s26, 0x2000
	s_nop 0
	global_load_lds_dwordx4 v194, s[22:23]
	s_waitcnt vmcnt(8)
	s_setprio 1
	s_barrier
	v_mfma_f32_16x16x32_bf16 v[52:55], v[176:179], v[144:147], v[52:55]
	v_mfma_f32_16x16x32_bf16 v[48:51], v[184:187], v[144:147], v[48:51]
	v_mfma_f32_16x16x32_bf16 v[36:39], v[176:179], v[152:155], v[36:39]
	v_mfma_f32_16x16x32_bf16 v[32:35], v[184:187], v[152:155], v[32:35]
	v_mfma_f32_16x16x32_bf16 v[20:23], v[176:179], v[160:163], v[20:23]
	v_mfma_f32_16x16x32_bf16 v[16:19], v[184:187], v[160:163], v[16:19]
	v_mfma_f32_16x16x32_bf16 v[4:7], v[176:179], v[168:171], v[4:7]
	v_mfma_f32_16x16x32_bf16 v[0:3], v[184:187], v[168:171], v[0:3]
	v_mfma_f32_16x16x32_bf16 v[52:55], v[180:183], v[148:151], v[52:55]
	v_mfma_f32_16x16x32_bf16 v[48:51], v[206:209], v[148:151], v[48:51]
	v_mfma_f32_16x16x32_bf16 v[36:39], v[180:183], v[156:159], v[36:39]
	v_mfma_f32_16x16x32_bf16 v[32:35], v[206:209], v[156:159], v[32:35]
	v_mfma_f32_16x16x32_bf16 v[20:23], v[180:183], v[164:167], v[20:23]
	v_mfma_f32_16x16x32_bf16 v[16:19], v[206:209], v[164:167], v[16:19]
	v_mfma_f32_16x16x32_bf16 v[4:7], v[180:183], v[172:175], v[4:7]
	v_mfma_f32_16x16x32_bf16 v[0:3], v[206:209], v[172:175], v[0:3]
	s_barrier
	s_setprio 0
	s_add_i32 s56, s56, 2
	s_add_u32 s54, s54, 0x100
	s_addc_u32 s55, s55, 0
	s_cmp_gt_u32 s56, 41
	s_mov_b64 s[22:23], s[24:25]
.LBB0_1097:
	ds_read_b128 v[128:131], v241
	ds_read_b128 v[132:135], v241 offset:1024
	ds_read_b128 v[136:139], v241 offset:2048
	ds_read_b128 v[140:143], v241 offset:3072
	s_add_u32 s24, s22, 0x100
	s_addc_u32 s25, s23, 0
	s_cmp_eq_u32 s56, 40
	s_cselect_b32 s29, s5, s25
	s_cselect_b32 s28, s4, s24
	s_cselect_b32 s27, s7, s55
	s_cselect_b32 s26, s6, s54
	v_lshl_add_u64 v[176:177], s[22:23], 0, v[196:197]
	s_add_i32 m0, s35, 0xc000
	ds_read_b128 v[144:147], v242
	ds_read_b128 v[148:151], v242 offset:1024
	ds_read_b128 v[152:155], v242 offset:2048
	ds_read_b128 v[156:159], v242 offset:3072
	ds_read_b128 v[160:163], v242 offset:4096
	ds_read_b128 v[164:167], v242 offset:5120
	ds_read_b128 v[168:171], v242 offset:6144
	ds_read_b128 v[172:175], v242 offset:7168
	global_load_lds_dwordx4 v[176:177], off
	v_lshl_add_u64 v[176:177], s[22:23], 0, v[198:199]
	s_add_i32 m0, s35, 0xe000
	s_nop 0
	global_load_lds_dwordx4 v[176:177], off
	s_waitcnt lgkmcnt(8)
	s_waitcnt vmcnt(8)
	s_setprio 1
	s_barrier
	s_waitcnt lgkmcnt(0)
	v_mfma_f32_16x16x32_bf16 v[124:127], v[128:131], v[144:147], v[124:127]
	v_mfma_f32_16x16x32_bf16 v[120:123], v[136:139], v[144:147], v[120:123]
	v_mfma_f32_16x16x32_bf16 v[108:111], v[128:131], v[152:155], v[108:111]
	v_mfma_f32_16x16x32_bf16 v[104:107], v[136:139], v[152:155], v[104:107]
	v_mfma_f32_16x16x32_bf16 v[92:95], v[128:131], v[160:163], v[92:95]
	v_mfma_f32_16x16x32_bf16 v[88:91], v[136:139], v[160:163], v[88:91]
	v_mfma_f32_16x16x32_bf16 v[76:79], v[128:131], v[168:171], v[76:79]
	v_mfma_f32_16x16x32_bf16 v[72:75], v[136:139], v[168:171], v[72:75]
	v_mfma_f32_16x16x32_bf16 v[124:127], v[132:135], v[148:151], v[124:127]
	v_mfma_f32_16x16x32_bf16 v[120:123], v[140:143], v[148:151], v[120:123]
	v_mfma_f32_16x16x32_bf16 v[108:111], v[132:135], v[156:159], v[108:111]
	v_mfma_f32_16x16x32_bf16 v[104:107], v[140:143], v[156:159], v[104:107]
	v_mfma_f32_16x16x32_bf16 v[92:95], v[132:135], v[164:167], v[92:95]
	v_mfma_f32_16x16x32_bf16 v[88:91], v[140:143], v[164:167], v[88:91]
	v_mfma_f32_16x16x32_bf16 v[76:79], v[132:135], v[172:175], v[76:79]
	v_mfma_f32_16x16x32_bf16 v[72:75], v[140:143], v[172:175], v[72:75]
	s_barrier
	s_setprio 0
	s_add_i32 s22, s48, s34
	s_mov_b32 m0, s22
	ds_read_b128 v[176:179], v243
	ds_read_b128 v[180:183], v243 offset:1024
	ds_read_b128 v[184:187], v243 offset:2048
	ds_read_b128 v[206:209], v243 offset:3072
	global_load_lds_dwordx4 v190, s[26:27]
	s_add_i32 m0, s22, 0x2000
	s_nop 0
	global_load_lds_dwordx4 v194, s[26:27]
	s_waitcnt vmcnt(8)
	s_setprio 1
	s_barrier
; #define PG8_STAGE(bufoff, gbase, voff) do { _Pragma("unroll") for (int _i = 0; _i < 2; ++_i) \
;         __builtin_amdgcn_global_load_lds((const unsigned*)((const char*)(gbase) + (voff)[_i]), (LAS unsigned*)(lds + (bufoff) + ldsw + _i * 8192), 16, 0, 0); } while (0)
; #define PG8_LDA(dst, b, h) do { _Pragma("unroll") for (int m = 0; m < 4; ++m) _Pragma("unroll") for (int k = 0; k < 2; ++k) dst[m][k] = *(const LAS bf16x8*)(lds + PG8_SA(b, h) + aoff + m * 2048 + k * 1024); } while (0)
; #define PG8_LDB(dst, b, h) do { _Pragma("unroll") for (int n = 0; n < 2; ++n) _Pragma("unroll") for (int k = 0; k < 2; ++k) dst[n][k] = *(const LAS bf16x8*)(lds + PG8_SB(b, h) + boff + n * 2048 + k * 1024); } while (0)
; #define PG8_MMA(ai, bj, At, Bt) do { __builtin_amdgcn_s_setprio(1); _Pragma("unroll") for (int m = 0; m < 4; ++m) _Pragma("unroll") for (int n = 0; n < 2; ++n) _Pragma("unroll") for (int k = 0; k < 2; ++k) \
;         acc[ai][bj][m][n] = __builtin_amdgcn_mfma_f32_16x16x32_bf16(Bt[n][k], At[m][k], acc[ai][bj][m][n], 0, 0, 0); __builtin_amdgcn_s_setprio(0); } while (0)
; #define PG8_WAIT_V(n) asm volatile("s_waitcnt vmcnt(" #n ")" ::: "memory")
; #define PG8_WAIT_L(n) asm volatile("s_waitcnt lgkmcnt(" #n ")" ::: "memory")
; #define PG8_BAR __builtin_amdgcn_s_barrier()
; #define PG8_SCHED __builtin_amdgcn_sched_barrier(0)
; template <class Epi, class Sched>
; __device__ __forceinline__ void gemm_phase(LAS unsigned char* lds, const Gemm g, const Sched& S, const Epi& E) {
;     ...
;             PG8_BAR; PG8_WAIT_L(0); PG8_MMA(0, 1, At, B1); PG8_BAR;
;             PG8_LDA(At, 0, 1); PG8_STAGE(PG8_SA(0, 0), a2, voffA);
;             PG8_BAR; PG8_WAIT_L(0); PG8_MMA(1, 0, At, B0); PG8_BAR; PG8_SCHED;
;             PG8_STAGE(PG8_SB(0, 1), b2 + hstep, voffB);
;             PG8_WAIT_V(6); PG8_BAR; PG8_MMA(1, 1, At, B1); PG8_BAR;
;             PG8_LDB(B0, 1, 0); PG8_SCHED; PG8_LDA(At, 1, 0); PG8_STAGE(PG8_SA(0, 1), a2 + hstep, voffA);
;             PG8_WAIT_L(8); PG8_BAR; PG8_WAIT_L(0); PG8_MMA(0, 0, At, B0); PG8_BAR; PG8_SCHED;
	s_waitcnt lgkmcnt(0)
	v_mfma_f32_16x16x32_bf16 v[116:119], v[176:179], v[144:147], v[116:119]
	v_mfma_f32_16x16x32_bf16 v[112:115], v[184:187], v[144:147], v[112:115]
	v_mfma_f32_16x16x32_bf16 v[100:103], v[176:179], v[152:155], v[100:103]
	v_mfma_f32_16x16x32_bf16 v[96:99], v[184:187], v[152:155], v[96:99]
	v_mfma_f32_16x16x32_bf16 v[84:87], v[176:179], v[160:163], v[84:87]
	v_mfma_f32_16x16x32_bf16 v[80:83], v[184:187], v[160:163], v[80:83]
	v_mfma_f32_16x16x32_bf16 v[68:71], v[176:179], v[168:171], v[68:71]
	v_mfma_f32_16x16x32_bf16 v[64:67], v[184:187], v[168:171], v[64:67]
	v_mfma_f32_16x16x32_bf16 v[116:119], v[180:183], v[148:151], v[116:119]
	v_mfma_f32_16x16x32_bf16 v[112:115], v[206:209], v[148:151], v[112:115]
	v_mfma_f32_16x16x32_bf16 v[100:103], v[180:183], v[156:159], v[100:103]
	v_mfma_f32_16x16x32_bf16 v[96:99], v[206:209], v[156:159], v[96:99]
	v_mfma_f32_16x16x32_bf16 v[84:87], v[180:183], v[164:167], v[84:87]
	v_mfma_f32_16x16x32_bf16 v[80:83], v[206:209], v[164:167], v[80:83]
	v_mfma_f32_16x16x32_bf16 v[68:71], v[180:183], v[172:175], v[68:71]
	v_mfma_f32_16x16x32_bf16 v[64:67], v[206:209], v[172:175], v[64:67]
	s_barrier
	s_setprio 0
	s_mov_b32 m0, s35
	v_lshl_add_u64 v[214:215], s[28:29], 0, v[188:189]
	ds_read_b128 v[144:147], v242 offset:16384
	ds_read_b128 v[148:151], v242 offset:17408
	ds_read_b128 v[152:155], v242 offset:18432
	ds_read_b128 v[156:159], v242 offset:19456
	ds_read_b128 v[160:163], v242 offset:20480
	ds_read_b128 v[164:167], v242 offset:21504
	ds_read_b128 v[168:171], v242 offset:22528
	ds_read_b128 v[172:175], v242 offset:23552
	global_load_lds_dwordx4 v188, s[28:29]
	v_lshl_add_u64 v[216:217], s[28:29], 0, v[192:193]
	s_mov_b32 m0, s36
	s_nop 0
	global_load_lds_dwordx4 v192, s[28:29]
	s_setprio 1
	s_barrier
	s_waitcnt lgkmcnt(0)
	v_mfma_f32_16x16x32_bf16 v[60:63], v[128:131], v[144:147], v[60:63]
	v_mfma_f32_16x16x32_bf16 v[56:59], v[136:139], v[144:147], v[56:59]
	v_mfma_f32_16x16x32_bf16 v[44:47], v[128:131], v[152:155], v[44:47]
	v_mfma_f32_16x16x32_bf16 v[40:43], v[136:139], v[152:155], v[40:43]
	v_mfma_f32_16x16x32_bf16 v[28:31], v[128:131], v[160:163], v[28:31]
	v_mfma_f32_16x16x32_bf16 v[24:27], v[136:139], v[160:163], v[24:27]
	v_mfma_f32_16x16x32_bf16 v[12:15], v[128:131], v[168:171], v[12:15]
	v_mfma_f32_16x16x32_bf16 v[8:11], v[136:139], v[168:171], v[8:11]
	v_mfma_f32_16x16x32_bf16 v[60:63], v[132:135], v[148:151], v[60:63]
	v_mfma_f32_16x16x32_bf16 v[56:59], v[140:143], v[148:151], v[56:59]
	v_mfma_f32_16x16x32_bf16 v[44:47], v[132:135], v[156:159], v[44:47]
	v_mfma_f32_16x16x32_bf16 v[40:43], v[140:143], v[156:159], v[40:43]
	v_mfma_f32_16x16x32_bf16 v[28:31], v[132:135], v[164:167], v[28:31]
	v_mfma_f32_16x16x32_bf16 v[24:27], v[140:143], v[164:167], v[24:27]
	v_mfma_f32_16x16x32_bf16 v[12:15], v[132:135], v[172:175], v[12:15]
	v_mfma_f32_16x16x32_bf16 v[8:11], v[140:143], v[172:175], v[8:11]
	s_barrier
	s_setprio 0
	s_add_u32 s22, s26, 0xb0000
	s_addc_u32 s23, s27, 0
	s_add_i32 s57, s49, s34
	s_mov_b32 m0, s57
	s_nop 0
	global_load_lds_dwordx4 v190, s[22:23]
	s_add_i32 m0, s57, 0x2000
	s_nop 0
	global_load_lds_dwordx4 v194, s[22:23]
	s_add_u32 s22, s28, 0xb0000
	s_addc_u32 s23, s29, 0
	s_mov_b32 m0, s37
	s_nop 0
	global_load_lds_dwordx4 v188, s[22:23]
	s_mov_b32 m0, s38
	s_nop 0
	global_load_lds_dwordx4 v192, s[22:23]
	s_waitcnt vmcnt(10)
	s_setprio 1
	s_barrier
	v_mfma_f32_16x16x32_bf16 v[52:55], v[176:179], v[144:147], v[52:55]
	v_mfma_f32_16x16x32_bf16 v[48:51], v[184:187], v[144:147], v[48:51]
	v_mfma_f32_16x16x32_bf16 v[36:39], v[176:179], v[152:155], v[36:39]
	v_mfma_f32_16x16x32_bf16 v[32:35], v[184:187], v[152:155], v[32:35]
	v_mfma_f32_16x16x32_bf16 v[20:23], v[176:179], v[160:163], v[20:23]
	v_mfma_f32_16x16x32_bf16 v[16:19], v[184:187], v[160:163], v[16:19]
	v_mfma_f32_16x16x32_bf16 v[4:7], v[176:179], v[168:171], v[4:7]
	v_mfma_f32_16x16x32_bf16 v[0:3], v[184:187], v[168:171], v[0:3]
	v_mfma_f32_16x16x32_bf16 v[52:55], v[180:183], v[148:151], v[52:55]
	v_mfma_f32_16x16x32_bf16 v[48:51], v[206:209], v[148:151], v[48:51]
	v_mfma_f32_16x16x32_bf16 v[36:39], v[180:183], v[156:159], v[36:39]
	v_mfma_f32_16x16x32_bf16 v[32:35], v[206:209], v[156:159], v[32:35]
	v_mfma_f32_16x16x32_bf16 v[20:23], v[180:183], v[164:167], v[20:23]
	v_mfma_f32_16x16x32_bf16 v[16:19], v[206:209], v[164:167], v[16:19]
	v_mfma_f32_16x16x32_bf16 v[4:7], v[180:183], v[172:175], v[4:7]
	v_mfma_f32_16x16x32_bf16 v[0:3], v[206:209], v[172:175], v[0:3]
	s_barrier
	s_setprio 0
	s_add_i32 s57, 0, 0x18000
	ds_read_b128 v[128:131], v243 offset:16384
	ds_read_b128 v[132:135], v243 offset:17408
	ds_read_b128 v[136:139], v243 offset:18432
	ds_read_b128 v[140:143], v243 offset:19456
	ds_read_b128 v[144:147], v242 offset:32768
	ds_read_b128 v[148:151], v242 offset:33792
	ds_read_b128 v[152:155], v242 offset:34816
	ds_read_b128 v[156:159], v242 offset:35840
	ds_read_b128 v[160:163], v242 offset:36864
	ds_read_b128 v[164:167], v242 offset:37888
	ds_read_b128 v[168:171], v242 offset:38912
	ds_read_b128 v[172:175], v242 offset:39936
	s_waitcnt lgkmcnt(8)
	s_waitcnt vmcnt(8)
	s_setprio 1
	s_barrier
; #define PG8_STAGE(bufoff, gbase, voff) do { _Pragma("unroll") for (int _i = 0; _i < 2; ++_i) \
;         __builtin_amdgcn_global_load_lds((const unsigned*)((const char*)(gbase) + (voff)[_i]), (LAS unsigned*)(lds + (bufoff) + ldsw + _i * 8192), 16, 0, 0); } while (0)
; #define PG8_LDA(dst, b, h) do { _Pragma("unroll") for (int m = 0; m < 4; ++m) _Pragma("unroll") for (int k = 0; k < 2; ++k) dst[m][k] = *(const LAS bf16x8*)(lds + PG8_SA(b, h) + aoff + m * 2048 + k * 1024); } while (0)
; #define PG8_LDB(dst, b, h) do { _Pragma("unroll") for (int n = 0; n < 2; ++n) _Pragma("unroll") for (int k = 0; k < 2; ++k) dst[n][k] = *(const LAS bf16x8*)(lds + PG8_SB(b, h) + boff + n * 2048 + k * 1024); } while (0)
; #define PG8_MMA(ai, bj, At, Bt) do { __builtin_amdgcn_s_setprio(1); _Pragma("unroll") for (int m = 0; m < 4; ++m) _Pragma("unroll") for (int n = 0; n < 2; ++n) _Pragma("unroll") for (int k = 0; k < 2; ++k) \
;         acc[ai][bj][m][n] = __builtin_amdgcn_mfma_f32_16x16x32_bf16(Bt[n][k], At[m][k], acc[ai][bj][m][n], 0, 0, 0); __builtin_amdgcn_s_setprio(0); } while (0)
; #define PG8_WAIT_V(n) asm volatile("s_waitcnt vmcnt(" #n ")" ::: "memory")
; #define PG8_WAIT_L(n) asm volatile("s_waitcnt lgkmcnt(" #n ")" ::: "memory")
; #define PG8_BAR __builtin_amdgcn_s_barrier()
; #define PG8_SCHED __builtin_amdgcn_sched_barrier(0)
; template <class Epi, class Sched>
; __device__ __forceinline__ void gemm_phase(LAS unsigned char* lds, const Gemm g, const Sched& S, const Epi& E) {
;     ...
;             PG8_WAIT_L(8); PG8_BAR; PG8_WAIT_L(0); PG8_MMA(0, 0, At, B0); PG8_BAR; PG8_SCHED;
;             PG8_LDB(B1, 1, 1); PG8_STAGE(PG8_SB(1, 0), b3, voffB);
;             PG8_BAR; PG8_WAIT_L(0); PG8_MMA(0, 1, At, B1); PG8_BAR;
;             PG8_LDA(At, 1, 1); PG8_STAGE(PG8_SA(1, 0), a3, voffA);
;             PG8_BAR; PG8_WAIT_L(0); PG8_MMA(1, 0, At, B0); PG8_BAR; PG8_SCHED;
;             PG8_STAGE(PG8_SB(1, 1), b3 + hstep, voffB);
;             PG8_WAIT_V(6); PG8_BAR; PG8_MMA(1, 1, At, B1); PG8_BAR;
	s_waitcnt lgkmcnt(0)
	v_mfma_f32_16x16x32_bf16 v[124:127], v[128:131], v[144:147], v[124:127]
	v_mfma_f32_16x16x32_bf16 v[120:123], v[136:139], v[144:147], v[120:123]
	v_mfma_f32_16x16x32_bf16 v[108:111], v[128:131], v[152:155], v[108:111]
	v_mfma_f32_16x16x32_bf16 v[104:107], v[136:139], v[152:155], v[104:107]
	v_mfma_f32_16x16x32_bf16 v[92:95], v[128:131], v[160:163], v[92:95]
	v_mfma_f32_16x16x32_bf16 v[88:91], v[136:139], v[160:163], v[88:91]
	v_mfma_f32_16x16x32_bf16 v[76:79], v[128:131], v[168:171], v[76:79]
	v_mfma_f32_16x16x32_bf16 v[72:75], v[136:139], v[168:171], v[72:75]
	v_mfma_f32_16x16x32_bf16 v[124:127], v[132:135], v[148:151], v[124:127]
	v_mfma_f32_16x16x32_bf16 v[120:123], v[140:143], v[148:151], v[120:123]
	v_mfma_f32_16x16x32_bf16 v[108:111], v[132:135], v[156:159], v[108:111]
	v_mfma_f32_16x16x32_bf16 v[104:107], v[140:143], v[156:159], v[104:107]
	v_mfma_f32_16x16x32_bf16 v[92:95], v[132:135], v[164:167], v[92:95]
	v_mfma_f32_16x16x32_bf16 v[88:91], v[140:143], v[164:167], v[88:91]
	v_mfma_f32_16x16x32_bf16 v[76:79], v[132:135], v[172:175], v[76:79]
	v_mfma_f32_16x16x32_bf16 v[72:75], v[140:143], v[172:175], v[72:75]
	s_barrier
	s_setprio 0
	s_add_i32 s28, 0, 0x1c000
	s_add_i32 s22, s57, s34
	s_add_u32 s0, s26, 0x80
	s_addc_u32 s1, s27, 0
	s_mov_b32 m0, s22
	ds_read_b128 v[176:179], v243 offset:32768
	ds_read_b128 v[180:183], v243 offset:33792
	ds_read_b128 v[184:187], v243 offset:34816
	ds_read_b128 v[206:209], v243 offset:35840
	global_load_lds_dwordx4 v190, s[0:1]
	s_add_i32 m0, s22, 0x2000
	s_nop 0
	global_load_lds_dwordx4 v194, s[0:1]
	s_waitcnt vmcnt(8)
	s_setprio 1
	s_barrier
	s_waitcnt lgkmcnt(0)
	v_mfma_f32_16x16x32_bf16 v[116:119], v[176:179], v[144:147], v[116:119]
	v_mfma_f32_16x16x32_bf16 v[112:115], v[184:187], v[144:147], v[112:115]
	v_mfma_f32_16x16x32_bf16 v[100:103], v[176:179], v[152:155], v[100:103]
	v_mfma_f32_16x16x32_bf16 v[96:99], v[184:187], v[152:155], v[96:99]
	v_mfma_f32_16x16x32_bf16 v[84:87], v[176:179], v[160:163], v[84:87]
	v_mfma_f32_16x16x32_bf16 v[80:83], v[184:187], v[160:163], v[80:83]
	v_mfma_f32_16x16x32_bf16 v[68:71], v[176:179], v[168:171], v[68:71]
	v_mfma_f32_16x16x32_bf16 v[64:67], v[184:187], v[168:171], v[64:67]
	v_mfma_f32_16x16x32_bf16 v[116:119], v[180:183], v[148:151], v[116:119]
	v_mfma_f32_16x16x32_bf16 v[112:115], v[206:209], v[148:151], v[112:115]
	v_mfma_f32_16x16x32_bf16 v[100:103], v[180:183], v[156:159], v[100:103]
	v_mfma_f32_16x16x32_bf16 v[96:99], v[206:209], v[156:159], v[96:99]
	v_mfma_f32_16x16x32_bf16 v[84:87], v[180:183], v[164:167], v[84:87]
	v_mfma_f32_16x16x32_bf16 v[80:83], v[206:209], v[164:167], v[80:83]
	v_mfma_f32_16x16x32_bf16 v[68:71], v[180:183], v[172:175], v[68:71]
	v_mfma_f32_16x16x32_bf16 v[64:67], v[206:209], v[172:175], v[64:67]
	s_barrier
	s_setprio 0
	s_mov_b32 m0, s44
	s_mov_b64 s[0:1], 0x80
	v_lshl_add_u64 v[210:211], v[214:215], 0, s[0:1]
	ds_read_b128 v[144:147], v242 offset:49152
	ds_read_b128 v[148:151], v242 offset:50176
	ds_read_b128 v[152:155], v242 offset:51200
	ds_read_b128 v[156:159], v242 offset:52224
	ds_read_b128 v[160:163], v242 offset:53248
	ds_read_b128 v[164:167], v242 offset:54272
	ds_read_b128 v[168:171], v242 offset:55296
	ds_read_b128 v[172:175], v242 offset:56320
	global_load_lds_dwordx4 v[210:211], off
	v_lshl_add_u64 v[210:211], v[216:217], 0, s[0:1]
	s_mov_b32 m0, s45
	s_nop 0
	global_load_lds_dwordx4 v[210:211], off
	s_setprio 1
	s_barrier
	s_waitcnt lgkmcnt(0)
	v_mfma_f32_16x16x32_bf16 v[60:63], v[128:131], v[144:147], v[60:63]
	v_mfma_f32_16x16x32_bf16 v[56:59], v[136:139], v[144:147], v[56:59]
	v_mfma_f32_16x16x32_bf16 v[44:47], v[128:131], v[152:155], v[44:47]
	v_mfma_f32_16x16x32_bf16 v[40:43], v[136:139], v[152:155], v[40:43]
	v_mfma_f32_16x16x32_bf16 v[28:31], v[128:131], v[160:163], v[28:31]
	v_mfma_f32_16x16x32_bf16 v[24:27], v[136:139], v[160:163], v[24:27]
	v_mfma_f32_16x16x32_bf16 v[12:15], v[128:131], v[168:171], v[12:15]
	v_mfma_f32_16x16x32_bf16 v[8:11], v[136:139], v[168:171], v[8:11]
	v_mfma_f32_16x16x32_bf16 v[60:63], v[132:135], v[148:151], v[60:63]
	v_mfma_f32_16x16x32_bf16 v[56:59], v[140:143], v[148:151], v[56:59]
	v_mfma_f32_16x16x32_bf16 v[44:47], v[132:135], v[156:159], v[44:47]
	v_mfma_f32_16x16x32_bf16 v[40:43], v[140:143], v[156:159], v[40:43]
	v_mfma_f32_16x16x32_bf16 v[28:31], v[132:135], v[164:167], v[28:31]
	v_mfma_f32_16x16x32_bf16 v[24:27], v[140:143], v[164:167], v[24:27]
	v_mfma_f32_16x16x32_bf16 v[12:15], v[132:135], v[172:175], v[12:15]
	v_mfma_f32_16x16x32_bf16 v[8:11], v[140:143], v[172:175], v[8:11]
	s_barrier
	s_setprio 0
	s_add_u32 s22, s26, 0xb0080
	s_addc_u32 s23, s27, 0
	s_add_i32 s26, s28, s34
	s_mov_b32 m0, s26
	s_nop 0
	global_load_lds_dwordx4 v190, s[22:23]
	s_add_i32 m0, s26, 0x2000
	s_nop 0
	global_load_lds_dwordx4 v194, s[22:23]
	s_waitcnt vmcnt(8)
	s_setprio 1
	s_barrier
	v_mfma_f32_16x16x32_bf16 v[52:55], v[176:179], v[144:147], v[52:55]
	v_mfma_f32_16x16x32_bf16 v[48:51], v[184:187], v[144:147], v[48:51]
	v_mfma_f32_16x16x32_bf16 v[36:39], v[176:179], v[152:155], v[36:39]
	v_mfma_f32_16x16x32_bf16 v[32:35], v[184:187], v[152:155], v[32:35]
	v_mfma_f32_16x16x32_bf16 v[20:23], v[176:179], v[160:163], v[20:23]
	v_mfma_f32_16x16x32_bf16 v[16:19], v[184:187], v[160:163], v[16:19]
	v_mfma_f32_16x16x32_bf16 v[4:7], v[176:179], v[168:171], v[4:7]
	v_mfma_f32_16x16x32_bf16 v[0:3], v[184:187], v[168:171], v[0:3]
	v_mfma_f32_16x16x32_bf16 v[52:55], v[180:183], v[148:151], v[52:55]
	v_mfma_f32_16x16x32_bf16 v[48:51], v[206:209], v[148:151], v[48:51]
	v_mfma_f32_16x16x32_bf16 v[36:39], v[180:183], v[156:159], v[36:39]
	v_mfma_f32_16x16x32_bf16 v[32:35], v[206:209], v[156:159], v[32:35]
	v_mfma_f32_16x16x32_bf16 v[20:23], v[180:183], v[164:167], v[20:23]
	v_mfma_f32_16x16x32_bf16 v[16:19], v[206:209], v[164:167], v[16:19]
	v_mfma_f32_16x16x32_bf16 v[4:7], v[180:183], v[172:175], v[4:7]
	v_mfma_f32_16x16x32_bf16 v[0:3], v[206:209], v[172:175], v[0:3]
	s_barrier
; __device__ __forceinline__ unsigned cvt_pk_bf16(float lo, float hi) { unsigned r; asm volatile("v_cvt_pk_bf16_f32 %0, %1, %2" : "=v"(r) : "v"(lo), "v"(hi)); return r; }
; __device__ __forceinline__ float bf_lo(unsigned u) { return __uint_as_float(u << 16); }
; __device__ __forceinline__ float bf_hi(unsigned u) { return __uint_as_float(u & 0xffff0000u); }
;     __device__ __forceinline__ void operator()(const AccT& acc, const Unit& u, int wr, int wc, int fr, int fq) const {
;         asm volatile("" : "+v"(fr), "+v"(fq));
;         const int rowt = u.pm * 256; const int b = rowt >> 11;
;         const bf16_t* res = res_b + (size_t)rowt * DM; bf16_t* out = hb + (size_t)rowt * DM;
;         const int col0 = u.pn * 256 + wc * 32 + 8 * fq;
;         f32x4 gv[2][2];
; #pragma unroll
;         for (int bj = 0; bj < 2; ++bj)
; #pragma unroll
;             for (int n = 0; n < 2; ++n) gv[bj][n] = *(const f32x4*)(gate + (size_t)b * NMOD + col0 + bj * 128 + n * 4) * gs;
;         u32x4 r[2][4][2];
; #pragma unroll
;         for (int ai = 0; ai < 2; ++ai)
; #pragma unroll
;             for (int m = 0; m < 4; ++m)
; #pragma unroll
;                 for (int bj = 0; bj < 2; ++bj) r[ai][m][bj] = *(const u32x4*)(res + (size_t)(wr * 64 + fr + ai * 128 + m * 16) * DM + col0 + bj * 128);
; #pragma unroll
;         for (int ai = 0; ai < 2; ++ai)
; #pragma unroll
;             for (int m = 0; m < 4; ++m)
; #pragma unroll
;                 for (int bj = 0; bj < 2; ++bj) {
;                     const u32x4 q = r[ai][m][bj];
;                     const f32x4 r0 = {bf_lo(q.x), bf_hi(q.x), bf_lo(q.y), bf_hi(q.y)}, r1 = {bf_lo(q.z), bf_hi(q.z), bf_lo(q.w), bf_hi(q.w)};
;                     const f32x4 h0 = r0 + gv[bj][0] * acc[ai][bj][m][0], h1 = r1 + gv[bj][1] * acc[ai][bj][m][1];
;                     u32x4 w; w.x = cvt_pk_bf16(h0[0], h0[1]); w.y = cvt_pk_bf16(h0[2], h0[3]); w.z = cvt_pk_bf16(h1[0], h1[1]); w.w = cvt_pk_bf16(h1[2], h1[3]);
;                     *(u32x4*)(out + (size_t)(wr * 64 + fr + ai * 128 + m * 16) * DM + col0 + bj * 128) = w;
	s_setprio 0
	s_add_i32 s56, s56, 2
	s_add_u32 s54, s54, 0x100
	s_addc_u32 s55, s55, 0
	s_cmp_gt_u32 s56, 41
	s_mov_b64 s[22:23], s[24:25]
	s_cbranch_scc0 .LBB0_1097
	s_lshl_b32 s25, s52, 8
	v_mov_b32_e32 v140, v239
	v_mov_b32_e32 v128, v238
	s_lshl_b32 s22, s53, 8
	s_ashr_i32 s24, s53, 3
	s_or_b32 s25, s25, s43
	s_ashr_i32 s23, s22, 31
	v_lshl_add_u32 v136, v128, 3, s25
	s_mul_hi_i32 s25, s24, 0x9000
	s_mul_i32 s24, s24, 0x9000
	s_add_u32 s24, s40, s24
	s_addc_u32 s25, s41, s25
	v_ashrrev_i32_e32 v137, 31, v136
	v_lshl_add_u64 v[138:139], v[136:137], 2, s[24:25]
	global_load_dwordx4 v[128:131], v[138:139], off offset:16
	global_load_dwordx4 v[132:135], v[138:139], off
	s_lshl_b64 s[22:23], s[22:23], 11
	s_add_u32 s24, s80, s22
	s_addc_u32 s25, s81, s23
	v_lshlrev_b64 v[226:227], 1, v[136:137]
	s_add_u32 s22, s96, s22
	s_addc_u32 s23, s97, s23
	s_and_b64 vcc, exec, s[2:3]
	s_mov_b32 s52, s50
	s_mov_b32 s53, s51
	s_waitcnt vmcnt(0)
	v_pk_mul_f32 v[216:217], v[130:131], 0.5 op_sel_hi:[1,0]
	v_pk_mul_f32 v[220:221], v[134:135], 0.5 op_sel_hi:[1,0]
	v_pk_mul_f32 v[218:219], v[132:133], 0.5 op_sel_hi:[1,0]
	v_pk_mul_f32 v[214:215], v[128:129], 0.5 op_sel_hi:[1,0]
	global_load_dwordx4 v[128:131], v[138:139], off offset:528
	global_load_dwordx4 v[132:135], v[138:139], off offset:512
	s_waitcnt vmcnt(0)
	v_pk_mul_f32 v[206:207], v[128:129], 0.5 op_sel_hi:[1,0]
	v_add_u32_e32 v128, s42, v140
	v_ashrrev_i32_e32 v129, 31, v128
	v_pk_mul_f32 v[208:209], v[130:131], 0.5 op_sel_hi:[1,0]
	v_lshl_add_u64 v[130:131], s[24:25], 0, v[226:227]
	v_lshlrev_b64 v[248:249], 11, v[128:129]
	v_lshl_add_u64 v[128:129], v[130:131], 0, v[248:249]
	global_load_dwordx4 v[244:247], v[128:129], off
	global_load_dwordx4 v[184:187], v[128:129], off offset:256
	v_lshl_add_u64 v[236:237], v[248:249], 0, s[8:9]
	v_lshl_add_u64 v[128:129], v[130:131], 0, v[236:237]
	global_load_dwordx4 v[180:183], v[128:129], off
	global_load_dwordx4 v[176:179], v[128:129], off offset:256
	v_lshl_add_u64 v[234:235], v[248:249], 0, s[10:11]
	v_lshl_add_u64 v[128:129], v[130:131], 0, v[234:235]
	global_load_dwordx4 v[172:175], v[128:129], off
	global_load_dwordx4 v[168:171], v[128:129], off offset:256
	v_lshl_add_u64 v[232:233], v[248:249], 0, s[12:13]
	v_lshl_add_u64 v[128:129], v[130:131], 0, v[232:233]
	global_load_dwordx4 v[164:167], v[128:129], off
	global_load_dwordx4 v[160:163], v[128:129], off offset:256
	v_lshl_add_u64 v[230:231], v[248:249], 0, s[14:15]
	v_lshl_add_u64 v[128:129], v[130:131], 0, v[230:231]
	global_load_dwordx4 v[156:159], v[128:129], off
	global_load_dwordx4 v[152:155], v[128:129], off offset:256
	v_lshl_add_u64 v[228:229], v[248:249], 0, s[16:17]
	v_lshl_add_u64 v[128:129], v[130:131], 0, v[228:229]
	global_load_dwordx4 v[148:151], v[128:129], off
	global_load_dwordx4 v[144:147], v[128:129], off offset:256
	v_lshl_add_u64 v[224:225], v[248:249], 0, s[18:19]
	v_lshl_add_u64 v[128:129], v[130:131], 0, v[224:225]
	global_load_dwordx4 v[140:143], v[128:129], off
	global_load_dwordx4 v[136:139], v[128:129], off offset:256
	v_lshl_add_u64 v[222:223], v[248:249], 0, s[20:21]
	v_lshl_add_u64 v[128:129], v[130:131], 0, v[222:223]
	v_pk_mul_f32 v[212:213], v[134:135], 0.5 op_sel_hi:[1,0]
	v_pk_mul_f32 v[210:211], v[132:133], 0.5 op_sel_hi:[1,0]
	global_load_dwordx4 v[132:135], v[128:129], off
	s_nop 0
	global_load_dwordx4 v[128:131], v[128:129], off offset:256
	v_lshl_add_u64 v[226:227], s[22:23], 0, v[226:227]
	v_lshl_add_u64 v[248:249], v[226:227], 0, v[248:249]
	s_mov_b64 s[24:25], s[6:7]
	s_mov_b64 s[22:23], s[4:5]
	s_waitcnt vmcnt(0)
	v_lshlrev_b32_e32 v250, 16, v244
	v_and_b32_e32 v251, 0xffff0000, v244
	v_lshlrev_b32_e32 v244, 16, v245
	v_and_b32_e32 v245, 0xffff0000, v245
	v_lshlrev_b32_e32 v252, 16, v246
	v_and_b32_e32 v253, 0xffff0000, v246
	v_lshlrev_b32_e32 v246, 16, v247
	v_and_b32_e32 v247, 0xffff0000, v247
	v_pk_fma_f32 v[126:127], v[126:127], v[220:221], v[244:245]
	v_pk_fma_f32 v[124:125], v[124:125], v[218:219], v[250:251]
	v_pk_fma_f32 v[244:245], v[122:123], v[216:217], v[246:247]
	v_pk_fma_f32 v[122:123], v[120:121], v[214:215], v[252:253]
	v_cvt_pk_bf16_f32 v120, v124, v125
	v_cvt_pk_bf16_f32 v121, v126, v127
	v_lshlrev_b32_e32 v124, 16, v186
	v_cvt_pk_bf16_f32 v122, v122, v123
	v_cvt_pk_bf16_f32 v123, v244, v245
	global_store_dwordx4 v[248:249], v[120:123], off
	v_and_b32_e32 v125, 0xffff0000, v186
	v_lshlrev_b32_e32 v126, 16, v187
	v_lshlrev_b32_e32 v120, 16, v184
	v_and_b32_e32 v121, 0xffff0000, v184
	v_and_b32_e32 v127, 0xffff0000, v187
	v_lshlrev_b32_e32 v122, 16, v185
	v_and_b32_e32 v123, 0xffff0000, v185
	v_pk_fma_f32 v[116:117], v[116:117], v[210:211], v[120:121]
	v_pk_fma_f32 v[120:121], v[114:115], v[208:209], v[126:127]
	v_pk_fma_f32 v[114:115], v[112:113], v[206:207], v[124:125]
	v_pk_fma_f32 v[118:119], v[118:119], v[212:213], v[122:123]
	v_cvt_pk_bf16_f32 v112, v116, v117
	v_lshlrev_b32_e32 v116, 16, v181
	v_cvt_pk_bf16_f32 v113, v118, v119
	v_cvt_pk_bf16_f32 v114, v114, v115
	v_cvt_pk_bf16_f32 v115, v120, v121
	global_store_dwordx4 v[248:249], v[112:115], off offset:256
	v_and_b32_e32 v117, 0xffff0000, v181
	v_lshlrev_b32_e32 v118, 16, v182
	v_lshlrev_b32_e32 v114, 16, v180
	v_and_b32_e32 v115, 0xffff0000, v180
	v_and_b32_e32 v119, 0xffff0000, v182
	v_lshlrev_b32_e32 v120, 16, v183
	v_and_b32_e32 v121, 0xffff0000, v183
	v_lshl_add_u64 v[112:113], v[226:227], 0, v[236:237]
	v_pk_fma_f32 v[110:111], v[110:111], v[220:221], v[116:117]
	v_pk_fma_f32 v[108:109], v[108:109], v[218:219], v[114:115]
	v_pk_fma_f32 v[114:115], v[106:107], v[216:217], v[120:121]
	v_pk_fma_f32 v[106:107], v[104:105], v[214:215], v[118:119]
	v_cvt_pk_bf16_f32 v104, v108, v109
; __device__ __forceinline__ unsigned cvt_pk_bf16(float lo, float hi) { unsigned r; asm volatile("v_cvt_pk_bf16_f32 %0, %1, %2" : "=v"(r) : "v"(lo), "v"(hi)); return r; }
; __device__ __forceinline__ float bf_lo(unsigned u) { return __uint_as_float(u << 16); }
; __device__ __forceinline__ float bf_hi(unsigned u) { return __uint_as_float(u & 0xffff0000u); }
;     __device__ __forceinline__ void operator()(const AccT& acc, const Unit& u, int wr, int wc, int fr, int fq) const {
;     ...
; #pragma unroll
;         for (int ai = 0; ai < 2; ++ai)
; #pragma unroll
;             for (int m = 0; m < 4; ++m)
; #pragma unroll
;                 for (int bj = 0; bj < 2; ++bj) {
;                     const u32x4 q = r[ai][m][bj];
;                     const f32x4 r0 = {bf_lo(q.x), bf_hi(q.x), bf_lo(q.y), bf_hi(q.y)}, r1 = {bf_lo(q.z), bf_hi(q.z), bf_lo(q.w), bf_hi(q.w)};
;                     const f32x4 h0 = r0 + gv[bj][0] * acc[ai][bj][m][0], h1 = r1 + gv[bj][1] * acc[ai][bj][m][1];
;                     u32x4 w; w.x = cvt_pk_bf16(h0[0], h0[1]); w.y = cvt_pk_bf16(h0[2], h0[3]); w.z = cvt_pk_bf16(h1[0], h1[1]); w.w = cvt_pk_bf16(h1[2], h1[3]);
;                     *(u32x4*)(out + (size_t)(wr * 64 + fr + ai * 128 + m * 16) * DM + col0 + bj * 128) = w;
	v_cvt_pk_bf16_f32 v105, v110, v111
	v_lshlrev_b32_e32 v108, 16, v178
	v_cvt_pk_bf16_f32 v106, v106, v107
	v_cvt_pk_bf16_f32 v107, v114, v115
	global_store_dwordx4 v[112:113], v[104:107], off
	v_and_b32_e32 v109, 0xffff0000, v178
	v_lshlrev_b32_e32 v110, 16, v179
	v_lshlrev_b32_e32 v104, 16, v176
	v_and_b32_e32 v105, 0xffff0000, v176
	v_and_b32_e32 v111, 0xffff0000, v179
	v_lshlrev_b32_e32 v106, 16, v177
	v_and_b32_e32 v107, 0xffff0000, v177
	v_pk_fma_f32 v[100:101], v[100:101], v[210:211], v[104:105]
	v_pk_fma_f32 v[104:105], v[98:99], v[208:209], v[110:111]
	v_pk_fma_f32 v[98:99], v[96:97], v[206:207], v[108:109]
	v_pk_fma_f32 v[102:103], v[102:103], v[212:213], v[106:107]
	v_cvt_pk_bf16_f32 v96, v100, v101
	v_lshlrev_b32_e32 v100, 16, v173
	v_cvt_pk_bf16_f32 v97, v102, v103
	v_cvt_pk_bf16_f32 v98, v98, v99
	v_cvt_pk_bf16_f32 v99, v104, v105
	global_store_dwordx4 v[112:113], v[96:99], off offset:256
	v_and_b32_e32 v101, 0xffff0000, v173
	v_lshlrev_b32_e32 v102, 16, v174
	v_lshlrev_b32_e32 v98, 16, v172
	v_and_b32_e32 v99, 0xffff0000, v172
	v_and_b32_e32 v103, 0xffff0000, v174
	v_lshlrev_b32_e32 v104, 16, v175
	v_and_b32_e32 v105, 0xffff0000, v175
	v_lshl_add_u64 v[96:97], v[226:227], 0, v[234:235]
	v_pk_fma_f32 v[94:95], v[94:95], v[220:221], v[100:101]
	v_pk_fma_f32 v[92:93], v[92:93], v[218:219], v[98:99]
	v_pk_fma_f32 v[98:99], v[90:91], v[216:217], v[104:105]
	v_pk_fma_f32 v[90:91], v[88:89], v[214:215], v[102:103]
	v_cvt_pk_bf16_f32 v88, v92, v93
	v_cvt_pk_bf16_f32 v89, v94, v95
	v_lshlrev_b32_e32 v92, 16, v170
	v_cvt_pk_bf16_f32 v90, v90, v91
	v_cvt_pk_bf16_f32 v91, v98, v99
	global_store_dwordx4 v[96:97], v[88:91], off
	v_and_b32_e32 v93, 0xffff0000, v170
	v_lshlrev_b32_e32 v94, 16, v171
	v_lshlrev_b32_e32 v88, 16, v168
	v_and_b32_e32 v89, 0xffff0000, v168
	v_and_b32_e32 v95, 0xffff0000, v171
	v_lshlrev_b32_e32 v90, 16, v169
	v_and_b32_e32 v91, 0xffff0000, v169
	v_pk_fma_f32 v[84:85], v[84:85], v[210:211], v[88:89]
	v_pk_fma_f32 v[88:89], v[82:83], v[208:209], v[94:95]
	v_pk_fma_f32 v[82:83], v[80:81], v[206:207], v[92:93]
	v_pk_fma_f32 v[86:87], v[86:87], v[212:213], v[90:91]
	v_cvt_pk_bf16_f32 v80, v84, v85
	v_lshlrev_b32_e32 v84, 16, v165
	v_cvt_pk_bf16_f32 v81, v86, v87
	v_cvt_pk_bf16_f32 v82, v82, v83
	v_cvt_pk_bf16_f32 v83, v88, v89
	global_store_dwordx4 v[96:97], v[80:83], off offset:256
	v_and_b32_e32 v85, 0xffff0000, v165
	v_lshlrev_b32_e32 v86, 16, v166
	v_lshlrev_b32_e32 v82, 16, v164
	v_and_b32_e32 v83, 0xffff0000, v164
	v_and_b32_e32 v87, 0xffff0000, v166
	v_lshlrev_b32_e32 v88, 16, v167
	v_and_b32_e32 v89, 0xffff0000, v167
	v_lshl_add_u64 v[80:81], v[226:227], 0, v[232:233]
	v_pk_fma_f32 v[78:79], v[78:79], v[220:221], v[84:85]
	v_pk_fma_f32 v[76:77], v[76:77], v[218:219], v[82:83]
	v_pk_fma_f32 v[82:83], v[74:75], v[216:217], v[88:89]
	v_pk_fma_f32 v[74:75], v[72:73], v[214:215], v[86:87]
	v_cvt_pk_bf16_f32 v72, v76, v77
	v_cvt_pk_bf16_f32 v73, v78, v79
	v_lshlrev_b32_e32 v76, 16, v162
	v_cvt_pk_bf16_f32 v74, v74, v75
	v_cvt_pk_bf16_f32 v75, v82, v83
	global_store_dwordx4 v[80:81], v[72:75], off
	v_and_b32_e32 v77, 0xffff0000, v162
	v_lshlrev_b32_e32 v78, 16, v163
	v_lshlrev_b32_e32 v72, 16, v160
	v_and_b32_e32 v73, 0xffff0000, v160
	v_and_b32_e32 v79, 0xffff0000, v163
	v_lshlrev_b32_e32 v74, 16, v161
	v_and_b32_e32 v75, 0xffff0000, v161
	v_pk_fma_f32 v[68:69], v[68:69], v[210:211], v[72:73]
	v_pk_fma_f32 v[72:73], v[66:67], v[208:209], v[78:79]
	v_pk_fma_f32 v[66:67], v[64:65], v[206:207], v[76:77]
	v_pk_fma_f32 v[70:71], v[70:71], v[212:213], v[74:75]
	v_cvt_pk_bf16_f32 v64, v68, v69
	v_lshlrev_b32_e32 v68, 16, v157
	v_cvt_pk_bf16_f32 v65, v70, v71
	v_cvt_pk_bf16_f32 v66, v66, v67
	v_cvt_pk_bf16_f32 v67, v72, v73
	global_store_dwordx4 v[80:81], v[64:67], off offset:256
	v_and_b32_e32 v69, 0xffff0000, v157
	v_lshlrev_b32_e32 v70, 16, v158
	v_lshlrev_b32_e32 v66, 16, v156
	v_and_b32_e32 v67, 0xffff0000, v156
	v_and_b32_e32 v71, 0xffff0000, v158
	v_lshlrev_b32_e32 v72, 16, v159
	v_and_b32_e32 v73, 0xffff0000, v159
	v_lshl_add_u64 v[64:65], v[226:227], 0, v[230:231]
	v_pk_fma_f32 v[62:63], v[62:63], v[220:221], v[68:69]
	v_pk_fma_f32 v[60:61], v[60:61], v[218:219], v[66:67]
	v_pk_fma_f32 v[66:67], v[58:59], v[216:217], v[72:73]
	v_pk_fma_f32 v[58:59], v[56:57], v[214:215], v[70:71]
	v_cvt_pk_bf16_f32 v56, v60, v61
	v_cvt_pk_bf16_f32 v57, v62, v63
	v_lshlrev_b32_e32 v60, 16, v154
	v_cvt_pk_bf16_f32 v58, v58, v59
	v_cvt_pk_bf16_f32 v59, v66, v67
	global_store_dwordx4 v[64:65], v[56:59], off
	v_and_b32_e32 v61, 0xffff0000, v154
	v_lshlrev_b32_e32 v62, 16, v155
	v_lshlrev_b32_e32 v56, 16, v152
	v_and_b32_e32 v57, 0xffff0000, v152
	v_and_b32_e32 v63, 0xffff0000, v155
	v_lshlrev_b32_e32 v58, 16, v153
	v_and_b32_e32 v59, 0xffff0000, v153
; __device__ __forceinline__ unsigned cvt_pk_bf16(float lo, float hi) { unsigned r; asm volatile("v_cvt_pk_bf16_f32 %0, %1, %2" : "=v"(r) : "v"(lo), "v"(hi)); return r; }
; __device__ __forceinline__ float bf_lo(unsigned u) { return __uint_as_float(u << 16); }
; __device__ __forceinline__ float bf_hi(unsigned u) { return __uint_as_float(u & 0xffff0000u); }
; #define PG8_WAIT_V(n) asm volatile("s_waitcnt vmcnt(" #n ")" ::: "memory")
; #define PG8_BAR __builtin_amdgcn_s_barrier()
; template <class Epi, class Sched>
; __device__ __forceinline__ void gemm_phase(LAS unsigned char* lds, const Gemm g, const Sched& S, const Epi& E) {
;     ...
;     PG8_WAIT_V(0);
;     if (wr == 0) PG8_BAR;
;     PG8_BAR;
;     __device__ __forceinline__ void operator()(const AccT& acc, const Unit& u, int wr, int wc, int fr, int fq) const {
;     ...
;         for (int ai = 0; ai < 2; ++ai)
; #pragma unroll
;             for (int m = 0; m < 4; ++m)
; #pragma unroll
;                 for (int bj = 0; bj < 2; ++bj) {
;                     const u32x4 q = r[ai][m][bj];
;                     const f32x4 r0 = {bf_lo(q.x), bf_hi(q.x), bf_lo(q.y), bf_hi(q.y)}, r1 = {bf_lo(q.z), bf_hi(q.z), bf_lo(q.w), bf_hi(q.w)};
;                     const f32x4 h0 = r0 + gv[bj][0] * acc[ai][bj][m][0], h1 = r1 + gv[bj][1] * acc[ai][bj][m][1];
;                     u32x4 w; w.x = cvt_pk_bf16(h0[0], h0[1]); w.y = cvt_pk_bf16(h0[2], h0[3]); w.z = cvt_pk_bf16(h1[0], h1[1]); w.w = cvt_pk_bf16(h1[2], h1[3]);
;                     *(u32x4*)(out + (size_t)(wr * 64 + fr + ai * 128 + m * 16) * DM + col0 + bj * 128) = w;
;                 }
	v_pk_fma_f32 v[52:53], v[52:53], v[210:211], v[56:57]
	v_pk_fma_f32 v[56:57], v[50:51], v[208:209], v[62:63]
	v_pk_fma_f32 v[50:51], v[48:49], v[206:207], v[60:61]
	v_pk_fma_f32 v[54:55], v[54:55], v[212:213], v[58:59]
	v_cvt_pk_bf16_f32 v48, v52, v53
	v_lshlrev_b32_e32 v52, 16, v149
	v_cvt_pk_bf16_f32 v49, v54, v55
	v_cvt_pk_bf16_f32 v50, v50, v51
	v_cvt_pk_bf16_f32 v51, v56, v57
	global_store_dwordx4 v[64:65], v[48:51], off offset:256
	v_and_b32_e32 v53, 0xffff0000, v149
	v_lshlrev_b32_e32 v54, 16, v150
	v_lshlrev_b32_e32 v50, 16, v148
	v_and_b32_e32 v51, 0xffff0000, v148
	v_and_b32_e32 v55, 0xffff0000, v150
	v_lshlrev_b32_e32 v56, 16, v151
	v_and_b32_e32 v57, 0xffff0000, v151
	v_lshl_add_u64 v[48:49], v[226:227], 0, v[228:229]
	v_pk_fma_f32 v[46:47], v[46:47], v[220:221], v[52:53]
	v_pk_fma_f32 v[44:45], v[44:45], v[218:219], v[50:51]
	v_pk_fma_f32 v[50:51], v[42:43], v[216:217], v[56:57]
	v_pk_fma_f32 v[42:43], v[40:41], v[214:215], v[54:55]
	v_cvt_pk_bf16_f32 v40, v44, v45
	v_cvt_pk_bf16_f32 v41, v46, v47
	v_lshlrev_b32_e32 v44, 16, v146
	v_cvt_pk_bf16_f32 v42, v42, v43
	v_cvt_pk_bf16_f32 v43, v50, v51
	global_store_dwordx4 v[48:49], v[40:43], off
	v_and_b32_e32 v45, 0xffff0000, v146
	v_lshlrev_b32_e32 v46, 16, v147
	v_lshlrev_b32_e32 v40, 16, v144
	v_and_b32_e32 v41, 0xffff0000, v144
	v_and_b32_e32 v47, 0xffff0000, v147
	v_lshlrev_b32_e32 v42, 16, v145
	v_and_b32_e32 v43, 0xffff0000, v145
	v_pk_fma_f32 v[36:37], v[36:37], v[210:211], v[40:41]
	v_pk_fma_f32 v[40:41], v[34:35], v[208:209], v[46:47]
	v_pk_fma_f32 v[34:35], v[32:33], v[206:207], v[44:45]
	v_pk_fma_f32 v[38:39], v[38:39], v[212:213], v[42:43]
	v_cvt_pk_bf16_f32 v32, v36, v37
	v_lshlrev_b32_e32 v36, 16, v141
	v_cvt_pk_bf16_f32 v33, v38, v39
	v_cvt_pk_bf16_f32 v34, v34, v35
	v_cvt_pk_bf16_f32 v35, v40, v41
	global_store_dwordx4 v[48:49], v[32:35], off offset:256
	v_and_b32_e32 v37, 0xffff0000, v141
	v_lshlrev_b32_e32 v38, 16, v142
	v_lshlrev_b32_e32 v34, 16, v140
	v_and_b32_e32 v35, 0xffff0000, v140
	v_and_b32_e32 v39, 0xffff0000, v142
	v_lshlrev_b32_e32 v40, 16, v143
	v_and_b32_e32 v41, 0xffff0000, v143
	v_lshl_add_u64 v[32:33], v[226:227], 0, v[224:225]
	v_pk_fma_f32 v[30:31], v[30:31], v[220:221], v[36:37]
	v_pk_fma_f32 v[28:29], v[28:29], v[218:219], v[34:35]
	v_pk_fma_f32 v[34:35], v[26:27], v[216:217], v[40:41]
	v_pk_fma_f32 v[26:27], v[24:25], v[214:215], v[38:39]
	v_cvt_pk_bf16_f32 v24, v28, v29
	v_cvt_pk_bf16_f32 v25, v30, v31
	v_lshlrev_b32_e32 v28, 16, v138
	v_cvt_pk_bf16_f32 v26, v26, v27
	v_cvt_pk_bf16_f32 v27, v34, v35
	global_store_dwordx4 v[32:33], v[24:27], off
	v_and_b32_e32 v29, 0xffff0000, v138
	v_lshlrev_b32_e32 v30, 16, v139
	v_lshlrev_b32_e32 v24, 16, v136
	v_and_b32_e32 v25, 0xffff0000, v136
	v_and_b32_e32 v31, 0xffff0000, v139
	v_lshlrev_b32_e32 v26, 16, v137
	v_and_b32_e32 v27, 0xffff0000, v137
	v_pk_fma_f32 v[20:21], v[20:21], v[210:211], v[24:25]
	v_pk_fma_f32 v[24:25], v[18:19], v[208:209], v[30:31]
	v_pk_fma_f32 v[18:19], v[16:17], v[206:207], v[28:29]
	v_pk_fma_f32 v[22:23], v[22:23], v[212:213], v[26:27]
	v_cvt_pk_bf16_f32 v16, v20, v21
	v_lshlrev_b32_e32 v20, 16, v133
	v_cvt_pk_bf16_f32 v17, v22, v23
	v_cvt_pk_bf16_f32 v18, v18, v19
	v_cvt_pk_bf16_f32 v19, v24, v25
	global_store_dwordx4 v[32:33], v[16:19], off offset:256
	v_and_b32_e32 v21, 0xffff0000, v133
	v_lshlrev_b32_e32 v22, 16, v134
	v_lshlrev_b32_e32 v18, 16, v132
	v_and_b32_e32 v19, 0xffff0000, v132
	v_and_b32_e32 v23, 0xffff0000, v134
	v_lshlrev_b32_e32 v24, 16, v135
	v_and_b32_e32 v25, 0xffff0000, v135
	v_lshl_add_u64 v[16:17], v[226:227], 0, v[222:223]
	v_pk_fma_f32 v[14:15], v[14:15], v[220:221], v[20:21]
	v_pk_fma_f32 v[12:13], v[12:13], v[218:219], v[18:19]
	v_pk_fma_f32 v[18:19], v[10:11], v[216:217], v[24:25]
	v_pk_fma_f32 v[10:11], v[8:9], v[214:215], v[22:23]
	v_cvt_pk_bf16_f32 v8, v12, v13
	v_cvt_pk_bf16_f32 v9, v14, v15
	v_lshlrev_b32_e32 v12, 16, v130
	v_cvt_pk_bf16_f32 v10, v10, v11
	v_cvt_pk_bf16_f32 v11, v18, v19
	global_store_dwordx4 v[16:17], v[8:11], off
	v_and_b32_e32 v13, 0xffff0000, v130
	v_lshlrev_b32_e32 v14, 16, v131
	v_lshlrev_b32_e32 v8, 16, v128
	v_and_b32_e32 v9, 0xffff0000, v128
	v_and_b32_e32 v15, 0xffff0000, v131
	v_lshlrev_b32_e32 v10, 16, v129
	v_and_b32_e32 v11, 0xffff0000, v129
	v_pk_fma_f32 v[4:5], v[4:5], v[210:211], v[8:9]
	v_pk_fma_f32 v[8:9], v[2:3], v[208:209], v[14:15]
	v_pk_fma_f32 v[2:3], v[0:1], v[206:207], v[12:13]
	v_pk_fma_f32 v[6:7], v[6:7], v[212:213], v[10:11]
	v_cvt_pk_bf16_f32 v0, v4, v5
	s_nop 0
	v_cvt_pk_bf16_f32 v1, v6, v7
	v_cvt_pk_bf16_f32 v2, v2, v3
	v_cvt_pk_bf16_f32 v3, v8, v9
	global_store_dwordx4 v[16:17], v[0:3], off offset:256
	s_cbranch_vccz .LBB0_1086
	s_waitcnt vmcnt(0)
	s_cmpk_gt_u32 s30, 0xff
	s_cbranch_scc1 .LBB0_1101
	s_barrier
